# GEMM MFMA blocks: redundant post-barrier lgkmcnt(0) removed (the same wait sits right before the barrier)
# baseline (speedup 1.0000x reference)
; #define PG8_STAGE(bufoff, gbase, voff) do { _Pragma("unroll") for (int _i = 0; _i < 2; ++_i) \
;         __builtin_amdgcn_global_load_lds((const unsigned*)((const char*)(gbase) + (voff)[_i]), (PG8_LAS unsigned*)(lds + (bufoff) + ldsw + _i * 8192), 16, 0, 0); } while (0)
; #define PG8_LDA(dst, b, h) do { _Pragma("unroll") for (int m = 0; m < 4; ++m) _Pragma("unroll") for (int k = 0; k < 2; ++k) dst[m][k] = *(const PG8_LAS bf16x8*)(lds + PG8_SA(b, h) + aoff + m * 2048 + k * 1024); } while (0)
; #define PG8_LDB(dst, b, h) do { _Pragma("unroll") for (int n = 0; n < 2; ++n) _Pragma("unroll") for (int k = 0; k < 2; ++k) dst[n][k] = *(const PG8_LAS bf16x8*)(lds + PG8_SB(b, h) + boff + n * 2048 + k * 1024); } while (0)
; #define PG8_MMA(ai, bj, At, Bt) do { __builtin_amdgcn_s_setprio(1); _Pragma("unroll") for (int m = 0; m < 4; ++m) _Pragma("unroll") for (int n = 0; n < 2; ++n) _Pragma("unroll") for (int k = 0; k < 2; ++k) \
;         acc[ai][bj][m][n] = mma16<F16>(Bt[n][k], At[m][k], acc[ai][bj][m][n]); __builtin_amdgcn_s_setprio(0); } while (0)
; #define PG8_WAIT_V(n) asm volatile("s_waitcnt vmcnt(" #n ")" ::: "memory")
; #define PG8_WAIT_L(n) asm volatile("s_waitcnt lgkmcnt(" #n ")" ::: "memory")
; #define PG8_BAR __builtin_amdgcn_s_barrier()
; #define PG8_SCHED __builtin_amdgcn_sched_barrier(0)
; template <class Epi, class Sched, bool ALIGN_EPI = false, bool SP2 = false, bool F16 = false>
; __device__ __forceinline__ void gemm_phase(PG8_LAS unsigned char* lds, const Gemm g, const Sched& S, const Epi& E, const int wid_in) {
;     ...
;             PG8_LDB(B0, 0, 0); PG8_LDB(B1, 0, 1); PG8_SCHED; PG8_LDA(At, 0, 0); PG8_STAGE(PG8_SA(1, 1), a1 + hstep, voffA);
;             PG8_WAIT_V(8); PG8_WAIT_L(0); PG8_BAR; PG8_MMA(0, 0, At, B0); PG8_MMA(0, 1, At, B1); PG8_BAR; PG8_SCHED;
;             PG8_LDA(At, 0, 1); PG8_STAGE(PG8_SB(0, 0), b2, voffB); PG8_STAGE(PG8_SB(0, 1), b2 + hstep, voffB); PG8_STAGE(PG8_SA(0, 0), a2, voffA);
;             PG8_WAIT_V(8); PG8_WAIT_L(0); PG8_BAR; PG8_MMA(1, 0, At, B0); PG8_MMA(1, 1, At, B1); PG8_BAR; PG8_SCHED;
.LBB0_224:
	ds_read_b128 v[128:131], v184
	ds_read_b128 v[132:135], v184 offset:1024
	ds_read_b128 v[136:139], v184 offset:2048
	ds_read_b128 v[140:143], v184 offset:3072
	ds_read_b128 v[144:147], v185
	ds_read_b128 v[148:151], v185 offset:1024
	ds_read_b128 v[152:155], v185 offset:2048
	ds_read_b128 v[174:177], v185 offset:3072
	s_add_u32 s58, s56, 0xfffc0080
	s_addc_u32 s59, s57, -1
	s_cmp_eq_u32 s62, 12
	s_cselect_b32 s61, s9, s59
	s_cselect_b32 s60, s21, s58
	s_cselect_b32 s59, s42, s51
	s_cselect_b32 s58, s43, s49
	v_lshl_add_u64 v[178:179], s[56:57], 0, v[166:167]
	s_add_i32 m0, s83, 0xc000
	ds_read_b128 v[190:193], v186
	ds_read_b128 v[194:197], v186 offset:1024
	ds_read_b128 v[198:201], v186 offset:2048
	ds_read_b128 v[202:205], v186 offset:3072
	ds_read_b128 v[206:209], v186 offset:4096
	ds_read_b128 v[210:213], v186 offset:5120
	ds_read_b128 v[214:217], v186 offset:6144
	ds_read_b128 v[218:221], v186 offset:7168
	global_load_lds_dwordx4 v[178:179], off
	v_lshl_add_u64 v[178:179], s[56:57], 0, v[168:169]
	s_add_i32 m0, s83, 0xe000
	s_nop 0
	global_load_lds_dwordx4 v[178:179], off
	s_waitcnt vmcnt(8)
	s_waitcnt lgkmcnt(0)
	s_barrier
	v_mfma_f32_16x16x32_f16 v[124:127], v[128:131], v[190:193], v[124:127]
	v_mfma_f32_16x16x32_f16 v[120:123], v[136:139], v[190:193], v[120:123]
	v_mfma_f32_16x16x32_f16 v[108:111], v[128:131], v[198:201], v[108:111]
	v_mfma_f32_16x16x32_f16 v[104:107], v[136:139], v[198:201], v[104:107]
	v_mfma_f32_16x16x32_f16 v[92:95], v[128:131], v[206:209], v[92:95]
	v_mfma_f32_16x16x32_f16 v[88:91], v[136:139], v[206:209], v[88:91]
	v_mfma_f32_16x16x32_f16 v[76:79], v[128:131], v[214:217], v[76:79]
	v_mfma_f32_16x16x32_f16 v[72:75], v[136:139], v[214:217], v[72:75]
	v_mfma_f32_16x16x32_f16 v[124:127], v[132:135], v[194:197], v[124:127]
	v_mfma_f32_16x16x32_f16 v[120:123], v[140:143], v[194:197], v[120:123]
	v_mfma_f32_16x16x32_f16 v[108:111], v[132:135], v[202:205], v[108:111]
	v_mfma_f32_16x16x32_f16 v[104:107], v[140:143], v[202:205], v[104:107]
	v_mfma_f32_16x16x32_f16 v[92:95], v[132:135], v[210:213], v[92:95]
	v_mfma_f32_16x16x32_f16 v[88:91], v[140:143], v[210:213], v[88:91]
	v_mfma_f32_16x16x32_f16 v[76:79], v[132:135], v[218:221], v[76:79]
	v_mfma_f32_16x16x32_f16 v[72:75], v[140:143], v[218:221], v[72:75]
	v_mfma_f32_16x16x32_f16 v[116:119], v[144:147], v[190:193], v[116:119]
	v_mfma_f32_16x16x32_f16 v[112:115], v[152:155], v[190:193], v[112:115]
	v_mfma_f32_16x16x32_f16 v[100:103], v[144:147], v[198:201], v[100:103]
	v_mfma_f32_16x16x32_f16 v[96:99], v[152:155], v[198:201], v[96:99]
	v_mfma_f32_16x16x32_f16 v[84:87], v[144:147], v[206:209], v[84:87]
	v_mfma_f32_16x16x32_f16 v[80:83], v[152:155], v[206:209], v[80:83]
	v_mfma_f32_16x16x32_f16 v[68:71], v[144:147], v[214:217], v[68:71]
	v_mfma_f32_16x16x32_f16 v[64:67], v[152:155], v[214:217], v[64:67]
	v_mfma_f32_16x16x32_f16 v[116:119], v[148:151], v[194:197], v[116:119]
	v_mfma_f32_16x16x32_f16 v[112:115], v[174:177], v[194:197], v[112:115]
	v_mfma_f32_16x16x32_f16 v[100:103], v[148:151], v[202:205], v[100:103]
	v_mfma_f32_16x16x32_f16 v[96:99], v[174:177], v[202:205], v[96:99]
	v_mfma_f32_16x16x32_f16 v[84:87], v[148:151], v[210:213], v[84:87]
	v_mfma_f32_16x16x32_f16 v[80:83], v[174:177], v[210:213], v[80:83]
	v_mfma_f32_16x16x32_f16 v[68:71], v[148:151], v[218:221], v[68:71]
	v_mfma_f32_16x16x32_f16 v[64:67], v[174:177], v[218:221], v[64:67]
	s_barrier
	s_add_i32 s63, s40, s68
	v_lshl_add_u64 v[178:179], s[58:59], 0, v[158:159]
	s_mov_b32 m0, s63
	ds_read_b128 v[190:193], v186 offset:16384
	ds_read_b128 v[194:197], v186 offset:17408
	ds_read_b128 v[198:201], v186 offset:18432
	ds_read_b128 v[202:205], v186 offset:19456
	ds_read_b128 v[206:209], v186 offset:20480
	ds_read_b128 v[210:213], v186 offset:21504
	ds_read_b128 v[214:217], v186 offset:22528
	ds_read_b128 v[218:221], v186 offset:23552
	global_load_lds_dwordx4 v[178:179], off
	s_add_i32 m0, s63, 0x2000
	s_add_u32 s64, s58, 0x40000
	v_lshl_add_u64 v[222:223], s[58:59], 0, v[162:163]
	s_addc_u32 s65, s59, 0
	s_add_i32 s63, s41, s68
	global_load_lds_dwordx4 v[222:223], off
	v_lshl_add_u64 v[224:225], s[64:65], 0, v[158:159]
	s_mov_b32 m0, s63
	v_lshl_add_u64 v[226:227], s[60:61], 0, v[160:161]
	global_load_lds_dwordx4 v[224:225], off
	v_lshl_add_u64 v[224:225], s[64:65], 0, v[162:163]
	s_add_i32 m0, s63, 0x2000
	s_nop 0
	global_load_lds_dwordx4 v[224:225], off
	v_lshl_add_u64 v[224:225], s[60:61], 0, v[156:157]
	s_mov_b32 m0, s83
	s_nop 0
	global_load_lds_dwordx4 v[224:225], off
	s_mov_b32 m0, s84
	s_nop 0
	global_load_lds_dwordx4 v[226:227], off
	s_waitcnt vmcnt(8)
	s_waitcnt lgkmcnt(0)
	s_barrier
; #define PG8_STAGE(bufoff, gbase, voff) do { _Pragma("unroll") for (int _i = 0; _i < 2; ++_i) \
;         __builtin_amdgcn_global_load_lds((const unsigned*)((const char*)(gbase) + (voff)[_i]), (PG8_LAS unsigned*)(lds + (bufoff) + ldsw + _i * 8192), 16, 0, 0); } while (0)
; #define PG8_LDA(dst, b, h) do { _Pragma("unroll") for (int m = 0; m < 4; ++m) _Pragma("unroll") for (int k = 0; k < 2; ++k) dst[m][k] = *(const PG8_LAS bf16x8*)(lds + PG8_SA(b, h) + aoff + m * 2048 + k * 1024); } while (0)
; #define PG8_LDB(dst, b, h) do { _Pragma("unroll") for (int n = 0; n < 2; ++n) _Pragma("unroll") for (int k = 0; k < 2; ++k) dst[n][k] = *(const PG8_LAS bf16x8*)(lds + PG8_SB(b, h) + boff + n * 2048 + k * 1024); } while (0)
; #define PG8_MMA(ai, bj, At, Bt) do { __builtin_amdgcn_s_setprio(1); _Pragma("unroll") for (int m = 0; m < 4; ++m) _Pragma("unroll") for (int n = 0; n < 2; ++n) _Pragma("unroll") for (int k = 0; k < 2; ++k) \
;         acc[ai][bj][m][n] = mma16<F16>(Bt[n][k], At[m][k], acc[ai][bj][m][n]); __builtin_amdgcn_s_setprio(0); } while (0)
; #define PG8_WAIT_V(n) asm volatile("s_waitcnt vmcnt(" #n ")" ::: "memory")
; #define PG8_WAIT_L(n) asm volatile("s_waitcnt lgkmcnt(" #n ")" ::: "memory")
; #define PG8_BAR __builtin_amdgcn_s_barrier()
; #define PG8_SCHED __builtin_amdgcn_sched_barrier(0)
; template <class Epi, class Sched, bool ALIGN_EPI = false, bool SP2 = false, bool F16 = false>
; __device__ __forceinline__ void gemm_phase(PG8_LAS unsigned char* lds, const Gemm g, const Sched& S, const Epi& E, const int wid_in) {
;     ...
;             PG8_WAIT_V(8); PG8_WAIT_L(0); PG8_BAR; PG8_MMA(1, 0, At, B0); PG8_MMA(1, 1, At, B1); PG8_BAR; PG8_SCHED;
;             PG8_LDB(B0, 1, 0); PG8_LDB(B1, 1, 1); PG8_SCHED; PG8_LDA(At, 1, 0); PG8_STAGE(PG8_SA(0, 1), a2 + hstep, voffA);
;             PG8_WAIT_V(8); PG8_WAIT_L(0); PG8_BAR; PG8_MMA(0, 0, At, B0); PG8_MMA(0, 1, At, B1); PG8_BAR; PG8_SCHED;
	v_mfma_f32_16x16x32_f16 v[60:63], v[128:131], v[190:193], v[60:63]
	v_mfma_f32_16x16x32_f16 v[56:59], v[136:139], v[190:193], v[56:59]
	v_mfma_f32_16x16x32_f16 v[44:47], v[128:131], v[198:201], v[44:47]
	v_mfma_f32_16x16x32_f16 v[40:43], v[136:139], v[198:201], v[40:43]
	v_mfma_f32_16x16x32_f16 v[28:31], v[128:131], v[206:209], v[28:31]
	v_mfma_f32_16x16x32_f16 v[24:27], v[136:139], v[206:209], v[24:27]
	v_mfma_f32_16x16x32_f16 v[12:15], v[128:131], v[214:217], v[12:15]
	v_mfma_f32_16x16x32_f16 v[8:11], v[136:139], v[214:217], v[8:11]
	v_mfma_f32_16x16x32_f16 v[60:63], v[132:135], v[194:197], v[60:63]
	v_mfma_f32_16x16x32_f16 v[56:59], v[140:143], v[194:197], v[56:59]
	v_mfma_f32_16x16x32_f16 v[44:47], v[132:135], v[202:205], v[44:47]
	v_mfma_f32_16x16x32_f16 v[40:43], v[140:143], v[202:205], v[40:43]
	v_mfma_f32_16x16x32_f16 v[28:31], v[132:135], v[210:213], v[28:31]
	v_mfma_f32_16x16x32_f16 v[24:27], v[140:143], v[210:213], v[24:27]
	v_mfma_f32_16x16x32_f16 v[12:15], v[132:135], v[218:221], v[12:15]
	v_mfma_f32_16x16x32_f16 v[8:11], v[140:143], v[218:221], v[8:11]
	v_mfma_f32_16x16x32_f16 v[52:55], v[144:147], v[190:193], v[52:55]
	v_mfma_f32_16x16x32_f16 v[48:51], v[152:155], v[190:193], v[48:51]
	v_mfma_f32_16x16x32_f16 v[36:39], v[144:147], v[198:201], v[36:39]
	v_mfma_f32_16x16x32_f16 v[32:35], v[152:155], v[198:201], v[32:35]
	v_mfma_f32_16x16x32_f16 v[20:23], v[144:147], v[206:209], v[20:23]
	v_mfma_f32_16x16x32_f16 v[16:19], v[152:155], v[206:209], v[16:19]
	v_mfma_f32_16x16x32_f16 v[4:7], v[144:147], v[214:217], v[4:7]
	v_mfma_f32_16x16x32_f16 v[0:3], v[152:155], v[214:217], v[0:3]
	v_mfma_f32_16x16x32_f16 v[52:55], v[148:151], v[194:197], v[52:55]
	v_mfma_f32_16x16x32_f16 v[48:51], v[174:177], v[194:197], v[48:51]
	v_mfma_f32_16x16x32_f16 v[36:39], v[148:151], v[202:205], v[36:39]
	v_mfma_f32_16x16x32_f16 v[32:35], v[174:177], v[202:205], v[32:35]
	v_mfma_f32_16x16x32_f16 v[20:23], v[148:151], v[210:213], v[20:23]
	v_mfma_f32_16x16x32_f16 v[16:19], v[174:177], v[210:213], v[16:19]
	v_mfma_f32_16x16x32_f16 v[4:7], v[148:151], v[218:221], v[4:7]
	v_mfma_f32_16x16x32_f16 v[0:3], v[174:177], v[218:221], v[0:3]
	s_barrier
	s_add_i32 s63, 0, 0x18000
	s_add_i32 s64, 0, 0x1c000
	v_add_u32_e32 v140, s63, v183
	v_add_u32_e32 v165, s64, v183
	ds_read_b128 v[128:131], v140
	ds_read_b128 v[132:135], v140 offset:1024
	ds_read_b128 v[136:139], v140 offset:2048
	ds_read_b128 v[140:143], v140 offset:3072
	ds_read_b128 v[144:147], v165
	ds_read_b128 v[148:151], v165 offset:1024
	ds_read_b128 v[152:155], v165 offset:2048
	ds_read_b128 v[174:177], v165 offset:3072
	s_add_u32 s60, s60, 0x40000
	s_addc_u32 s61, s61, 0
	s_mov_b32 m0, s85
	v_lshl_add_u64 v[228:229], s[60:61], 0, v[156:157]
	ds_read_b128 v[190:193], v186 offset:32768
	ds_read_b128 v[194:197], v186 offset:33792
	ds_read_b128 v[198:201], v186 offset:34816
	ds_read_b128 v[202:205], v186 offset:35840
	ds_read_b128 v[206:209], v186 offset:36864
	ds_read_b128 v[210:213], v186 offset:37888
	ds_read_b128 v[214:217], v186 offset:38912
	ds_read_b128 v[218:221], v186 offset:39936
	global_load_lds_dwordx4 v[228:229], off
	v_lshl_add_u64 v[228:229], s[60:61], 0, v[160:161]
	s_mov_b32 m0, s86
	s_nop 0
	global_load_lds_dwordx4 v[228:229], off
	s_waitcnt vmcnt(8)
	s_waitcnt lgkmcnt(0)
	s_barrier
	v_mfma_f32_16x16x32_f16 v[124:127], v[128:131], v[190:193], v[124:127]
	v_mfma_f32_16x16x32_f16 v[120:123], v[136:139], v[190:193], v[120:123]
	v_mfma_f32_16x16x32_f16 v[108:111], v[128:131], v[198:201], v[108:111]
	v_mfma_f32_16x16x32_f16 v[104:107], v[136:139], v[198:201], v[104:107]
	v_mfma_f32_16x16x32_f16 v[92:95], v[128:131], v[206:209], v[92:95]
	v_mfma_f32_16x16x32_f16 v[88:91], v[136:139], v[206:209], v[88:91]
	v_mfma_f32_16x16x32_f16 v[76:79], v[128:131], v[214:217], v[76:79]
	v_mfma_f32_16x16x32_f16 v[72:75], v[136:139], v[214:217], v[72:75]
	v_mfma_f32_16x16x32_f16 v[124:127], v[132:135], v[194:197], v[124:127]
	v_mfma_f32_16x16x32_f16 v[120:123], v[140:143], v[194:197], v[120:123]
	v_mfma_f32_16x16x32_f16 v[108:111], v[132:135], v[202:205], v[108:111]
	v_mfma_f32_16x16x32_f16 v[104:107], v[140:143], v[202:205], v[104:107]
	v_mfma_f32_16x16x32_f16 v[92:95], v[132:135], v[210:213], v[92:95]
	v_mfma_f32_16x16x32_f16 v[88:91], v[140:143], v[210:213], v[88:91]
	v_mfma_f32_16x16x32_f16 v[76:79], v[132:135], v[218:221], v[76:79]
	v_mfma_f32_16x16x32_f16 v[72:75], v[140:143], v[218:221], v[72:75]
	v_mfma_f32_16x16x32_f16 v[116:119], v[144:147], v[190:193], v[116:119]
	v_mfma_f32_16x16x32_f16 v[112:115], v[152:155], v[190:193], v[112:115]
	v_mfma_f32_16x16x32_f16 v[100:103], v[144:147], v[198:201], v[100:103]
	v_mfma_f32_16x16x32_f16 v[96:99], v[152:155], v[198:201], v[96:99]
	v_mfma_f32_16x16x32_f16 v[84:87], v[144:147], v[206:209], v[84:87]
	v_mfma_f32_16x16x32_f16 v[80:83], v[152:155], v[206:209], v[80:83]
	v_mfma_f32_16x16x32_f16 v[68:71], v[144:147], v[214:217], v[68:71]
	v_mfma_f32_16x16x32_f16 v[64:67], v[152:155], v[214:217], v[64:67]
	v_mfma_f32_16x16x32_f16 v[116:119], v[148:151], v[194:197], v[116:119]
	v_mfma_f32_16x16x32_f16 v[112:115], v[174:177], v[194:197], v[112:115]
	v_mfma_f32_16x16x32_f16 v[100:103], v[148:151], v[202:205], v[100:103]
	v_mfma_f32_16x16x32_f16 v[96:99], v[174:177], v[202:205], v[96:99]
	v_mfma_f32_16x16x32_f16 v[84:87], v[148:151], v[210:213], v[84:87]
	v_mfma_f32_16x16x32_f16 v[80:83], v[174:177], v[210:213], v[80:83]
	v_mfma_f32_16x16x32_f16 v[68:71], v[148:151], v[218:221], v[68:71]
	v_mfma_f32_16x16x32_f16 v[64:67], v[174:177], v[218:221], v[64:67]
	s_barrier
; #define PG8_STAGE(bufoff, gbase, voff) do { _Pragma("unroll") for (int _i = 0; _i < 2; ++_i) \
;         __builtin_amdgcn_global_load_lds((const unsigned*)((const char*)(gbase) + (voff)[_i]), (PG8_LAS unsigned*)(lds + (bufoff) + ldsw + _i * 8192), 16, 0, 0); } while (0)
; #define PG8_LDA(dst, b, h) do { _Pragma("unroll") for (int m = 0; m < 4; ++m) _Pragma("unroll") for (int k = 0; k < 2; ++k) dst[m][k] = *(const PG8_LAS bf16x8*)(lds + PG8_SA(b, h) + aoff + m * 2048 + k * 1024); } while (0)
; #define PG8_MMA(ai, bj, At, Bt) do { __builtin_amdgcn_s_setprio(1); _Pragma("unroll") for (int m = 0; m < 4; ++m) _Pragma("unroll") for (int n = 0; n < 2; ++n) _Pragma("unroll") for (int k = 0; k < 2; ++k) \
;         acc[ai][bj][m][n] = mma16<F16>(Bt[n][k], At[m][k], acc[ai][bj][m][n]); __builtin_amdgcn_s_setprio(0); } while (0)
; #define PG8_WAIT_V(n) asm volatile("s_waitcnt vmcnt(" #n ")" ::: "memory")
; #define PG8_WAIT_L(n) asm volatile("s_waitcnt lgkmcnt(" #n ")" ::: "memory")
; #define PG8_BAR __builtin_amdgcn_s_barrier()
; #define PG8_SCHED __builtin_amdgcn_sched_barrier(0)
; template <class Epi, class Sched, bool ALIGN_EPI = false, bool SP2 = false, bool F16 = false>
; __device__ __forceinline__ void gemm_phase(PG8_LAS unsigned char* lds, const Gemm g, const Sched& S, const Epi& E, const int wid_in) {
;     ...
;             PG8_LDA(At, 1, 1); PG8_STAGE(PG8_SB(1, 0), b3, voffB); PG8_STAGE(PG8_SB(1, 1), b3 + hstep, voffB); PG8_STAGE(PG8_SA(1, 0), a3, voffA);
;             PG8_WAIT_V(8); PG8_WAIT_L(0); PG8_BAR; PG8_MMA(1, 0, At, B0); PG8_MMA(1, 1, At, B1); PG8_BAR; PG8_SCHED;
;     ...
;         }
;         if constexpr (ALIGN_EPI) { if (wr == 0) PG8_BAR; }
	s_add_i32 s60, s63, s68
	v_lshl_add_u64 v[178:179], v[178:179], 0, s[24:25]
	s_mov_b32 m0, s60
	ds_read_b128 v[190:193], v186 offset:49152
	ds_read_b128 v[194:197], v186 offset:50176
	ds_read_b128 v[198:201], v186 offset:51200
	ds_read_b128 v[202:205], v186 offset:52224
	ds_read_b128 v[206:209], v186 offset:53248
	ds_read_b128 v[210:213], v186 offset:54272
	ds_read_b128 v[214:217], v186 offset:55296
	ds_read_b128 v[218:221], v186 offset:56320
	global_load_lds_dwordx4 v[178:179], off
	s_add_i32 m0, s60, 0x2000
	s_add_u32 s58, s58, 0x40080
	v_lshl_add_u64 v[178:179], v[222:223], 0, s[24:25]
	s_addc_u32 s59, s59, 0
	s_add_i32 s60, s64, s68
	global_load_lds_dwordx4 v[178:179], off
	v_lshl_add_u64 v[178:179], s[58:59], 0, v[158:159]
	s_mov_b32 m0, s60
	s_nop 0
	global_load_lds_dwordx4 v[178:179], off
	v_lshl_add_u64 v[178:179], s[58:59], 0, v[162:163]
	s_add_i32 m0, s60, 0x2000
	s_nop 0
	global_load_lds_dwordx4 v[178:179], off
	v_lshl_add_u64 v[178:179], v[224:225], 0, s[24:25]
	s_mov_b32 m0, s90
	s_nop 0
	global_load_lds_dwordx4 v[178:179], off
	v_lshl_add_u64 v[178:179], v[226:227], 0, s[24:25]
	s_mov_b32 m0, s91
	s_nop 0
	global_load_lds_dwordx4 v[178:179], off
	s_waitcnt vmcnt(8)
	s_waitcnt lgkmcnt(0)
	s_barrier
	v_mfma_f32_16x16x32_f16 v[60:63], v[128:131], v[190:193], v[60:63]
	v_mfma_f32_16x16x32_f16 v[56:59], v[136:139], v[190:193], v[56:59]
	v_mfma_f32_16x16x32_f16 v[44:47], v[128:131], v[198:201], v[44:47]
	v_mfma_f32_16x16x32_f16 v[40:43], v[136:139], v[198:201], v[40:43]
	v_mfma_f32_16x16x32_f16 v[28:31], v[128:131], v[206:209], v[28:31]
	v_mfma_f32_16x16x32_f16 v[24:27], v[136:139], v[206:209], v[24:27]
	v_mfma_f32_16x16x32_f16 v[12:15], v[128:131], v[214:217], v[12:15]
	v_mfma_f32_16x16x32_f16 v[8:11], v[136:139], v[214:217], v[8:11]
	v_mfma_f32_16x16x32_f16 v[60:63], v[132:135], v[194:197], v[60:63]
	v_mfma_f32_16x16x32_f16 v[56:59], v[140:143], v[194:197], v[56:59]
	v_mfma_f32_16x16x32_f16 v[44:47], v[132:135], v[202:205], v[44:47]
	v_mfma_f32_16x16x32_f16 v[40:43], v[140:143], v[202:205], v[40:43]
	v_mfma_f32_16x16x32_f16 v[28:31], v[132:135], v[210:213], v[28:31]
	v_mfma_f32_16x16x32_f16 v[24:27], v[140:143], v[210:213], v[24:27]
	v_mfma_f32_16x16x32_f16 v[12:15], v[132:135], v[218:221], v[12:15]
	v_mfma_f32_16x16x32_f16 v[8:11], v[140:143], v[218:221], v[8:11]
	v_mfma_f32_16x16x32_f16 v[52:55], v[144:147], v[190:193], v[52:55]
	v_mfma_f32_16x16x32_f16 v[48:51], v[152:155], v[190:193], v[48:51]
	v_mfma_f32_16x16x32_f16 v[36:39], v[144:147], v[198:201], v[36:39]
	v_mfma_f32_16x16x32_f16 v[32:35], v[152:155], v[198:201], v[32:35]
	v_mfma_f32_16x16x32_f16 v[20:23], v[144:147], v[206:209], v[20:23]
	v_mfma_f32_16x16x32_f16 v[16:19], v[152:155], v[206:209], v[16:19]
	v_mfma_f32_16x16x32_f16 v[4:7], v[144:147], v[214:217], v[4:7]
	v_mfma_f32_16x16x32_f16 v[0:3], v[152:155], v[214:217], v[0:3]
	v_mfma_f32_16x16x32_f16 v[52:55], v[148:151], v[194:197], v[52:55]
	v_mfma_f32_16x16x32_f16 v[48:51], v[174:177], v[194:197], v[48:51]
	v_mfma_f32_16x16x32_f16 v[36:39], v[148:151], v[202:205], v[36:39]
	v_mfma_f32_16x16x32_f16 v[32:35], v[174:177], v[202:205], v[32:35]
	v_mfma_f32_16x16x32_f16 v[20:23], v[148:151], v[210:213], v[20:23]
	v_mfma_f32_16x16x32_f16 v[16:19], v[174:177], v[210:213], v[16:19]
	v_mfma_f32_16x16x32_f16 v[4:7], v[148:151], v[218:221], v[4:7]
	v_mfma_f32_16x16x32_f16 v[0:3], v[174:177], v[218:221], v[0:3]
	s_barrier
	s_add_i32 s62, s62, 2
	s_add_u32 s56, s56, 0x100
	s_addc_u32 s57, s57, 0
	s_add_u32 s49, s49, 0x100
	s_addc_u32 s51, s51, 0
	s_cmp_gt_u32 s62, 13
	s_cbranch_scc0 .LBB0_224
	s_and_b64 vcc, exec, s[26:27]
	s_cbranch_vccz .LBB0_227
	s_barrier

; #define PG8_STAGE(bufoff, gbase, voff) do { _Pragma("unroll") for (int _i = 0; _i < 2; ++_i) \
;         __builtin_amdgcn_global_load_lds((const unsigned*)((const char*)(gbase) + (voff)[_i]), (PG8_LAS unsigned*)(lds + (bufoff) + ldsw + _i * 8192), 16, 0, 0); } while (0)
; #define PG8_LDA(dst, b, h) do { _Pragma("unroll") for (int m = 0; m < 4; ++m) _Pragma("unroll") for (int k = 0; k < 2; ++k) dst[m][k] = *(const PG8_LAS bf16x8*)(lds + PG8_SA(b, h) + aoff + m * 2048 + k * 1024); } while (0)
; #define PG8_LDB(dst, b, h) do { _Pragma("unroll") for (int n = 0; n < 2; ++n) _Pragma("unroll") for (int k = 0; k < 2; ++k) dst[n][k] = *(const PG8_LAS bf16x8*)(lds + PG8_SB(b, h) + boff + n * 2048 + k * 1024); } while (0)
; #define PG8_MMA(ai, bj, At, Bt) do { __builtin_amdgcn_s_setprio(1); _Pragma("unroll") for (int m = 0; m < 4; ++m) _Pragma("unroll") for (int n = 0; n < 2; ++n) _Pragma("unroll") for (int k = 0; k < 2; ++k) \
;         acc[ai][bj][m][n] = mma16<F16>(Bt[n][k], At[m][k], acc[ai][bj][m][n]); __builtin_amdgcn_s_setprio(0); } while (0)
; #define PG8_WAIT_V(n) asm volatile("s_waitcnt vmcnt(" #n ")" ::: "memory")
; #define PG8_WAIT_L(n) asm volatile("s_waitcnt lgkmcnt(" #n ")" ::: "memory")
; #define PG8_BAR __builtin_amdgcn_s_barrier()
; #define PG8_SCHED __builtin_amdgcn_sched_barrier(0)
; template <class Epi, class Sched, bool ALIGN_EPI = false, bool SP2 = false, bool F16 = false>
; __device__ __forceinline__ void gemm_phase(PG8_LAS unsigned char* lds, const Gemm g, const Sched& S, const Epi& E, const int wid_in) {
;     ...
;             PG8_LDB(B0, 0, 0); PG8_LDB(B1, 0, 1); PG8_SCHED; PG8_LDA(At, 0, 0); PG8_STAGE(PG8_SA(1, 1), a1 + hstep, voffA);
;             PG8_WAIT_V(8); PG8_WAIT_L(0); PG8_BAR; PG8_MMA(0, 0, At, B0); PG8_MMA(0, 1, At, B1); PG8_BAR; PG8_SCHED;
;             PG8_LDA(At, 0, 1); PG8_STAGE(PG8_SB(0, 0), b2, voffB); PG8_STAGE(PG8_SB(0, 1), b2 + hstep, voffB); PG8_STAGE(PG8_SA(0, 0), a2, voffA);
;             PG8_WAIT_V(8); PG8_WAIT_L(0); PG8_BAR; PG8_MMA(1, 0, At, B0); PG8_MMA(1, 1, At, B1); PG8_BAR; PG8_SCHED;
.LBB0_508:
	ds_read_b128 v[128:131], v189
	ds_read_b128 v[132:135], v189 offset:1024
	ds_read_b128 v[136:139], v189 offset:2048
	ds_read_b128 v[140:143], v189 offset:3072
	ds_read_b128 v[144:147], v190
	ds_read_b128 v[148:151], v190 offset:1024
	ds_read_b128 v[168:171], v190 offset:2048
	ds_read_b128 v[172:175], v190 offset:3072
	s_add_u32 s46, s44, 0xfffc0080
	s_addc_u32 s47, s45, -1
	s_cmp_eq_u32 s43, 12
	s_cselect_b32 s49, s10, s47
	s_cselect_b32 s48, s27, s46
	s_cselect_b32 s47, s25, s42
	s_cselect_b32 s46, s35, s37
	v_lshl_add_u64 v[184:185], s[44:45], 0, v[160:161]
	s_add_i32 m0, s74, 0xc000
	ds_read_b128 v[176:179], v191
	ds_read_b128 v[180:183], v191 offset:1024
	ds_read_b128 v[192:195], v191 offset:2048
	ds_read_b128 v[196:199], v191 offset:3072
	ds_read_b128 v[200:203], v191 offset:4096
	ds_read_b128 v[204:207], v191 offset:5120
	ds_read_b128 v[208:211], v191 offset:6144
	ds_read_b128 v[212:215], v191 offset:7168
	global_load_lds_dwordx4 v[184:185], off
	v_lshl_add_u64 v[184:185], s[44:45], 0, v[162:163]
	s_add_i32 m0, s74, 0xe000
	s_nop 0
	global_load_lds_dwordx4 v[184:185], off
	s_waitcnt vmcnt(8)
	s_waitcnt lgkmcnt(0)
	s_barrier
	v_mfma_f32_16x16x32_bf16 v[124:127], v[128:131], v[176:179], v[124:127]
	v_mfma_f32_16x16x32_bf16 v[120:123], v[136:139], v[176:179], v[120:123]
	v_mfma_f32_16x16x32_bf16 v[108:111], v[128:131], v[192:195], v[108:111]
	v_mfma_f32_16x16x32_bf16 v[104:107], v[136:139], v[192:195], v[104:107]
	v_mfma_f32_16x16x32_bf16 v[92:95], v[128:131], v[200:203], v[92:95]
	v_mfma_f32_16x16x32_bf16 v[88:91], v[136:139], v[200:203], v[88:91]
	v_mfma_f32_16x16x32_bf16 v[76:79], v[128:131], v[208:211], v[76:79]
	v_mfma_f32_16x16x32_bf16 v[72:75], v[136:139], v[208:211], v[72:75]
	v_mfma_f32_16x16x32_bf16 v[124:127], v[132:135], v[180:183], v[124:127]
	v_mfma_f32_16x16x32_bf16 v[120:123], v[140:143], v[180:183], v[120:123]
	v_mfma_f32_16x16x32_bf16 v[108:111], v[132:135], v[196:199], v[108:111]
	v_mfma_f32_16x16x32_bf16 v[104:107], v[140:143], v[196:199], v[104:107]
	v_mfma_f32_16x16x32_bf16 v[92:95], v[132:135], v[204:207], v[92:95]
	v_mfma_f32_16x16x32_bf16 v[88:91], v[140:143], v[204:207], v[88:91]
	v_mfma_f32_16x16x32_bf16 v[76:79], v[132:135], v[212:215], v[76:79]
	v_mfma_f32_16x16x32_bf16 v[72:75], v[140:143], v[212:215], v[72:75]
	v_mfma_f32_16x16x32_bf16 v[116:119], v[144:147], v[176:179], v[116:119]
	v_mfma_f32_16x16x32_bf16 v[112:115], v[168:171], v[176:179], v[112:115]
	v_mfma_f32_16x16x32_bf16 v[100:103], v[144:147], v[192:195], v[100:103]
	v_mfma_f32_16x16x32_bf16 v[96:99], v[168:171], v[192:195], v[96:99]
	v_mfma_f32_16x16x32_bf16 v[84:87], v[144:147], v[200:203], v[84:87]
	v_mfma_f32_16x16x32_bf16 v[80:83], v[168:171], v[200:203], v[80:83]
	v_mfma_f32_16x16x32_bf16 v[68:71], v[144:147], v[208:211], v[68:71]
	v_mfma_f32_16x16x32_bf16 v[64:67], v[168:171], v[208:211], v[64:67]
	v_mfma_f32_16x16x32_bf16 v[116:119], v[148:151], v[180:183], v[116:119]
	v_mfma_f32_16x16x32_bf16 v[112:115], v[172:175], v[180:183], v[112:115]
	v_mfma_f32_16x16x32_bf16 v[100:103], v[148:151], v[196:199], v[100:103]
	v_mfma_f32_16x16x32_bf16 v[96:99], v[172:175], v[196:199], v[96:99]
	v_mfma_f32_16x16x32_bf16 v[84:87], v[148:151], v[204:207], v[84:87]
	v_mfma_f32_16x16x32_bf16 v[80:83], v[172:175], v[204:207], v[80:83]
	v_mfma_f32_16x16x32_bf16 v[68:71], v[148:151], v[212:215], v[68:71]
	v_mfma_f32_16x16x32_bf16 v[64:67], v[172:175], v[212:215], v[64:67]
	s_barrier
	s_add_i32 s63, s60, s68
	v_lshl_add_u64 v[184:185], s[46:47], 0, v[154:155]
	s_mov_b32 m0, s63
	ds_read_b128 v[176:179], v191 offset:16384
	ds_read_b128 v[180:183], v191 offset:17408
	ds_read_b128 v[192:195], v191 offset:18432
	ds_read_b128 v[196:199], v191 offset:19456
	ds_read_b128 v[200:203], v191 offset:20480
	ds_read_b128 v[204:207], v191 offset:21504
	ds_read_b128 v[208:211], v191 offset:22528
	ds_read_b128 v[212:215], v191 offset:23552
	global_load_lds_dwordx4 v[184:185], off
	s_add_i32 m0, s63, 0x2000
	s_add_u32 s64, s46, 0x40000
	v_lshl_add_u64 v[216:217], s[46:47], 0, v[158:159]
	s_addc_u32 s65, s47, 0
	s_add_i32 s63, s61, s68
	global_load_lds_dwordx4 v[216:217], off
	v_lshl_add_u64 v[218:219], s[64:65], 0, v[154:155]
	s_mov_b32 m0, s63
	v_lshl_add_u64 v[220:221], s[48:49], 0, v[156:157]
	global_load_lds_dwordx4 v[218:219], off
	v_lshl_add_u64 v[218:219], s[64:65], 0, v[158:159]
	s_add_i32 m0, s63, 0x2000
	s_nop 0
	global_load_lds_dwordx4 v[218:219], off
	v_lshl_add_u64 v[218:219], s[48:49], 0, v[152:153]
	s_mov_b32 m0, s74
	s_nop 0
	global_load_lds_dwordx4 v[218:219], off
	s_mov_b32 m0, s51
	s_nop 0
	global_load_lds_dwordx4 v[220:221], off
	s_waitcnt vmcnt(8)
	s_waitcnt lgkmcnt(0)
	s_barrier
; #define PG8_STAGE(bufoff, gbase, voff) do { _Pragma("unroll") for (int _i = 0; _i < 2; ++_i) \
;         __builtin_amdgcn_global_load_lds((const unsigned*)((const char*)(gbase) + (voff)[_i]), (PG8_LAS unsigned*)(lds + (bufoff) + ldsw + _i * 8192), 16, 0, 0); } while (0)
; #define PG8_LDA(dst, b, h) do { _Pragma("unroll") for (int m = 0; m < 4; ++m) _Pragma("unroll") for (int k = 0; k < 2; ++k) dst[m][k] = *(const PG8_LAS bf16x8*)(lds + PG8_SA(b, h) + aoff + m * 2048 + k * 1024); } while (0)
; #define PG8_LDB(dst, b, h) do { _Pragma("unroll") for (int n = 0; n < 2; ++n) _Pragma("unroll") for (int k = 0; k < 2; ++k) dst[n][k] = *(const PG8_LAS bf16x8*)(lds + PG8_SB(b, h) + boff + n * 2048 + k * 1024); } while (0)
; #define PG8_MMA(ai, bj, At, Bt) do { __builtin_amdgcn_s_setprio(1); _Pragma("unroll") for (int m = 0; m < 4; ++m) _Pragma("unroll") for (int n = 0; n < 2; ++n) _Pragma("unroll") for (int k = 0; k < 2; ++k) \
;         acc[ai][bj][m][n] = mma16<F16>(Bt[n][k], At[m][k], acc[ai][bj][m][n]); __builtin_amdgcn_s_setprio(0); } while (0)
; #define PG8_WAIT_V(n) asm volatile("s_waitcnt vmcnt(" #n ")" ::: "memory")
; #define PG8_WAIT_L(n) asm volatile("s_waitcnt lgkmcnt(" #n ")" ::: "memory")
; #define PG8_BAR __builtin_amdgcn_s_barrier()
; #define PG8_SCHED __builtin_amdgcn_sched_barrier(0)
; template <class Epi, class Sched, bool ALIGN_EPI = false, bool SP2 = false, bool F16 = false>
; __device__ __forceinline__ void gemm_phase(PG8_LAS unsigned char* lds, const Gemm g, const Sched& S, const Epi& E, const int wid_in) {
;     ...
;             PG8_WAIT_V(8); PG8_WAIT_L(0); PG8_BAR; PG8_MMA(1, 0, At, B0); PG8_MMA(1, 1, At, B1); PG8_BAR; PG8_SCHED;
;             PG8_LDB(B0, 1, 0); PG8_LDB(B1, 1, 1); PG8_SCHED; PG8_LDA(At, 1, 0); PG8_STAGE(PG8_SA(0, 1), a2 + hstep, voffA);
;             PG8_WAIT_V(8); PG8_WAIT_L(0); PG8_BAR; PG8_MMA(0, 0, At, B0); PG8_MMA(0, 1, At, B1); PG8_BAR; PG8_SCHED;
	v_mfma_f32_16x16x32_bf16 v[60:63], v[128:131], v[176:179], v[60:63]
	v_mfma_f32_16x16x32_bf16 v[56:59], v[136:139], v[176:179], v[56:59]
	v_mfma_f32_16x16x32_bf16 v[44:47], v[128:131], v[192:195], v[44:47]
	v_mfma_f32_16x16x32_bf16 v[40:43], v[136:139], v[192:195], v[40:43]
	v_mfma_f32_16x16x32_bf16 v[28:31], v[128:131], v[200:203], v[28:31]
	v_mfma_f32_16x16x32_bf16 v[24:27], v[136:139], v[200:203], v[24:27]
	v_mfma_f32_16x16x32_bf16 v[12:15], v[128:131], v[208:211], v[12:15]
	v_mfma_f32_16x16x32_bf16 v[8:11], v[136:139], v[208:211], v[8:11]
	v_mfma_f32_16x16x32_bf16 v[60:63], v[132:135], v[180:183], v[60:63]
	v_mfma_f32_16x16x32_bf16 v[56:59], v[140:143], v[180:183], v[56:59]
	v_mfma_f32_16x16x32_bf16 v[44:47], v[132:135], v[196:199], v[44:47]
	v_mfma_f32_16x16x32_bf16 v[40:43], v[140:143], v[196:199], v[40:43]
	v_mfma_f32_16x16x32_bf16 v[28:31], v[132:135], v[204:207], v[28:31]
	v_mfma_f32_16x16x32_bf16 v[24:27], v[140:143], v[204:207], v[24:27]
	v_mfma_f32_16x16x32_bf16 v[12:15], v[132:135], v[212:215], v[12:15]
	v_mfma_f32_16x16x32_bf16 v[8:11], v[140:143], v[212:215], v[8:11]
	v_mfma_f32_16x16x32_bf16 v[52:55], v[144:147], v[176:179], v[52:55]
	v_mfma_f32_16x16x32_bf16 v[48:51], v[168:171], v[176:179], v[48:51]
	v_mfma_f32_16x16x32_bf16 v[36:39], v[144:147], v[192:195], v[36:39]
	v_mfma_f32_16x16x32_bf16 v[32:35], v[168:171], v[192:195], v[32:35]
	v_mfma_f32_16x16x32_bf16 v[20:23], v[144:147], v[200:203], v[20:23]
	v_mfma_f32_16x16x32_bf16 v[16:19], v[168:171], v[200:203], v[16:19]
	v_mfma_f32_16x16x32_bf16 v[4:7], v[144:147], v[208:211], v[4:7]
	v_mfma_f32_16x16x32_bf16 v[0:3], v[168:171], v[208:211], v[0:3]
	v_mfma_f32_16x16x32_bf16 v[52:55], v[148:151], v[180:183], v[52:55]
	v_mfma_f32_16x16x32_bf16 v[48:51], v[172:175], v[180:183], v[48:51]
	v_mfma_f32_16x16x32_bf16 v[36:39], v[148:151], v[196:199], v[36:39]
	v_mfma_f32_16x16x32_bf16 v[32:35], v[172:175], v[196:199], v[32:35]
	v_mfma_f32_16x16x32_bf16 v[20:23], v[148:151], v[204:207], v[20:23]
	v_mfma_f32_16x16x32_bf16 v[16:19], v[172:175], v[204:207], v[16:19]
	v_mfma_f32_16x16x32_bf16 v[4:7], v[148:151], v[212:215], v[4:7]
	v_mfma_f32_16x16x32_bf16 v[0:3], v[172:175], v[212:215], v[0:3]
	s_barrier
	s_add_i32 s63, 0, 0x18000
	s_add_i32 s64, 0, 0x1c000
	v_add_u32_e32 v140, s63, v188
	v_add_u32_e32 v172, s64, v188
	ds_read_b128 v[128:131], v140
	ds_read_b128 v[132:135], v140 offset:1024
	ds_read_b128 v[136:139], v140 offset:2048
	ds_read_b128 v[140:143], v140 offset:3072
	ds_read_b128 v[144:147], v172
	ds_read_b128 v[148:151], v172 offset:1024
	ds_read_b128 v[168:171], v172 offset:2048
	ds_read_b128 v[172:175], v172 offset:3072
	s_add_u32 s48, s48, 0x40000
	s_addc_u32 s49, s49, 0
	s_mov_b32 m0, s52
	v_lshl_add_u64 v[222:223], s[48:49], 0, v[152:153]
	ds_read_b128 v[176:179], v191 offset:32768
	ds_read_b128 v[180:183], v191 offset:33792
	ds_read_b128 v[192:195], v191 offset:34816
	ds_read_b128 v[196:199], v191 offset:35840
	ds_read_b128 v[200:203], v191 offset:36864
	ds_read_b128 v[204:207], v191 offset:37888
	ds_read_b128 v[208:211], v191 offset:38912
	ds_read_b128 v[212:215], v191 offset:39936
	global_load_lds_dwordx4 v[222:223], off
	v_lshl_add_u64 v[222:223], s[48:49], 0, v[156:157]
	s_mov_b32 m0, s53
	s_nop 0
	global_load_lds_dwordx4 v[222:223], off
	s_waitcnt vmcnt(8)
	s_waitcnt lgkmcnt(0)
	s_barrier
	v_mfma_f32_16x16x32_bf16 v[124:127], v[128:131], v[176:179], v[124:127]
	v_mfma_f32_16x16x32_bf16 v[120:123], v[136:139], v[176:179], v[120:123]
	v_mfma_f32_16x16x32_bf16 v[108:111], v[128:131], v[192:195], v[108:111]
	v_mfma_f32_16x16x32_bf16 v[104:107], v[136:139], v[192:195], v[104:107]
	v_mfma_f32_16x16x32_bf16 v[92:95], v[128:131], v[200:203], v[92:95]
	v_mfma_f32_16x16x32_bf16 v[88:91], v[136:139], v[200:203], v[88:91]
	v_mfma_f32_16x16x32_bf16 v[76:79], v[128:131], v[208:211], v[76:79]
	v_mfma_f32_16x16x32_bf16 v[72:75], v[136:139], v[208:211], v[72:75]
	v_mfma_f32_16x16x32_bf16 v[124:127], v[132:135], v[180:183], v[124:127]
	v_mfma_f32_16x16x32_bf16 v[120:123], v[140:143], v[180:183], v[120:123]
	v_mfma_f32_16x16x32_bf16 v[108:111], v[132:135], v[196:199], v[108:111]
	v_mfma_f32_16x16x32_bf16 v[104:107], v[140:143], v[196:199], v[104:107]
	v_mfma_f32_16x16x32_bf16 v[92:95], v[132:135], v[204:207], v[92:95]
	v_mfma_f32_16x16x32_bf16 v[88:91], v[140:143], v[204:207], v[88:91]
	v_mfma_f32_16x16x32_bf16 v[76:79], v[132:135], v[212:215], v[76:79]
	v_mfma_f32_16x16x32_bf16 v[72:75], v[140:143], v[212:215], v[72:75]
	v_mfma_f32_16x16x32_bf16 v[116:119], v[144:147], v[176:179], v[116:119]
	v_mfma_f32_16x16x32_bf16 v[112:115], v[168:171], v[176:179], v[112:115]
	v_mfma_f32_16x16x32_bf16 v[100:103], v[144:147], v[192:195], v[100:103]
	v_mfma_f32_16x16x32_bf16 v[96:99], v[168:171], v[192:195], v[96:99]
	v_mfma_f32_16x16x32_bf16 v[84:87], v[144:147], v[200:203], v[84:87]
	v_mfma_f32_16x16x32_bf16 v[80:83], v[168:171], v[200:203], v[80:83]
	v_mfma_f32_16x16x32_bf16 v[68:71], v[144:147], v[208:211], v[68:71]
	v_mfma_f32_16x16x32_bf16 v[64:67], v[168:171], v[208:211], v[64:67]
	v_mfma_f32_16x16x32_bf16 v[116:119], v[148:151], v[180:183], v[116:119]
	v_mfma_f32_16x16x32_bf16 v[112:115], v[172:175], v[180:183], v[112:115]
	v_mfma_f32_16x16x32_bf16 v[100:103], v[148:151], v[196:199], v[100:103]
	v_mfma_f32_16x16x32_bf16 v[96:99], v[172:175], v[196:199], v[96:99]
	v_mfma_f32_16x16x32_bf16 v[84:87], v[148:151], v[204:207], v[84:87]
	v_mfma_f32_16x16x32_bf16 v[80:83], v[172:175], v[204:207], v[80:83]
	v_mfma_f32_16x16x32_bf16 v[68:71], v[148:151], v[212:215], v[68:71]
	v_mfma_f32_16x16x32_bf16 v[64:67], v[172:175], v[212:215], v[64:67]
	s_barrier
; #define PG8_STAGE(bufoff, gbase, voff) do { _Pragma("unroll") for (int _i = 0; _i < 2; ++_i) \
;         __builtin_amdgcn_global_load_lds((const unsigned*)((const char*)(gbase) + (voff)[_i]), (PG8_LAS unsigned*)(lds + (bufoff) + ldsw + _i * 8192), 16, 0, 0); } while (0)
; #define PG8_LDA(dst, b, h) do { _Pragma("unroll") for (int m = 0; m < 4; ++m) _Pragma("unroll") for (int k = 0; k < 2; ++k) dst[m][k] = *(const PG8_LAS bf16x8*)(lds + PG8_SA(b, h) + aoff + m * 2048 + k * 1024); } while (0)
; #define PG8_MMA(ai, bj, At, Bt) do { __builtin_amdgcn_s_setprio(1); _Pragma("unroll") for (int m = 0; m < 4; ++m) _Pragma("unroll") for (int n = 0; n < 2; ++n) _Pragma("unroll") for (int k = 0; k < 2; ++k) \
;         acc[ai][bj][m][n] = mma16<F16>(Bt[n][k], At[m][k], acc[ai][bj][m][n]); __builtin_amdgcn_s_setprio(0); } while (0)
; #define PG8_WAIT_V(n) asm volatile("s_waitcnt vmcnt(" #n ")" ::: "memory")
; #define PG8_WAIT_L(n) asm volatile("s_waitcnt lgkmcnt(" #n ")" ::: "memory")
; #define PG8_BAR __builtin_amdgcn_s_barrier()
; #define PG8_SCHED __builtin_amdgcn_sched_barrier(0)
; template <class Epi, class Sched, bool ALIGN_EPI = false, bool SP2 = false, bool F16 = false>
; __device__ __forceinline__ void gemm_phase(PG8_LAS unsigned char* lds, const Gemm g, const Sched& S, const Epi& E, const int wid_in) {
;     ...
;             PG8_LDA(At, 1, 1); PG8_STAGE(PG8_SB(1, 0), b3, voffB); PG8_STAGE(PG8_SB(1, 1), b3 + hstep, voffB); PG8_STAGE(PG8_SA(1, 0), a3, voffA);
;             PG8_WAIT_V(8); PG8_WAIT_L(0); PG8_BAR; PG8_MMA(1, 0, At, B0); PG8_MMA(1, 1, At, B1); PG8_BAR; PG8_SCHED;
;     ...
;         }
;         if constexpr (ALIGN_EPI) { if (wr == 0) PG8_BAR; }
	s_add_i32 s48, s63, s68
	v_lshl_add_u64 v[184:185], v[184:185], 0, s[22:23]
	s_mov_b32 m0, s48
	ds_read_b128 v[176:179], v191 offset:49152
	ds_read_b128 v[180:183], v191 offset:50176
	ds_read_b128 v[192:195], v191 offset:51200
	ds_read_b128 v[196:199], v191 offset:52224
	ds_read_b128 v[200:203], v191 offset:53248
	ds_read_b128 v[204:207], v191 offset:54272
	ds_read_b128 v[208:211], v191 offset:55296
	ds_read_b128 v[212:215], v191 offset:56320
	global_load_lds_dwordx4 v[184:185], off
	s_add_i32 m0, s48, 0x2000
	s_add_u32 s46, s46, 0x40080
	v_lshl_add_u64 v[184:185], v[216:217], 0, s[22:23]
	s_addc_u32 s47, s47, 0
	s_add_i32 s48, s64, s68
	global_load_lds_dwordx4 v[184:185], off
	v_lshl_add_u64 v[184:185], s[46:47], 0, v[154:155]
	s_mov_b32 m0, s48
	s_nop 0
	global_load_lds_dwordx4 v[184:185], off
	v_lshl_add_u64 v[184:185], s[46:47], 0, v[158:159]
	s_add_i32 m0, s48, 0x2000
	s_nop 0
	global_load_lds_dwordx4 v[184:185], off
	v_lshl_add_u64 v[184:185], v[218:219], 0, s[22:23]
	s_mov_b32 m0, s75
	s_nop 0
	global_load_lds_dwordx4 v[184:185], off
	v_lshl_add_u64 v[184:185], v[220:221], 0, s[22:23]
	s_mov_b32 m0, s54
	s_nop 0
	global_load_lds_dwordx4 v[184:185], off
	s_waitcnt vmcnt(8)
	s_waitcnt lgkmcnt(0)
	s_barrier
	v_mfma_f32_16x16x32_bf16 v[60:63], v[128:131], v[176:179], v[60:63]
	v_mfma_f32_16x16x32_bf16 v[56:59], v[136:139], v[176:179], v[56:59]
	v_mfma_f32_16x16x32_bf16 v[44:47], v[128:131], v[192:195], v[44:47]
	v_mfma_f32_16x16x32_bf16 v[40:43], v[136:139], v[192:195], v[40:43]
	v_mfma_f32_16x16x32_bf16 v[28:31], v[128:131], v[200:203], v[28:31]
	v_mfma_f32_16x16x32_bf16 v[24:27], v[136:139], v[200:203], v[24:27]
	v_mfma_f32_16x16x32_bf16 v[12:15], v[128:131], v[208:211], v[12:15]
	v_mfma_f32_16x16x32_bf16 v[8:11], v[136:139], v[208:211], v[8:11]
	v_mfma_f32_16x16x32_bf16 v[60:63], v[132:135], v[180:183], v[60:63]
	v_mfma_f32_16x16x32_bf16 v[56:59], v[140:143], v[180:183], v[56:59]
	v_mfma_f32_16x16x32_bf16 v[44:47], v[132:135], v[196:199], v[44:47]
	v_mfma_f32_16x16x32_bf16 v[40:43], v[140:143], v[196:199], v[40:43]
	v_mfma_f32_16x16x32_bf16 v[28:31], v[132:135], v[204:207], v[28:31]
	v_mfma_f32_16x16x32_bf16 v[24:27], v[140:143], v[204:207], v[24:27]
	v_mfma_f32_16x16x32_bf16 v[12:15], v[132:135], v[212:215], v[12:15]
	v_mfma_f32_16x16x32_bf16 v[8:11], v[140:143], v[212:215], v[8:11]
	v_mfma_f32_16x16x32_bf16 v[52:55], v[144:147], v[176:179], v[52:55]
	v_mfma_f32_16x16x32_bf16 v[48:51], v[168:171], v[176:179], v[48:51]
	v_mfma_f32_16x16x32_bf16 v[36:39], v[144:147], v[192:195], v[36:39]
	v_mfma_f32_16x16x32_bf16 v[32:35], v[168:171], v[192:195], v[32:35]
	v_mfma_f32_16x16x32_bf16 v[20:23], v[144:147], v[200:203], v[20:23]
	v_mfma_f32_16x16x32_bf16 v[16:19], v[168:171], v[200:203], v[16:19]
	v_mfma_f32_16x16x32_bf16 v[4:7], v[144:147], v[208:211], v[4:7]
	v_mfma_f32_16x16x32_bf16 v[0:3], v[168:171], v[208:211], v[0:3]
	v_mfma_f32_16x16x32_bf16 v[52:55], v[148:151], v[180:183], v[52:55]
	v_mfma_f32_16x16x32_bf16 v[48:51], v[172:175], v[180:183], v[48:51]
	v_mfma_f32_16x16x32_bf16 v[36:39], v[148:151], v[196:199], v[36:39]
	v_mfma_f32_16x16x32_bf16 v[32:35], v[172:175], v[196:199], v[32:35]
	v_mfma_f32_16x16x32_bf16 v[20:23], v[148:151], v[204:207], v[20:23]
	v_mfma_f32_16x16x32_bf16 v[16:19], v[172:175], v[204:207], v[16:19]
	v_mfma_f32_16x16x32_bf16 v[4:7], v[148:151], v[212:215], v[4:7]
	v_mfma_f32_16x16x32_bf16 v[0:3], v[172:175], v[212:215], v[0:3]
	s_barrier
	s_add_i32 s43, s43, 2
	s_add_u32 s44, s44, 0x100
	s_addc_u32 s45, s45, 0
	s_add_u32 s37, s37, 0x100
	s_addc_u32 s42, s42, 0
	s_cmp_gt_u32 s43, 13
	s_cbranch_scc0 .LBB0_508
	s_and_b64 vcc, exec, s[16:17]
	s_cbranch_vccz .LBB0_511
	s_barrier

; #define PG8_STAGE(bufoff, gbase, voff) do { _Pragma("unroll") for (int _i = 0; _i < 2; ++_i) \
;         __builtin_amdgcn_global_load_lds((const unsigned*)((const char*)(gbase) + (voff)[_i]), (PG8_LAS unsigned*)(lds + (bufoff) + ldsw + _i * 8192), 16, 0, 0); } while (0)
; #define PG8_LDA(dst, b, h) do { _Pragma("unroll") for (int m = 0; m < 4; ++m) _Pragma("unroll") for (int k = 0; k < 2; ++k) dst[m][k] = *(const PG8_LAS bf16x8*)(lds + PG8_SA(b, h) + aoff + m * 2048 + k * 1024); } while (0)
; #define PG8_LDB(dst, b, h) do { _Pragma("unroll") for (int n = 0; n < 2; ++n) _Pragma("unroll") for (int k = 0; k < 2; ++k) dst[n][k] = *(const PG8_LAS bf16x8*)(lds + PG8_SB(b, h) + boff + n * 2048 + k * 1024); } while (0)
; #define PG8_MMA(ai, bj, At, Bt) do { __builtin_amdgcn_s_setprio(1); _Pragma("unroll") for (int m = 0; m < 4; ++m) _Pragma("unroll") for (int n = 0; n < 2; ++n) _Pragma("unroll") for (int k = 0; k < 2; ++k) \
;         acc[ai][bj][m][n] = mma16<F16>(Bt[n][k], At[m][k], acc[ai][bj][m][n]); __builtin_amdgcn_s_setprio(0); } while (0)
; #define PG8_WAIT_V(n) asm volatile("s_waitcnt vmcnt(" #n ")" ::: "memory")
; #define PG8_WAIT_L(n) asm volatile("s_waitcnt lgkmcnt(" #n ")" ::: "memory")
; #define PG8_BAR __builtin_amdgcn_s_barrier()
; #define PG8_SCHED __builtin_amdgcn_sched_barrier(0)
; template <class Epi, class Sched, bool ALIGN_EPI = false, bool SP2 = false, bool F16 = false>
; __device__ __forceinline__ void gemm_phase(PG8_LAS unsigned char* lds, const Gemm g, const Sched& S, const Epi& E, const int wid_in) {
;     ...
;             PG8_LDB(B0, 0, 0); PG8_LDB(B1, 0, 1); PG8_SCHED; PG8_LDA(At, 0, 0); PG8_STAGE(PG8_SA(1, 1), a1 + hstep, voffA);
;             PG8_WAIT_V(8); PG8_WAIT_L(0); PG8_BAR; PG8_MMA(0, 0, At, B0); PG8_MMA(0, 1, At, B1); PG8_BAR; PG8_SCHED;
;             PG8_LDA(At, 0, 1); PG8_STAGE(PG8_SB(0, 0), b2, voffB); PG8_STAGE(PG8_SB(0, 1), b2 + hstep, voffB); PG8_STAGE(PG8_SA(0, 0), a2, voffA);
;             PG8_WAIT_V(8); PG8_WAIT_L(0); PG8_BAR; PG8_MMA(1, 0, At, B0); PG8_MMA(1, 1, At, B1); PG8_BAR; PG8_SCHED;
.LBB0_585:
	ds_read_b128 v[0:3], v193
	ds_read_b128 v[4:7], v193 offset:1024
	ds_read_b128 v[136:139], v193 offset:2048
	ds_read_b128 v[140:143], v193 offset:3072
	ds_read_b128 v[144:147], v194
	ds_read_b128 v[148:151], v194 offset:1024
	ds_read_b128 v[152:155], v194 offset:2048
	ds_read_b128 v[156:159], v194 offset:3072
	s_add_u32 s36, s34, 0xfffc0080
	s_addc_u32 s37, s35, -1
	s_cmp_eq_u32 s65, 12
	s_cselect_b32 s45, s23, s37
	s_cselect_b32 s44, s31, s36
	s_cselect_b32 s37, s21, s64
	s_cselect_b32 s36, s42, s43
	v_lshl_add_u64 v[188:189], s[34:35], 0, v[168:169]
	s_add_i32 m0, s74, 0xc000
	ds_read_b128 v[176:179], v195
	ds_read_b128 v[180:183], v195 offset:1024
	ds_read_b128 v[184:187], v195 offset:2048
	ds_read_b128 v[198:201], v195 offset:3072
	ds_read_b128 v[202:205], v195 offset:4096
	ds_read_b128 v[206:209], v195 offset:5120
	ds_read_b128 v[210:213], v195 offset:6144
	ds_read_b128 v[214:217], v195 offset:7168
	global_load_lds_dwordx4 v[188:189], off
	v_lshl_add_u64 v[188:189], s[34:35], 0, v[170:171]
	s_add_i32 m0, s74, 0xe000
	s_nop 0
	global_load_lds_dwordx4 v[188:189], off
	s_waitcnt vmcnt(8)
	s_waitcnt lgkmcnt(0)
	s_barrier
	v_mfma_f32_16x16x32_f16 v[132:135], v[0:3], v[176:179], v[132:135]
	v_mfma_f32_16x16x32_f16 v[128:131], v[136:139], v[176:179], v[128:131]
	v_mfma_f32_16x16x32_f16 v[116:119], v[0:3], v[184:187], v[116:119]
	v_mfma_f32_16x16x32_f16 v[112:115], v[136:139], v[184:187], v[112:115]
	v_mfma_f32_16x16x32_f16 v[100:103], v[0:3], v[202:205], v[100:103]
	v_mfma_f32_16x16x32_f16 v[96:99], v[136:139], v[202:205], v[96:99]
	v_mfma_f32_16x16x32_f16 v[84:87], v[0:3], v[210:213], v[84:87]
	v_mfma_f32_16x16x32_f16 v[80:83], v[136:139], v[210:213], v[80:83]
	v_mfma_f32_16x16x32_f16 v[132:135], v[4:7], v[180:183], v[132:135]
	v_mfma_f32_16x16x32_f16 v[128:131], v[140:143], v[180:183], v[128:131]
	v_mfma_f32_16x16x32_f16 v[116:119], v[4:7], v[198:201], v[116:119]
	v_mfma_f32_16x16x32_f16 v[112:115], v[140:143], v[198:201], v[112:115]
	v_mfma_f32_16x16x32_f16 v[100:103], v[4:7], v[206:209], v[100:103]
	v_mfma_f32_16x16x32_f16 v[96:99], v[140:143], v[206:209], v[96:99]
	v_mfma_f32_16x16x32_f16 v[84:87], v[4:7], v[214:217], v[84:87]
	v_mfma_f32_16x16x32_f16 v[80:83], v[140:143], v[214:217], v[80:83]
	v_mfma_f32_16x16x32_f16 v[124:127], v[144:147], v[176:179], v[124:127]
	v_mfma_f32_16x16x32_f16 v[120:123], v[152:155], v[176:179], v[120:123]
	v_mfma_f32_16x16x32_f16 v[108:111], v[144:147], v[184:187], v[108:111]
	v_mfma_f32_16x16x32_f16 v[104:107], v[152:155], v[184:187], v[104:107]
	v_mfma_f32_16x16x32_f16 v[92:95], v[144:147], v[202:205], v[92:95]
	v_mfma_f32_16x16x32_f16 v[88:91], v[152:155], v[202:205], v[88:91]
	v_mfma_f32_16x16x32_f16 v[76:79], v[144:147], v[210:213], v[76:79]
	v_mfma_f32_16x16x32_f16 v[72:75], v[152:155], v[210:213], v[72:75]
	v_mfma_f32_16x16x32_f16 v[124:127], v[148:151], v[180:183], v[124:127]
	v_mfma_f32_16x16x32_f16 v[120:123], v[156:159], v[180:183], v[120:123]
	v_mfma_f32_16x16x32_f16 v[108:111], v[148:151], v[198:201], v[108:111]
	v_mfma_f32_16x16x32_f16 v[104:107], v[156:159], v[198:201], v[104:107]
	v_mfma_f32_16x16x32_f16 v[92:95], v[148:151], v[206:209], v[92:95]
	v_mfma_f32_16x16x32_f16 v[88:91], v[156:159], v[206:209], v[88:91]
	v_mfma_f32_16x16x32_f16 v[76:79], v[148:151], v[214:217], v[76:79]
	v_mfma_f32_16x16x32_f16 v[72:75], v[156:159], v[214:217], v[72:75]
	s_barrier
	s_add_i32 s66, s61, s68
	v_lshl_add_u64 v[188:189], s[36:37], 0, v[162:163]
	s_mov_b32 m0, s66
	ds_read_b128 v[176:179], v195 offset:16384
	ds_read_b128 v[180:183], v195 offset:17408
	ds_read_b128 v[184:187], v195 offset:18432
	ds_read_b128 v[198:201], v195 offset:19456
	ds_read_b128 v[202:205], v195 offset:20480
	ds_read_b128 v[206:209], v195 offset:21504
	ds_read_b128 v[210:213], v195 offset:22528
	ds_read_b128 v[214:217], v195 offset:23552
	global_load_lds_dwordx4 v[188:189], off
	s_add_i32 m0, s66, 0x2000
	s_add_u32 s66, s36, 0x40000
	v_lshl_add_u64 v[218:219], s[36:37], 0, v[166:167]
	s_addc_u32 s67, s37, 0
	s_add_i32 s76, s62, s68
	global_load_lds_dwordx4 v[218:219], off
	v_lshl_add_u64 v[220:221], s[66:67], 0, v[162:163]
	s_mov_b32 m0, s76
	v_lshl_add_u64 v[222:223], s[44:45], 0, v[164:165]
	global_load_lds_dwordx4 v[220:221], off
	v_lshl_add_u64 v[220:221], s[66:67], 0, v[166:167]
	s_add_i32 m0, s76, 0x2000
	s_nop 0
	global_load_lds_dwordx4 v[220:221], off
	v_lshl_add_u64 v[220:221], s[44:45], 0, v[160:161]
	s_mov_b32 m0, s74
	s_nop 0
	global_load_lds_dwordx4 v[220:221], off
	s_mov_b32 m0, s29
	s_nop 0
	global_load_lds_dwordx4 v[222:223], off
	s_waitcnt vmcnt(8)
	s_waitcnt lgkmcnt(0)
	s_barrier
; #define PG8_STAGE(bufoff, gbase, voff) do { _Pragma("unroll") for (int _i = 0; _i < 2; ++_i) \
;         __builtin_amdgcn_global_load_lds((const unsigned*)((const char*)(gbase) + (voff)[_i]), (PG8_LAS unsigned*)(lds + (bufoff) + ldsw + _i * 8192), 16, 0, 0); } while (0)
; #define PG8_LDA(dst, b, h) do { _Pragma("unroll") for (int m = 0; m < 4; ++m) _Pragma("unroll") for (int k = 0; k < 2; ++k) dst[m][k] = *(const PG8_LAS bf16x8*)(lds + PG8_SA(b, h) + aoff + m * 2048 + k * 1024); } while (0)
; #define PG8_LDB(dst, b, h) do { _Pragma("unroll") for (int n = 0; n < 2; ++n) _Pragma("unroll") for (int k = 0; k < 2; ++k) dst[n][k] = *(const PG8_LAS bf16x8*)(lds + PG8_SB(b, h) + boff + n * 2048 + k * 1024); } while (0)
; #define PG8_MMA(ai, bj, At, Bt) do { __builtin_amdgcn_s_setprio(1); _Pragma("unroll") for (int m = 0; m < 4; ++m) _Pragma("unroll") for (int n = 0; n < 2; ++n) _Pragma("unroll") for (int k = 0; k < 2; ++k) \
;         acc[ai][bj][m][n] = mma16<F16>(Bt[n][k], At[m][k], acc[ai][bj][m][n]); __builtin_amdgcn_s_setprio(0); } while (0)
; #define PG8_WAIT_V(n) asm volatile("s_waitcnt vmcnt(" #n ")" ::: "memory")
; #define PG8_WAIT_L(n) asm volatile("s_waitcnt lgkmcnt(" #n ")" ::: "memory")
; #define PG8_BAR __builtin_amdgcn_s_barrier()
; #define PG8_SCHED __builtin_amdgcn_sched_barrier(0)
; template <class Epi, class Sched, bool ALIGN_EPI = false, bool SP2 = false, bool F16 = false>
; __device__ __forceinline__ void gemm_phase(PG8_LAS unsigned char* lds, const Gemm g, const Sched& S, const Epi& E, const int wid_in) {
;     ...
;             PG8_WAIT_V(8); PG8_WAIT_L(0); PG8_BAR; PG8_MMA(1, 0, At, B0); PG8_MMA(1, 1, At, B1); PG8_BAR; PG8_SCHED;
;             PG8_LDB(B0, 1, 0); PG8_LDB(B1, 1, 1); PG8_SCHED; PG8_LDA(At, 1, 0); PG8_STAGE(PG8_SA(0, 1), a2 + hstep, voffA);
;             PG8_WAIT_V(8); PG8_WAIT_L(0); PG8_BAR; PG8_MMA(0, 0, At, B0); PG8_MMA(0, 1, At, B1); PG8_BAR; PG8_SCHED;
	v_mfma_f32_16x16x32_f16 v[68:71], v[0:3], v[176:179], v[68:71]
	v_mfma_f32_16x16x32_f16 v[64:67], v[136:139], v[176:179], v[64:67]
	v_mfma_f32_16x16x32_f16 v[52:55], v[0:3], v[184:187], v[52:55]
	v_mfma_f32_16x16x32_f16 v[48:51], v[136:139], v[184:187], v[48:51]
	v_mfma_f32_16x16x32_f16 v[36:39], v[0:3], v[202:205], v[36:39]
	v_mfma_f32_16x16x32_f16 v[32:35], v[136:139], v[202:205], v[32:35]
	v_mfma_f32_16x16x32_f16 v[0:3], v[0:3], v[210:213], v[20:23]
	v_mfma_f32_16x16x32_f16 v[68:71], v[4:7], v[180:183], v[68:71]
	v_mfma_f32_16x16x32_f16 v[64:67], v[140:143], v[180:183], v[64:67]
	v_mfma_f32_16x16x32_f16 v[52:55], v[4:7], v[198:201], v[52:55]
	v_mfma_f32_16x16x32_f16 v[48:51], v[140:143], v[198:201], v[48:51]
	v_mfma_f32_16x16x32_f16 v[36:39], v[4:7], v[206:209], v[36:39]
	v_mfma_f32_16x16x32_f16 v[32:35], v[140:143], v[206:209], v[32:35]
	v_mfma_f32_16x16x32_f16 v[0:3], v[4:7], v[214:217], v[0:3]
	v_mfma_f32_16x16x32_f16 v[4:7], v[136:139], v[210:213], v[16:19]
	v_mfma_f32_16x16x32_f16 v[4:7], v[140:143], v[214:217], v[4:7]
	v_mfma_f32_16x16x32_f16 v[16:19], v[144:147], v[176:179], v[60:63]
	v_mfma_f32_16x16x32_f16 v[60:63], v[148:151], v[180:183], v[16:19]
	v_mfma_f32_16x16x32_f16 v[16:19], v[152:155], v[176:179], v[56:59]
	v_mfma_f32_16x16x32_f16 v[56:59], v[156:159], v[180:183], v[16:19]
	v_mfma_f32_16x16x32_f16 v[16:19], v[144:147], v[184:187], v[44:47]
	v_mfma_f32_16x16x32_f16 v[44:47], v[148:151], v[198:201], v[16:19]
	v_mfma_f32_16x16x32_f16 v[16:19], v[152:155], v[184:187], v[40:43]
	v_mfma_f32_16x16x32_f16 v[40:43], v[156:159], v[198:201], v[16:19]
	v_mfma_f32_16x16x32_f16 v[16:19], v[144:147], v[202:205], v[28:31]
	v_mfma_f32_16x16x32_f16 v[28:31], v[148:151], v[206:209], v[16:19]
	v_mfma_f32_16x16x32_f16 v[16:19], v[152:155], v[202:205], v[24:27]
	v_mfma_f32_16x16x32_f16 v[12:15], v[144:147], v[210:213], v[12:15]
	v_mfma_f32_16x16x32_f16 v[8:11], v[152:155], v[210:213], v[8:11]
	v_mfma_f32_16x16x32_f16 v[24:27], v[156:159], v[206:209], v[16:19]
	v_mfma_f32_16x16x32_f16 v[12:15], v[148:151], v[214:217], v[12:15]
	v_mfma_f32_16x16x32_f16 v[8:11], v[156:159], v[214:217], v[8:11]
	s_barrier
	s_add_i32 s66, 0, 0x18000
	s_add_i32 s67, 0, 0x1c000
	v_add_u32_e32 v140, s66, v192
	v_add_u32_e32 v156, s67, v192
	ds_read_b128 v[16:19], v140
	ds_read_b128 v[20:23], v140 offset:1024
	ds_read_b128 v[136:139], v140 offset:2048
	ds_read_b128 v[140:143], v140 offset:3072
	ds_read_b128 v[144:147], v156
	ds_read_b128 v[148:151], v156 offset:1024
	ds_read_b128 v[152:155], v156 offset:2048
	ds_read_b128 v[156:159], v156 offset:3072
	s_add_u32 s44, s44, 0x40000
	s_addc_u32 s45, s45, 0
	s_mov_b32 m0, s49
	v_lshl_add_u64 v[224:225], s[44:45], 0, v[160:161]
	ds_read_b128 v[176:179], v195 offset:32768
	ds_read_b128 v[180:183], v195 offset:33792
	ds_read_b128 v[184:187], v195 offset:34816
	ds_read_b128 v[198:201], v195 offset:35840
	ds_read_b128 v[202:205], v195 offset:36864
	ds_read_b128 v[206:209], v195 offset:37888
	ds_read_b128 v[210:213], v195 offset:38912
	ds_read_b128 v[214:217], v195 offset:39936
	global_load_lds_dwordx4 v[224:225], off
	v_lshl_add_u64 v[224:225], s[44:45], 0, v[164:165]
	s_mov_b32 m0, s50
	s_nop 0
	global_load_lds_dwordx4 v[224:225], off
	s_waitcnt vmcnt(8)
	s_waitcnt lgkmcnt(0)
	s_barrier
	v_mfma_f32_16x16x32_f16 v[132:135], v[16:19], v[176:179], v[132:135]
	v_mfma_f32_16x16x32_f16 v[128:131], v[136:139], v[176:179], v[128:131]
	v_mfma_f32_16x16x32_f16 v[116:119], v[16:19], v[184:187], v[116:119]
	v_mfma_f32_16x16x32_f16 v[112:115], v[136:139], v[184:187], v[112:115]
	v_mfma_f32_16x16x32_f16 v[100:103], v[16:19], v[202:205], v[100:103]
	v_mfma_f32_16x16x32_f16 v[96:99], v[136:139], v[202:205], v[96:99]
	v_mfma_f32_16x16x32_f16 v[84:87], v[16:19], v[210:213], v[84:87]
	v_mfma_f32_16x16x32_f16 v[80:83], v[136:139], v[210:213], v[80:83]
	v_mfma_f32_16x16x32_f16 v[132:135], v[20:23], v[180:183], v[132:135]
	v_mfma_f32_16x16x32_f16 v[128:131], v[140:143], v[180:183], v[128:131]
	v_mfma_f32_16x16x32_f16 v[116:119], v[20:23], v[198:201], v[116:119]
	v_mfma_f32_16x16x32_f16 v[112:115], v[140:143], v[198:201], v[112:115]
	v_mfma_f32_16x16x32_f16 v[100:103], v[20:23], v[206:209], v[100:103]
	v_mfma_f32_16x16x32_f16 v[96:99], v[140:143], v[206:209], v[96:99]
	v_mfma_f32_16x16x32_f16 v[84:87], v[20:23], v[214:217], v[84:87]
	v_mfma_f32_16x16x32_f16 v[80:83], v[140:143], v[214:217], v[80:83]
	v_mfma_f32_16x16x32_f16 v[124:127], v[144:147], v[176:179], v[124:127]
	v_mfma_f32_16x16x32_f16 v[120:123], v[152:155], v[176:179], v[120:123]
	v_mfma_f32_16x16x32_f16 v[108:111], v[144:147], v[184:187], v[108:111]
	v_mfma_f32_16x16x32_f16 v[104:107], v[152:155], v[184:187], v[104:107]
	v_mfma_f32_16x16x32_f16 v[92:95], v[144:147], v[202:205], v[92:95]
	v_mfma_f32_16x16x32_f16 v[88:91], v[152:155], v[202:205], v[88:91]
	v_mfma_f32_16x16x32_f16 v[76:79], v[144:147], v[210:213], v[76:79]
	v_mfma_f32_16x16x32_f16 v[72:75], v[152:155], v[210:213], v[72:75]
	v_mfma_f32_16x16x32_f16 v[124:127], v[148:151], v[180:183], v[124:127]
	v_mfma_f32_16x16x32_f16 v[120:123], v[156:159], v[180:183], v[120:123]
	v_mfma_f32_16x16x32_f16 v[108:111], v[148:151], v[198:201], v[108:111]
	v_mfma_f32_16x16x32_f16 v[104:107], v[156:159], v[198:201], v[104:107]
	v_mfma_f32_16x16x32_f16 v[92:95], v[148:151], v[206:209], v[92:95]
	v_mfma_f32_16x16x32_f16 v[88:91], v[156:159], v[206:209], v[88:91]
	v_mfma_f32_16x16x32_f16 v[76:79], v[148:151], v[214:217], v[76:79]
	v_mfma_f32_16x16x32_f16 v[72:75], v[156:159], v[214:217], v[72:75]
	s_barrier
; #define PG8_STAGE(bufoff, gbase, voff) do { _Pragma("unroll") for (int _i = 0; _i < 2; ++_i) \
;         __builtin_amdgcn_global_load_lds((const unsigned*)((const char*)(gbase) + (voff)[_i]), (PG8_LAS unsigned*)(lds + (bufoff) + ldsw + _i * 8192), 16, 0, 0); } while (0)
; #define PG8_LDA(dst, b, h) do { _Pragma("unroll") for (int m = 0; m < 4; ++m) _Pragma("unroll") for (int k = 0; k < 2; ++k) dst[m][k] = *(const PG8_LAS bf16x8*)(lds + PG8_SA(b, h) + aoff + m * 2048 + k * 1024); } while (0)
; #define PG8_MMA(ai, bj, At, Bt) do { __builtin_amdgcn_s_setprio(1); _Pragma("unroll") for (int m = 0; m < 4; ++m) _Pragma("unroll") for (int n = 0; n < 2; ++n) _Pragma("unroll") for (int k = 0; k < 2; ++k) \
;         acc[ai][bj][m][n] = mma16<F16>(Bt[n][k], At[m][k], acc[ai][bj][m][n]); __builtin_amdgcn_s_setprio(0); } while (0)
; #define PG8_WAIT_V(n) asm volatile("s_waitcnt vmcnt(" #n ")" ::: "memory")
; #define PG8_WAIT_L(n) asm volatile("s_waitcnt lgkmcnt(" #n ")" ::: "memory")
; #define PG8_BAR __builtin_amdgcn_s_barrier()
; #define PG8_SCHED __builtin_amdgcn_sched_barrier(0)
; template <class Epi, class Sched, bool ALIGN_EPI = false, bool SP2 = false, bool F16 = false>
; __device__ __forceinline__ void gemm_phase(PG8_LAS unsigned char* lds, const Gemm g, const Sched& S, const Epi& E, const int wid_in) {
;     ...
;             PG8_LDA(At, 1, 1); PG8_STAGE(PG8_SB(1, 0), b3, voffB); PG8_STAGE(PG8_SB(1, 1), b3 + hstep, voffB); PG8_STAGE(PG8_SA(1, 0), a3, voffA);
;             PG8_WAIT_V(8); PG8_WAIT_L(0); PG8_BAR; PG8_MMA(1, 0, At, B0); PG8_MMA(1, 1, At, B1); PG8_BAR; PG8_SCHED;
;     ...
;         }
;         if constexpr (ALIGN_EPI) { if (wr == 0) PG8_BAR; }
	s_add_i32 s44, s66, s68
	v_lshl_add_u64 v[188:189], v[188:189], 0, s[18:19]
	s_mov_b32 m0, s44
	ds_read_b128 v[176:179], v195 offset:49152
	ds_read_b128 v[180:183], v195 offset:50176
	ds_read_b128 v[184:187], v195 offset:51200
	ds_read_b128 v[198:201], v195 offset:52224
	ds_read_b128 v[202:205], v195 offset:53248
	ds_read_b128 v[206:209], v195 offset:54272
	ds_read_b128 v[210:213], v195 offset:55296
	ds_read_b128 v[214:217], v195 offset:56320
	global_load_lds_dwordx4 v[188:189], off
	s_add_i32 m0, s44, 0x2000
	s_add_u32 s36, s36, 0x40080
	v_lshl_add_u64 v[188:189], v[218:219], 0, s[18:19]
	s_addc_u32 s37, s37, 0
	s_add_i32 s44, s67, s68
	global_load_lds_dwordx4 v[188:189], off
	v_lshl_add_u64 v[188:189], s[36:37], 0, v[162:163]
	s_mov_b32 m0, s44
	s_nop 0
	global_load_lds_dwordx4 v[188:189], off
	v_lshl_add_u64 v[188:189], s[36:37], 0, v[166:167]
	s_add_i32 m0, s44, 0x2000
	s_nop 0
	global_load_lds_dwordx4 v[188:189], off
	v_lshl_add_u64 v[188:189], v[220:221], 0, s[18:19]
	s_mov_b32 m0, s75
	s_nop 0
	global_load_lds_dwordx4 v[188:189], off
	v_lshl_add_u64 v[188:189], v[222:223], 0, s[18:19]
	s_mov_b32 m0, s53
	s_nop 0
	global_load_lds_dwordx4 v[188:189], off
	s_waitcnt vmcnt(8)
	s_waitcnt lgkmcnt(0)
	s_barrier
	v_mfma_f32_16x16x32_f16 v[68:71], v[16:19], v[176:179], v[68:71]
	v_mfma_f32_16x16x32_f16 v[52:55], v[16:19], v[184:187], v[52:55]
	v_mfma_f32_16x16x32_f16 v[36:39], v[16:19], v[202:205], v[36:39]
	v_mfma_f32_16x16x32_f16 v[0:3], v[16:19], v[210:213], v[0:3]
	v_mfma_f32_16x16x32_f16 v[68:71], v[20:23], v[180:183], v[68:71]
	v_mfma_f32_16x16x32_f16 v[64:67], v[136:139], v[176:179], v[64:67]
	v_mfma_f32_16x16x32_f16 v[52:55], v[20:23], v[198:201], v[52:55]
	v_mfma_f32_16x16x32_f16 v[48:51], v[136:139], v[184:187], v[48:51]
	v_mfma_f32_16x16x32_f16 v[36:39], v[20:23], v[206:209], v[36:39]
	v_mfma_f32_16x16x32_f16 v[32:35], v[136:139], v[202:205], v[32:35]
	v_mfma_f32_16x16x32_f16 v[20:23], v[20:23], v[214:217], v[0:3]
	v_mfma_f32_16x16x32_f16 v[0:3], v[136:139], v[210:213], v[4:7]
	v_mfma_f32_16x16x32_f16 v[64:67], v[140:143], v[180:183], v[64:67]
	v_mfma_f32_16x16x32_f16 v[48:51], v[140:143], v[198:201], v[48:51]
	v_mfma_f32_16x16x32_f16 v[32:35], v[140:143], v[206:209], v[32:35]
	v_mfma_f32_16x16x32_f16 v[16:19], v[140:143], v[214:217], v[0:3]
	v_mfma_f32_16x16x32_f16 v[0:3], v[144:147], v[176:179], v[60:63]
	v_mfma_f32_16x16x32_f16 v[60:63], v[148:151], v[180:183], v[0:3]
	v_mfma_f32_16x16x32_f16 v[0:3], v[152:155], v[176:179], v[56:59]
	v_mfma_f32_16x16x32_f16 v[56:59], v[156:159], v[180:183], v[0:3]
	v_mfma_f32_16x16x32_f16 v[0:3], v[144:147], v[184:187], v[44:47]
	v_mfma_f32_16x16x32_f16 v[44:47], v[148:151], v[198:201], v[0:3]
	v_mfma_f32_16x16x32_f16 v[0:3], v[152:155], v[184:187], v[40:43]
	v_mfma_f32_16x16x32_f16 v[40:43], v[156:159], v[198:201], v[0:3]
	v_mfma_f32_16x16x32_f16 v[0:3], v[144:147], v[202:205], v[28:31]
	v_mfma_f32_16x16x32_f16 v[28:31], v[148:151], v[206:209], v[0:3]
	v_mfma_f32_16x16x32_f16 v[0:3], v[152:155], v[202:205], v[24:27]
	v_mfma_f32_16x16x32_f16 v[24:27], v[156:159], v[206:209], v[0:3]
	v_mfma_f32_16x16x32_f16 v[0:3], v[144:147], v[210:213], v[12:15]
	v_mfma_f32_16x16x32_f16 v[12:15], v[148:151], v[214:217], v[0:3]
	v_mfma_f32_16x16x32_f16 v[0:3], v[152:155], v[210:213], v[8:11]
	v_mfma_f32_16x16x32_f16 v[8:11], v[156:159], v[214:217], v[0:3]
	s_barrier
	s_add_i32 s65, s65, 2
	s_add_u32 s34, s34, 0x100
	s_addc_u32 s35, s35, 0
	s_add_u32 s43, s43, 0x100
	s_addc_u32 s64, s64, 0
	s_cmp_gt_u32 s65, 13
	s_cbranch_scc0 .LBB0_585
	s_and_b64 vcc, exec, s[16:17]
	s_cbranch_vccz .LBB0_588
	s_barrier

; #define PG8_STAGE(bufoff, gbase, voff) do { _Pragma("unroll") for (int _i = 0; _i < 2; ++_i) \
;         __builtin_amdgcn_global_load_lds((const unsigned*)((const char*)(gbase) + (voff)[_i]), (PG8_LAS unsigned*)(lds + (bufoff) + ldsw + _i * 8192), 16, 0, 0); } while (0)
; #define PG8_LDA(dst, b, h) do { _Pragma("unroll") for (int m = 0; m < 4; ++m) _Pragma("unroll") for (int k = 0; k < 2; ++k) dst[m][k] = *(const PG8_LAS bf16x8*)(lds + PG8_SA(b, h) + aoff + m * 2048 + k * 1024); } while (0)
; #define PG8_LDB(dst, b, h) do { _Pragma("unroll") for (int n = 0; n < 2; ++n) _Pragma("unroll") for (int k = 0; k < 2; ++k) dst[n][k] = *(const PG8_LAS bf16x8*)(lds + PG8_SB(b, h) + boff + n * 2048 + k * 1024); } while (0)
; #define PG8_MMA(ai, bj, At, Bt) do { __builtin_amdgcn_s_setprio(1); _Pragma("unroll") for (int m = 0; m < 4; ++m) _Pragma("unroll") for (int n = 0; n < 2; ++n) _Pragma("unroll") for (int k = 0; k < 2; ++k) \
;         acc[ai][bj][m][n] = mma16<F16>(Bt[n][k], At[m][k], acc[ai][bj][m][n]); __builtin_amdgcn_s_setprio(0); } while (0)
; #define PG8_WAIT_V(n) asm volatile("s_waitcnt vmcnt(" #n ")" ::: "memory")
; #define PG8_WAIT_L(n) asm volatile("s_waitcnt lgkmcnt(" #n ")" ::: "memory")
; #define PG8_BAR __builtin_amdgcn_s_barrier()
; #define PG8_SCHED __builtin_amdgcn_sched_barrier(0)
; template <class Epi, class Sched, bool ALIGN_EPI = false, bool SP2 = false, bool F16 = false>
; __device__ __forceinline__ void gemm_phase(PG8_LAS unsigned char* lds, const Gemm g, const Sched& S, const Epi& E, const int wid_in) {
;     ...
;         const bool has_next = S.next(ui + 1, nxt);
;         const char* nA = has_next ? (const char*)g.A + (size_t)nxt.pm * tstep : cA; const char* nB = has_next ? (const char*)g.Bt + (size_t)nxt.pn * tstep : cB;
;     ...
;             PG8_LDB(B0, 0, 0); PG8_LDB(B1, 0, 1); PG8_SCHED; PG8_LDA(At, 0, 0); PG8_STAGE(PG8_SA(1, 1), a1 + hstep, voffA);
;             PG8_WAIT_V(8); PG8_WAIT_L(0); PG8_BAR; PG8_MMA(0, 0, At, B0); PG8_MMA(0, 1, At, B1); PG8_BAR; PG8_SCHED;
;             PG8_LDA(At, 0, 1); PG8_STAGE(PG8_SB(0, 0), b2, voffB); PG8_STAGE(PG8_SB(0, 1), b2 + hstep, voffB); PG8_STAGE(PG8_SA(0, 0), a2, voffA);
;             PG8_WAIT_V(8); PG8_WAIT_L(0); PG8_BAR; PG8_MMA(1, 0, At, B0); PG8_MMA(1, 1, At, B1); PG8_BAR; PG8_SCHED;
.LBB0_620:
	s_mov_b64 s[44:45], s[10:11]
	s_add_i32 s10, s30, s40
	s_mov_b64 s[36:37], s[12:13]
	s_mov_b32 s12, s62
	s_mov_b32 s13, s61
	s_and_b32 s61, s10, 3
	s_ashr_i32 s62, s10, 2
	s_and_b64 s[10:11], s[26:27], exec
	s_cselect_b32 s12, s62, s12
	ds_read_b128 v[0:3], v134
	ds_read_b128 v[4:7], v134 offset:1024
	ds_read_b128 v[8:11], v134 offset:2048
	ds_read_b128 v[12:15], v134 offset:3072
	ds_read_b128 v[16:19], v135
	ds_read_b128 v[20:23], v135 offset:1024
	ds_read_b128 v[24:27], v135 offset:2048
	ds_read_b128 v[28:31], v135 offset:3072
	s_cselect_b32 s10, s61, s13
	s_ashr_i32 s13, s12, 31
	s_lshl_b64 s[12:13], s[12:13], 17
	s_add_u32 s12, s43, s12
	s_addc_u32 s13, s46, s13
	s_and_b64 s[30:31], s[26:27], exec
	s_cselect_b32 s35, s13, s37
	s_cselect_b32 s34, s12, s36
	s_ashr_i32 s11, s10, 31
	s_lshl_b64 s[10:11], s[10:11], 17
	s_add_u32 s10, s41, s10
	s_addc_u32 s11, s42, s11
	s_and_b64 s[30:31], s[26:27], exec
	s_cselect_b32 s31, s11, s45
	s_cselect_b32 s30, s10, s44
	s_add_u32 s64, s36, 0x10080
	s_addc_u32 s65, s37, 0
	s_mov_b32 m0, s15
	v_lshl_add_u64 v[64:65], s[64:65], 0, v[130:131]
	ds_read_b128 v[32:35], v136
	ds_read_b128 v[36:39], v136 offset:1024
	ds_read_b128 v[40:43], v136 offset:2048
	ds_read_b128 v[44:47], v136 offset:3072
	ds_read_b128 v[48:51], v136 offset:4096
	ds_read_b128 v[52:55], v136 offset:5120
	ds_read_b128 v[56:59], v136 offset:6144
	ds_read_b128 v[60:63], v136 offset:7168
	global_load_lds_dwordx4 v[64:65], off
	v_lshl_add_u64 v[64:65], s[64:65], 0, v[128:129]
	s_mov_b32 m0, s50
	s_nop 0
	global_load_lds_dwordx4 v[64:65], off
	s_waitcnt vmcnt(8)
	s_waitcnt lgkmcnt(0)
	s_barrier
	v_mfma_f32_16x16x32_bf16 v[64:67], v[0:3], v[32:35], 0
	v_mfma_f32_16x16x32_bf16 v[68:71], v[8:11], v[32:35], 0
	v_mfma_f32_16x16x32_bf16 v[72:75], v[0:3], v[40:43], 0
	v_mfma_f32_16x16x32_bf16 v[76:79], v[8:11], v[40:43], 0
	v_mfma_f32_16x16x32_bf16 v[80:83], v[0:3], v[48:51], 0
	v_mfma_f32_16x16x32_bf16 v[84:87], v[8:11], v[48:51], 0
	v_mfma_f32_16x16x32_bf16 v[88:91], v[0:3], v[56:59], 0
	v_mfma_f32_16x16x32_bf16 v[92:95], v[8:11], v[56:59], 0
	v_mfma_f32_16x16x32_bf16 v[64:67], v[4:7], v[36:39], v[64:67]
	v_mfma_f32_16x16x32_bf16 v[68:71], v[12:15], v[36:39], v[68:71]
	v_mfma_f32_16x16x32_bf16 v[72:75], v[4:7], v[44:47], v[72:75]
	v_mfma_f32_16x16x32_bf16 v[76:79], v[12:15], v[44:47], v[76:79]
	v_mfma_f32_16x16x32_bf16 v[80:83], v[4:7], v[52:55], v[80:83]
	v_mfma_f32_16x16x32_bf16 v[84:87], v[12:15], v[52:55], v[84:87]
	v_mfma_f32_16x16x32_bf16 v[88:91], v[4:7], v[60:63], v[88:91]
	v_mfma_f32_16x16x32_bf16 v[92:95], v[12:15], v[60:63], v[92:95]
	v_mfma_f32_16x16x32_bf16 v[96:99], v[16:19], v[32:35], 0
	v_mfma_f32_16x16x32_bf16 v[32:35], v[24:27], v[32:35], 0
	v_mfma_f32_16x16x32_bf16 v[96:99], v[20:23], v[36:39], v[96:99]
	v_mfma_f32_16x16x32_bf16 v[32:35], v[28:31], v[36:39], v[32:35]
	v_mfma_f32_16x16x32_bf16 v[36:39], v[16:19], v[40:43], 0
	v_mfma_f32_16x16x32_bf16 v[40:43], v[24:27], v[40:43], 0
	v_mfma_f32_16x16x32_bf16 v[36:39], v[20:23], v[44:47], v[36:39]
	v_mfma_f32_16x16x32_bf16 v[40:43], v[28:31], v[44:47], v[40:43]
	v_mfma_f32_16x16x32_bf16 v[44:47], v[16:19], v[48:51], 0
	v_mfma_f32_16x16x32_bf16 v[48:51], v[24:27], v[48:51], 0
	v_mfma_f32_16x16x32_bf16 v[44:47], v[20:23], v[52:55], v[44:47]
	v_mfma_f32_16x16x32_bf16 v[48:51], v[28:31], v[52:55], v[48:51]
	v_mfma_f32_16x16x32_bf16 v[52:55], v[16:19], v[56:59], 0
	v_mfma_f32_16x16x32_bf16 v[56:59], v[24:27], v[56:59], 0
	v_mfma_f32_16x16x32_bf16 v[52:55], v[20:23], v[60:63], v[52:55]
	v_mfma_f32_16x16x32_bf16 v[56:59], v[28:31], v[60:63], v[56:59]
	s_barrier
	v_lshl_add_u64 v[204:205], s[44:45], 0, v[130:131]
	s_mov_b32 m0, s51
	v_lshl_add_u64 v[140:141], v[204:205], 0, s[22:23]
	v_lshl_add_u64 v[206:207], s[44:45], 0, v[128:129]
	s_add_u32 s64, s44, 0x10100
	ds_read_b128 v[60:63], v136 offset:16384
	ds_read_b128 v[100:103], v136 offset:17408
	ds_read_b128 v[104:107], v136 offset:18432
	ds_read_b128 v[108:111], v136 offset:19456
	ds_read_b128 v[112:115], v136 offset:20480
	ds_read_b128 v[116:119], v136 offset:21504
	ds_read_b128 v[120:123], v136 offset:22528
	ds_read_b128 v[124:127], v136 offset:23552
	global_load_lds_dwordx4 v[140:141], off
	v_lshl_add_u64 v[140:141], v[206:207], 0, s[22:23]
	s_mov_b32 m0, s52
	s_addc_u32 s65, s45, 0
	global_load_lds_dwordx4 v[140:141], off
	v_lshl_add_u64 v[140:141], s[64:65], 0, v[130:131]
	s_mov_b32 m0, s53
	v_lshl_add_u64 v[208:209], s[36:37], 0, v[130:131]
	global_load_lds_dwordx4 v[140:141], off
	v_lshl_add_u64 v[140:141], s[64:65], 0, v[128:129]
	s_mov_b32 m0, s54
	v_lshl_add_u64 v[210:211], s[36:37], 0, v[128:129]
	global_load_lds_dwordx4 v[140:141], off
	v_lshl_add_u64 v[140:141], v[208:209], 0, s[22:23]
	s_mov_b32 m0, s74
	s_nop 0
	global_load_lds_dwordx4 v[140:141], off
	v_lshl_add_u64 v[140:141], v[210:211], 0, s[22:23]
	s_mov_b32 m0, s47
	s_nop 0
	global_load_lds_dwordx4 v[140:141], off
	s_waitcnt vmcnt(8)
	s_waitcnt lgkmcnt(0)
	s_barrier
; #define PG8_STAGE(bufoff, gbase, voff) do { _Pragma("unroll") for (int _i = 0; _i < 2; ++_i) \
;         __builtin_amdgcn_global_load_lds((const unsigned*)((const char*)(gbase) + (voff)[_i]), (PG8_LAS unsigned*)(lds + (bufoff) + ldsw + _i * 8192), 16, 0, 0); } while (0)
; #define PG8_LDA(dst, b, h) do { _Pragma("unroll") for (int m = 0; m < 4; ++m) _Pragma("unroll") for (int k = 0; k < 2; ++k) dst[m][k] = *(const PG8_LAS bf16x8*)(lds + PG8_SA(b, h) + aoff + m * 2048 + k * 1024); } while (0)
; #define PG8_LDB(dst, b, h) do { _Pragma("unroll") for (int n = 0; n < 2; ++n) _Pragma("unroll") for (int k = 0; k < 2; ++k) dst[n][k] = *(const PG8_LAS bf16x8*)(lds + PG8_SB(b, h) + boff + n * 2048 + k * 1024); } while (0)
; #define PG8_MMA(ai, bj, At, Bt) do { __builtin_amdgcn_s_setprio(1); _Pragma("unroll") for (int m = 0; m < 4; ++m) _Pragma("unroll") for (int n = 0; n < 2; ++n) _Pragma("unroll") for (int k = 0; k < 2; ++k) \
;         acc[ai][bj][m][n] = mma16<F16>(Bt[n][k], At[m][k], acc[ai][bj][m][n]); __builtin_amdgcn_s_setprio(0); } while (0)
; #define PG8_WAIT_V(n) asm volatile("s_waitcnt vmcnt(" #n ")" ::: "memory")
; #define PG8_WAIT_L(n) asm volatile("s_waitcnt lgkmcnt(" #n ")" ::: "memory")
; #define PG8_BAR __builtin_amdgcn_s_barrier()
; #define PG8_SCHED __builtin_amdgcn_sched_barrier(0)
; template <class Epi, class Sched, bool ALIGN_EPI = false, bool SP2 = false, bool F16 = false>
; __device__ __forceinline__ void gemm_phase(PG8_LAS unsigned char* lds, const Gemm g, const Sched& S, const Epi& E, const int wid_in) {
;     ...
;             PG8_WAIT_V(8); PG8_WAIT_L(0); PG8_BAR; PG8_MMA(1, 0, At, B0); PG8_MMA(1, 1, At, B1); PG8_BAR; PG8_SCHED;
;             PG8_LDB(B0, 1, 0); PG8_LDB(B1, 1, 1); PG8_SCHED; PG8_LDA(At, 1, 0); PG8_STAGE(PG8_SA(0, 1), a2 + hstep, voffA);
;             PG8_WAIT_V(8); PG8_WAIT_L(0); PG8_BAR; PG8_MMA(0, 0, At, B0); PG8_MMA(0, 1, At, B1); PG8_BAR; PG8_SCHED;
	v_mfma_f32_16x16x32_bf16 v[140:143], v[0:3], v[60:63], 0
	v_mfma_f32_16x16x32_bf16 v[148:151], v[0:3], v[104:107], 0
	v_mfma_f32_16x16x32_bf16 v[156:159], v[0:3], v[112:115], 0
	v_mfma_f32_16x16x32_bf16 v[0:3], v[0:3], v[120:123], 0
	v_mfma_f32_16x16x32_bf16 v[140:143], v[4:7], v[100:103], v[140:143]
	v_mfma_f32_16x16x32_bf16 v[148:151], v[4:7], v[108:111], v[148:151]
	v_mfma_f32_16x16x32_bf16 v[156:159], v[4:7], v[116:119], v[156:159]
	v_mfma_f32_16x16x32_bf16 v[0:3], v[4:7], v[124:127], v[0:3]
	v_mfma_f32_16x16x32_bf16 v[4:7], v[8:11], v[120:123], 0
	v_mfma_f32_16x16x32_bf16 v[144:147], v[8:11], v[60:63], 0
	v_mfma_f32_16x16x32_bf16 v[152:155], v[8:11], v[104:107], 0
	v_mfma_f32_16x16x32_bf16 v[160:163], v[8:11], v[112:115], 0
	v_mfma_f32_16x16x32_bf16 v[4:7], v[12:15], v[124:127], v[4:7]
	v_mfma_f32_16x16x32_bf16 v[144:147], v[12:15], v[100:103], v[144:147]
	v_mfma_f32_16x16x32_bf16 v[152:155], v[12:15], v[108:111], v[152:155]
	v_mfma_f32_16x16x32_bf16 v[160:163], v[12:15], v[116:119], v[160:163]
	v_mfma_f32_16x16x32_bf16 v[8:11], v[16:19], v[60:63], 0
	v_mfma_f32_16x16x32_bf16 v[12:15], v[24:27], v[60:63], 0
	v_mfma_f32_16x16x32_bf16 v[8:11], v[20:23], v[100:103], v[8:11]
	v_mfma_f32_16x16x32_bf16 v[12:15], v[28:31], v[100:103], v[12:15]
	v_mfma_f32_16x16x32_bf16 v[60:63], v[16:19], v[104:107], 0
	v_mfma_f32_16x16x32_bf16 v[100:103], v[24:27], v[104:107], 0
	v_mfma_f32_16x16x32_bf16 v[104:107], v[16:19], v[112:115], 0
	v_mfma_f32_16x16x32_bf16 v[16:19], v[16:19], v[120:123], 0
	v_mfma_f32_16x16x32_bf16 v[60:63], v[20:23], v[108:111], v[60:63]
	v_mfma_f32_16x16x32_bf16 v[100:103], v[28:31], v[108:111], v[100:103]
	v_mfma_f32_16x16x32_bf16 v[104:107], v[20:23], v[116:119], v[104:107]
	v_mfma_f32_16x16x32_bf16 v[108:111], v[24:27], v[112:115], 0
	v_mfma_f32_16x16x32_bf16 v[16:19], v[20:23], v[124:127], v[16:19]
	v_mfma_f32_16x16x32_bf16 v[20:23], v[24:27], v[120:123], 0
	v_mfma_f32_16x16x32_bf16 v[108:111], v[28:31], v[116:119], v[108:111]
	v_mfma_f32_16x16x32_bf16 v[20:23], v[28:31], v[124:127], v[20:23]
	s_barrier
	ds_read_b128 v[24:27], v137
	ds_read_b128 v[28:31], v137 offset:1024
	ds_read_b128 v[112:115], v137 offset:2048
	ds_read_b128 v[116:119], v137 offset:3072
	ds_read_b128 v[120:123], v138
	ds_read_b128 v[124:127], v138 offset:1024
	ds_read_b128 v[164:167], v138 offset:2048
	ds_read_b128 v[168:171], v138 offset:3072
	s_add_u32 s64, s36, 0x10100
	s_addc_u32 s65, s37, 0
	s_mov_b32 m0, s48
	v_lshl_add_u64 v[212:213], s[64:65], 0, v[130:131]
	ds_read_b128 v[172:175], v136 offset:32768
	ds_read_b128 v[176:179], v136 offset:33792
	ds_read_b128 v[180:183], v136 offset:34816
	ds_read_b128 v[184:187], v136 offset:35840
	ds_read_b128 v[188:191], v136 offset:36864
	ds_read_b128 v[192:195], v136 offset:37888
	ds_read_b128 v[196:199], v136 offset:38912
	ds_read_b128 v[200:203], v136 offset:39936
	global_load_lds_dwordx4 v[212:213], off
	v_lshl_add_u64 v[212:213], s[64:65], 0, v[128:129]
	s_mov_b32 m0, s49
	s_nop 0
	global_load_lds_dwordx4 v[212:213], off
	s_waitcnt vmcnt(8)
	s_waitcnt lgkmcnt(0)
	s_barrier
	v_mfma_f32_16x16x32_bf16 v[64:67], v[24:27], v[172:175], v[64:67]
	v_mfma_f32_16x16x32_bf16 v[68:71], v[112:115], v[172:175], v[68:71]
	v_mfma_f32_16x16x32_bf16 v[72:75], v[24:27], v[180:183], v[72:75]
	v_mfma_f32_16x16x32_bf16 v[76:79], v[112:115], v[180:183], v[76:79]
	v_mfma_f32_16x16x32_bf16 v[80:83], v[24:27], v[188:191], v[80:83]
	v_mfma_f32_16x16x32_bf16 v[84:87], v[112:115], v[188:191], v[84:87]
	v_mfma_f32_16x16x32_bf16 v[88:91], v[24:27], v[196:199], v[88:91]
	v_mfma_f32_16x16x32_bf16 v[92:95], v[112:115], v[196:199], v[92:95]
	v_mfma_f32_16x16x32_bf16 v[64:67], v[28:31], v[176:179], v[64:67]
	v_mfma_f32_16x16x32_bf16 v[68:71], v[116:119], v[176:179], v[68:71]
	v_mfma_f32_16x16x32_bf16 v[72:75], v[28:31], v[184:187], v[72:75]
	v_mfma_f32_16x16x32_bf16 v[76:79], v[116:119], v[184:187], v[76:79]
	v_mfma_f32_16x16x32_bf16 v[80:83], v[28:31], v[192:195], v[80:83]
	v_mfma_f32_16x16x32_bf16 v[84:87], v[116:119], v[192:195], v[84:87]
	v_mfma_f32_16x16x32_bf16 v[88:91], v[28:31], v[200:203], v[88:91]
	v_mfma_f32_16x16x32_bf16 v[92:95], v[116:119], v[200:203], v[92:95]
	v_mfma_f32_16x16x32_bf16 v[96:99], v[120:123], v[172:175], v[96:99]
	v_mfma_f32_16x16x32_bf16 v[32:35], v[164:167], v[172:175], v[32:35]
	v_mfma_f32_16x16x32_bf16 v[36:39], v[120:123], v[180:183], v[36:39]
	v_mfma_f32_16x16x32_bf16 v[40:43], v[164:167], v[180:183], v[40:43]
	v_mfma_f32_16x16x32_bf16 v[44:47], v[120:123], v[188:191], v[44:47]
	v_mfma_f32_16x16x32_bf16 v[48:51], v[164:167], v[188:191], v[48:51]
	v_mfma_f32_16x16x32_bf16 v[52:55], v[120:123], v[196:199], v[52:55]
	v_mfma_f32_16x16x32_bf16 v[56:59], v[164:167], v[196:199], v[56:59]
	v_mfma_f32_16x16x32_bf16 v[96:99], v[124:127], v[176:179], v[96:99]
	v_mfma_f32_16x16x32_bf16 v[32:35], v[168:171], v[176:179], v[32:35]
	v_mfma_f32_16x16x32_bf16 v[36:39], v[124:127], v[184:187], v[36:39]
	v_mfma_f32_16x16x32_bf16 v[40:43], v[168:171], v[184:187], v[40:43]
	v_mfma_f32_16x16x32_bf16 v[44:47], v[124:127], v[192:195], v[44:47]
	v_mfma_f32_16x16x32_bf16 v[48:51], v[168:171], v[192:195], v[48:51]
	v_mfma_f32_16x16x32_bf16 v[52:55], v[124:127], v[200:203], v[52:55]
	v_mfma_f32_16x16x32_bf16 v[56:59], v[168:171], v[200:203], v[56:59]
	s_barrier
; #define PG8_STAGE(bufoff, gbase, voff) do { _Pragma("unroll") for (int _i = 0; _i < 2; ++_i) \
;         __builtin_amdgcn_global_load_lds((const unsigned*)((const char*)(gbase) + (voff)[_i]), (PG8_LAS unsigned*)(lds + (bufoff) + ldsw + _i * 8192), 16, 0, 0); } while (0)
; #define PG8_LDA(dst, b, h) do { _Pragma("unroll") for (int m = 0; m < 4; ++m) _Pragma("unroll") for (int k = 0; k < 2; ++k) dst[m][k] = *(const PG8_LAS bf16x8*)(lds + PG8_SA(b, h) + aoff + m * 2048 + k * 1024); } while (0)
; #define PG8_LDB(dst, b, h) do { _Pragma("unroll") for (int n = 0; n < 2; ++n) _Pragma("unroll") for (int k = 0; k < 2; ++k) dst[n][k] = *(const PG8_LAS bf16x8*)(lds + PG8_SB(b, h) + boff + n * 2048 + k * 1024); } while (0)
; #define PG8_MMA(ai, bj, At, Bt) do { __builtin_amdgcn_s_setprio(1); _Pragma("unroll") for (int m = 0; m < 4; ++m) _Pragma("unroll") for (int n = 0; n < 2; ++n) _Pragma("unroll") for (int k = 0; k < 2; ++k) \
;         acc[ai][bj][m][n] = mma16<F16>(Bt[n][k], At[m][k], acc[ai][bj][m][n]); __builtin_amdgcn_s_setprio(0); } while (0)
; #define PG8_WAIT_V(n) asm volatile("s_waitcnt vmcnt(" #n ")" ::: "memory")
; template <class Epi, class Sched, bool ALIGN_EPI = false, bool SP2 = false, bool F16 = false>
; __device__ __forceinline__ void gemm_phase(PG8_LAS unsigned char* lds, const Gemm g, const Sched& S, const Epi& E, const int wid_in) {
;     ...
;             PG8_LDB(B0, 0, 0); PG8_LDB(B1, 0, 1); PG8_SCHED; PG8_LDA(At, 0, 0); PG8_STAGE(PG8_SA(1, 1), a1 + hstep, voffA);
;             PG8_WAIT_V(8); PG8_WAIT_L(0); PG8_BAR; PG8_MMA(0, 0, At, B0); PG8_MMA(0, 1, At, B1); PG8_BAR; PG8_SCHED;
;             PG8_LDA(At, 0, 1); PG8_STAGE(PG8_SB(0, 0), b2, voffB); PG8_STAGE(PG8_SB(0, 1), b2 + hstep, voffB); PG8_STAGE(PG8_SA(0, 0), a2, voffA);
;             PG8_WAIT_V(8); PG8_WAIT_L(0); PG8_BAR; PG8_MMA(1, 0, At, B0); PG8_MMA(1, 1, At, B1); PG8_BAR; PG8_SCHED;
;             PG8_LDB(B0, 1, 0); PG8_LDB(B1, 1, 1); PG8_SCHED; PG8_LDA(At, 1, 0); PG8_STAGE(PG8_SA(0, 1), a2 + hstep, voffA);
;             PG8_WAIT_V(8); PG8_WAIT_L(0); PG8_BAR; PG8_MMA(0, 0, At, B0); PG8_MMA(0, 1, At, B1); PG8_BAR; PG8_SCHED;
;             PG8_LDA(At, 1, 1); PG8_STAGE(PG8_SB(1, 0), b3, voffB); PG8_STAGE(PG8_SB(1, 1), b3 + hstep, voffB); PG8_STAGE(PG8_SA(1, 0), a3, voffA);
;             PG8_WAIT_V(8); PG8_WAIT_L(0); PG8_BAR; PG8_MMA(1, 0, At, B0); PG8_MMA(1, 1, At, B1); PG8_BAR; PG8_SCHED;
	s_mov_b32 m0, s55
	v_lshl_add_u64 v[204:205], v[204:205], 0, s[24:25]
	s_add_u32 s44, s44, 0x10180
	ds_read_b128 v[172:175], v136 offset:49152
	ds_read_b128 v[176:179], v136 offset:50176
	ds_read_b128 v[180:183], v136 offset:51200
	ds_read_b128 v[184:187], v136 offset:52224
	ds_read_b128 v[188:191], v136 offset:53248
	ds_read_b128 v[192:195], v136 offset:54272
	ds_read_b128 v[196:199], v136 offset:55296
	ds_read_b128 v[200:203], v136 offset:56320
	global_load_lds_dwordx4 v[204:205], off
	v_lshl_add_u64 v[204:205], v[206:207], 0, s[24:25]
	s_mov_b32 m0, s58
	s_addc_u32 s45, s45, 0
	global_load_lds_dwordx4 v[204:205], off
	v_lshl_add_u64 v[204:205], s[44:45], 0, v[130:131]
	s_mov_b32 m0, s59
	s_nop 0
	global_load_lds_dwordx4 v[204:205], off
	v_lshl_add_u64 v[204:205], s[44:45], 0, v[128:129]
	s_mov_b32 m0, s60
	s_nop 0
	global_load_lds_dwordx4 v[204:205], off
	v_lshl_add_u64 v[204:205], v[208:209], 0, s[24:25]
	s_mov_b32 m0, s75
	s_nop 0
	global_load_lds_dwordx4 v[204:205], off
	v_lshl_add_u64 v[204:205], v[210:211], 0, s[24:25]
	s_mov_b32 m0, s14
	s_nop 0
	global_load_lds_dwordx4 v[204:205], off
	s_waitcnt vmcnt(8)
	s_waitcnt lgkmcnt(0)
	s_barrier
	v_mfma_f32_16x16x32_bf16 v[0:3], v[24:27], v[196:199], v[0:3]
	v_mfma_f32_16x16x32_bf16 v[4:7], v[112:115], v[196:199], v[4:7]
	v_mfma_f32_16x16x32_bf16 v[140:143], v[24:27], v[172:175], v[140:143]
	v_mfma_f32_16x16x32_bf16 v[144:147], v[112:115], v[172:175], v[144:147]
	v_mfma_f32_16x16x32_bf16 v[148:151], v[24:27], v[180:183], v[148:151]
	v_mfma_f32_16x16x32_bf16 v[152:155], v[112:115], v[180:183], v[152:155]
	v_mfma_f32_16x16x32_bf16 v[156:159], v[24:27], v[188:191], v[156:159]
	v_mfma_f32_16x16x32_bf16 v[160:163], v[112:115], v[188:191], v[160:163]
	v_mfma_f32_16x16x32_bf16 v[0:3], v[28:31], v[200:203], v[0:3]
	v_mfma_f32_16x16x32_bf16 v[4:7], v[116:119], v[200:203], v[4:7]
	v_mfma_f32_16x16x32_bf16 v[140:143], v[28:31], v[176:179], v[140:143]
	v_mfma_f32_16x16x32_bf16 v[144:147], v[116:119], v[176:179], v[144:147]
	v_mfma_f32_16x16x32_bf16 v[148:151], v[28:31], v[184:187], v[148:151]
	v_mfma_f32_16x16x32_bf16 v[152:155], v[116:119], v[184:187], v[152:155]
	v_mfma_f32_16x16x32_bf16 v[156:159], v[28:31], v[192:195], v[156:159]
	v_mfma_f32_16x16x32_bf16 v[160:163], v[116:119], v[192:195], v[160:163]
	v_mfma_f32_16x16x32_bf16 v[8:11], v[120:123], v[172:175], v[8:11]
	v_mfma_f32_16x16x32_bf16 v[12:15], v[164:167], v[172:175], v[12:15]
	v_mfma_f32_16x16x32_bf16 v[24:27], v[120:123], v[180:183], v[60:63]
	v_mfma_f32_16x16x32_bf16 v[28:31], v[164:167], v[180:183], v[100:103]
	v_mfma_f32_16x16x32_bf16 v[60:63], v[120:123], v[188:191], v[104:107]
	v_mfma_f32_16x16x32_bf16 v[100:103], v[164:167], v[188:191], v[108:111]
	v_mfma_f32_16x16x32_bf16 v[16:19], v[120:123], v[196:199], v[16:19]
	v_mfma_f32_16x16x32_bf16 v[20:23], v[164:167], v[196:199], v[20:23]
	v_mfma_f32_16x16x32_bf16 v[8:11], v[124:127], v[176:179], v[8:11]
	v_mfma_f32_16x16x32_bf16 v[12:15], v[168:171], v[176:179], v[12:15]
	v_mfma_f32_16x16x32_bf16 v[24:27], v[124:127], v[184:187], v[24:27]
	v_mfma_f32_16x16x32_bf16 v[28:31], v[168:171], v[184:187], v[28:31]
	v_mfma_f32_16x16x32_bf16 v[60:63], v[124:127], v[192:195], v[60:63]
	v_mfma_f32_16x16x32_bf16 v[100:103], v[168:171], v[192:195], v[100:103]
	v_mfma_f32_16x16x32_bf16 v[16:19], v[124:127], v[200:203], v[16:19]
	v_mfma_f32_16x16x32_bf16 v[20:23], v[168:171], v[200:203], v[20:23]
	s_barrier
	ds_read_b128 v[104:107], v134
	ds_read_b128 v[108:111], v134 offset:1024
	ds_read_b128 v[112:115], v134 offset:2048
	ds_read_b128 v[116:119], v134 offset:3072
	ds_read_b128 v[120:123], v135
	ds_read_b128 v[124:127], v135 offset:1024
	ds_read_b128 v[164:167], v135 offset:2048
	ds_read_b128 v[168:171], v135 offset:3072
	s_add_u32 s36, s36, 0x10180
	s_addc_u32 s37, s37, 0
	s_mov_b32 m0, s15
	v_lshl_add_u64 v[204:205], s[36:37], 0, v[130:131]
	ds_read_b128 v[172:175], v136
	ds_read_b128 v[176:179], v136 offset:1024
	ds_read_b128 v[180:183], v136 offset:2048
	ds_read_b128 v[184:187], v136 offset:3072
	ds_read_b128 v[188:191], v136 offset:4096
	ds_read_b128 v[192:195], v136 offset:5120
	ds_read_b128 v[196:199], v136 offset:6144
	ds_read_b128 v[200:203], v136 offset:7168
	global_load_lds_dwordx4 v[204:205], off
	v_lshl_add_u64 v[204:205], s[36:37], 0, v[128:129]
	s_mov_b32 m0, s50
	s_nop 0
	global_load_lds_dwordx4 v[204:205], off
	s_waitcnt vmcnt(8)
	s_waitcnt lgkmcnt(0)
	s_barrier
	v_mfma_f32_16x16x32_bf16 v[64:67], v[104:107], v[172:175], v[64:67]
	v_mfma_f32_16x16x32_bf16 v[68:71], v[112:115], v[172:175], v[68:71]
	v_mfma_f32_16x16x32_bf16 v[72:75], v[104:107], v[180:183], v[72:75]
	v_mfma_f32_16x16x32_bf16 v[76:79], v[112:115], v[180:183], v[76:79]
	v_mfma_f32_16x16x32_bf16 v[80:83], v[104:107], v[188:191], v[80:83]
	v_mfma_f32_16x16x32_bf16 v[84:87], v[112:115], v[188:191], v[84:87]
	v_mfma_f32_16x16x32_bf16 v[88:91], v[104:107], v[196:199], v[88:91]
	v_mfma_f32_16x16x32_bf16 v[92:95], v[112:115], v[196:199], v[92:95]
	v_mfma_f32_16x16x32_bf16 v[64:67], v[108:111], v[176:179], v[64:67]
	v_mfma_f32_16x16x32_bf16 v[68:71], v[116:119], v[176:179], v[68:71]
	v_mfma_f32_16x16x32_bf16 v[72:75], v[108:111], v[184:187], v[72:75]
	v_mfma_f32_16x16x32_bf16 v[76:79], v[116:119], v[184:187], v[76:79]
	v_mfma_f32_16x16x32_bf16 v[80:83], v[108:111], v[192:195], v[80:83]
	v_mfma_f32_16x16x32_bf16 v[84:87], v[116:119], v[192:195], v[84:87]
	v_mfma_f32_16x16x32_bf16 v[88:91], v[108:111], v[200:203], v[88:91]
	v_mfma_f32_16x16x32_bf16 v[92:95], v[116:119], v[200:203], v[92:95]
	v_mfma_f32_16x16x32_bf16 v[32:35], v[164:167], v[172:175], v[32:35]
	v_mfma_f32_16x16x32_bf16 v[96:99], v[120:123], v[172:175], v[96:99]
	v_mfma_f32_16x16x32_bf16 v[172:175], v[168:171], v[176:179], v[32:35]
	v_mfma_f32_16x16x32_bf16 v[32:35], v[120:123], v[180:183], v[36:39]
	v_mfma_f32_16x16x32_bf16 v[204:207], v[124:127], v[176:179], v[96:99]
	v_mfma_f32_16x16x32_bf16 v[176:179], v[124:127], v[184:187], v[32:35]
	v_mfma_f32_16x16x32_bf16 v[32:35], v[164:167], v[180:183], v[40:43]
	v_mfma_f32_16x16x32_bf16 v[40:43], v[168:171], v[184:187], v[32:35]
	v_mfma_f32_16x16x32_bf16 v[32:35], v[120:123], v[188:191], v[44:47]
	v_mfma_f32_16x16x32_bf16 v[44:47], v[124:127], v[192:195], v[32:35]
	v_mfma_f32_16x16x32_bf16 v[32:35], v[164:167], v[188:191], v[48:51]
	v_mfma_f32_16x16x32_bf16 v[48:51], v[168:171], v[192:195], v[32:35]
	v_mfma_f32_16x16x32_bf16 v[32:35], v[120:123], v[196:199], v[52:55]
	v_mfma_f32_16x16x32_bf16 v[52:55], v[124:127], v[200:203], v[32:35]
	v_mfma_f32_16x16x32_bf16 v[32:35], v[164:167], v[196:199], v[56:59]
	v_mfma_f32_16x16x32_bf16 v[56:59], v[168:171], v[200:203], v[32:35]
	s_barrier
; #define PG8_STAGE(bufoff, gbase, voff) do { _Pragma("unroll") for (int _i = 0; _i < 2; ++_i) \
;         __builtin_amdgcn_global_load_lds((const unsigned*)((const char*)(gbase) + (voff)[_i]), (PG8_LAS unsigned*)(lds + (bufoff) + ldsw + _i * 8192), 16, 0, 0); } while (0)
; #define PG8_LDA(dst, b, h) do { _Pragma("unroll") for (int m = 0; m < 4; ++m) _Pragma("unroll") for (int k = 0; k < 2; ++k) dst[m][k] = *(const PG8_LAS bf16x8*)(lds + PG8_SA(b, h) + aoff + m * 2048 + k * 1024); } while (0)
; #define PG8_LDB(dst, b, h) do { _Pragma("unroll") for (int n = 0; n < 2; ++n) _Pragma("unroll") for (int k = 0; k < 2; ++k) dst[n][k] = *(const PG8_LAS bf16x8*)(lds + PG8_SB(b, h) + boff + n * 2048 + k * 1024); } while (0)
; #define PG8_MMA(ai, bj, At, Bt) do { __builtin_amdgcn_s_setprio(1); _Pragma("unroll") for (int m = 0; m < 4; ++m) _Pragma("unroll") for (int n = 0; n < 2; ++n) _Pragma("unroll") for (int k = 0; k < 2; ++k) \
;         acc[ai][bj][m][n] = mma16<F16>(Bt[n][k], At[m][k], acc[ai][bj][m][n]); __builtin_amdgcn_s_setprio(0); } while (0)
; #define PG8_WAIT_V(n) asm volatile("s_waitcnt vmcnt(" #n ")" ::: "memory")
; #define PG8_WAIT_L(n) asm volatile("s_waitcnt lgkmcnt(" #n ")" ::: "memory")
; #define PG8_BAR __builtin_amdgcn_s_barrier()
; #define PG8_SCHED __builtin_amdgcn_sched_barrier(0)
; template <class Epi, class Sched, bool ALIGN_EPI = false, bool SP2 = false, bool F16 = false>
; __device__ __forceinline__ void gemm_phase(PG8_LAS unsigned char* lds, const Gemm g, const Sched& S, const Epi& E, const int wid_in) {
;     ...
;             PG8_LDA(At, 0, 1); PG8_STAGE(PG8_SB(0, 0), b2, voffB); PG8_STAGE(PG8_SB(0, 1), b2 + hstep, voffB); PG8_STAGE(PG8_SA(0, 0), a2, voffA);
;             PG8_WAIT_V(8); PG8_WAIT_L(0); PG8_BAR; PG8_MMA(1, 0, At, B0); PG8_MMA(1, 1, At, B1); PG8_BAR; PG8_SCHED;
;             PG8_LDB(B0, 1, 0); PG8_LDB(B1, 1, 1); PG8_SCHED; PG8_LDA(At, 1, 0); PG8_STAGE(PG8_SA(0, 1), a2 + hstep, voffA);
;             PG8_WAIT_V(8); PG8_WAIT_L(0); PG8_BAR; PG8_MMA(0, 0, At, B0); PG8_MMA(0, 1, At, B1); PG8_BAR; PG8_SCHED;
	s_mov_b32 m0, s51
	v_lshl_add_u64 v[240:241], s[30:31], 0, v[130:131]
	s_add_u32 s36, s30, 0x10000
	s_nop 1
	ds_read_b128 v[32:35], v136 offset:16384
	ds_read_b128 v[36:39], v136 offset:17408
	ds_read_b128 v[96:99], v136 offset:18432
	ds_read_b128 v[180:183], v136 offset:19456
	ds_read_b128 v[184:187], v136 offset:20480
	ds_read_b128 v[188:191], v136 offset:21504
	ds_read_b128 v[192:195], v136 offset:22528
	ds_read_b128 v[196:199], v136 offset:23552
	global_load_lds_dwordx4 v[240:241], off
	v_lshl_add_u64 v[242:243], s[30:31], 0, v[128:129]
	s_mov_b32 m0, s52
	s_addc_u32 s37, s31, 0
	global_load_lds_dwordx4 v[242:243], off
	v_lshl_add_u64 v[200:201], s[36:37], 0, v[130:131]
	s_mov_b32 m0, s53
	v_lshl_add_u64 v[244:245], s[34:35], 0, v[130:131]
	global_load_lds_dwordx4 v[200:201], off
	v_lshl_add_u64 v[200:201], s[36:37], 0, v[128:129]
	s_mov_b32 m0, s54
	v_lshl_add_u64 v[246:247], s[34:35], 0, v[128:129]
	global_load_lds_dwordx4 v[200:201], off
	s_mov_b32 m0, s74
	s_nop 0
	global_load_lds_dwordx4 v[244:245], off
	s_mov_b32 m0, s47
	s_nop 0
	global_load_lds_dwordx4 v[246:247], off
	s_waitcnt vmcnt(8)
	s_waitcnt lgkmcnt(0)
	s_barrier
	v_mfma_f32_16x16x32_bf16 v[0:3], v[104:107], v[192:195], v[0:3]
	v_mfma_f32_16x16x32_bf16 v[140:143], v[104:107], v[32:35], v[140:143]
	v_mfma_f32_16x16x32_bf16 v[144:147], v[112:115], v[32:35], v[144:147]
	v_mfma_f32_16x16x32_bf16 v[148:151], v[104:107], v[96:99], v[148:151]
	v_mfma_f32_16x16x32_bf16 v[152:155], v[112:115], v[96:99], v[152:155]
	v_mfma_f32_16x16x32_bf16 v[156:159], v[104:107], v[184:187], v[156:159]
	v_mfma_f32_16x16x32_bf16 v[160:163], v[112:115], v[184:187], v[160:163]
	v_mfma_f32_16x16x32_bf16 v[0:3], v[108:111], v[196:199], v[0:3]
	v_mfma_f32_16x16x32_bf16 v[4:7], v[112:115], v[192:195], v[4:7]
	v_mfma_f32_16x16x32_bf16 v[140:143], v[108:111], v[36:39], v[140:143]
	v_mfma_f32_16x16x32_bf16 v[144:147], v[116:119], v[36:39], v[144:147]
	v_mfma_f32_16x16x32_bf16 v[148:151], v[108:111], v[180:183], v[148:151]
	v_mfma_f32_16x16x32_bf16 v[152:155], v[116:119], v[180:183], v[152:155]
	v_mfma_f32_16x16x32_bf16 v[156:159], v[108:111], v[188:191], v[156:159]
	v_mfma_f32_16x16x32_bf16 v[160:163], v[116:119], v[188:191], v[160:163]
	v_mfma_f32_16x16x32_bf16 v[200:203], v[116:119], v[196:199], v[4:7]
	v_mfma_f32_16x16x32_bf16 v[4:7], v[120:123], v[32:35], v[8:11]
	v_mfma_f32_16x16x32_bf16 v[8:11], v[124:127], v[36:39], v[4:7]
	v_mfma_f32_16x16x32_bf16 v[4:7], v[164:167], v[32:35], v[12:15]
	v_mfma_f32_16x16x32_bf16 v[12:15], v[168:171], v[36:39], v[4:7]
	v_mfma_f32_16x16x32_bf16 v[4:7], v[120:123], v[96:99], v[24:27]
	v_mfma_f32_16x16x32_bf16 v[24:27], v[124:127], v[180:183], v[4:7]
	v_mfma_f32_16x16x32_bf16 v[4:7], v[164:167], v[96:99], v[28:31]
	v_mfma_f32_16x16x32_bf16 v[28:31], v[168:171], v[180:183], v[4:7]
	v_mfma_f32_16x16x32_bf16 v[4:7], v[120:123], v[184:187], v[60:63]
	v_mfma_f32_16x16x32_bf16 v[180:183], v[124:127], v[188:191], v[4:7]
	v_mfma_f32_16x16x32_bf16 v[4:7], v[164:167], v[184:187], v[100:103]
	v_mfma_f32_16x16x32_bf16 v[184:187], v[168:171], v[188:191], v[4:7]
	v_mfma_f32_16x16x32_bf16 v[4:7], v[120:123], v[192:195], v[16:19]
	v_mfma_f32_16x16x32_bf16 v[188:191], v[124:127], v[196:199], v[4:7]
	v_mfma_f32_16x16x32_bf16 v[4:7], v[164:167], v[192:195], v[20:23]
	v_mfma_f32_16x16x32_bf16 v[164:167], v[168:171], v[196:199], v[4:7]
	s_barrier
	s_nop 4
	ds_read_b128 v[4:7], v137
	ds_read_b128 v[60:63], v137 offset:1024
	ds_read_b128 v[168:171], v137 offset:2048
	ds_read_b128 v[192:195], v137 offset:3072
	ds_read_b128 v[196:199], v138
	ds_read_b128 v[208:211], v138 offset:1024
	ds_read_b128 v[212:215], v138 offset:2048
	ds_read_b128 v[216:219], v138 offset:3072
	s_add_u32 s34, s34, 0x10000
	s_addc_u32 s35, s35, 0
	s_mov_b32 m0, s48
	v_lshl_add_u64 v[32:33], s[34:35], 0, v[130:131]
	ds_read_b128 v[16:19], v136 offset:32768
	ds_read_b128 v[20:23], v136 offset:33792
	ds_read_b128 v[104:107], v136 offset:34816
	ds_read_b128 v[220:223], v136 offset:35840
	ds_read_b128 v[224:227], v136 offset:36864
	ds_read_b128 v[228:231], v136 offset:37888
	ds_read_b128 v[232:235], v136 offset:38912
	ds_read_b128 v[236:239], v136 offset:39936
	global_load_lds_dwordx4 v[32:33], off
	v_lshl_add_u64 v[32:33], s[34:35], 0, v[128:129]
	s_mov_b32 m0, s49
	s_nop 0
	global_load_lds_dwordx4 v[32:33], off
	s_waitcnt vmcnt(8)
	s_waitcnt lgkmcnt(0)
	s_barrier
; #define PG8_STAGE(bufoff, gbase, voff) do { _Pragma("unroll") for (int _i = 0; _i < 2; ++_i) \
;         __builtin_amdgcn_global_load_lds((const unsigned*)((const char*)(gbase) + (voff)[_i]), (PG8_LAS unsigned*)(lds + (bufoff) + ldsw + _i * 8192), 16, 0, 0); } while (0)
; #define PG8_LDA(dst, b, h) do { _Pragma("unroll") for (int m = 0; m < 4; ++m) _Pragma("unroll") for (int k = 0; k < 2; ++k) dst[m][k] = *(const PG8_LAS bf16x8*)(lds + PG8_SA(b, h) + aoff + m * 2048 + k * 1024); } while (0)
; #define PG8_MMA(ai, bj, At, Bt) do { __builtin_amdgcn_s_setprio(1); _Pragma("unroll") for (int m = 0; m < 4; ++m) _Pragma("unroll") for (int n = 0; n < 2; ++n) _Pragma("unroll") for (int k = 0; k < 2; ++k) \
;         acc[ai][bj][m][n] = mma16<F16>(Bt[n][k], At[m][k], acc[ai][bj][m][n]); __builtin_amdgcn_s_setprio(0); } while (0)
; #define PG8_WAIT_V(n) asm volatile("s_waitcnt vmcnt(" #n ")" ::: "memory")
; #define PG8_WAIT_L(n) asm volatile("s_waitcnt lgkmcnt(" #n ")" ::: "memory")
; #define PG8_BAR __builtin_amdgcn_s_barrier()
; #define PG8_SCHED __builtin_amdgcn_sched_barrier(0)
; template <class Epi, class Sched, bool ALIGN_EPI = false, bool SP2 = false, bool F16 = false>
; __device__ __forceinline__ void gemm_phase(PG8_LAS unsigned char* lds, const Gemm g, const Sched& S, const Epi& E, const int wid_in) {
;     ...
;             PG8_WAIT_V(8); PG8_WAIT_L(0); PG8_BAR; PG8_MMA(0, 0, At, B0); PG8_MMA(0, 1, At, B1); PG8_BAR; PG8_SCHED;
;             PG8_LDA(At, 1, 1); PG8_STAGE(PG8_SB(1, 0), b3, voffB); PG8_STAGE(PG8_SB(1, 1), b3 + hstep, voffB); PG8_STAGE(PG8_SA(1, 0), a3, voffA);
;             PG8_WAIT_V(8); PG8_WAIT_L(0); PG8_BAR; PG8_MMA(1, 0, At, B0); PG8_MMA(1, 1, At, B1); PG8_BAR; PG8_SCHED;
;     ...
;         if constexpr (ALIGN_EPI) { if (wr == 0) PG8_BAR; }
	v_mfma_f32_16x16x32_bf16 v[32:35], v[4:7], v[16:19], v[64:67]
	v_mfma_f32_16x16x32_bf16 v[116:119], v[60:63], v[20:23], v[32:35]
	v_mfma_f32_16x16x32_bf16 v[32:35], v[168:171], v[16:19], v[68:71]
	v_mfma_f32_16x16x32_bf16 v[112:115], v[192:195], v[20:23], v[32:35]
	v_mfma_f32_16x16x32_bf16 v[32:35], v[4:7], v[104:107], v[72:75]
	v_mfma_f32_16x16x32_bf16 v[100:103], v[60:63], v[220:223], v[32:35]
	v_mfma_f32_16x16x32_bf16 v[32:35], v[168:171], v[104:107], v[76:79]
	v_mfma_f32_16x16x32_bf16 v[96:99], v[192:195], v[220:223], v[32:35]
	v_mfma_f32_16x16x32_bf16 v[32:35], v[4:7], v[224:227], v[80:83]
	v_mfma_f32_16x16x32_bf16 v[68:71], v[60:63], v[228:231], v[32:35]
	v_mfma_f32_16x16x32_bf16 v[32:35], v[168:171], v[224:227], v[84:87]
	v_mfma_f32_16x16x32_bf16 v[64:67], v[192:195], v[228:231], v[32:35]
	v_mfma_f32_16x16x32_bf16 v[32:35], v[4:7], v[232:235], v[88:91]
	v_mfma_f32_16x16x32_bf16 v[36:39], v[60:63], v[236:239], v[32:35]
	v_mfma_f32_16x16x32_bf16 v[32:35], v[168:171], v[232:235], v[92:95]
	v_mfma_f32_16x16x32_bf16 v[32:35], v[192:195], v[236:239], v[32:35]
	v_mfma_f32_16x16x32_bf16 v[72:75], v[196:199], v[16:19], v[204:207]
	v_mfma_f32_16x16x32_bf16 v[16:19], v[212:215], v[16:19], v[172:175]
	v_mfma_f32_16x16x32_bf16 v[120:123], v[216:219], v[20:23], v[16:19]
	v_mfma_f32_16x16x32_bf16 v[16:19], v[196:199], v[104:107], v[176:179]
	v_mfma_f32_16x16x32_bf16 v[108:111], v[208:211], v[220:223], v[16:19]
	v_mfma_f32_16x16x32_bf16 v[16:19], v[212:215], v[104:107], v[40:43]
	v_mfma_f32_16x16x32_bf16 v[104:107], v[216:219], v[220:223], v[16:19]
	v_mfma_f32_16x16x32_bf16 v[16:19], v[196:199], v[224:227], v[44:47]
	v_mfma_f32_16x16x32_bf16 v[80:83], v[208:211], v[228:231], v[16:19]
	v_mfma_f32_16x16x32_bf16 v[16:19], v[212:215], v[224:227], v[48:51]
	v_mfma_f32_16x16x32_bf16 v[124:127], v[208:211], v[20:23], v[72:75]
	v_mfma_f32_16x16x32_bf16 v[72:75], v[216:219], v[228:231], v[16:19]
	v_mfma_f32_16x16x32_bf16 v[16:19], v[196:199], v[232:235], v[52:55]
	v_mfma_f32_16x16x32_bf16 v[48:51], v[208:211], v[236:239], v[16:19]
	v_mfma_f32_16x16x32_bf16 v[16:19], v[212:215], v[232:235], v[56:59]
	v_mfma_f32_16x16x32_bf16 v[40:43], v[216:219], v[236:239], v[16:19]
	s_barrier
	s_mov_b32 m0, s55
	s_nop 3
	v_lshl_add_u64 v[16:17], v[240:241], 0, s[20:21]
	s_add_u32 s30, s30, 0x10080
	ds_read_b128 v[56:59], v136 offset:49152
	ds_read_b128 v[88:91], v136 offset:50176
	ds_read_b128 v[172:175], v136 offset:51200
	ds_read_b128 v[176:179], v136 offset:52224
	ds_read_b128 v[204:207], v136 offset:53248
	ds_read_b128 v[220:223], v136 offset:54272
	ds_read_b128 v[224:227], v136 offset:55296
	ds_read_b128 v[228:231], v136 offset:56320
	global_load_lds_dwordx4 v[16:17], off
	v_lshl_add_u64 v[16:17], v[242:243], 0, s[20:21]
	s_mov_b32 m0, s58
	s_addc_u32 s31, s31, 0
	global_load_lds_dwordx4 v[16:17], off
	v_lshl_add_u64 v[16:17], s[30:31], 0, v[130:131]
	s_mov_b32 m0, s59
	s_nop 0
	global_load_lds_dwordx4 v[16:17], off
	v_lshl_add_u64 v[16:17], s[30:31], 0, v[128:129]
	s_mov_b32 m0, s60
	s_nop 0
	global_load_lds_dwordx4 v[16:17], off
	v_lshl_add_u64 v[16:17], v[244:245], 0, s[20:21]
	s_mov_b32 m0, s75
	s_nop 0
	global_load_lds_dwordx4 v[16:17], off
	v_lshl_add_u64 v[16:17], v[246:247], 0, s[20:21]
	s_mov_b32 m0, s14
	s_nop 0
	global_load_lds_dwordx4 v[16:17], off
	s_waitcnt vmcnt(8)
	s_waitcnt lgkmcnt(0)
	s_barrier
	v_mfma_f32_16x16x32_bf16 v[16:19], v[4:7], v[56:59], v[140:143]
	v_mfma_f32_16x16x32_bf16 v[84:87], v[60:63], v[88:91], v[16:19]
	v_mfma_f32_16x16x32_bf16 v[16:19], v[168:171], v[56:59], v[144:147]
	v_mfma_f32_16x16x32_bf16 v[76:79], v[192:195], v[88:91], v[16:19]
	v_mfma_f32_16x16x32_bf16 v[16:19], v[4:7], v[172:175], v[148:151]
	v_mfma_f32_16x16x32_bf16 v[52:55], v[60:63], v[176:179], v[16:19]
	v_mfma_f32_16x16x32_bf16 v[16:19], v[168:171], v[172:175], v[152:155]
	v_mfma_f32_16x16x32_bf16 v[44:47], v[192:195], v[176:179], v[16:19]
	v_mfma_f32_16x16x32_bf16 v[16:19], v[4:7], v[204:207], v[156:159]
	v_mfma_f32_16x16x32_bf16 v[0:3], v[4:7], v[224:227], v[0:3]
	v_mfma_f32_16x16x32_bf16 v[20:23], v[60:63], v[220:223], v[16:19]
	v_mfma_f32_16x16x32_bf16 v[16:19], v[168:171], v[204:207], v[160:163]
	v_mfma_f32_16x16x32_bf16 v[4:7], v[60:63], v[228:231], v[0:3]
	v_mfma_f32_16x16x32_bf16 v[0:3], v[168:171], v[224:227], v[200:203]
	v_mfma_f32_16x16x32_bf16 v[16:19], v[192:195], v[220:223], v[16:19]
	v_mfma_f32_16x16x32_bf16 v[0:3], v[192:195], v[228:231], v[0:3]
	v_mfma_f32_16x16x32_bf16 v[8:11], v[196:199], v[56:59], v[8:11]
	v_mfma_f32_16x16x32_bf16 v[92:95], v[208:211], v[88:91], v[8:11]
	v_mfma_f32_16x16x32_bf16 v[8:11], v[212:215], v[56:59], v[12:15]
	v_mfma_f32_16x16x32_bf16 v[88:91], v[216:219], v[88:91], v[8:11]
	v_mfma_f32_16x16x32_bf16 v[8:11], v[196:199], v[172:175], v[24:27]
	v_mfma_f32_16x16x32_bf16 v[60:63], v[208:211], v[176:179], v[8:11]
	v_mfma_f32_16x16x32_bf16 v[8:11], v[212:215], v[172:175], v[28:31]
	v_mfma_f32_16x16x32_bf16 v[56:59], v[216:219], v[176:179], v[8:11]
	v_mfma_f32_16x16x32_bf16 v[8:11], v[196:199], v[204:207], v[180:183]
	v_mfma_f32_16x16x32_bf16 v[28:31], v[208:211], v[220:223], v[8:11]
	v_mfma_f32_16x16x32_bf16 v[8:11], v[212:215], v[204:207], v[184:187]
	v_mfma_f32_16x16x32_bf16 v[24:27], v[216:219], v[220:223], v[8:11]
	v_mfma_f32_16x16x32_bf16 v[8:11], v[196:199], v[224:227], v[188:191]
	v_mfma_f32_16x16x32_bf16 v[12:15], v[208:211], v[228:231], v[8:11]
	v_mfma_f32_16x16x32_bf16 v[8:11], v[212:215], v[224:227], v[164:167]
	v_mfma_f32_16x16x32_bf16 v[8:11], v[216:219], v[228:231], v[8:11]
	s_barrier
	s_and_b64 vcc, exec, s[8:9]
	s_cbranch_vccnz .LBB0_622
	s_barrier

; #define PG8_STAGE(bufoff, gbase, voff) do { _Pragma("unroll") for (int _i = 0; _i < 2; ++_i) \
;         __builtin_amdgcn_global_load_lds((const unsigned*)((const char*)(gbase) + (voff)[_i]), (PG8_LAS unsigned*)(lds + (bufoff) + ldsw + _i * 8192), 16, 0, 0); } while (0)
; #define PG8_LDA(dst, b, h) do { _Pragma("unroll") for (int m = 0; m < 4; ++m) _Pragma("unroll") for (int k = 0; k < 2; ++k) dst[m][k] = *(const PG8_LAS bf16x8*)(lds + PG8_SA(b, h) + aoff + m * 2048 + k * 1024); } while (0)
; #define PG8_LDB(dst, b, h) do { _Pragma("unroll") for (int n = 0; n < 2; ++n) _Pragma("unroll") for (int k = 0; k < 2; ++k) dst[n][k] = *(const PG8_LAS bf16x8*)(lds + PG8_SB(b, h) + boff + n * 2048 + k * 1024); } while (0)
; #define PG8_MMA(ai, bj, At, Bt) do { __builtin_amdgcn_s_setprio(1); _Pragma("unroll") for (int m = 0; m < 4; ++m) _Pragma("unroll") for (int n = 0; n < 2; ++n) _Pragma("unroll") for (int k = 0; k < 2; ++k) \
;         acc[ai][bj][m][n] = mma16<F16>(Bt[n][k], At[m][k], acc[ai][bj][m][n]); __builtin_amdgcn_s_setprio(0); } while (0)
; #define PG8_WAIT_V(n) asm volatile("s_waitcnt vmcnt(" #n ")" ::: "memory")
; #define PG8_WAIT_L(n) asm volatile("s_waitcnt lgkmcnt(" #n ")" ::: "memory")
; #define PG8_BAR __builtin_amdgcn_s_barrier()
; #define PG8_SCHED __builtin_amdgcn_sched_barrier(0)
; template <class Epi, class Sched, bool ALIGN_EPI = false, bool SP2 = false, bool F16 = false>
; __device__ __forceinline__ void gemm_phase(PG8_LAS unsigned char* lds, const Gemm g, const Sched& S, const Epi& E, const int wid_in) {
;     ...
;             PG8_LDB(B0, 0, 0); PG8_LDB(B1, 0, 1); PG8_SCHED; PG8_LDA(At, 0, 0); PG8_STAGE(PG8_SA(1, 1), a1 + hstep, voffA);
;             PG8_WAIT_V(8); PG8_WAIT_L(0); PG8_BAR; PG8_MMA(0, 0, At, B0); PG8_MMA(0, 1, At, B1); PG8_BAR; PG8_SCHED;
;             PG8_LDA(At, 0, 1); PG8_STAGE(PG8_SB(0, 0), b2, voffB); PG8_STAGE(PG8_SB(0, 1), b2 + hstep, voffB); PG8_STAGE(PG8_SA(0, 0), a2, voffA);
;             PG8_WAIT_V(8); PG8_WAIT_L(0); PG8_BAR; PG8_MMA(1, 0, At, B0); PG8_MMA(1, 1, At, B1); PG8_BAR; PG8_SCHED;
.LBB0_716:
	ds_read_b128 v[128:131], v189
	ds_read_b128 v[132:135], v189 offset:1024
	ds_read_b128 v[136:139], v189 offset:2048
	ds_read_b128 v[140:143], v189 offset:3072
	ds_read_b128 v[144:147], v190
	ds_read_b128 v[148:151], v190 offset:1024
	ds_read_b128 v[168:171], v190 offset:2048
	ds_read_b128 v[172:175], v190 offset:3072
	s_add_u32 s30, s28, 0x100
	s_addc_u32 s31, s29, 0
	s_cmp_eq_u32 s60, 40
	s_cselect_b32 s37, s11, s31
	s_cselect_b32 s36, s10, s30
	s_cselect_b32 s35, s27, s59
	s_cselect_b32 s34, s26, s43
	v_lshl_add_u64 v[184:185], s[28:29], 0, v[160:161]
	s_add_i32 m0, s74, 0xc000
	ds_read_b128 v[176:179], v191
	ds_read_b128 v[180:183], v191 offset:1024
	ds_read_b128 v[192:195], v191 offset:2048
	ds_read_b128 v[196:199], v191 offset:3072
	ds_read_b128 v[200:203], v191 offset:4096
	ds_read_b128 v[204:207], v191 offset:5120
	ds_read_b128 v[208:211], v191 offset:6144
	ds_read_b128 v[212:215], v191 offset:7168
	global_load_lds_dwordx4 v[184:185], off
	v_lshl_add_u64 v[184:185], s[28:29], 0, v[162:163]
	s_add_i32 m0, s74, 0xe000
	s_nop 0
	global_load_lds_dwordx4 v[184:185], off
	s_waitcnt vmcnt(8)
	s_waitcnt lgkmcnt(0)
	s_barrier
	v_mfma_f32_16x16x32_bf16 v[124:127], v[128:131], v[176:179], v[124:127]
	v_mfma_f32_16x16x32_bf16 v[120:123], v[136:139], v[176:179], v[120:123]
	v_mfma_f32_16x16x32_bf16 v[108:111], v[128:131], v[192:195], v[108:111]
	v_mfma_f32_16x16x32_bf16 v[104:107], v[136:139], v[192:195], v[104:107]
	v_mfma_f32_16x16x32_bf16 v[92:95], v[128:131], v[200:203], v[92:95]
	v_mfma_f32_16x16x32_bf16 v[88:91], v[136:139], v[200:203], v[88:91]
	v_mfma_f32_16x16x32_bf16 v[76:79], v[128:131], v[208:211], v[76:79]
	v_mfma_f32_16x16x32_bf16 v[72:75], v[136:139], v[208:211], v[72:75]
	v_mfma_f32_16x16x32_bf16 v[124:127], v[132:135], v[180:183], v[124:127]
	v_mfma_f32_16x16x32_bf16 v[120:123], v[140:143], v[180:183], v[120:123]
	v_mfma_f32_16x16x32_bf16 v[108:111], v[132:135], v[196:199], v[108:111]
	v_mfma_f32_16x16x32_bf16 v[104:107], v[140:143], v[196:199], v[104:107]
	v_mfma_f32_16x16x32_bf16 v[92:95], v[132:135], v[204:207], v[92:95]
	v_mfma_f32_16x16x32_bf16 v[88:91], v[140:143], v[204:207], v[88:91]
	v_mfma_f32_16x16x32_bf16 v[76:79], v[132:135], v[212:215], v[76:79]
	v_mfma_f32_16x16x32_bf16 v[72:75], v[140:143], v[212:215], v[72:75]
	v_mfma_f32_16x16x32_bf16 v[116:119], v[144:147], v[176:179], v[116:119]
	v_mfma_f32_16x16x32_bf16 v[112:115], v[168:171], v[176:179], v[112:115]
	v_mfma_f32_16x16x32_bf16 v[100:103], v[144:147], v[192:195], v[100:103]
	v_mfma_f32_16x16x32_bf16 v[96:99], v[168:171], v[192:195], v[96:99]
	v_mfma_f32_16x16x32_bf16 v[84:87], v[144:147], v[200:203], v[84:87]
	v_mfma_f32_16x16x32_bf16 v[80:83], v[168:171], v[200:203], v[80:83]
	v_mfma_f32_16x16x32_bf16 v[68:71], v[144:147], v[208:211], v[68:71]
	v_mfma_f32_16x16x32_bf16 v[64:67], v[168:171], v[208:211], v[64:67]
	v_mfma_f32_16x16x32_bf16 v[116:119], v[148:151], v[180:183], v[116:119]
	v_mfma_f32_16x16x32_bf16 v[112:115], v[172:175], v[180:183], v[112:115]
	v_mfma_f32_16x16x32_bf16 v[100:103], v[148:151], v[196:199], v[100:103]
	v_mfma_f32_16x16x32_bf16 v[96:99], v[172:175], v[196:199], v[96:99]
	v_mfma_f32_16x16x32_bf16 v[84:87], v[148:151], v[204:207], v[84:87]
	v_mfma_f32_16x16x32_bf16 v[80:83], v[172:175], v[204:207], v[80:83]
	v_mfma_f32_16x16x32_bf16 v[68:71], v[148:151], v[212:215], v[68:71]
	v_mfma_f32_16x16x32_bf16 v[64:67], v[172:175], v[212:215], v[64:67]
	s_barrier
	s_add_i32 s28, s52, s68
	v_lshl_add_u64 v[184:185], s[34:35], 0, v[154:155]
	s_mov_b32 m0, s28
	ds_read_b128 v[176:179], v191 offset:16384
	ds_read_b128 v[180:183], v191 offset:17408
	ds_read_b128 v[192:195], v191 offset:18432
	ds_read_b128 v[196:199], v191 offset:19456
	ds_read_b128 v[200:203], v191 offset:20480
	ds_read_b128 v[204:207], v191 offset:21504
	ds_read_b128 v[208:211], v191 offset:22528
	ds_read_b128 v[212:215], v191 offset:23552
	global_load_lds_dwordx4 v[184:185], off
	s_add_i32 m0, s28, 0x2000
	s_add_u32 s28, s34, 0xb0000
	v_lshl_add_u64 v[216:217], s[34:35], 0, v[158:159]
	s_addc_u32 s29, s35, 0
	s_add_i32 s61, s53, s68
	global_load_lds_dwordx4 v[216:217], off
	v_lshl_add_u64 v[218:219], s[28:29], 0, v[154:155]
	s_mov_b32 m0, s61
	v_lshl_add_u64 v[220:221], s[36:37], 0, v[156:157]
	global_load_lds_dwordx4 v[218:219], off
	v_lshl_add_u64 v[218:219], s[28:29], 0, v[158:159]
	s_add_i32 m0, s61, 0x2000
	s_nop 0
	global_load_lds_dwordx4 v[218:219], off
	v_lshl_add_u64 v[218:219], s[36:37], 0, v[152:153]
	s_mov_b32 m0, s74
	s_nop 0
	global_load_lds_dwordx4 v[218:219], off
	s_mov_b32 m0, s45
	s_nop 0
	global_load_lds_dwordx4 v[220:221], off
	s_waitcnt vmcnt(8)
	s_waitcnt lgkmcnt(0)
	s_barrier
; #define PG8_STAGE(bufoff, gbase, voff) do { _Pragma("unroll") for (int _i = 0; _i < 2; ++_i) \
;         __builtin_amdgcn_global_load_lds((const unsigned*)((const char*)(gbase) + (voff)[_i]), (PG8_LAS unsigned*)(lds + (bufoff) + ldsw + _i * 8192), 16, 0, 0); } while (0)
; #define PG8_LDA(dst, b, h) do { _Pragma("unroll") for (int m = 0; m < 4; ++m) _Pragma("unroll") for (int k = 0; k < 2; ++k) dst[m][k] = *(const PG8_LAS bf16x8*)(lds + PG8_SA(b, h) + aoff + m * 2048 + k * 1024); } while (0)
; #define PG8_LDB(dst, b, h) do { _Pragma("unroll") for (int n = 0; n < 2; ++n) _Pragma("unroll") for (int k = 0; k < 2; ++k) dst[n][k] = *(const PG8_LAS bf16x8*)(lds + PG8_SB(b, h) + boff + n * 2048 + k * 1024); } while (0)
; #define PG8_MMA(ai, bj, At, Bt) do { __builtin_amdgcn_s_setprio(1); _Pragma("unroll") for (int m = 0; m < 4; ++m) _Pragma("unroll") for (int n = 0; n < 2; ++n) _Pragma("unroll") for (int k = 0; k < 2; ++k) \
;         acc[ai][bj][m][n] = mma16<F16>(Bt[n][k], At[m][k], acc[ai][bj][m][n]); __builtin_amdgcn_s_setprio(0); } while (0)
; #define PG8_WAIT_V(n) asm volatile("s_waitcnt vmcnt(" #n ")" ::: "memory")
; #define PG8_WAIT_L(n) asm volatile("s_waitcnt lgkmcnt(" #n ")" ::: "memory")
; #define PG8_BAR __builtin_amdgcn_s_barrier()
; #define PG8_SCHED __builtin_amdgcn_sched_barrier(0)
; template <class Epi, class Sched, bool ALIGN_EPI = false, bool SP2 = false, bool F16 = false>
; __device__ __forceinline__ void gemm_phase(PG8_LAS unsigned char* lds, const Gemm g, const Sched& S, const Epi& E, const int wid_in) {
;     ...
;             PG8_WAIT_V(8); PG8_WAIT_L(0); PG8_BAR; PG8_MMA(1, 0, At, B0); PG8_MMA(1, 1, At, B1); PG8_BAR; PG8_SCHED;
;             PG8_LDB(B0, 1, 0); PG8_LDB(B1, 1, 1); PG8_SCHED; PG8_LDA(At, 1, 0); PG8_STAGE(PG8_SA(0, 1), a2 + hstep, voffA);
;             PG8_WAIT_V(8); PG8_WAIT_L(0); PG8_BAR; PG8_MMA(0, 0, At, B0); PG8_MMA(0, 1, At, B1); PG8_BAR; PG8_SCHED;
	v_mfma_f32_16x16x32_bf16 v[60:63], v[128:131], v[176:179], v[60:63]
	v_mfma_f32_16x16x32_bf16 v[56:59], v[136:139], v[176:179], v[56:59]
	v_mfma_f32_16x16x32_bf16 v[44:47], v[128:131], v[192:195], v[44:47]
	v_mfma_f32_16x16x32_bf16 v[40:43], v[136:139], v[192:195], v[40:43]
	v_mfma_f32_16x16x32_bf16 v[28:31], v[128:131], v[200:203], v[28:31]
	v_mfma_f32_16x16x32_bf16 v[24:27], v[136:139], v[200:203], v[24:27]
	v_mfma_f32_16x16x32_bf16 v[12:15], v[128:131], v[208:211], v[12:15]
	v_mfma_f32_16x16x32_bf16 v[8:11], v[136:139], v[208:211], v[8:11]
	v_mfma_f32_16x16x32_bf16 v[60:63], v[132:135], v[180:183], v[60:63]
	v_mfma_f32_16x16x32_bf16 v[56:59], v[140:143], v[180:183], v[56:59]
	v_mfma_f32_16x16x32_bf16 v[44:47], v[132:135], v[196:199], v[44:47]
	v_mfma_f32_16x16x32_bf16 v[40:43], v[140:143], v[196:199], v[40:43]
	v_mfma_f32_16x16x32_bf16 v[28:31], v[132:135], v[204:207], v[28:31]
	v_mfma_f32_16x16x32_bf16 v[24:27], v[140:143], v[204:207], v[24:27]
	v_mfma_f32_16x16x32_bf16 v[12:15], v[132:135], v[212:215], v[12:15]
	v_mfma_f32_16x16x32_bf16 v[8:11], v[140:143], v[212:215], v[8:11]
	v_mfma_f32_16x16x32_bf16 v[52:55], v[144:147], v[176:179], v[52:55]
	v_mfma_f32_16x16x32_bf16 v[48:51], v[168:171], v[176:179], v[48:51]
	v_mfma_f32_16x16x32_bf16 v[36:39], v[144:147], v[192:195], v[36:39]
	v_mfma_f32_16x16x32_bf16 v[32:35], v[168:171], v[192:195], v[32:35]
	v_mfma_f32_16x16x32_bf16 v[20:23], v[144:147], v[200:203], v[20:23]
	v_mfma_f32_16x16x32_bf16 v[16:19], v[168:171], v[200:203], v[16:19]
	v_mfma_f32_16x16x32_bf16 v[4:7], v[144:147], v[208:211], v[4:7]
	v_mfma_f32_16x16x32_bf16 v[0:3], v[168:171], v[208:211], v[0:3]
	v_mfma_f32_16x16x32_bf16 v[52:55], v[148:151], v[180:183], v[52:55]
	v_mfma_f32_16x16x32_bf16 v[48:51], v[172:175], v[180:183], v[48:51]
	v_mfma_f32_16x16x32_bf16 v[36:39], v[148:151], v[196:199], v[36:39]
	v_mfma_f32_16x16x32_bf16 v[32:35], v[172:175], v[196:199], v[32:35]
	v_mfma_f32_16x16x32_bf16 v[20:23], v[148:151], v[204:207], v[20:23]
	v_mfma_f32_16x16x32_bf16 v[16:19], v[172:175], v[204:207], v[16:19]
	v_mfma_f32_16x16x32_bf16 v[4:7], v[148:151], v[212:215], v[4:7]
	v_mfma_f32_16x16x32_bf16 v[0:3], v[172:175], v[212:215], v[0:3]
	s_barrier
	s_add_i32 s61, 0, 0x18000
	s_add_i32 s62, 0, 0x1c000
	v_add_u32_e32 v140, s61, v188
	v_add_u32_e32 v172, s62, v188
	ds_read_b128 v[128:131], v140
	ds_read_b128 v[132:135], v140 offset:1024
	ds_read_b128 v[136:139], v140 offset:2048
	ds_read_b128 v[140:143], v140 offset:3072
	ds_read_b128 v[144:147], v172
	ds_read_b128 v[148:151], v172 offset:1024
	ds_read_b128 v[168:171], v172 offset:2048
	ds_read_b128 v[172:175], v172 offset:3072
	s_add_u32 s28, s36, 0xb0000
	s_addc_u32 s29, s37, 0
	s_mov_b32 m0, s46
	v_lshl_add_u64 v[222:223], s[28:29], 0, v[152:153]
	ds_read_b128 v[176:179], v191 offset:32768
	ds_read_b128 v[180:183], v191 offset:33792
	ds_read_b128 v[192:195], v191 offset:34816
	ds_read_b128 v[196:199], v191 offset:35840
	ds_read_b128 v[200:203], v191 offset:36864
	ds_read_b128 v[204:207], v191 offset:37888
	ds_read_b128 v[208:211], v191 offset:38912
	ds_read_b128 v[212:215], v191 offset:39936
	global_load_lds_dwordx4 v[222:223], off
	v_lshl_add_u64 v[222:223], s[28:29], 0, v[156:157]
	s_mov_b32 m0, s47
	s_nop 0
	global_load_lds_dwordx4 v[222:223], off
	s_waitcnt vmcnt(8)
	s_waitcnt lgkmcnt(0)
	s_barrier
	v_mfma_f32_16x16x32_bf16 v[124:127], v[128:131], v[176:179], v[124:127]
	v_mfma_f32_16x16x32_bf16 v[120:123], v[136:139], v[176:179], v[120:123]
	v_mfma_f32_16x16x32_bf16 v[108:111], v[128:131], v[192:195], v[108:111]
	v_mfma_f32_16x16x32_bf16 v[104:107], v[136:139], v[192:195], v[104:107]
	v_mfma_f32_16x16x32_bf16 v[92:95], v[128:131], v[200:203], v[92:95]
	v_mfma_f32_16x16x32_bf16 v[88:91], v[136:139], v[200:203], v[88:91]
	v_mfma_f32_16x16x32_bf16 v[76:79], v[128:131], v[208:211], v[76:79]
	v_mfma_f32_16x16x32_bf16 v[72:75], v[136:139], v[208:211], v[72:75]
	v_mfma_f32_16x16x32_bf16 v[124:127], v[132:135], v[180:183], v[124:127]
	v_mfma_f32_16x16x32_bf16 v[120:123], v[140:143], v[180:183], v[120:123]
	v_mfma_f32_16x16x32_bf16 v[108:111], v[132:135], v[196:199], v[108:111]
	v_mfma_f32_16x16x32_bf16 v[104:107], v[140:143], v[196:199], v[104:107]
	v_mfma_f32_16x16x32_bf16 v[92:95], v[132:135], v[204:207], v[92:95]
	v_mfma_f32_16x16x32_bf16 v[88:91], v[140:143], v[204:207], v[88:91]
	v_mfma_f32_16x16x32_bf16 v[76:79], v[132:135], v[212:215], v[76:79]
	v_mfma_f32_16x16x32_bf16 v[72:75], v[140:143], v[212:215], v[72:75]
	v_mfma_f32_16x16x32_bf16 v[116:119], v[144:147], v[176:179], v[116:119]
	v_mfma_f32_16x16x32_bf16 v[112:115], v[168:171], v[176:179], v[112:115]
	v_mfma_f32_16x16x32_bf16 v[100:103], v[144:147], v[192:195], v[100:103]
	v_mfma_f32_16x16x32_bf16 v[96:99], v[168:171], v[192:195], v[96:99]
	v_mfma_f32_16x16x32_bf16 v[84:87], v[144:147], v[200:203], v[84:87]
	v_mfma_f32_16x16x32_bf16 v[80:83], v[168:171], v[200:203], v[80:83]
	v_mfma_f32_16x16x32_bf16 v[68:71], v[144:147], v[208:211], v[68:71]
	v_mfma_f32_16x16x32_bf16 v[64:67], v[168:171], v[208:211], v[64:67]
	v_mfma_f32_16x16x32_bf16 v[116:119], v[148:151], v[180:183], v[116:119]
	v_mfma_f32_16x16x32_bf16 v[112:115], v[172:175], v[180:183], v[112:115]
	v_mfma_f32_16x16x32_bf16 v[100:103], v[148:151], v[196:199], v[100:103]
	v_mfma_f32_16x16x32_bf16 v[96:99], v[172:175], v[196:199], v[96:99]
	v_mfma_f32_16x16x32_bf16 v[84:87], v[148:151], v[204:207], v[84:87]
	v_mfma_f32_16x16x32_bf16 v[80:83], v[172:175], v[204:207], v[80:83]
	v_mfma_f32_16x16x32_bf16 v[68:71], v[148:151], v[212:215], v[68:71]
	v_mfma_f32_16x16x32_bf16 v[64:67], v[172:175], v[212:215], v[64:67]
	s_barrier
; #define PG8_STAGE(bufoff, gbase, voff) do { _Pragma("unroll") for (int _i = 0; _i < 2; ++_i) \
;         __builtin_amdgcn_global_load_lds((const unsigned*)((const char*)(gbase) + (voff)[_i]), (PG8_LAS unsigned*)(lds + (bufoff) + ldsw + _i * 8192), 16, 0, 0); } while (0)
; #define PG8_LDA(dst, b, h) do { _Pragma("unroll") for (int m = 0; m < 4; ++m) _Pragma("unroll") for (int k = 0; k < 2; ++k) dst[m][k] = *(const PG8_LAS bf16x8*)(lds + PG8_SA(b, h) + aoff + m * 2048 + k * 1024); } while (0)
; #define PG8_MMA(ai, bj, At, Bt) do { __builtin_amdgcn_s_setprio(1); _Pragma("unroll") for (int m = 0; m < 4; ++m) _Pragma("unroll") for (int n = 0; n < 2; ++n) _Pragma("unroll") for (int k = 0; k < 2; ++k) \
;         acc[ai][bj][m][n] = mma16<F16>(Bt[n][k], At[m][k], acc[ai][bj][m][n]); __builtin_amdgcn_s_setprio(0); } while (0)
; #define PG8_WAIT_V(n) asm volatile("s_waitcnt vmcnt(" #n ")" ::: "memory")
; #define PG8_WAIT_L(n) asm volatile("s_waitcnt lgkmcnt(" #n ")" ::: "memory")
; #define PG8_BAR __builtin_amdgcn_s_barrier()
; #define PG8_SCHED __builtin_amdgcn_sched_barrier(0)
; template <class Epi, class Sched, bool ALIGN_EPI = false, bool SP2 = false, bool F16 = false>
; __device__ __forceinline__ void gemm_phase(PG8_LAS unsigned char* lds, const Gemm g, const Sched& S, const Epi& E, const int wid_in) {
;     ...
;             PG8_LDA(At, 1, 1); PG8_STAGE(PG8_SB(1, 0), b3, voffB); PG8_STAGE(PG8_SB(1, 1), b3 + hstep, voffB); PG8_STAGE(PG8_SA(1, 0), a3, voffA);
;             PG8_WAIT_V(8); PG8_WAIT_L(0); PG8_BAR; PG8_MMA(1, 0, At, B0); PG8_MMA(1, 1, At, B1); PG8_BAR; PG8_SCHED;
;     ...
;         }
;         if constexpr (ALIGN_EPI) { if (wr == 0) PG8_BAR; }
	s_add_i32 s28, s61, s68
	v_lshl_add_u64 v[184:185], v[184:185], 0, s[24:25]
	s_mov_b32 m0, s28
	ds_read_b128 v[176:179], v191 offset:49152
	ds_read_b128 v[180:183], v191 offset:50176
	ds_read_b128 v[192:195], v191 offset:51200
	ds_read_b128 v[196:199], v191 offset:52224
	ds_read_b128 v[200:203], v191 offset:53248
	ds_read_b128 v[204:207], v191 offset:54272
	ds_read_b128 v[208:211], v191 offset:55296
	ds_read_b128 v[212:215], v191 offset:56320
	global_load_lds_dwordx4 v[184:185], off
	s_add_i32 m0, s28, 0x2000
	s_add_u32 s28, s34, 0xb0080
	v_lshl_add_u64 v[184:185], v[216:217], 0, s[24:25]
	s_addc_u32 s29, s35, 0
	s_add_i32 s34, s62, s68
	global_load_lds_dwordx4 v[184:185], off
	v_lshl_add_u64 v[184:185], s[28:29], 0, v[154:155]
	s_mov_b32 m0, s34
	s_nop 0
	global_load_lds_dwordx4 v[184:185], off
	v_lshl_add_u64 v[184:185], s[28:29], 0, v[158:159]
	s_add_i32 m0, s34, 0x2000
	s_nop 0
	global_load_lds_dwordx4 v[184:185], off
	v_lshl_add_u64 v[184:185], v[218:219], 0, s[24:25]
	s_mov_b32 m0, s75
	s_nop 0
	global_load_lds_dwordx4 v[184:185], off
	v_lshl_add_u64 v[184:185], v[220:221], 0, s[24:25]
	s_mov_b32 m0, s48
	s_nop 0
	global_load_lds_dwordx4 v[184:185], off
	s_waitcnt vmcnt(8)
	s_waitcnt lgkmcnt(0)
	s_barrier
	v_mfma_f32_16x16x32_bf16 v[60:63], v[128:131], v[176:179], v[60:63]
	v_mfma_f32_16x16x32_bf16 v[56:59], v[136:139], v[176:179], v[56:59]
	v_mfma_f32_16x16x32_bf16 v[44:47], v[128:131], v[192:195], v[44:47]
	v_mfma_f32_16x16x32_bf16 v[40:43], v[136:139], v[192:195], v[40:43]
	v_mfma_f32_16x16x32_bf16 v[28:31], v[128:131], v[200:203], v[28:31]
	v_mfma_f32_16x16x32_bf16 v[24:27], v[136:139], v[200:203], v[24:27]
	v_mfma_f32_16x16x32_bf16 v[12:15], v[128:131], v[208:211], v[12:15]
	v_mfma_f32_16x16x32_bf16 v[8:11], v[136:139], v[208:211], v[8:11]
	v_mfma_f32_16x16x32_bf16 v[60:63], v[132:135], v[180:183], v[60:63]
	v_mfma_f32_16x16x32_bf16 v[56:59], v[140:143], v[180:183], v[56:59]
	v_mfma_f32_16x16x32_bf16 v[44:47], v[132:135], v[196:199], v[44:47]
	v_mfma_f32_16x16x32_bf16 v[40:43], v[140:143], v[196:199], v[40:43]
	v_mfma_f32_16x16x32_bf16 v[28:31], v[132:135], v[204:207], v[28:31]
	v_mfma_f32_16x16x32_bf16 v[24:27], v[140:143], v[204:207], v[24:27]
	v_mfma_f32_16x16x32_bf16 v[12:15], v[132:135], v[212:215], v[12:15]
	v_mfma_f32_16x16x32_bf16 v[8:11], v[140:143], v[212:215], v[8:11]
	v_mfma_f32_16x16x32_bf16 v[52:55], v[144:147], v[176:179], v[52:55]
	v_mfma_f32_16x16x32_bf16 v[48:51], v[168:171], v[176:179], v[48:51]
	v_mfma_f32_16x16x32_bf16 v[36:39], v[144:147], v[192:195], v[36:39]
	v_mfma_f32_16x16x32_bf16 v[32:35], v[168:171], v[192:195], v[32:35]
	v_mfma_f32_16x16x32_bf16 v[20:23], v[144:147], v[200:203], v[20:23]
	v_mfma_f32_16x16x32_bf16 v[16:19], v[168:171], v[200:203], v[16:19]
	v_mfma_f32_16x16x32_bf16 v[4:7], v[144:147], v[208:211], v[4:7]
	v_mfma_f32_16x16x32_bf16 v[0:3], v[168:171], v[208:211], v[0:3]
	v_mfma_f32_16x16x32_bf16 v[52:55], v[148:151], v[180:183], v[52:55]
	v_mfma_f32_16x16x32_bf16 v[48:51], v[172:175], v[180:183], v[48:51]
	v_mfma_f32_16x16x32_bf16 v[36:39], v[148:151], v[196:199], v[36:39]
	v_mfma_f32_16x16x32_bf16 v[32:35], v[172:175], v[196:199], v[32:35]
	v_mfma_f32_16x16x32_bf16 v[20:23], v[148:151], v[204:207], v[20:23]
	v_mfma_f32_16x16x32_bf16 v[16:19], v[172:175], v[204:207], v[16:19]
	v_mfma_f32_16x16x32_bf16 v[4:7], v[148:151], v[212:215], v[4:7]
	v_mfma_f32_16x16x32_bf16 v[0:3], v[172:175], v[212:215], v[0:3]
	s_barrier
	s_add_i32 s60, s60, 2
	s_add_u32 s43, s43, 0x100
	s_addc_u32 s59, s59, 0
	s_cmp_gt_u32 s60, 41
	s_mov_b64 s[28:29], s[30:31]
	s_cbranch_scc0 .LBB0_716
	s_and_b64 vcc, exec, s[16:17]
	s_cbranch_vccz .LBB0_719
	s_barrier

; #define PG8_STAGE(bufoff, gbase, voff) do { _Pragma("unroll") for (int _i = 0; _i < 2; ++_i) \
;         __builtin_amdgcn_global_load_lds((const unsigned*)((const char*)(gbase) + (voff)[_i]), (PG8_LAS unsigned*)(lds + (bufoff) + ldsw + _i * 8192), 16, 0, 0); } while (0)
; #define PG8_LDA(dst, b, h) do { _Pragma("unroll") for (int m = 0; m < 4; ++m) _Pragma("unroll") for (int k = 0; k < 2; ++k) dst[m][k] = *(const PG8_LAS bf16x8*)(lds + PG8_SA(b, h) + aoff + m * 2048 + k * 1024); } while (0)
; #define PG8_LDB(dst, b, h) do { _Pragma("unroll") for (int n = 0; n < 2; ++n) _Pragma("unroll") for (int k = 0; k < 2; ++k) dst[n][k] = *(const PG8_LAS bf16x8*)(lds + PG8_SB(b, h) + boff + n * 2048 + k * 1024); } while (0)
; #define PG8_MMA(ai, bj, At, Bt) do { __builtin_amdgcn_s_setprio(1); _Pragma("unroll") for (int m = 0; m < 4; ++m) _Pragma("unroll") for (int n = 0; n < 2; ++n) _Pragma("unroll") for (int k = 0; k < 2; ++k) \
;         acc[ai][bj][m][n] = mma16<F16>(Bt[n][k], At[m][k], acc[ai][bj][m][n]); __builtin_amdgcn_s_setprio(0); } while (0)
; #define PG8_WAIT_V(n) asm volatile("s_waitcnt vmcnt(" #n ")" ::: "memory")
; #define PG8_WAIT_L(n) asm volatile("s_waitcnt lgkmcnt(" #n ")" ::: "memory")
; #define PG8_BAR __builtin_amdgcn_s_barrier()
; #define PG8_SCHED __builtin_amdgcn_sched_barrier(0)
; template <class Epi, class Sched, bool ALIGN_EPI = false, bool SP2 = false, bool F16 = false>
; __device__ __forceinline__ void gemm_phase(PG8_LAS unsigned char* lds, const Gemm g, const Sched& S, const Epi& E, const int wid_in) {
;     ...
;             PG8_LDB(B0, 0, 0); PG8_LDB(B1, 0, 1); PG8_SCHED; PG8_LDA(At, 0, 0); PG8_STAGE(PG8_SA(1, 1), a1 + hstep, voffA);
;             PG8_WAIT_V(8); PG8_WAIT_L(0); PG8_BAR; PG8_MMA(0, 0, At, B0); PG8_MMA(0, 1, At, B1); PG8_BAR; PG8_SCHED;
;             PG8_LDA(At, 0, 1); PG8_STAGE(PG8_SB(0, 0), b2, voffB); PG8_STAGE(PG8_SB(0, 1), b2 + hstep, voffB); PG8_STAGE(PG8_SA(0, 0), a2, voffA);
;             PG8_WAIT_V(8); PG8_WAIT_L(0); PG8_BAR; PG8_MMA(1, 0, At, B0); PG8_MMA(1, 1, At, B1); PG8_BAR; PG8_SCHED;
.LBB0_812:
	ds_read_b128 v[112:115], v235
	ds_read_b128 v[116:119], v235 offset:1024
	ds_read_b128 v[128:131], v235 offset:2048
	ds_read_b128 v[132:135], v235 offset:3072
	ds_read_b128 v[144:147], v236
	ds_read_b128 v[148:151], v236 offset:1024
	ds_read_b128 v[152:155], v236 offset:2048
	ds_read_b128 v[156:159], v236 offset:3072
	s_add_u32 s43, s46, 0xfffc0080
	s_addc_u32 s45, s47, -1
	s_cmp_eq_u32 s42, 12
	s_cselect_b32 s51, s14, s45
	s_cselect_b32 s50, s15, s43
	s_cselect_b32 s49, s29, s41
	s_cselect_b32 s48, s31, s40
	v_lshl_add_u64 v[192:193], s[46:47], 0, v[204:205]
	s_add_i32 m0, s74, 0xc000
	ds_read_b128 v[160:163], v237
	ds_read_b128 v[164:167], v237 offset:1024
	ds_read_b128 v[168:171], v237 offset:2048
	ds_read_b128 v[172:175], v237 offset:3072
	ds_read_b128 v[176:179], v237 offset:4096
	ds_read_b128 v[180:183], v237 offset:5120
	ds_read_b128 v[184:187], v237 offset:6144
	ds_read_b128 v[188:191], v237 offset:7168
	global_load_lds_dwordx4 v[192:193], off
	v_lshl_add_u64 v[192:193], s[46:47], 0, v[206:207]
	s_add_i32 m0, s74, 0xe000
	s_nop 0
	global_load_lds_dwordx4 v[192:193], off
	s_waitcnt vmcnt(8)
	s_waitcnt lgkmcnt(0)
	s_barrier
	v_mfma_f32_16x16x32_f16 v[140:143], v[112:115], v[160:163], v[140:143]
	v_mfma_f32_16x16x32_f16 v[136:139], v[128:131], v[160:163], v[136:139]
	v_mfma_f32_16x16x32_f16 v[108:111], v[112:115], v[168:171], v[108:111]
	v_mfma_f32_16x16x32_f16 v[104:107], v[128:131], v[168:171], v[104:107]
	v_mfma_f32_16x16x32_f16 v[92:95], v[112:115], v[176:179], v[92:95]
	v_mfma_f32_16x16x32_f16 v[88:91], v[128:131], v[176:179], v[88:91]
	v_mfma_f32_16x16x32_f16 v[76:79], v[112:115], v[184:187], v[76:79]
	v_mfma_f32_16x16x32_f16 v[72:75], v[128:131], v[184:187], v[72:75]
	v_mfma_f32_16x16x32_f16 v[140:143], v[116:119], v[164:167], v[140:143]
	v_mfma_f32_16x16x32_f16 v[136:139], v[132:135], v[164:167], v[136:139]
	v_mfma_f32_16x16x32_f16 v[108:111], v[116:119], v[172:175], v[108:111]
	v_mfma_f32_16x16x32_f16 v[104:107], v[132:135], v[172:175], v[104:107]
	v_mfma_f32_16x16x32_f16 v[92:95], v[116:119], v[180:183], v[92:95]
	v_mfma_f32_16x16x32_f16 v[88:91], v[132:135], v[180:183], v[88:91]
	v_mfma_f32_16x16x32_f16 v[76:79], v[116:119], v[188:191], v[76:79]
	v_mfma_f32_16x16x32_f16 v[72:75], v[132:135], v[188:191], v[72:75]
	v_mfma_f32_16x16x32_f16 v[124:127], v[144:147], v[160:163], v[124:127]
	v_mfma_f32_16x16x32_f16 v[120:123], v[152:155], v[160:163], v[120:123]
	v_mfma_f32_16x16x32_f16 v[100:103], v[144:147], v[168:171], v[100:103]
	v_mfma_f32_16x16x32_f16 v[96:99], v[152:155], v[168:171], v[96:99]
	v_mfma_f32_16x16x32_f16 v[84:87], v[144:147], v[176:179], v[84:87]
	v_mfma_f32_16x16x32_f16 v[80:83], v[152:155], v[176:179], v[80:83]
	v_mfma_f32_16x16x32_f16 v[68:71], v[144:147], v[184:187], v[68:71]
	v_mfma_f32_16x16x32_f16 v[64:67], v[152:155], v[184:187], v[64:67]
	v_mfma_f32_16x16x32_f16 v[124:127], v[148:151], v[164:167], v[124:127]
	v_mfma_f32_16x16x32_f16 v[120:123], v[156:159], v[164:167], v[120:123]
	v_mfma_f32_16x16x32_f16 v[100:103], v[148:151], v[172:175], v[100:103]
	v_mfma_f32_16x16x32_f16 v[96:99], v[156:159], v[172:175], v[96:99]
	v_mfma_f32_16x16x32_f16 v[84:87], v[148:151], v[180:183], v[84:87]
	v_mfma_f32_16x16x32_f16 v[80:83], v[156:159], v[180:183], v[80:83]
	v_mfma_f32_16x16x32_f16 v[68:71], v[148:151], v[188:191], v[68:71]
	v_mfma_f32_16x16x32_f16 v[64:67], v[156:159], v[188:191], v[64:67]
	s_barrier
	s_add_i32 s43, s64, s68
	v_lshl_add_u64 v[192:193], s[48:49], 0, v[198:199]
	s_mov_b32 m0, s43
	ds_read_b128 v[160:163], v237 offset:16384
	ds_read_b128 v[164:167], v237 offset:17408
	ds_read_b128 v[168:171], v237 offset:18432
	ds_read_b128 v[172:175], v237 offset:19456
	ds_read_b128 v[176:179], v237 offset:20480
	ds_read_b128 v[180:183], v237 offset:21504
	ds_read_b128 v[184:187], v237 offset:22528
	ds_read_b128 v[188:191], v237 offset:23552
	global_load_lds_dwordx4 v[192:193], off
	s_add_i32 m0, s43, 0x2000
	s_add_u32 s86, s48, 0x40000
	v_lshl_add_u64 v[194:195], s[48:49], 0, v[202:203]
	s_addc_u32 s87, s49, 0
	s_add_i32 s43, s65, s68
	global_load_lds_dwordx4 v[194:195], off
	v_lshl_add_u64 v[212:213], s[86:87], 0, v[198:199]
	s_mov_b32 m0, s43
	v_lshl_add_u64 v[214:215], s[50:51], 0, v[200:201]
	global_load_lds_dwordx4 v[212:213], off
	v_lshl_add_u64 v[212:213], s[86:87], 0, v[202:203]
	s_add_i32 m0, s43, 0x2000
	s_nop 0
	global_load_lds_dwordx4 v[212:213], off
	v_lshl_add_u64 v[212:213], s[50:51], 0, v[196:197]
	s_mov_b32 m0, s74
	s_nop 0
	global_load_lds_dwordx4 v[212:213], off
	s_mov_b32 m0, s55
	s_nop 0
	global_load_lds_dwordx4 v[214:215], off
	s_waitcnt vmcnt(8)
	s_waitcnt lgkmcnt(0)
	s_barrier
; #define PG8_STAGE(bufoff, gbase, voff) do { _Pragma("unroll") for (int _i = 0; _i < 2; ++_i) \
;         __builtin_amdgcn_global_load_lds((const unsigned*)((const char*)(gbase) + (voff)[_i]), (PG8_LAS unsigned*)(lds + (bufoff) + ldsw + _i * 8192), 16, 0, 0); } while (0)
; #define PG8_LDA(dst, b, h) do { _Pragma("unroll") for (int m = 0; m < 4; ++m) _Pragma("unroll") for (int k = 0; k < 2; ++k) dst[m][k] = *(const PG8_LAS bf16x8*)(lds + PG8_SA(b, h) + aoff + m * 2048 + k * 1024); } while (0)
; #define PG8_LDB(dst, b, h) do { _Pragma("unroll") for (int n = 0; n < 2; ++n) _Pragma("unroll") for (int k = 0; k < 2; ++k) dst[n][k] = *(const PG8_LAS bf16x8*)(lds + PG8_SB(b, h) + boff + n * 2048 + k * 1024); } while (0)
; #define PG8_MMA(ai, bj, At, Bt) do { __builtin_amdgcn_s_setprio(1); _Pragma("unroll") for (int m = 0; m < 4; ++m) _Pragma("unroll") for (int n = 0; n < 2; ++n) _Pragma("unroll") for (int k = 0; k < 2; ++k) \
;         acc[ai][bj][m][n] = mma16<F16>(Bt[n][k], At[m][k], acc[ai][bj][m][n]); __builtin_amdgcn_s_setprio(0); } while (0)
; #define PG8_WAIT_V(n) asm volatile("s_waitcnt vmcnt(" #n ")" ::: "memory")
; #define PG8_WAIT_L(n) asm volatile("s_waitcnt lgkmcnt(" #n ")" ::: "memory")
; #define PG8_BAR __builtin_amdgcn_s_barrier()
; #define PG8_SCHED __builtin_amdgcn_sched_barrier(0)
; template <class Epi, class Sched, bool ALIGN_EPI = false, bool SP2 = false, bool F16 = false>
; __device__ __forceinline__ void gemm_phase(PG8_LAS unsigned char* lds, const Gemm g, const Sched& S, const Epi& E, const int wid_in) {
;     ...
;             PG8_WAIT_V(8); PG8_WAIT_L(0); PG8_BAR; PG8_MMA(1, 0, At, B0); PG8_MMA(1, 1, At, B1); PG8_BAR; PG8_SCHED;
;             PG8_LDB(B0, 1, 0); PG8_LDB(B1, 1, 1); PG8_SCHED; PG8_LDA(At, 1, 0); PG8_STAGE(PG8_SA(0, 1), a2 + hstep, voffA);
;             PG8_WAIT_V(8); PG8_WAIT_L(0); PG8_BAR; PG8_MMA(0, 0, At, B0); PG8_MMA(0, 1, At, B1); PG8_BAR; PG8_SCHED;
	v_mfma_f32_16x16x32_f16 v[60:63], v[112:115], v[160:163], v[60:63]
	v_mfma_f32_16x16x32_f16 v[56:59], v[128:131], v[160:163], v[56:59]
	v_mfma_f32_16x16x32_f16 v[44:47], v[112:115], v[168:171], v[44:47]
	v_mfma_f32_16x16x32_f16 v[40:43], v[128:131], v[168:171], v[40:43]
	v_mfma_f32_16x16x32_f16 v[28:31], v[112:115], v[176:179], v[28:31]
	v_mfma_f32_16x16x32_f16 v[24:27], v[128:131], v[176:179], v[24:27]
	v_mfma_f32_16x16x32_f16 v[12:15], v[112:115], v[184:187], v[12:15]
	v_mfma_f32_16x16x32_f16 v[8:11], v[128:131], v[184:187], v[8:11]
	v_mfma_f32_16x16x32_f16 v[60:63], v[116:119], v[164:167], v[60:63]
	v_mfma_f32_16x16x32_f16 v[56:59], v[132:135], v[164:167], v[56:59]
	v_mfma_f32_16x16x32_f16 v[44:47], v[116:119], v[172:175], v[44:47]
	v_mfma_f32_16x16x32_f16 v[40:43], v[132:135], v[172:175], v[40:43]
	v_mfma_f32_16x16x32_f16 v[28:31], v[116:119], v[180:183], v[28:31]
	v_mfma_f32_16x16x32_f16 v[24:27], v[132:135], v[180:183], v[24:27]
	v_mfma_f32_16x16x32_f16 v[12:15], v[116:119], v[188:191], v[12:15]
	v_mfma_f32_16x16x32_f16 v[8:11], v[132:135], v[188:191], v[8:11]
	v_mfma_f32_16x16x32_f16 v[52:55], v[144:147], v[160:163], v[52:55]
	v_mfma_f32_16x16x32_f16 v[48:51], v[152:155], v[160:163], v[48:51]
	v_mfma_f32_16x16x32_f16 v[36:39], v[144:147], v[168:171], v[36:39]
	v_mfma_f32_16x16x32_f16 v[32:35], v[152:155], v[168:171], v[32:35]
	v_mfma_f32_16x16x32_f16 v[20:23], v[144:147], v[176:179], v[20:23]
	v_mfma_f32_16x16x32_f16 v[16:19], v[152:155], v[176:179], v[16:19]
	v_mfma_f32_16x16x32_f16 v[4:7], v[144:147], v[184:187], v[4:7]
	v_mfma_f32_16x16x32_f16 v[0:3], v[152:155], v[184:187], v[0:3]
	v_mfma_f32_16x16x32_f16 v[52:55], v[148:151], v[164:167], v[52:55]
	v_mfma_f32_16x16x32_f16 v[48:51], v[156:159], v[164:167], v[48:51]
	v_mfma_f32_16x16x32_f16 v[36:39], v[148:151], v[172:175], v[36:39]
	v_mfma_f32_16x16x32_f16 v[32:35], v[156:159], v[172:175], v[32:35]
	v_mfma_f32_16x16x32_f16 v[20:23], v[148:151], v[180:183], v[20:23]
	v_mfma_f32_16x16x32_f16 v[16:19], v[156:159], v[180:183], v[16:19]
	v_mfma_f32_16x16x32_f16 v[4:7], v[148:151], v[188:191], v[4:7]
	v_mfma_f32_16x16x32_f16 v[0:3], v[156:159], v[188:191], v[0:3]
	s_barrier
	s_add_i32 s43, 0, 0x18000
	s_add_i32 s45, 0, 0x1c000
	v_add_u32_e32 v132, s43, v234
	v_add_u32_e32 v156, s45, v234
	ds_read_b128 v[112:115], v132
	ds_read_b128 v[116:119], v132 offset:1024
	ds_read_b128 v[128:131], v132 offset:2048
	ds_read_b128 v[132:135], v132 offset:3072
	ds_read_b128 v[144:147], v156
	ds_read_b128 v[148:151], v156 offset:1024
	ds_read_b128 v[152:155], v156 offset:2048
	ds_read_b128 v[156:159], v156 offset:3072
	s_add_u32 s50, s50, 0x40000
	s_addc_u32 s51, s51, 0
	s_mov_b32 m0, s58
	v_lshl_add_u64 v[216:217], s[50:51], 0, v[196:197]
	ds_read_b128 v[160:163], v237 offset:32768
	ds_read_b128 v[164:167], v237 offset:33792
	ds_read_b128 v[168:171], v237 offset:34816
	ds_read_b128 v[172:175], v237 offset:35840
	ds_read_b128 v[176:179], v237 offset:36864
	ds_read_b128 v[180:183], v237 offset:37888
	ds_read_b128 v[184:187], v237 offset:38912
	ds_read_b128 v[188:191], v237 offset:39936
	global_load_lds_dwordx4 v[216:217], off
	v_lshl_add_u64 v[216:217], s[50:51], 0, v[200:201]
	s_mov_b32 m0, s59
	s_nop 0
	global_load_lds_dwordx4 v[216:217], off
	s_waitcnt vmcnt(8)
	s_waitcnt lgkmcnt(0)
	s_barrier
	v_mfma_f32_16x16x32_f16 v[140:143], v[112:115], v[160:163], v[140:143]
	v_mfma_f32_16x16x32_f16 v[136:139], v[128:131], v[160:163], v[136:139]
	v_mfma_f32_16x16x32_f16 v[108:111], v[112:115], v[168:171], v[108:111]
	v_mfma_f32_16x16x32_f16 v[104:107], v[128:131], v[168:171], v[104:107]
	v_mfma_f32_16x16x32_f16 v[92:95], v[112:115], v[176:179], v[92:95]
	v_mfma_f32_16x16x32_f16 v[88:91], v[128:131], v[176:179], v[88:91]
	v_mfma_f32_16x16x32_f16 v[76:79], v[112:115], v[184:187], v[76:79]
	v_mfma_f32_16x16x32_f16 v[72:75], v[128:131], v[184:187], v[72:75]
	v_mfma_f32_16x16x32_f16 v[140:143], v[116:119], v[164:167], v[140:143]
	v_mfma_f32_16x16x32_f16 v[136:139], v[132:135], v[164:167], v[136:139]
	v_mfma_f32_16x16x32_f16 v[108:111], v[116:119], v[172:175], v[108:111]
	v_mfma_f32_16x16x32_f16 v[104:107], v[132:135], v[172:175], v[104:107]
	v_mfma_f32_16x16x32_f16 v[92:95], v[116:119], v[180:183], v[92:95]
	v_mfma_f32_16x16x32_f16 v[88:91], v[132:135], v[180:183], v[88:91]
	v_mfma_f32_16x16x32_f16 v[76:79], v[116:119], v[188:191], v[76:79]
	v_mfma_f32_16x16x32_f16 v[72:75], v[132:135], v[188:191], v[72:75]
	v_mfma_f32_16x16x32_f16 v[124:127], v[144:147], v[160:163], v[124:127]
	v_mfma_f32_16x16x32_f16 v[120:123], v[152:155], v[160:163], v[120:123]
	v_mfma_f32_16x16x32_f16 v[100:103], v[144:147], v[168:171], v[100:103]
	v_mfma_f32_16x16x32_f16 v[96:99], v[152:155], v[168:171], v[96:99]
	v_mfma_f32_16x16x32_f16 v[84:87], v[144:147], v[176:179], v[84:87]
	v_mfma_f32_16x16x32_f16 v[80:83], v[152:155], v[176:179], v[80:83]
	v_mfma_f32_16x16x32_f16 v[68:71], v[144:147], v[184:187], v[68:71]
	v_mfma_f32_16x16x32_f16 v[64:67], v[152:155], v[184:187], v[64:67]
	v_mfma_f32_16x16x32_f16 v[124:127], v[148:151], v[164:167], v[124:127]
	v_mfma_f32_16x16x32_f16 v[120:123], v[156:159], v[164:167], v[120:123]
	v_mfma_f32_16x16x32_f16 v[100:103], v[148:151], v[172:175], v[100:103]
	v_mfma_f32_16x16x32_f16 v[96:99], v[156:159], v[172:175], v[96:99]
	v_mfma_f32_16x16x32_f16 v[84:87], v[148:151], v[180:183], v[84:87]
	v_mfma_f32_16x16x32_f16 v[80:83], v[156:159], v[180:183], v[80:83]
	v_mfma_f32_16x16x32_f16 v[68:71], v[148:151], v[188:191], v[68:71]
	v_mfma_f32_16x16x32_f16 v[64:67], v[156:159], v[188:191], v[64:67]
	s_barrier
; #define PG8_STAGE(bufoff, gbase, voff) do { _Pragma("unroll") for (int _i = 0; _i < 2; ++_i) \
;         __builtin_amdgcn_global_load_lds((const unsigned*)((const char*)(gbase) + (voff)[_i]), (PG8_LAS unsigned*)(lds + (bufoff) + ldsw + _i * 8192), 16, 0, 0); } while (0)
; #define PG8_LDA(dst, b, h) do { _Pragma("unroll") for (int m = 0; m < 4; ++m) _Pragma("unroll") for (int k = 0; k < 2; ++k) dst[m][k] = *(const PG8_LAS bf16x8*)(lds + PG8_SA(b, h) + aoff + m * 2048 + k * 1024); } while (0)
; #define PG8_MMA(ai, bj, At, Bt) do { __builtin_amdgcn_s_setprio(1); _Pragma("unroll") for (int m = 0; m < 4; ++m) _Pragma("unroll") for (int n = 0; n < 2; ++n) _Pragma("unroll") for (int k = 0; k < 2; ++k) \
;         acc[ai][bj][m][n] = mma16<F16>(Bt[n][k], At[m][k], acc[ai][bj][m][n]); __builtin_amdgcn_s_setprio(0); } while (0)
; #define PG8_WAIT_V(n) asm volatile("s_waitcnt vmcnt(" #n ")" ::: "memory")
; #define PG8_WAIT_L(n) asm volatile("s_waitcnt lgkmcnt(" #n ")" ::: "memory")
; #define PG8_BAR __builtin_amdgcn_s_barrier()
; #define PG8_SCHED __builtin_amdgcn_sched_barrier(0)
; template <class Epi, class Sched, bool ALIGN_EPI = false, bool SP2 = false, bool F16 = false>
; __device__ __forceinline__ void gemm_phase(PG8_LAS unsigned char* lds, const Gemm g, const Sched& S, const Epi& E, const int wid_in) {
;     ...
;             PG8_LDA(At, 1, 1); PG8_STAGE(PG8_SB(1, 0), b3, voffB); PG8_STAGE(PG8_SB(1, 1), b3 + hstep, voffB); PG8_STAGE(PG8_SA(1, 0), a3, voffA);
;             PG8_WAIT_V(8); PG8_WAIT_L(0); PG8_BAR; PG8_MMA(1, 0, At, B0); PG8_MMA(1, 1, At, B1); PG8_BAR; PG8_SCHED;
;     ...
;         }
;         if constexpr (ALIGN_EPI) { if (wr == 0) PG8_BAR; }
	s_add_i32 s43, s43, s68
	v_lshl_add_u64 v[192:193], v[192:193], 0, s[26:27]
	s_mov_b32 m0, s43
	ds_read_b128 v[160:163], v237 offset:49152
	ds_read_b128 v[164:167], v237 offset:50176
	ds_read_b128 v[168:171], v237 offset:51200
	ds_read_b128 v[172:175], v237 offset:52224
	ds_read_b128 v[176:179], v237 offset:53248
	ds_read_b128 v[180:183], v237 offset:54272
	ds_read_b128 v[184:187], v237 offset:55296
	ds_read_b128 v[188:191], v237 offset:56320
	global_load_lds_dwordx4 v[192:193], off
	s_add_i32 m0, s43, 0x2000
	s_add_u32 s48, s48, 0x40080
	v_lshl_add_u64 v[192:193], v[194:195], 0, s[26:27]
	s_addc_u32 s49, s49, 0
	s_add_i32 s43, s45, s68
	global_load_lds_dwordx4 v[192:193], off
	v_lshl_add_u64 v[192:193], s[48:49], 0, v[198:199]
	s_mov_b32 m0, s43
	s_nop 0
	global_load_lds_dwordx4 v[192:193], off
	v_lshl_add_u64 v[192:193], s[48:49], 0, v[202:203]
	s_add_i32 m0, s43, 0x2000
	s_nop 0
	global_load_lds_dwordx4 v[192:193], off
	v_lshl_add_u64 v[192:193], v[212:213], 0, s[26:27]
	s_mov_b32 m0, s75
	s_nop 0
	global_load_lds_dwordx4 v[192:193], off
	v_lshl_add_u64 v[192:193], v[214:215], 0, s[26:27]
	s_mov_b32 m0, s60
	s_nop 0
	global_load_lds_dwordx4 v[192:193], off
	s_waitcnt vmcnt(8)
	s_waitcnt lgkmcnt(0)
	s_barrier
	v_mfma_f32_16x16x32_f16 v[60:63], v[112:115], v[160:163], v[60:63]
	v_mfma_f32_16x16x32_f16 v[56:59], v[128:131], v[160:163], v[56:59]
	v_mfma_f32_16x16x32_f16 v[44:47], v[112:115], v[168:171], v[44:47]
	v_mfma_f32_16x16x32_f16 v[40:43], v[128:131], v[168:171], v[40:43]
	v_mfma_f32_16x16x32_f16 v[28:31], v[112:115], v[176:179], v[28:31]
	v_mfma_f32_16x16x32_f16 v[24:27], v[128:131], v[176:179], v[24:27]
	v_mfma_f32_16x16x32_f16 v[12:15], v[112:115], v[184:187], v[12:15]
	v_mfma_f32_16x16x32_f16 v[8:11], v[128:131], v[184:187], v[8:11]
	v_mfma_f32_16x16x32_f16 v[60:63], v[116:119], v[164:167], v[60:63]
	v_mfma_f32_16x16x32_f16 v[56:59], v[132:135], v[164:167], v[56:59]
	v_mfma_f32_16x16x32_f16 v[44:47], v[116:119], v[172:175], v[44:47]
	v_mfma_f32_16x16x32_f16 v[40:43], v[132:135], v[172:175], v[40:43]
	v_mfma_f32_16x16x32_f16 v[28:31], v[116:119], v[180:183], v[28:31]
	v_mfma_f32_16x16x32_f16 v[24:27], v[132:135], v[180:183], v[24:27]
	v_mfma_f32_16x16x32_f16 v[12:15], v[116:119], v[188:191], v[12:15]
	v_mfma_f32_16x16x32_f16 v[8:11], v[132:135], v[188:191], v[8:11]
	v_mfma_f32_16x16x32_f16 v[52:55], v[144:147], v[160:163], v[52:55]
	v_mfma_f32_16x16x32_f16 v[48:51], v[152:155], v[160:163], v[48:51]
	v_mfma_f32_16x16x32_f16 v[36:39], v[144:147], v[168:171], v[36:39]
	v_mfma_f32_16x16x32_f16 v[32:35], v[152:155], v[168:171], v[32:35]
	v_mfma_f32_16x16x32_f16 v[20:23], v[144:147], v[176:179], v[20:23]
	v_mfma_f32_16x16x32_f16 v[16:19], v[152:155], v[176:179], v[16:19]
	v_mfma_f32_16x16x32_f16 v[4:7], v[144:147], v[184:187], v[4:7]
	v_mfma_f32_16x16x32_f16 v[0:3], v[152:155], v[184:187], v[0:3]
	v_mfma_f32_16x16x32_f16 v[52:55], v[148:151], v[164:167], v[52:55]
	v_mfma_f32_16x16x32_f16 v[48:51], v[156:159], v[164:167], v[48:51]
	v_mfma_f32_16x16x32_f16 v[36:39], v[148:151], v[172:175], v[36:39]
	v_mfma_f32_16x16x32_f16 v[32:35], v[156:159], v[172:175], v[32:35]
	v_mfma_f32_16x16x32_f16 v[20:23], v[148:151], v[180:183], v[20:23]
	v_mfma_f32_16x16x32_f16 v[16:19], v[156:159], v[180:183], v[16:19]
	v_mfma_f32_16x16x32_f16 v[4:7], v[148:151], v[188:191], v[4:7]
	v_mfma_f32_16x16x32_f16 v[0:3], v[156:159], v[188:191], v[0:3]
	s_barrier
	s_add_i32 s42, s42, 2
	s_add_u32 s46, s46, 0x100
	s_addc_u32 s47, s47, 0
	s_add_u32 s40, s40, 0x100
	s_addc_u32 s41, s41, 0
	s_cmp_gt_u32 s42, 13
	s_cbranch_scc0 .LBB0_812
	s_and_b64 vcc, exec, s[16:17]
	s_cbranch_vccz .LBB0_815
	s_barrier

; #define PG8_STAGE(bufoff, gbase, voff) do { _Pragma("unroll") for (int _i = 0; _i < 2; ++_i) \
;         __builtin_amdgcn_global_load_lds((const unsigned*)((const char*)(gbase) + (voff)[_i]), (PG8_LAS unsigned*)(lds + (bufoff) + ldsw + _i * 8192), 16, 0, 0); } while (0)
; #define PG8_LDA(dst, b, h) do { _Pragma("unroll") for (int m = 0; m < 4; ++m) _Pragma("unroll") for (int k = 0; k < 2; ++k) dst[m][k] = *(const PG8_LAS bf16x8*)(lds + PG8_SA(b, h) + aoff + m * 2048 + k * 1024); } while (0)
; #define PG8_LDB(dst, b, h) do { _Pragma("unroll") for (int n = 0; n < 2; ++n) _Pragma("unroll") for (int k = 0; k < 2; ++k) dst[n][k] = *(const PG8_LAS bf16x8*)(lds + PG8_SB(b, h) + boff + n * 2048 + k * 1024); } while (0)
; #define PG8_MMA(ai, bj, At, Bt) do { __builtin_amdgcn_s_setprio(1); _Pragma("unroll") for (int m = 0; m < 4; ++m) _Pragma("unroll") for (int n = 0; n < 2; ++n) _Pragma("unroll") for (int k = 0; k < 2; ++k) \
;         acc[ai][bj][m][n] = mma16<F16>(Bt[n][k], At[m][k], acc[ai][bj][m][n]); __builtin_amdgcn_s_setprio(0); } while (0)
; #define PG8_WAIT_V(n) asm volatile("s_waitcnt vmcnt(" #n ")" ::: "memory")
; #define PG8_BAR __builtin_amdgcn_s_barrier()
; template <class Epi, class Sched, bool ALIGN_EPI = false, bool SP2 = false, bool F16 = false>
; __device__ __forceinline__ void gemm_phase(PG8_LAS unsigned char* lds, const Gemm g, const Sched& S, const Epi& E, const int wid_in) {
;     ...
;         for (int t = 0; t < nt; t += 2) {
;             const bool last = (t == nt - 2);
;             const char* a1 = cA + (size_t)(t + 1) * kstep;
;             const char* a2 = last ? nA : cA + (size_t)(t + 2) * kstep; const char* b2 = last ? nB : cB + (size_t)(t + 2) * kstep;
;             const char* a3 = a2 + kstep; const char* b3 = b2 + kstep;
;             if (last && has_next) S.a_ready(nxt);
;             if constexpr (SP2) {
;             PG8_LDB(B0, 0, 0); PG8_LDB(B1, 0, 1); PG8_SCHED; PG8_LDA(At, 0, 0); PG8_STAGE(PG8_SA(1, 1), a1 + hstep, voffA);
;             PG8_WAIT_V(8); PG8_WAIT_L(0); PG8_BAR; PG8_MMA(0, 0, At, B0); PG8_MMA(0, 1, At, B1); PG8_BAR; PG8_SCHED;
;             PG8_LDA(At, 0, 1); PG8_STAGE(PG8_SB(0, 0), b2, voffB); PG8_STAGE(PG8_SB(0, 1), b2 + hstep, voffB); PG8_STAGE(PG8_SA(0, 0), a2, voffA);
;             PG8_WAIT_V(8); PG8_WAIT_L(0); PG8_BAR; PG8_MMA(1, 0, At, B0); PG8_MMA(1, 1, At, B1); PG8_BAR; PG8_SCHED;
.LBB0_902:
	ds_read_b128 v[128:131], v183
	ds_read_b128 v[132:135], v183 offset:1024
	ds_read_b128 v[136:139], v183 offset:2048
	ds_read_b128 v[140:143], v183 offset:3072
	ds_read_b128 v[144:147], v184
	ds_read_b128 v[148:151], v184 offset:1024
	ds_read_b128 v[152:155], v184 offset:2048
	ds_read_b128 v[174:177], v184 offset:3072
	s_add_u32 s48, s46, 0xfffc0080
	s_addc_u32 s49, s47, -1
	s_cmp_eq_u32 s52, 12
	s_cselect_b32 s51, s11, s49
	s_cselect_b32 s50, s13, s48
	s_cselect_b32 s49, s31, s43
	s_cselect_b32 s48, s35, s42
	v_lshl_add_u64 v[178:179], s[46:47], 0, v[166:167]
	s_add_i32 m0, s74, 0xc000
	ds_read_b128 v[188:191], v185
	ds_read_b128 v[192:195], v185 offset:1024
	ds_read_b128 v[196:199], v185 offset:2048
	ds_read_b128 v[200:203], v185 offset:3072
	ds_read_b128 v[204:207], v185 offset:4096
	ds_read_b128 v[208:211], v185 offset:5120
	ds_read_b128 v[212:215], v185 offset:6144
	ds_read_b128 v[216:219], v185 offset:7168
	global_load_lds_dwordx4 v[178:179], off
	v_lshl_add_u64 v[178:179], s[46:47], 0, v[168:169]
	s_add_i32 m0, s74, 0xe000
	s_nop 0
	global_load_lds_dwordx4 v[178:179], off
	s_waitcnt vmcnt(8)
	s_waitcnt lgkmcnt(0)
	s_barrier
	v_mfma_f32_16x16x32_f16 v[124:127], v[128:131], v[188:191], v[124:127]
	v_mfma_f32_16x16x32_f16 v[120:123], v[136:139], v[188:191], v[120:123]
	v_mfma_f32_16x16x32_f16 v[108:111], v[128:131], v[196:199], v[108:111]
	v_mfma_f32_16x16x32_f16 v[104:107], v[136:139], v[196:199], v[104:107]
	v_mfma_f32_16x16x32_f16 v[92:95], v[128:131], v[204:207], v[92:95]
	v_mfma_f32_16x16x32_f16 v[88:91], v[136:139], v[204:207], v[88:91]
	v_mfma_f32_16x16x32_f16 v[76:79], v[128:131], v[212:215], v[76:79]
	v_mfma_f32_16x16x32_f16 v[72:75], v[136:139], v[212:215], v[72:75]
	v_mfma_f32_16x16x32_f16 v[124:127], v[132:135], v[192:195], v[124:127]
	v_mfma_f32_16x16x32_f16 v[120:123], v[140:143], v[192:195], v[120:123]
	v_mfma_f32_16x16x32_f16 v[108:111], v[132:135], v[200:203], v[108:111]
	v_mfma_f32_16x16x32_f16 v[104:107], v[140:143], v[200:203], v[104:107]
	v_mfma_f32_16x16x32_f16 v[92:95], v[132:135], v[208:211], v[92:95]
	v_mfma_f32_16x16x32_f16 v[88:91], v[140:143], v[208:211], v[88:91]
	v_mfma_f32_16x16x32_f16 v[76:79], v[132:135], v[216:219], v[76:79]
	v_mfma_f32_16x16x32_f16 v[72:75], v[140:143], v[216:219], v[72:75]
	v_mfma_f32_16x16x32_f16 v[116:119], v[144:147], v[188:191], v[116:119]
	v_mfma_f32_16x16x32_f16 v[112:115], v[152:155], v[188:191], v[112:115]
	v_mfma_f32_16x16x32_f16 v[100:103], v[144:147], v[196:199], v[100:103]
	v_mfma_f32_16x16x32_f16 v[96:99], v[152:155], v[196:199], v[96:99]
	v_mfma_f32_16x16x32_f16 v[84:87], v[144:147], v[204:207], v[84:87]
	v_mfma_f32_16x16x32_f16 v[80:83], v[152:155], v[204:207], v[80:83]
	v_mfma_f32_16x16x32_f16 v[68:71], v[144:147], v[212:215], v[68:71]
	v_mfma_f32_16x16x32_f16 v[64:67], v[152:155], v[212:215], v[64:67]
	v_mfma_f32_16x16x32_f16 v[116:119], v[148:151], v[192:195], v[116:119]
	v_mfma_f32_16x16x32_f16 v[112:115], v[174:177], v[192:195], v[112:115]
	v_mfma_f32_16x16x32_f16 v[100:103], v[148:151], v[200:203], v[100:103]
	v_mfma_f32_16x16x32_f16 v[96:99], v[174:177], v[200:203], v[96:99]
	v_mfma_f32_16x16x32_f16 v[84:87], v[148:151], v[208:211], v[84:87]
	v_mfma_f32_16x16x32_f16 v[80:83], v[174:177], v[208:211], v[80:83]
	v_mfma_f32_16x16x32_f16 v[68:71], v[148:151], v[216:219], v[68:71]
	v_mfma_f32_16x16x32_f16 v[64:67], v[174:177], v[216:219], v[64:67]
	s_barrier
	s_add_i32 s53, s40, s68
	v_lshl_add_u64 v[178:179], s[48:49], 0, v[158:159]
	s_mov_b32 m0, s53
	ds_read_b128 v[188:191], v185 offset:16384
	ds_read_b128 v[192:195], v185 offset:17408
	ds_read_b128 v[196:199], v185 offset:18432
	ds_read_b128 v[200:203], v185 offset:19456
	ds_read_b128 v[204:207], v185 offset:20480
	ds_read_b128 v[208:211], v185 offset:21504
	ds_read_b128 v[212:215], v185 offset:22528
	ds_read_b128 v[216:219], v185 offset:23552
	global_load_lds_dwordx4 v[178:179], off
	s_add_i32 m0, s53, 0x2000
	s_add_u32 s54, s48, 0x40000
	v_lshl_add_u64 v[220:221], s[48:49], 0, v[162:163]
	s_addc_u32 s55, s49, 0
	s_add_i32 s53, s41, s68
	global_load_lds_dwordx4 v[220:221], off
	v_lshl_add_u64 v[222:223], s[54:55], 0, v[158:159]
	s_mov_b32 m0, s53
	v_lshl_add_u64 v[224:225], s[50:51], 0, v[160:161]
	global_load_lds_dwordx4 v[222:223], off
	v_lshl_add_u64 v[222:223], s[54:55], 0, v[162:163]
	s_add_i32 m0, s53, 0x2000
	s_nop 0
	global_load_lds_dwordx4 v[222:223], off
	v_lshl_add_u64 v[222:223], s[50:51], 0, v[156:157]
	s_mov_b32 m0, s74
	s_nop 0
	global_load_lds_dwordx4 v[222:223], off
	s_mov_b32 m0, s65
	s_nop 0
	global_load_lds_dwordx4 v[224:225], off
	s_waitcnt vmcnt(8)
	s_waitcnt lgkmcnt(0)
	s_barrier
; #define PG8_STAGE(bufoff, gbase, voff) do { _Pragma("unroll") for (int _i = 0; _i < 2; ++_i) \
;         __builtin_amdgcn_global_load_lds((const unsigned*)((const char*)(gbase) + (voff)[_i]), (PG8_LAS unsigned*)(lds + (bufoff) + ldsw + _i * 8192), 16, 0, 0); } while (0)
; #define PG8_LDA(dst, b, h) do { _Pragma("unroll") for (int m = 0; m < 4; ++m) _Pragma("unroll") for (int k = 0; k < 2; ++k) dst[m][k] = *(const PG8_LAS bf16x8*)(lds + PG8_SA(b, h) + aoff + m * 2048 + k * 1024); } while (0)
; #define PG8_LDB(dst, b, h) do { _Pragma("unroll") for (int n = 0; n < 2; ++n) _Pragma("unroll") for (int k = 0; k < 2; ++k) dst[n][k] = *(const PG8_LAS bf16x8*)(lds + PG8_SB(b, h) + boff + n * 2048 + k * 1024); } while (0)
; #define PG8_MMA(ai, bj, At, Bt) do { __builtin_amdgcn_s_setprio(1); _Pragma("unroll") for (int m = 0; m < 4; ++m) _Pragma("unroll") for (int n = 0; n < 2; ++n) _Pragma("unroll") for (int k = 0; k < 2; ++k) \
;         acc[ai][bj][m][n] = mma16<F16>(Bt[n][k], At[m][k], acc[ai][bj][m][n]); __builtin_amdgcn_s_setprio(0); } while (0)
; #define PG8_WAIT_V(n) asm volatile("s_waitcnt vmcnt(" #n ")" ::: "memory")
; #define PG8_WAIT_L(n) asm volatile("s_waitcnt lgkmcnt(" #n ")" ::: "memory")
; #define PG8_BAR __builtin_amdgcn_s_barrier()
; #define PG8_SCHED __builtin_amdgcn_sched_barrier(0)
; template <class Epi, class Sched, bool ALIGN_EPI = false, bool SP2 = false, bool F16 = false>
; __device__ __forceinline__ void gemm_phase(PG8_LAS unsigned char* lds, const Gemm g, const Sched& S, const Epi& E, const int wid_in) {
;     ...
;             PG8_WAIT_V(8); PG8_WAIT_L(0); PG8_BAR; PG8_MMA(1, 0, At, B0); PG8_MMA(1, 1, At, B1); PG8_BAR; PG8_SCHED;
;             PG8_LDB(B0, 1, 0); PG8_LDB(B1, 1, 1); PG8_SCHED; PG8_LDA(At, 1, 0); PG8_STAGE(PG8_SA(0, 1), a2 + hstep, voffA);
;             PG8_WAIT_V(8); PG8_WAIT_L(0); PG8_BAR; PG8_MMA(0, 0, At, B0); PG8_MMA(0, 1, At, B1); PG8_BAR; PG8_SCHED;
	v_mfma_f32_16x16x32_f16 v[60:63], v[128:131], v[188:191], v[60:63]
	v_mfma_f32_16x16x32_f16 v[56:59], v[136:139], v[188:191], v[56:59]
	v_mfma_f32_16x16x32_f16 v[44:47], v[128:131], v[196:199], v[44:47]
	v_mfma_f32_16x16x32_f16 v[40:43], v[136:139], v[196:199], v[40:43]
	v_mfma_f32_16x16x32_f16 v[28:31], v[128:131], v[204:207], v[28:31]
	v_mfma_f32_16x16x32_f16 v[24:27], v[136:139], v[204:207], v[24:27]
	v_mfma_f32_16x16x32_f16 v[12:15], v[128:131], v[212:215], v[12:15]
	v_mfma_f32_16x16x32_f16 v[8:11], v[136:139], v[212:215], v[8:11]
	v_mfma_f32_16x16x32_f16 v[60:63], v[132:135], v[192:195], v[60:63]
	v_mfma_f32_16x16x32_f16 v[56:59], v[140:143], v[192:195], v[56:59]
	v_mfma_f32_16x16x32_f16 v[44:47], v[132:135], v[200:203], v[44:47]
	v_mfma_f32_16x16x32_f16 v[40:43], v[140:143], v[200:203], v[40:43]
	v_mfma_f32_16x16x32_f16 v[28:31], v[132:135], v[208:211], v[28:31]
	v_mfma_f32_16x16x32_f16 v[24:27], v[140:143], v[208:211], v[24:27]
	v_mfma_f32_16x16x32_f16 v[12:15], v[132:135], v[216:219], v[12:15]
	v_mfma_f32_16x16x32_f16 v[8:11], v[140:143], v[216:219], v[8:11]
	v_mfma_f32_16x16x32_f16 v[52:55], v[144:147], v[188:191], v[52:55]
	v_mfma_f32_16x16x32_f16 v[48:51], v[152:155], v[188:191], v[48:51]
	v_mfma_f32_16x16x32_f16 v[36:39], v[144:147], v[196:199], v[36:39]
	v_mfma_f32_16x16x32_f16 v[32:35], v[152:155], v[196:199], v[32:35]
	v_mfma_f32_16x16x32_f16 v[20:23], v[144:147], v[204:207], v[20:23]
	v_mfma_f32_16x16x32_f16 v[16:19], v[152:155], v[204:207], v[16:19]
	v_mfma_f32_16x16x32_f16 v[4:7], v[144:147], v[212:215], v[4:7]
	v_mfma_f32_16x16x32_f16 v[0:3], v[152:155], v[212:215], v[0:3]
	v_mfma_f32_16x16x32_f16 v[52:55], v[148:151], v[192:195], v[52:55]
	v_mfma_f32_16x16x32_f16 v[48:51], v[174:177], v[192:195], v[48:51]
	v_mfma_f32_16x16x32_f16 v[36:39], v[148:151], v[200:203], v[36:39]
	v_mfma_f32_16x16x32_f16 v[32:35], v[174:177], v[200:203], v[32:35]
	v_mfma_f32_16x16x32_f16 v[20:23], v[148:151], v[208:211], v[20:23]
	v_mfma_f32_16x16x32_f16 v[16:19], v[174:177], v[208:211], v[16:19]
	v_mfma_f32_16x16x32_f16 v[4:7], v[148:151], v[216:219], v[4:7]
	v_mfma_f32_16x16x32_f16 v[0:3], v[174:177], v[216:219], v[0:3]
	s_barrier
	s_add_i32 s53, 0, 0x18000
	s_add_i32 s54, 0, 0x1c000
	v_add_u32_e32 v140, s53, v182
	v_add_u32_e32 v165, s54, v182
	ds_read_b128 v[128:131], v140
	ds_read_b128 v[132:135], v140 offset:1024
	ds_read_b128 v[136:139], v140 offset:2048
	ds_read_b128 v[140:143], v140 offset:3072
	ds_read_b128 v[144:147], v165
	ds_read_b128 v[148:151], v165 offset:1024
	ds_read_b128 v[152:155], v165 offset:2048
	ds_read_b128 v[174:177], v165 offset:3072
	s_add_u32 s50, s50, 0x40000
	s_addc_u32 s51, s51, 0
	s_mov_b32 m0, s66
	v_lshl_add_u64 v[226:227], s[50:51], 0, v[156:157]
	ds_read_b128 v[188:191], v185 offset:32768
	ds_read_b128 v[192:195], v185 offset:33792
	ds_read_b128 v[196:199], v185 offset:34816
	ds_read_b128 v[200:203], v185 offset:35840
	ds_read_b128 v[204:207], v185 offset:36864
	ds_read_b128 v[208:211], v185 offset:37888
	ds_read_b128 v[212:215], v185 offset:38912
	ds_read_b128 v[216:219], v185 offset:39936
	global_load_lds_dwordx4 v[226:227], off
	v_lshl_add_u64 v[226:227], s[50:51], 0, v[160:161]
	s_mov_b32 m0, s67
	s_nop 0
	global_load_lds_dwordx4 v[226:227], off
	s_waitcnt vmcnt(8)
	s_waitcnt lgkmcnt(0)
	s_barrier
	v_mfma_f32_16x16x32_f16 v[124:127], v[128:131], v[188:191], v[124:127]
	v_mfma_f32_16x16x32_f16 v[120:123], v[136:139], v[188:191], v[120:123]
	v_mfma_f32_16x16x32_f16 v[108:111], v[128:131], v[196:199], v[108:111]
	v_mfma_f32_16x16x32_f16 v[104:107], v[136:139], v[196:199], v[104:107]
	v_mfma_f32_16x16x32_f16 v[92:95], v[128:131], v[204:207], v[92:95]
	v_mfma_f32_16x16x32_f16 v[88:91], v[136:139], v[204:207], v[88:91]
	v_mfma_f32_16x16x32_f16 v[76:79], v[128:131], v[212:215], v[76:79]
	v_mfma_f32_16x16x32_f16 v[72:75], v[136:139], v[212:215], v[72:75]
	v_mfma_f32_16x16x32_f16 v[124:127], v[132:135], v[192:195], v[124:127]
	v_mfma_f32_16x16x32_f16 v[120:123], v[140:143], v[192:195], v[120:123]
	v_mfma_f32_16x16x32_f16 v[108:111], v[132:135], v[200:203], v[108:111]
	v_mfma_f32_16x16x32_f16 v[104:107], v[140:143], v[200:203], v[104:107]
	v_mfma_f32_16x16x32_f16 v[92:95], v[132:135], v[208:211], v[92:95]
	v_mfma_f32_16x16x32_f16 v[88:91], v[140:143], v[208:211], v[88:91]
	v_mfma_f32_16x16x32_f16 v[76:79], v[132:135], v[216:219], v[76:79]
	v_mfma_f32_16x16x32_f16 v[72:75], v[140:143], v[216:219], v[72:75]
	v_mfma_f32_16x16x32_f16 v[116:119], v[144:147], v[188:191], v[116:119]
	v_mfma_f32_16x16x32_f16 v[112:115], v[152:155], v[188:191], v[112:115]
	v_mfma_f32_16x16x32_f16 v[100:103], v[144:147], v[196:199], v[100:103]
	v_mfma_f32_16x16x32_f16 v[96:99], v[152:155], v[196:199], v[96:99]
	v_mfma_f32_16x16x32_f16 v[84:87], v[144:147], v[204:207], v[84:87]
	v_mfma_f32_16x16x32_f16 v[80:83], v[152:155], v[204:207], v[80:83]
	v_mfma_f32_16x16x32_f16 v[68:71], v[144:147], v[212:215], v[68:71]
	v_mfma_f32_16x16x32_f16 v[64:67], v[152:155], v[212:215], v[64:67]
	v_mfma_f32_16x16x32_f16 v[116:119], v[148:151], v[192:195], v[116:119]
	v_mfma_f32_16x16x32_f16 v[112:115], v[174:177], v[192:195], v[112:115]
	v_mfma_f32_16x16x32_f16 v[100:103], v[148:151], v[200:203], v[100:103]
	v_mfma_f32_16x16x32_f16 v[96:99], v[174:177], v[200:203], v[96:99]
	v_mfma_f32_16x16x32_f16 v[84:87], v[148:151], v[208:211], v[84:87]
	v_mfma_f32_16x16x32_f16 v[80:83], v[174:177], v[208:211], v[80:83]
	v_mfma_f32_16x16x32_f16 v[68:71], v[148:151], v[216:219], v[68:71]
	v_mfma_f32_16x16x32_f16 v[64:67], v[174:177], v[216:219], v[64:67]
	s_barrier
; #define PG8_STAGE(bufoff, gbase, voff) do { _Pragma("unroll") for (int _i = 0; _i < 2; ++_i) \
;         __builtin_amdgcn_global_load_lds((const unsigned*)((const char*)(gbase) + (voff)[_i]), (PG8_LAS unsigned*)(lds + (bufoff) + ldsw + _i * 8192), 16, 0, 0); } while (0)
; #define PG8_LDA(dst, b, h) do { _Pragma("unroll") for (int m = 0; m < 4; ++m) _Pragma("unroll") for (int k = 0; k < 2; ++k) dst[m][k] = *(const PG8_LAS bf16x8*)(lds + PG8_SA(b, h) + aoff + m * 2048 + k * 1024); } while (0)
; #define PG8_MMA(ai, bj, At, Bt) do { __builtin_amdgcn_s_setprio(1); _Pragma("unroll") for (int m = 0; m < 4; ++m) _Pragma("unroll") for (int n = 0; n < 2; ++n) _Pragma("unroll") for (int k = 0; k < 2; ++k) \
;         acc[ai][bj][m][n] = mma16<F16>(Bt[n][k], At[m][k], acc[ai][bj][m][n]); __builtin_amdgcn_s_setprio(0); } while (0)
; #define PG8_WAIT_V(n) asm volatile("s_waitcnt vmcnt(" #n ")" ::: "memory")
; #define PG8_WAIT_L(n) asm volatile("s_waitcnt lgkmcnt(" #n ")" ::: "memory")
; #define PG8_BAR __builtin_amdgcn_s_barrier()
; #define PG8_SCHED __builtin_amdgcn_sched_barrier(0)
; template <class Epi, class Sched, bool ALIGN_EPI = false, bool SP2 = false, bool F16 = false>
; __device__ __forceinline__ void gemm_phase(PG8_LAS unsigned char* lds, const Gemm g, const Sched& S, const Epi& E, const int wid_in) {
;     ...
;         for (int t = 0; t < nt; t += 2) {
;     ...
;             PG8_LDA(At, 1, 1); PG8_STAGE(PG8_SB(1, 0), b3, voffB); PG8_STAGE(PG8_SB(1, 1), b3 + hstep, voffB); PG8_STAGE(PG8_SA(1, 0), a3, voffA);
;             PG8_WAIT_V(8); PG8_WAIT_L(0); PG8_BAR; PG8_MMA(1, 0, At, B0); PG8_MMA(1, 1, At, B1); PG8_BAR; PG8_SCHED;
;     ...
;         if constexpr (ALIGN_EPI) { if (wr == 0) PG8_BAR; }
	s_add_i32 s50, s53, s68
	v_lshl_add_u64 v[178:179], v[178:179], 0, s[20:21]
	s_mov_b32 m0, s50
	ds_read_b128 v[188:191], v185 offset:49152
	ds_read_b128 v[192:195], v185 offset:50176
	ds_read_b128 v[196:199], v185 offset:51200
	ds_read_b128 v[200:203], v185 offset:52224
	ds_read_b128 v[204:207], v185 offset:53248
	ds_read_b128 v[208:211], v185 offset:54272
	ds_read_b128 v[212:215], v185 offset:55296
	ds_read_b128 v[216:219], v185 offset:56320
	global_load_lds_dwordx4 v[178:179], off
	s_add_i32 m0, s50, 0x2000
	s_add_u32 s48, s48, 0x40080
	v_lshl_add_u64 v[178:179], v[220:221], 0, s[20:21]
	s_addc_u32 s49, s49, 0
	s_add_i32 s50, s54, s68
	global_load_lds_dwordx4 v[178:179], off
	v_lshl_add_u64 v[178:179], s[48:49], 0, v[158:159]
	s_mov_b32 m0, s50
	s_nop 0
	global_load_lds_dwordx4 v[178:179], off
	v_lshl_add_u64 v[178:179], s[48:49], 0, v[162:163]
	s_add_i32 m0, s50, 0x2000
	s_nop 0
	global_load_lds_dwordx4 v[178:179], off
	v_lshl_add_u64 v[178:179], v[222:223], 0, s[20:21]
	s_mov_b32 m0, s75
	s_nop 0
	global_load_lds_dwordx4 v[178:179], off
	v_lshl_add_u64 v[178:179], v[224:225], 0, s[20:21]
	s_mov_b32 m0, s89
	s_nop 0
	global_load_lds_dwordx4 v[178:179], off
	s_waitcnt vmcnt(8)
	s_waitcnt lgkmcnt(0)
	s_barrier
	v_mfma_f32_16x16x32_f16 v[60:63], v[128:131], v[188:191], v[60:63]
	v_mfma_f32_16x16x32_f16 v[56:59], v[136:139], v[188:191], v[56:59]
	v_mfma_f32_16x16x32_f16 v[44:47], v[128:131], v[196:199], v[44:47]
	v_mfma_f32_16x16x32_f16 v[40:43], v[136:139], v[196:199], v[40:43]
	v_mfma_f32_16x16x32_f16 v[28:31], v[128:131], v[204:207], v[28:31]
	v_mfma_f32_16x16x32_f16 v[24:27], v[136:139], v[204:207], v[24:27]
	v_mfma_f32_16x16x32_f16 v[12:15], v[128:131], v[212:215], v[12:15]
	v_mfma_f32_16x16x32_f16 v[8:11], v[136:139], v[212:215], v[8:11]
	v_mfma_f32_16x16x32_f16 v[60:63], v[132:135], v[192:195], v[60:63]
	v_mfma_f32_16x16x32_f16 v[56:59], v[140:143], v[192:195], v[56:59]
	v_mfma_f32_16x16x32_f16 v[44:47], v[132:135], v[200:203], v[44:47]
	v_mfma_f32_16x16x32_f16 v[40:43], v[140:143], v[200:203], v[40:43]
	v_mfma_f32_16x16x32_f16 v[28:31], v[132:135], v[208:211], v[28:31]
	v_mfma_f32_16x16x32_f16 v[24:27], v[140:143], v[208:211], v[24:27]
	v_mfma_f32_16x16x32_f16 v[12:15], v[132:135], v[216:219], v[12:15]
	v_mfma_f32_16x16x32_f16 v[8:11], v[140:143], v[216:219], v[8:11]
	v_mfma_f32_16x16x32_f16 v[52:55], v[144:147], v[188:191], v[52:55]
	v_mfma_f32_16x16x32_f16 v[48:51], v[152:155], v[188:191], v[48:51]
	v_mfma_f32_16x16x32_f16 v[36:39], v[144:147], v[196:199], v[36:39]
	v_mfma_f32_16x16x32_f16 v[32:35], v[152:155], v[196:199], v[32:35]
	v_mfma_f32_16x16x32_f16 v[20:23], v[144:147], v[204:207], v[20:23]
	v_mfma_f32_16x16x32_f16 v[16:19], v[152:155], v[204:207], v[16:19]
	v_mfma_f32_16x16x32_f16 v[4:7], v[144:147], v[212:215], v[4:7]
	v_mfma_f32_16x16x32_f16 v[0:3], v[152:155], v[212:215], v[0:3]
	v_mfma_f32_16x16x32_f16 v[52:55], v[148:151], v[192:195], v[52:55]
	v_mfma_f32_16x16x32_f16 v[48:51], v[174:177], v[192:195], v[48:51]
	v_mfma_f32_16x16x32_f16 v[36:39], v[148:151], v[200:203], v[36:39]
	v_mfma_f32_16x16x32_f16 v[32:35], v[174:177], v[200:203], v[32:35]
	v_mfma_f32_16x16x32_f16 v[20:23], v[148:151], v[208:211], v[20:23]
	v_mfma_f32_16x16x32_f16 v[16:19], v[174:177], v[208:211], v[16:19]
	v_mfma_f32_16x16x32_f16 v[4:7], v[148:151], v[216:219], v[4:7]
	v_mfma_f32_16x16x32_f16 v[0:3], v[174:177], v[216:219], v[0:3]
	s_barrier
	s_add_i32 s52, s52, 2
	s_add_u32 s46, s46, 0x100
	s_addc_u32 s47, s47, 0
	s_add_u32 s42, s42, 0x100
	s_addc_u32 s43, s43, 0
	s_cmp_gt_u32 s52, 13
	s_cbranch_scc0 .LBB0_902
	s_and_b64 vcc, exec, s[16:17]
	s_cbranch_vccz .LBB0_905
	s_barrier

; #define PG8_STAGE(bufoff, gbase, voff) do { _Pragma("unroll") for (int _i = 0; _i < 2; ++_i) \
;         __builtin_amdgcn_global_load_lds((const unsigned*)((const char*)(gbase) + (voff)[_i]), (PG8_LAS unsigned*)(lds + (bufoff) + ldsw + _i * 8192), 16, 0, 0); } while (0)
; #define PG8_LDA(dst, b, h) do { _Pragma("unroll") for (int m = 0; m < 4; ++m) _Pragma("unroll") for (int k = 0; k < 2; ++k) dst[m][k] = *(const PG8_LAS bf16x8*)(lds + PG8_SA(b, h) + aoff + m * 2048 + k * 1024); } while (0)
; #define PG8_LDB(dst, b, h) do { _Pragma("unroll") for (int n = 0; n < 2; ++n) _Pragma("unroll") for (int k = 0; k < 2; ++k) dst[n][k] = *(const PG8_LAS bf16x8*)(lds + PG8_SB(b, h) + boff + n * 2048 + k * 1024); } while (0)
; #define PG8_MMA(ai, bj, At, Bt) do { __builtin_amdgcn_s_setprio(1); _Pragma("unroll") for (int m = 0; m < 4; ++m) _Pragma("unroll") for (int n = 0; n < 2; ++n) _Pragma("unroll") for (int k = 0; k < 2; ++k) \
;         acc[ai][bj][m][n] = mma16<F16>(Bt[n][k], At[m][k], acc[ai][bj][m][n]); __builtin_amdgcn_s_setprio(0); } while (0)
; #define PG8_WAIT_V(n) asm volatile("s_waitcnt vmcnt(" #n ")" ::: "memory")
; #define PG8_BAR __builtin_amdgcn_s_barrier()
; template <class Epi, class Sched, bool ALIGN_EPI = false, bool SP2 = false, bool F16 = false>
; __device__ __forceinline__ void gemm_phase(PG8_LAS unsigned char* lds, const Gemm g, const Sched& S, const Epi& E, const int wid_in) {
;     ...
;         for (int t = 0; t < nt; t += 2) {
;             const bool last = (t == nt - 2);
;             const char* a1 = cA + (size_t)(t + 1) * kstep;
;             const char* a2 = last ? nA : cA + (size_t)(t + 2) * kstep; const char* b2 = last ? nB : cB + (size_t)(t + 2) * kstep;
;             const char* a3 = a2 + kstep; const char* b3 = b2 + kstep;
;             if (last && has_next) S.a_ready(nxt);
;             if constexpr (SP2) {
;             PG8_LDB(B0, 0, 0); PG8_LDB(B1, 0, 1); PG8_SCHED; PG8_LDA(At, 0, 0); PG8_STAGE(PG8_SA(1, 1), a1 + hstep, voffA);
;             PG8_WAIT_V(8); PG8_WAIT_L(0); PG8_BAR; PG8_MMA(0, 0, At, B0); PG8_MMA(0, 1, At, B1); PG8_BAR; PG8_SCHED;
;             PG8_LDA(At, 0, 1); PG8_STAGE(PG8_SB(0, 0), b2, voffB); PG8_STAGE(PG8_SB(0, 1), b2 + hstep, voffB); PG8_STAGE(PG8_SA(0, 0), a2, voffA);
;             PG8_WAIT_V(8); PG8_WAIT_L(0); PG8_BAR; PG8_MMA(1, 0, At, B0); PG8_MMA(1, 1, At, B1); PG8_BAR; PG8_SCHED;
.LBB0_1165:
	ds_read_b128 v[128:131], v189
	ds_read_b128 v[132:135], v189 offset:1024
	ds_read_b128 v[136:139], v189 offset:2048
	ds_read_b128 v[140:143], v189 offset:3072
	ds_read_b128 v[144:147], v190
	ds_read_b128 v[148:151], v190 offset:1024
	ds_read_b128 v[168:171], v190 offset:2048
	ds_read_b128 v[172:175], v190 offset:3072
	s_add_u32 s50, s48, 0xfffc0080
	s_addc_u32 s51, s49, -1
	s_cmp_eq_u32 s64, 12
	s_cselect_b32 s53, s35, s51
	s_cselect_b32 s52, s42, s50
	s_cselect_b32 s51, s31, s63
	s_cselect_b32 s50, s43, s47
	v_lshl_add_u64 v[184:185], s[48:49], 0, v[160:161]
	s_add_i32 m0, s74, 0xc000
	ds_read_b128 v[176:179], v191
	ds_read_b128 v[180:183], v191 offset:1024
	ds_read_b128 v[192:195], v191 offset:2048
	ds_read_b128 v[196:199], v191 offset:3072
	ds_read_b128 v[200:203], v191 offset:4096
	ds_read_b128 v[204:207], v191 offset:5120
	ds_read_b128 v[208:211], v191 offset:6144
	ds_read_b128 v[212:215], v191 offset:7168
	global_load_lds_dwordx4 v[184:185], off
	v_lshl_add_u64 v[184:185], s[48:49], 0, v[162:163]
	s_add_i32 m0, s74, 0xe000
	s_nop 0
	global_load_lds_dwordx4 v[184:185], off
	s_waitcnt vmcnt(8)
	s_waitcnt lgkmcnt(0)
	s_barrier
	v_mfma_f32_16x16x32_bf16 v[124:127], v[128:131], v[176:179], v[124:127]
	v_mfma_f32_16x16x32_bf16 v[120:123], v[136:139], v[176:179], v[120:123]
	v_mfma_f32_16x16x32_bf16 v[108:111], v[128:131], v[192:195], v[108:111]
	v_mfma_f32_16x16x32_bf16 v[104:107], v[136:139], v[192:195], v[104:107]
	v_mfma_f32_16x16x32_bf16 v[92:95], v[128:131], v[200:203], v[92:95]
	v_mfma_f32_16x16x32_bf16 v[88:91], v[136:139], v[200:203], v[88:91]
	v_mfma_f32_16x16x32_bf16 v[76:79], v[128:131], v[208:211], v[76:79]
	v_mfma_f32_16x16x32_bf16 v[72:75], v[136:139], v[208:211], v[72:75]
	v_mfma_f32_16x16x32_bf16 v[124:127], v[132:135], v[180:183], v[124:127]
	v_mfma_f32_16x16x32_bf16 v[120:123], v[140:143], v[180:183], v[120:123]
	v_mfma_f32_16x16x32_bf16 v[108:111], v[132:135], v[196:199], v[108:111]
	v_mfma_f32_16x16x32_bf16 v[104:107], v[140:143], v[196:199], v[104:107]
	v_mfma_f32_16x16x32_bf16 v[92:95], v[132:135], v[204:207], v[92:95]
	v_mfma_f32_16x16x32_bf16 v[88:91], v[140:143], v[204:207], v[88:91]
	v_mfma_f32_16x16x32_bf16 v[76:79], v[132:135], v[212:215], v[76:79]
	v_mfma_f32_16x16x32_bf16 v[72:75], v[140:143], v[212:215], v[72:75]
	v_mfma_f32_16x16x32_bf16 v[116:119], v[144:147], v[176:179], v[116:119]
	v_mfma_f32_16x16x32_bf16 v[112:115], v[168:171], v[176:179], v[112:115]
	v_mfma_f32_16x16x32_bf16 v[100:103], v[144:147], v[192:195], v[100:103]
	v_mfma_f32_16x16x32_bf16 v[96:99], v[168:171], v[192:195], v[96:99]
	v_mfma_f32_16x16x32_bf16 v[84:87], v[144:147], v[200:203], v[84:87]
	v_mfma_f32_16x16x32_bf16 v[80:83], v[168:171], v[200:203], v[80:83]
	v_mfma_f32_16x16x32_bf16 v[68:71], v[144:147], v[208:211], v[68:71]
	v_mfma_f32_16x16x32_bf16 v[64:67], v[168:171], v[208:211], v[64:67]
	v_mfma_f32_16x16x32_bf16 v[116:119], v[148:151], v[180:183], v[116:119]
	v_mfma_f32_16x16x32_bf16 v[112:115], v[172:175], v[180:183], v[112:115]
	v_mfma_f32_16x16x32_bf16 v[100:103], v[148:151], v[196:199], v[100:103]
	v_mfma_f32_16x16x32_bf16 v[96:99], v[172:175], v[196:199], v[96:99]
	v_mfma_f32_16x16x32_bf16 v[84:87], v[148:151], v[204:207], v[84:87]
	v_mfma_f32_16x16x32_bf16 v[80:83], v[172:175], v[204:207], v[80:83]
	v_mfma_f32_16x16x32_bf16 v[68:71], v[148:151], v[212:215], v[68:71]
	v_mfma_f32_16x16x32_bf16 v[64:67], v[172:175], v[212:215], v[64:67]
	s_barrier
	s_add_i32 s65, s60, s68
	v_lshl_add_u64 v[184:185], s[50:51], 0, v[154:155]
	s_mov_b32 m0, s65
	ds_read_b128 v[176:179], v191 offset:16384
	ds_read_b128 v[180:183], v191 offset:17408
	ds_read_b128 v[192:195], v191 offset:18432
	ds_read_b128 v[196:199], v191 offset:19456
	ds_read_b128 v[200:203], v191 offset:20480
	ds_read_b128 v[204:207], v191 offset:21504
	ds_read_b128 v[208:211], v191 offset:22528
	ds_read_b128 v[212:215], v191 offset:23552
	global_load_lds_dwordx4 v[184:185], off
	s_add_i32 m0, s65, 0x2000
	s_add_u32 s66, s50, 0x40000
	v_lshl_add_u64 v[216:217], s[50:51], 0, v[158:159]
	s_addc_u32 s67, s51, 0
	s_add_i32 s65, s61, s68
	global_load_lds_dwordx4 v[216:217], off
	v_lshl_add_u64 v[218:219], s[66:67], 0, v[154:155]
	s_mov_b32 m0, s65
	v_lshl_add_u64 v[220:221], s[52:53], 0, v[156:157]
	global_load_lds_dwordx4 v[218:219], off
	v_lshl_add_u64 v[218:219], s[66:67], 0, v[158:159]
	s_add_i32 m0, s65, 0x2000
	s_nop 0
	global_load_lds_dwordx4 v[218:219], off
	v_lshl_add_u64 v[218:219], s[52:53], 0, v[152:153]
	s_mov_b32 m0, s74
	s_nop 0
	global_load_lds_dwordx4 v[218:219], off
	s_mov_b32 m0, s41
	s_nop 0
	global_load_lds_dwordx4 v[220:221], off
	s_waitcnt vmcnt(8)
	s_waitcnt lgkmcnt(0)
	s_barrier
; #define PG8_STAGE(bufoff, gbase, voff) do { _Pragma("unroll") for (int _i = 0; _i < 2; ++_i) \
;         __builtin_amdgcn_global_load_lds((const unsigned*)((const char*)(gbase) + (voff)[_i]), (PG8_LAS unsigned*)(lds + (bufoff) + ldsw + _i * 8192), 16, 0, 0); } while (0)
; #define PG8_LDA(dst, b, h) do { _Pragma("unroll") for (int m = 0; m < 4; ++m) _Pragma("unroll") for (int k = 0; k < 2; ++k) dst[m][k] = *(const PG8_LAS bf16x8*)(lds + PG8_SA(b, h) + aoff + m * 2048 + k * 1024); } while (0)
; #define PG8_LDB(dst, b, h) do { _Pragma("unroll") for (int n = 0; n < 2; ++n) _Pragma("unroll") for (int k = 0; k < 2; ++k) dst[n][k] = *(const PG8_LAS bf16x8*)(lds + PG8_SB(b, h) + boff + n * 2048 + k * 1024); } while (0)
; #define PG8_MMA(ai, bj, At, Bt) do { __builtin_amdgcn_s_setprio(1); _Pragma("unroll") for (int m = 0; m < 4; ++m) _Pragma("unroll") for (int n = 0; n < 2; ++n) _Pragma("unroll") for (int k = 0; k < 2; ++k) \
;         acc[ai][bj][m][n] = mma16<F16>(Bt[n][k], At[m][k], acc[ai][bj][m][n]); __builtin_amdgcn_s_setprio(0); } while (0)
; #define PG8_WAIT_V(n) asm volatile("s_waitcnt vmcnt(" #n ")" ::: "memory")
; #define PG8_WAIT_L(n) asm volatile("s_waitcnt lgkmcnt(" #n ")" ::: "memory")
; #define PG8_BAR __builtin_amdgcn_s_barrier()
; #define PG8_SCHED __builtin_amdgcn_sched_barrier(0)
; template <class Epi, class Sched, bool ALIGN_EPI = false, bool SP2 = false, bool F16 = false>
; __device__ __forceinline__ void gemm_phase(PG8_LAS unsigned char* lds, const Gemm g, const Sched& S, const Epi& E, const int wid_in) {
;     ...
;             PG8_WAIT_V(8); PG8_WAIT_L(0); PG8_BAR; PG8_MMA(1, 0, At, B0); PG8_MMA(1, 1, At, B1); PG8_BAR; PG8_SCHED;
;             PG8_LDB(B0, 1, 0); PG8_LDB(B1, 1, 1); PG8_SCHED; PG8_LDA(At, 1, 0); PG8_STAGE(PG8_SA(0, 1), a2 + hstep, voffA);
;             PG8_WAIT_V(8); PG8_WAIT_L(0); PG8_BAR; PG8_MMA(0, 0, At, B0); PG8_MMA(0, 1, At, B1); PG8_BAR; PG8_SCHED;
	v_mfma_f32_16x16x32_bf16 v[60:63], v[128:131], v[176:179], v[60:63]
	v_mfma_f32_16x16x32_bf16 v[56:59], v[136:139], v[176:179], v[56:59]
	v_mfma_f32_16x16x32_bf16 v[44:47], v[128:131], v[192:195], v[44:47]
	v_mfma_f32_16x16x32_bf16 v[40:43], v[136:139], v[192:195], v[40:43]
	v_mfma_f32_16x16x32_bf16 v[28:31], v[128:131], v[200:203], v[28:31]
	v_mfma_f32_16x16x32_bf16 v[24:27], v[136:139], v[200:203], v[24:27]
	v_mfma_f32_16x16x32_bf16 v[12:15], v[128:131], v[208:211], v[12:15]
	v_mfma_f32_16x16x32_bf16 v[8:11], v[136:139], v[208:211], v[8:11]
	v_mfma_f32_16x16x32_bf16 v[60:63], v[132:135], v[180:183], v[60:63]
	v_mfma_f32_16x16x32_bf16 v[56:59], v[140:143], v[180:183], v[56:59]
	v_mfma_f32_16x16x32_bf16 v[44:47], v[132:135], v[196:199], v[44:47]
	v_mfma_f32_16x16x32_bf16 v[40:43], v[140:143], v[196:199], v[40:43]
	v_mfma_f32_16x16x32_bf16 v[28:31], v[132:135], v[204:207], v[28:31]
	v_mfma_f32_16x16x32_bf16 v[24:27], v[140:143], v[204:207], v[24:27]
	v_mfma_f32_16x16x32_bf16 v[12:15], v[132:135], v[212:215], v[12:15]
	v_mfma_f32_16x16x32_bf16 v[8:11], v[140:143], v[212:215], v[8:11]
	v_mfma_f32_16x16x32_bf16 v[52:55], v[144:147], v[176:179], v[52:55]
	v_mfma_f32_16x16x32_bf16 v[48:51], v[168:171], v[176:179], v[48:51]
	v_mfma_f32_16x16x32_bf16 v[36:39], v[144:147], v[192:195], v[36:39]
	v_mfma_f32_16x16x32_bf16 v[32:35], v[168:171], v[192:195], v[32:35]
	v_mfma_f32_16x16x32_bf16 v[20:23], v[144:147], v[200:203], v[20:23]
	v_mfma_f32_16x16x32_bf16 v[16:19], v[168:171], v[200:203], v[16:19]
	v_mfma_f32_16x16x32_bf16 v[4:7], v[144:147], v[208:211], v[4:7]
	v_mfma_f32_16x16x32_bf16 v[0:3], v[168:171], v[208:211], v[0:3]
	v_mfma_f32_16x16x32_bf16 v[52:55], v[148:151], v[180:183], v[52:55]
	v_mfma_f32_16x16x32_bf16 v[48:51], v[172:175], v[180:183], v[48:51]
	v_mfma_f32_16x16x32_bf16 v[36:39], v[148:151], v[196:199], v[36:39]
	v_mfma_f32_16x16x32_bf16 v[32:35], v[172:175], v[196:199], v[32:35]
	v_mfma_f32_16x16x32_bf16 v[20:23], v[148:151], v[204:207], v[20:23]
	v_mfma_f32_16x16x32_bf16 v[16:19], v[172:175], v[204:207], v[16:19]
	v_mfma_f32_16x16x32_bf16 v[4:7], v[148:151], v[212:215], v[4:7]
	v_mfma_f32_16x16x32_bf16 v[0:3], v[172:175], v[212:215], v[0:3]
	s_barrier
	s_add_i32 s65, 0, 0x18000
	s_add_i32 s66, 0, 0x1c000
	v_add_u32_e32 v140, s65, v188
	v_add_u32_e32 v172, s66, v188
	ds_read_b128 v[128:131], v140
	ds_read_b128 v[132:135], v140 offset:1024
	ds_read_b128 v[136:139], v140 offset:2048
	ds_read_b128 v[140:143], v140 offset:3072
	ds_read_b128 v[144:147], v172
	ds_read_b128 v[148:151], v172 offset:1024
	ds_read_b128 v[168:171], v172 offset:2048
	ds_read_b128 v[172:175], v172 offset:3072
	s_add_u32 s52, s52, 0x40000
	s_addc_u32 s53, s53, 0
	s_mov_b32 m0, s54
	v_lshl_add_u64 v[222:223], s[52:53], 0, v[152:153]
	ds_read_b128 v[176:179], v191 offset:32768
	ds_read_b128 v[180:183], v191 offset:33792
	ds_read_b128 v[192:195], v191 offset:34816
	ds_read_b128 v[196:199], v191 offset:35840
	ds_read_b128 v[200:203], v191 offset:36864
	ds_read_b128 v[204:207], v191 offset:37888
	ds_read_b128 v[208:211], v191 offset:38912
	ds_read_b128 v[212:215], v191 offset:39936
	global_load_lds_dwordx4 v[222:223], off
	v_lshl_add_u64 v[222:223], s[52:53], 0, v[156:157]
	s_mov_b32 m0, s55
	s_nop 0
	global_load_lds_dwordx4 v[222:223], off
	s_waitcnt vmcnt(8)
	s_waitcnt lgkmcnt(0)
	s_barrier
	v_mfma_f32_16x16x32_bf16 v[124:127], v[128:131], v[176:179], v[124:127]
	v_mfma_f32_16x16x32_bf16 v[120:123], v[136:139], v[176:179], v[120:123]
	v_mfma_f32_16x16x32_bf16 v[108:111], v[128:131], v[192:195], v[108:111]
	v_mfma_f32_16x16x32_bf16 v[104:107], v[136:139], v[192:195], v[104:107]
	v_mfma_f32_16x16x32_bf16 v[92:95], v[128:131], v[200:203], v[92:95]
	v_mfma_f32_16x16x32_bf16 v[88:91], v[136:139], v[200:203], v[88:91]
	v_mfma_f32_16x16x32_bf16 v[76:79], v[128:131], v[208:211], v[76:79]
	v_mfma_f32_16x16x32_bf16 v[72:75], v[136:139], v[208:211], v[72:75]
	v_mfma_f32_16x16x32_bf16 v[124:127], v[132:135], v[180:183], v[124:127]
	v_mfma_f32_16x16x32_bf16 v[120:123], v[140:143], v[180:183], v[120:123]
	v_mfma_f32_16x16x32_bf16 v[108:111], v[132:135], v[196:199], v[108:111]
	v_mfma_f32_16x16x32_bf16 v[104:107], v[140:143], v[196:199], v[104:107]
	v_mfma_f32_16x16x32_bf16 v[92:95], v[132:135], v[204:207], v[92:95]
	v_mfma_f32_16x16x32_bf16 v[88:91], v[140:143], v[204:207], v[88:91]
	v_mfma_f32_16x16x32_bf16 v[76:79], v[132:135], v[212:215], v[76:79]
	v_mfma_f32_16x16x32_bf16 v[72:75], v[140:143], v[212:215], v[72:75]
	v_mfma_f32_16x16x32_bf16 v[116:119], v[144:147], v[176:179], v[116:119]
	v_mfma_f32_16x16x32_bf16 v[112:115], v[168:171], v[176:179], v[112:115]
	v_mfma_f32_16x16x32_bf16 v[100:103], v[144:147], v[192:195], v[100:103]
	v_mfma_f32_16x16x32_bf16 v[96:99], v[168:171], v[192:195], v[96:99]
	v_mfma_f32_16x16x32_bf16 v[84:87], v[144:147], v[200:203], v[84:87]
	v_mfma_f32_16x16x32_bf16 v[80:83], v[168:171], v[200:203], v[80:83]
	v_mfma_f32_16x16x32_bf16 v[68:71], v[144:147], v[208:211], v[68:71]
	v_mfma_f32_16x16x32_bf16 v[64:67], v[168:171], v[208:211], v[64:67]
	v_mfma_f32_16x16x32_bf16 v[116:119], v[148:151], v[180:183], v[116:119]
	v_mfma_f32_16x16x32_bf16 v[112:115], v[172:175], v[180:183], v[112:115]
	v_mfma_f32_16x16x32_bf16 v[100:103], v[148:151], v[196:199], v[100:103]
	v_mfma_f32_16x16x32_bf16 v[96:99], v[172:175], v[196:199], v[96:99]
	v_mfma_f32_16x16x32_bf16 v[84:87], v[148:151], v[204:207], v[84:87]
	v_mfma_f32_16x16x32_bf16 v[80:83], v[172:175], v[204:207], v[80:83]
	v_mfma_f32_16x16x32_bf16 v[68:71], v[148:151], v[212:215], v[68:71]
	v_mfma_f32_16x16x32_bf16 v[64:67], v[172:175], v[212:215], v[64:67]
	s_barrier
; #define PG8_STAGE(bufoff, gbase, voff) do { _Pragma("unroll") for (int _i = 0; _i < 2; ++_i) \
;         __builtin_amdgcn_global_load_lds((const unsigned*)((const char*)(gbase) + (voff)[_i]), (PG8_LAS unsigned*)(lds + (bufoff) + ldsw + _i * 8192), 16, 0, 0); } while (0)
; #define PG8_LDA(dst, b, h) do { _Pragma("unroll") for (int m = 0; m < 4; ++m) _Pragma("unroll") for (int k = 0; k < 2; ++k) dst[m][k] = *(const PG8_LAS bf16x8*)(lds + PG8_SA(b, h) + aoff + m * 2048 + k * 1024); } while (0)
; #define PG8_MMA(ai, bj, At, Bt) do { __builtin_amdgcn_s_setprio(1); _Pragma("unroll") for (int m = 0; m < 4; ++m) _Pragma("unroll") for (int n = 0; n < 2; ++n) _Pragma("unroll") for (int k = 0; k < 2; ++k) \
;         acc[ai][bj][m][n] = mma16<F16>(Bt[n][k], At[m][k], acc[ai][bj][m][n]); __builtin_amdgcn_s_setprio(0); } while (0)
; #define PG8_WAIT_V(n) asm volatile("s_waitcnt vmcnt(" #n ")" ::: "memory")
; #define PG8_WAIT_L(n) asm volatile("s_waitcnt lgkmcnt(" #n ")" ::: "memory")
; #define PG8_BAR __builtin_amdgcn_s_barrier()
; #define PG8_SCHED __builtin_amdgcn_sched_barrier(0)
; template <class Epi, class Sched, bool ALIGN_EPI = false, bool SP2 = false, bool F16 = false>
; __device__ __forceinline__ void gemm_phase(PG8_LAS unsigned char* lds, const Gemm g, const Sched& S, const Epi& E, const int wid_in) {
;     ...
;         for (int t = 0; t < nt; t += 2) {
;     ...
;             PG8_LDA(At, 1, 1); PG8_STAGE(PG8_SB(1, 0), b3, voffB); PG8_STAGE(PG8_SB(1, 1), b3 + hstep, voffB); PG8_STAGE(PG8_SA(1, 0), a3, voffA);
;             PG8_WAIT_V(8); PG8_WAIT_L(0); PG8_BAR; PG8_MMA(1, 0, At, B0); PG8_MMA(1, 1, At, B1); PG8_BAR; PG8_SCHED;
;     ...
;         if constexpr (ALIGN_EPI) { if (wr == 0) PG8_BAR; }
	s_add_i32 s52, s65, s68
	v_lshl_add_u64 v[184:185], v[184:185], 0, s[28:29]
	s_mov_b32 m0, s52
	ds_read_b128 v[176:179], v191 offset:49152
	ds_read_b128 v[180:183], v191 offset:50176
	ds_read_b128 v[192:195], v191 offset:51200
	ds_read_b128 v[196:199], v191 offset:52224
	ds_read_b128 v[200:203], v191 offset:53248
	ds_read_b128 v[204:207], v191 offset:54272
	ds_read_b128 v[208:211], v191 offset:55296
	ds_read_b128 v[212:215], v191 offset:56320
	global_load_lds_dwordx4 v[184:185], off
	s_add_i32 m0, s52, 0x2000
	s_add_u32 s50, s50, 0x40080
	v_lshl_add_u64 v[184:185], v[216:217], 0, s[28:29]
	s_addc_u32 s51, s51, 0
	s_add_i32 s52, s66, s68
	global_load_lds_dwordx4 v[184:185], off
	v_lshl_add_u64 v[184:185], s[50:51], 0, v[154:155]
	s_mov_b32 m0, s52
	s_nop 0
	global_load_lds_dwordx4 v[184:185], off
	v_lshl_add_u64 v[184:185], s[50:51], 0, v[158:159]
	s_add_i32 m0, s52, 0x2000
	s_nop 0
	global_load_lds_dwordx4 v[184:185], off
	v_lshl_add_u64 v[184:185], v[218:219], 0, s[28:29]
	s_mov_b32 m0, s75
	s_nop 0
	global_load_lds_dwordx4 v[184:185], off
	v_lshl_add_u64 v[184:185], v[220:221], 0, s[28:29]
	s_mov_b32 m0, s56
	s_nop 0
	global_load_lds_dwordx4 v[184:185], off
	s_waitcnt vmcnt(8)
	s_waitcnt lgkmcnt(0)
	s_barrier
	v_mfma_f32_16x16x32_bf16 v[60:63], v[128:131], v[176:179], v[60:63]
	v_mfma_f32_16x16x32_bf16 v[56:59], v[136:139], v[176:179], v[56:59]
	v_mfma_f32_16x16x32_bf16 v[44:47], v[128:131], v[192:195], v[44:47]
	v_mfma_f32_16x16x32_bf16 v[40:43], v[136:139], v[192:195], v[40:43]
	v_mfma_f32_16x16x32_bf16 v[28:31], v[128:131], v[200:203], v[28:31]
	v_mfma_f32_16x16x32_bf16 v[24:27], v[136:139], v[200:203], v[24:27]
	v_mfma_f32_16x16x32_bf16 v[12:15], v[128:131], v[208:211], v[12:15]
	v_mfma_f32_16x16x32_bf16 v[8:11], v[136:139], v[208:211], v[8:11]
	v_mfma_f32_16x16x32_bf16 v[60:63], v[132:135], v[180:183], v[60:63]
	v_mfma_f32_16x16x32_bf16 v[56:59], v[140:143], v[180:183], v[56:59]
	v_mfma_f32_16x16x32_bf16 v[44:47], v[132:135], v[196:199], v[44:47]
	v_mfma_f32_16x16x32_bf16 v[40:43], v[140:143], v[196:199], v[40:43]
	v_mfma_f32_16x16x32_bf16 v[28:31], v[132:135], v[204:207], v[28:31]
	v_mfma_f32_16x16x32_bf16 v[24:27], v[140:143], v[204:207], v[24:27]
	v_mfma_f32_16x16x32_bf16 v[12:15], v[132:135], v[212:215], v[12:15]
	v_mfma_f32_16x16x32_bf16 v[8:11], v[140:143], v[212:215], v[8:11]
	v_mfma_f32_16x16x32_bf16 v[52:55], v[144:147], v[176:179], v[52:55]
	v_mfma_f32_16x16x32_bf16 v[48:51], v[168:171], v[176:179], v[48:51]
	v_mfma_f32_16x16x32_bf16 v[36:39], v[144:147], v[192:195], v[36:39]
	v_mfma_f32_16x16x32_bf16 v[32:35], v[168:171], v[192:195], v[32:35]
	v_mfma_f32_16x16x32_bf16 v[20:23], v[144:147], v[200:203], v[20:23]
	v_mfma_f32_16x16x32_bf16 v[16:19], v[168:171], v[200:203], v[16:19]
	v_mfma_f32_16x16x32_bf16 v[4:7], v[144:147], v[208:211], v[4:7]
	v_mfma_f32_16x16x32_bf16 v[0:3], v[168:171], v[208:211], v[0:3]
	v_mfma_f32_16x16x32_bf16 v[52:55], v[148:151], v[180:183], v[52:55]
	v_mfma_f32_16x16x32_bf16 v[48:51], v[172:175], v[180:183], v[48:51]
	v_mfma_f32_16x16x32_bf16 v[36:39], v[148:151], v[196:199], v[36:39]
	v_mfma_f32_16x16x32_bf16 v[32:35], v[172:175], v[196:199], v[32:35]
	v_mfma_f32_16x16x32_bf16 v[20:23], v[148:151], v[204:207], v[20:23]
	v_mfma_f32_16x16x32_bf16 v[16:19], v[172:175], v[204:207], v[16:19]
	v_mfma_f32_16x16x32_bf16 v[4:7], v[148:151], v[212:215], v[4:7]
	v_mfma_f32_16x16x32_bf16 v[0:3], v[172:175], v[212:215], v[0:3]
	s_barrier
	s_add_i32 s64, s64, 2
	s_add_u32 s48, s48, 0x100
	s_addc_u32 s49, s49, 0
	s_add_u32 s47, s47, 0x100
	s_addc_u32 s63, s63, 0
	s_cmp_gt_u32 s64, 13
	s_cbranch_scc0 .LBB0_1165
	s_and_b64 vcc, exec, s[16:17]
	s_cbranch_vccz .LBB0_1168
	s_barrier

; #define PG8_STAGE(bufoff, gbase, voff) do { _Pragma("unroll") for (int _i = 0; _i < 2; ++_i) \
;         __builtin_amdgcn_global_load_lds((const unsigned*)((const char*)(gbase) + (voff)[_i]), (PG8_LAS unsigned*)(lds + (bufoff) + ldsw + _i * 8192), 16, 0, 0); } while (0)
; #define PG8_LDA(dst, b, h) do { _Pragma("unroll") for (int m = 0; m < 4; ++m) _Pragma("unroll") for (int k = 0; k < 2; ++k) dst[m][k] = *(const PG8_LAS bf16x8*)(lds + PG8_SA(b, h) + aoff + m * 2048 + k * 1024); } while (0)
; #define PG8_LDB(dst, b, h) do { _Pragma("unroll") for (int n = 0; n < 2; ++n) _Pragma("unroll") for (int k = 0; k < 2; ++k) dst[n][k] = *(const PG8_LAS bf16x8*)(lds + PG8_SB(b, h) + boff + n * 2048 + k * 1024); } while (0)
; #define PG8_MMA(ai, bj, At, Bt) do { __builtin_amdgcn_s_setprio(1); _Pragma("unroll") for (int m = 0; m < 4; ++m) _Pragma("unroll") for (int n = 0; n < 2; ++n) _Pragma("unroll") for (int k = 0; k < 2; ++k) \
;         acc[ai][bj][m][n] = mma16<F16>(Bt[n][k], At[m][k], acc[ai][bj][m][n]); __builtin_amdgcn_s_setprio(0); } while (0)
; #define PG8_WAIT_V(n) asm volatile("s_waitcnt vmcnt(" #n ")" ::: "memory")
; #define PG8_BAR __builtin_amdgcn_s_barrier()
; template <class Epi, class Sched, bool ALIGN_EPI = false, bool SP2 = false, bool F16 = false>
; __device__ __forceinline__ void gemm_phase(PG8_LAS unsigned char* lds, const Gemm g, const Sched& S, const Epi& E, const int wid_in) {
;     ...
;         for (int t = 0; t < nt; t += 2) {
;             const bool last = (t == nt - 2);
;             const char* a1 = cA + (size_t)(t + 1) * kstep;
;             const char* a2 = last ? nA : cA + (size_t)(t + 2) * kstep; const char* b2 = last ? nB : cB + (size_t)(t + 2) * kstep;
;             const char* a3 = a2 + kstep; const char* b3 = b2 + kstep;
;             if (last && has_next) S.a_ready(nxt);
;             if constexpr (SP2) {
;             PG8_LDB(B0, 0, 0); PG8_LDB(B1, 0, 1); PG8_SCHED; PG8_LDA(At, 0, 0); PG8_STAGE(PG8_SA(1, 1), a1 + hstep, voffA);
;             PG8_WAIT_V(8); PG8_WAIT_L(0); PG8_BAR; PG8_MMA(0, 0, At, B0); PG8_MMA(0, 1, At, B1); PG8_BAR; PG8_SCHED;
;             PG8_LDA(At, 0, 1); PG8_STAGE(PG8_SB(0, 0), b2, voffB); PG8_STAGE(PG8_SB(0, 1), b2 + hstep, voffB); PG8_STAGE(PG8_SA(0, 0), a2, voffA);
;             PG8_WAIT_V(8); PG8_WAIT_L(0); PG8_BAR; PG8_MMA(1, 0, At, B0); PG8_MMA(1, 1, At, B1); PG8_BAR; PG8_SCHED;
.LBB0_1242:
	ds_read_b128 v[0:3], v193
	ds_read_b128 v[4:7], v193 offset:1024
	ds_read_b128 v[136:139], v193 offset:2048
	ds_read_b128 v[140:143], v193 offset:3072
	ds_read_b128 v[144:147], v194
	ds_read_b128 v[148:151], v194 offset:1024
	ds_read_b128 v[152:155], v194 offset:2048
	ds_read_b128 v[156:159], v194 offset:3072
	s_add_u32 s48, s46, 0xfffc0080
	s_addc_u32 s49, s47, -1
	s_cmp_eq_u32 s67, 12
	s_cselect_b32 s51, s29, s49
	s_cselect_b32 s50, s42, s48
	s_cselect_b32 s49, s27, s66
	s_cselect_b32 s48, s43, s45
	v_lshl_add_u64 v[188:189], s[46:47], 0, v[168:169]
	s_add_i32 m0, s74, 0xc000
	ds_read_b128 v[176:179], v195
	ds_read_b128 v[180:183], v195 offset:1024
	ds_read_b128 v[184:187], v195 offset:2048
	ds_read_b128 v[198:201], v195 offset:3072
	ds_read_b128 v[202:205], v195 offset:4096
	ds_read_b128 v[206:209], v195 offset:5120
	ds_read_b128 v[210:213], v195 offset:6144
	ds_read_b128 v[214:217], v195 offset:7168
	global_load_lds_dwordx4 v[188:189], off
	v_lshl_add_u64 v[188:189], s[46:47], 0, v[170:171]
	s_add_i32 m0, s74, 0xe000
	s_nop 0
	global_load_lds_dwordx4 v[188:189], off
	s_waitcnt vmcnt(8)
	s_waitcnt lgkmcnt(0)
	s_barrier
	v_mfma_f32_16x16x32_f16 v[132:135], v[0:3], v[176:179], v[132:135]
	v_mfma_f32_16x16x32_f16 v[128:131], v[136:139], v[176:179], v[128:131]
	v_mfma_f32_16x16x32_f16 v[116:119], v[0:3], v[184:187], v[116:119]
	v_mfma_f32_16x16x32_f16 v[112:115], v[136:139], v[184:187], v[112:115]
	v_mfma_f32_16x16x32_f16 v[100:103], v[0:3], v[202:205], v[100:103]
	v_mfma_f32_16x16x32_f16 v[96:99], v[136:139], v[202:205], v[96:99]
	v_mfma_f32_16x16x32_f16 v[84:87], v[0:3], v[210:213], v[84:87]
	v_mfma_f32_16x16x32_f16 v[80:83], v[136:139], v[210:213], v[80:83]
	v_mfma_f32_16x16x32_f16 v[132:135], v[4:7], v[180:183], v[132:135]
	v_mfma_f32_16x16x32_f16 v[128:131], v[140:143], v[180:183], v[128:131]
	v_mfma_f32_16x16x32_f16 v[116:119], v[4:7], v[198:201], v[116:119]
	v_mfma_f32_16x16x32_f16 v[112:115], v[140:143], v[198:201], v[112:115]
	v_mfma_f32_16x16x32_f16 v[100:103], v[4:7], v[206:209], v[100:103]
	v_mfma_f32_16x16x32_f16 v[96:99], v[140:143], v[206:209], v[96:99]
	v_mfma_f32_16x16x32_f16 v[84:87], v[4:7], v[214:217], v[84:87]
	v_mfma_f32_16x16x32_f16 v[80:83], v[140:143], v[214:217], v[80:83]
	v_mfma_f32_16x16x32_f16 v[124:127], v[144:147], v[176:179], v[124:127]
	v_mfma_f32_16x16x32_f16 v[120:123], v[152:155], v[176:179], v[120:123]
	v_mfma_f32_16x16x32_f16 v[108:111], v[144:147], v[184:187], v[108:111]
	v_mfma_f32_16x16x32_f16 v[104:107], v[152:155], v[184:187], v[104:107]
	v_mfma_f32_16x16x32_f16 v[92:95], v[144:147], v[202:205], v[92:95]
	v_mfma_f32_16x16x32_f16 v[88:91], v[152:155], v[202:205], v[88:91]
	v_mfma_f32_16x16x32_f16 v[76:79], v[144:147], v[210:213], v[76:79]
	v_mfma_f32_16x16x32_f16 v[72:75], v[152:155], v[210:213], v[72:75]
	v_mfma_f32_16x16x32_f16 v[124:127], v[148:151], v[180:183], v[124:127]
	v_mfma_f32_16x16x32_f16 v[120:123], v[156:159], v[180:183], v[120:123]
	v_mfma_f32_16x16x32_f16 v[108:111], v[148:151], v[198:201], v[108:111]
	v_mfma_f32_16x16x32_f16 v[104:107], v[156:159], v[198:201], v[104:107]
	v_mfma_f32_16x16x32_f16 v[92:95], v[148:151], v[206:209], v[92:95]
	v_mfma_f32_16x16x32_f16 v[88:91], v[156:159], v[206:209], v[88:91]
	v_mfma_f32_16x16x32_f16 v[76:79], v[148:151], v[214:217], v[76:79]
	v_mfma_f32_16x16x32_f16 v[72:75], v[156:159], v[214:217], v[72:75]
	s_barrier
	s_add_i32 s76, s63, s68
	v_lshl_add_u64 v[188:189], s[48:49], 0, v[162:163]
	s_mov_b32 m0, s76
	ds_read_b128 v[176:179], v195 offset:16384
	ds_read_b128 v[180:183], v195 offset:17408
	ds_read_b128 v[184:187], v195 offset:18432
	ds_read_b128 v[198:201], v195 offset:19456
	ds_read_b128 v[202:205], v195 offset:20480
	ds_read_b128 v[206:209], v195 offset:21504
	ds_read_b128 v[210:213], v195 offset:22528
	ds_read_b128 v[214:217], v195 offset:23552
	global_load_lds_dwordx4 v[188:189], off
	s_add_i32 m0, s76, 0x2000
	s_add_u32 s90, s48, 0x40000
	v_lshl_add_u64 v[218:219], s[48:49], 0, v[166:167]
	s_addc_u32 s91, s49, 0
	s_add_i32 s76, s64, s68
	global_load_lds_dwordx4 v[218:219], off
	v_lshl_add_u64 v[220:221], s[90:91], 0, v[162:163]
	s_mov_b32 m0, s76
	v_lshl_add_u64 v[222:223], s[50:51], 0, v[164:165]
	global_load_lds_dwordx4 v[220:221], off
	v_lshl_add_u64 v[220:221], s[90:91], 0, v[166:167]
	s_add_i32 m0, s76, 0x2000
	s_nop 0
	global_load_lds_dwordx4 v[220:221], off
	v_lshl_add_u64 v[220:221], s[50:51], 0, v[160:161]
	s_mov_b32 m0, s74
	s_nop 0
	global_load_lds_dwordx4 v[220:221], off
	s_mov_b32 m0, s37
	s_nop 0
	global_load_lds_dwordx4 v[222:223], off
	s_waitcnt vmcnt(8)
	s_waitcnt lgkmcnt(0)
	s_barrier
; #define PG8_STAGE(bufoff, gbase, voff) do { _Pragma("unroll") for (int _i = 0; _i < 2; ++_i) \
;         __builtin_amdgcn_global_load_lds((const unsigned*)((const char*)(gbase) + (voff)[_i]), (PG8_LAS unsigned*)(lds + (bufoff) + ldsw + _i * 8192), 16, 0, 0); } while (0)
; #define PG8_LDA(dst, b, h) do { _Pragma("unroll") for (int m = 0; m < 4; ++m) _Pragma("unroll") for (int k = 0; k < 2; ++k) dst[m][k] = *(const PG8_LAS bf16x8*)(lds + PG8_SA(b, h) + aoff + m * 2048 + k * 1024); } while (0)
; #define PG8_LDB(dst, b, h) do { _Pragma("unroll") for (int n = 0; n < 2; ++n) _Pragma("unroll") for (int k = 0; k < 2; ++k) dst[n][k] = *(const PG8_LAS bf16x8*)(lds + PG8_SB(b, h) + boff + n * 2048 + k * 1024); } while (0)
; #define PG8_MMA(ai, bj, At, Bt) do { __builtin_amdgcn_s_setprio(1); _Pragma("unroll") for (int m = 0; m < 4; ++m) _Pragma("unroll") for (int n = 0; n < 2; ++n) _Pragma("unroll") for (int k = 0; k < 2; ++k) \
;         acc[ai][bj][m][n] = mma16<F16>(Bt[n][k], At[m][k], acc[ai][bj][m][n]); __builtin_amdgcn_s_setprio(0); } while (0)
; #define PG8_WAIT_V(n) asm volatile("s_waitcnt vmcnt(" #n ")" ::: "memory")
; #define PG8_WAIT_L(n) asm volatile("s_waitcnt lgkmcnt(" #n ")" ::: "memory")
; #define PG8_BAR __builtin_amdgcn_s_barrier()
; #define PG8_SCHED __builtin_amdgcn_sched_barrier(0)
; template <class Epi, class Sched, bool ALIGN_EPI = false, bool SP2 = false, bool F16 = false>
; __device__ __forceinline__ void gemm_phase(PG8_LAS unsigned char* lds, const Gemm g, const Sched& S, const Epi& E, const int wid_in) {
;     ...
;             PG8_WAIT_V(8); PG8_WAIT_L(0); PG8_BAR; PG8_MMA(1, 0, At, B0); PG8_MMA(1, 1, At, B1); PG8_BAR; PG8_SCHED;
;             PG8_LDB(B0, 1, 0); PG8_LDB(B1, 1, 1); PG8_SCHED; PG8_LDA(At, 1, 0); PG8_STAGE(PG8_SA(0, 1), a2 + hstep, voffA);
;             PG8_WAIT_V(8); PG8_WAIT_L(0); PG8_BAR; PG8_MMA(0, 0, At, B0); PG8_MMA(0, 1, At, B1); PG8_BAR; PG8_SCHED;
	v_mfma_f32_16x16x32_f16 v[68:71], v[0:3], v[176:179], v[68:71]
	v_mfma_f32_16x16x32_f16 v[64:67], v[136:139], v[176:179], v[64:67]
	v_mfma_f32_16x16x32_f16 v[52:55], v[0:3], v[184:187], v[52:55]
	v_mfma_f32_16x16x32_f16 v[48:51], v[136:139], v[184:187], v[48:51]
	v_mfma_f32_16x16x32_f16 v[36:39], v[0:3], v[202:205], v[36:39]
	v_mfma_f32_16x16x32_f16 v[32:35], v[136:139], v[202:205], v[32:35]
	v_mfma_f32_16x16x32_f16 v[0:3], v[0:3], v[210:213], v[20:23]
	v_mfma_f32_16x16x32_f16 v[68:71], v[4:7], v[180:183], v[68:71]
	v_mfma_f32_16x16x32_f16 v[64:67], v[140:143], v[180:183], v[64:67]
	v_mfma_f32_16x16x32_f16 v[52:55], v[4:7], v[198:201], v[52:55]
	v_mfma_f32_16x16x32_f16 v[48:51], v[140:143], v[198:201], v[48:51]
	v_mfma_f32_16x16x32_f16 v[36:39], v[4:7], v[206:209], v[36:39]
	v_mfma_f32_16x16x32_f16 v[32:35], v[140:143], v[206:209], v[32:35]
	v_mfma_f32_16x16x32_f16 v[0:3], v[4:7], v[214:217], v[0:3]
	v_mfma_f32_16x16x32_f16 v[4:7], v[136:139], v[210:213], v[16:19]
	v_mfma_f32_16x16x32_f16 v[4:7], v[140:143], v[214:217], v[4:7]
	v_mfma_f32_16x16x32_f16 v[16:19], v[144:147], v[176:179], v[60:63]
	v_mfma_f32_16x16x32_f16 v[60:63], v[148:151], v[180:183], v[16:19]
	v_mfma_f32_16x16x32_f16 v[16:19], v[152:155], v[176:179], v[56:59]
	v_mfma_f32_16x16x32_f16 v[56:59], v[156:159], v[180:183], v[16:19]
	v_mfma_f32_16x16x32_f16 v[16:19], v[144:147], v[184:187], v[44:47]
	v_mfma_f32_16x16x32_f16 v[44:47], v[148:151], v[198:201], v[16:19]
	v_mfma_f32_16x16x32_f16 v[16:19], v[152:155], v[184:187], v[40:43]
	v_mfma_f32_16x16x32_f16 v[40:43], v[156:159], v[198:201], v[16:19]
	v_mfma_f32_16x16x32_f16 v[16:19], v[144:147], v[202:205], v[28:31]
	v_mfma_f32_16x16x32_f16 v[28:31], v[148:151], v[206:209], v[16:19]
	v_mfma_f32_16x16x32_f16 v[16:19], v[152:155], v[202:205], v[24:27]
	v_mfma_f32_16x16x32_f16 v[12:15], v[144:147], v[210:213], v[12:15]
	v_mfma_f32_16x16x32_f16 v[8:11], v[152:155], v[210:213], v[8:11]
	v_mfma_f32_16x16x32_f16 v[24:27], v[156:159], v[206:209], v[16:19]
	v_mfma_f32_16x16x32_f16 v[12:15], v[148:151], v[214:217], v[12:15]
	v_mfma_f32_16x16x32_f16 v[8:11], v[156:159], v[214:217], v[8:11]
	s_barrier
	s_add_i32 s76, 0, 0x18000
	s_add_i32 s83, 0, 0x1c000
	v_add_u32_e32 v140, s76, v192
	v_add_u32_e32 v156, s83, v192
	ds_read_b128 v[16:19], v140
	ds_read_b128 v[20:23], v140 offset:1024
	ds_read_b128 v[136:139], v140 offset:2048
	ds_read_b128 v[140:143], v140 offset:3072
	ds_read_b128 v[144:147], v156
	ds_read_b128 v[148:151], v156 offset:1024
	ds_read_b128 v[152:155], v156 offset:2048
	ds_read_b128 v[156:159], v156 offset:3072
	s_add_u32 s50, s50, 0x40000
	s_addc_u32 s51, s51, 0
	s_mov_b32 m0, s53
	v_lshl_add_u64 v[224:225], s[50:51], 0, v[160:161]
	ds_read_b128 v[176:179], v195 offset:32768
	ds_read_b128 v[180:183], v195 offset:33792
	ds_read_b128 v[184:187], v195 offset:34816
	ds_read_b128 v[198:201], v195 offset:35840
	ds_read_b128 v[202:205], v195 offset:36864
	ds_read_b128 v[206:209], v195 offset:37888
	ds_read_b128 v[210:213], v195 offset:38912
	ds_read_b128 v[214:217], v195 offset:39936
	global_load_lds_dwordx4 v[224:225], off
	v_lshl_add_u64 v[224:225], s[50:51], 0, v[164:165]
	s_mov_b32 m0, s54
	s_nop 0
	global_load_lds_dwordx4 v[224:225], off
	s_waitcnt vmcnt(8)
	s_waitcnt lgkmcnt(0)
	s_barrier
	v_mfma_f32_16x16x32_f16 v[132:135], v[16:19], v[176:179], v[132:135]
	v_mfma_f32_16x16x32_f16 v[128:131], v[136:139], v[176:179], v[128:131]
	v_mfma_f32_16x16x32_f16 v[116:119], v[16:19], v[184:187], v[116:119]
	v_mfma_f32_16x16x32_f16 v[112:115], v[136:139], v[184:187], v[112:115]
	v_mfma_f32_16x16x32_f16 v[100:103], v[16:19], v[202:205], v[100:103]
	v_mfma_f32_16x16x32_f16 v[96:99], v[136:139], v[202:205], v[96:99]
	v_mfma_f32_16x16x32_f16 v[84:87], v[16:19], v[210:213], v[84:87]
	v_mfma_f32_16x16x32_f16 v[80:83], v[136:139], v[210:213], v[80:83]
	v_mfma_f32_16x16x32_f16 v[132:135], v[20:23], v[180:183], v[132:135]
	v_mfma_f32_16x16x32_f16 v[128:131], v[140:143], v[180:183], v[128:131]
	v_mfma_f32_16x16x32_f16 v[116:119], v[20:23], v[198:201], v[116:119]
	v_mfma_f32_16x16x32_f16 v[112:115], v[140:143], v[198:201], v[112:115]
	v_mfma_f32_16x16x32_f16 v[100:103], v[20:23], v[206:209], v[100:103]
	v_mfma_f32_16x16x32_f16 v[96:99], v[140:143], v[206:209], v[96:99]
	v_mfma_f32_16x16x32_f16 v[84:87], v[20:23], v[214:217], v[84:87]
	v_mfma_f32_16x16x32_f16 v[80:83], v[140:143], v[214:217], v[80:83]
	v_mfma_f32_16x16x32_f16 v[124:127], v[144:147], v[176:179], v[124:127]
	v_mfma_f32_16x16x32_f16 v[120:123], v[152:155], v[176:179], v[120:123]
	v_mfma_f32_16x16x32_f16 v[108:111], v[144:147], v[184:187], v[108:111]
	v_mfma_f32_16x16x32_f16 v[104:107], v[152:155], v[184:187], v[104:107]
	v_mfma_f32_16x16x32_f16 v[92:95], v[144:147], v[202:205], v[92:95]
	v_mfma_f32_16x16x32_f16 v[88:91], v[152:155], v[202:205], v[88:91]
	v_mfma_f32_16x16x32_f16 v[76:79], v[144:147], v[210:213], v[76:79]
	v_mfma_f32_16x16x32_f16 v[72:75], v[152:155], v[210:213], v[72:75]
	v_mfma_f32_16x16x32_f16 v[124:127], v[148:151], v[180:183], v[124:127]
	v_mfma_f32_16x16x32_f16 v[120:123], v[156:159], v[180:183], v[120:123]
	v_mfma_f32_16x16x32_f16 v[108:111], v[148:151], v[198:201], v[108:111]
	v_mfma_f32_16x16x32_f16 v[104:107], v[156:159], v[198:201], v[104:107]
	v_mfma_f32_16x16x32_f16 v[92:95], v[148:151], v[206:209], v[92:95]
	v_mfma_f32_16x16x32_f16 v[88:91], v[156:159], v[206:209], v[88:91]
	v_mfma_f32_16x16x32_f16 v[76:79], v[148:151], v[214:217], v[76:79]
	v_mfma_f32_16x16x32_f16 v[72:75], v[156:159], v[214:217], v[72:75]
	s_barrier
; #define PG8_STAGE(bufoff, gbase, voff) do { _Pragma("unroll") for (int _i = 0; _i < 2; ++_i) \
;         __builtin_amdgcn_global_load_lds((const unsigned*)((const char*)(gbase) + (voff)[_i]), (PG8_LAS unsigned*)(lds + (bufoff) + ldsw + _i * 8192), 16, 0, 0); } while (0)
; #define PG8_LDA(dst, b, h) do { _Pragma("unroll") for (int m = 0; m < 4; ++m) _Pragma("unroll") for (int k = 0; k < 2; ++k) dst[m][k] = *(const PG8_LAS bf16x8*)(lds + PG8_SA(b, h) + aoff + m * 2048 + k * 1024); } while (0)
; #define PG8_MMA(ai, bj, At, Bt) do { __builtin_amdgcn_s_setprio(1); _Pragma("unroll") for (int m = 0; m < 4; ++m) _Pragma("unroll") for (int n = 0; n < 2; ++n) _Pragma("unroll") for (int k = 0; k < 2; ++k) \
;         acc[ai][bj][m][n] = mma16<F16>(Bt[n][k], At[m][k], acc[ai][bj][m][n]); __builtin_amdgcn_s_setprio(0); } while (0)
; #define PG8_WAIT_V(n) asm volatile("s_waitcnt vmcnt(" #n ")" ::: "memory")
; #define PG8_WAIT_L(n) asm volatile("s_waitcnt lgkmcnt(" #n ")" ::: "memory")
; #define PG8_BAR __builtin_amdgcn_s_barrier()
; #define PG8_SCHED __builtin_amdgcn_sched_barrier(0)
; template <class Epi, class Sched, bool ALIGN_EPI = false, bool SP2 = false, bool F16 = false>
; __device__ __forceinline__ void gemm_phase(PG8_LAS unsigned char* lds, const Gemm g, const Sched& S, const Epi& E, const int wid_in) {
;     ...
;         for (int t = 0; t < nt; t += 2) {
;     ...
;             PG8_LDA(At, 1, 1); PG8_STAGE(PG8_SB(1, 0), b3, voffB); PG8_STAGE(PG8_SB(1, 1), b3 + hstep, voffB); PG8_STAGE(PG8_SA(1, 0), a3, voffA);
;             PG8_WAIT_V(8); PG8_WAIT_L(0); PG8_BAR; PG8_MMA(1, 0, At, B0); PG8_MMA(1, 1, At, B1); PG8_BAR; PG8_SCHED;
;     ...
;         if constexpr (ALIGN_EPI) { if (wr == 0) PG8_BAR; }
	s_add_i32 s50, s76, s68
	v_lshl_add_u64 v[188:189], v[188:189], 0, s[24:25]
	s_mov_b32 m0, s50
	ds_read_b128 v[176:179], v195 offset:49152
	ds_read_b128 v[180:183], v195 offset:50176
	ds_read_b128 v[184:187], v195 offset:51200
	ds_read_b128 v[198:201], v195 offset:52224
	ds_read_b128 v[202:205], v195 offset:53248
	ds_read_b128 v[206:209], v195 offset:54272
	ds_read_b128 v[210:213], v195 offset:55296
	ds_read_b128 v[214:217], v195 offset:56320
	global_load_lds_dwordx4 v[188:189], off
	s_add_i32 m0, s50, 0x2000
	s_add_u32 s48, s48, 0x40080
	v_lshl_add_u64 v[188:189], v[218:219], 0, s[24:25]
	s_addc_u32 s49, s49, 0
	s_add_i32 s50, s83, s68
	global_load_lds_dwordx4 v[188:189], off
	v_lshl_add_u64 v[188:189], s[48:49], 0, v[162:163]
	s_mov_b32 m0, s50
	s_nop 0
	global_load_lds_dwordx4 v[188:189], off
	v_lshl_add_u64 v[188:189], s[48:49], 0, v[166:167]
	s_add_i32 m0, s50, 0x2000
	s_nop 0
	global_load_lds_dwordx4 v[188:189], off
	v_lshl_add_u64 v[188:189], v[220:221], 0, s[24:25]
	s_mov_b32 m0, s75
	s_nop 0
	global_load_lds_dwordx4 v[188:189], off
	v_lshl_add_u64 v[188:189], v[222:223], 0, s[24:25]
	s_mov_b32 m0, s57
	s_nop 0
	global_load_lds_dwordx4 v[188:189], off
	s_waitcnt vmcnt(8)
	s_waitcnt lgkmcnt(0)
	s_barrier
	v_mfma_f32_16x16x32_f16 v[68:71], v[16:19], v[176:179], v[68:71]
	v_mfma_f32_16x16x32_f16 v[52:55], v[16:19], v[184:187], v[52:55]
	v_mfma_f32_16x16x32_f16 v[36:39], v[16:19], v[202:205], v[36:39]
	v_mfma_f32_16x16x32_f16 v[0:3], v[16:19], v[210:213], v[0:3]
	v_mfma_f32_16x16x32_f16 v[68:71], v[20:23], v[180:183], v[68:71]
	v_mfma_f32_16x16x32_f16 v[64:67], v[136:139], v[176:179], v[64:67]
	v_mfma_f32_16x16x32_f16 v[52:55], v[20:23], v[198:201], v[52:55]
	v_mfma_f32_16x16x32_f16 v[48:51], v[136:139], v[184:187], v[48:51]
	v_mfma_f32_16x16x32_f16 v[36:39], v[20:23], v[206:209], v[36:39]
	v_mfma_f32_16x16x32_f16 v[32:35], v[136:139], v[202:205], v[32:35]
	v_mfma_f32_16x16x32_f16 v[20:23], v[20:23], v[214:217], v[0:3]
	v_mfma_f32_16x16x32_f16 v[0:3], v[136:139], v[210:213], v[4:7]
	v_mfma_f32_16x16x32_f16 v[64:67], v[140:143], v[180:183], v[64:67]
	v_mfma_f32_16x16x32_f16 v[48:51], v[140:143], v[198:201], v[48:51]
	v_mfma_f32_16x16x32_f16 v[32:35], v[140:143], v[206:209], v[32:35]
	v_mfma_f32_16x16x32_f16 v[16:19], v[140:143], v[214:217], v[0:3]
	v_mfma_f32_16x16x32_f16 v[0:3], v[144:147], v[176:179], v[60:63]
	v_mfma_f32_16x16x32_f16 v[60:63], v[148:151], v[180:183], v[0:3]
	v_mfma_f32_16x16x32_f16 v[0:3], v[152:155], v[176:179], v[56:59]
	v_mfma_f32_16x16x32_f16 v[56:59], v[156:159], v[180:183], v[0:3]
	v_mfma_f32_16x16x32_f16 v[0:3], v[144:147], v[184:187], v[44:47]
	v_mfma_f32_16x16x32_f16 v[44:47], v[148:151], v[198:201], v[0:3]
	v_mfma_f32_16x16x32_f16 v[0:3], v[152:155], v[184:187], v[40:43]
	v_mfma_f32_16x16x32_f16 v[40:43], v[156:159], v[198:201], v[0:3]
	v_mfma_f32_16x16x32_f16 v[0:3], v[144:147], v[202:205], v[28:31]
	v_mfma_f32_16x16x32_f16 v[28:31], v[148:151], v[206:209], v[0:3]
	v_mfma_f32_16x16x32_f16 v[0:3], v[152:155], v[202:205], v[24:27]
	v_mfma_f32_16x16x32_f16 v[24:27], v[156:159], v[206:209], v[0:3]
	v_mfma_f32_16x16x32_f16 v[0:3], v[144:147], v[210:213], v[12:15]
	v_mfma_f32_16x16x32_f16 v[12:15], v[148:151], v[214:217], v[0:3]
	v_mfma_f32_16x16x32_f16 v[0:3], v[152:155], v[210:213], v[8:11]
	v_mfma_f32_16x16x32_f16 v[8:11], v[156:159], v[214:217], v[0:3]
	s_barrier
	s_add_i32 s67, s67, 2
	s_add_u32 s46, s46, 0x100
	s_addc_u32 s47, s47, 0
	s_add_u32 s45, s45, 0x100
	s_addc_u32 s66, s66, 0
	s_cmp_gt_u32 s67, 13
	s_cbranch_scc0 .LBB0_1242
	s_and_b64 vcc, exec, s[16:17]
	s_cbranch_vccz .LBB0_1245
	s_barrier

; #define PG8_STAGE(bufoff, gbase, voff) do { _Pragma("unroll") for (int _i = 0; _i < 2; ++_i) \
;         __builtin_amdgcn_global_load_lds((const unsigned*)((const char*)(gbase) + (voff)[_i]), (PG8_LAS unsigned*)(lds + (bufoff) + ldsw + _i * 8192), 16, 0, 0); } while (0)
; #define PG8_LDA(dst, b, h) do { _Pragma("unroll") for (int m = 0; m < 4; ++m) _Pragma("unroll") for (int k = 0; k < 2; ++k) dst[m][k] = *(const PG8_LAS bf16x8*)(lds + PG8_SA(b, h) + aoff + m * 2048 + k * 1024); } while (0)
; #define PG8_LDB(dst, b, h) do { _Pragma("unroll") for (int n = 0; n < 2; ++n) _Pragma("unroll") for (int k = 0; k < 2; ++k) dst[n][k] = *(const PG8_LAS bf16x8*)(lds + PG8_SB(b, h) + boff + n * 2048 + k * 1024); } while (0)
; #define PG8_MMA(ai, bj, At, Bt) do { __builtin_amdgcn_s_setprio(1); _Pragma("unroll") for (int m = 0; m < 4; ++m) _Pragma("unroll") for (int n = 0; n < 2; ++n) _Pragma("unroll") for (int k = 0; k < 2; ++k) \
;         acc[ai][bj][m][n] = mma16<F16>(Bt[n][k], At[m][k], acc[ai][bj][m][n]); __builtin_amdgcn_s_setprio(0); } while (0)
; #define PG8_WAIT_V(n) asm volatile("s_waitcnt vmcnt(" #n ")" ::: "memory")
; #define PG8_WAIT_L(n) asm volatile("s_waitcnt lgkmcnt(" #n ")" ::: "memory")
; #define PG8_BAR __builtin_amdgcn_s_barrier()
; template <class Epi, class Sched, bool ALIGN_EPI = false, bool SP2 = false, bool F16 = false>
; __device__ __forceinline__ void gemm_phase(PG8_LAS unsigned char* lds, const Gemm g, const Sched& S, const Epi& E, const int wid_in) {
;     ...
;         const bool has_next = S.next(ui + 1, nxt);
;         const char* nA = has_next ? (const char*)g.A + (size_t)nxt.pm * tstep : cA; const char* nB = has_next ? (const char*)g.Bt + (size_t)nxt.pn * tstep : cB;
;         for (int t = 0; t < nt; t += 2) {
;             const bool last = (t == nt - 2);
;             const char* a1 = cA + (size_t)(t + 1) * kstep;
;             const char* a2 = last ? nA : cA + (size_t)(t + 2) * kstep; const char* b2 = last ? nB : cB + (size_t)(t + 2) * kstep;
;             const char* a3 = a2 + kstep; const char* b3 = b2 + kstep;
;             if (last && has_next) S.a_ready(nxt);
;             if constexpr (SP2) {
;             PG8_LDB(B0, 0, 0); PG8_LDB(B1, 0, 1); PG8_SCHED; PG8_LDA(At, 0, 0); PG8_STAGE(PG8_SA(1, 1), a1 + hstep, voffA);
;             PG8_WAIT_V(8); PG8_WAIT_L(0); PG8_BAR; PG8_MMA(0, 0, At, B0); PG8_MMA(0, 1, At, B1); PG8_BAR; PG8_SCHED;
.LBB0_1277:
	s_mov_b64 s[48:49], s[10:11]
	s_add_i32 s10, s36, s19
	s_mov_b64 s[46:47], s[12:13]
	s_mov_b32 s12, s62
	s_mov_b32 s13, s61
	s_and_b32 s61, s10, 3
	s_ashr_i32 s62, s10, 2
	s_and_b64 s[10:11], s[30:31], exec
	s_cselect_b32 s12, s62, s12
	ds_read_b128 v[0:3], v134
	ds_read_b128 v[4:7], v134 offset:1024
	ds_read_b128 v[8:11], v134 offset:2048
	ds_read_b128 v[12:15], v134 offset:3072
	ds_read_b128 v[16:19], v135
	ds_read_b128 v[20:23], v135 offset:1024
	ds_read_b128 v[24:27], v135 offset:2048
	ds_read_b128 v[28:31], v135 offset:3072
	s_cselect_b32 s10, s61, s13
	s_ashr_i32 s13, s12, 31
	s_lshl_b64 s[12:13], s[12:13], 17
	s_add_u32 s12, s21, s12
	s_addc_u32 s13, s40, s13
	s_and_b64 s[36:37], s[30:31], exec
	s_cselect_b32 s45, s13, s47
	s_cselect_b32 s44, s12, s46
	s_ashr_i32 s11, s10, 31
	s_lshl_b64 s[10:11], s[10:11], 17
	s_add_u32 s10, s41, s10
	s_addc_u32 s11, s42, s11
	s_and_b64 s[36:37], s[30:31], exec
	s_cselect_b32 s37, s11, s49
	s_cselect_b32 s36, s10, s48
	s_add_u32 s64, s46, 0x10080
	s_addc_u32 s65, s47, 0
	s_mov_b32 m0, s15
	v_lshl_add_u64 v[64:65], s[64:65], 0, v[130:131]
	ds_read_b128 v[32:35], v136
	ds_read_b128 v[36:39], v136 offset:1024
	ds_read_b128 v[40:43], v136 offset:2048
	ds_read_b128 v[44:47], v136 offset:3072
	ds_read_b128 v[48:51], v136 offset:4096
	ds_read_b128 v[52:55], v136 offset:5120
	ds_read_b128 v[56:59], v136 offset:6144
	ds_read_b128 v[60:63], v136 offset:7168
	global_load_lds_dwordx4 v[64:65], off
	v_lshl_add_u64 v[64:65], s[64:65], 0, v[128:129]
	s_mov_b32 m0, s52
	s_nop 0
	global_load_lds_dwordx4 v[64:65], off
	s_waitcnt vmcnt(8)
	s_waitcnt lgkmcnt(0)
	s_barrier
	v_mfma_f32_16x16x32_bf16 v[64:67], v[0:3], v[32:35], 0
	v_mfma_f32_16x16x32_bf16 v[68:71], v[8:11], v[32:35], 0
	v_mfma_f32_16x16x32_bf16 v[72:75], v[0:3], v[40:43], 0
	v_mfma_f32_16x16x32_bf16 v[76:79], v[8:11], v[40:43], 0
	v_mfma_f32_16x16x32_bf16 v[80:83], v[0:3], v[48:51], 0
	v_mfma_f32_16x16x32_bf16 v[84:87], v[8:11], v[48:51], 0
	v_mfma_f32_16x16x32_bf16 v[88:91], v[0:3], v[56:59], 0
	v_mfma_f32_16x16x32_bf16 v[92:95], v[8:11], v[56:59], 0
	v_mfma_f32_16x16x32_bf16 v[64:67], v[4:7], v[36:39], v[64:67]
	v_mfma_f32_16x16x32_bf16 v[68:71], v[12:15], v[36:39], v[68:71]
	v_mfma_f32_16x16x32_bf16 v[72:75], v[4:7], v[44:47], v[72:75]
	v_mfma_f32_16x16x32_bf16 v[76:79], v[12:15], v[44:47], v[76:79]
	v_mfma_f32_16x16x32_bf16 v[80:83], v[4:7], v[52:55], v[80:83]
	v_mfma_f32_16x16x32_bf16 v[84:87], v[12:15], v[52:55], v[84:87]
	v_mfma_f32_16x16x32_bf16 v[88:91], v[4:7], v[60:63], v[88:91]
	v_mfma_f32_16x16x32_bf16 v[92:95], v[12:15], v[60:63], v[92:95]
	v_mfma_f32_16x16x32_bf16 v[96:99], v[16:19], v[32:35], 0
	v_mfma_f32_16x16x32_bf16 v[32:35], v[24:27], v[32:35], 0
	v_mfma_f32_16x16x32_bf16 v[96:99], v[20:23], v[36:39], v[96:99]
	v_mfma_f32_16x16x32_bf16 v[32:35], v[28:31], v[36:39], v[32:35]
	v_mfma_f32_16x16x32_bf16 v[36:39], v[16:19], v[40:43], 0
	v_mfma_f32_16x16x32_bf16 v[40:43], v[24:27], v[40:43], 0
	v_mfma_f32_16x16x32_bf16 v[36:39], v[20:23], v[44:47], v[36:39]
	v_mfma_f32_16x16x32_bf16 v[40:43], v[28:31], v[44:47], v[40:43]
	v_mfma_f32_16x16x32_bf16 v[44:47], v[16:19], v[48:51], 0
	v_mfma_f32_16x16x32_bf16 v[48:51], v[24:27], v[48:51], 0
	v_mfma_f32_16x16x32_bf16 v[44:47], v[20:23], v[52:55], v[44:47]
	v_mfma_f32_16x16x32_bf16 v[48:51], v[28:31], v[52:55], v[48:51]
	v_mfma_f32_16x16x32_bf16 v[52:55], v[16:19], v[56:59], 0
	v_mfma_f32_16x16x32_bf16 v[56:59], v[24:27], v[56:59], 0
	v_mfma_f32_16x16x32_bf16 v[52:55], v[20:23], v[60:63], v[52:55]
	v_mfma_f32_16x16x32_bf16 v[56:59], v[28:31], v[60:63], v[56:59]
	s_barrier
	v_lshl_add_u64 v[204:205], s[48:49], 0, v[130:131]
	s_mov_b32 m0, s53
	v_lshl_add_u64 v[140:141], v[204:205], 0, s[26:27]
	v_lshl_add_u64 v[206:207], s[48:49], 0, v[128:129]
	s_add_u32 s64, s48, 0x10100
	ds_read_b128 v[60:63], v136 offset:16384
	ds_read_b128 v[100:103], v136 offset:17408
	ds_read_b128 v[104:107], v136 offset:18432
	ds_read_b128 v[108:111], v136 offset:19456
	ds_read_b128 v[112:115], v136 offset:20480
	ds_read_b128 v[116:119], v136 offset:21504
	ds_read_b128 v[120:123], v136 offset:22528
	ds_read_b128 v[124:127], v136 offset:23552
	global_load_lds_dwordx4 v[140:141], off
	v_lshl_add_u64 v[140:141], v[206:207], 0, s[26:27]
	s_mov_b32 m0, s54
	s_addc_u32 s65, s49, 0
	global_load_lds_dwordx4 v[140:141], off
	v_lshl_add_u64 v[140:141], s[64:65], 0, v[130:131]
	s_mov_b32 m0, s55
	v_lshl_add_u64 v[208:209], s[46:47], 0, v[130:131]
	global_load_lds_dwordx4 v[140:141], off
	v_lshl_add_u64 v[140:141], s[64:65], 0, v[128:129]
	s_mov_b32 m0, s56
	v_lshl_add_u64 v[210:211], s[46:47], 0, v[128:129]
	global_load_lds_dwordx4 v[140:141], off
	v_lshl_add_u64 v[140:141], v[208:209], 0, s[26:27]
	s_mov_b32 m0, s74
	s_nop 0
	global_load_lds_dwordx4 v[140:141], off
	v_lshl_add_u64 v[140:141], v[210:211], 0, s[26:27]
	s_mov_b32 m0, s43
	s_nop 0
	global_load_lds_dwordx4 v[140:141], off
	s_waitcnt vmcnt(8)
	s_waitcnt lgkmcnt(0)
	s_barrier
; #define PG8_STAGE(bufoff, gbase, voff) do { _Pragma("unroll") for (int _i = 0; _i < 2; ++_i) \
;         __builtin_amdgcn_global_load_lds((const unsigned*)((const char*)(gbase) + (voff)[_i]), (PG8_LAS unsigned*)(lds + (bufoff) + ldsw + _i * 8192), 16, 0, 0); } while (0)
; #define PG8_LDA(dst, b, h) do { _Pragma("unroll") for (int m = 0; m < 4; ++m) _Pragma("unroll") for (int k = 0; k < 2; ++k) dst[m][k] = *(const PG8_LAS bf16x8*)(lds + PG8_SA(b, h) + aoff + m * 2048 + k * 1024); } while (0)
; #define PG8_LDB(dst, b, h) do { _Pragma("unroll") for (int n = 0; n < 2; ++n) _Pragma("unroll") for (int k = 0; k < 2; ++k) dst[n][k] = *(const PG8_LAS bf16x8*)(lds + PG8_SB(b, h) + boff + n * 2048 + k * 1024); } while (0)
; #define PG8_MMA(ai, bj, At, Bt) do { __builtin_amdgcn_s_setprio(1); _Pragma("unroll") for (int m = 0; m < 4; ++m) _Pragma("unroll") for (int n = 0; n < 2; ++n) _Pragma("unroll") for (int k = 0; k < 2; ++k) \
;         acc[ai][bj][m][n] = mma16<F16>(Bt[n][k], At[m][k], acc[ai][bj][m][n]); __builtin_amdgcn_s_setprio(0); } while (0)
; #define PG8_WAIT_V(n) asm volatile("s_waitcnt vmcnt(" #n ")" ::: "memory")
; #define PG8_WAIT_L(n) asm volatile("s_waitcnt lgkmcnt(" #n ")" ::: "memory")
; #define PG8_BAR __builtin_amdgcn_s_barrier()
; #define PG8_SCHED __builtin_amdgcn_sched_barrier(0)
; template <class Epi, class Sched, bool ALIGN_EPI = false, bool SP2 = false, bool F16 = false>
; __device__ __forceinline__ void gemm_phase(PG8_LAS unsigned char* lds, const Gemm g, const Sched& S, const Epi& E, const int wid_in) {
;     ...
;             PG8_WAIT_V(8); PG8_WAIT_L(0); PG8_BAR; PG8_MMA(0, 0, At, B0); PG8_MMA(0, 1, At, B1); PG8_BAR; PG8_SCHED;
;             PG8_LDA(At, 0, 1); PG8_STAGE(PG8_SB(0, 0), b2, voffB); PG8_STAGE(PG8_SB(0, 1), b2 + hstep, voffB); PG8_STAGE(PG8_SA(0, 0), a2, voffA);
;             PG8_WAIT_V(8); PG8_WAIT_L(0); PG8_BAR; PG8_MMA(1, 0, At, B0); PG8_MMA(1, 1, At, B1); PG8_BAR; PG8_SCHED;
;             PG8_LDB(B0, 1, 0); PG8_LDB(B1, 1, 1); PG8_SCHED; PG8_LDA(At, 1, 0); PG8_STAGE(PG8_SA(0, 1), a2 + hstep, voffA);
;             PG8_WAIT_V(8); PG8_WAIT_L(0); PG8_BAR; PG8_MMA(0, 0, At, B0); PG8_MMA(0, 1, At, B1); PG8_BAR; PG8_SCHED;
	v_mfma_f32_16x16x32_bf16 v[140:143], v[0:3], v[60:63], 0
	v_mfma_f32_16x16x32_bf16 v[148:151], v[0:3], v[104:107], 0
	v_mfma_f32_16x16x32_bf16 v[156:159], v[0:3], v[112:115], 0
	v_mfma_f32_16x16x32_bf16 v[0:3], v[0:3], v[120:123], 0
	v_mfma_f32_16x16x32_bf16 v[140:143], v[4:7], v[100:103], v[140:143]
	v_mfma_f32_16x16x32_bf16 v[148:151], v[4:7], v[108:111], v[148:151]
	v_mfma_f32_16x16x32_bf16 v[156:159], v[4:7], v[116:119], v[156:159]
	v_mfma_f32_16x16x32_bf16 v[0:3], v[4:7], v[124:127], v[0:3]
	v_mfma_f32_16x16x32_bf16 v[4:7], v[8:11], v[120:123], 0
	v_mfma_f32_16x16x32_bf16 v[144:147], v[8:11], v[60:63], 0
	v_mfma_f32_16x16x32_bf16 v[152:155], v[8:11], v[104:107], 0
	v_mfma_f32_16x16x32_bf16 v[160:163], v[8:11], v[112:115], 0
	v_mfma_f32_16x16x32_bf16 v[4:7], v[12:15], v[124:127], v[4:7]
	v_mfma_f32_16x16x32_bf16 v[144:147], v[12:15], v[100:103], v[144:147]
	v_mfma_f32_16x16x32_bf16 v[152:155], v[12:15], v[108:111], v[152:155]
	v_mfma_f32_16x16x32_bf16 v[160:163], v[12:15], v[116:119], v[160:163]
	v_mfma_f32_16x16x32_bf16 v[8:11], v[16:19], v[60:63], 0
	v_mfma_f32_16x16x32_bf16 v[12:15], v[24:27], v[60:63], 0
	v_mfma_f32_16x16x32_bf16 v[8:11], v[20:23], v[100:103], v[8:11]
	v_mfma_f32_16x16x32_bf16 v[12:15], v[28:31], v[100:103], v[12:15]
	v_mfma_f32_16x16x32_bf16 v[60:63], v[16:19], v[104:107], 0
	v_mfma_f32_16x16x32_bf16 v[100:103], v[24:27], v[104:107], 0
	v_mfma_f32_16x16x32_bf16 v[104:107], v[16:19], v[112:115], 0
	v_mfma_f32_16x16x32_bf16 v[16:19], v[16:19], v[120:123], 0
	v_mfma_f32_16x16x32_bf16 v[60:63], v[20:23], v[108:111], v[60:63]
	v_mfma_f32_16x16x32_bf16 v[100:103], v[28:31], v[108:111], v[100:103]
	v_mfma_f32_16x16x32_bf16 v[104:107], v[20:23], v[116:119], v[104:107]
	v_mfma_f32_16x16x32_bf16 v[108:111], v[24:27], v[112:115], 0
	v_mfma_f32_16x16x32_bf16 v[16:19], v[20:23], v[124:127], v[16:19]
	v_mfma_f32_16x16x32_bf16 v[20:23], v[24:27], v[120:123], 0
	v_mfma_f32_16x16x32_bf16 v[108:111], v[28:31], v[116:119], v[108:111]
	v_mfma_f32_16x16x32_bf16 v[20:23], v[28:31], v[124:127], v[20:23]
	s_barrier
	ds_read_b128 v[24:27], v137
	ds_read_b128 v[28:31], v137 offset:1024
	ds_read_b128 v[112:115], v137 offset:2048
	ds_read_b128 v[116:119], v137 offset:3072
	ds_read_b128 v[120:123], v138
	ds_read_b128 v[124:127], v138 offset:1024
	ds_read_b128 v[164:167], v138 offset:2048
	ds_read_b128 v[168:171], v138 offset:3072
	s_add_u32 s64, s46, 0x10100
	s_addc_u32 s65, s47, 0
	s_mov_b32 m0, s50
	v_lshl_add_u64 v[212:213], s[64:65], 0, v[130:131]
	ds_read_b128 v[172:175], v136 offset:32768
	ds_read_b128 v[176:179], v136 offset:33792
	ds_read_b128 v[180:183], v136 offset:34816
	ds_read_b128 v[184:187], v136 offset:35840
	ds_read_b128 v[188:191], v136 offset:36864
	ds_read_b128 v[192:195], v136 offset:37888
	ds_read_b128 v[196:199], v136 offset:38912
	ds_read_b128 v[200:203], v136 offset:39936
	global_load_lds_dwordx4 v[212:213], off
	v_lshl_add_u64 v[212:213], s[64:65], 0, v[128:129]
	s_mov_b32 m0, s51
	s_nop 0
	global_load_lds_dwordx4 v[212:213], off
	s_waitcnt vmcnt(8)
	s_waitcnt lgkmcnt(0)
	s_barrier
	v_mfma_f32_16x16x32_bf16 v[64:67], v[24:27], v[172:175], v[64:67]
	v_mfma_f32_16x16x32_bf16 v[68:71], v[112:115], v[172:175], v[68:71]
	v_mfma_f32_16x16x32_bf16 v[72:75], v[24:27], v[180:183], v[72:75]
	v_mfma_f32_16x16x32_bf16 v[76:79], v[112:115], v[180:183], v[76:79]
	v_mfma_f32_16x16x32_bf16 v[80:83], v[24:27], v[188:191], v[80:83]
	v_mfma_f32_16x16x32_bf16 v[84:87], v[112:115], v[188:191], v[84:87]
	v_mfma_f32_16x16x32_bf16 v[88:91], v[24:27], v[196:199], v[88:91]
	v_mfma_f32_16x16x32_bf16 v[92:95], v[112:115], v[196:199], v[92:95]
	v_mfma_f32_16x16x32_bf16 v[64:67], v[28:31], v[176:179], v[64:67]
	v_mfma_f32_16x16x32_bf16 v[68:71], v[116:119], v[176:179], v[68:71]
	v_mfma_f32_16x16x32_bf16 v[72:75], v[28:31], v[184:187], v[72:75]
	v_mfma_f32_16x16x32_bf16 v[76:79], v[116:119], v[184:187], v[76:79]
	v_mfma_f32_16x16x32_bf16 v[80:83], v[28:31], v[192:195], v[80:83]
	v_mfma_f32_16x16x32_bf16 v[84:87], v[116:119], v[192:195], v[84:87]
	v_mfma_f32_16x16x32_bf16 v[88:91], v[28:31], v[200:203], v[88:91]
	v_mfma_f32_16x16x32_bf16 v[92:95], v[116:119], v[200:203], v[92:95]
	v_mfma_f32_16x16x32_bf16 v[96:99], v[120:123], v[172:175], v[96:99]
	v_mfma_f32_16x16x32_bf16 v[32:35], v[164:167], v[172:175], v[32:35]
	v_mfma_f32_16x16x32_bf16 v[36:39], v[120:123], v[180:183], v[36:39]
	v_mfma_f32_16x16x32_bf16 v[40:43], v[164:167], v[180:183], v[40:43]
	v_mfma_f32_16x16x32_bf16 v[44:47], v[120:123], v[188:191], v[44:47]
	v_mfma_f32_16x16x32_bf16 v[48:51], v[164:167], v[188:191], v[48:51]
	v_mfma_f32_16x16x32_bf16 v[52:55], v[120:123], v[196:199], v[52:55]
	v_mfma_f32_16x16x32_bf16 v[56:59], v[164:167], v[196:199], v[56:59]
	v_mfma_f32_16x16x32_bf16 v[96:99], v[124:127], v[176:179], v[96:99]
	v_mfma_f32_16x16x32_bf16 v[32:35], v[168:171], v[176:179], v[32:35]
	v_mfma_f32_16x16x32_bf16 v[36:39], v[124:127], v[184:187], v[36:39]
	v_mfma_f32_16x16x32_bf16 v[40:43], v[168:171], v[184:187], v[40:43]
	v_mfma_f32_16x16x32_bf16 v[44:47], v[124:127], v[192:195], v[44:47]
	v_mfma_f32_16x16x32_bf16 v[48:51], v[168:171], v[192:195], v[48:51]
	v_mfma_f32_16x16x32_bf16 v[52:55], v[124:127], v[200:203], v[52:55]
	v_mfma_f32_16x16x32_bf16 v[56:59], v[168:171], v[200:203], v[56:59]
	s_barrier
; #define PG8_STAGE(bufoff, gbase, voff) do { _Pragma("unroll") for (int _i = 0; _i < 2; ++_i) \
;         __builtin_amdgcn_global_load_lds((const unsigned*)((const char*)(gbase) + (voff)[_i]), (PG8_LAS unsigned*)(lds + (bufoff) + ldsw + _i * 8192), 16, 0, 0); } while (0)
; #define PG8_LDA(dst, b, h) do { _Pragma("unroll") for (int m = 0; m < 4; ++m) _Pragma("unroll") for (int k = 0; k < 2; ++k) dst[m][k] = *(const PG8_LAS bf16x8*)(lds + PG8_SA(b, h) + aoff + m * 2048 + k * 1024); } while (0)
; #define PG8_LDB(dst, b, h) do { _Pragma("unroll") for (int n = 0; n < 2; ++n) _Pragma("unroll") for (int k = 0; k < 2; ++k) dst[n][k] = *(const PG8_LAS bf16x8*)(lds + PG8_SB(b, h) + boff + n * 2048 + k * 1024); } while (0)
; #define PG8_MMA(ai, bj, At, Bt) do { __builtin_amdgcn_s_setprio(1); _Pragma("unroll") for (int m = 0; m < 4; ++m) _Pragma("unroll") for (int n = 0; n < 2; ++n) _Pragma("unroll") for (int k = 0; k < 2; ++k) \
;         acc[ai][bj][m][n] = mma16<F16>(Bt[n][k], At[m][k], acc[ai][bj][m][n]); __builtin_amdgcn_s_setprio(0); } while (0)
; #define PG8_WAIT_V(n) asm volatile("s_waitcnt vmcnt(" #n ")" ::: "memory")
; template <class Epi, class Sched, bool ALIGN_EPI = false, bool SP2 = false, bool F16 = false>
; __device__ __forceinline__ void gemm_phase(PG8_LAS unsigned char* lds, const Gemm g, const Sched& S, const Epi& E, const int wid_in) {
;     ...
;             PG8_LDB(B0, 0, 0); PG8_LDB(B1, 0, 1); PG8_SCHED; PG8_LDA(At, 0, 0); PG8_STAGE(PG8_SA(1, 1), a1 + hstep, voffA);
;             PG8_WAIT_V(8); PG8_WAIT_L(0); PG8_BAR; PG8_MMA(0, 0, At, B0); PG8_MMA(0, 1, At, B1); PG8_BAR; PG8_SCHED;
;             PG8_LDA(At, 0, 1); PG8_STAGE(PG8_SB(0, 0), b2, voffB); PG8_STAGE(PG8_SB(0, 1), b2 + hstep, voffB); PG8_STAGE(PG8_SA(0, 0), a2, voffA);
;             PG8_WAIT_V(8); PG8_WAIT_L(0); PG8_BAR; PG8_MMA(1, 0, At, B0); PG8_MMA(1, 1, At, B1); PG8_BAR; PG8_SCHED;
;             PG8_LDB(B0, 1, 0); PG8_LDB(B1, 1, 1); PG8_SCHED; PG8_LDA(At, 1, 0); PG8_STAGE(PG8_SA(0, 1), a2 + hstep, voffA);
;             PG8_WAIT_V(8); PG8_WAIT_L(0); PG8_BAR; PG8_MMA(0, 0, At, B0); PG8_MMA(0, 1, At, B1); PG8_BAR; PG8_SCHED;
;             PG8_LDA(At, 1, 1); PG8_STAGE(PG8_SB(1, 0), b3, voffB); PG8_STAGE(PG8_SB(1, 1), b3 + hstep, voffB); PG8_STAGE(PG8_SA(1, 0), a3, voffA);
;             PG8_WAIT_V(8); PG8_WAIT_L(0); PG8_BAR; PG8_MMA(1, 0, At, B0); PG8_MMA(1, 1, At, B1); PG8_BAR; PG8_SCHED;
	s_mov_b32 m0, s57
	v_lshl_add_u64 v[204:205], v[204:205], 0, s[28:29]
	s_add_u32 s48, s48, 0x10180
	ds_read_b128 v[172:175], v136 offset:49152
	ds_read_b128 v[176:179], v136 offset:50176
	ds_read_b128 v[180:183], v136 offset:51200
	ds_read_b128 v[184:187], v136 offset:52224
	ds_read_b128 v[188:191], v136 offset:53248
	ds_read_b128 v[192:195], v136 offset:54272
	ds_read_b128 v[196:199], v136 offset:55296
	ds_read_b128 v[200:203], v136 offset:56320
	global_load_lds_dwordx4 v[204:205], off
	v_lshl_add_u64 v[204:205], v[206:207], 0, s[28:29]
	s_mov_b32 m0, s58
	s_addc_u32 s49, s49, 0
	global_load_lds_dwordx4 v[204:205], off
	v_lshl_add_u64 v[204:205], s[48:49], 0, v[130:131]
	s_mov_b32 m0, s59
	s_nop 0
	global_load_lds_dwordx4 v[204:205], off
	v_lshl_add_u64 v[204:205], s[48:49], 0, v[128:129]
	s_mov_b32 m0, s60
	s_nop 0
	global_load_lds_dwordx4 v[204:205], off
	v_lshl_add_u64 v[204:205], v[208:209], 0, s[28:29]
	s_mov_b32 m0, s75
	s_nop 0
	global_load_lds_dwordx4 v[204:205], off
	v_lshl_add_u64 v[204:205], v[210:211], 0, s[28:29]
	s_mov_b32 m0, s14
	s_nop 0
	global_load_lds_dwordx4 v[204:205], off
	s_waitcnt vmcnt(8)
	s_waitcnt lgkmcnt(0)
	s_barrier
	v_mfma_f32_16x16x32_bf16 v[0:3], v[24:27], v[196:199], v[0:3]
	v_mfma_f32_16x16x32_bf16 v[4:7], v[112:115], v[196:199], v[4:7]
	v_mfma_f32_16x16x32_bf16 v[140:143], v[24:27], v[172:175], v[140:143]
	v_mfma_f32_16x16x32_bf16 v[144:147], v[112:115], v[172:175], v[144:147]
	v_mfma_f32_16x16x32_bf16 v[148:151], v[24:27], v[180:183], v[148:151]
	v_mfma_f32_16x16x32_bf16 v[152:155], v[112:115], v[180:183], v[152:155]
	v_mfma_f32_16x16x32_bf16 v[156:159], v[24:27], v[188:191], v[156:159]
	v_mfma_f32_16x16x32_bf16 v[160:163], v[112:115], v[188:191], v[160:163]
	v_mfma_f32_16x16x32_bf16 v[0:3], v[28:31], v[200:203], v[0:3]
	v_mfma_f32_16x16x32_bf16 v[4:7], v[116:119], v[200:203], v[4:7]
	v_mfma_f32_16x16x32_bf16 v[140:143], v[28:31], v[176:179], v[140:143]
	v_mfma_f32_16x16x32_bf16 v[144:147], v[116:119], v[176:179], v[144:147]
	v_mfma_f32_16x16x32_bf16 v[148:151], v[28:31], v[184:187], v[148:151]
	v_mfma_f32_16x16x32_bf16 v[152:155], v[116:119], v[184:187], v[152:155]
	v_mfma_f32_16x16x32_bf16 v[156:159], v[28:31], v[192:195], v[156:159]
	v_mfma_f32_16x16x32_bf16 v[160:163], v[116:119], v[192:195], v[160:163]
	v_mfma_f32_16x16x32_bf16 v[8:11], v[120:123], v[172:175], v[8:11]
	v_mfma_f32_16x16x32_bf16 v[12:15], v[164:167], v[172:175], v[12:15]
	v_mfma_f32_16x16x32_bf16 v[24:27], v[120:123], v[180:183], v[60:63]
	v_mfma_f32_16x16x32_bf16 v[28:31], v[164:167], v[180:183], v[100:103]
	v_mfma_f32_16x16x32_bf16 v[60:63], v[120:123], v[188:191], v[104:107]
	v_mfma_f32_16x16x32_bf16 v[100:103], v[164:167], v[188:191], v[108:111]
	v_mfma_f32_16x16x32_bf16 v[16:19], v[120:123], v[196:199], v[16:19]
	v_mfma_f32_16x16x32_bf16 v[20:23], v[164:167], v[196:199], v[20:23]
	v_mfma_f32_16x16x32_bf16 v[8:11], v[124:127], v[176:179], v[8:11]
	v_mfma_f32_16x16x32_bf16 v[12:15], v[168:171], v[176:179], v[12:15]
	v_mfma_f32_16x16x32_bf16 v[24:27], v[124:127], v[184:187], v[24:27]
	v_mfma_f32_16x16x32_bf16 v[28:31], v[168:171], v[184:187], v[28:31]
	v_mfma_f32_16x16x32_bf16 v[60:63], v[124:127], v[192:195], v[60:63]
	v_mfma_f32_16x16x32_bf16 v[100:103], v[168:171], v[192:195], v[100:103]
	v_mfma_f32_16x16x32_bf16 v[16:19], v[124:127], v[200:203], v[16:19]
	v_mfma_f32_16x16x32_bf16 v[20:23], v[168:171], v[200:203], v[20:23]
	s_barrier
	ds_read_b128 v[104:107], v134
	ds_read_b128 v[108:111], v134 offset:1024
	ds_read_b128 v[112:115], v134 offset:2048
	ds_read_b128 v[116:119], v134 offset:3072
	ds_read_b128 v[120:123], v135
	ds_read_b128 v[124:127], v135 offset:1024
	ds_read_b128 v[164:167], v135 offset:2048
	ds_read_b128 v[168:171], v135 offset:3072
	s_add_u32 s46, s46, 0x10180
	s_addc_u32 s47, s47, 0
	s_mov_b32 m0, s15
	v_lshl_add_u64 v[204:205], s[46:47], 0, v[130:131]
	ds_read_b128 v[172:175], v136
	ds_read_b128 v[176:179], v136 offset:1024
	ds_read_b128 v[180:183], v136 offset:2048
	ds_read_b128 v[184:187], v136 offset:3072
	ds_read_b128 v[188:191], v136 offset:4096
	ds_read_b128 v[192:195], v136 offset:5120
	ds_read_b128 v[196:199], v136 offset:6144
	ds_read_b128 v[200:203], v136 offset:7168
	global_load_lds_dwordx4 v[204:205], off
	v_lshl_add_u64 v[204:205], s[46:47], 0, v[128:129]
	s_mov_b32 m0, s52
	s_nop 0
	global_load_lds_dwordx4 v[204:205], off
	s_waitcnt vmcnt(8)
	s_waitcnt lgkmcnt(0)
	s_barrier
	v_mfma_f32_16x16x32_bf16 v[64:67], v[104:107], v[172:175], v[64:67]
	v_mfma_f32_16x16x32_bf16 v[68:71], v[112:115], v[172:175], v[68:71]
	v_mfma_f32_16x16x32_bf16 v[72:75], v[104:107], v[180:183], v[72:75]
	v_mfma_f32_16x16x32_bf16 v[76:79], v[112:115], v[180:183], v[76:79]
	v_mfma_f32_16x16x32_bf16 v[80:83], v[104:107], v[188:191], v[80:83]
	v_mfma_f32_16x16x32_bf16 v[84:87], v[112:115], v[188:191], v[84:87]
	v_mfma_f32_16x16x32_bf16 v[88:91], v[104:107], v[196:199], v[88:91]
	v_mfma_f32_16x16x32_bf16 v[92:95], v[112:115], v[196:199], v[92:95]
	v_mfma_f32_16x16x32_bf16 v[64:67], v[108:111], v[176:179], v[64:67]
	v_mfma_f32_16x16x32_bf16 v[68:71], v[116:119], v[176:179], v[68:71]
	v_mfma_f32_16x16x32_bf16 v[72:75], v[108:111], v[184:187], v[72:75]
	v_mfma_f32_16x16x32_bf16 v[76:79], v[116:119], v[184:187], v[76:79]
	v_mfma_f32_16x16x32_bf16 v[80:83], v[108:111], v[192:195], v[80:83]
	v_mfma_f32_16x16x32_bf16 v[84:87], v[116:119], v[192:195], v[84:87]
	v_mfma_f32_16x16x32_bf16 v[88:91], v[108:111], v[200:203], v[88:91]
	v_mfma_f32_16x16x32_bf16 v[92:95], v[116:119], v[200:203], v[92:95]
	v_mfma_f32_16x16x32_bf16 v[32:35], v[164:167], v[172:175], v[32:35]
	v_mfma_f32_16x16x32_bf16 v[96:99], v[120:123], v[172:175], v[96:99]
	v_mfma_f32_16x16x32_bf16 v[172:175], v[168:171], v[176:179], v[32:35]
	v_mfma_f32_16x16x32_bf16 v[32:35], v[120:123], v[180:183], v[36:39]
	v_mfma_f32_16x16x32_bf16 v[204:207], v[124:127], v[176:179], v[96:99]
	v_mfma_f32_16x16x32_bf16 v[176:179], v[124:127], v[184:187], v[32:35]
	v_mfma_f32_16x16x32_bf16 v[32:35], v[164:167], v[180:183], v[40:43]
	v_mfma_f32_16x16x32_bf16 v[40:43], v[168:171], v[184:187], v[32:35]
	v_mfma_f32_16x16x32_bf16 v[32:35], v[120:123], v[188:191], v[44:47]
	v_mfma_f32_16x16x32_bf16 v[44:47], v[124:127], v[192:195], v[32:35]
	v_mfma_f32_16x16x32_bf16 v[32:35], v[164:167], v[188:191], v[48:51]
	v_mfma_f32_16x16x32_bf16 v[48:51], v[168:171], v[192:195], v[32:35]
	v_mfma_f32_16x16x32_bf16 v[32:35], v[120:123], v[196:199], v[52:55]
	v_mfma_f32_16x16x32_bf16 v[52:55], v[124:127], v[200:203], v[32:35]
	v_mfma_f32_16x16x32_bf16 v[32:35], v[164:167], v[196:199], v[56:59]
	v_mfma_f32_16x16x32_bf16 v[56:59], v[168:171], v[200:203], v[32:35]
	s_barrier
; #define PG8_STAGE(bufoff, gbase, voff) do { _Pragma("unroll") for (int _i = 0; _i < 2; ++_i) \
;         __builtin_amdgcn_global_load_lds((const unsigned*)((const char*)(gbase) + (voff)[_i]), (PG8_LAS unsigned*)(lds + (bufoff) + ldsw + _i * 8192), 16, 0, 0); } while (0)
; #define PG8_LDA(dst, b, h) do { _Pragma("unroll") for (int m = 0; m < 4; ++m) _Pragma("unroll") for (int k = 0; k < 2; ++k) dst[m][k] = *(const PG8_LAS bf16x8*)(lds + PG8_SA(b, h) + aoff + m * 2048 + k * 1024); } while (0)
; #define PG8_LDB(dst, b, h) do { _Pragma("unroll") for (int n = 0; n < 2; ++n) _Pragma("unroll") for (int k = 0; k < 2; ++k) dst[n][k] = *(const PG8_LAS bf16x8*)(lds + PG8_SB(b, h) + boff + n * 2048 + k * 1024); } while (0)
; #define PG8_WAIT_V(n) asm volatile("s_waitcnt vmcnt(" #n ")" ::: "memory")
; #define PG8_BAR __builtin_amdgcn_s_barrier()
; template <class Epi, class Sched, bool ALIGN_EPI = false, bool SP2 = false, bool F16 = false>
; __device__ __forceinline__ void gemm_phase(PG8_LAS unsigned char* lds, const Gemm g, const Sched& S, const Epi& E, const int wid_in) {
;     ...
;             const char* a2 = last ? nA : cA + (size_t)(t + 2) * kstep; const char* b2 = last ? nB : cB + (size_t)(t + 2) * kstep;
;             const char* a3 = a2 + kstep; const char* b3 = b2 + kstep;
;             if (last && has_next) S.a_ready(nxt);
;             if constexpr (SP2) {
;             PG8_LDB(B0, 0, 0); PG8_LDB(B1, 0, 1); PG8_SCHED; PG8_LDA(At, 0, 0); PG8_STAGE(PG8_SA(1, 1), a1 + hstep, voffA);
;             PG8_WAIT_V(8); PG8_WAIT_L(0); PG8_BAR; PG8_MMA(0, 0, At, B0); PG8_MMA(0, 1, At, B1); PG8_BAR; PG8_SCHED;
;             PG8_LDA(At, 0, 1); PG8_STAGE(PG8_SB(0, 0), b2, voffB); PG8_STAGE(PG8_SB(0, 1), b2 + hstep, voffB); PG8_STAGE(PG8_SA(0, 0), a2, voffA);
;             PG8_WAIT_V(8); PG8_WAIT_L(0); PG8_BAR; PG8_MMA(1, 0, At, B0); PG8_MMA(1, 1, At, B1); PG8_BAR; PG8_SCHED;
;             PG8_LDB(B0, 1, 0); PG8_LDB(B1, 1, 1); PG8_SCHED; PG8_LDA(At, 1, 0); PG8_STAGE(PG8_SA(0, 1), a2 + hstep, voffA);
;             PG8_WAIT_V(8); PG8_WAIT_L(0); PG8_BAR; PG8_MMA(0, 0, At, B0); PG8_MMA(0, 1, At, B1); PG8_BAR; PG8_SCHED;
;             PG8_LDA(At, 1, 1); PG8_STAGE(PG8_SB(1, 0), b3, voffB); PG8_STAGE(PG8_SB(1, 1), b3 + hstep, voffB); PG8_STAGE(PG8_SA(1, 0), a3, voffA);
;             PG8_WAIT_V(8); PG8_WAIT_L(0); PG8_BAR; PG8_MMA(1, 0, At, B0); PG8_MMA(1, 1, At, B1); PG8_BAR; PG8_SCHED;
	s_mov_b32 m0, s53
	v_lshl_add_u64 v[240:241], s[36:37], 0, v[130:131]
	s_add_u32 s46, s36, 0x10000
	s_nop 1
	ds_read_b128 v[32:35], v136 offset:16384
	ds_read_b128 v[36:39], v136 offset:17408
	ds_read_b128 v[96:99], v136 offset:18432
	ds_read_b128 v[180:183], v136 offset:19456
	ds_read_b128 v[184:187], v136 offset:20480
	ds_read_b128 v[188:191], v136 offset:21504
	ds_read_b128 v[192:195], v136 offset:22528
	ds_read_b128 v[196:199], v136 offset:23552
	global_load_lds_dwordx4 v[240:241], off
	v_lshl_add_u64 v[242:243], s[36:37], 0, v[128:129]
	s_mov_b32 m0, s54
	s_addc_u32 s47, s37, 0
	global_load_lds_dwordx4 v[242:243], off
	v_lshl_add_u64 v[200:201], s[46:47], 0, v[130:131]
	s_mov_b32 m0, s55
	v_lshl_add_u64 v[244:245], s[44:45], 0, v[130:131]
	global_load_lds_dwordx4 v[200:201], off
	v_lshl_add_u64 v[200:201], s[46:47], 0, v[128:129]
	s_mov_b32 m0, s56
	v_lshl_add_u64 v[246:247], s[44:45], 0, v[128:129]
	global_load_lds_dwordx4 v[200:201], off
	s_mov_b32 m0, s74
	s_nop 0
	global_load_lds_dwordx4 v[244:245], off
	s_mov_b32 m0, s43
	s_nop 0
	global_load_lds_dwordx4 v[246:247], off
	s_waitcnt vmcnt(8)
	s_waitcnt lgkmcnt(0)
	s_barrier
	v_mfma_f32_16x16x32_bf16 v[0:3], v[104:107], v[192:195], v[0:3]
	v_mfma_f32_16x16x32_bf16 v[140:143], v[104:107], v[32:35], v[140:143]
	v_mfma_f32_16x16x32_bf16 v[144:147], v[112:115], v[32:35], v[144:147]
	v_mfma_f32_16x16x32_bf16 v[148:151], v[104:107], v[96:99], v[148:151]
	v_mfma_f32_16x16x32_bf16 v[152:155], v[112:115], v[96:99], v[152:155]
	v_mfma_f32_16x16x32_bf16 v[156:159], v[104:107], v[184:187], v[156:159]
	v_mfma_f32_16x16x32_bf16 v[160:163], v[112:115], v[184:187], v[160:163]
	v_mfma_f32_16x16x32_bf16 v[0:3], v[108:111], v[196:199], v[0:3]
	v_mfma_f32_16x16x32_bf16 v[4:7], v[112:115], v[192:195], v[4:7]
	v_mfma_f32_16x16x32_bf16 v[140:143], v[108:111], v[36:39], v[140:143]
	v_mfma_f32_16x16x32_bf16 v[144:147], v[116:119], v[36:39], v[144:147]
	v_mfma_f32_16x16x32_bf16 v[148:151], v[108:111], v[180:183], v[148:151]
	v_mfma_f32_16x16x32_bf16 v[152:155], v[116:119], v[180:183], v[152:155]
	v_mfma_f32_16x16x32_bf16 v[156:159], v[108:111], v[188:191], v[156:159]
	v_mfma_f32_16x16x32_bf16 v[160:163], v[116:119], v[188:191], v[160:163]
	v_mfma_f32_16x16x32_bf16 v[200:203], v[116:119], v[196:199], v[4:7]
	v_mfma_f32_16x16x32_bf16 v[4:7], v[120:123], v[32:35], v[8:11]
	v_mfma_f32_16x16x32_bf16 v[8:11], v[124:127], v[36:39], v[4:7]
	v_mfma_f32_16x16x32_bf16 v[4:7], v[164:167], v[32:35], v[12:15]
	v_mfma_f32_16x16x32_bf16 v[12:15], v[168:171], v[36:39], v[4:7]
	v_mfma_f32_16x16x32_bf16 v[4:7], v[120:123], v[96:99], v[24:27]
	v_mfma_f32_16x16x32_bf16 v[24:27], v[124:127], v[180:183], v[4:7]
	v_mfma_f32_16x16x32_bf16 v[4:7], v[164:167], v[96:99], v[28:31]
	v_mfma_f32_16x16x32_bf16 v[28:31], v[168:171], v[180:183], v[4:7]
	v_mfma_f32_16x16x32_bf16 v[4:7], v[120:123], v[184:187], v[60:63]
	v_mfma_f32_16x16x32_bf16 v[180:183], v[124:127], v[188:191], v[4:7]
	v_mfma_f32_16x16x32_bf16 v[4:7], v[164:167], v[184:187], v[100:103]
	v_mfma_f32_16x16x32_bf16 v[184:187], v[168:171], v[188:191], v[4:7]
	v_mfma_f32_16x16x32_bf16 v[4:7], v[120:123], v[192:195], v[16:19]
	v_mfma_f32_16x16x32_bf16 v[188:191], v[124:127], v[196:199], v[4:7]
	v_mfma_f32_16x16x32_bf16 v[4:7], v[164:167], v[192:195], v[20:23]
	v_mfma_f32_16x16x32_bf16 v[164:167], v[168:171], v[196:199], v[4:7]
	s_barrier
	s_nop 4
	ds_read_b128 v[4:7], v137
	ds_read_b128 v[60:63], v137 offset:1024
	ds_read_b128 v[168:171], v137 offset:2048
	ds_read_b128 v[192:195], v137 offset:3072
	ds_read_b128 v[196:199], v138
	ds_read_b128 v[208:211], v138 offset:1024
	ds_read_b128 v[212:215], v138 offset:2048
	ds_read_b128 v[216:219], v138 offset:3072
	s_add_u32 s44, s44, 0x10000
	s_addc_u32 s45, s45, 0
	s_mov_b32 m0, s50
	v_lshl_add_u64 v[32:33], s[44:45], 0, v[130:131]
	ds_read_b128 v[16:19], v136 offset:32768
	ds_read_b128 v[20:23], v136 offset:33792
	ds_read_b128 v[104:107], v136 offset:34816
	ds_read_b128 v[220:223], v136 offset:35840
	ds_read_b128 v[224:227], v136 offset:36864
	ds_read_b128 v[228:231], v136 offset:37888
	ds_read_b128 v[232:235], v136 offset:38912
	ds_read_b128 v[236:239], v136 offset:39936
	global_load_lds_dwordx4 v[32:33], off
	v_lshl_add_u64 v[32:33], s[44:45], 0, v[128:129]
	s_mov_b32 m0, s51
	s_nop 0
	global_load_lds_dwordx4 v[32:33], off
	s_waitcnt vmcnt(8)
	s_waitcnt lgkmcnt(0)
	s_barrier
; #define PG8_STAGE(bufoff, gbase, voff) do { _Pragma("unroll") for (int _i = 0; _i < 2; ++_i) \
;         __builtin_amdgcn_global_load_lds((const unsigned*)((const char*)(gbase) + (voff)[_i]), (PG8_LAS unsigned*)(lds + (bufoff) + ldsw + _i * 8192), 16, 0, 0); } while (0)
; #define PG8_LDA(dst, b, h) do { _Pragma("unroll") for (int m = 0; m < 4; ++m) _Pragma("unroll") for (int k = 0; k < 2; ++k) dst[m][k] = *(const PG8_LAS bf16x8*)(lds + PG8_SA(b, h) + aoff + m * 2048 + k * 1024); } while (0)
; #define PG8_MMA(ai, bj, At, Bt) do { __builtin_amdgcn_s_setprio(1); _Pragma("unroll") for (int m = 0; m < 4; ++m) _Pragma("unroll") for (int n = 0; n < 2; ++n) _Pragma("unroll") for (int k = 0; k < 2; ++k) \
;         acc[ai][bj][m][n] = mma16<F16>(Bt[n][k], At[m][k], acc[ai][bj][m][n]); __builtin_amdgcn_s_setprio(0); } while (0)
; #define PG8_WAIT_V(n) asm volatile("s_waitcnt vmcnt(" #n ")" ::: "memory")
; #define PG8_WAIT_L(n) asm volatile("s_waitcnt lgkmcnt(" #n ")" ::: "memory")
; #define PG8_BAR __builtin_amdgcn_s_barrier()
; #define PG8_SCHED __builtin_amdgcn_sched_barrier(0)
; template <class Epi, class Sched, bool ALIGN_EPI = false, bool SP2 = false, bool F16 = false>
; __device__ __forceinline__ void gemm_phase(PG8_LAS unsigned char* lds, const Gemm g, const Sched& S, const Epi& E, const int wid_in) {
;     ...
;             PG8_WAIT_V(8); PG8_WAIT_L(0); PG8_BAR; PG8_MMA(0, 0, At, B0); PG8_MMA(0, 1, At, B1); PG8_BAR; PG8_SCHED;
;             PG8_LDA(At, 1, 1); PG8_STAGE(PG8_SB(1, 0), b3, voffB); PG8_STAGE(PG8_SB(1, 1), b3 + hstep, voffB); PG8_STAGE(PG8_SA(1, 0), a3, voffA);
;             PG8_WAIT_V(8); PG8_WAIT_L(0); PG8_BAR; PG8_MMA(1, 0, At, B0); PG8_MMA(1, 1, At, B1); PG8_BAR; PG8_SCHED;
;     ...
;         if constexpr (ALIGN_EPI) { if (wr == 0) PG8_BAR; }
	v_mfma_f32_16x16x32_bf16 v[32:35], v[4:7], v[16:19], v[64:67]
	v_mfma_f32_16x16x32_bf16 v[116:119], v[60:63], v[20:23], v[32:35]
	v_mfma_f32_16x16x32_bf16 v[32:35], v[168:171], v[16:19], v[68:71]
	v_mfma_f32_16x16x32_bf16 v[112:115], v[192:195], v[20:23], v[32:35]
	v_mfma_f32_16x16x32_bf16 v[32:35], v[4:7], v[104:107], v[72:75]
	v_mfma_f32_16x16x32_bf16 v[100:103], v[60:63], v[220:223], v[32:35]
	v_mfma_f32_16x16x32_bf16 v[32:35], v[168:171], v[104:107], v[76:79]
	v_mfma_f32_16x16x32_bf16 v[96:99], v[192:195], v[220:223], v[32:35]
	v_mfma_f32_16x16x32_bf16 v[32:35], v[4:7], v[224:227], v[80:83]
	v_mfma_f32_16x16x32_bf16 v[68:71], v[60:63], v[228:231], v[32:35]
	v_mfma_f32_16x16x32_bf16 v[32:35], v[168:171], v[224:227], v[84:87]
	v_mfma_f32_16x16x32_bf16 v[64:67], v[192:195], v[228:231], v[32:35]
	v_mfma_f32_16x16x32_bf16 v[32:35], v[4:7], v[232:235], v[88:91]
	v_mfma_f32_16x16x32_bf16 v[36:39], v[60:63], v[236:239], v[32:35]
	v_mfma_f32_16x16x32_bf16 v[32:35], v[168:171], v[232:235], v[92:95]
	v_mfma_f32_16x16x32_bf16 v[32:35], v[192:195], v[236:239], v[32:35]
	v_mfma_f32_16x16x32_bf16 v[72:75], v[196:199], v[16:19], v[204:207]
	v_mfma_f32_16x16x32_bf16 v[16:19], v[212:215], v[16:19], v[172:175]
	v_mfma_f32_16x16x32_bf16 v[120:123], v[216:219], v[20:23], v[16:19]
	v_mfma_f32_16x16x32_bf16 v[16:19], v[196:199], v[104:107], v[176:179]
	v_mfma_f32_16x16x32_bf16 v[108:111], v[208:211], v[220:223], v[16:19]
	v_mfma_f32_16x16x32_bf16 v[16:19], v[212:215], v[104:107], v[40:43]
	v_mfma_f32_16x16x32_bf16 v[104:107], v[216:219], v[220:223], v[16:19]
	v_mfma_f32_16x16x32_bf16 v[16:19], v[196:199], v[224:227], v[44:47]
	v_mfma_f32_16x16x32_bf16 v[80:83], v[208:211], v[228:231], v[16:19]
	v_mfma_f32_16x16x32_bf16 v[16:19], v[212:215], v[224:227], v[48:51]
	v_mfma_f32_16x16x32_bf16 v[124:127], v[208:211], v[20:23], v[72:75]
	v_mfma_f32_16x16x32_bf16 v[72:75], v[216:219], v[228:231], v[16:19]
	v_mfma_f32_16x16x32_bf16 v[16:19], v[196:199], v[232:235], v[52:55]
	v_mfma_f32_16x16x32_bf16 v[48:51], v[208:211], v[236:239], v[16:19]
	v_mfma_f32_16x16x32_bf16 v[16:19], v[212:215], v[232:235], v[56:59]
	v_mfma_f32_16x16x32_bf16 v[40:43], v[216:219], v[236:239], v[16:19]
	s_barrier
	s_mov_b32 m0, s57
	s_nop 3
	v_lshl_add_u64 v[16:17], v[240:241], 0, s[24:25]
	s_add_u32 s36, s36, 0x10080
	ds_read_b128 v[56:59], v136 offset:49152
	ds_read_b128 v[88:91], v136 offset:50176
	ds_read_b128 v[172:175], v136 offset:51200
	ds_read_b128 v[176:179], v136 offset:52224
	ds_read_b128 v[204:207], v136 offset:53248
	ds_read_b128 v[220:223], v136 offset:54272
	ds_read_b128 v[224:227], v136 offset:55296
	ds_read_b128 v[228:231], v136 offset:56320
	global_load_lds_dwordx4 v[16:17], off
	v_lshl_add_u64 v[16:17], v[242:243], 0, s[24:25]
	s_mov_b32 m0, s58
	s_addc_u32 s37, s37, 0
	global_load_lds_dwordx4 v[16:17], off
	v_lshl_add_u64 v[16:17], s[36:37], 0, v[130:131]
	s_mov_b32 m0, s59
	s_nop 0
	global_load_lds_dwordx4 v[16:17], off
	v_lshl_add_u64 v[16:17], s[36:37], 0, v[128:129]
	s_mov_b32 m0, s60
	s_nop 0
	global_load_lds_dwordx4 v[16:17], off
	v_lshl_add_u64 v[16:17], v[244:245], 0, s[24:25]
	s_mov_b32 m0, s75
	s_nop 0
	global_load_lds_dwordx4 v[16:17], off
	v_lshl_add_u64 v[16:17], v[246:247], 0, s[24:25]
	s_mov_b32 m0, s14
	s_nop 0
	global_load_lds_dwordx4 v[16:17], off
	s_waitcnt vmcnt(8)
	s_waitcnt lgkmcnt(0)
	s_barrier
	v_mfma_f32_16x16x32_bf16 v[16:19], v[4:7], v[56:59], v[140:143]
	v_mfma_f32_16x16x32_bf16 v[84:87], v[60:63], v[88:91], v[16:19]
	v_mfma_f32_16x16x32_bf16 v[16:19], v[168:171], v[56:59], v[144:147]
	v_mfma_f32_16x16x32_bf16 v[76:79], v[192:195], v[88:91], v[16:19]
	v_mfma_f32_16x16x32_bf16 v[16:19], v[4:7], v[172:175], v[148:151]
	v_mfma_f32_16x16x32_bf16 v[52:55], v[60:63], v[176:179], v[16:19]
	v_mfma_f32_16x16x32_bf16 v[16:19], v[168:171], v[172:175], v[152:155]
	v_mfma_f32_16x16x32_bf16 v[44:47], v[192:195], v[176:179], v[16:19]
	v_mfma_f32_16x16x32_bf16 v[16:19], v[4:7], v[204:207], v[156:159]
	v_mfma_f32_16x16x32_bf16 v[0:3], v[4:7], v[224:227], v[0:3]
	v_mfma_f32_16x16x32_bf16 v[20:23], v[60:63], v[220:223], v[16:19]
	v_mfma_f32_16x16x32_bf16 v[16:19], v[168:171], v[204:207], v[160:163]
	v_mfma_f32_16x16x32_bf16 v[4:7], v[60:63], v[228:231], v[0:3]
	v_mfma_f32_16x16x32_bf16 v[0:3], v[168:171], v[224:227], v[200:203]
	v_mfma_f32_16x16x32_bf16 v[16:19], v[192:195], v[220:223], v[16:19]
	v_mfma_f32_16x16x32_bf16 v[0:3], v[192:195], v[228:231], v[0:3]
	v_mfma_f32_16x16x32_bf16 v[8:11], v[196:199], v[56:59], v[8:11]
	v_mfma_f32_16x16x32_bf16 v[92:95], v[208:211], v[88:91], v[8:11]
	v_mfma_f32_16x16x32_bf16 v[8:11], v[212:215], v[56:59], v[12:15]
	v_mfma_f32_16x16x32_bf16 v[88:91], v[216:219], v[88:91], v[8:11]
	v_mfma_f32_16x16x32_bf16 v[8:11], v[196:199], v[172:175], v[24:27]
	v_mfma_f32_16x16x32_bf16 v[60:63], v[208:211], v[176:179], v[8:11]
	v_mfma_f32_16x16x32_bf16 v[8:11], v[212:215], v[172:175], v[28:31]
	v_mfma_f32_16x16x32_bf16 v[56:59], v[216:219], v[176:179], v[8:11]
	v_mfma_f32_16x16x32_bf16 v[8:11], v[196:199], v[204:207], v[180:183]
	v_mfma_f32_16x16x32_bf16 v[28:31], v[208:211], v[220:223], v[8:11]
	v_mfma_f32_16x16x32_bf16 v[8:11], v[212:215], v[204:207], v[184:187]
	v_mfma_f32_16x16x32_bf16 v[24:27], v[216:219], v[220:223], v[8:11]
	v_mfma_f32_16x16x32_bf16 v[8:11], v[196:199], v[224:227], v[188:191]
	v_mfma_f32_16x16x32_bf16 v[12:15], v[208:211], v[228:231], v[8:11]
	v_mfma_f32_16x16x32_bf16 v[8:11], v[212:215], v[224:227], v[164:167]
	v_mfma_f32_16x16x32_bf16 v[8:11], v[216:219], v[228:231], v[8:11]
	s_barrier
	s_and_b64 vcc, exec, s[8:9]
	s_cbranch_vccnz .LBB0_1279
	s_barrier

; #define PG8_STAGE(bufoff, gbase, voff) do { _Pragma("unroll") for (int _i = 0; _i < 2; ++_i) \
;         __builtin_amdgcn_global_load_lds((const unsigned*)((const char*)(gbase) + (voff)[_i]), (PG8_LAS unsigned*)(lds + (bufoff) + ldsw + _i * 8192), 16, 0, 0); } while (0)
; #define PG8_LDA(dst, b, h) do { _Pragma("unroll") for (int m = 0; m < 4; ++m) _Pragma("unroll") for (int k = 0; k < 2; ++k) dst[m][k] = *(const PG8_LAS bf16x8*)(lds + PG8_SA(b, h) + aoff + m * 2048 + k * 1024); } while (0)
; #define PG8_LDB(dst, b, h) do { _Pragma("unroll") for (int n = 0; n < 2; ++n) _Pragma("unroll") for (int k = 0; k < 2; ++k) dst[n][k] = *(const PG8_LAS bf16x8*)(lds + PG8_SB(b, h) + boff + n * 2048 + k * 1024); } while (0)
; #define PG8_MMA(ai, bj, At, Bt) do { __builtin_amdgcn_s_setprio(1); _Pragma("unroll") for (int m = 0; m < 4; ++m) _Pragma("unroll") for (int n = 0; n < 2; ++n) _Pragma("unroll") for (int k = 0; k < 2; ++k) \
;         acc[ai][bj][m][n] = mma16<F16>(Bt[n][k], At[m][k], acc[ai][bj][m][n]); __builtin_amdgcn_s_setprio(0); } while (0)
; #define PG8_WAIT_V(n) asm volatile("s_waitcnt vmcnt(" #n ")" ::: "memory")
; #define PG8_BAR __builtin_amdgcn_s_barrier()
; template <class Epi, class Sched, bool ALIGN_EPI = false, bool SP2 = false, bool F16 = false>
; __device__ __forceinline__ void gemm_phase(PG8_LAS unsigned char* lds, const Gemm g, const Sched& S, const Epi& E, const int wid_in) {
;     ...
;         for (int t = 0; t < nt; t += 2) {
;             const bool last = (t == nt - 2);
;             const char* a1 = cA + (size_t)(t + 1) * kstep;
;             const char* a2 = last ? nA : cA + (size_t)(t + 2) * kstep; const char* b2 = last ? nB : cB + (size_t)(t + 2) * kstep;
;             const char* a3 = a2 + kstep; const char* b3 = b2 + kstep;
;             if (last && has_next) S.a_ready(nxt);
;             if constexpr (SP2) {
;             PG8_LDB(B0, 0, 0); PG8_LDB(B1, 0, 1); PG8_SCHED; PG8_LDA(At, 0, 0); PG8_STAGE(PG8_SA(1, 1), a1 + hstep, voffA);
;             PG8_WAIT_V(8); PG8_WAIT_L(0); PG8_BAR; PG8_MMA(0, 0, At, B0); PG8_MMA(0, 1, At, B1); PG8_BAR; PG8_SCHED;
;             PG8_LDA(At, 0, 1); PG8_STAGE(PG8_SB(0, 0), b2, voffB); PG8_STAGE(PG8_SB(0, 1), b2 + hstep, voffB); PG8_STAGE(PG8_SA(0, 0), a2, voffA);
;             PG8_WAIT_V(8); PG8_WAIT_L(0); PG8_BAR; PG8_MMA(1, 0, At, B0); PG8_MMA(1, 1, At, B1); PG8_BAR; PG8_SCHED;
.LBB0_1373:
	ds_read_b128 v[128:131], v189
	ds_read_b128 v[132:135], v189 offset:1024
	ds_read_b128 v[136:139], v189 offset:2048
	ds_read_b128 v[140:143], v189 offset:3072
	ds_read_b128 v[144:147], v190
	ds_read_b128 v[148:151], v190 offset:1024
	ds_read_b128 v[168:171], v190 offset:2048
	ds_read_b128 v[172:175], v190 offset:3072
	s_add_u32 s44, s36, 0x100
	s_addc_u32 s45, s37, 0
	s_cmp_eq_u32 s62, 40
	s_cselect_b32 s49, s13, s45
	s_cselect_b32 s48, s12, s44
	s_cselect_b32 s47, s35, s61
	s_cselect_b32 s46, s34, s43
	v_lshl_add_u64 v[184:185], s[36:37], 0, v[160:161]
	s_add_i32 m0, s74, 0xc000
	ds_read_b128 v[176:179], v191
	ds_read_b128 v[180:183], v191 offset:1024
	ds_read_b128 v[192:195], v191 offset:2048
	ds_read_b128 v[196:199], v191 offset:3072
	ds_read_b128 v[200:203], v191 offset:4096
	ds_read_b128 v[204:207], v191 offset:5120
	ds_read_b128 v[208:211], v191 offset:6144
	ds_read_b128 v[212:215], v191 offset:7168
	global_load_lds_dwordx4 v[184:185], off
	v_lshl_add_u64 v[184:185], s[36:37], 0, v[162:163]
	s_add_i32 m0, s74, 0xe000
	s_nop 0
	global_load_lds_dwordx4 v[184:185], off
	s_waitcnt vmcnt(8)
	s_waitcnt lgkmcnt(0)
	s_barrier
	v_mfma_f32_16x16x32_bf16 v[124:127], v[128:131], v[176:179], v[124:127]
	v_mfma_f32_16x16x32_bf16 v[120:123], v[136:139], v[176:179], v[120:123]
	v_mfma_f32_16x16x32_bf16 v[108:111], v[128:131], v[192:195], v[108:111]
	v_mfma_f32_16x16x32_bf16 v[104:107], v[136:139], v[192:195], v[104:107]
	v_mfma_f32_16x16x32_bf16 v[92:95], v[128:131], v[200:203], v[92:95]
	v_mfma_f32_16x16x32_bf16 v[88:91], v[136:139], v[200:203], v[88:91]
	v_mfma_f32_16x16x32_bf16 v[76:79], v[128:131], v[208:211], v[76:79]
	v_mfma_f32_16x16x32_bf16 v[72:75], v[136:139], v[208:211], v[72:75]
	v_mfma_f32_16x16x32_bf16 v[124:127], v[132:135], v[180:183], v[124:127]
	v_mfma_f32_16x16x32_bf16 v[120:123], v[140:143], v[180:183], v[120:123]
	v_mfma_f32_16x16x32_bf16 v[108:111], v[132:135], v[196:199], v[108:111]
	v_mfma_f32_16x16x32_bf16 v[104:107], v[140:143], v[196:199], v[104:107]
	v_mfma_f32_16x16x32_bf16 v[92:95], v[132:135], v[204:207], v[92:95]
	v_mfma_f32_16x16x32_bf16 v[88:91], v[140:143], v[204:207], v[88:91]
	v_mfma_f32_16x16x32_bf16 v[76:79], v[132:135], v[212:215], v[76:79]
	v_mfma_f32_16x16x32_bf16 v[72:75], v[140:143], v[212:215], v[72:75]
	v_mfma_f32_16x16x32_bf16 v[116:119], v[144:147], v[176:179], v[116:119]
	v_mfma_f32_16x16x32_bf16 v[112:115], v[168:171], v[176:179], v[112:115]
	v_mfma_f32_16x16x32_bf16 v[100:103], v[144:147], v[192:195], v[100:103]
	v_mfma_f32_16x16x32_bf16 v[96:99], v[168:171], v[192:195], v[96:99]
	v_mfma_f32_16x16x32_bf16 v[84:87], v[144:147], v[200:203], v[84:87]
	v_mfma_f32_16x16x32_bf16 v[80:83], v[168:171], v[200:203], v[80:83]
	v_mfma_f32_16x16x32_bf16 v[68:71], v[144:147], v[208:211], v[68:71]
	v_mfma_f32_16x16x32_bf16 v[64:67], v[168:171], v[208:211], v[64:67]
	v_mfma_f32_16x16x32_bf16 v[116:119], v[148:151], v[180:183], v[116:119]
	v_mfma_f32_16x16x32_bf16 v[112:115], v[172:175], v[180:183], v[112:115]
	v_mfma_f32_16x16x32_bf16 v[100:103], v[148:151], v[196:199], v[100:103]
	v_mfma_f32_16x16x32_bf16 v[96:99], v[172:175], v[196:199], v[96:99]
	v_mfma_f32_16x16x32_bf16 v[84:87], v[148:151], v[204:207], v[84:87]
	v_mfma_f32_16x16x32_bf16 v[80:83], v[172:175], v[204:207], v[80:83]
	v_mfma_f32_16x16x32_bf16 v[68:71], v[148:151], v[212:215], v[68:71]
	v_mfma_f32_16x16x32_bf16 v[64:67], v[172:175], v[212:215], v[64:67]
	s_barrier
	s_add_i32 s36, s56, s68
	v_lshl_add_u64 v[184:185], s[46:47], 0, v[154:155]
	s_mov_b32 m0, s36
	ds_read_b128 v[176:179], v191 offset:16384
	ds_read_b128 v[180:183], v191 offset:17408
	ds_read_b128 v[192:195], v191 offset:18432
	ds_read_b128 v[196:199], v191 offset:19456
	ds_read_b128 v[200:203], v191 offset:20480
	ds_read_b128 v[204:207], v191 offset:21504
	ds_read_b128 v[208:211], v191 offset:22528
	ds_read_b128 v[212:215], v191 offset:23552
	global_load_lds_dwordx4 v[184:185], off
	s_add_i32 m0, s36, 0x2000
	s_add_u32 s36, s46, 0xb0000
	v_lshl_add_u64 v[216:217], s[46:47], 0, v[158:159]
	s_addc_u32 s37, s47, 0
	s_add_i32 s63, s57, s68
	global_load_lds_dwordx4 v[216:217], off
	v_lshl_add_u64 v[218:219], s[36:37], 0, v[154:155]
	s_mov_b32 m0, s63
	v_lshl_add_u64 v[220:221], s[48:49], 0, v[156:157]
	global_load_lds_dwordx4 v[218:219], off
	v_lshl_add_u64 v[218:219], s[36:37], 0, v[158:159]
	s_add_i32 m0, s63, 0x2000
	s_nop 0
	global_load_lds_dwordx4 v[218:219], off
	v_lshl_add_u64 v[218:219], s[48:49], 0, v[152:153]
	s_mov_b32 m0, s74
	s_nop 0
	global_load_lds_dwordx4 v[218:219], off
	s_mov_b32 m0, s41
	s_nop 0
	global_load_lds_dwordx4 v[220:221], off
	s_waitcnt vmcnt(8)
	s_waitcnt lgkmcnt(0)
	s_barrier
; #define PG8_STAGE(bufoff, gbase, voff) do { _Pragma("unroll") for (int _i = 0; _i < 2; ++_i) \
;         __builtin_amdgcn_global_load_lds((const unsigned*)((const char*)(gbase) + (voff)[_i]), (PG8_LAS unsigned*)(lds + (bufoff) + ldsw + _i * 8192), 16, 0, 0); } while (0)
; #define PG8_LDA(dst, b, h) do { _Pragma("unroll") for (int m = 0; m < 4; ++m) _Pragma("unroll") for (int k = 0; k < 2; ++k) dst[m][k] = *(const PG8_LAS bf16x8*)(lds + PG8_SA(b, h) + aoff + m * 2048 + k * 1024); } while (0)
; #define PG8_LDB(dst, b, h) do { _Pragma("unroll") for (int n = 0; n < 2; ++n) _Pragma("unroll") for (int k = 0; k < 2; ++k) dst[n][k] = *(const PG8_LAS bf16x8*)(lds + PG8_SB(b, h) + boff + n * 2048 + k * 1024); } while (0)
; #define PG8_MMA(ai, bj, At, Bt) do { __builtin_amdgcn_s_setprio(1); _Pragma("unroll") for (int m = 0; m < 4; ++m) _Pragma("unroll") for (int n = 0; n < 2; ++n) _Pragma("unroll") for (int k = 0; k < 2; ++k) \
;         acc[ai][bj][m][n] = mma16<F16>(Bt[n][k], At[m][k], acc[ai][bj][m][n]); __builtin_amdgcn_s_setprio(0); } while (0)
; #define PG8_WAIT_V(n) asm volatile("s_waitcnt vmcnt(" #n ")" ::: "memory")
; #define PG8_WAIT_L(n) asm volatile("s_waitcnt lgkmcnt(" #n ")" ::: "memory")
; #define PG8_BAR __builtin_amdgcn_s_barrier()
; #define PG8_SCHED __builtin_amdgcn_sched_barrier(0)
; template <class Epi, class Sched, bool ALIGN_EPI = false, bool SP2 = false, bool F16 = false>
; __device__ __forceinline__ void gemm_phase(PG8_LAS unsigned char* lds, const Gemm g, const Sched& S, const Epi& E, const int wid_in) {
;     ...
;             PG8_WAIT_V(8); PG8_WAIT_L(0); PG8_BAR; PG8_MMA(1, 0, At, B0); PG8_MMA(1, 1, At, B1); PG8_BAR; PG8_SCHED;
;             PG8_LDB(B0, 1, 0); PG8_LDB(B1, 1, 1); PG8_SCHED; PG8_LDA(At, 1, 0); PG8_STAGE(PG8_SA(0, 1), a2 + hstep, voffA);
;             PG8_WAIT_V(8); PG8_WAIT_L(0); PG8_BAR; PG8_MMA(0, 0, At, B0); PG8_MMA(0, 1, At, B1); PG8_BAR; PG8_SCHED;
	v_mfma_f32_16x16x32_bf16 v[60:63], v[128:131], v[176:179], v[60:63]
	v_mfma_f32_16x16x32_bf16 v[56:59], v[136:139], v[176:179], v[56:59]
	v_mfma_f32_16x16x32_bf16 v[44:47], v[128:131], v[192:195], v[44:47]
	v_mfma_f32_16x16x32_bf16 v[40:43], v[136:139], v[192:195], v[40:43]
	v_mfma_f32_16x16x32_bf16 v[28:31], v[128:131], v[200:203], v[28:31]
	v_mfma_f32_16x16x32_bf16 v[24:27], v[136:139], v[200:203], v[24:27]
	v_mfma_f32_16x16x32_bf16 v[12:15], v[128:131], v[208:211], v[12:15]
	v_mfma_f32_16x16x32_bf16 v[8:11], v[136:139], v[208:211], v[8:11]
	v_mfma_f32_16x16x32_bf16 v[60:63], v[132:135], v[180:183], v[60:63]
	v_mfma_f32_16x16x32_bf16 v[56:59], v[140:143], v[180:183], v[56:59]
	v_mfma_f32_16x16x32_bf16 v[44:47], v[132:135], v[196:199], v[44:47]
	v_mfma_f32_16x16x32_bf16 v[40:43], v[140:143], v[196:199], v[40:43]
	v_mfma_f32_16x16x32_bf16 v[28:31], v[132:135], v[204:207], v[28:31]
	v_mfma_f32_16x16x32_bf16 v[24:27], v[140:143], v[204:207], v[24:27]
	v_mfma_f32_16x16x32_bf16 v[12:15], v[132:135], v[212:215], v[12:15]
	v_mfma_f32_16x16x32_bf16 v[8:11], v[140:143], v[212:215], v[8:11]
	v_mfma_f32_16x16x32_bf16 v[52:55], v[144:147], v[176:179], v[52:55]
	v_mfma_f32_16x16x32_bf16 v[48:51], v[168:171], v[176:179], v[48:51]
	v_mfma_f32_16x16x32_bf16 v[36:39], v[144:147], v[192:195], v[36:39]
	v_mfma_f32_16x16x32_bf16 v[32:35], v[168:171], v[192:195], v[32:35]
	v_mfma_f32_16x16x32_bf16 v[20:23], v[144:147], v[200:203], v[20:23]
	v_mfma_f32_16x16x32_bf16 v[16:19], v[168:171], v[200:203], v[16:19]
	v_mfma_f32_16x16x32_bf16 v[4:7], v[144:147], v[208:211], v[4:7]
	v_mfma_f32_16x16x32_bf16 v[0:3], v[168:171], v[208:211], v[0:3]
	v_mfma_f32_16x16x32_bf16 v[52:55], v[148:151], v[180:183], v[52:55]
	v_mfma_f32_16x16x32_bf16 v[48:51], v[172:175], v[180:183], v[48:51]
	v_mfma_f32_16x16x32_bf16 v[36:39], v[148:151], v[196:199], v[36:39]
	v_mfma_f32_16x16x32_bf16 v[32:35], v[172:175], v[196:199], v[32:35]
	v_mfma_f32_16x16x32_bf16 v[20:23], v[148:151], v[204:207], v[20:23]
	v_mfma_f32_16x16x32_bf16 v[16:19], v[172:175], v[204:207], v[16:19]
	v_mfma_f32_16x16x32_bf16 v[4:7], v[148:151], v[212:215], v[4:7]
	v_mfma_f32_16x16x32_bf16 v[0:3], v[172:175], v[212:215], v[0:3]
	s_barrier
	s_add_i32 s63, 0, 0x18000
	s_add_i32 s64, 0, 0x1c000
	v_add_u32_e32 v140, s63, v188
	v_add_u32_e32 v172, s64, v188
	ds_read_b128 v[128:131], v140
	ds_read_b128 v[132:135], v140 offset:1024
	ds_read_b128 v[136:139], v140 offset:2048
	ds_read_b128 v[140:143], v140 offset:3072
	ds_read_b128 v[144:147], v172
	ds_read_b128 v[148:151], v172 offset:1024
	ds_read_b128 v[168:171], v172 offset:2048
	ds_read_b128 v[172:175], v172 offset:3072
	s_add_u32 s36, s48, 0xb0000
	s_addc_u32 s37, s49, 0
	s_mov_b32 m0, s50
	v_lshl_add_u64 v[222:223], s[36:37], 0, v[152:153]
	ds_read_b128 v[176:179], v191 offset:32768
	ds_read_b128 v[180:183], v191 offset:33792
	ds_read_b128 v[192:195], v191 offset:34816
	ds_read_b128 v[196:199], v191 offset:35840
	ds_read_b128 v[200:203], v191 offset:36864
	ds_read_b128 v[204:207], v191 offset:37888
	ds_read_b128 v[208:211], v191 offset:38912
	ds_read_b128 v[212:215], v191 offset:39936
	global_load_lds_dwordx4 v[222:223], off
	v_lshl_add_u64 v[222:223], s[36:37], 0, v[156:157]
	s_mov_b32 m0, s51
	s_nop 0
	global_load_lds_dwordx4 v[222:223], off
	s_waitcnt vmcnt(8)
	s_waitcnt lgkmcnt(0)
	s_barrier
	v_mfma_f32_16x16x32_bf16 v[124:127], v[128:131], v[176:179], v[124:127]
	v_mfma_f32_16x16x32_bf16 v[120:123], v[136:139], v[176:179], v[120:123]
	v_mfma_f32_16x16x32_bf16 v[108:111], v[128:131], v[192:195], v[108:111]
	v_mfma_f32_16x16x32_bf16 v[104:107], v[136:139], v[192:195], v[104:107]
	v_mfma_f32_16x16x32_bf16 v[92:95], v[128:131], v[200:203], v[92:95]
	v_mfma_f32_16x16x32_bf16 v[88:91], v[136:139], v[200:203], v[88:91]
	v_mfma_f32_16x16x32_bf16 v[76:79], v[128:131], v[208:211], v[76:79]
	v_mfma_f32_16x16x32_bf16 v[72:75], v[136:139], v[208:211], v[72:75]
	v_mfma_f32_16x16x32_bf16 v[124:127], v[132:135], v[180:183], v[124:127]
	v_mfma_f32_16x16x32_bf16 v[120:123], v[140:143], v[180:183], v[120:123]
	v_mfma_f32_16x16x32_bf16 v[108:111], v[132:135], v[196:199], v[108:111]
	v_mfma_f32_16x16x32_bf16 v[104:107], v[140:143], v[196:199], v[104:107]
	v_mfma_f32_16x16x32_bf16 v[92:95], v[132:135], v[204:207], v[92:95]
	v_mfma_f32_16x16x32_bf16 v[88:91], v[140:143], v[204:207], v[88:91]
	v_mfma_f32_16x16x32_bf16 v[76:79], v[132:135], v[212:215], v[76:79]
	v_mfma_f32_16x16x32_bf16 v[72:75], v[140:143], v[212:215], v[72:75]
	v_mfma_f32_16x16x32_bf16 v[116:119], v[144:147], v[176:179], v[116:119]
	v_mfma_f32_16x16x32_bf16 v[112:115], v[168:171], v[176:179], v[112:115]
	v_mfma_f32_16x16x32_bf16 v[100:103], v[144:147], v[192:195], v[100:103]
	v_mfma_f32_16x16x32_bf16 v[96:99], v[168:171], v[192:195], v[96:99]
	v_mfma_f32_16x16x32_bf16 v[84:87], v[144:147], v[200:203], v[84:87]
	v_mfma_f32_16x16x32_bf16 v[80:83], v[168:171], v[200:203], v[80:83]
	v_mfma_f32_16x16x32_bf16 v[68:71], v[144:147], v[208:211], v[68:71]
	v_mfma_f32_16x16x32_bf16 v[64:67], v[168:171], v[208:211], v[64:67]
	v_mfma_f32_16x16x32_bf16 v[116:119], v[148:151], v[180:183], v[116:119]
	v_mfma_f32_16x16x32_bf16 v[112:115], v[172:175], v[180:183], v[112:115]
	v_mfma_f32_16x16x32_bf16 v[100:103], v[148:151], v[196:199], v[100:103]
	v_mfma_f32_16x16x32_bf16 v[96:99], v[172:175], v[196:199], v[96:99]
	v_mfma_f32_16x16x32_bf16 v[84:87], v[148:151], v[204:207], v[84:87]
	v_mfma_f32_16x16x32_bf16 v[80:83], v[172:175], v[204:207], v[80:83]
	v_mfma_f32_16x16x32_bf16 v[68:71], v[148:151], v[212:215], v[68:71]
	v_mfma_f32_16x16x32_bf16 v[64:67], v[172:175], v[212:215], v[64:67]
	s_barrier
; #define PG8_STAGE(bufoff, gbase, voff) do { _Pragma("unroll") for (int _i = 0; _i < 2; ++_i) \
;         __builtin_amdgcn_global_load_lds((const unsigned*)((const char*)(gbase) + (voff)[_i]), (PG8_LAS unsigned*)(lds + (bufoff) + ldsw + _i * 8192), 16, 0, 0); } while (0)
; #define PG8_LDA(dst, b, h) do { _Pragma("unroll") for (int m = 0; m < 4; ++m) _Pragma("unroll") for (int k = 0; k < 2; ++k) dst[m][k] = *(const PG8_LAS bf16x8*)(lds + PG8_SA(b, h) + aoff + m * 2048 + k * 1024); } while (0)
; #define PG8_MMA(ai, bj, At, Bt) do { __builtin_amdgcn_s_setprio(1); _Pragma("unroll") for (int m = 0; m < 4; ++m) _Pragma("unroll") for (int n = 0; n < 2; ++n) _Pragma("unroll") for (int k = 0; k < 2; ++k) \
;         acc[ai][bj][m][n] = mma16<F16>(Bt[n][k], At[m][k], acc[ai][bj][m][n]); __builtin_amdgcn_s_setprio(0); } while (0)
; #define PG8_WAIT_V(n) asm volatile("s_waitcnt vmcnt(" #n ")" ::: "memory")
; #define PG8_WAIT_L(n) asm volatile("s_waitcnt lgkmcnt(" #n ")" ::: "memory")
; #define PG8_BAR __builtin_amdgcn_s_barrier()
; #define PG8_SCHED __builtin_amdgcn_sched_barrier(0)
; template <class Epi, class Sched, bool ALIGN_EPI = false, bool SP2 = false, bool F16 = false>
; __device__ __forceinline__ void gemm_phase(PG8_LAS unsigned char* lds, const Gemm g, const Sched& S, const Epi& E, const int wid_in) {
;     ...
;         for (int t = 0; t < nt; t += 2) {
;     ...
;             PG8_LDA(At, 1, 1); PG8_STAGE(PG8_SB(1, 0), b3, voffB); PG8_STAGE(PG8_SB(1, 1), b3 + hstep, voffB); PG8_STAGE(PG8_SA(1, 0), a3, voffA);
;             PG8_WAIT_V(8); PG8_WAIT_L(0); PG8_BAR; PG8_MMA(1, 0, At, B0); PG8_MMA(1, 1, At, B1); PG8_BAR; PG8_SCHED;
;     ...
;         if constexpr (ALIGN_EPI) { if (wr == 0) PG8_BAR; }
	s_add_i32 s36, s63, s68
	v_lshl_add_u64 v[184:185], v[184:185], 0, s[30:31]
	s_mov_b32 m0, s36
	ds_read_b128 v[176:179], v191 offset:49152
	ds_read_b128 v[180:183], v191 offset:50176
	ds_read_b128 v[192:195], v191 offset:51200
	ds_read_b128 v[196:199], v191 offset:52224
	ds_read_b128 v[200:203], v191 offset:53248
	ds_read_b128 v[204:207], v191 offset:54272
	ds_read_b128 v[208:211], v191 offset:55296
	ds_read_b128 v[212:215], v191 offset:56320
	global_load_lds_dwordx4 v[184:185], off
	s_add_i32 m0, s36, 0x2000
	s_add_u32 s36, s46, 0xb0080
	v_lshl_add_u64 v[184:185], v[216:217], 0, s[30:31]
	s_addc_u32 s37, s47, 0
	s_add_i32 s46, s64, s68
	global_load_lds_dwordx4 v[184:185], off
	v_lshl_add_u64 v[184:185], s[36:37], 0, v[154:155]
	s_mov_b32 m0, s46
	s_nop 0
	global_load_lds_dwordx4 v[184:185], off
	v_lshl_add_u64 v[184:185], s[36:37], 0, v[158:159]
	s_add_i32 m0, s46, 0x2000
	s_nop 0
	global_load_lds_dwordx4 v[184:185], off
	v_lshl_add_u64 v[184:185], v[218:219], 0, s[30:31]
	s_mov_b32 m0, s75
	s_nop 0
	global_load_lds_dwordx4 v[184:185], off
	v_lshl_add_u64 v[184:185], v[220:221], 0, s[30:31]
	s_mov_b32 m0, s52
	s_nop 0
	global_load_lds_dwordx4 v[184:185], off
	s_waitcnt vmcnt(8)
	s_waitcnt lgkmcnt(0)
	s_barrier
	v_mfma_f32_16x16x32_bf16 v[60:63], v[128:131], v[176:179], v[60:63]
	v_mfma_f32_16x16x32_bf16 v[56:59], v[136:139], v[176:179], v[56:59]
	v_mfma_f32_16x16x32_bf16 v[44:47], v[128:131], v[192:195], v[44:47]
	v_mfma_f32_16x16x32_bf16 v[40:43], v[136:139], v[192:195], v[40:43]
	v_mfma_f32_16x16x32_bf16 v[28:31], v[128:131], v[200:203], v[28:31]
	v_mfma_f32_16x16x32_bf16 v[24:27], v[136:139], v[200:203], v[24:27]
	v_mfma_f32_16x16x32_bf16 v[12:15], v[128:131], v[208:211], v[12:15]
	v_mfma_f32_16x16x32_bf16 v[8:11], v[136:139], v[208:211], v[8:11]
	v_mfma_f32_16x16x32_bf16 v[60:63], v[132:135], v[180:183], v[60:63]
	v_mfma_f32_16x16x32_bf16 v[56:59], v[140:143], v[180:183], v[56:59]
	v_mfma_f32_16x16x32_bf16 v[44:47], v[132:135], v[196:199], v[44:47]
	v_mfma_f32_16x16x32_bf16 v[40:43], v[140:143], v[196:199], v[40:43]
	v_mfma_f32_16x16x32_bf16 v[28:31], v[132:135], v[204:207], v[28:31]
	v_mfma_f32_16x16x32_bf16 v[24:27], v[140:143], v[204:207], v[24:27]
	v_mfma_f32_16x16x32_bf16 v[12:15], v[132:135], v[212:215], v[12:15]
	v_mfma_f32_16x16x32_bf16 v[8:11], v[140:143], v[212:215], v[8:11]
	v_mfma_f32_16x16x32_bf16 v[52:55], v[144:147], v[176:179], v[52:55]
	v_mfma_f32_16x16x32_bf16 v[48:51], v[168:171], v[176:179], v[48:51]
	v_mfma_f32_16x16x32_bf16 v[36:39], v[144:147], v[192:195], v[36:39]
	v_mfma_f32_16x16x32_bf16 v[32:35], v[168:171], v[192:195], v[32:35]
	v_mfma_f32_16x16x32_bf16 v[20:23], v[144:147], v[200:203], v[20:23]
	v_mfma_f32_16x16x32_bf16 v[16:19], v[168:171], v[200:203], v[16:19]
	v_mfma_f32_16x16x32_bf16 v[4:7], v[144:147], v[208:211], v[4:7]
	v_mfma_f32_16x16x32_bf16 v[0:3], v[168:171], v[208:211], v[0:3]
	v_mfma_f32_16x16x32_bf16 v[52:55], v[148:151], v[180:183], v[52:55]
	v_mfma_f32_16x16x32_bf16 v[48:51], v[172:175], v[180:183], v[48:51]
	v_mfma_f32_16x16x32_bf16 v[36:39], v[148:151], v[196:199], v[36:39]
	v_mfma_f32_16x16x32_bf16 v[32:35], v[172:175], v[196:199], v[32:35]
	v_mfma_f32_16x16x32_bf16 v[20:23], v[148:151], v[204:207], v[20:23]
	v_mfma_f32_16x16x32_bf16 v[16:19], v[172:175], v[204:207], v[16:19]
	v_mfma_f32_16x16x32_bf16 v[4:7], v[148:151], v[212:215], v[4:7]
	v_mfma_f32_16x16x32_bf16 v[0:3], v[172:175], v[212:215], v[0:3]
	s_barrier
	s_add_i32 s62, s62, 2
	s_add_u32 s43, s43, 0x100
	s_addc_u32 s61, s61, 0
	s_cmp_gt_u32 s62, 41
	s_mov_b64 s[36:37], s[44:45]
	s_cbranch_scc0 .LBB0_1373
	s_and_b64 vcc, exec, s[16:17]
	s_cbranch_vccz .LBB0_1376
	s_barrier

; #define PG8_STAGE(bufoff, gbase, voff) do { _Pragma("unroll") for (int _i = 0; _i < 2; ++_i) \
;         __builtin_amdgcn_global_load_lds((const unsigned*)((const char*)(gbase) + (voff)[_i]), (PG8_LAS unsigned*)(lds + (bufoff) + ldsw + _i * 8192), 16, 0, 0); } while (0)
; #define PG8_LDA(dst, b, h) do { _Pragma("unroll") for (int m = 0; m < 4; ++m) _Pragma("unroll") for (int k = 0; k < 2; ++k) dst[m][k] = *(const PG8_LAS bf16x8*)(lds + PG8_SA(b, h) + aoff + m * 2048 + k * 1024); } while (0)
; #define PG8_LDB(dst, b, h) do { _Pragma("unroll") for (int n = 0; n < 2; ++n) _Pragma("unroll") for (int k = 0; k < 2; ++k) dst[n][k] = *(const PG8_LAS bf16x8*)(lds + PG8_SB(b, h) + boff + n * 2048 + k * 1024); } while (0)
; #define PG8_MMA(ai, bj, At, Bt) do { __builtin_amdgcn_s_setprio(1); _Pragma("unroll") for (int m = 0; m < 4; ++m) _Pragma("unroll") for (int n = 0; n < 2; ++n) _Pragma("unroll") for (int k = 0; k < 2; ++k) \
;         acc[ai][bj][m][n] = mma16<F16>(Bt[n][k], At[m][k], acc[ai][bj][m][n]); __builtin_amdgcn_s_setprio(0); } while (0)
; #define PG8_WAIT_V(n) asm volatile("s_waitcnt vmcnt(" #n ")" ::: "memory")
; #define PG8_BAR __builtin_amdgcn_s_barrier()
; template <class Epi, class Sched, bool ALIGN_EPI = false, bool SP2 = false, bool F16 = false>
; __device__ __forceinline__ void gemm_phase(PG8_LAS unsigned char* lds, const Gemm g, const Sched& S, const Epi& E, const int wid_in) {
;     ...
;         for (int t = 0; t < nt; t += 2) {
;             const bool last = (t == nt - 2);
;             const char* a1 = cA + (size_t)(t + 1) * kstep;
;             const char* a2 = last ? nA : cA + (size_t)(t + 2) * kstep; const char* b2 = last ? nB : cB + (size_t)(t + 2) * kstep;
;             const char* a3 = a2 + kstep; const char* b3 = b2 + kstep;
;             if (last && has_next) S.a_ready(nxt);
;             if constexpr (SP2) {
;             PG8_LDB(B0, 0, 0); PG8_LDB(B1, 0, 1); PG8_SCHED; PG8_LDA(At, 0, 0); PG8_STAGE(PG8_SA(1, 1), a1 + hstep, voffA);
;             PG8_WAIT_V(8); PG8_WAIT_L(0); PG8_BAR; PG8_MMA(0, 0, At, B0); PG8_MMA(0, 1, At, B1); PG8_BAR; PG8_SCHED;
;             PG8_LDA(At, 0, 1); PG8_STAGE(PG8_SB(0, 0), b2, voffB); PG8_STAGE(PG8_SB(0, 1), b2 + hstep, voffB); PG8_STAGE(PG8_SA(0, 0), a2, voffA);
;             PG8_WAIT_V(8); PG8_WAIT_L(0); PG8_BAR; PG8_MMA(1, 0, At, B0); PG8_MMA(1, 1, At, B1); PG8_BAR; PG8_SCHED;
.LBB0_1469:
	ds_read_b128 v[112:115], v235
	ds_read_b128 v[116:119], v235 offset:1024
	ds_read_b128 v[128:131], v235 offset:2048
	ds_read_b128 v[132:135], v235 offset:3072
	ds_read_b128 v[144:147], v236
	ds_read_b128 v[148:151], v236 offset:1024
	ds_read_b128 v[152:155], v236 offset:2048
	ds_read_b128 v[156:159], v236 offset:3072
	s_add_u32 s45, s52, 0xfffc0080
	s_addc_u32 s51, s53, -1
	s_cmp_eq_u32 s43, 12
	s_cselect_b32 s57, s14, s51
	s_cselect_b32 s56, s15, s45
	s_cselect_b32 s55, s37, s42
	s_cselect_b32 s54, s40, s41
	v_lshl_add_u64 v[192:193], s[52:53], 0, v[204:205]
	s_add_i32 m0, s74, 0xc000
	ds_read_b128 v[160:163], v237
	ds_read_b128 v[164:167], v237 offset:1024
	ds_read_b128 v[168:171], v237 offset:2048
	ds_read_b128 v[172:175], v237 offset:3072
	ds_read_b128 v[176:179], v237 offset:4096
	ds_read_b128 v[180:183], v237 offset:5120
	ds_read_b128 v[184:187], v237 offset:6144
	ds_read_b128 v[188:191], v237 offset:7168
	global_load_lds_dwordx4 v[192:193], off
	v_lshl_add_u64 v[192:193], s[52:53], 0, v[206:207]
	s_add_i32 m0, s74, 0xe000
	s_nop 0
	global_load_lds_dwordx4 v[192:193], off
	s_waitcnt vmcnt(8)
	s_waitcnt lgkmcnt(0)
	s_barrier
	v_mfma_f32_16x16x32_f16 v[140:143], v[112:115], v[160:163], v[140:143]
	v_mfma_f32_16x16x32_f16 v[136:139], v[128:131], v[160:163], v[136:139]
	v_mfma_f32_16x16x32_f16 v[108:111], v[112:115], v[168:171], v[108:111]
	v_mfma_f32_16x16x32_f16 v[104:107], v[128:131], v[168:171], v[104:107]
	v_mfma_f32_16x16x32_f16 v[92:95], v[112:115], v[176:179], v[92:95]
	v_mfma_f32_16x16x32_f16 v[88:91], v[128:131], v[176:179], v[88:91]
	v_mfma_f32_16x16x32_f16 v[76:79], v[112:115], v[184:187], v[76:79]
	v_mfma_f32_16x16x32_f16 v[72:75], v[128:131], v[184:187], v[72:75]
	v_mfma_f32_16x16x32_f16 v[140:143], v[116:119], v[164:167], v[140:143]
	v_mfma_f32_16x16x32_f16 v[136:139], v[132:135], v[164:167], v[136:139]
	v_mfma_f32_16x16x32_f16 v[108:111], v[116:119], v[172:175], v[108:111]
	v_mfma_f32_16x16x32_f16 v[104:107], v[132:135], v[172:175], v[104:107]
	v_mfma_f32_16x16x32_f16 v[92:95], v[116:119], v[180:183], v[92:95]
	v_mfma_f32_16x16x32_f16 v[88:91], v[132:135], v[180:183], v[88:91]
	v_mfma_f32_16x16x32_f16 v[76:79], v[116:119], v[188:191], v[76:79]
	v_mfma_f32_16x16x32_f16 v[72:75], v[132:135], v[188:191], v[72:75]
	v_mfma_f32_16x16x32_f16 v[124:127], v[144:147], v[160:163], v[124:127]
	v_mfma_f32_16x16x32_f16 v[120:123], v[152:155], v[160:163], v[120:123]
	v_mfma_f32_16x16x32_f16 v[100:103], v[144:147], v[168:171], v[100:103]
	v_mfma_f32_16x16x32_f16 v[96:99], v[152:155], v[168:171], v[96:99]
	v_mfma_f32_16x16x32_f16 v[84:87], v[144:147], v[176:179], v[84:87]
	v_mfma_f32_16x16x32_f16 v[80:83], v[152:155], v[176:179], v[80:83]
	v_mfma_f32_16x16x32_f16 v[68:71], v[144:147], v[184:187], v[68:71]
	v_mfma_f32_16x16x32_f16 v[64:67], v[152:155], v[184:187], v[64:67]
	v_mfma_f32_16x16x32_f16 v[124:127], v[148:151], v[164:167], v[124:127]
	v_mfma_f32_16x16x32_f16 v[120:123], v[156:159], v[164:167], v[120:123]
	v_mfma_f32_16x16x32_f16 v[100:103], v[148:151], v[172:175], v[100:103]
	v_mfma_f32_16x16x32_f16 v[96:99], v[156:159], v[172:175], v[96:99]
	v_mfma_f32_16x16x32_f16 v[84:87], v[148:151], v[180:183], v[84:87]
	v_mfma_f32_16x16x32_f16 v[80:83], v[156:159], v[180:183], v[80:83]
	v_mfma_f32_16x16x32_f16 v[68:71], v[148:151], v[188:191], v[68:71]
	v_mfma_f32_16x16x32_f16 v[64:67], v[156:159], v[188:191], v[64:67]
	s_barrier
	s_add_i32 s45, s66, s68
	v_lshl_add_u64 v[192:193], s[54:55], 0, v[198:199]
	s_mov_b32 m0, s45
	ds_read_b128 v[160:163], v237 offset:16384
	ds_read_b128 v[164:167], v237 offset:17408
	ds_read_b128 v[168:171], v237 offset:18432
	ds_read_b128 v[172:175], v237 offset:19456
	ds_read_b128 v[176:179], v237 offset:20480
	ds_read_b128 v[180:183], v237 offset:21504
	ds_read_b128 v[184:187], v237 offset:22528
	ds_read_b128 v[188:191], v237 offset:23552
	global_load_lds_dwordx4 v[192:193], off
	s_add_i32 m0, s45, 0x2000
	s_add_u32 s94, s54, 0x40000
	v_lshl_add_u64 v[194:195], s[54:55], 0, v[202:203]
	s_addc_u32 s95, s55, 0
	s_add_i32 s45, s67, s68
	global_load_lds_dwordx4 v[194:195], off
	v_lshl_add_u64 v[212:213], s[94:95], 0, v[198:199]
	s_mov_b32 m0, s45
	v_lshl_add_u64 v[214:215], s[56:57], 0, v[200:201]
	global_load_lds_dwordx4 v[212:213], off
	v_lshl_add_u64 v[212:213], s[94:95], 0, v[202:203]
	s_add_i32 m0, s45, 0x2000
	s_nop 0
	global_load_lds_dwordx4 v[212:213], off
	v_lshl_add_u64 v[212:213], s[56:57], 0, v[196:197]
	s_mov_b32 m0, s74
	s_nop 0
	global_load_lds_dwordx4 v[212:213], off
	s_mov_b32 m0, s59
	s_nop 0
	global_load_lds_dwordx4 v[214:215], off
	s_waitcnt vmcnt(8)
	s_waitcnt lgkmcnt(0)
	s_barrier
; #define PG8_STAGE(bufoff, gbase, voff) do { _Pragma("unroll") for (int _i = 0; _i < 2; ++_i) \
;         __builtin_amdgcn_global_load_lds((const unsigned*)((const char*)(gbase) + (voff)[_i]), (PG8_LAS unsigned*)(lds + (bufoff) + ldsw + _i * 8192), 16, 0, 0); } while (0)
; #define PG8_LDA(dst, b, h) do { _Pragma("unroll") for (int m = 0; m < 4; ++m) _Pragma("unroll") for (int k = 0; k < 2; ++k) dst[m][k] = *(const PG8_LAS bf16x8*)(lds + PG8_SA(b, h) + aoff + m * 2048 + k * 1024); } while (0)
; #define PG8_LDB(dst, b, h) do { _Pragma("unroll") for (int n = 0; n < 2; ++n) _Pragma("unroll") for (int k = 0; k < 2; ++k) dst[n][k] = *(const PG8_LAS bf16x8*)(lds + PG8_SB(b, h) + boff + n * 2048 + k * 1024); } while (0)
; #define PG8_MMA(ai, bj, At, Bt) do { __builtin_amdgcn_s_setprio(1); _Pragma("unroll") for (int m = 0; m < 4; ++m) _Pragma("unroll") for (int n = 0; n < 2; ++n) _Pragma("unroll") for (int k = 0; k < 2; ++k) \
;         acc[ai][bj][m][n] = mma16<F16>(Bt[n][k], At[m][k], acc[ai][bj][m][n]); __builtin_amdgcn_s_setprio(0); } while (0)
; #define PG8_WAIT_V(n) asm volatile("s_waitcnt vmcnt(" #n ")" ::: "memory")
; #define PG8_WAIT_L(n) asm volatile("s_waitcnt lgkmcnt(" #n ")" ::: "memory")
; #define PG8_BAR __builtin_amdgcn_s_barrier()
; #define PG8_SCHED __builtin_amdgcn_sched_barrier(0)
; template <class Epi, class Sched, bool ALIGN_EPI = false, bool SP2 = false, bool F16 = false>
; __device__ __forceinline__ void gemm_phase(PG8_LAS unsigned char* lds, const Gemm g, const Sched& S, const Epi& E, const int wid_in) {
;     ...
;             PG8_WAIT_V(8); PG8_WAIT_L(0); PG8_BAR; PG8_MMA(1, 0, At, B0); PG8_MMA(1, 1, At, B1); PG8_BAR; PG8_SCHED;
;             PG8_LDB(B0, 1, 0); PG8_LDB(B1, 1, 1); PG8_SCHED; PG8_LDA(At, 1, 0); PG8_STAGE(PG8_SA(0, 1), a2 + hstep, voffA);
;             PG8_WAIT_V(8); PG8_WAIT_L(0); PG8_BAR; PG8_MMA(0, 0, At, B0); PG8_MMA(0, 1, At, B1); PG8_BAR; PG8_SCHED;
	v_mfma_f32_16x16x32_f16 v[60:63], v[112:115], v[160:163], v[60:63]
	v_mfma_f32_16x16x32_f16 v[56:59], v[128:131], v[160:163], v[56:59]
	v_mfma_f32_16x16x32_f16 v[44:47], v[112:115], v[168:171], v[44:47]
	v_mfma_f32_16x16x32_f16 v[40:43], v[128:131], v[168:171], v[40:43]
	v_mfma_f32_16x16x32_f16 v[28:31], v[112:115], v[176:179], v[28:31]
	v_mfma_f32_16x16x32_f16 v[24:27], v[128:131], v[176:179], v[24:27]
	v_mfma_f32_16x16x32_f16 v[12:15], v[112:115], v[184:187], v[12:15]
	v_mfma_f32_16x16x32_f16 v[8:11], v[128:131], v[184:187], v[8:11]
	v_mfma_f32_16x16x32_f16 v[60:63], v[116:119], v[164:167], v[60:63]
	v_mfma_f32_16x16x32_f16 v[56:59], v[132:135], v[164:167], v[56:59]
	v_mfma_f32_16x16x32_f16 v[44:47], v[116:119], v[172:175], v[44:47]
	v_mfma_f32_16x16x32_f16 v[40:43], v[132:135], v[172:175], v[40:43]
	v_mfma_f32_16x16x32_f16 v[28:31], v[116:119], v[180:183], v[28:31]
	v_mfma_f32_16x16x32_f16 v[24:27], v[132:135], v[180:183], v[24:27]
	v_mfma_f32_16x16x32_f16 v[12:15], v[116:119], v[188:191], v[12:15]
	v_mfma_f32_16x16x32_f16 v[8:11], v[132:135], v[188:191], v[8:11]
	v_mfma_f32_16x16x32_f16 v[52:55], v[144:147], v[160:163], v[52:55]
	v_mfma_f32_16x16x32_f16 v[48:51], v[152:155], v[160:163], v[48:51]
	v_mfma_f32_16x16x32_f16 v[36:39], v[144:147], v[168:171], v[36:39]
	v_mfma_f32_16x16x32_f16 v[32:35], v[152:155], v[168:171], v[32:35]
	v_mfma_f32_16x16x32_f16 v[20:23], v[144:147], v[176:179], v[20:23]
	v_mfma_f32_16x16x32_f16 v[16:19], v[152:155], v[176:179], v[16:19]
	v_mfma_f32_16x16x32_f16 v[4:7], v[144:147], v[184:187], v[4:7]
	v_mfma_f32_16x16x32_f16 v[0:3], v[152:155], v[184:187], v[0:3]
	v_mfma_f32_16x16x32_f16 v[52:55], v[148:151], v[164:167], v[52:55]
	v_mfma_f32_16x16x32_f16 v[48:51], v[156:159], v[164:167], v[48:51]
	v_mfma_f32_16x16x32_f16 v[36:39], v[148:151], v[172:175], v[36:39]
	v_mfma_f32_16x16x32_f16 v[32:35], v[156:159], v[172:175], v[32:35]
	v_mfma_f32_16x16x32_f16 v[20:23], v[148:151], v[180:183], v[20:23]
	v_mfma_f32_16x16x32_f16 v[16:19], v[156:159], v[180:183], v[16:19]
	v_mfma_f32_16x16x32_f16 v[4:7], v[148:151], v[188:191], v[4:7]
	v_mfma_f32_16x16x32_f16 v[0:3], v[156:159], v[188:191], v[0:3]
	s_barrier
	s_add_i32 s45, 0, 0x18000
	s_add_i32 s51, 0, 0x1c000
	v_add_u32_e32 v132, s45, v234
	v_add_u32_e32 v156, s51, v234
	ds_read_b128 v[112:115], v132
	ds_read_b128 v[116:119], v132 offset:1024
	ds_read_b128 v[128:131], v132 offset:2048
	ds_read_b128 v[132:135], v132 offset:3072
	ds_read_b128 v[144:147], v156
	ds_read_b128 v[148:151], v156 offset:1024
	ds_read_b128 v[152:155], v156 offset:2048
	ds_read_b128 v[156:159], v156 offset:3072
	s_add_u32 s56, s56, 0x40000
	s_addc_u32 s57, s57, 0
	s_mov_b32 m0, s60
	v_lshl_add_u64 v[216:217], s[56:57], 0, v[196:197]
	ds_read_b128 v[160:163], v237 offset:32768
	ds_read_b128 v[164:167], v237 offset:33792
	ds_read_b128 v[168:171], v237 offset:34816
	ds_read_b128 v[172:175], v237 offset:35840
	ds_read_b128 v[176:179], v237 offset:36864
	ds_read_b128 v[180:183], v237 offset:37888
	ds_read_b128 v[184:187], v237 offset:38912
	ds_read_b128 v[188:191], v237 offset:39936
	global_load_lds_dwordx4 v[216:217], off
	v_lshl_add_u64 v[216:217], s[56:57], 0, v[200:201]
	s_mov_b32 m0, s61
	s_nop 0
	global_load_lds_dwordx4 v[216:217], off
	s_waitcnt vmcnt(8)
	s_waitcnt lgkmcnt(0)
	s_barrier
	v_mfma_f32_16x16x32_f16 v[140:143], v[112:115], v[160:163], v[140:143]
	v_mfma_f32_16x16x32_f16 v[136:139], v[128:131], v[160:163], v[136:139]
	v_mfma_f32_16x16x32_f16 v[108:111], v[112:115], v[168:171], v[108:111]
	v_mfma_f32_16x16x32_f16 v[104:107], v[128:131], v[168:171], v[104:107]
	v_mfma_f32_16x16x32_f16 v[92:95], v[112:115], v[176:179], v[92:95]
	v_mfma_f32_16x16x32_f16 v[88:91], v[128:131], v[176:179], v[88:91]
	v_mfma_f32_16x16x32_f16 v[76:79], v[112:115], v[184:187], v[76:79]
	v_mfma_f32_16x16x32_f16 v[72:75], v[128:131], v[184:187], v[72:75]
	v_mfma_f32_16x16x32_f16 v[140:143], v[116:119], v[164:167], v[140:143]
	v_mfma_f32_16x16x32_f16 v[136:139], v[132:135], v[164:167], v[136:139]
	v_mfma_f32_16x16x32_f16 v[108:111], v[116:119], v[172:175], v[108:111]
	v_mfma_f32_16x16x32_f16 v[104:107], v[132:135], v[172:175], v[104:107]
	v_mfma_f32_16x16x32_f16 v[92:95], v[116:119], v[180:183], v[92:95]
	v_mfma_f32_16x16x32_f16 v[88:91], v[132:135], v[180:183], v[88:91]
	v_mfma_f32_16x16x32_f16 v[76:79], v[116:119], v[188:191], v[76:79]
	v_mfma_f32_16x16x32_f16 v[72:75], v[132:135], v[188:191], v[72:75]
	v_mfma_f32_16x16x32_f16 v[124:127], v[144:147], v[160:163], v[124:127]
	v_mfma_f32_16x16x32_f16 v[120:123], v[152:155], v[160:163], v[120:123]
	v_mfma_f32_16x16x32_f16 v[100:103], v[144:147], v[168:171], v[100:103]
	v_mfma_f32_16x16x32_f16 v[96:99], v[152:155], v[168:171], v[96:99]
	v_mfma_f32_16x16x32_f16 v[84:87], v[144:147], v[176:179], v[84:87]
	v_mfma_f32_16x16x32_f16 v[80:83], v[152:155], v[176:179], v[80:83]
	v_mfma_f32_16x16x32_f16 v[68:71], v[144:147], v[184:187], v[68:71]
	v_mfma_f32_16x16x32_f16 v[64:67], v[152:155], v[184:187], v[64:67]
	v_mfma_f32_16x16x32_f16 v[124:127], v[148:151], v[164:167], v[124:127]
	v_mfma_f32_16x16x32_f16 v[120:123], v[156:159], v[164:167], v[120:123]
	v_mfma_f32_16x16x32_f16 v[100:103], v[148:151], v[172:175], v[100:103]
	v_mfma_f32_16x16x32_f16 v[96:99], v[156:159], v[172:175], v[96:99]
	v_mfma_f32_16x16x32_f16 v[84:87], v[148:151], v[180:183], v[84:87]
	v_mfma_f32_16x16x32_f16 v[80:83], v[156:159], v[180:183], v[80:83]
	v_mfma_f32_16x16x32_f16 v[68:71], v[148:151], v[188:191], v[68:71]
	v_mfma_f32_16x16x32_f16 v[64:67], v[156:159], v[188:191], v[64:67]
	s_barrier
; #define PG8_STAGE(bufoff, gbase, voff) do { _Pragma("unroll") for (int _i = 0; _i < 2; ++_i) \
;         __builtin_amdgcn_global_load_lds((const unsigned*)((const char*)(gbase) + (voff)[_i]), (PG8_LAS unsigned*)(lds + (bufoff) + ldsw + _i * 8192), 16, 0, 0); } while (0)
; #define PG8_LDA(dst, b, h) do { _Pragma("unroll") for (int m = 0; m < 4; ++m) _Pragma("unroll") for (int k = 0; k < 2; ++k) dst[m][k] = *(const PG8_LAS bf16x8*)(lds + PG8_SA(b, h) + aoff + m * 2048 + k * 1024); } while (0)
; #define PG8_MMA(ai, bj, At, Bt) do { __builtin_amdgcn_s_setprio(1); _Pragma("unroll") for (int m = 0; m < 4; ++m) _Pragma("unroll") for (int n = 0; n < 2; ++n) _Pragma("unroll") for (int k = 0; k < 2; ++k) \
;         acc[ai][bj][m][n] = mma16<F16>(Bt[n][k], At[m][k], acc[ai][bj][m][n]); __builtin_amdgcn_s_setprio(0); } while (0)
; #define PG8_WAIT_V(n) asm volatile("s_waitcnt vmcnt(" #n ")" ::: "memory")
; #define PG8_WAIT_L(n) asm volatile("s_waitcnt lgkmcnt(" #n ")" ::: "memory")
; #define PG8_BAR __builtin_amdgcn_s_barrier()
; #define PG8_SCHED __builtin_amdgcn_sched_barrier(0)
; template <class Epi, class Sched, bool ALIGN_EPI = false, bool SP2 = false, bool F16 = false>
; __device__ __forceinline__ void gemm_phase(PG8_LAS unsigned char* lds, const Gemm g, const Sched& S, const Epi& E, const int wid_in) {
;     ...
;         for (int t = 0; t < nt; t += 2) {
;     ...
;             PG8_LDA(At, 1, 1); PG8_STAGE(PG8_SB(1, 0), b3, voffB); PG8_STAGE(PG8_SB(1, 1), b3 + hstep, voffB); PG8_STAGE(PG8_SA(1, 0), a3, voffA);
;             PG8_WAIT_V(8); PG8_WAIT_L(0); PG8_BAR; PG8_MMA(1, 0, At, B0); PG8_MMA(1, 1, At, B1); PG8_BAR; PG8_SCHED;
;     ...
;         if constexpr (ALIGN_EPI) { if (wr == 0) PG8_BAR; }
	s_add_i32 s45, s45, s68
	v_lshl_add_u64 v[192:193], v[192:193], 0, s[34:35]
	s_mov_b32 m0, s45
	ds_read_b128 v[160:163], v237 offset:49152
	ds_read_b128 v[164:167], v237 offset:50176
	ds_read_b128 v[168:171], v237 offset:51200
	ds_read_b128 v[172:175], v237 offset:52224
	ds_read_b128 v[176:179], v237 offset:53248
	ds_read_b128 v[180:183], v237 offset:54272
	ds_read_b128 v[184:187], v237 offset:55296
	ds_read_b128 v[188:191], v237 offset:56320
	global_load_lds_dwordx4 v[192:193], off
	s_add_i32 m0, s45, 0x2000
	s_add_u32 s54, s54, 0x40080
	v_lshl_add_u64 v[192:193], v[194:195], 0, s[34:35]
	s_addc_u32 s55, s55, 0
	s_add_i32 s45, s51, s68
	global_load_lds_dwordx4 v[192:193], off
	v_lshl_add_u64 v[192:193], s[54:55], 0, v[198:199]
	s_mov_b32 m0, s45
	s_nop 0
	global_load_lds_dwordx4 v[192:193], off
	v_lshl_add_u64 v[192:193], s[54:55], 0, v[202:203]
	s_add_i32 m0, s45, 0x2000
	s_nop 0
	global_load_lds_dwordx4 v[192:193], off
	v_lshl_add_u64 v[192:193], v[212:213], 0, s[34:35]
	s_mov_b32 m0, s75
	s_nop 0
	global_load_lds_dwordx4 v[192:193], off
	v_lshl_add_u64 v[192:193], v[214:215], 0, s[34:35]
	s_mov_b32 m0, s62
	s_nop 0
	global_load_lds_dwordx4 v[192:193], off
	s_waitcnt vmcnt(8)
	s_waitcnt lgkmcnt(0)
	s_barrier
	v_mfma_f32_16x16x32_f16 v[60:63], v[112:115], v[160:163], v[60:63]
	v_mfma_f32_16x16x32_f16 v[56:59], v[128:131], v[160:163], v[56:59]
	v_mfma_f32_16x16x32_f16 v[44:47], v[112:115], v[168:171], v[44:47]
	v_mfma_f32_16x16x32_f16 v[40:43], v[128:131], v[168:171], v[40:43]
	v_mfma_f32_16x16x32_f16 v[28:31], v[112:115], v[176:179], v[28:31]
	v_mfma_f32_16x16x32_f16 v[24:27], v[128:131], v[176:179], v[24:27]
	v_mfma_f32_16x16x32_f16 v[12:15], v[112:115], v[184:187], v[12:15]
	v_mfma_f32_16x16x32_f16 v[8:11], v[128:131], v[184:187], v[8:11]
	v_mfma_f32_16x16x32_f16 v[60:63], v[116:119], v[164:167], v[60:63]
	v_mfma_f32_16x16x32_f16 v[56:59], v[132:135], v[164:167], v[56:59]
	v_mfma_f32_16x16x32_f16 v[44:47], v[116:119], v[172:175], v[44:47]
	v_mfma_f32_16x16x32_f16 v[40:43], v[132:135], v[172:175], v[40:43]
	v_mfma_f32_16x16x32_f16 v[28:31], v[116:119], v[180:183], v[28:31]
	v_mfma_f32_16x16x32_f16 v[24:27], v[132:135], v[180:183], v[24:27]
	v_mfma_f32_16x16x32_f16 v[12:15], v[116:119], v[188:191], v[12:15]
	v_mfma_f32_16x16x32_f16 v[8:11], v[132:135], v[188:191], v[8:11]
	v_mfma_f32_16x16x32_f16 v[52:55], v[144:147], v[160:163], v[52:55]
	v_mfma_f32_16x16x32_f16 v[48:51], v[152:155], v[160:163], v[48:51]
	v_mfma_f32_16x16x32_f16 v[36:39], v[144:147], v[168:171], v[36:39]
	v_mfma_f32_16x16x32_f16 v[32:35], v[152:155], v[168:171], v[32:35]
	v_mfma_f32_16x16x32_f16 v[20:23], v[144:147], v[176:179], v[20:23]
	v_mfma_f32_16x16x32_f16 v[16:19], v[152:155], v[176:179], v[16:19]
	v_mfma_f32_16x16x32_f16 v[4:7], v[144:147], v[184:187], v[4:7]
	v_mfma_f32_16x16x32_f16 v[0:3], v[152:155], v[184:187], v[0:3]
	v_mfma_f32_16x16x32_f16 v[52:55], v[148:151], v[164:167], v[52:55]
	v_mfma_f32_16x16x32_f16 v[48:51], v[156:159], v[164:167], v[48:51]
	v_mfma_f32_16x16x32_f16 v[36:39], v[148:151], v[172:175], v[36:39]
	v_mfma_f32_16x16x32_f16 v[32:35], v[156:159], v[172:175], v[32:35]
	v_mfma_f32_16x16x32_f16 v[20:23], v[148:151], v[180:183], v[20:23]
	v_mfma_f32_16x16x32_f16 v[16:19], v[156:159], v[180:183], v[16:19]
	v_mfma_f32_16x16x32_f16 v[4:7], v[148:151], v[188:191], v[4:7]
	v_mfma_f32_16x16x32_f16 v[0:3], v[156:159], v[188:191], v[0:3]
	s_barrier
	s_add_i32 s43, s43, 2
	s_add_u32 s52, s52, 0x100
	s_addc_u32 s53, s53, 0
	s_add_u32 s41, s41, 0x100
	s_addc_u32 s42, s42, 0
	s_cmp_gt_u32 s43, 13
	s_cbranch_scc0 .LBB0_1469
	s_and_b64 vcc, exec, s[16:17]
	s_cbranch_vccz .LBB0_1472
	s_barrier

; #define PG8_STAGE(bufoff, gbase, voff) do { _Pragma("unroll") for (int _i = 0; _i < 2; ++_i) \
;         __builtin_amdgcn_global_load_lds((const unsigned*)((const char*)(gbase) + (voff)[_i]), (PG8_LAS unsigned*)(lds + (bufoff) + ldsw + _i * 8192), 16, 0, 0); } while (0)
; #define PG8_LDA(dst, b, h) do { _Pragma("unroll") for (int m = 0; m < 4; ++m) _Pragma("unroll") for (int k = 0; k < 2; ++k) dst[m][k] = *(const PG8_LAS bf16x8*)(lds + PG8_SA(b, h) + aoff + m * 2048 + k * 1024); } while (0)
; #define PG8_LDB(dst, b, h) do { _Pragma("unroll") for (int n = 0; n < 2; ++n) _Pragma("unroll") for (int k = 0; k < 2; ++k) dst[n][k] = *(const PG8_LAS bf16x8*)(lds + PG8_SB(b, h) + boff + n * 2048 + k * 1024); } while (0)
; #define PG8_MMA(ai, bj, At, Bt) do { __builtin_amdgcn_s_setprio(1); _Pragma("unroll") for (int m = 0; m < 4; ++m) _Pragma("unroll") for (int n = 0; n < 2; ++n) _Pragma("unroll") for (int k = 0; k < 2; ++k) \
;         acc[ai][bj][m][n] = mma16<F16>(Bt[n][k], At[m][k], acc[ai][bj][m][n]); __builtin_amdgcn_s_setprio(0); } while (0)
; #define PG8_WAIT_V(n) asm volatile("s_waitcnt vmcnt(" #n ")" ::: "memory")
; #define PG8_BAR __builtin_amdgcn_s_barrier()
; template <class Epi, class Sched, bool ALIGN_EPI = false, bool SP2 = false, bool F16 = false>
; __device__ __forceinline__ void gemm_phase(PG8_LAS unsigned char* lds, const Gemm g, const Sched& S, const Epi& E, const int wid_in) {
;     ...
;         for (int t = 0; t < nt; t += 2) {
;             const bool last = (t == nt - 2);
;             const char* a1 = cA + (size_t)(t + 1) * kstep;
;             const char* a2 = last ? nA : cA + (size_t)(t + 2) * kstep; const char* b2 = last ? nB : cB + (size_t)(t + 2) * kstep;
;             const char* a3 = a2 + kstep; const char* b3 = b2 + kstep;
;             if (last && has_next) S.a_ready(nxt);
;             if constexpr (SP2) {
;             PG8_LDB(B0, 0, 0); PG8_LDB(B1, 0, 1); PG8_SCHED; PG8_LDA(At, 0, 0); PG8_STAGE(PG8_SA(1, 1), a1 + hstep, voffA);
;             PG8_WAIT_V(8); PG8_WAIT_L(0); PG8_BAR; PG8_MMA(0, 0, At, B0); PG8_MMA(0, 1, At, B1); PG8_BAR; PG8_SCHED;
;             PG8_LDA(At, 0, 1); PG8_STAGE(PG8_SB(0, 0), b2, voffB); PG8_STAGE(PG8_SB(0, 1), b2 + hstep, voffB); PG8_STAGE(PG8_SA(0, 0), a2, voffA);
;             PG8_WAIT_V(8); PG8_WAIT_L(0); PG8_BAR; PG8_MMA(1, 0, At, B0); PG8_MMA(1, 1, At, B1); PG8_BAR; PG8_SCHED;
.LBB0_1548:
	ds_read_b128 v[128:131], v184
	ds_read_b128 v[132:135], v184 offset:1024
	ds_read_b128 v[136:139], v184 offset:2048
	ds_read_b128 v[140:143], v184 offset:3072
	ds_read_b128 v[144:147], v185
	ds_read_b128 v[148:151], v185 offset:1024
	ds_read_b128 v[152:155], v185 offset:2048
	ds_read_b128 v[174:177], v185 offset:3072
	s_add_u32 s45, s50, 0xfffc0080
	s_addc_u32 s52, s51, -1
	s_cmp_eq_u32 s43, 12
	s_cselect_b32 s55, s13, s52
	s_cselect_b32 s54, s31, s45
	s_cselect_b32 s53, s37, s42
	s_cselect_b32 s52, s40, s41
	v_lshl_add_u64 v[178:179], s[50:51], 0, v[166:167]
	s_add_i32 m0, s74, 0xc000
	ds_read_b128 v[190:193], v186
	ds_read_b128 v[194:197], v186 offset:1024
	ds_read_b128 v[198:201], v186 offset:2048
	ds_read_b128 v[202:205], v186 offset:3072
	ds_read_b128 v[206:209], v186 offset:4096
	ds_read_b128 v[210:213], v186 offset:5120
	ds_read_b128 v[214:217], v186 offset:6144
	ds_read_b128 v[218:221], v186 offset:7168
	global_load_lds_dwordx4 v[178:179], off
	v_lshl_add_u64 v[178:179], s[50:51], 0, v[168:169]
	s_add_i32 m0, s74, 0xe000
	s_nop 0
	global_load_lds_dwordx4 v[178:179], off
	s_waitcnt vmcnt(8)
	s_waitcnt lgkmcnt(0)
	s_barrier
	v_mfma_f32_16x16x32_f16 v[124:127], v[128:131], v[190:193], v[124:127]
	v_mfma_f32_16x16x32_f16 v[120:123], v[136:139], v[190:193], v[120:123]
	v_mfma_f32_16x16x32_f16 v[108:111], v[128:131], v[198:201], v[108:111]
	v_mfma_f32_16x16x32_f16 v[104:107], v[136:139], v[198:201], v[104:107]
	v_mfma_f32_16x16x32_f16 v[92:95], v[128:131], v[206:209], v[92:95]
	v_mfma_f32_16x16x32_f16 v[88:91], v[136:139], v[206:209], v[88:91]
	v_mfma_f32_16x16x32_f16 v[76:79], v[128:131], v[214:217], v[76:79]
	v_mfma_f32_16x16x32_f16 v[72:75], v[136:139], v[214:217], v[72:75]
	v_mfma_f32_16x16x32_f16 v[124:127], v[132:135], v[194:197], v[124:127]
	v_mfma_f32_16x16x32_f16 v[120:123], v[140:143], v[194:197], v[120:123]
	v_mfma_f32_16x16x32_f16 v[108:111], v[132:135], v[202:205], v[108:111]
	v_mfma_f32_16x16x32_f16 v[104:107], v[140:143], v[202:205], v[104:107]
	v_mfma_f32_16x16x32_f16 v[92:95], v[132:135], v[210:213], v[92:95]
	v_mfma_f32_16x16x32_f16 v[88:91], v[140:143], v[210:213], v[88:91]
	v_mfma_f32_16x16x32_f16 v[76:79], v[132:135], v[218:221], v[76:79]
	v_mfma_f32_16x16x32_f16 v[72:75], v[140:143], v[218:221], v[72:75]
	v_mfma_f32_16x16x32_f16 v[116:119], v[144:147], v[190:193], v[116:119]
	v_mfma_f32_16x16x32_f16 v[112:115], v[152:155], v[190:193], v[112:115]
	v_mfma_f32_16x16x32_f16 v[100:103], v[144:147], v[198:201], v[100:103]
	v_mfma_f32_16x16x32_f16 v[96:99], v[152:155], v[198:201], v[96:99]
	v_mfma_f32_16x16x32_f16 v[84:87], v[144:147], v[206:209], v[84:87]
	v_mfma_f32_16x16x32_f16 v[80:83], v[152:155], v[206:209], v[80:83]
	v_mfma_f32_16x16x32_f16 v[68:71], v[144:147], v[214:217], v[68:71]
	v_mfma_f32_16x16x32_f16 v[64:67], v[152:155], v[214:217], v[64:67]
	v_mfma_f32_16x16x32_f16 v[116:119], v[148:151], v[194:197], v[116:119]
	v_mfma_f32_16x16x32_f16 v[112:115], v[174:177], v[194:197], v[112:115]
	v_mfma_f32_16x16x32_f16 v[100:103], v[148:151], v[202:205], v[100:103]
	v_mfma_f32_16x16x32_f16 v[96:99], v[174:177], v[202:205], v[96:99]
	v_mfma_f32_16x16x32_f16 v[84:87], v[148:151], v[210:213], v[84:87]
	v_mfma_f32_16x16x32_f16 v[80:83], v[174:177], v[210:213], v[80:83]
	v_mfma_f32_16x16x32_f16 v[68:71], v[148:151], v[218:221], v[68:71]
	v_mfma_f32_16x16x32_f16 v[64:67], v[174:177], v[218:221], v[64:67]
	s_barrier
	s_add_i32 s45, s90, s68
	v_lshl_add_u64 v[178:179], s[52:53], 0, v[158:159]
	s_mov_b32 m0, s45
	ds_read_b128 v[190:193], v186 offset:16384
	ds_read_b128 v[194:197], v186 offset:17408
	ds_read_b128 v[198:201], v186 offset:18432
	ds_read_b128 v[202:205], v186 offset:19456
	ds_read_b128 v[206:209], v186 offset:20480
	ds_read_b128 v[210:213], v186 offset:21504
	ds_read_b128 v[214:217], v186 offset:22528
	ds_read_b128 v[218:221], v186 offset:23552
	global_load_lds_dwordx4 v[178:179], off
	s_add_i32 m0, s45, 0x2000
	s_add_u32 s56, s52, 0x40000
	v_lshl_add_u64 v[222:223], s[52:53], 0, v[162:163]
	s_addc_u32 s57, s53, 0
	s_add_i32 s45, s84, s68
	global_load_lds_dwordx4 v[222:223], off
	v_lshl_add_u64 v[224:225], s[56:57], 0, v[158:159]
	s_mov_b32 m0, s45
	v_lshl_add_u64 v[226:227], s[54:55], 0, v[160:161]
	global_load_lds_dwordx4 v[224:225], off
	v_lshl_add_u64 v[224:225], s[56:57], 0, v[162:163]
	s_add_i32 m0, s45, 0x2000
	s_nop 0
	global_load_lds_dwordx4 v[224:225], off
	v_lshl_add_u64 v[224:225], s[54:55], 0, v[156:157]
	s_mov_b32 m0, s74
	s_nop 0
	global_load_lds_dwordx4 v[224:225], off
	s_mov_b32 m0, s66
	s_nop 0
	global_load_lds_dwordx4 v[226:227], off
	s_waitcnt vmcnt(8)
	s_waitcnt lgkmcnt(0)
	s_barrier
; #define PG8_STAGE(bufoff, gbase, voff) do { _Pragma("unroll") for (int _i = 0; _i < 2; ++_i) \
;         __builtin_amdgcn_global_load_lds((const unsigned*)((const char*)(gbase) + (voff)[_i]), (PG8_LAS unsigned*)(lds + (bufoff) + ldsw + _i * 8192), 16, 0, 0); } while (0)
; #define PG8_LDA(dst, b, h) do { _Pragma("unroll") for (int m = 0; m < 4; ++m) _Pragma("unroll") for (int k = 0; k < 2; ++k) dst[m][k] = *(const PG8_LAS bf16x8*)(lds + PG8_SA(b, h) + aoff + m * 2048 + k * 1024); } while (0)
; #define PG8_LDB(dst, b, h) do { _Pragma("unroll") for (int n = 0; n < 2; ++n) _Pragma("unroll") for (int k = 0; k < 2; ++k) dst[n][k] = *(const PG8_LAS bf16x8*)(lds + PG8_SB(b, h) + boff + n * 2048 + k * 1024); } while (0)
; #define PG8_MMA(ai, bj, At, Bt) do { __builtin_amdgcn_s_setprio(1); _Pragma("unroll") for (int m = 0; m < 4; ++m) _Pragma("unroll") for (int n = 0; n < 2; ++n) _Pragma("unroll") for (int k = 0; k < 2; ++k) \
;         acc[ai][bj][m][n] = mma16<F16>(Bt[n][k], At[m][k], acc[ai][bj][m][n]); __builtin_amdgcn_s_setprio(0); } while (0)
; #define PG8_WAIT_V(n) asm volatile("s_waitcnt vmcnt(" #n ")" ::: "memory")
; #define PG8_WAIT_L(n) asm volatile("s_waitcnt lgkmcnt(" #n ")" ::: "memory")
; #define PG8_BAR __builtin_amdgcn_s_barrier()
; #define PG8_SCHED __builtin_amdgcn_sched_barrier(0)
; template <class Epi, class Sched, bool ALIGN_EPI = false, bool SP2 = false, bool F16 = false>
; __device__ __forceinline__ void gemm_phase(PG8_LAS unsigned char* lds, const Gemm g, const Sched& S, const Epi& E, const int wid_in) {
;     ...
;             PG8_WAIT_V(8); PG8_WAIT_L(0); PG8_BAR; PG8_MMA(1, 0, At, B0); PG8_MMA(1, 1, At, B1); PG8_BAR; PG8_SCHED;
;             PG8_LDB(B0, 1, 0); PG8_LDB(B1, 1, 1); PG8_SCHED; PG8_LDA(At, 1, 0); PG8_STAGE(PG8_SA(0, 1), a2 + hstep, voffA);
;             PG8_WAIT_V(8); PG8_WAIT_L(0); PG8_BAR; PG8_MMA(0, 0, At, B0); PG8_MMA(0, 1, At, B1); PG8_BAR; PG8_SCHED;
	v_mfma_f32_16x16x32_f16 v[60:63], v[128:131], v[190:193], v[60:63]
	v_mfma_f32_16x16x32_f16 v[56:59], v[136:139], v[190:193], v[56:59]
	v_mfma_f32_16x16x32_f16 v[44:47], v[128:131], v[198:201], v[44:47]
	v_mfma_f32_16x16x32_f16 v[40:43], v[136:139], v[198:201], v[40:43]
	v_mfma_f32_16x16x32_f16 v[28:31], v[128:131], v[206:209], v[28:31]
	v_mfma_f32_16x16x32_f16 v[24:27], v[136:139], v[206:209], v[24:27]
	v_mfma_f32_16x16x32_f16 v[12:15], v[128:131], v[214:217], v[12:15]
	v_mfma_f32_16x16x32_f16 v[8:11], v[136:139], v[214:217], v[8:11]
	v_mfma_f32_16x16x32_f16 v[60:63], v[132:135], v[194:197], v[60:63]
	v_mfma_f32_16x16x32_f16 v[56:59], v[140:143], v[194:197], v[56:59]
	v_mfma_f32_16x16x32_f16 v[44:47], v[132:135], v[202:205], v[44:47]
	v_mfma_f32_16x16x32_f16 v[40:43], v[140:143], v[202:205], v[40:43]
	v_mfma_f32_16x16x32_f16 v[28:31], v[132:135], v[210:213], v[28:31]
	v_mfma_f32_16x16x32_f16 v[24:27], v[140:143], v[210:213], v[24:27]
	v_mfma_f32_16x16x32_f16 v[12:15], v[132:135], v[218:221], v[12:15]
	v_mfma_f32_16x16x32_f16 v[8:11], v[140:143], v[218:221], v[8:11]
	v_mfma_f32_16x16x32_f16 v[52:55], v[144:147], v[190:193], v[52:55]
	v_mfma_f32_16x16x32_f16 v[48:51], v[152:155], v[190:193], v[48:51]
	v_mfma_f32_16x16x32_f16 v[36:39], v[144:147], v[198:201], v[36:39]
	v_mfma_f32_16x16x32_f16 v[32:35], v[152:155], v[198:201], v[32:35]
	v_mfma_f32_16x16x32_f16 v[20:23], v[144:147], v[206:209], v[20:23]
	v_mfma_f32_16x16x32_f16 v[16:19], v[152:155], v[206:209], v[16:19]
	v_mfma_f32_16x16x32_f16 v[4:7], v[144:147], v[214:217], v[4:7]
	v_mfma_f32_16x16x32_f16 v[0:3], v[152:155], v[214:217], v[0:3]
	v_mfma_f32_16x16x32_f16 v[52:55], v[148:151], v[194:197], v[52:55]
	v_mfma_f32_16x16x32_f16 v[48:51], v[174:177], v[194:197], v[48:51]
	v_mfma_f32_16x16x32_f16 v[36:39], v[148:151], v[202:205], v[36:39]
	v_mfma_f32_16x16x32_f16 v[32:35], v[174:177], v[202:205], v[32:35]
	v_mfma_f32_16x16x32_f16 v[20:23], v[148:151], v[210:213], v[20:23]
	v_mfma_f32_16x16x32_f16 v[16:19], v[174:177], v[210:213], v[16:19]
	v_mfma_f32_16x16x32_f16 v[4:7], v[148:151], v[218:221], v[4:7]
	v_mfma_f32_16x16x32_f16 v[0:3], v[174:177], v[218:221], v[0:3]
	s_barrier
	s_add_i32 s45, 0, 0x18000
	s_add_i32 s56, 0, 0x1c000
	v_add_u32_e32 v140, s45, v183
	v_add_u32_e32 v165, s56, v183
	ds_read_b128 v[128:131], v140
	ds_read_b128 v[132:135], v140 offset:1024
	ds_read_b128 v[136:139], v140 offset:2048
	ds_read_b128 v[140:143], v140 offset:3072
	ds_read_b128 v[144:147], v165
	ds_read_b128 v[148:151], v165 offset:1024
	ds_read_b128 v[152:155], v165 offset:2048
	ds_read_b128 v[174:177], v165 offset:3072
	s_add_u32 s54, s54, 0x40000
	s_addc_u32 s55, s55, 0
	s_mov_b32 m0, s67
	v_lshl_add_u64 v[228:229], s[54:55], 0, v[156:157]
	ds_read_b128 v[190:193], v186 offset:32768
	ds_read_b128 v[194:197], v186 offset:33792
	ds_read_b128 v[198:201], v186 offset:34816
	ds_read_b128 v[202:205], v186 offset:35840
	ds_read_b128 v[206:209], v186 offset:36864
	ds_read_b128 v[210:213], v186 offset:37888
	ds_read_b128 v[214:217], v186 offset:38912
	ds_read_b128 v[218:221], v186 offset:39936
	global_load_lds_dwordx4 v[228:229], off
	v_lshl_add_u64 v[228:229], s[54:55], 0, v[160:161]
	s_mov_b32 m0, s91
	s_nop 0
	global_load_lds_dwordx4 v[228:229], off
	s_waitcnt vmcnt(8)
	s_waitcnt lgkmcnt(0)
	s_barrier
	v_mfma_f32_16x16x32_f16 v[124:127], v[128:131], v[190:193], v[124:127]
	v_mfma_f32_16x16x32_f16 v[120:123], v[136:139], v[190:193], v[120:123]
	v_mfma_f32_16x16x32_f16 v[108:111], v[128:131], v[198:201], v[108:111]
	v_mfma_f32_16x16x32_f16 v[104:107], v[136:139], v[198:201], v[104:107]
	v_mfma_f32_16x16x32_f16 v[92:95], v[128:131], v[206:209], v[92:95]
	v_mfma_f32_16x16x32_f16 v[88:91], v[136:139], v[206:209], v[88:91]
	v_mfma_f32_16x16x32_f16 v[76:79], v[128:131], v[214:217], v[76:79]
	v_mfma_f32_16x16x32_f16 v[72:75], v[136:139], v[214:217], v[72:75]
	v_mfma_f32_16x16x32_f16 v[124:127], v[132:135], v[194:197], v[124:127]
	v_mfma_f32_16x16x32_f16 v[120:123], v[140:143], v[194:197], v[120:123]
	v_mfma_f32_16x16x32_f16 v[108:111], v[132:135], v[202:205], v[108:111]
	v_mfma_f32_16x16x32_f16 v[104:107], v[140:143], v[202:205], v[104:107]
	v_mfma_f32_16x16x32_f16 v[92:95], v[132:135], v[210:213], v[92:95]
	v_mfma_f32_16x16x32_f16 v[88:91], v[140:143], v[210:213], v[88:91]
	v_mfma_f32_16x16x32_f16 v[76:79], v[132:135], v[218:221], v[76:79]
	v_mfma_f32_16x16x32_f16 v[72:75], v[140:143], v[218:221], v[72:75]
	v_mfma_f32_16x16x32_f16 v[116:119], v[144:147], v[190:193], v[116:119]
	v_mfma_f32_16x16x32_f16 v[112:115], v[152:155], v[190:193], v[112:115]
	v_mfma_f32_16x16x32_f16 v[100:103], v[144:147], v[198:201], v[100:103]
	v_mfma_f32_16x16x32_f16 v[96:99], v[152:155], v[198:201], v[96:99]
	v_mfma_f32_16x16x32_f16 v[84:87], v[144:147], v[206:209], v[84:87]
	v_mfma_f32_16x16x32_f16 v[80:83], v[152:155], v[206:209], v[80:83]
	v_mfma_f32_16x16x32_f16 v[68:71], v[144:147], v[214:217], v[68:71]
	v_mfma_f32_16x16x32_f16 v[64:67], v[152:155], v[214:217], v[64:67]
	v_mfma_f32_16x16x32_f16 v[116:119], v[148:151], v[194:197], v[116:119]
	v_mfma_f32_16x16x32_f16 v[112:115], v[174:177], v[194:197], v[112:115]
	v_mfma_f32_16x16x32_f16 v[100:103], v[148:151], v[202:205], v[100:103]
	v_mfma_f32_16x16x32_f16 v[96:99], v[174:177], v[202:205], v[96:99]
	v_mfma_f32_16x16x32_f16 v[84:87], v[148:151], v[210:213], v[84:87]
	v_mfma_f32_16x16x32_f16 v[80:83], v[174:177], v[210:213], v[80:83]
	v_mfma_f32_16x16x32_f16 v[68:71], v[148:151], v[218:221], v[68:71]
	v_mfma_f32_16x16x32_f16 v[64:67], v[174:177], v[218:221], v[64:67]
	s_barrier
; #define PG8_STAGE(bufoff, gbase, voff) do { _Pragma("unroll") for (int _i = 0; _i < 2; ++_i) \
;         __builtin_amdgcn_global_load_lds((const unsigned*)((const char*)(gbase) + (voff)[_i]), (PG8_LAS unsigned*)(lds + (bufoff) + ldsw + _i * 8192), 16, 0, 0); } while (0)
; #define PG8_LDA(dst, b, h) do { _Pragma("unroll") for (int m = 0; m < 4; ++m) _Pragma("unroll") for (int k = 0; k < 2; ++k) dst[m][k] = *(const PG8_LAS bf16x8*)(lds + PG8_SA(b, h) + aoff + m * 2048 + k * 1024); } while (0)
; #define PG8_MMA(ai, bj, At, Bt) do { __builtin_amdgcn_s_setprio(1); _Pragma("unroll") for (int m = 0; m < 4; ++m) _Pragma("unroll") for (int n = 0; n < 2; ++n) _Pragma("unroll") for (int k = 0; k < 2; ++k) \
;         acc[ai][bj][m][n] = mma16<F16>(Bt[n][k], At[m][k], acc[ai][bj][m][n]); __builtin_amdgcn_s_setprio(0); } while (0)
; #define PG8_WAIT_V(n) asm volatile("s_waitcnt vmcnt(" #n ")" ::: "memory")
; #define PG8_WAIT_L(n) asm volatile("s_waitcnt lgkmcnt(" #n ")" ::: "memory")
; #define PG8_BAR __builtin_amdgcn_s_barrier()
; #define PG8_SCHED __builtin_amdgcn_sched_barrier(0)
; template <class Epi, class Sched, bool ALIGN_EPI = false, bool SP2 = false, bool F16 = false>
; __device__ __forceinline__ void gemm_phase(PG8_LAS unsigned char* lds, const Gemm g, const Sched& S, const Epi& E, const int wid_in) {
;     ...
;         for (int t = 0; t < nt; t += 2) {
;     ...
;             PG8_LDA(At, 1, 1); PG8_STAGE(PG8_SB(1, 0), b3, voffB); PG8_STAGE(PG8_SB(1, 1), b3 + hstep, voffB); PG8_STAGE(PG8_SA(1, 0), a3, voffA);
;             PG8_WAIT_V(8); PG8_WAIT_L(0); PG8_BAR; PG8_MMA(1, 0, At, B0); PG8_MMA(1, 1, At, B1); PG8_BAR; PG8_SCHED;
;     ...
;         if constexpr (ALIGN_EPI) { if (wr == 0) PG8_BAR; }
	s_add_i32 s45, s45, s68
	v_lshl_add_u64 v[178:179], v[178:179], 0, s[34:35]
	s_mov_b32 m0, s45
	ds_read_b128 v[190:193], v186 offset:49152
	ds_read_b128 v[194:197], v186 offset:50176
	ds_read_b128 v[198:201], v186 offset:51200
	ds_read_b128 v[202:205], v186 offset:52224
	ds_read_b128 v[206:209], v186 offset:53248
	ds_read_b128 v[210:213], v186 offset:54272
	ds_read_b128 v[214:217], v186 offset:55296
	ds_read_b128 v[218:221], v186 offset:56320
	global_load_lds_dwordx4 v[178:179], off
	s_add_i32 m0, s45, 0x2000
	s_add_u32 s52, s52, 0x40080
	v_lshl_add_u64 v[178:179], v[222:223], 0, s[34:35]
	s_addc_u32 s53, s53, 0
	s_add_i32 s45, s56, s68
	global_load_lds_dwordx4 v[178:179], off
	v_lshl_add_u64 v[178:179], s[52:53], 0, v[158:159]
	s_mov_b32 m0, s45
	s_nop 0
	global_load_lds_dwordx4 v[178:179], off
	v_lshl_add_u64 v[178:179], s[52:53], 0, v[162:163]
	s_add_i32 m0, s45, 0x2000
	s_nop 0
	global_load_lds_dwordx4 v[178:179], off
	v_lshl_add_u64 v[178:179], v[224:225], 0, s[34:35]
	s_mov_b32 m0, s75
	s_nop 0
	global_load_lds_dwordx4 v[178:179], off
	v_lshl_add_u64 v[178:179], v[226:227], 0, s[34:35]
	s_mov_b32 m0, s97
	s_nop 0
	global_load_lds_dwordx4 v[178:179], off
	s_waitcnt vmcnt(8)
	s_waitcnt lgkmcnt(0)
	s_barrier
	v_mfma_f32_16x16x32_f16 v[60:63], v[128:131], v[190:193], v[60:63]
	v_mfma_f32_16x16x32_f16 v[56:59], v[136:139], v[190:193], v[56:59]
	v_mfma_f32_16x16x32_f16 v[44:47], v[128:131], v[198:201], v[44:47]
	v_mfma_f32_16x16x32_f16 v[40:43], v[136:139], v[198:201], v[40:43]
	v_mfma_f32_16x16x32_f16 v[28:31], v[128:131], v[206:209], v[28:31]
	v_mfma_f32_16x16x32_f16 v[24:27], v[136:139], v[206:209], v[24:27]
	v_mfma_f32_16x16x32_f16 v[12:15], v[128:131], v[214:217], v[12:15]
	v_mfma_f32_16x16x32_f16 v[8:11], v[136:139], v[214:217], v[8:11]
	v_mfma_f32_16x16x32_f16 v[60:63], v[132:135], v[194:197], v[60:63]
	v_mfma_f32_16x16x32_f16 v[56:59], v[140:143], v[194:197], v[56:59]
	v_mfma_f32_16x16x32_f16 v[44:47], v[132:135], v[202:205], v[44:47]
	v_mfma_f32_16x16x32_f16 v[40:43], v[140:143], v[202:205], v[40:43]
	v_mfma_f32_16x16x32_f16 v[28:31], v[132:135], v[210:213], v[28:31]
	v_mfma_f32_16x16x32_f16 v[24:27], v[140:143], v[210:213], v[24:27]
	v_mfma_f32_16x16x32_f16 v[12:15], v[132:135], v[218:221], v[12:15]
	v_mfma_f32_16x16x32_f16 v[8:11], v[140:143], v[218:221], v[8:11]
	v_mfma_f32_16x16x32_f16 v[52:55], v[144:147], v[190:193], v[52:55]
	v_mfma_f32_16x16x32_f16 v[48:51], v[152:155], v[190:193], v[48:51]
	v_mfma_f32_16x16x32_f16 v[36:39], v[144:147], v[198:201], v[36:39]
	v_mfma_f32_16x16x32_f16 v[32:35], v[152:155], v[198:201], v[32:35]
	v_mfma_f32_16x16x32_f16 v[20:23], v[144:147], v[206:209], v[20:23]
	v_mfma_f32_16x16x32_f16 v[16:19], v[152:155], v[206:209], v[16:19]
	v_mfma_f32_16x16x32_f16 v[4:7], v[144:147], v[214:217], v[4:7]
	v_mfma_f32_16x16x32_f16 v[0:3], v[152:155], v[214:217], v[0:3]
	v_mfma_f32_16x16x32_f16 v[52:55], v[148:151], v[194:197], v[52:55]
	v_mfma_f32_16x16x32_f16 v[48:51], v[174:177], v[194:197], v[48:51]
	v_mfma_f32_16x16x32_f16 v[36:39], v[148:151], v[202:205], v[36:39]
	v_mfma_f32_16x16x32_f16 v[32:35], v[174:177], v[202:205], v[32:35]
	v_mfma_f32_16x16x32_f16 v[20:23], v[148:151], v[210:213], v[20:23]
	v_mfma_f32_16x16x32_f16 v[16:19], v[174:177], v[210:213], v[16:19]
	v_mfma_f32_16x16x32_f16 v[4:7], v[148:151], v[218:221], v[4:7]
	v_mfma_f32_16x16x32_f16 v[0:3], v[174:177], v[218:221], v[0:3]
	s_barrier
	s_add_i32 s43, s43, 2
	s_add_u32 s50, s50, 0x100
	s_addc_u32 s51, s51, 0
	s_add_u32 s41, s41, 0x100
	s_addc_u32 s42, s42, 0
	s_cmp_gt_u32 s43, 13
	s_cbranch_scc0 .LBB0_1548
	s_and_b64 vcc, exec, s[16:17]
	s_cbranch_vccz .LBB0_1551
	s_barrier

; #define PG8_STAGE(bufoff, gbase, voff) do { _Pragma("unroll") for (int _i = 0; _i < 2; ++_i) \
;         __builtin_amdgcn_global_load_lds((const unsigned*)((const char*)(gbase) + (voff)[_i]), (PG8_LAS unsigned*)(lds + (bufoff) + ldsw + _i * 8192), 16, 0, 0); } while (0)
; #define PG8_LDA(dst, b, h) do { _Pragma("unroll") for (int m = 0; m < 4; ++m) _Pragma("unroll") for (int k = 0; k < 2; ++k) dst[m][k] = *(const PG8_LAS bf16x8*)(lds + PG8_SA(b, h) + aoff + m * 2048 + k * 1024); } while (0)
; #define PG8_LDB(dst, b, h) do { _Pragma("unroll") for (int n = 0; n < 2; ++n) _Pragma("unroll") for (int k = 0; k < 2; ++k) dst[n][k] = *(const PG8_LAS bf16x8*)(lds + PG8_SB(b, h) + boff + n * 2048 + k * 1024); } while (0)
; #define PG8_MMA(ai, bj, At, Bt) do { __builtin_amdgcn_s_setprio(1); _Pragma("unroll") for (int m = 0; m < 4; ++m) _Pragma("unroll") for (int n = 0; n < 2; ++n) _Pragma("unroll") for (int k = 0; k < 2; ++k) \
;         acc[ai][bj][m][n] = mma16<F16>(Bt[n][k], At[m][k], acc[ai][bj][m][n]); __builtin_amdgcn_s_setprio(0); } while (0)
; #define PG8_WAIT_V(n) asm volatile("s_waitcnt vmcnt(" #n ")" ::: "memory")
; #define PG8_BAR __builtin_amdgcn_s_barrier()
; template <class Epi, class Sched, bool ALIGN_EPI = false, bool SP2 = false, bool F16 = false>
; __device__ __forceinline__ void gemm_phase(PG8_LAS unsigned char* lds, const Gemm g, const Sched& S, const Epi& E, const int wid_in) {
;     ...
;         for (int t = 0; t < nt; t += 2) {
;             const bool last = (t == nt - 2);
;             const char* a1 = cA + (size_t)(t + 1) * kstep;
;             const char* a2 = last ? nA : cA + (size_t)(t + 2) * kstep; const char* b2 = last ? nB : cB + (size_t)(t + 2) * kstep;
;             const char* a3 = a2 + kstep; const char* b3 = b2 + kstep;
;             if (last && has_next) S.a_ready(nxt);
;             if constexpr (SP2) {
;             PG8_LDB(B0, 0, 0); PG8_LDB(B1, 0, 1); PG8_SCHED; PG8_LDA(At, 0, 0); PG8_STAGE(PG8_SA(1, 1), a1 + hstep, voffA);
;             PG8_WAIT_V(8); PG8_WAIT_L(0); PG8_BAR; PG8_MMA(0, 0, At, B0); PG8_MMA(0, 1, At, B1); PG8_BAR; PG8_SCHED;
;             PG8_LDA(At, 0, 1); PG8_STAGE(PG8_SB(0, 0), b2, voffB); PG8_STAGE(PG8_SB(0, 1), b2 + hstep, voffB); PG8_STAGE(PG8_SA(0, 0), a2, voffA);
;             PG8_WAIT_V(8); PG8_WAIT_L(0); PG8_BAR; PG8_MMA(1, 0, At, B0); PG8_MMA(1, 1, At, B1); PG8_BAR; PG8_SCHED;
.LBB0_1832:
	ds_read_b128 v[128:131], v189
	ds_read_b128 v[132:135], v189 offset:1024
	ds_read_b128 v[136:139], v189 offset:2048
	ds_read_b128 v[140:143], v189 offset:3072
	ds_read_b128 v[144:147], v190
	ds_read_b128 v[148:151], v190 offset:1024
	ds_read_b128 v[168:171], v190 offset:2048
	ds_read_b128 v[172:175], v190 offset:3072
	s_add_u32 s50, s48, 0xfffc0080
	s_addc_u32 s51, s49, -1
	s_cmp_eq_u32 s61, 12
	s_cselect_b32 s53, s35, s51
	s_cselect_b32 s52, s42, s50
	s_cselect_b32 s51, s31, s60
	s_cselect_b32 s50, s43, s47
	s_mov_b32 m0, s91
	v_lshl_add_u64 v[184:185], s[48:49], 0, v[160:161]
	ds_read_b128 v[176:179], v191
	ds_read_b128 v[180:183], v191 offset:1024
	ds_read_b128 v[192:195], v191 offset:2048
	ds_read_b128 v[196:199], v191 offset:3072
	ds_read_b128 v[200:203], v191 offset:4096
	ds_read_b128 v[204:207], v191 offset:5120
	ds_read_b128 v[208:211], v191 offset:6144
	ds_read_b128 v[212:215], v191 offset:7168
	global_load_lds_dwordx4 v[184:185], off
	v_lshl_add_u64 v[184:185], s[48:49], 0, v[162:163]
	s_add_i32 m0, s74, 0xe000
	s_nop 0
	global_load_lds_dwordx4 v[184:185], off
	s_waitcnt vmcnt(8)
	s_waitcnt lgkmcnt(0)
	s_barrier
	v_mfma_f32_16x16x32_bf16 v[124:127], v[128:131], v[176:179], v[124:127]
	v_mfma_f32_16x16x32_bf16 v[120:123], v[136:139], v[176:179], v[120:123]
	v_mfma_f32_16x16x32_bf16 v[108:111], v[128:131], v[192:195], v[108:111]
	v_mfma_f32_16x16x32_bf16 v[104:107], v[136:139], v[192:195], v[104:107]
	v_mfma_f32_16x16x32_bf16 v[92:95], v[128:131], v[200:203], v[92:95]
	v_mfma_f32_16x16x32_bf16 v[88:91], v[136:139], v[200:203], v[88:91]
	v_mfma_f32_16x16x32_bf16 v[76:79], v[128:131], v[208:211], v[76:79]
	v_mfma_f32_16x16x32_bf16 v[72:75], v[136:139], v[208:211], v[72:75]
	v_mfma_f32_16x16x32_bf16 v[124:127], v[132:135], v[180:183], v[124:127]
	v_mfma_f32_16x16x32_bf16 v[120:123], v[140:143], v[180:183], v[120:123]
	v_mfma_f32_16x16x32_bf16 v[108:111], v[132:135], v[196:199], v[108:111]
	v_mfma_f32_16x16x32_bf16 v[104:107], v[140:143], v[196:199], v[104:107]
	v_mfma_f32_16x16x32_bf16 v[92:95], v[132:135], v[204:207], v[92:95]
	v_mfma_f32_16x16x32_bf16 v[88:91], v[140:143], v[204:207], v[88:91]
	v_mfma_f32_16x16x32_bf16 v[76:79], v[132:135], v[212:215], v[76:79]
	v_mfma_f32_16x16x32_bf16 v[72:75], v[140:143], v[212:215], v[72:75]
	v_mfma_f32_16x16x32_bf16 v[116:119], v[144:147], v[176:179], v[116:119]
	v_mfma_f32_16x16x32_bf16 v[112:115], v[168:171], v[176:179], v[112:115]
	v_mfma_f32_16x16x32_bf16 v[100:103], v[144:147], v[192:195], v[100:103]
	v_mfma_f32_16x16x32_bf16 v[96:99], v[168:171], v[192:195], v[96:99]
	v_mfma_f32_16x16x32_bf16 v[84:87], v[144:147], v[200:203], v[84:87]
	v_mfma_f32_16x16x32_bf16 v[80:83], v[168:171], v[200:203], v[80:83]
	v_mfma_f32_16x16x32_bf16 v[68:71], v[144:147], v[208:211], v[68:71]
	v_mfma_f32_16x16x32_bf16 v[64:67], v[168:171], v[208:211], v[64:67]
	v_mfma_f32_16x16x32_bf16 v[116:119], v[148:151], v[180:183], v[116:119]
	v_mfma_f32_16x16x32_bf16 v[112:115], v[172:175], v[180:183], v[112:115]
	v_mfma_f32_16x16x32_bf16 v[100:103], v[148:151], v[196:199], v[100:103]
	v_mfma_f32_16x16x32_bf16 v[96:99], v[172:175], v[196:199], v[96:99]
	v_mfma_f32_16x16x32_bf16 v[84:87], v[148:151], v[204:207], v[84:87]
	v_mfma_f32_16x16x32_bf16 v[80:83], v[172:175], v[204:207], v[80:83]
	v_mfma_f32_16x16x32_bf16 v[68:71], v[148:151], v[212:215], v[68:71]
	v_mfma_f32_16x16x32_bf16 v[64:67], v[172:175], v[212:215], v[64:67]
	s_barrier
	s_add_i32 s62, s57, s68
	v_lshl_add_u64 v[184:185], s[50:51], 0, v[154:155]
	s_mov_b32 m0, s62
	ds_read_b128 v[176:179], v191 offset:16384
	ds_read_b128 v[180:183], v191 offset:17408
	ds_read_b128 v[192:195], v191 offset:18432
	ds_read_b128 v[196:199], v191 offset:19456
	ds_read_b128 v[200:203], v191 offset:20480
	ds_read_b128 v[204:207], v191 offset:21504
	ds_read_b128 v[208:211], v191 offset:22528
	ds_read_b128 v[212:215], v191 offset:23552
	global_load_lds_dwordx4 v[184:185], off
	s_add_i32 m0, s62, 0x2000
	s_add_u32 s62, s50, 0x40000
	v_lshl_add_u64 v[216:217], s[50:51], 0, v[158:159]
	s_addc_u32 s63, s51, 0
	s_add_i32 s64, s58, s68
	global_load_lds_dwordx4 v[216:217], off
	v_lshl_add_u64 v[218:219], s[62:63], 0, v[154:155]
	s_mov_b32 m0, s64
	v_lshl_add_u64 v[220:221], s[52:53], 0, v[156:157]
	global_load_lds_dwordx4 v[218:219], off
	v_lshl_add_u64 v[218:219], s[62:63], 0, v[158:159]
	s_add_i32 m0, s64, 0x2000
	s_nop 0
	global_load_lds_dwordx4 v[218:219], off
	v_lshl_add_u64 v[218:219], s[52:53], 0, v[152:153]
	s_mov_b32 m0, s74
	s_nop 0
	global_load_lds_dwordx4 v[218:219], off
	s_mov_b32 m0, s66
	s_nop 0
	global_load_lds_dwordx4 v[220:221], off
	s_waitcnt vmcnt(8)
	s_waitcnt lgkmcnt(0)
	s_barrier
; #define PG8_STAGE(bufoff, gbase, voff) do { _Pragma("unroll") for (int _i = 0; _i < 2; ++_i) \
;         __builtin_amdgcn_global_load_lds((const unsigned*)((const char*)(gbase) + (voff)[_i]), (PG8_LAS unsigned*)(lds + (bufoff) + ldsw + _i * 8192), 16, 0, 0); } while (0)
; #define PG8_LDA(dst, b, h) do { _Pragma("unroll") for (int m = 0; m < 4; ++m) _Pragma("unroll") for (int k = 0; k < 2; ++k) dst[m][k] = *(const PG8_LAS bf16x8*)(lds + PG8_SA(b, h) + aoff + m * 2048 + k * 1024); } while (0)
; #define PG8_LDB(dst, b, h) do { _Pragma("unroll") for (int n = 0; n < 2; ++n) _Pragma("unroll") for (int k = 0; k < 2; ++k) dst[n][k] = *(const PG8_LAS bf16x8*)(lds + PG8_SB(b, h) + boff + n * 2048 + k * 1024); } while (0)
; #define PG8_MMA(ai, bj, At, Bt) do { __builtin_amdgcn_s_setprio(1); _Pragma("unroll") for (int m = 0; m < 4; ++m) _Pragma("unroll") for (int n = 0; n < 2; ++n) _Pragma("unroll") for (int k = 0; k < 2; ++k) \
;         acc[ai][bj][m][n] = mma16<F16>(Bt[n][k], At[m][k], acc[ai][bj][m][n]); __builtin_amdgcn_s_setprio(0); } while (0)
; #define PG8_WAIT_V(n) asm volatile("s_waitcnt vmcnt(" #n ")" ::: "memory")
; #define PG8_WAIT_L(n) asm volatile("s_waitcnt lgkmcnt(" #n ")" ::: "memory")
; #define PG8_BAR __builtin_amdgcn_s_barrier()
; #define PG8_SCHED __builtin_amdgcn_sched_barrier(0)
; template <class Epi, class Sched, bool ALIGN_EPI = false, bool SP2 = false, bool F16 = false>
; __device__ __forceinline__ void gemm_phase(PG8_LAS unsigned char* lds, const Gemm g, const Sched& S, const Epi& E, const int wid_in) {
;     ...
;             PG8_WAIT_V(8); PG8_WAIT_L(0); PG8_BAR; PG8_MMA(1, 0, At, B0); PG8_MMA(1, 1, At, B1); PG8_BAR; PG8_SCHED;
;             PG8_LDB(B0, 1, 0); PG8_LDB(B1, 1, 1); PG8_SCHED; PG8_LDA(At, 1, 0); PG8_STAGE(PG8_SA(0, 1), a2 + hstep, voffA);
;             PG8_WAIT_V(8); PG8_WAIT_L(0); PG8_BAR; PG8_MMA(0, 0, At, B0); PG8_MMA(0, 1, At, B1); PG8_BAR; PG8_SCHED;
	v_mfma_f32_16x16x32_bf16 v[60:63], v[128:131], v[176:179], v[60:63]
	v_mfma_f32_16x16x32_bf16 v[56:59], v[136:139], v[176:179], v[56:59]
	v_mfma_f32_16x16x32_bf16 v[44:47], v[128:131], v[192:195], v[44:47]
	v_mfma_f32_16x16x32_bf16 v[40:43], v[136:139], v[192:195], v[40:43]
	v_mfma_f32_16x16x32_bf16 v[28:31], v[128:131], v[200:203], v[28:31]
	v_mfma_f32_16x16x32_bf16 v[24:27], v[136:139], v[200:203], v[24:27]
	v_mfma_f32_16x16x32_bf16 v[12:15], v[128:131], v[208:211], v[12:15]
	v_mfma_f32_16x16x32_bf16 v[8:11], v[136:139], v[208:211], v[8:11]
	v_mfma_f32_16x16x32_bf16 v[60:63], v[132:135], v[180:183], v[60:63]
	v_mfma_f32_16x16x32_bf16 v[56:59], v[140:143], v[180:183], v[56:59]
	v_mfma_f32_16x16x32_bf16 v[44:47], v[132:135], v[196:199], v[44:47]
	v_mfma_f32_16x16x32_bf16 v[40:43], v[140:143], v[196:199], v[40:43]
	v_mfma_f32_16x16x32_bf16 v[28:31], v[132:135], v[204:207], v[28:31]
	v_mfma_f32_16x16x32_bf16 v[24:27], v[140:143], v[204:207], v[24:27]
	v_mfma_f32_16x16x32_bf16 v[12:15], v[132:135], v[212:215], v[12:15]
	v_mfma_f32_16x16x32_bf16 v[8:11], v[140:143], v[212:215], v[8:11]
	v_mfma_f32_16x16x32_bf16 v[52:55], v[144:147], v[176:179], v[52:55]
	v_mfma_f32_16x16x32_bf16 v[48:51], v[168:171], v[176:179], v[48:51]
	v_mfma_f32_16x16x32_bf16 v[36:39], v[144:147], v[192:195], v[36:39]
	v_mfma_f32_16x16x32_bf16 v[32:35], v[168:171], v[192:195], v[32:35]
	v_mfma_f32_16x16x32_bf16 v[20:23], v[144:147], v[200:203], v[20:23]
	v_mfma_f32_16x16x32_bf16 v[16:19], v[168:171], v[200:203], v[16:19]
	v_mfma_f32_16x16x32_bf16 v[4:7], v[144:147], v[208:211], v[4:7]
	v_mfma_f32_16x16x32_bf16 v[0:3], v[168:171], v[208:211], v[0:3]
	v_mfma_f32_16x16x32_bf16 v[52:55], v[148:151], v[180:183], v[52:55]
	v_mfma_f32_16x16x32_bf16 v[48:51], v[172:175], v[180:183], v[48:51]
	v_mfma_f32_16x16x32_bf16 v[36:39], v[148:151], v[196:199], v[36:39]
	v_mfma_f32_16x16x32_bf16 v[32:35], v[172:175], v[196:199], v[32:35]
	v_mfma_f32_16x16x32_bf16 v[20:23], v[148:151], v[204:207], v[20:23]
	v_mfma_f32_16x16x32_bf16 v[16:19], v[172:175], v[204:207], v[16:19]
	v_mfma_f32_16x16x32_bf16 v[4:7], v[148:151], v[212:215], v[4:7]
	v_mfma_f32_16x16x32_bf16 v[0:3], v[172:175], v[212:215], v[0:3]
	s_barrier
	s_add_i32 s62, 0, 0x18000
	s_add_i32 s63, 0, 0x1c000
	v_add_u32_e32 v140, s62, v188
	v_add_u32_e32 v172, s63, v188
	ds_read_b128 v[128:131], v140
	ds_read_b128 v[132:135], v140 offset:1024
	ds_read_b128 v[136:139], v140 offset:2048
	ds_read_b128 v[140:143], v140 offset:3072
	ds_read_b128 v[144:147], v172
	ds_read_b128 v[148:151], v172 offset:1024
	ds_read_b128 v[168:171], v172 offset:2048
	ds_read_b128 v[172:175], v172 offset:3072
	s_add_u32 s52, s52, 0x40000
	s_addc_u32 s53, s53, 0
	s_mov_b32 m0, s90
	v_lshl_add_u64 v[222:223], s[52:53], 0, v[152:153]
	ds_read_b128 v[176:179], v191 offset:32768
	ds_read_b128 v[180:183], v191 offset:33792
	ds_read_b128 v[192:195], v191 offset:34816
	ds_read_b128 v[196:199], v191 offset:35840
	ds_read_b128 v[200:203], v191 offset:36864
	ds_read_b128 v[204:207], v191 offset:37888
	ds_read_b128 v[208:211], v191 offset:38912
	ds_read_b128 v[212:215], v191 offset:39936
	global_load_lds_dwordx4 v[222:223], off
	v_lshl_add_u64 v[222:223], s[52:53], 0, v[156:157]
	s_mov_b32 m0, s41
	s_nop 0
	global_load_lds_dwordx4 v[222:223], off
	s_waitcnt vmcnt(8)
	s_waitcnt lgkmcnt(0)
	s_barrier
	v_mfma_f32_16x16x32_bf16 v[124:127], v[128:131], v[176:179], v[124:127]
	v_mfma_f32_16x16x32_bf16 v[120:123], v[136:139], v[176:179], v[120:123]
	v_mfma_f32_16x16x32_bf16 v[108:111], v[128:131], v[192:195], v[108:111]
	v_mfma_f32_16x16x32_bf16 v[104:107], v[136:139], v[192:195], v[104:107]
	v_mfma_f32_16x16x32_bf16 v[92:95], v[128:131], v[200:203], v[92:95]
	v_mfma_f32_16x16x32_bf16 v[88:91], v[136:139], v[200:203], v[88:91]
	v_mfma_f32_16x16x32_bf16 v[76:79], v[128:131], v[208:211], v[76:79]
	v_mfma_f32_16x16x32_bf16 v[72:75], v[136:139], v[208:211], v[72:75]
	v_mfma_f32_16x16x32_bf16 v[124:127], v[132:135], v[180:183], v[124:127]
	v_mfma_f32_16x16x32_bf16 v[120:123], v[140:143], v[180:183], v[120:123]
	v_mfma_f32_16x16x32_bf16 v[108:111], v[132:135], v[196:199], v[108:111]
	v_mfma_f32_16x16x32_bf16 v[104:107], v[140:143], v[196:199], v[104:107]
	v_mfma_f32_16x16x32_bf16 v[92:95], v[132:135], v[204:207], v[92:95]
	v_mfma_f32_16x16x32_bf16 v[88:91], v[140:143], v[204:207], v[88:91]
	v_mfma_f32_16x16x32_bf16 v[76:79], v[132:135], v[212:215], v[76:79]
	v_mfma_f32_16x16x32_bf16 v[72:75], v[140:143], v[212:215], v[72:75]
	v_mfma_f32_16x16x32_bf16 v[116:119], v[144:147], v[176:179], v[116:119]
	v_mfma_f32_16x16x32_bf16 v[112:115], v[168:171], v[176:179], v[112:115]
	v_mfma_f32_16x16x32_bf16 v[100:103], v[144:147], v[192:195], v[100:103]
	v_mfma_f32_16x16x32_bf16 v[96:99], v[168:171], v[192:195], v[96:99]
	v_mfma_f32_16x16x32_bf16 v[84:87], v[144:147], v[200:203], v[84:87]
	v_mfma_f32_16x16x32_bf16 v[80:83], v[168:171], v[200:203], v[80:83]
	v_mfma_f32_16x16x32_bf16 v[68:71], v[144:147], v[208:211], v[68:71]
	v_mfma_f32_16x16x32_bf16 v[64:67], v[168:171], v[208:211], v[64:67]
	v_mfma_f32_16x16x32_bf16 v[116:119], v[148:151], v[180:183], v[116:119]
	v_mfma_f32_16x16x32_bf16 v[112:115], v[172:175], v[180:183], v[112:115]
	v_mfma_f32_16x16x32_bf16 v[100:103], v[148:151], v[196:199], v[100:103]
	v_mfma_f32_16x16x32_bf16 v[96:99], v[172:175], v[196:199], v[96:99]
	v_mfma_f32_16x16x32_bf16 v[84:87], v[148:151], v[204:207], v[84:87]
	v_mfma_f32_16x16x32_bf16 v[80:83], v[172:175], v[204:207], v[80:83]
	v_mfma_f32_16x16x32_bf16 v[68:71], v[148:151], v[212:215], v[68:71]
	v_mfma_f32_16x16x32_bf16 v[64:67], v[172:175], v[212:215], v[64:67]
	s_barrier
; #define PG8_STAGE(bufoff, gbase, voff) do { _Pragma("unroll") for (int _i = 0; _i < 2; ++_i) \
;         __builtin_amdgcn_global_load_lds((const unsigned*)((const char*)(gbase) + (voff)[_i]), (PG8_LAS unsigned*)(lds + (bufoff) + ldsw + _i * 8192), 16, 0, 0); } while (0)
; #define PG8_LDA(dst, b, h) do { _Pragma("unroll") for (int m = 0; m < 4; ++m) _Pragma("unroll") for (int k = 0; k < 2; ++k) dst[m][k] = *(const PG8_LAS bf16x8*)(lds + PG8_SA(b, h) + aoff + m * 2048 + k * 1024); } while (0)
; #define PG8_BAR __builtin_amdgcn_s_barrier()
; template <class Epi, class Sched, bool ALIGN_EPI = false, bool SP2 = false, bool F16 = false>
; __device__ __forceinline__ void gemm_phase(PG8_LAS unsigned char* lds, const Gemm g, const Sched& S, const Epi& E, const int wid_in) {
;     ...
;             PG8_LDA(At, 1, 1); PG8_STAGE(PG8_SB(1, 0), b3, voffB); PG8_STAGE(PG8_SB(1, 1), b3 + hstep, voffB); PG8_STAGE(PG8_SA(1, 0), a3, voffA);
;             PG8_WAIT_V(8); PG8_WAIT_L(0); PG8_BAR; PG8_MMA(1, 0, At, B0); PG8_MMA(1, 1, At, B1); PG8_BAR; PG8_SCHED;
;             } else {
;             PG8_LDB(B0, 0, 0); PG8_SCHED; PG8_LDA(At, 0, 0); PG8_STAGE(PG8_SA(1, 1), a1 + hstep, voffA);
;             PG8_WAIT_L(8); PG8_BAR; PG8_WAIT_L(0); PG8_MMA(0, 0, At, B0); PG8_BAR; PG8_SCHED;
;             PG8_LDB(B1, 0, 1); PG8_STAGE(PG8_SB(0, 0), b2, voffB);
;             PG8_BAR; PG8_WAIT_L(0); PG8_MMA(0, 1, At, B1); PG8_BAR;
;             PG8_LDA(At, 0, 1); PG8_STAGE(PG8_SA(0, 0), a2, voffA);
;             PG8_BAR; PG8_WAIT_L(0); PG8_MMA(1, 0, At, B0); PG8_BAR; PG8_SCHED;
;             PG8_STAGE(PG8_SB(0, 1), b2 + hstep, voffB);
;             PG8_WAIT_V(6); PG8_BAR; PG8_MMA(1, 1, At, B1); PG8_BAR;
;             PG8_LDB(B0, 1, 0); PG8_SCHED; PG8_LDA(At, 1, 0); PG8_STAGE(PG8_SA(0, 1), a2 + hstep, voffA);
;             PG8_WAIT_L(8); PG8_BAR; PG8_WAIT_L(0); PG8_MMA(0, 0, At, B0); PG8_BAR; PG8_SCHED;
;             PG8_LDB(B1, 1, 1); PG8_STAGE(PG8_SB(1, 0), b3, voffB);
;             PG8_BAR; PG8_WAIT_L(0); PG8_MMA(0, 1, At, B1); PG8_BAR;
;             PG8_LDA(At, 1, 1); PG8_STAGE(PG8_SA(1, 0), a3, voffA);
;             PG8_BAR; PG8_WAIT_L(0); PG8_MMA(1, 0, At, B0); PG8_BAR; PG8_SCHED;
;             PG8_STAGE(PG8_SB(1, 1), b3 + hstep, voffB);
;             PG8_WAIT_V(6); PG8_BAR; PG8_MMA(1, 1, At, B1); PG8_BAR;
;             }
;         }
;         if constexpr (ALIGN_EPI) { if (wr == 0) PG8_BAR; }
	s_add_i32 s52, s62, s68
	v_lshl_add_u64 v[184:185], v[184:185], 0, s[28:29]
	s_mov_b32 m0, s52
	ds_read_b128 v[176:179], v191 offset:49152
	ds_read_b128 v[180:183], v191 offset:50176
	ds_read_b128 v[192:195], v191 offset:51200
	ds_read_b128 v[196:199], v191 offset:52224
	ds_read_b128 v[200:203], v191 offset:53248
	ds_read_b128 v[204:207], v191 offset:54272
	ds_read_b128 v[208:211], v191 offset:55296
	ds_read_b128 v[212:215], v191 offset:56320
	global_load_lds_dwordx4 v[184:185], off
	s_add_i32 m0, s52, 0x2000
	s_add_u32 s50, s50, 0x40080
	v_lshl_add_u64 v[184:185], v[216:217], 0, s[28:29]
	s_addc_u32 s51, s51, 0
	s_add_i32 s52, s63, s68
	global_load_lds_dwordx4 v[184:185], off
	v_lshl_add_u64 v[184:185], s[50:51], 0, v[154:155]
	s_mov_b32 m0, s52
	s_nop 0
	global_load_lds_dwordx4 v[184:185], off
	v_lshl_add_u64 v[184:185], s[50:51], 0, v[158:159]
	s_add_i32 m0, s52, 0x2000
	s_nop 0
	global_load_lds_dwordx4 v[184:185], off
	v_lshl_add_u64 v[184:185], v[218:219], 0, s[28:29]
	s_mov_b32 m0, s75
	s_nop 0
	global_load_lds_dwordx4 v[184:185], off
	v_lshl_add_u64 v[184:185], v[220:221], 0, s[28:29]
	s_mov_b32 m0, s67
	s_nop 0
	global_load_lds_dwordx4 v[184:185], off
	s_waitcnt vmcnt(8)
	s_waitcnt lgkmcnt(0)
	s_barrier
	v_mfma_f32_16x16x32_bf16 v[60:63], v[128:131], v[176:179], v[60:63]
	v_mfma_f32_16x16x32_bf16 v[56:59], v[136:139], v[176:179], v[56:59]
	v_mfma_f32_16x16x32_bf16 v[44:47], v[128:131], v[192:195], v[44:47]
	v_mfma_f32_16x16x32_bf16 v[40:43], v[136:139], v[192:195], v[40:43]
	v_mfma_f32_16x16x32_bf16 v[28:31], v[128:131], v[200:203], v[28:31]
	v_mfma_f32_16x16x32_bf16 v[24:27], v[136:139], v[200:203], v[24:27]
	v_mfma_f32_16x16x32_bf16 v[12:15], v[128:131], v[208:211], v[12:15]
	v_mfma_f32_16x16x32_bf16 v[8:11], v[136:139], v[208:211], v[8:11]
	v_mfma_f32_16x16x32_bf16 v[60:63], v[132:135], v[180:183], v[60:63]
	v_mfma_f32_16x16x32_bf16 v[56:59], v[140:143], v[180:183], v[56:59]
	v_mfma_f32_16x16x32_bf16 v[44:47], v[132:135], v[196:199], v[44:47]
	v_mfma_f32_16x16x32_bf16 v[40:43], v[140:143], v[196:199], v[40:43]
	v_mfma_f32_16x16x32_bf16 v[28:31], v[132:135], v[204:207], v[28:31]
	v_mfma_f32_16x16x32_bf16 v[24:27], v[140:143], v[204:207], v[24:27]
	v_mfma_f32_16x16x32_bf16 v[12:15], v[132:135], v[212:215], v[12:15]
	v_mfma_f32_16x16x32_bf16 v[8:11], v[140:143], v[212:215], v[8:11]
	v_mfma_f32_16x16x32_bf16 v[52:55], v[144:147], v[176:179], v[52:55]
	v_mfma_f32_16x16x32_bf16 v[48:51], v[168:171], v[176:179], v[48:51]
	v_mfma_f32_16x16x32_bf16 v[36:39], v[144:147], v[192:195], v[36:39]
	v_mfma_f32_16x16x32_bf16 v[32:35], v[168:171], v[192:195], v[32:35]
	v_mfma_f32_16x16x32_bf16 v[20:23], v[144:147], v[200:203], v[20:23]
	v_mfma_f32_16x16x32_bf16 v[16:19], v[168:171], v[200:203], v[16:19]
	v_mfma_f32_16x16x32_bf16 v[4:7], v[144:147], v[208:211], v[4:7]
	v_mfma_f32_16x16x32_bf16 v[0:3], v[168:171], v[208:211], v[0:3]
	v_mfma_f32_16x16x32_bf16 v[52:55], v[148:151], v[180:183], v[52:55]
	v_mfma_f32_16x16x32_bf16 v[48:51], v[172:175], v[180:183], v[48:51]
	v_mfma_f32_16x16x32_bf16 v[36:39], v[148:151], v[196:199], v[36:39]
	v_mfma_f32_16x16x32_bf16 v[32:35], v[172:175], v[196:199], v[32:35]
	v_mfma_f32_16x16x32_bf16 v[20:23], v[148:151], v[204:207], v[20:23]
	v_mfma_f32_16x16x32_bf16 v[16:19], v[172:175], v[204:207], v[16:19]
	v_mfma_f32_16x16x32_bf16 v[4:7], v[148:151], v[212:215], v[4:7]
	v_mfma_f32_16x16x32_bf16 v[0:3], v[172:175], v[212:215], v[0:3]
	s_barrier
	s_add_i32 s61, s61, 2
	s_add_u32 s48, s48, 0x100
	s_addc_u32 s49, s49, 0
	s_add_u32 s47, s47, 0x100
	s_addc_u32 s60, s60, 0
	s_cmp_gt_u32 s61, 13
	s_cbranch_scc0 .LBB0_1832
	s_and_b64 vcc, exec, s[16:17]
	s_cbranch_vccz .LBB0_1835
	s_barrier

; #define PG8_STAGE(bufoff, gbase, voff) do { _Pragma("unroll") for (int _i = 0; _i < 2; ++_i) \
;         __builtin_amdgcn_global_load_lds((const unsigned*)((const char*)(gbase) + (voff)[_i]), (PG8_LAS unsigned*)(lds + (bufoff) + ldsw + _i * 8192), 16, 0, 0); } while (0)
; #define PG8_LDA(dst, b, h) do { _Pragma("unroll") for (int m = 0; m < 4; ++m) _Pragma("unroll") for (int k = 0; k < 2; ++k) dst[m][k] = *(const PG8_LAS bf16x8*)(lds + PG8_SA(b, h) + aoff + m * 2048 + k * 1024); } while (0)
; #define PG8_LDB(dst, b, h) do { _Pragma("unroll") for (int n = 0; n < 2; ++n) _Pragma("unroll") for (int k = 0; k < 2; ++k) dst[n][k] = *(const PG8_LAS bf16x8*)(lds + PG8_SB(b, h) + boff + n * 2048 + k * 1024); } while (0)
; #define PG8_MMA(ai, bj, At, Bt) do { __builtin_amdgcn_s_setprio(1); _Pragma("unroll") for (int m = 0; m < 4; ++m) _Pragma("unroll") for (int n = 0; n < 2; ++n) _Pragma("unroll") for (int k = 0; k < 2; ++k) \
;         acc[ai][bj][m][n] = mma16<F16>(Bt[n][k], At[m][k], acc[ai][bj][m][n]); __builtin_amdgcn_s_setprio(0); } while (0)
; #define PG8_WAIT_V(n) asm volatile("s_waitcnt vmcnt(" #n ")" ::: "memory")
; #define PG8_WAIT_L(n) asm volatile("s_waitcnt lgkmcnt(" #n ")" ::: "memory")
; #define PG8_BAR __builtin_amdgcn_s_barrier()
; #define PG8_SCHED __builtin_amdgcn_sched_barrier(0)
; template <class Epi, class Sched, bool ALIGN_EPI = false, bool SP2 = false, bool F16 = false>
; __device__ __forceinline__ void gemm_phase(PG8_LAS unsigned char* lds, const Gemm g, const Sched& S, const Epi& E, const int wid_in) {
;     ...
;             PG8_LDB(B0, 0, 0); PG8_LDB(B1, 0, 1); PG8_SCHED; PG8_LDA(At, 0, 0); PG8_STAGE(PG8_SA(1, 1), a1 + hstep, voffA);
;             PG8_WAIT_V(8); PG8_WAIT_L(0); PG8_BAR; PG8_MMA(0, 0, At, B0); PG8_MMA(0, 1, At, B1); PG8_BAR; PG8_SCHED;
;             PG8_LDA(At, 0, 1); PG8_STAGE(PG8_SB(0, 0), b2, voffB); PG8_STAGE(PG8_SB(0, 1), b2 + hstep, voffB); PG8_STAGE(PG8_SA(0, 0), a2, voffA);
;             PG8_WAIT_V(8); PG8_WAIT_L(0); PG8_BAR; PG8_MMA(1, 0, At, B0); PG8_MMA(1, 1, At, B1); PG8_BAR; PG8_SCHED;
.LBB0_1909:
	ds_read_b128 v[0:3], v193
	ds_read_b128 v[4:7], v193 offset:1024
	ds_read_b128 v[136:139], v193 offset:2048
	ds_read_b128 v[140:143], v193 offset:3072
	ds_read_b128 v[144:147], v194
	ds_read_b128 v[148:151], v194 offset:1024
	ds_read_b128 v[152:155], v194 offset:2048
	ds_read_b128 v[156:159], v194 offset:3072
	s_add_u32 s48, s46, 0xfffc0080
	s_addc_u32 s49, s47, -1
	s_cmp_eq_u32 s64, 12
	s_cselect_b32 s51, s29, s49
	s_cselect_b32 s50, s42, s48
	s_cselect_b32 s49, s27, s63
	s_cselect_b32 s48, s43, s45
	s_mov_b32 m0, s91
	v_lshl_add_u64 v[188:189], s[46:47], 0, v[168:169]
	ds_read_b128 v[176:179], v195
	ds_read_b128 v[180:183], v195 offset:1024
	ds_read_b128 v[184:187], v195 offset:2048
	ds_read_b128 v[198:201], v195 offset:3072
	ds_read_b128 v[202:205], v195 offset:4096
	ds_read_b128 v[206:209], v195 offset:5120
	ds_read_b128 v[210:213], v195 offset:6144
	ds_read_b128 v[214:217], v195 offset:7168
	global_load_lds_dwordx4 v[188:189], off
	v_lshl_add_u64 v[188:189], s[46:47], 0, v[170:171]
	s_add_i32 m0, s74, 0xe000
	s_nop 0
	global_load_lds_dwordx4 v[188:189], off
	s_waitcnt vmcnt(8)
	s_waitcnt lgkmcnt(0)
	s_barrier
	v_mfma_f32_16x16x32_f16 v[132:135], v[0:3], v[176:179], v[132:135]
	v_mfma_f32_16x16x32_f16 v[128:131], v[136:139], v[176:179], v[128:131]
	v_mfma_f32_16x16x32_f16 v[116:119], v[0:3], v[184:187], v[116:119]
	v_mfma_f32_16x16x32_f16 v[112:115], v[136:139], v[184:187], v[112:115]
	v_mfma_f32_16x16x32_f16 v[100:103], v[0:3], v[202:205], v[100:103]
	v_mfma_f32_16x16x32_f16 v[96:99], v[136:139], v[202:205], v[96:99]
	v_mfma_f32_16x16x32_f16 v[84:87], v[0:3], v[210:213], v[84:87]
	v_mfma_f32_16x16x32_f16 v[80:83], v[136:139], v[210:213], v[80:83]
	v_mfma_f32_16x16x32_f16 v[132:135], v[4:7], v[180:183], v[132:135]
	v_mfma_f32_16x16x32_f16 v[128:131], v[140:143], v[180:183], v[128:131]
	v_mfma_f32_16x16x32_f16 v[116:119], v[4:7], v[198:201], v[116:119]
	v_mfma_f32_16x16x32_f16 v[112:115], v[140:143], v[198:201], v[112:115]
	v_mfma_f32_16x16x32_f16 v[100:103], v[4:7], v[206:209], v[100:103]
	v_mfma_f32_16x16x32_f16 v[96:99], v[140:143], v[206:209], v[96:99]
	v_mfma_f32_16x16x32_f16 v[84:87], v[4:7], v[214:217], v[84:87]
	v_mfma_f32_16x16x32_f16 v[80:83], v[140:143], v[214:217], v[80:83]
	v_mfma_f32_16x16x32_f16 v[124:127], v[144:147], v[176:179], v[124:127]
	v_mfma_f32_16x16x32_f16 v[120:123], v[152:155], v[176:179], v[120:123]
	v_mfma_f32_16x16x32_f16 v[108:111], v[144:147], v[184:187], v[108:111]
	v_mfma_f32_16x16x32_f16 v[104:107], v[152:155], v[184:187], v[104:107]
	v_mfma_f32_16x16x32_f16 v[92:95], v[144:147], v[202:205], v[92:95]
	v_mfma_f32_16x16x32_f16 v[88:91], v[152:155], v[202:205], v[88:91]
	v_mfma_f32_16x16x32_f16 v[76:79], v[144:147], v[210:213], v[76:79]
	v_mfma_f32_16x16x32_f16 v[72:75], v[152:155], v[210:213], v[72:75]
	v_mfma_f32_16x16x32_f16 v[124:127], v[148:151], v[180:183], v[124:127]
	v_mfma_f32_16x16x32_f16 v[120:123], v[156:159], v[180:183], v[120:123]
	v_mfma_f32_16x16x32_f16 v[108:111], v[148:151], v[198:201], v[108:111]
	v_mfma_f32_16x16x32_f16 v[104:107], v[156:159], v[198:201], v[104:107]
	v_mfma_f32_16x16x32_f16 v[92:95], v[148:151], v[206:209], v[92:95]
	v_mfma_f32_16x16x32_f16 v[88:91], v[156:159], v[206:209], v[88:91]
	v_mfma_f32_16x16x32_f16 v[76:79], v[148:151], v[214:217], v[76:79]
	v_mfma_f32_16x16x32_f16 v[72:75], v[156:159], v[214:217], v[72:75]
	s_barrier
	s_add_i32 s65, s60, s68
	v_lshl_add_u64 v[188:189], s[48:49], 0, v[162:163]
	s_mov_b32 m0, s65
	ds_read_b128 v[176:179], v195 offset:16384
	ds_read_b128 v[180:183], v195 offset:17408
	ds_read_b128 v[184:187], v195 offset:18432
	ds_read_b128 v[198:201], v195 offset:19456
	ds_read_b128 v[202:205], v195 offset:20480
	ds_read_b128 v[206:209], v195 offset:21504
	ds_read_b128 v[210:213], v195 offset:22528
	ds_read_b128 v[214:217], v195 offset:23552
	global_load_lds_dwordx4 v[188:189], off
	s_add_i32 m0, s65, 0x2000
	s_add_u32 s84, s48, 0x40000
	v_lshl_add_u64 v[218:219], s[48:49], 0, v[166:167]
	s_addc_u32 s85, s49, 0
	s_add_i32 s65, s61, s68
	global_load_lds_dwordx4 v[218:219], off
	v_lshl_add_u64 v[220:221], s[84:85], 0, v[162:163]
	s_mov_b32 m0, s65
	v_lshl_add_u64 v[222:223], s[50:51], 0, v[164:165]
	global_load_lds_dwordx4 v[220:221], off
	v_lshl_add_u64 v[220:221], s[84:85], 0, v[166:167]
	s_add_i32 m0, s65, 0x2000
	s_nop 0
	global_load_lds_dwordx4 v[220:221], off
	v_lshl_add_u64 v[220:221], s[50:51], 0, v[160:161]
	s_mov_b32 m0, s74
	s_nop 0
	global_load_lds_dwordx4 v[220:221], off
	s_mov_b32 m0, s66
	s_nop 0
	global_load_lds_dwordx4 v[222:223], off
	s_waitcnt vmcnt(8)
	s_waitcnt lgkmcnt(0)
	s_barrier
; #define PG8_STAGE(bufoff, gbase, voff) do { _Pragma("unroll") for (int _i = 0; _i < 2; ++_i) \
;         __builtin_amdgcn_global_load_lds((const unsigned*)((const char*)(gbase) + (voff)[_i]), (PG8_LAS unsigned*)(lds + (bufoff) + ldsw + _i * 8192), 16, 0, 0); } while (0)
; #define PG8_LDA(dst, b, h) do { _Pragma("unroll") for (int m = 0; m < 4; ++m) _Pragma("unroll") for (int k = 0; k < 2; ++k) dst[m][k] = *(const PG8_LAS bf16x8*)(lds + PG8_SA(b, h) + aoff + m * 2048 + k * 1024); } while (0)
; #define PG8_LDB(dst, b, h) do { _Pragma("unroll") for (int n = 0; n < 2; ++n) _Pragma("unroll") for (int k = 0; k < 2; ++k) dst[n][k] = *(const PG8_LAS bf16x8*)(lds + PG8_SB(b, h) + boff + n * 2048 + k * 1024); } while (0)
; #define PG8_MMA(ai, bj, At, Bt) do { __builtin_amdgcn_s_setprio(1); _Pragma("unroll") for (int m = 0; m < 4; ++m) _Pragma("unroll") for (int n = 0; n < 2; ++n) _Pragma("unroll") for (int k = 0; k < 2; ++k) \
;         acc[ai][bj][m][n] = mma16<F16>(Bt[n][k], At[m][k], acc[ai][bj][m][n]); __builtin_amdgcn_s_setprio(0); } while (0)
; #define PG8_WAIT_V(n) asm volatile("s_waitcnt vmcnt(" #n ")" ::: "memory")
; #define PG8_WAIT_L(n) asm volatile("s_waitcnt lgkmcnt(" #n ")" ::: "memory")
; #define PG8_BAR __builtin_amdgcn_s_barrier()
; #define PG8_SCHED __builtin_amdgcn_sched_barrier(0)
; template <class Epi, class Sched, bool ALIGN_EPI = false, bool SP2 = false, bool F16 = false>
; __device__ __forceinline__ void gemm_phase(PG8_LAS unsigned char* lds, const Gemm g, const Sched& S, const Epi& E, const int wid_in) {
;     ...
;             PG8_WAIT_V(8); PG8_WAIT_L(0); PG8_BAR; PG8_MMA(1, 0, At, B0); PG8_MMA(1, 1, At, B1); PG8_BAR; PG8_SCHED;
;             PG8_LDB(B0, 1, 0); PG8_LDB(B1, 1, 1); PG8_SCHED; PG8_LDA(At, 1, 0); PG8_STAGE(PG8_SA(0, 1), a2 + hstep, voffA);
;             PG8_WAIT_V(8); PG8_WAIT_L(0); PG8_BAR; PG8_MMA(0, 0, At, B0); PG8_MMA(0, 1, At, B1); PG8_BAR; PG8_SCHED;
	v_mfma_f32_16x16x32_f16 v[68:71], v[0:3], v[176:179], v[68:71]
	v_mfma_f32_16x16x32_f16 v[64:67], v[136:139], v[176:179], v[64:67]
	v_mfma_f32_16x16x32_f16 v[52:55], v[0:3], v[184:187], v[52:55]
	v_mfma_f32_16x16x32_f16 v[48:51], v[136:139], v[184:187], v[48:51]
	v_mfma_f32_16x16x32_f16 v[36:39], v[0:3], v[202:205], v[36:39]
	v_mfma_f32_16x16x32_f16 v[32:35], v[136:139], v[202:205], v[32:35]
	v_mfma_f32_16x16x32_f16 v[0:3], v[0:3], v[210:213], v[20:23]
	v_mfma_f32_16x16x32_f16 v[68:71], v[4:7], v[180:183], v[68:71]
	v_mfma_f32_16x16x32_f16 v[64:67], v[140:143], v[180:183], v[64:67]
	v_mfma_f32_16x16x32_f16 v[52:55], v[4:7], v[198:201], v[52:55]
	v_mfma_f32_16x16x32_f16 v[48:51], v[140:143], v[198:201], v[48:51]
	v_mfma_f32_16x16x32_f16 v[36:39], v[4:7], v[206:209], v[36:39]
	v_mfma_f32_16x16x32_f16 v[32:35], v[140:143], v[206:209], v[32:35]
	v_mfma_f32_16x16x32_f16 v[0:3], v[4:7], v[214:217], v[0:3]
	v_mfma_f32_16x16x32_f16 v[4:7], v[136:139], v[210:213], v[16:19]
	v_mfma_f32_16x16x32_f16 v[4:7], v[140:143], v[214:217], v[4:7]
	v_mfma_f32_16x16x32_f16 v[16:19], v[144:147], v[176:179], v[60:63]
	v_mfma_f32_16x16x32_f16 v[60:63], v[148:151], v[180:183], v[16:19]
	v_mfma_f32_16x16x32_f16 v[16:19], v[152:155], v[176:179], v[56:59]
	v_mfma_f32_16x16x32_f16 v[56:59], v[156:159], v[180:183], v[16:19]
	v_mfma_f32_16x16x32_f16 v[16:19], v[144:147], v[184:187], v[44:47]
	v_mfma_f32_16x16x32_f16 v[44:47], v[148:151], v[198:201], v[16:19]
	v_mfma_f32_16x16x32_f16 v[16:19], v[152:155], v[184:187], v[40:43]
	v_mfma_f32_16x16x32_f16 v[40:43], v[156:159], v[198:201], v[16:19]
	v_mfma_f32_16x16x32_f16 v[16:19], v[144:147], v[202:205], v[28:31]
	v_mfma_f32_16x16x32_f16 v[28:31], v[148:151], v[206:209], v[16:19]
	v_mfma_f32_16x16x32_f16 v[16:19], v[152:155], v[202:205], v[24:27]
	v_mfma_f32_16x16x32_f16 v[12:15], v[144:147], v[210:213], v[12:15]
	v_mfma_f32_16x16x32_f16 v[8:11], v[152:155], v[210:213], v[8:11]
	v_mfma_f32_16x16x32_f16 v[24:27], v[156:159], v[206:209], v[16:19]
	v_mfma_f32_16x16x32_f16 v[12:15], v[148:151], v[214:217], v[12:15]
	v_mfma_f32_16x16x32_f16 v[8:11], v[156:159], v[214:217], v[8:11]
	s_barrier
	s_add_i32 s65, 0, 0x18000
	s_add_i32 s76, 0, 0x1c000
	v_add_u32_e32 v140, s65, v192
	v_add_u32_e32 v156, s76, v192
	ds_read_b128 v[16:19], v140
	ds_read_b128 v[20:23], v140 offset:1024
	ds_read_b128 v[136:139], v140 offset:2048
	ds_read_b128 v[140:143], v140 offset:3072
	ds_read_b128 v[144:147], v156
	ds_read_b128 v[148:151], v156 offset:1024
	ds_read_b128 v[152:155], v156 offset:2048
	ds_read_b128 v[156:159], v156 offset:3072
	s_add_u32 s50, s50, 0x40000
	s_addc_u32 s51, s51, 0
	s_mov_b32 m0, s90
	v_lshl_add_u64 v[224:225], s[50:51], 0, v[160:161]
	ds_read_b128 v[176:179], v195 offset:32768
	ds_read_b128 v[180:183], v195 offset:33792
	ds_read_b128 v[184:187], v195 offset:34816
	ds_read_b128 v[198:201], v195 offset:35840
	ds_read_b128 v[202:205], v195 offset:36864
	ds_read_b128 v[206:209], v195 offset:37888
	ds_read_b128 v[210:213], v195 offset:38912
	ds_read_b128 v[214:217], v195 offset:39936
	global_load_lds_dwordx4 v[224:225], off
	v_lshl_add_u64 v[224:225], s[50:51], 0, v[164:165]
	s_mov_b32 m0, s37
	s_nop 0
	global_load_lds_dwordx4 v[224:225], off
	s_waitcnt vmcnt(8)
	s_waitcnt lgkmcnt(0)
	s_barrier
	v_mfma_f32_16x16x32_f16 v[132:135], v[16:19], v[176:179], v[132:135]
	v_mfma_f32_16x16x32_f16 v[128:131], v[136:139], v[176:179], v[128:131]
	v_mfma_f32_16x16x32_f16 v[116:119], v[16:19], v[184:187], v[116:119]
	v_mfma_f32_16x16x32_f16 v[112:115], v[136:139], v[184:187], v[112:115]
	v_mfma_f32_16x16x32_f16 v[100:103], v[16:19], v[202:205], v[100:103]
	v_mfma_f32_16x16x32_f16 v[96:99], v[136:139], v[202:205], v[96:99]
	v_mfma_f32_16x16x32_f16 v[84:87], v[16:19], v[210:213], v[84:87]
	v_mfma_f32_16x16x32_f16 v[80:83], v[136:139], v[210:213], v[80:83]
	v_mfma_f32_16x16x32_f16 v[132:135], v[20:23], v[180:183], v[132:135]
	v_mfma_f32_16x16x32_f16 v[128:131], v[140:143], v[180:183], v[128:131]
	v_mfma_f32_16x16x32_f16 v[116:119], v[20:23], v[198:201], v[116:119]
	v_mfma_f32_16x16x32_f16 v[112:115], v[140:143], v[198:201], v[112:115]
	v_mfma_f32_16x16x32_f16 v[100:103], v[20:23], v[206:209], v[100:103]
	v_mfma_f32_16x16x32_f16 v[96:99], v[140:143], v[206:209], v[96:99]
	v_mfma_f32_16x16x32_f16 v[84:87], v[20:23], v[214:217], v[84:87]
	v_mfma_f32_16x16x32_f16 v[80:83], v[140:143], v[214:217], v[80:83]
	v_mfma_f32_16x16x32_f16 v[124:127], v[144:147], v[176:179], v[124:127]
	v_mfma_f32_16x16x32_f16 v[120:123], v[152:155], v[176:179], v[120:123]
	v_mfma_f32_16x16x32_f16 v[108:111], v[144:147], v[184:187], v[108:111]
	v_mfma_f32_16x16x32_f16 v[104:107], v[152:155], v[184:187], v[104:107]
	v_mfma_f32_16x16x32_f16 v[92:95], v[144:147], v[202:205], v[92:95]
	v_mfma_f32_16x16x32_f16 v[88:91], v[152:155], v[202:205], v[88:91]
	v_mfma_f32_16x16x32_f16 v[76:79], v[144:147], v[210:213], v[76:79]
	v_mfma_f32_16x16x32_f16 v[72:75], v[152:155], v[210:213], v[72:75]
	v_mfma_f32_16x16x32_f16 v[124:127], v[148:151], v[180:183], v[124:127]
	v_mfma_f32_16x16x32_f16 v[120:123], v[156:159], v[180:183], v[120:123]
	v_mfma_f32_16x16x32_f16 v[108:111], v[148:151], v[198:201], v[108:111]
	v_mfma_f32_16x16x32_f16 v[104:107], v[156:159], v[198:201], v[104:107]
	v_mfma_f32_16x16x32_f16 v[92:95], v[148:151], v[206:209], v[92:95]
	v_mfma_f32_16x16x32_f16 v[88:91], v[156:159], v[206:209], v[88:91]
	v_mfma_f32_16x16x32_f16 v[76:79], v[148:151], v[214:217], v[76:79]
	v_mfma_f32_16x16x32_f16 v[72:75], v[156:159], v[214:217], v[72:75]
	s_barrier
; #define PG8_STAGE(bufoff, gbase, voff) do { _Pragma("unroll") for (int _i = 0; _i < 2; ++_i) \
;         __builtin_amdgcn_global_load_lds((const unsigned*)((const char*)(gbase) + (voff)[_i]), (PG8_LAS unsigned*)(lds + (bufoff) + ldsw + _i * 8192), 16, 0, 0); } while (0)
; #define PG8_LDA(dst, b, h) do { _Pragma("unroll") for (int m = 0; m < 4; ++m) _Pragma("unroll") for (int k = 0; k < 2; ++k) dst[m][k] = *(const PG8_LAS bf16x8*)(lds + PG8_SA(b, h) + aoff + m * 2048 + k * 1024); } while (0)
; #define PG8_BAR __builtin_amdgcn_s_barrier()
; template <class Epi, class Sched, bool ALIGN_EPI = false, bool SP2 = false, bool F16 = false>
; __device__ __forceinline__ void gemm_phase(PG8_LAS unsigned char* lds, const Gemm g, const Sched& S, const Epi& E, const int wid_in) {
;     ...
;             PG8_LDA(At, 1, 1); PG8_STAGE(PG8_SB(1, 0), b3, voffB); PG8_STAGE(PG8_SB(1, 1), b3 + hstep, voffB); PG8_STAGE(PG8_SA(1, 0), a3, voffA);
;             PG8_WAIT_V(8); PG8_WAIT_L(0); PG8_BAR; PG8_MMA(1, 0, At, B0); PG8_MMA(1, 1, At, B1); PG8_BAR; PG8_SCHED;
;             } else {
;             PG8_LDB(B0, 0, 0); PG8_SCHED; PG8_LDA(At, 0, 0); PG8_STAGE(PG8_SA(1, 1), a1 + hstep, voffA);
;             PG8_WAIT_L(8); PG8_BAR; PG8_WAIT_L(0); PG8_MMA(0, 0, At, B0); PG8_BAR; PG8_SCHED;
;             PG8_LDB(B1, 0, 1); PG8_STAGE(PG8_SB(0, 0), b2, voffB);
;             PG8_BAR; PG8_WAIT_L(0); PG8_MMA(0, 1, At, B1); PG8_BAR;
;             PG8_LDA(At, 0, 1); PG8_STAGE(PG8_SA(0, 0), a2, voffA);
;             PG8_BAR; PG8_WAIT_L(0); PG8_MMA(1, 0, At, B0); PG8_BAR; PG8_SCHED;
;             PG8_STAGE(PG8_SB(0, 1), b2 + hstep, voffB);
;             PG8_WAIT_V(6); PG8_BAR; PG8_MMA(1, 1, At, B1); PG8_BAR;
;             PG8_LDB(B0, 1, 0); PG8_SCHED; PG8_LDA(At, 1, 0); PG8_STAGE(PG8_SA(0, 1), a2 + hstep, voffA);
;             PG8_WAIT_L(8); PG8_BAR; PG8_WAIT_L(0); PG8_MMA(0, 0, At, B0); PG8_BAR; PG8_SCHED;
;             PG8_LDB(B1, 1, 1); PG8_STAGE(PG8_SB(1, 0), b3, voffB);
;             PG8_BAR; PG8_WAIT_L(0); PG8_MMA(0, 1, At, B1); PG8_BAR;
;             PG8_LDA(At, 1, 1); PG8_STAGE(PG8_SA(1, 0), a3, voffA);
;             PG8_BAR; PG8_WAIT_L(0); PG8_MMA(1, 0, At, B0); PG8_BAR; PG8_SCHED;
;             PG8_STAGE(PG8_SB(1, 1), b3 + hstep, voffB);
;             PG8_WAIT_V(6); PG8_BAR; PG8_MMA(1, 1, At, B1); PG8_BAR;
;             }
;         }
;         if constexpr (ALIGN_EPI) { if (wr == 0) PG8_BAR; }
	s_add_i32 s50, s65, s68
	v_lshl_add_u64 v[188:189], v[188:189], 0, s[24:25]
	s_mov_b32 m0, s50
	ds_read_b128 v[176:179], v195 offset:49152
	ds_read_b128 v[180:183], v195 offset:50176
	ds_read_b128 v[184:187], v195 offset:51200
	ds_read_b128 v[198:201], v195 offset:52224
	ds_read_b128 v[202:205], v195 offset:53248
	ds_read_b128 v[206:209], v195 offset:54272
	ds_read_b128 v[210:213], v195 offset:55296
	ds_read_b128 v[214:217], v195 offset:56320
	global_load_lds_dwordx4 v[188:189], off
	s_add_i32 m0, s50, 0x2000
	s_add_u32 s48, s48, 0x40080
	v_lshl_add_u64 v[188:189], v[218:219], 0, s[24:25]
	s_addc_u32 s49, s49, 0
	s_add_i32 s50, s76, s68
	global_load_lds_dwordx4 v[188:189], off
	v_lshl_add_u64 v[188:189], s[48:49], 0, v[162:163]
	s_mov_b32 m0, s50
	s_nop 0
	global_load_lds_dwordx4 v[188:189], off
	v_lshl_add_u64 v[188:189], s[48:49], 0, v[166:167]
	s_add_i32 m0, s50, 0x2000
	s_nop 0
	global_load_lds_dwordx4 v[188:189], off
	v_lshl_add_u64 v[188:189], v[220:221], 0, s[24:25]
	s_mov_b32 m0, s75
	s_nop 0
	global_load_lds_dwordx4 v[188:189], off
	v_lshl_add_u64 v[188:189], v[222:223], 0, s[24:25]
	s_mov_b32 m0, s67
	s_nop 0
	global_load_lds_dwordx4 v[188:189], off
	s_waitcnt vmcnt(8)
	s_waitcnt lgkmcnt(0)
	s_barrier
	v_mfma_f32_16x16x32_f16 v[68:71], v[16:19], v[176:179], v[68:71]
	v_mfma_f32_16x16x32_f16 v[52:55], v[16:19], v[184:187], v[52:55]
	v_mfma_f32_16x16x32_f16 v[36:39], v[16:19], v[202:205], v[36:39]
	v_mfma_f32_16x16x32_f16 v[0:3], v[16:19], v[210:213], v[0:3]
	v_mfma_f32_16x16x32_f16 v[68:71], v[20:23], v[180:183], v[68:71]
	v_mfma_f32_16x16x32_f16 v[64:67], v[136:139], v[176:179], v[64:67]
	v_mfma_f32_16x16x32_f16 v[52:55], v[20:23], v[198:201], v[52:55]
	v_mfma_f32_16x16x32_f16 v[48:51], v[136:139], v[184:187], v[48:51]
	v_mfma_f32_16x16x32_f16 v[36:39], v[20:23], v[206:209], v[36:39]
	v_mfma_f32_16x16x32_f16 v[32:35], v[136:139], v[202:205], v[32:35]
	v_mfma_f32_16x16x32_f16 v[20:23], v[20:23], v[214:217], v[0:3]
	v_mfma_f32_16x16x32_f16 v[0:3], v[136:139], v[210:213], v[4:7]
	v_mfma_f32_16x16x32_f16 v[64:67], v[140:143], v[180:183], v[64:67]
	v_mfma_f32_16x16x32_f16 v[48:51], v[140:143], v[198:201], v[48:51]
	v_mfma_f32_16x16x32_f16 v[32:35], v[140:143], v[206:209], v[32:35]
	v_mfma_f32_16x16x32_f16 v[16:19], v[140:143], v[214:217], v[0:3]
	v_mfma_f32_16x16x32_f16 v[0:3], v[144:147], v[176:179], v[60:63]
	v_mfma_f32_16x16x32_f16 v[60:63], v[148:151], v[180:183], v[0:3]
	v_mfma_f32_16x16x32_f16 v[0:3], v[152:155], v[176:179], v[56:59]
	v_mfma_f32_16x16x32_f16 v[56:59], v[156:159], v[180:183], v[0:3]
	v_mfma_f32_16x16x32_f16 v[0:3], v[144:147], v[184:187], v[44:47]
	v_mfma_f32_16x16x32_f16 v[44:47], v[148:151], v[198:201], v[0:3]
	v_mfma_f32_16x16x32_f16 v[0:3], v[152:155], v[184:187], v[40:43]
	v_mfma_f32_16x16x32_f16 v[40:43], v[156:159], v[198:201], v[0:3]
	v_mfma_f32_16x16x32_f16 v[0:3], v[144:147], v[202:205], v[28:31]
	v_mfma_f32_16x16x32_f16 v[28:31], v[148:151], v[206:209], v[0:3]
	v_mfma_f32_16x16x32_f16 v[0:3], v[152:155], v[202:205], v[24:27]
	v_mfma_f32_16x16x32_f16 v[24:27], v[156:159], v[206:209], v[0:3]
	v_mfma_f32_16x16x32_f16 v[0:3], v[144:147], v[210:213], v[12:15]
	v_mfma_f32_16x16x32_f16 v[12:15], v[148:151], v[214:217], v[0:3]
	v_mfma_f32_16x16x32_f16 v[0:3], v[152:155], v[210:213], v[8:11]
	v_mfma_f32_16x16x32_f16 v[8:11], v[156:159], v[214:217], v[0:3]
	s_barrier
	s_add_i32 s64, s64, 2
	s_add_u32 s46, s46, 0x100
	s_addc_u32 s47, s47, 0
	s_add_u32 s45, s45, 0x100
	s_addc_u32 s63, s63, 0
	s_cmp_gt_u32 s64, 13
	s_cbranch_scc0 .LBB0_1909
	s_and_b64 vcc, exec, s[16:17]
	s_cbranch_vccz .LBB0_1912
	s_barrier

; #define PG8_STAGE(bufoff, gbase, voff) do { _Pragma("unroll") for (int _i = 0; _i < 2; ++_i) \
;         __builtin_amdgcn_global_load_lds((const unsigned*)((const char*)(gbase) + (voff)[_i]), (PG8_LAS unsigned*)(lds + (bufoff) + ldsw + _i * 8192), 16, 0, 0); } while (0)
; #define PG8_LDA(dst, b, h) do { _Pragma("unroll") for (int m = 0; m < 4; ++m) _Pragma("unroll") for (int k = 0; k < 2; ++k) dst[m][k] = *(const PG8_LAS bf16x8*)(lds + PG8_SA(b, h) + aoff + m * 2048 + k * 1024); } while (0)
; #define PG8_LDB(dst, b, h) do { _Pragma("unroll") for (int n = 0; n < 2; ++n) _Pragma("unroll") for (int k = 0; k < 2; ++k) dst[n][k] = *(const PG8_LAS bf16x8*)(lds + PG8_SB(b, h) + boff + n * 2048 + k * 1024); } while (0)
; #define PG8_WAIT_V(n) asm volatile("s_waitcnt vmcnt(" #n ")" ::: "memory")
; #define PG8_WAIT_L(n) asm volatile("s_waitcnt lgkmcnt(" #n ")" ::: "memory")
; #define PG8_BAR __builtin_amdgcn_s_barrier()
; #define PG8_SCHED __builtin_amdgcn_sched_barrier(0)
; template <class Epi, class Sched, bool ALIGN_EPI = false, bool SP2 = false, bool F16 = false>
; __device__ __forceinline__ void gemm_phase(PG8_LAS unsigned char* lds, const Gemm g, const Sched& S, const Epi& E, const int wid_in) {
;     ...
;         const bool has_next = S.next(ui + 1, nxt);
;         const char* nA = has_next ? (const char*)g.A + (size_t)nxt.pm * tstep : cA; const char* nB = has_next ? (const char*)g.Bt + (size_t)nxt.pn * tstep : cB;
;         for (int t = 0; t < nt; t += 2) {
;             const bool last = (t == nt - 2);
;             const char* a1 = cA + (size_t)(t + 1) * kstep;
;             const char* a2 = last ? nA : cA + (size_t)(t + 2) * kstep; const char* b2 = last ? nB : cB + (size_t)(t + 2) * kstep;
;             const char* a3 = a2 + kstep; const char* b3 = b2 + kstep;
;             if (last && has_next) S.a_ready(nxt);
;             if constexpr (SP2) {
;             PG8_LDB(B0, 0, 0); PG8_LDB(B1, 0, 1); PG8_SCHED; PG8_LDA(At, 0, 0); PG8_STAGE(PG8_SA(1, 1), a1 + hstep, voffA);
;             PG8_WAIT_V(8); PG8_WAIT_L(0); PG8_BAR; PG8_MMA(0, 0, At, B0); PG8_MMA(0, 1, At, B1); PG8_BAR; PG8_SCHED;
;             PG8_LDA(At, 0, 1); PG8_STAGE(PG8_SB(0, 0), b2, voffB); PG8_STAGE(PG8_SB(0, 1), b2 + hstep, voffB); PG8_STAGE(PG8_SA(0, 0), a2, voffA);
;             PG8_WAIT_V(8); PG8_WAIT_L(0); PG8_BAR; PG8_MMA(1, 0, At, B0); PG8_MMA(1, 1, At, B1); PG8_BAR; PG8_SCHED;
.LBB0_1944:
	s_mov_b64 s[48:49], s[10:11]
	s_add_i32 s10, s36, s19
	s_mov_b64 s[46:47], s[12:13]
	s_mov_b32 s12, s58
	s_mov_b32 s13, s57
	s_and_b32 s57, s10, 3
	s_ashr_i32 s58, s10, 2
	s_and_b64 s[10:11], s[30:31], exec
	s_cselect_b32 s12, s58, s12
	ds_read_b128 v[0:3], v134
	ds_read_b128 v[4:7], v134 offset:1024
	ds_read_b128 v[8:11], v134 offset:2048
	ds_read_b128 v[12:15], v134 offset:3072
	ds_read_b128 v[16:19], v135
	ds_read_b128 v[20:23], v135 offset:1024
	ds_read_b128 v[24:27], v135 offset:2048
	ds_read_b128 v[28:31], v135 offset:3072
	s_cselect_b32 s10, s57, s13
	s_ashr_i32 s13, s12, 31
	s_lshl_b64 s[12:13], s[12:13], 17
	s_add_u32 s12, s21, s12
	s_addc_u32 s13, s40, s13
	s_and_b64 s[36:37], s[30:31], exec
	s_cselect_b32 s45, s13, s47
	s_cselect_b32 s44, s12, s46
	s_ashr_i32 s11, s10, 31
	s_lshl_b64 s[10:11], s[10:11], 17
	s_add_u32 s10, s41, s10
	s_addc_u32 s11, s42, s11
	s_and_b64 s[36:37], s[30:31], exec
	s_cselect_b32 s37, s11, s49
	s_cselect_b32 s36, s10, s48
	s_add_u32 s60, s46, 0x10080
	s_addc_u32 s61, s47, 0
	s_mov_b32 m0, s91
	v_lshl_add_u64 v[64:65], s[60:61], 0, v[130:131]
	ds_read_b128 v[32:35], v136
	ds_read_b128 v[36:39], v136 offset:1024
	ds_read_b128 v[40:43], v136 offset:2048
	ds_read_b128 v[44:47], v136 offset:3072
	ds_read_b128 v[48:51], v136 offset:4096
	ds_read_b128 v[52:55], v136 offset:5120
	ds_read_b128 v[56:59], v136 offset:6144
	ds_read_b128 v[60:63], v136 offset:7168
	global_load_lds_dwordx4 v[64:65], off
	v_lshl_add_u64 v[64:65], s[60:61], 0, v[128:129]
	s_mov_b32 m0, s14
	s_nop 0
	global_load_lds_dwordx4 v[64:65], off
	s_waitcnt vmcnt(8)
	s_waitcnt lgkmcnt(0)
	s_barrier
	v_mfma_f32_16x16x32_bf16 v[64:67], v[0:3], v[32:35], 0
	v_mfma_f32_16x16x32_bf16 v[68:71], v[8:11], v[32:35], 0
	v_mfma_f32_16x16x32_bf16 v[72:75], v[0:3], v[40:43], 0
	v_mfma_f32_16x16x32_bf16 v[76:79], v[8:11], v[40:43], 0
	v_mfma_f32_16x16x32_bf16 v[80:83], v[0:3], v[48:51], 0
	v_mfma_f32_16x16x32_bf16 v[84:87], v[8:11], v[48:51], 0
	v_mfma_f32_16x16x32_bf16 v[88:91], v[0:3], v[56:59], 0
	v_mfma_f32_16x16x32_bf16 v[92:95], v[8:11], v[56:59], 0
	v_mfma_f32_16x16x32_bf16 v[64:67], v[4:7], v[36:39], v[64:67]
	v_mfma_f32_16x16x32_bf16 v[68:71], v[12:15], v[36:39], v[68:71]
	v_mfma_f32_16x16x32_bf16 v[72:75], v[4:7], v[44:47], v[72:75]
	v_mfma_f32_16x16x32_bf16 v[76:79], v[12:15], v[44:47], v[76:79]
	v_mfma_f32_16x16x32_bf16 v[80:83], v[4:7], v[52:55], v[80:83]
	v_mfma_f32_16x16x32_bf16 v[84:87], v[12:15], v[52:55], v[84:87]
	v_mfma_f32_16x16x32_bf16 v[88:91], v[4:7], v[60:63], v[88:91]
	v_mfma_f32_16x16x32_bf16 v[92:95], v[12:15], v[60:63], v[92:95]
	v_mfma_f32_16x16x32_bf16 v[96:99], v[16:19], v[32:35], 0
	v_mfma_f32_16x16x32_bf16 v[32:35], v[24:27], v[32:35], 0
	v_mfma_f32_16x16x32_bf16 v[96:99], v[20:23], v[36:39], v[96:99]
	v_mfma_f32_16x16x32_bf16 v[32:35], v[28:31], v[36:39], v[32:35]
	v_mfma_f32_16x16x32_bf16 v[36:39], v[16:19], v[40:43], 0
	v_mfma_f32_16x16x32_bf16 v[40:43], v[24:27], v[40:43], 0
	v_mfma_f32_16x16x32_bf16 v[36:39], v[20:23], v[44:47], v[36:39]
	v_mfma_f32_16x16x32_bf16 v[40:43], v[28:31], v[44:47], v[40:43]
	v_mfma_f32_16x16x32_bf16 v[44:47], v[16:19], v[48:51], 0
	v_mfma_f32_16x16x32_bf16 v[48:51], v[24:27], v[48:51], 0
	v_mfma_f32_16x16x32_bf16 v[44:47], v[20:23], v[52:55], v[44:47]
	v_mfma_f32_16x16x32_bf16 v[48:51], v[28:31], v[52:55], v[48:51]
	v_mfma_f32_16x16x32_bf16 v[52:55], v[16:19], v[56:59], 0
	v_mfma_f32_16x16x32_bf16 v[56:59], v[24:27], v[56:59], 0
	v_mfma_f32_16x16x32_bf16 v[52:55], v[20:23], v[60:63], v[52:55]
	v_mfma_f32_16x16x32_bf16 v[56:59], v[28:31], v[60:63], v[56:59]
	s_barrier
	v_lshl_add_u64 v[204:205], s[48:49], 0, v[130:131]
	s_mov_b32 m0, s15
	v_lshl_add_u64 v[140:141], v[204:205], 0, s[26:27]
	v_lshl_add_u64 v[206:207], s[48:49], 0, v[128:129]
	s_add_u32 s60, s48, 0x10100
	ds_read_b128 v[60:63], v136 offset:16384
	ds_read_b128 v[100:103], v136 offset:17408
	ds_read_b128 v[104:107], v136 offset:18432
	ds_read_b128 v[108:111], v136 offset:19456
	ds_read_b128 v[112:115], v136 offset:20480
	ds_read_b128 v[116:119], v136 offset:21504
	ds_read_b128 v[120:123], v136 offset:22528
	ds_read_b128 v[124:127], v136 offset:23552
	global_load_lds_dwordx4 v[140:141], off
	v_lshl_add_u64 v[140:141], v[206:207], 0, s[26:27]
	s_mov_b32 m0, s50
	s_addc_u32 s61, s49, 0
	global_load_lds_dwordx4 v[140:141], off
	v_lshl_add_u64 v[140:141], s[60:61], 0, v[130:131]
	s_mov_b32 m0, s51
	v_lshl_add_u64 v[208:209], s[46:47], 0, v[130:131]
	global_load_lds_dwordx4 v[140:141], off
	v_lshl_add_u64 v[140:141], s[60:61], 0, v[128:129]
	s_mov_b32 m0, s52
	v_lshl_add_u64 v[210:211], s[46:47], 0, v[128:129]
	global_load_lds_dwordx4 v[140:141], off
	v_lshl_add_u64 v[140:141], v[208:209], 0, s[26:27]
	s_mov_b32 m0, s74
	s_nop 0
	global_load_lds_dwordx4 v[140:141], off
	v_lshl_add_u64 v[140:141], v[210:211], 0, s[26:27]
	s_mov_b32 m0, s66
	s_nop 0
	global_load_lds_dwordx4 v[140:141], off
	s_waitcnt vmcnt(8)
	s_waitcnt lgkmcnt(0)
	s_barrier
; #define PG8_STAGE(bufoff, gbase, voff) do { _Pragma("unroll") for (int _i = 0; _i < 2; ++_i) \
;         __builtin_amdgcn_global_load_lds((const unsigned*)((const char*)(gbase) + (voff)[_i]), (PG8_LAS unsigned*)(lds + (bufoff) + ldsw + _i * 8192), 16, 0, 0); } while (0)
; #define PG8_LDA(dst, b, h) do { _Pragma("unroll") for (int m = 0; m < 4; ++m) _Pragma("unroll") for (int k = 0; k < 2; ++k) dst[m][k] = *(const PG8_LAS bf16x8*)(lds + PG8_SA(b, h) + aoff + m * 2048 + k * 1024); } while (0)
; #define PG8_LDB(dst, b, h) do { _Pragma("unroll") for (int n = 0; n < 2; ++n) _Pragma("unroll") for (int k = 0; k < 2; ++k) dst[n][k] = *(const PG8_LAS bf16x8*)(lds + PG8_SB(b, h) + boff + n * 2048 + k * 1024); } while (0)
; #define PG8_MMA(ai, bj, At, Bt) do { __builtin_amdgcn_s_setprio(1); _Pragma("unroll") for (int m = 0; m < 4; ++m) _Pragma("unroll") for (int n = 0; n < 2; ++n) _Pragma("unroll") for (int k = 0; k < 2; ++k) \
;         acc[ai][bj][m][n] = mma16<F16>(Bt[n][k], At[m][k], acc[ai][bj][m][n]); __builtin_amdgcn_s_setprio(0); } while (0)
; #define PG8_WAIT_V(n) asm volatile("s_waitcnt vmcnt(" #n ")" ::: "memory")
; #define PG8_WAIT_L(n) asm volatile("s_waitcnt lgkmcnt(" #n ")" ::: "memory")
; #define PG8_BAR __builtin_amdgcn_s_barrier()
; #define PG8_SCHED __builtin_amdgcn_sched_barrier(0)
; template <class Epi, class Sched, bool ALIGN_EPI = false, bool SP2 = false, bool F16 = false>
; __device__ __forceinline__ void gemm_phase(PG8_LAS unsigned char* lds, const Gemm g, const Sched& S, const Epi& E, const int wid_in) {
;     ...
;             PG8_LDA(At, 0, 1); PG8_STAGE(PG8_SB(0, 0), b2, voffB); PG8_STAGE(PG8_SB(0, 1), b2 + hstep, voffB); PG8_STAGE(PG8_SA(0, 0), a2, voffA);
;             PG8_WAIT_V(8); PG8_WAIT_L(0); PG8_BAR; PG8_MMA(1, 0, At, B0); PG8_MMA(1, 1, At, B1); PG8_BAR; PG8_SCHED;
;             PG8_LDB(B0, 1, 0); PG8_LDB(B1, 1, 1); PG8_SCHED; PG8_LDA(At, 1, 0); PG8_STAGE(PG8_SA(0, 1), a2 + hstep, voffA);
;             PG8_WAIT_V(8); PG8_WAIT_L(0); PG8_BAR; PG8_MMA(0, 0, At, B0); PG8_MMA(0, 1, At, B1); PG8_BAR; PG8_SCHED;
	v_mfma_f32_16x16x32_bf16 v[140:143], v[0:3], v[60:63], 0
	v_mfma_f32_16x16x32_bf16 v[148:151], v[0:3], v[104:107], 0
	v_mfma_f32_16x16x32_bf16 v[156:159], v[0:3], v[112:115], 0
	v_mfma_f32_16x16x32_bf16 v[0:3], v[0:3], v[120:123], 0
	v_mfma_f32_16x16x32_bf16 v[140:143], v[4:7], v[100:103], v[140:143]
	v_mfma_f32_16x16x32_bf16 v[148:151], v[4:7], v[108:111], v[148:151]
	v_mfma_f32_16x16x32_bf16 v[156:159], v[4:7], v[116:119], v[156:159]
	v_mfma_f32_16x16x32_bf16 v[0:3], v[4:7], v[124:127], v[0:3]
	v_mfma_f32_16x16x32_bf16 v[4:7], v[8:11], v[120:123], 0
	v_mfma_f32_16x16x32_bf16 v[144:147], v[8:11], v[60:63], 0
	v_mfma_f32_16x16x32_bf16 v[152:155], v[8:11], v[104:107], 0
	v_mfma_f32_16x16x32_bf16 v[160:163], v[8:11], v[112:115], 0
	v_mfma_f32_16x16x32_bf16 v[4:7], v[12:15], v[124:127], v[4:7]
	v_mfma_f32_16x16x32_bf16 v[144:147], v[12:15], v[100:103], v[144:147]
	v_mfma_f32_16x16x32_bf16 v[152:155], v[12:15], v[108:111], v[152:155]
	v_mfma_f32_16x16x32_bf16 v[160:163], v[12:15], v[116:119], v[160:163]
	v_mfma_f32_16x16x32_bf16 v[8:11], v[16:19], v[60:63], 0
	v_mfma_f32_16x16x32_bf16 v[12:15], v[24:27], v[60:63], 0
	v_mfma_f32_16x16x32_bf16 v[8:11], v[20:23], v[100:103], v[8:11]
	v_mfma_f32_16x16x32_bf16 v[12:15], v[28:31], v[100:103], v[12:15]
	v_mfma_f32_16x16x32_bf16 v[60:63], v[16:19], v[104:107], 0
	v_mfma_f32_16x16x32_bf16 v[100:103], v[24:27], v[104:107], 0
	v_mfma_f32_16x16x32_bf16 v[104:107], v[16:19], v[112:115], 0
	v_mfma_f32_16x16x32_bf16 v[16:19], v[16:19], v[120:123], 0
	v_mfma_f32_16x16x32_bf16 v[60:63], v[20:23], v[108:111], v[60:63]
	v_mfma_f32_16x16x32_bf16 v[100:103], v[28:31], v[108:111], v[100:103]
	v_mfma_f32_16x16x32_bf16 v[104:107], v[20:23], v[116:119], v[104:107]
	v_mfma_f32_16x16x32_bf16 v[108:111], v[24:27], v[112:115], 0
	v_mfma_f32_16x16x32_bf16 v[16:19], v[20:23], v[124:127], v[16:19]
	v_mfma_f32_16x16x32_bf16 v[20:23], v[24:27], v[120:123], 0
	v_mfma_f32_16x16x32_bf16 v[108:111], v[28:31], v[116:119], v[108:111]
	v_mfma_f32_16x16x32_bf16 v[20:23], v[28:31], v[124:127], v[20:23]
	s_barrier
	ds_read_b128 v[24:27], v137
	ds_read_b128 v[28:31], v137 offset:1024
	ds_read_b128 v[112:115], v137 offset:2048
	ds_read_b128 v[116:119], v137 offset:3072
	ds_read_b128 v[120:123], v138
	ds_read_b128 v[124:127], v138 offset:1024
	ds_read_b128 v[164:167], v138 offset:2048
	ds_read_b128 v[168:171], v138 offset:3072
	s_add_u32 s60, s46, 0x10100
	s_addc_u32 s61, s47, 0
	s_mov_b32 m0, s90
	v_lshl_add_u64 v[212:213], s[60:61], 0, v[130:131]
	ds_read_b128 v[172:175], v136 offset:32768
	ds_read_b128 v[176:179], v136 offset:33792
	ds_read_b128 v[180:183], v136 offset:34816
	ds_read_b128 v[184:187], v136 offset:35840
	ds_read_b128 v[188:191], v136 offset:36864
	ds_read_b128 v[192:195], v136 offset:37888
	ds_read_b128 v[196:199], v136 offset:38912
	ds_read_b128 v[200:203], v136 offset:39936
	global_load_lds_dwordx4 v[212:213], off
	v_lshl_add_u64 v[212:213], s[60:61], 0, v[128:129]
	s_mov_b32 m0, s43
	s_nop 0
	global_load_lds_dwordx4 v[212:213], off
	s_waitcnt vmcnt(8)
	s_waitcnt lgkmcnt(0)
	s_barrier
	v_mfma_f32_16x16x32_bf16 v[64:67], v[24:27], v[172:175], v[64:67]
	v_mfma_f32_16x16x32_bf16 v[68:71], v[112:115], v[172:175], v[68:71]
	v_mfma_f32_16x16x32_bf16 v[72:75], v[24:27], v[180:183], v[72:75]
	v_mfma_f32_16x16x32_bf16 v[76:79], v[112:115], v[180:183], v[76:79]
	v_mfma_f32_16x16x32_bf16 v[80:83], v[24:27], v[188:191], v[80:83]
	v_mfma_f32_16x16x32_bf16 v[84:87], v[112:115], v[188:191], v[84:87]
	v_mfma_f32_16x16x32_bf16 v[88:91], v[24:27], v[196:199], v[88:91]
	v_mfma_f32_16x16x32_bf16 v[92:95], v[112:115], v[196:199], v[92:95]
	v_mfma_f32_16x16x32_bf16 v[64:67], v[28:31], v[176:179], v[64:67]
	v_mfma_f32_16x16x32_bf16 v[68:71], v[116:119], v[176:179], v[68:71]
	v_mfma_f32_16x16x32_bf16 v[72:75], v[28:31], v[184:187], v[72:75]
	v_mfma_f32_16x16x32_bf16 v[76:79], v[116:119], v[184:187], v[76:79]
	v_mfma_f32_16x16x32_bf16 v[80:83], v[28:31], v[192:195], v[80:83]
	v_mfma_f32_16x16x32_bf16 v[84:87], v[116:119], v[192:195], v[84:87]
	v_mfma_f32_16x16x32_bf16 v[88:91], v[28:31], v[200:203], v[88:91]
	v_mfma_f32_16x16x32_bf16 v[92:95], v[116:119], v[200:203], v[92:95]
	v_mfma_f32_16x16x32_bf16 v[96:99], v[120:123], v[172:175], v[96:99]
	v_mfma_f32_16x16x32_bf16 v[32:35], v[164:167], v[172:175], v[32:35]
	v_mfma_f32_16x16x32_bf16 v[36:39], v[120:123], v[180:183], v[36:39]
	v_mfma_f32_16x16x32_bf16 v[40:43], v[164:167], v[180:183], v[40:43]
	v_mfma_f32_16x16x32_bf16 v[44:47], v[120:123], v[188:191], v[44:47]
	v_mfma_f32_16x16x32_bf16 v[48:51], v[164:167], v[188:191], v[48:51]
	v_mfma_f32_16x16x32_bf16 v[52:55], v[120:123], v[196:199], v[52:55]
	v_mfma_f32_16x16x32_bf16 v[56:59], v[164:167], v[196:199], v[56:59]
	v_mfma_f32_16x16x32_bf16 v[96:99], v[124:127], v[176:179], v[96:99]
	v_mfma_f32_16x16x32_bf16 v[32:35], v[168:171], v[176:179], v[32:35]
	v_mfma_f32_16x16x32_bf16 v[36:39], v[124:127], v[184:187], v[36:39]
	v_mfma_f32_16x16x32_bf16 v[40:43], v[168:171], v[184:187], v[40:43]
	v_mfma_f32_16x16x32_bf16 v[44:47], v[124:127], v[192:195], v[44:47]
	v_mfma_f32_16x16x32_bf16 v[48:51], v[168:171], v[192:195], v[48:51]
	v_mfma_f32_16x16x32_bf16 v[52:55], v[124:127], v[200:203], v[52:55]
	v_mfma_f32_16x16x32_bf16 v[56:59], v[168:171], v[200:203], v[56:59]
	s_barrier
; #define PG8_STAGE(bufoff, gbase, voff) do { _Pragma("unroll") for (int _i = 0; _i < 2; ++_i) \
;         __builtin_amdgcn_global_load_lds((const unsigned*)((const char*)(gbase) + (voff)[_i]), (PG8_LAS unsigned*)(lds + (bufoff) + ldsw + _i * 8192), 16, 0, 0); } while (0)
; #define PG8_LDA(dst, b, h) do { _Pragma("unroll") for (int m = 0; m < 4; ++m) _Pragma("unroll") for (int k = 0; k < 2; ++k) dst[m][k] = *(const PG8_LAS bf16x8*)(lds + PG8_SA(b, h) + aoff + m * 2048 + k * 1024); } while (0)
; #define PG8_LDB(dst, b, h) do { _Pragma("unroll") for (int n = 0; n < 2; ++n) _Pragma("unroll") for (int k = 0; k < 2; ++k) dst[n][k] = *(const PG8_LAS bf16x8*)(lds + PG8_SB(b, h) + boff + n * 2048 + k * 1024); } while (0)
; #define PG8_MMA(ai, bj, At, Bt) do { __builtin_amdgcn_s_setprio(1); _Pragma("unroll") for (int m = 0; m < 4; ++m) _Pragma("unroll") for (int n = 0; n < 2; ++n) _Pragma("unroll") for (int k = 0; k < 2; ++k) \
;         acc[ai][bj][m][n] = mma16<F16>(Bt[n][k], At[m][k], acc[ai][bj][m][n]); __builtin_amdgcn_s_setprio(0); } while (0)
; #define PG8_WAIT_V(n) asm volatile("s_waitcnt vmcnt(" #n ")" ::: "memory")
; #define PG8_WAIT_L(n) asm volatile("s_waitcnt lgkmcnt(" #n ")" ::: "memory")
; #define PG8_BAR __builtin_amdgcn_s_barrier()
; #define PG8_SCHED __builtin_amdgcn_sched_barrier(0)
; template <class Epi, class Sched, bool ALIGN_EPI = false, bool SP2 = false, bool F16 = false>
; __device__ __forceinline__ void gemm_phase(PG8_LAS unsigned char* lds, const Gemm g, const Sched& S, const Epi& E, const int wid_in) {
;     ...
;             PG8_LDA(At, 1, 1); PG8_STAGE(PG8_SB(1, 0), b3, voffB); PG8_STAGE(PG8_SB(1, 1), b3 + hstep, voffB); PG8_STAGE(PG8_SA(1, 0), a3, voffA);
;             PG8_WAIT_V(8); PG8_WAIT_L(0); PG8_BAR; PG8_MMA(1, 0, At, B0); PG8_MMA(1, 1, At, B1); PG8_BAR; PG8_SCHED;
;             } else {
;             PG8_LDB(B0, 0, 0); PG8_SCHED; PG8_LDA(At, 0, 0); PG8_STAGE(PG8_SA(1, 1), a1 + hstep, voffA);
	s_mov_b32 m0, s53
	v_lshl_add_u64 v[204:205], v[204:205], 0, s[28:29]
	s_add_u32 s48, s48, 0x10180
	ds_read_b128 v[172:175], v136 offset:49152
	ds_read_b128 v[176:179], v136 offset:50176
	ds_read_b128 v[180:183], v136 offset:51200
	ds_read_b128 v[184:187], v136 offset:52224
	ds_read_b128 v[188:191], v136 offset:53248
	ds_read_b128 v[192:195], v136 offset:54272
	ds_read_b128 v[196:199], v136 offset:55296
	ds_read_b128 v[200:203], v136 offset:56320
	global_load_lds_dwordx4 v[204:205], off
	v_lshl_add_u64 v[204:205], v[206:207], 0, s[28:29]
	s_mov_b32 m0, s54
	s_addc_u32 s49, s49, 0
	global_load_lds_dwordx4 v[204:205], off
	v_lshl_add_u64 v[204:205], s[48:49], 0, v[130:131]
	s_mov_b32 m0, s55
	s_nop 0
	global_load_lds_dwordx4 v[204:205], off
	v_lshl_add_u64 v[204:205], s[48:49], 0, v[128:129]
	s_mov_b32 m0, s56
	s_nop 0
	global_load_lds_dwordx4 v[204:205], off
	v_lshl_add_u64 v[204:205], v[208:209], 0, s[28:29]
	s_mov_b32 m0, s75
	s_nop 0
	global_load_lds_dwordx4 v[204:205], off
	v_lshl_add_u64 v[204:205], v[210:211], 0, s[28:29]
	s_mov_b32 m0, s67
	s_nop 0
	global_load_lds_dwordx4 v[204:205], off
	s_waitcnt vmcnt(8)
	s_waitcnt lgkmcnt(0)
	s_barrier
	v_mfma_f32_16x16x32_bf16 v[0:3], v[24:27], v[196:199], v[0:3]
	v_mfma_f32_16x16x32_bf16 v[4:7], v[112:115], v[196:199], v[4:7]
	v_mfma_f32_16x16x32_bf16 v[140:143], v[24:27], v[172:175], v[140:143]
	v_mfma_f32_16x16x32_bf16 v[144:147], v[112:115], v[172:175], v[144:147]
	v_mfma_f32_16x16x32_bf16 v[148:151], v[24:27], v[180:183], v[148:151]
	v_mfma_f32_16x16x32_bf16 v[152:155], v[112:115], v[180:183], v[152:155]
	v_mfma_f32_16x16x32_bf16 v[156:159], v[24:27], v[188:191], v[156:159]
	v_mfma_f32_16x16x32_bf16 v[160:163], v[112:115], v[188:191], v[160:163]
	v_mfma_f32_16x16x32_bf16 v[0:3], v[28:31], v[200:203], v[0:3]
	v_mfma_f32_16x16x32_bf16 v[4:7], v[116:119], v[200:203], v[4:7]
	v_mfma_f32_16x16x32_bf16 v[140:143], v[28:31], v[176:179], v[140:143]
	v_mfma_f32_16x16x32_bf16 v[144:147], v[116:119], v[176:179], v[144:147]
	v_mfma_f32_16x16x32_bf16 v[148:151], v[28:31], v[184:187], v[148:151]
	v_mfma_f32_16x16x32_bf16 v[152:155], v[116:119], v[184:187], v[152:155]
	v_mfma_f32_16x16x32_bf16 v[156:159], v[28:31], v[192:195], v[156:159]
	v_mfma_f32_16x16x32_bf16 v[160:163], v[116:119], v[192:195], v[160:163]
	v_mfma_f32_16x16x32_bf16 v[8:11], v[120:123], v[172:175], v[8:11]
	v_mfma_f32_16x16x32_bf16 v[12:15], v[164:167], v[172:175], v[12:15]
	v_mfma_f32_16x16x32_bf16 v[24:27], v[120:123], v[180:183], v[60:63]
	v_mfma_f32_16x16x32_bf16 v[28:31], v[164:167], v[180:183], v[100:103]
	v_mfma_f32_16x16x32_bf16 v[60:63], v[120:123], v[188:191], v[104:107]
	v_mfma_f32_16x16x32_bf16 v[100:103], v[164:167], v[188:191], v[108:111]
	v_mfma_f32_16x16x32_bf16 v[16:19], v[120:123], v[196:199], v[16:19]
	v_mfma_f32_16x16x32_bf16 v[20:23], v[164:167], v[196:199], v[20:23]
	v_mfma_f32_16x16x32_bf16 v[8:11], v[124:127], v[176:179], v[8:11]
	v_mfma_f32_16x16x32_bf16 v[12:15], v[168:171], v[176:179], v[12:15]
	v_mfma_f32_16x16x32_bf16 v[24:27], v[124:127], v[184:187], v[24:27]
	v_mfma_f32_16x16x32_bf16 v[28:31], v[168:171], v[184:187], v[28:31]
	v_mfma_f32_16x16x32_bf16 v[60:63], v[124:127], v[192:195], v[60:63]
	v_mfma_f32_16x16x32_bf16 v[100:103], v[168:171], v[192:195], v[100:103]
	v_mfma_f32_16x16x32_bf16 v[16:19], v[124:127], v[200:203], v[16:19]
	v_mfma_f32_16x16x32_bf16 v[20:23], v[168:171], v[200:203], v[20:23]
	s_barrier
	ds_read_b128 v[104:107], v134
	ds_read_b128 v[108:111], v134 offset:1024
	ds_read_b128 v[112:115], v134 offset:2048
	ds_read_b128 v[116:119], v134 offset:3072
	ds_read_b128 v[120:123], v135
	ds_read_b128 v[124:127], v135 offset:1024
	ds_read_b128 v[164:167], v135 offset:2048
	ds_read_b128 v[168:171], v135 offset:3072
	s_add_u32 s46, s46, 0x10180
	s_addc_u32 s47, s47, 0
	s_mov_b32 m0, s91
	v_lshl_add_u64 v[204:205], s[46:47], 0, v[130:131]
	ds_read_b128 v[172:175], v136
	ds_read_b128 v[176:179], v136 offset:1024
	ds_read_b128 v[180:183], v136 offset:2048
	ds_read_b128 v[184:187], v136 offset:3072
	ds_read_b128 v[188:191], v136 offset:4096
	ds_read_b128 v[192:195], v136 offset:5120
	ds_read_b128 v[196:199], v136 offset:6144
	ds_read_b128 v[200:203], v136 offset:7168
	global_load_lds_dwordx4 v[204:205], off
	v_lshl_add_u64 v[204:205], s[46:47], 0, v[128:129]
	s_mov_b32 m0, s14
	s_nop 0
	global_load_lds_dwordx4 v[204:205], off
	s_waitcnt vmcnt(8)
	s_waitcnt lgkmcnt(0)
	s_barrier
	v_mfma_f32_16x16x32_bf16 v[64:67], v[104:107], v[172:175], v[64:67]
	v_mfma_f32_16x16x32_bf16 v[68:71], v[112:115], v[172:175], v[68:71]
	v_mfma_f32_16x16x32_bf16 v[72:75], v[104:107], v[180:183], v[72:75]
	v_mfma_f32_16x16x32_bf16 v[76:79], v[112:115], v[180:183], v[76:79]
	v_mfma_f32_16x16x32_bf16 v[80:83], v[104:107], v[188:191], v[80:83]
	v_mfma_f32_16x16x32_bf16 v[84:87], v[112:115], v[188:191], v[84:87]
	v_mfma_f32_16x16x32_bf16 v[88:91], v[104:107], v[196:199], v[88:91]
	v_mfma_f32_16x16x32_bf16 v[92:95], v[112:115], v[196:199], v[92:95]
	v_mfma_f32_16x16x32_bf16 v[64:67], v[108:111], v[176:179], v[64:67]
	v_mfma_f32_16x16x32_bf16 v[68:71], v[116:119], v[176:179], v[68:71]
	v_mfma_f32_16x16x32_bf16 v[72:75], v[108:111], v[184:187], v[72:75]
	v_mfma_f32_16x16x32_bf16 v[76:79], v[116:119], v[184:187], v[76:79]
	v_mfma_f32_16x16x32_bf16 v[80:83], v[108:111], v[192:195], v[80:83]
	v_mfma_f32_16x16x32_bf16 v[84:87], v[116:119], v[192:195], v[84:87]
	v_mfma_f32_16x16x32_bf16 v[88:91], v[108:111], v[200:203], v[88:91]
	v_mfma_f32_16x16x32_bf16 v[92:95], v[116:119], v[200:203], v[92:95]
	v_mfma_f32_16x16x32_bf16 v[32:35], v[164:167], v[172:175], v[32:35]
	v_mfma_f32_16x16x32_bf16 v[96:99], v[120:123], v[172:175], v[96:99]
	v_mfma_f32_16x16x32_bf16 v[172:175], v[168:171], v[176:179], v[32:35]
	v_mfma_f32_16x16x32_bf16 v[32:35], v[120:123], v[180:183], v[36:39]
	v_mfma_f32_16x16x32_bf16 v[204:207], v[124:127], v[176:179], v[96:99]
	v_mfma_f32_16x16x32_bf16 v[176:179], v[124:127], v[184:187], v[32:35]
	v_mfma_f32_16x16x32_bf16 v[32:35], v[164:167], v[180:183], v[40:43]
	v_mfma_f32_16x16x32_bf16 v[40:43], v[168:171], v[184:187], v[32:35]
	v_mfma_f32_16x16x32_bf16 v[32:35], v[120:123], v[188:191], v[44:47]
	v_mfma_f32_16x16x32_bf16 v[44:47], v[124:127], v[192:195], v[32:35]
	v_mfma_f32_16x16x32_bf16 v[32:35], v[164:167], v[188:191], v[48:51]
	v_mfma_f32_16x16x32_bf16 v[48:51], v[168:171], v[192:195], v[32:35]
	v_mfma_f32_16x16x32_bf16 v[32:35], v[120:123], v[196:199], v[52:55]
	v_mfma_f32_16x16x32_bf16 v[52:55], v[124:127], v[200:203], v[32:35]
	v_mfma_f32_16x16x32_bf16 v[32:35], v[164:167], v[196:199], v[56:59]
	v_mfma_f32_16x16x32_bf16 v[56:59], v[168:171], v[200:203], v[32:35]
	s_barrier
; #define PG8_STAGE(bufoff, gbase, voff) do { _Pragma("unroll") for (int _i = 0; _i < 2; ++_i) \
;         __builtin_amdgcn_global_load_lds((const unsigned*)((const char*)(gbase) + (voff)[_i]), (PG8_LAS unsigned*)(lds + (bufoff) + ldsw + _i * 8192), 16, 0, 0); } while (0)
; #define PG8_LDA(dst, b, h) do { _Pragma("unroll") for (int m = 0; m < 4; ++m) _Pragma("unroll") for (int k = 0; k < 2; ++k) dst[m][k] = *(const PG8_LAS bf16x8*)(lds + PG8_SA(b, h) + aoff + m * 2048 + k * 1024); } while (0)
; #define PG8_LDB(dst, b, h) do { _Pragma("unroll") for (int n = 0; n < 2; ++n) _Pragma("unroll") for (int k = 0; k < 2; ++k) dst[n][k] = *(const PG8_LAS bf16x8*)(lds + PG8_SB(b, h) + boff + n * 2048 + k * 1024); } while (0)
; #define PG8_MMA(ai, bj, At, Bt) do { __builtin_amdgcn_s_setprio(1); _Pragma("unroll") for (int m = 0; m < 4; ++m) _Pragma("unroll") for (int n = 0; n < 2; ++n) _Pragma("unroll") for (int k = 0; k < 2; ++k) \
;         acc[ai][bj][m][n] = mma16<F16>(Bt[n][k], At[m][k], acc[ai][bj][m][n]); __builtin_amdgcn_s_setprio(0); } while (0)
; #define PG8_WAIT_V(n) asm volatile("s_waitcnt vmcnt(" #n ")" ::: "memory")
; #define PG8_WAIT_L(n) asm volatile("s_waitcnt lgkmcnt(" #n ")" ::: "memory")
; #define PG8_BAR __builtin_amdgcn_s_barrier()
; #define PG8_SCHED __builtin_amdgcn_sched_barrier(0)
; template <class Epi, class Sched, bool ALIGN_EPI = false, bool SP2 = false, bool F16 = false>
; __device__ __forceinline__ void gemm_phase(PG8_LAS unsigned char* lds, const Gemm g, const Sched& S, const Epi& E, const int wid_in) {
;     ...
;             PG8_LDB(B0, 1, 0); PG8_LDB(B1, 1, 1); PG8_SCHED; PG8_LDA(At, 1, 0); PG8_STAGE(PG8_SA(0, 1), a2 + hstep, voffA);
;             PG8_WAIT_V(8); PG8_WAIT_L(0); PG8_BAR; PG8_MMA(0, 0, At, B0); PG8_MMA(0, 1, At, B1); PG8_BAR; PG8_SCHED;
;             PG8_LDA(At, 1, 1); PG8_STAGE(PG8_SB(1, 0), b3, voffB); PG8_STAGE(PG8_SB(1, 1), b3 + hstep, voffB); PG8_STAGE(PG8_SA(1, 0), a3, voffA);
;             PG8_WAIT_V(8); PG8_WAIT_L(0); PG8_BAR; PG8_MMA(1, 0, At, B0); PG8_MMA(1, 1, At, B1); PG8_BAR; PG8_SCHED;
	s_mov_b32 m0, s15
	v_lshl_add_u64 v[240:241], s[36:37], 0, v[130:131]
	s_add_u32 s46, s36, 0x10000
	s_nop 1
	ds_read_b128 v[32:35], v136 offset:16384
	ds_read_b128 v[36:39], v136 offset:17408
	ds_read_b128 v[96:99], v136 offset:18432
	ds_read_b128 v[180:183], v136 offset:19456
	ds_read_b128 v[184:187], v136 offset:20480
	ds_read_b128 v[188:191], v136 offset:21504
	ds_read_b128 v[192:195], v136 offset:22528
	ds_read_b128 v[196:199], v136 offset:23552
	global_load_lds_dwordx4 v[240:241], off
	v_lshl_add_u64 v[242:243], s[36:37], 0, v[128:129]
	s_mov_b32 m0, s50
	s_addc_u32 s47, s37, 0
	global_load_lds_dwordx4 v[242:243], off
	v_lshl_add_u64 v[200:201], s[46:47], 0, v[130:131]
	s_mov_b32 m0, s51
	v_lshl_add_u64 v[244:245], s[44:45], 0, v[130:131]
	global_load_lds_dwordx4 v[200:201], off
	v_lshl_add_u64 v[200:201], s[46:47], 0, v[128:129]
	s_mov_b32 m0, s52
	v_lshl_add_u64 v[246:247], s[44:45], 0, v[128:129]
	global_load_lds_dwordx4 v[200:201], off
	s_mov_b32 m0, s74
	s_nop 0
	global_load_lds_dwordx4 v[244:245], off
	s_mov_b32 m0, s66
	s_nop 0
	global_load_lds_dwordx4 v[246:247], off
	s_waitcnt vmcnt(8)
	s_waitcnt lgkmcnt(0)
	s_barrier
	v_mfma_f32_16x16x32_bf16 v[0:3], v[104:107], v[192:195], v[0:3]
	v_mfma_f32_16x16x32_bf16 v[140:143], v[104:107], v[32:35], v[140:143]
	v_mfma_f32_16x16x32_bf16 v[144:147], v[112:115], v[32:35], v[144:147]
	v_mfma_f32_16x16x32_bf16 v[148:151], v[104:107], v[96:99], v[148:151]
	v_mfma_f32_16x16x32_bf16 v[152:155], v[112:115], v[96:99], v[152:155]
	v_mfma_f32_16x16x32_bf16 v[156:159], v[104:107], v[184:187], v[156:159]
	v_mfma_f32_16x16x32_bf16 v[160:163], v[112:115], v[184:187], v[160:163]
	v_mfma_f32_16x16x32_bf16 v[0:3], v[108:111], v[196:199], v[0:3]
	v_mfma_f32_16x16x32_bf16 v[4:7], v[112:115], v[192:195], v[4:7]
	v_mfma_f32_16x16x32_bf16 v[140:143], v[108:111], v[36:39], v[140:143]
	v_mfma_f32_16x16x32_bf16 v[144:147], v[116:119], v[36:39], v[144:147]
	v_mfma_f32_16x16x32_bf16 v[148:151], v[108:111], v[180:183], v[148:151]
	v_mfma_f32_16x16x32_bf16 v[152:155], v[116:119], v[180:183], v[152:155]
	v_mfma_f32_16x16x32_bf16 v[156:159], v[108:111], v[188:191], v[156:159]
	v_mfma_f32_16x16x32_bf16 v[160:163], v[116:119], v[188:191], v[160:163]
	v_mfma_f32_16x16x32_bf16 v[200:203], v[116:119], v[196:199], v[4:7]
	v_mfma_f32_16x16x32_bf16 v[4:7], v[120:123], v[32:35], v[8:11]
	v_mfma_f32_16x16x32_bf16 v[8:11], v[124:127], v[36:39], v[4:7]
	v_mfma_f32_16x16x32_bf16 v[4:7], v[164:167], v[32:35], v[12:15]
	v_mfma_f32_16x16x32_bf16 v[12:15], v[168:171], v[36:39], v[4:7]
	v_mfma_f32_16x16x32_bf16 v[4:7], v[120:123], v[96:99], v[24:27]
	v_mfma_f32_16x16x32_bf16 v[24:27], v[124:127], v[180:183], v[4:7]
	v_mfma_f32_16x16x32_bf16 v[4:7], v[164:167], v[96:99], v[28:31]
	v_mfma_f32_16x16x32_bf16 v[28:31], v[168:171], v[180:183], v[4:7]
	v_mfma_f32_16x16x32_bf16 v[4:7], v[120:123], v[184:187], v[60:63]
	v_mfma_f32_16x16x32_bf16 v[180:183], v[124:127], v[188:191], v[4:7]
	v_mfma_f32_16x16x32_bf16 v[4:7], v[164:167], v[184:187], v[100:103]
	v_mfma_f32_16x16x32_bf16 v[184:187], v[168:171], v[188:191], v[4:7]
	v_mfma_f32_16x16x32_bf16 v[4:7], v[120:123], v[192:195], v[16:19]
	v_mfma_f32_16x16x32_bf16 v[188:191], v[124:127], v[196:199], v[4:7]
	v_mfma_f32_16x16x32_bf16 v[4:7], v[164:167], v[192:195], v[20:23]
	v_mfma_f32_16x16x32_bf16 v[164:167], v[168:171], v[196:199], v[4:7]
	s_barrier
	s_nop 4
	ds_read_b128 v[4:7], v137
	ds_read_b128 v[60:63], v137 offset:1024
	ds_read_b128 v[168:171], v137 offset:2048
	ds_read_b128 v[192:195], v137 offset:3072
	ds_read_b128 v[196:199], v138
	ds_read_b128 v[208:211], v138 offset:1024
	ds_read_b128 v[212:215], v138 offset:2048
	ds_read_b128 v[216:219], v138 offset:3072
	s_add_u32 s44, s44, 0x10000
	s_addc_u32 s45, s45, 0
	s_mov_b32 m0, s90
	v_lshl_add_u64 v[32:33], s[44:45], 0, v[130:131]
	ds_read_b128 v[16:19], v136 offset:32768
	ds_read_b128 v[20:23], v136 offset:33792
	ds_read_b128 v[104:107], v136 offset:34816
	ds_read_b128 v[220:223], v136 offset:35840
	ds_read_b128 v[224:227], v136 offset:36864
	ds_read_b128 v[228:231], v136 offset:37888
	ds_read_b128 v[232:235], v136 offset:38912
	ds_read_b128 v[236:239], v136 offset:39936
	global_load_lds_dwordx4 v[32:33], off
	v_lshl_add_u64 v[32:33], s[44:45], 0, v[128:129]
	s_mov_b32 m0, s43
	s_nop 0
	global_load_lds_dwordx4 v[32:33], off
	s_waitcnt vmcnt(8)
	s_waitcnt lgkmcnt(0)
	s_barrier
; #define PG8_STAGE(bufoff, gbase, voff) do { _Pragma("unroll") for (int _i = 0; _i < 2; ++_i) \
;         __builtin_amdgcn_global_load_lds((const unsigned*)((const char*)(gbase) + (voff)[_i]), (PG8_LAS unsigned*)(lds + (bufoff) + ldsw + _i * 8192), 16, 0, 0); } while (0)
; #define PG8_LDA(dst, b, h) do { _Pragma("unroll") for (int m = 0; m < 4; ++m) _Pragma("unroll") for (int k = 0; k < 2; ++k) dst[m][k] = *(const PG8_LAS bf16x8*)(lds + PG8_SA(b, h) + aoff + m * 2048 + k * 1024); } while (0)
; #define PG8_BAR __builtin_amdgcn_s_barrier()
; template <class Epi, class Sched, bool ALIGN_EPI = false, bool SP2 = false, bool F16 = false>
; __device__ __forceinline__ void gemm_phase(PG8_LAS unsigned char* lds, const Gemm g, const Sched& S, const Epi& E, const int wid_in) {
;     ...
;             PG8_LDA(At, 1, 1); PG8_STAGE(PG8_SB(1, 0), b3, voffB); PG8_STAGE(PG8_SB(1, 1), b3 + hstep, voffB); PG8_STAGE(PG8_SA(1, 0), a3, voffA);
;             PG8_WAIT_V(8); PG8_WAIT_L(0); PG8_BAR; PG8_MMA(1, 0, At, B0); PG8_MMA(1, 1, At, B1); PG8_BAR; PG8_SCHED;
;             } else {
;             PG8_LDB(B0, 0, 0); PG8_SCHED; PG8_LDA(At, 0, 0); PG8_STAGE(PG8_SA(1, 1), a1 + hstep, voffA);
;             PG8_WAIT_L(8); PG8_BAR; PG8_WAIT_L(0); PG8_MMA(0, 0, At, B0); PG8_BAR; PG8_SCHED;
;             PG8_LDB(B1, 0, 1); PG8_STAGE(PG8_SB(0, 0), b2, voffB);
;             PG8_BAR; PG8_WAIT_L(0); PG8_MMA(0, 1, At, B1); PG8_BAR;
;             PG8_LDA(At, 0, 1); PG8_STAGE(PG8_SA(0, 0), a2, voffA);
;             PG8_BAR; PG8_WAIT_L(0); PG8_MMA(1, 0, At, B0); PG8_BAR; PG8_SCHED;
;             PG8_STAGE(PG8_SB(0, 1), b2 + hstep, voffB);
;             PG8_WAIT_V(6); PG8_BAR; PG8_MMA(1, 1, At, B1); PG8_BAR;
;             PG8_LDB(B0, 1, 0); PG8_SCHED; PG8_LDA(At, 1, 0); PG8_STAGE(PG8_SA(0, 1), a2 + hstep, voffA);
;             PG8_WAIT_L(8); PG8_BAR; PG8_WAIT_L(0); PG8_MMA(0, 0, At, B0); PG8_BAR; PG8_SCHED;
;             PG8_LDB(B1, 1, 1); PG8_STAGE(PG8_SB(1, 0), b3, voffB);
;             PG8_BAR; PG8_WAIT_L(0); PG8_MMA(0, 1, At, B1); PG8_BAR;
;             PG8_LDA(At, 1, 1); PG8_STAGE(PG8_SA(1, 0), a3, voffA);
;             PG8_BAR; PG8_WAIT_L(0); PG8_MMA(1, 0, At, B0); PG8_BAR; PG8_SCHED;
;             PG8_STAGE(PG8_SB(1, 1), b3 + hstep, voffB);
;             PG8_WAIT_V(6); PG8_BAR; PG8_MMA(1, 1, At, B1); PG8_BAR;
;             }
;         }
;         if constexpr (ALIGN_EPI) { if (wr == 0) PG8_BAR; }
	v_mfma_f32_16x16x32_bf16 v[32:35], v[4:7], v[16:19], v[64:67]
	v_mfma_f32_16x16x32_bf16 v[116:119], v[60:63], v[20:23], v[32:35]
	v_mfma_f32_16x16x32_bf16 v[32:35], v[168:171], v[16:19], v[68:71]
	v_mfma_f32_16x16x32_bf16 v[112:115], v[192:195], v[20:23], v[32:35]
	v_mfma_f32_16x16x32_bf16 v[32:35], v[4:7], v[104:107], v[72:75]
	v_mfma_f32_16x16x32_bf16 v[100:103], v[60:63], v[220:223], v[32:35]
	v_mfma_f32_16x16x32_bf16 v[32:35], v[168:171], v[104:107], v[76:79]
	v_mfma_f32_16x16x32_bf16 v[96:99], v[192:195], v[220:223], v[32:35]
	v_mfma_f32_16x16x32_bf16 v[32:35], v[4:7], v[224:227], v[80:83]
	v_mfma_f32_16x16x32_bf16 v[68:71], v[60:63], v[228:231], v[32:35]
	v_mfma_f32_16x16x32_bf16 v[32:35], v[168:171], v[224:227], v[84:87]
	v_mfma_f32_16x16x32_bf16 v[64:67], v[192:195], v[228:231], v[32:35]
	v_mfma_f32_16x16x32_bf16 v[32:35], v[4:7], v[232:235], v[88:91]
	v_mfma_f32_16x16x32_bf16 v[36:39], v[60:63], v[236:239], v[32:35]
	v_mfma_f32_16x16x32_bf16 v[32:35], v[168:171], v[232:235], v[92:95]
	v_mfma_f32_16x16x32_bf16 v[32:35], v[192:195], v[236:239], v[32:35]
	v_mfma_f32_16x16x32_bf16 v[72:75], v[196:199], v[16:19], v[204:207]
	v_mfma_f32_16x16x32_bf16 v[16:19], v[212:215], v[16:19], v[172:175]
	v_mfma_f32_16x16x32_bf16 v[120:123], v[216:219], v[20:23], v[16:19]
	v_mfma_f32_16x16x32_bf16 v[16:19], v[196:199], v[104:107], v[176:179]
	v_mfma_f32_16x16x32_bf16 v[108:111], v[208:211], v[220:223], v[16:19]
	v_mfma_f32_16x16x32_bf16 v[16:19], v[212:215], v[104:107], v[40:43]
	v_mfma_f32_16x16x32_bf16 v[104:107], v[216:219], v[220:223], v[16:19]
	v_mfma_f32_16x16x32_bf16 v[16:19], v[196:199], v[224:227], v[44:47]
	v_mfma_f32_16x16x32_bf16 v[80:83], v[208:211], v[228:231], v[16:19]
	v_mfma_f32_16x16x32_bf16 v[16:19], v[212:215], v[224:227], v[48:51]
	v_mfma_f32_16x16x32_bf16 v[124:127], v[208:211], v[20:23], v[72:75]
	v_mfma_f32_16x16x32_bf16 v[72:75], v[216:219], v[228:231], v[16:19]
	v_mfma_f32_16x16x32_bf16 v[16:19], v[196:199], v[232:235], v[52:55]
	v_mfma_f32_16x16x32_bf16 v[48:51], v[208:211], v[236:239], v[16:19]
	v_mfma_f32_16x16x32_bf16 v[16:19], v[212:215], v[232:235], v[56:59]
	v_mfma_f32_16x16x32_bf16 v[40:43], v[216:219], v[236:239], v[16:19]
	s_barrier
	s_mov_b32 m0, s53
	s_nop 3
	v_lshl_add_u64 v[16:17], v[240:241], 0, s[24:25]
	s_add_u32 s36, s36, 0x10080
	ds_read_b128 v[56:59], v136 offset:49152
	ds_read_b128 v[88:91], v136 offset:50176
	ds_read_b128 v[172:175], v136 offset:51200
	ds_read_b128 v[176:179], v136 offset:52224
	ds_read_b128 v[204:207], v136 offset:53248
	ds_read_b128 v[220:223], v136 offset:54272
	ds_read_b128 v[224:227], v136 offset:55296
	ds_read_b128 v[228:231], v136 offset:56320
	global_load_lds_dwordx4 v[16:17], off
	v_lshl_add_u64 v[16:17], v[242:243], 0, s[24:25]
	s_mov_b32 m0, s54
	s_addc_u32 s37, s37, 0
	global_load_lds_dwordx4 v[16:17], off
	v_lshl_add_u64 v[16:17], s[36:37], 0, v[130:131]
	s_mov_b32 m0, s55
	s_nop 0
	global_load_lds_dwordx4 v[16:17], off
	v_lshl_add_u64 v[16:17], s[36:37], 0, v[128:129]
	s_mov_b32 m0, s56
	s_nop 0
	global_load_lds_dwordx4 v[16:17], off
	v_lshl_add_u64 v[16:17], v[244:245], 0, s[24:25]
	s_mov_b32 m0, s75
	s_nop 0
	global_load_lds_dwordx4 v[16:17], off
	v_lshl_add_u64 v[16:17], v[246:247], 0, s[24:25]
	s_mov_b32 m0, s67
	s_nop 0
	global_load_lds_dwordx4 v[16:17], off
	s_waitcnt vmcnt(8)
	s_waitcnt lgkmcnt(0)
	s_barrier
	v_mfma_f32_16x16x32_bf16 v[16:19], v[4:7], v[56:59], v[140:143]
	v_mfma_f32_16x16x32_bf16 v[84:87], v[60:63], v[88:91], v[16:19]
	v_mfma_f32_16x16x32_bf16 v[16:19], v[168:171], v[56:59], v[144:147]
	v_mfma_f32_16x16x32_bf16 v[76:79], v[192:195], v[88:91], v[16:19]
	v_mfma_f32_16x16x32_bf16 v[16:19], v[4:7], v[172:175], v[148:151]
	v_mfma_f32_16x16x32_bf16 v[52:55], v[60:63], v[176:179], v[16:19]
	v_mfma_f32_16x16x32_bf16 v[16:19], v[168:171], v[172:175], v[152:155]
	v_mfma_f32_16x16x32_bf16 v[44:47], v[192:195], v[176:179], v[16:19]
	v_mfma_f32_16x16x32_bf16 v[16:19], v[4:7], v[204:207], v[156:159]
	v_mfma_f32_16x16x32_bf16 v[0:3], v[4:7], v[224:227], v[0:3]
	v_mfma_f32_16x16x32_bf16 v[20:23], v[60:63], v[220:223], v[16:19]
	v_mfma_f32_16x16x32_bf16 v[16:19], v[168:171], v[204:207], v[160:163]
	v_mfma_f32_16x16x32_bf16 v[4:7], v[60:63], v[228:231], v[0:3]
	v_mfma_f32_16x16x32_bf16 v[0:3], v[168:171], v[224:227], v[200:203]
	v_mfma_f32_16x16x32_bf16 v[16:19], v[192:195], v[220:223], v[16:19]
	v_mfma_f32_16x16x32_bf16 v[0:3], v[192:195], v[228:231], v[0:3]
	v_mfma_f32_16x16x32_bf16 v[8:11], v[196:199], v[56:59], v[8:11]
	v_mfma_f32_16x16x32_bf16 v[92:95], v[208:211], v[88:91], v[8:11]
	v_mfma_f32_16x16x32_bf16 v[8:11], v[212:215], v[56:59], v[12:15]
	v_mfma_f32_16x16x32_bf16 v[88:91], v[216:219], v[88:91], v[8:11]
	v_mfma_f32_16x16x32_bf16 v[8:11], v[196:199], v[172:175], v[24:27]
	v_mfma_f32_16x16x32_bf16 v[60:63], v[208:211], v[176:179], v[8:11]
	v_mfma_f32_16x16x32_bf16 v[8:11], v[212:215], v[172:175], v[28:31]
	v_mfma_f32_16x16x32_bf16 v[56:59], v[216:219], v[176:179], v[8:11]
	v_mfma_f32_16x16x32_bf16 v[8:11], v[196:199], v[204:207], v[180:183]
	v_mfma_f32_16x16x32_bf16 v[28:31], v[208:211], v[220:223], v[8:11]
	v_mfma_f32_16x16x32_bf16 v[8:11], v[212:215], v[204:207], v[184:187]
	v_mfma_f32_16x16x32_bf16 v[24:27], v[216:219], v[220:223], v[8:11]
	v_mfma_f32_16x16x32_bf16 v[8:11], v[196:199], v[224:227], v[188:191]
	v_mfma_f32_16x16x32_bf16 v[12:15], v[208:211], v[228:231], v[8:11]
	v_mfma_f32_16x16x32_bf16 v[8:11], v[212:215], v[224:227], v[164:167]
	v_mfma_f32_16x16x32_bf16 v[8:11], v[216:219], v[228:231], v[8:11]
	s_barrier
	s_and_b64 vcc, exec, s[8:9]
	s_cbranch_vccnz .LBB0_1946
	s_barrier

; #define PG8_STAGE(bufoff, gbase, voff) do { _Pragma("unroll") for (int _i = 0; _i < 2; ++_i) \
;         __builtin_amdgcn_global_load_lds((const unsigned*)((const char*)(gbase) + (voff)[_i]), (PG8_LAS unsigned*)(lds + (bufoff) + ldsw + _i * 8192), 16, 0, 0); } while (0)
; #define PG8_LDA(dst, b, h) do { _Pragma("unroll") for (int m = 0; m < 4; ++m) _Pragma("unroll") for (int k = 0; k < 2; ++k) dst[m][k] = *(const PG8_LAS bf16x8*)(lds + PG8_SA(b, h) + aoff + m * 2048 + k * 1024); } while (0)
; #define PG8_LDB(dst, b, h) do { _Pragma("unroll") for (int n = 0; n < 2; ++n) _Pragma("unroll") for (int k = 0; k < 2; ++k) dst[n][k] = *(const PG8_LAS bf16x8*)(lds + PG8_SB(b, h) + boff + n * 2048 + k * 1024); } while (0)
; #define PG8_MMA(ai, bj, At, Bt) do { __builtin_amdgcn_s_setprio(1); _Pragma("unroll") for (int m = 0; m < 4; ++m) _Pragma("unroll") for (int n = 0; n < 2; ++n) _Pragma("unroll") for (int k = 0; k < 2; ++k) \
;         acc[ai][bj][m][n] = mma16<F16>(Bt[n][k], At[m][k], acc[ai][bj][m][n]); __builtin_amdgcn_s_setprio(0); } while (0)
; #define PG8_WAIT_V(n) asm volatile("s_waitcnt vmcnt(" #n ")" ::: "memory")
; #define PG8_WAIT_L(n) asm volatile("s_waitcnt lgkmcnt(" #n ")" ::: "memory")
; template <class Epi, class Sched, bool ALIGN_EPI = false, bool SP2 = false, bool F16 = false>
; __device__ __forceinline__ void gemm_phase(PG8_LAS unsigned char* lds, const Gemm g, const Sched& S, const Epi& E, const int wid_in) {
;     ...
;             const bool last = (t == nt - 2);
;             const char* a1 = cA + (size_t)(t + 1) * kstep;
;             const char* a2 = last ? nA : cA + (size_t)(t + 2) * kstep; const char* b2 = last ? nB : cB + (size_t)(t + 2) * kstep;
;             const char* a3 = a2 + kstep; const char* b3 = b2 + kstep;
;             if (last && has_next) S.a_ready(nxt);
;             if constexpr (SP2) {
;             PG8_LDB(B0, 0, 0); PG8_LDB(B1, 0, 1); PG8_SCHED; PG8_LDA(At, 0, 0); PG8_STAGE(PG8_SA(1, 1), a1 + hstep, voffA);
;             PG8_WAIT_V(8); PG8_WAIT_L(0); PG8_BAR; PG8_MMA(0, 0, At, B0); PG8_MMA(0, 1, At, B1); PG8_BAR; PG8_SCHED;
;             PG8_LDA(At, 0, 1); PG8_STAGE(PG8_SB(0, 0), b2, voffB); PG8_STAGE(PG8_SB(0, 1), b2 + hstep, voffB); PG8_STAGE(PG8_SA(0, 0), a2, voffA);
;             PG8_WAIT_V(8); PG8_WAIT_L(0); PG8_BAR; PG8_MMA(1, 0, At, B0); PG8_MMA(1, 1, At, B1); PG8_BAR; PG8_SCHED;
.LBB0_2040:
	ds_read_b128 v[128:131], v189
	ds_read_b128 v[132:135], v189 offset:1024
	ds_read_b128 v[136:139], v189 offset:2048
	ds_read_b128 v[140:143], v189 offset:3072
	ds_read_b128 v[144:147], v190
	ds_read_b128 v[148:151], v190 offset:1024
	ds_read_b128 v[168:171], v190 offset:2048
	ds_read_b128 v[172:175], v190 offset:3072
	s_add_u32 s44, s36, 0x100
	s_addc_u32 s45, s37, 0
	s_cmp_eq_u32 s59, 40
	s_cselect_b32 s49, s13, s45
	s_cselect_b32 s48, s12, s44
	s_cselect_b32 s47, s35, s58
	s_cselect_b32 s46, s34, s43
	s_mov_b32 m0, s91
	v_lshl_add_u64 v[184:185], s[36:37], 0, v[160:161]
	ds_read_b128 v[176:179], v191
	ds_read_b128 v[180:183], v191 offset:1024
	ds_read_b128 v[192:195], v191 offset:2048
	ds_read_b128 v[196:199], v191 offset:3072
	ds_read_b128 v[200:203], v191 offset:4096
	ds_read_b128 v[204:207], v191 offset:5120
	ds_read_b128 v[208:211], v191 offset:6144
	ds_read_b128 v[212:215], v191 offset:7168
	global_load_lds_dwordx4 v[184:185], off
	v_lshl_add_u64 v[184:185], s[36:37], 0, v[162:163]
	s_add_i32 m0, s74, 0xe000
	s_nop 0
	global_load_lds_dwordx4 v[184:185], off
	s_waitcnt vmcnt(8)
	s_waitcnt lgkmcnt(0)
	s_barrier
	v_mfma_f32_16x16x32_bf16 v[124:127], v[128:131], v[176:179], v[124:127]
	v_mfma_f32_16x16x32_bf16 v[120:123], v[136:139], v[176:179], v[120:123]
	v_mfma_f32_16x16x32_bf16 v[108:111], v[128:131], v[192:195], v[108:111]
	v_mfma_f32_16x16x32_bf16 v[104:107], v[136:139], v[192:195], v[104:107]
	v_mfma_f32_16x16x32_bf16 v[92:95], v[128:131], v[200:203], v[92:95]
	v_mfma_f32_16x16x32_bf16 v[88:91], v[136:139], v[200:203], v[88:91]
	v_mfma_f32_16x16x32_bf16 v[76:79], v[128:131], v[208:211], v[76:79]
	v_mfma_f32_16x16x32_bf16 v[72:75], v[136:139], v[208:211], v[72:75]
	v_mfma_f32_16x16x32_bf16 v[124:127], v[132:135], v[180:183], v[124:127]
	v_mfma_f32_16x16x32_bf16 v[120:123], v[140:143], v[180:183], v[120:123]
	v_mfma_f32_16x16x32_bf16 v[108:111], v[132:135], v[196:199], v[108:111]
	v_mfma_f32_16x16x32_bf16 v[104:107], v[140:143], v[196:199], v[104:107]
	v_mfma_f32_16x16x32_bf16 v[92:95], v[132:135], v[204:207], v[92:95]
	v_mfma_f32_16x16x32_bf16 v[88:91], v[140:143], v[204:207], v[88:91]
	v_mfma_f32_16x16x32_bf16 v[76:79], v[132:135], v[212:215], v[76:79]
	v_mfma_f32_16x16x32_bf16 v[72:75], v[140:143], v[212:215], v[72:75]
	v_mfma_f32_16x16x32_bf16 v[116:119], v[144:147], v[176:179], v[116:119]
	v_mfma_f32_16x16x32_bf16 v[112:115], v[168:171], v[176:179], v[112:115]
	v_mfma_f32_16x16x32_bf16 v[100:103], v[144:147], v[192:195], v[100:103]
	v_mfma_f32_16x16x32_bf16 v[96:99], v[168:171], v[192:195], v[96:99]
	v_mfma_f32_16x16x32_bf16 v[84:87], v[144:147], v[200:203], v[84:87]
	v_mfma_f32_16x16x32_bf16 v[80:83], v[168:171], v[200:203], v[80:83]
	v_mfma_f32_16x16x32_bf16 v[68:71], v[144:147], v[208:211], v[68:71]
	v_mfma_f32_16x16x32_bf16 v[64:67], v[168:171], v[208:211], v[64:67]
	v_mfma_f32_16x16x32_bf16 v[116:119], v[148:151], v[180:183], v[116:119]
	v_mfma_f32_16x16x32_bf16 v[112:115], v[172:175], v[180:183], v[112:115]
	v_mfma_f32_16x16x32_bf16 v[100:103], v[148:151], v[196:199], v[100:103]
	v_mfma_f32_16x16x32_bf16 v[96:99], v[172:175], v[196:199], v[96:99]
	v_mfma_f32_16x16x32_bf16 v[84:87], v[148:151], v[204:207], v[84:87]
	v_mfma_f32_16x16x32_bf16 v[80:83], v[172:175], v[204:207], v[80:83]
	v_mfma_f32_16x16x32_bf16 v[68:71], v[148:151], v[212:215], v[68:71]
	v_mfma_f32_16x16x32_bf16 v[64:67], v[172:175], v[212:215], v[64:67]
	s_barrier
	s_add_i32 s36, s53, s68
	v_lshl_add_u64 v[184:185], s[46:47], 0, v[154:155]
	s_mov_b32 m0, s36
	ds_read_b128 v[176:179], v191 offset:16384
	ds_read_b128 v[180:183], v191 offset:17408
	ds_read_b128 v[192:195], v191 offset:18432
	ds_read_b128 v[196:199], v191 offset:19456
	ds_read_b128 v[200:203], v191 offset:20480
	ds_read_b128 v[204:207], v191 offset:21504
	ds_read_b128 v[208:211], v191 offset:22528
	ds_read_b128 v[212:215], v191 offset:23552
	global_load_lds_dwordx4 v[184:185], off
	s_add_i32 m0, s36, 0x2000
	s_add_u32 s36, s46, 0xb0000
	v_lshl_add_u64 v[216:217], s[46:47], 0, v[158:159]
	s_addc_u32 s37, s47, 0
	s_add_i32 s60, s54, s68
	global_load_lds_dwordx4 v[216:217], off
	v_lshl_add_u64 v[218:219], s[36:37], 0, v[154:155]
	s_mov_b32 m0, s60
	v_lshl_add_u64 v[220:221], s[48:49], 0, v[156:157]
	global_load_lds_dwordx4 v[218:219], off
	v_lshl_add_u64 v[218:219], s[36:37], 0, v[158:159]
	s_add_i32 m0, s60, 0x2000
	s_nop 0
	global_load_lds_dwordx4 v[218:219], off
	v_lshl_add_u64 v[218:219], s[48:49], 0, v[152:153]
	s_mov_b32 m0, s74
	s_nop 0
	global_load_lds_dwordx4 v[218:219], off
	s_mov_b32 m0, s66
	s_nop 0
	global_load_lds_dwordx4 v[220:221], off
	s_waitcnt vmcnt(8)
	s_waitcnt lgkmcnt(0)
	s_barrier
; #define PG8_STAGE(bufoff, gbase, voff) do { _Pragma("unroll") for (int _i = 0; _i < 2; ++_i) \
;         __builtin_amdgcn_global_load_lds((const unsigned*)((const char*)(gbase) + (voff)[_i]), (PG8_LAS unsigned*)(lds + (bufoff) + ldsw + _i * 8192), 16, 0, 0); } while (0)
; #define PG8_LDA(dst, b, h) do { _Pragma("unroll") for (int m = 0; m < 4; ++m) _Pragma("unroll") for (int k = 0; k < 2; ++k) dst[m][k] = *(const PG8_LAS bf16x8*)(lds + PG8_SA(b, h) + aoff + m * 2048 + k * 1024); } while (0)
; #define PG8_LDB(dst, b, h) do { _Pragma("unroll") for (int n = 0; n < 2; ++n) _Pragma("unroll") for (int k = 0; k < 2; ++k) dst[n][k] = *(const PG8_LAS bf16x8*)(lds + PG8_SB(b, h) + boff + n * 2048 + k * 1024); } while (0)
; #define PG8_MMA(ai, bj, At, Bt) do { __builtin_amdgcn_s_setprio(1); _Pragma("unroll") for (int m = 0; m < 4; ++m) _Pragma("unroll") for (int n = 0; n < 2; ++n) _Pragma("unroll") for (int k = 0; k < 2; ++k) \
;         acc[ai][bj][m][n] = mma16<F16>(Bt[n][k], At[m][k], acc[ai][bj][m][n]); __builtin_amdgcn_s_setprio(0); } while (0)
; #define PG8_WAIT_V(n) asm volatile("s_waitcnt vmcnt(" #n ")" ::: "memory")
; #define PG8_WAIT_L(n) asm volatile("s_waitcnt lgkmcnt(" #n ")" ::: "memory")
; #define PG8_BAR __builtin_amdgcn_s_barrier()
; #define PG8_SCHED __builtin_amdgcn_sched_barrier(0)
; template <class Epi, class Sched, bool ALIGN_EPI = false, bool SP2 = false, bool F16 = false>
; __device__ __forceinline__ void gemm_phase(PG8_LAS unsigned char* lds, const Gemm g, const Sched& S, const Epi& E, const int wid_in) {
;     ...
;             PG8_WAIT_V(8); PG8_WAIT_L(0); PG8_BAR; PG8_MMA(1, 0, At, B0); PG8_MMA(1, 1, At, B1); PG8_BAR; PG8_SCHED;
;             PG8_LDB(B0, 1, 0); PG8_LDB(B1, 1, 1); PG8_SCHED; PG8_LDA(At, 1, 0); PG8_STAGE(PG8_SA(0, 1), a2 + hstep, voffA);
;             PG8_WAIT_V(8); PG8_WAIT_L(0); PG8_BAR; PG8_MMA(0, 0, At, B0); PG8_MMA(0, 1, At, B1); PG8_BAR; PG8_SCHED;
	v_mfma_f32_16x16x32_bf16 v[60:63], v[128:131], v[176:179], v[60:63]
	v_mfma_f32_16x16x32_bf16 v[56:59], v[136:139], v[176:179], v[56:59]
	v_mfma_f32_16x16x32_bf16 v[44:47], v[128:131], v[192:195], v[44:47]
	v_mfma_f32_16x16x32_bf16 v[40:43], v[136:139], v[192:195], v[40:43]
	v_mfma_f32_16x16x32_bf16 v[28:31], v[128:131], v[200:203], v[28:31]
	v_mfma_f32_16x16x32_bf16 v[24:27], v[136:139], v[200:203], v[24:27]
	v_mfma_f32_16x16x32_bf16 v[12:15], v[128:131], v[208:211], v[12:15]
	v_mfma_f32_16x16x32_bf16 v[8:11], v[136:139], v[208:211], v[8:11]
	v_mfma_f32_16x16x32_bf16 v[60:63], v[132:135], v[180:183], v[60:63]
	v_mfma_f32_16x16x32_bf16 v[56:59], v[140:143], v[180:183], v[56:59]
	v_mfma_f32_16x16x32_bf16 v[44:47], v[132:135], v[196:199], v[44:47]
	v_mfma_f32_16x16x32_bf16 v[40:43], v[140:143], v[196:199], v[40:43]
	v_mfma_f32_16x16x32_bf16 v[28:31], v[132:135], v[204:207], v[28:31]
	v_mfma_f32_16x16x32_bf16 v[24:27], v[140:143], v[204:207], v[24:27]
	v_mfma_f32_16x16x32_bf16 v[12:15], v[132:135], v[212:215], v[12:15]
	v_mfma_f32_16x16x32_bf16 v[8:11], v[140:143], v[212:215], v[8:11]
	v_mfma_f32_16x16x32_bf16 v[52:55], v[144:147], v[176:179], v[52:55]
	v_mfma_f32_16x16x32_bf16 v[48:51], v[168:171], v[176:179], v[48:51]
	v_mfma_f32_16x16x32_bf16 v[36:39], v[144:147], v[192:195], v[36:39]
	v_mfma_f32_16x16x32_bf16 v[32:35], v[168:171], v[192:195], v[32:35]
	v_mfma_f32_16x16x32_bf16 v[20:23], v[144:147], v[200:203], v[20:23]
	v_mfma_f32_16x16x32_bf16 v[16:19], v[168:171], v[200:203], v[16:19]
	v_mfma_f32_16x16x32_bf16 v[4:7], v[144:147], v[208:211], v[4:7]
	v_mfma_f32_16x16x32_bf16 v[0:3], v[168:171], v[208:211], v[0:3]
	v_mfma_f32_16x16x32_bf16 v[52:55], v[148:151], v[180:183], v[52:55]
	v_mfma_f32_16x16x32_bf16 v[48:51], v[172:175], v[180:183], v[48:51]
	v_mfma_f32_16x16x32_bf16 v[36:39], v[148:151], v[196:199], v[36:39]
	v_mfma_f32_16x16x32_bf16 v[32:35], v[172:175], v[196:199], v[32:35]
	v_mfma_f32_16x16x32_bf16 v[20:23], v[148:151], v[204:207], v[20:23]
	v_mfma_f32_16x16x32_bf16 v[16:19], v[172:175], v[204:207], v[16:19]
	v_mfma_f32_16x16x32_bf16 v[4:7], v[148:151], v[212:215], v[4:7]
	v_mfma_f32_16x16x32_bf16 v[0:3], v[172:175], v[212:215], v[0:3]
	s_barrier
	s_add_i32 s60, 0, 0x18000
	s_add_i32 s61, 0, 0x1c000
	v_add_u32_e32 v140, s60, v188
	v_add_u32_e32 v172, s61, v188
	ds_read_b128 v[128:131], v140
	ds_read_b128 v[132:135], v140 offset:1024
	ds_read_b128 v[136:139], v140 offset:2048
	ds_read_b128 v[140:143], v140 offset:3072
	ds_read_b128 v[144:147], v172
	ds_read_b128 v[148:151], v172 offset:1024
	ds_read_b128 v[168:171], v172 offset:2048
	ds_read_b128 v[172:175], v172 offset:3072
	s_add_u32 s36, s48, 0xb0000
	s_addc_u32 s37, s49, 0
	s_mov_b32 m0, s90
	v_lshl_add_u64 v[222:223], s[36:37], 0, v[152:153]
	ds_read_b128 v[176:179], v191 offset:32768
	ds_read_b128 v[180:183], v191 offset:33792
	ds_read_b128 v[192:195], v191 offset:34816
	ds_read_b128 v[196:199], v191 offset:35840
	ds_read_b128 v[200:203], v191 offset:36864
	ds_read_b128 v[204:207], v191 offset:37888
	ds_read_b128 v[208:211], v191 offset:38912
	ds_read_b128 v[212:215], v191 offset:39936
	global_load_lds_dwordx4 v[222:223], off
	v_lshl_add_u64 v[222:223], s[36:37], 0, v[156:157]
	s_mov_b32 m0, s41
	s_nop 0
	global_load_lds_dwordx4 v[222:223], off
	s_waitcnt vmcnt(8)
	s_waitcnt lgkmcnt(0)
	s_barrier
	v_mfma_f32_16x16x32_bf16 v[124:127], v[128:131], v[176:179], v[124:127]
	v_mfma_f32_16x16x32_bf16 v[120:123], v[136:139], v[176:179], v[120:123]
	v_mfma_f32_16x16x32_bf16 v[108:111], v[128:131], v[192:195], v[108:111]
	v_mfma_f32_16x16x32_bf16 v[104:107], v[136:139], v[192:195], v[104:107]
	v_mfma_f32_16x16x32_bf16 v[92:95], v[128:131], v[200:203], v[92:95]
	v_mfma_f32_16x16x32_bf16 v[88:91], v[136:139], v[200:203], v[88:91]
	v_mfma_f32_16x16x32_bf16 v[76:79], v[128:131], v[208:211], v[76:79]
	v_mfma_f32_16x16x32_bf16 v[72:75], v[136:139], v[208:211], v[72:75]
	v_mfma_f32_16x16x32_bf16 v[124:127], v[132:135], v[180:183], v[124:127]
	v_mfma_f32_16x16x32_bf16 v[120:123], v[140:143], v[180:183], v[120:123]
	v_mfma_f32_16x16x32_bf16 v[108:111], v[132:135], v[196:199], v[108:111]
	v_mfma_f32_16x16x32_bf16 v[104:107], v[140:143], v[196:199], v[104:107]
	v_mfma_f32_16x16x32_bf16 v[92:95], v[132:135], v[204:207], v[92:95]
	v_mfma_f32_16x16x32_bf16 v[88:91], v[140:143], v[204:207], v[88:91]
	v_mfma_f32_16x16x32_bf16 v[76:79], v[132:135], v[212:215], v[76:79]
	v_mfma_f32_16x16x32_bf16 v[72:75], v[140:143], v[212:215], v[72:75]
	v_mfma_f32_16x16x32_bf16 v[116:119], v[144:147], v[176:179], v[116:119]
	v_mfma_f32_16x16x32_bf16 v[112:115], v[168:171], v[176:179], v[112:115]
	v_mfma_f32_16x16x32_bf16 v[100:103], v[144:147], v[192:195], v[100:103]
	v_mfma_f32_16x16x32_bf16 v[96:99], v[168:171], v[192:195], v[96:99]
	v_mfma_f32_16x16x32_bf16 v[84:87], v[144:147], v[200:203], v[84:87]
	v_mfma_f32_16x16x32_bf16 v[80:83], v[168:171], v[200:203], v[80:83]
	v_mfma_f32_16x16x32_bf16 v[68:71], v[144:147], v[208:211], v[68:71]
	v_mfma_f32_16x16x32_bf16 v[64:67], v[168:171], v[208:211], v[64:67]
	v_mfma_f32_16x16x32_bf16 v[116:119], v[148:151], v[180:183], v[116:119]
	v_mfma_f32_16x16x32_bf16 v[112:115], v[172:175], v[180:183], v[112:115]
	v_mfma_f32_16x16x32_bf16 v[100:103], v[148:151], v[196:199], v[100:103]
	v_mfma_f32_16x16x32_bf16 v[96:99], v[172:175], v[196:199], v[96:99]
	v_mfma_f32_16x16x32_bf16 v[84:87], v[148:151], v[204:207], v[84:87]
	v_mfma_f32_16x16x32_bf16 v[80:83], v[172:175], v[204:207], v[80:83]
	v_mfma_f32_16x16x32_bf16 v[68:71], v[148:151], v[212:215], v[68:71]
	v_mfma_f32_16x16x32_bf16 v[64:67], v[172:175], v[212:215], v[64:67]
	s_barrier
; #define PG8_STAGE(bufoff, gbase, voff) do { _Pragma("unroll") for (int _i = 0; _i < 2; ++_i) \
;         __builtin_amdgcn_global_load_lds((const unsigned*)((const char*)(gbase) + (voff)[_i]), (PG8_LAS unsigned*)(lds + (bufoff) + ldsw + _i * 8192), 16, 0, 0); } while (0)
; #define PG8_LDA(dst, b, h) do { _Pragma("unroll") for (int m = 0; m < 4; ++m) _Pragma("unroll") for (int k = 0; k < 2; ++k) dst[m][k] = *(const PG8_LAS bf16x8*)(lds + PG8_SA(b, h) + aoff + m * 2048 + k * 1024); } while (0)
; #define PG8_BAR __builtin_amdgcn_s_barrier()
; template <class Epi, class Sched, bool ALIGN_EPI = false, bool SP2 = false, bool F16 = false>
; __device__ __forceinline__ void gemm_phase(PG8_LAS unsigned char* lds, const Gemm g, const Sched& S, const Epi& E, const int wid_in) {
;     ...
;             PG8_LDA(At, 1, 1); PG8_STAGE(PG8_SB(1, 0), b3, voffB); PG8_STAGE(PG8_SB(1, 1), b3 + hstep, voffB); PG8_STAGE(PG8_SA(1, 0), a3, voffA);
;             PG8_WAIT_V(8); PG8_WAIT_L(0); PG8_BAR; PG8_MMA(1, 0, At, B0); PG8_MMA(1, 1, At, B1); PG8_BAR; PG8_SCHED;
;             } else {
;             PG8_LDB(B0, 0, 0); PG8_SCHED; PG8_LDA(At, 0, 0); PG8_STAGE(PG8_SA(1, 1), a1 + hstep, voffA);
;             PG8_WAIT_L(8); PG8_BAR; PG8_WAIT_L(0); PG8_MMA(0, 0, At, B0); PG8_BAR; PG8_SCHED;
;             PG8_LDB(B1, 0, 1); PG8_STAGE(PG8_SB(0, 0), b2, voffB);
;             PG8_BAR; PG8_WAIT_L(0); PG8_MMA(0, 1, At, B1); PG8_BAR;
;             PG8_LDA(At, 0, 1); PG8_STAGE(PG8_SA(0, 0), a2, voffA);
;             PG8_BAR; PG8_WAIT_L(0); PG8_MMA(1, 0, At, B0); PG8_BAR; PG8_SCHED;
;             PG8_STAGE(PG8_SB(0, 1), b2 + hstep, voffB);
;             PG8_WAIT_V(6); PG8_BAR; PG8_MMA(1, 1, At, B1); PG8_BAR;
;             PG8_LDB(B0, 1, 0); PG8_SCHED; PG8_LDA(At, 1, 0); PG8_STAGE(PG8_SA(0, 1), a2 + hstep, voffA);
;             PG8_WAIT_L(8); PG8_BAR; PG8_WAIT_L(0); PG8_MMA(0, 0, At, B0); PG8_BAR; PG8_SCHED;
;             PG8_LDB(B1, 1, 1); PG8_STAGE(PG8_SB(1, 0), b3, voffB);
;             PG8_BAR; PG8_WAIT_L(0); PG8_MMA(0, 1, At, B1); PG8_BAR;
;             PG8_LDA(At, 1, 1); PG8_STAGE(PG8_SA(1, 0), a3, voffA);
;             PG8_BAR; PG8_WAIT_L(0); PG8_MMA(1, 0, At, B0); PG8_BAR; PG8_SCHED;
;             PG8_STAGE(PG8_SB(1, 1), b3 + hstep, voffB);
;             PG8_WAIT_V(6); PG8_BAR; PG8_MMA(1, 1, At, B1); PG8_BAR;
;             }
;         }
;         if constexpr (ALIGN_EPI) { if (wr == 0) PG8_BAR; }
	s_add_i32 s36, s60, s68
	v_lshl_add_u64 v[184:185], v[184:185], 0, s[30:31]
	s_mov_b32 m0, s36
	ds_read_b128 v[176:179], v191 offset:49152
	ds_read_b128 v[180:183], v191 offset:50176
	ds_read_b128 v[192:195], v191 offset:51200
	ds_read_b128 v[196:199], v191 offset:52224
	ds_read_b128 v[200:203], v191 offset:53248
	ds_read_b128 v[204:207], v191 offset:54272
	ds_read_b128 v[208:211], v191 offset:55296
	ds_read_b128 v[212:215], v191 offset:56320
	global_load_lds_dwordx4 v[184:185], off
	s_add_i32 m0, s36, 0x2000
	s_add_u32 s36, s46, 0xb0080
	v_lshl_add_u64 v[184:185], v[216:217], 0, s[30:31]
	s_addc_u32 s37, s47, 0
	s_add_i32 s46, s61, s68
	global_load_lds_dwordx4 v[184:185], off
	v_lshl_add_u64 v[184:185], s[36:37], 0, v[154:155]
	s_mov_b32 m0, s46
	s_nop 0
	global_load_lds_dwordx4 v[184:185], off
	v_lshl_add_u64 v[184:185], s[36:37], 0, v[158:159]
	s_add_i32 m0, s46, 0x2000
	s_nop 0
	global_load_lds_dwordx4 v[184:185], off
	v_lshl_add_u64 v[184:185], v[218:219], 0, s[30:31]
	s_mov_b32 m0, s75
	s_nop 0
	global_load_lds_dwordx4 v[184:185], off
	v_lshl_add_u64 v[184:185], v[220:221], 0, s[30:31]
	s_mov_b32 m0, s67
	s_nop 0
	global_load_lds_dwordx4 v[184:185], off
	s_waitcnt vmcnt(8)
	s_waitcnt lgkmcnt(0)
	s_barrier
	v_mfma_f32_16x16x32_bf16 v[60:63], v[128:131], v[176:179], v[60:63]
	v_mfma_f32_16x16x32_bf16 v[56:59], v[136:139], v[176:179], v[56:59]
	v_mfma_f32_16x16x32_bf16 v[44:47], v[128:131], v[192:195], v[44:47]
	v_mfma_f32_16x16x32_bf16 v[40:43], v[136:139], v[192:195], v[40:43]
	v_mfma_f32_16x16x32_bf16 v[28:31], v[128:131], v[200:203], v[28:31]
	v_mfma_f32_16x16x32_bf16 v[24:27], v[136:139], v[200:203], v[24:27]
	v_mfma_f32_16x16x32_bf16 v[12:15], v[128:131], v[208:211], v[12:15]
	v_mfma_f32_16x16x32_bf16 v[8:11], v[136:139], v[208:211], v[8:11]
	v_mfma_f32_16x16x32_bf16 v[60:63], v[132:135], v[180:183], v[60:63]
	v_mfma_f32_16x16x32_bf16 v[56:59], v[140:143], v[180:183], v[56:59]
	v_mfma_f32_16x16x32_bf16 v[44:47], v[132:135], v[196:199], v[44:47]
	v_mfma_f32_16x16x32_bf16 v[40:43], v[140:143], v[196:199], v[40:43]
	v_mfma_f32_16x16x32_bf16 v[28:31], v[132:135], v[204:207], v[28:31]
	v_mfma_f32_16x16x32_bf16 v[24:27], v[140:143], v[204:207], v[24:27]
	v_mfma_f32_16x16x32_bf16 v[12:15], v[132:135], v[212:215], v[12:15]
	v_mfma_f32_16x16x32_bf16 v[8:11], v[140:143], v[212:215], v[8:11]
	v_mfma_f32_16x16x32_bf16 v[52:55], v[144:147], v[176:179], v[52:55]
	v_mfma_f32_16x16x32_bf16 v[48:51], v[168:171], v[176:179], v[48:51]
	v_mfma_f32_16x16x32_bf16 v[36:39], v[144:147], v[192:195], v[36:39]
	v_mfma_f32_16x16x32_bf16 v[32:35], v[168:171], v[192:195], v[32:35]
	v_mfma_f32_16x16x32_bf16 v[20:23], v[144:147], v[200:203], v[20:23]
	v_mfma_f32_16x16x32_bf16 v[16:19], v[168:171], v[200:203], v[16:19]
	v_mfma_f32_16x16x32_bf16 v[4:7], v[144:147], v[208:211], v[4:7]
	v_mfma_f32_16x16x32_bf16 v[0:3], v[168:171], v[208:211], v[0:3]
	v_mfma_f32_16x16x32_bf16 v[52:55], v[148:151], v[180:183], v[52:55]
	v_mfma_f32_16x16x32_bf16 v[48:51], v[172:175], v[180:183], v[48:51]
	v_mfma_f32_16x16x32_bf16 v[36:39], v[148:151], v[196:199], v[36:39]
	v_mfma_f32_16x16x32_bf16 v[32:35], v[172:175], v[196:199], v[32:35]
	v_mfma_f32_16x16x32_bf16 v[20:23], v[148:151], v[204:207], v[20:23]
	v_mfma_f32_16x16x32_bf16 v[16:19], v[172:175], v[204:207], v[16:19]
	v_mfma_f32_16x16x32_bf16 v[4:7], v[148:151], v[212:215], v[4:7]
	v_mfma_f32_16x16x32_bf16 v[0:3], v[172:175], v[212:215], v[0:3]
	s_barrier
	s_add_i32 s59, s59, 2
	s_add_u32 s43, s43, 0x100
	s_addc_u32 s58, s58, 0
	s_cmp_gt_u32 s59, 41
	s_mov_b64 s[36:37], s[44:45]
	s_cbranch_scc0 .LBB0_2040
	s_and_b64 vcc, exec, s[16:17]
	s_cbranch_vccz .LBB0_2043
	s_barrier

; #define PG8_STAGE(bufoff, gbase, voff) do { _Pragma("unroll") for (int _i = 0; _i < 2; ++_i) \
;         __builtin_amdgcn_global_load_lds((const unsigned*)((const char*)(gbase) + (voff)[_i]), (PG8_LAS unsigned*)(lds + (bufoff) + ldsw + _i * 8192), 16, 0, 0); } while (0)
; #define PG8_LDA(dst, b, h) do { _Pragma("unroll") for (int m = 0; m < 4; ++m) _Pragma("unroll") for (int k = 0; k < 2; ++k) dst[m][k] = *(const PG8_LAS bf16x8*)(lds + PG8_SA(b, h) + aoff + m * 2048 + k * 1024); } while (0)
; #define PG8_LDB(dst, b, h) do { _Pragma("unroll") for (int n = 0; n < 2; ++n) _Pragma("unroll") for (int k = 0; k < 2; ++k) dst[n][k] = *(const PG8_LAS bf16x8*)(lds + PG8_SB(b, h) + boff + n * 2048 + k * 1024); } while (0)
; #define PG8_MMA(ai, bj, At, Bt) do { __builtin_amdgcn_s_setprio(1); _Pragma("unroll") for (int m = 0; m < 4; ++m) _Pragma("unroll") for (int n = 0; n < 2; ++n) _Pragma("unroll") for (int k = 0; k < 2; ++k) \
;         acc[ai][bj][m][n] = mma16<F16>(Bt[n][k], At[m][k], acc[ai][bj][m][n]); __builtin_amdgcn_s_setprio(0); } while (0)
; #define PG8_WAIT_V(n) asm volatile("s_waitcnt vmcnt(" #n ")" ::: "memory")
; #define PG8_WAIT_L(n) asm volatile("s_waitcnt lgkmcnt(" #n ")" ::: "memory")
; template <class Epi, class Sched, bool ALIGN_EPI = false, bool SP2 = false, bool F16 = false>
; __device__ __forceinline__ void gemm_phase(PG8_LAS unsigned char* lds, const Gemm g, const Sched& S, const Epi& E, const int wid_in) {
;     ...
;             const bool last = (t == nt - 2);
;             const char* a1 = cA + (size_t)(t + 1) * kstep;
;             const char* a2 = last ? nA : cA + (size_t)(t + 2) * kstep; const char* b2 = last ? nB : cB + (size_t)(t + 2) * kstep;
;             const char* a3 = a2 + kstep; const char* b3 = b2 + kstep;
;             if (last && has_next) S.a_ready(nxt);
;             if constexpr (SP2) {
;             PG8_LDB(B0, 0, 0); PG8_LDB(B1, 0, 1); PG8_SCHED; PG8_LDA(At, 0, 0); PG8_STAGE(PG8_SA(1, 1), a1 + hstep, voffA);
;             PG8_WAIT_V(8); PG8_WAIT_L(0); PG8_BAR; PG8_MMA(0, 0, At, B0); PG8_MMA(0, 1, At, B1); PG8_BAR; PG8_SCHED;
;             PG8_LDA(At, 0, 1); PG8_STAGE(PG8_SB(0, 0), b2, voffB); PG8_STAGE(PG8_SB(0, 1), b2 + hstep, voffB); PG8_STAGE(PG8_SA(0, 0), a2, voffA);
;             PG8_WAIT_V(8); PG8_WAIT_L(0); PG8_BAR; PG8_MMA(1, 0, At, B0); PG8_MMA(1, 1, At, B1); PG8_BAR; PG8_SCHED;
.LBB0_2136:
	ds_read_b128 v[112:115], v235
	ds_read_b128 v[116:119], v235 offset:1024
	ds_read_b128 v[128:131], v235 offset:2048
	ds_read_b128 v[132:135], v235 offset:3072
	ds_read_b128 v[144:147], v236
	ds_read_b128 v[148:151], v236 offset:1024
	ds_read_b128 v[152:155], v236 offset:2048
	ds_read_b128 v[156:159], v236 offset:3072
	s_add_u32 s45, s52, 0xfffc0080
	s_addc_u32 s51, s53, -1
	s_cmp_eq_u32 s43, 12
	s_cselect_b32 s57, s14, s51
	s_cselect_b32 s56, s15, s45
	s_cselect_b32 s55, s37, s42
	s_cselect_b32 s54, s40, s41
	s_mov_b32 m0, s91
	v_lshl_add_u64 v[192:193], s[52:53], 0, v[204:205]
	ds_read_b128 v[160:163], v237
	ds_read_b128 v[164:167], v237 offset:1024
	ds_read_b128 v[168:171], v237 offset:2048
	ds_read_b128 v[172:175], v237 offset:3072
	ds_read_b128 v[176:179], v237 offset:4096
	ds_read_b128 v[180:183], v237 offset:5120
	ds_read_b128 v[184:187], v237 offset:6144
	ds_read_b128 v[188:191], v237 offset:7168
	global_load_lds_dwordx4 v[192:193], off
	v_lshl_add_u64 v[192:193], s[52:53], 0, v[206:207]
	s_add_i32 m0, s74, 0xe000
	s_nop 0
	global_load_lds_dwordx4 v[192:193], off
	s_waitcnt vmcnt(8)
	s_waitcnt lgkmcnt(0)
	s_barrier
	v_mfma_f32_16x16x32_f16 v[140:143], v[112:115], v[160:163], v[140:143]
	v_mfma_f32_16x16x32_f16 v[136:139], v[128:131], v[160:163], v[136:139]
	v_mfma_f32_16x16x32_f16 v[108:111], v[112:115], v[168:171], v[108:111]
	v_mfma_f32_16x16x32_f16 v[104:107], v[128:131], v[168:171], v[104:107]
	v_mfma_f32_16x16x32_f16 v[92:95], v[112:115], v[176:179], v[92:95]
	v_mfma_f32_16x16x32_f16 v[88:91], v[128:131], v[176:179], v[88:91]
	v_mfma_f32_16x16x32_f16 v[76:79], v[112:115], v[184:187], v[76:79]
	v_mfma_f32_16x16x32_f16 v[72:75], v[128:131], v[184:187], v[72:75]
	v_mfma_f32_16x16x32_f16 v[140:143], v[116:119], v[164:167], v[140:143]
	v_mfma_f32_16x16x32_f16 v[136:139], v[132:135], v[164:167], v[136:139]
	v_mfma_f32_16x16x32_f16 v[108:111], v[116:119], v[172:175], v[108:111]
	v_mfma_f32_16x16x32_f16 v[104:107], v[132:135], v[172:175], v[104:107]
	v_mfma_f32_16x16x32_f16 v[92:95], v[116:119], v[180:183], v[92:95]
	v_mfma_f32_16x16x32_f16 v[88:91], v[132:135], v[180:183], v[88:91]
	v_mfma_f32_16x16x32_f16 v[76:79], v[116:119], v[188:191], v[76:79]
	v_mfma_f32_16x16x32_f16 v[72:75], v[132:135], v[188:191], v[72:75]
	v_mfma_f32_16x16x32_f16 v[124:127], v[144:147], v[160:163], v[124:127]
	v_mfma_f32_16x16x32_f16 v[120:123], v[152:155], v[160:163], v[120:123]
	v_mfma_f32_16x16x32_f16 v[100:103], v[144:147], v[168:171], v[100:103]
	v_mfma_f32_16x16x32_f16 v[96:99], v[152:155], v[168:171], v[96:99]
	v_mfma_f32_16x16x32_f16 v[84:87], v[144:147], v[176:179], v[84:87]
	v_mfma_f32_16x16x32_f16 v[80:83], v[152:155], v[176:179], v[80:83]
	v_mfma_f32_16x16x32_f16 v[68:71], v[144:147], v[184:187], v[68:71]
	v_mfma_f32_16x16x32_f16 v[64:67], v[152:155], v[184:187], v[64:67]
	v_mfma_f32_16x16x32_f16 v[124:127], v[148:151], v[164:167], v[124:127]
	v_mfma_f32_16x16x32_f16 v[120:123], v[156:159], v[164:167], v[120:123]
	v_mfma_f32_16x16x32_f16 v[100:103], v[148:151], v[172:175], v[100:103]
	v_mfma_f32_16x16x32_f16 v[96:99], v[156:159], v[172:175], v[96:99]
	v_mfma_f32_16x16x32_f16 v[84:87], v[148:151], v[180:183], v[84:87]
	v_mfma_f32_16x16x32_f16 v[80:83], v[156:159], v[180:183], v[80:83]
	v_mfma_f32_16x16x32_f16 v[68:71], v[148:151], v[188:191], v[68:71]
	v_mfma_f32_16x16x32_f16 v[64:67], v[156:159], v[188:191], v[64:67]
	s_barrier
	s_add_i32 s45, s63, s68
	v_lshl_add_u64 v[192:193], s[54:55], 0, v[198:199]
	s_mov_b32 m0, s45
	ds_read_b128 v[160:163], v237 offset:16384
	ds_read_b128 v[164:167], v237 offset:17408
	ds_read_b128 v[168:171], v237 offset:18432
	ds_read_b128 v[172:175], v237 offset:19456
	ds_read_b128 v[176:179], v237 offset:20480
	ds_read_b128 v[180:183], v237 offset:21504
	ds_read_b128 v[184:187], v237 offset:22528
	ds_read_b128 v[188:191], v237 offset:23552
	global_load_lds_dwordx4 v[192:193], off
	s_add_i32 m0, s45, 0x2000
	s_add_u32 s84, s54, 0x40000
	v_lshl_add_u64 v[194:195], s[54:55], 0, v[202:203]
	s_addc_u32 s85, s55, 0
	s_add_i32 s45, s64, s68
	global_load_lds_dwordx4 v[194:195], off
	v_lshl_add_u64 v[212:213], s[84:85], 0, v[198:199]
	s_mov_b32 m0, s45
	v_lshl_add_u64 v[214:215], s[56:57], 0, v[200:201]
	global_load_lds_dwordx4 v[212:213], off
	v_lshl_add_u64 v[212:213], s[84:85], 0, v[202:203]
	s_add_i32 m0, s45, 0x2000
	s_nop 0
	global_load_lds_dwordx4 v[212:213], off
	v_lshl_add_u64 v[212:213], s[56:57], 0, v[196:197]
	s_mov_b32 m0, s74
	s_nop 0
	global_load_lds_dwordx4 v[212:213], off
	s_mov_b32 m0, s66
	s_nop 0
	global_load_lds_dwordx4 v[214:215], off
	s_waitcnt vmcnt(8)
	s_waitcnt lgkmcnt(0)
	s_barrier
; #define PG8_STAGE(bufoff, gbase, voff) do { _Pragma("unroll") for (int _i = 0; _i < 2; ++_i) \
;         __builtin_amdgcn_global_load_lds((const unsigned*)((const char*)(gbase) + (voff)[_i]), (PG8_LAS unsigned*)(lds + (bufoff) + ldsw + _i * 8192), 16, 0, 0); } while (0)
; #define PG8_LDA(dst, b, h) do { _Pragma("unroll") for (int m = 0; m < 4; ++m) _Pragma("unroll") for (int k = 0; k < 2; ++k) dst[m][k] = *(const PG8_LAS bf16x8*)(lds + PG8_SA(b, h) + aoff + m * 2048 + k * 1024); } while (0)
; #define PG8_LDB(dst, b, h) do { _Pragma("unroll") for (int n = 0; n < 2; ++n) _Pragma("unroll") for (int k = 0; k < 2; ++k) dst[n][k] = *(const PG8_LAS bf16x8*)(lds + PG8_SB(b, h) + boff + n * 2048 + k * 1024); } while (0)
; #define PG8_MMA(ai, bj, At, Bt) do { __builtin_amdgcn_s_setprio(1); _Pragma("unroll") for (int m = 0; m < 4; ++m) _Pragma("unroll") for (int n = 0; n < 2; ++n) _Pragma("unroll") for (int k = 0; k < 2; ++k) \
;         acc[ai][bj][m][n] = mma16<F16>(Bt[n][k], At[m][k], acc[ai][bj][m][n]); __builtin_amdgcn_s_setprio(0); } while (0)
; #define PG8_WAIT_V(n) asm volatile("s_waitcnt vmcnt(" #n ")" ::: "memory")
; #define PG8_WAIT_L(n) asm volatile("s_waitcnt lgkmcnt(" #n ")" ::: "memory")
; #define PG8_BAR __builtin_amdgcn_s_barrier()
; #define PG8_SCHED __builtin_amdgcn_sched_barrier(0)
; template <class Epi, class Sched, bool ALIGN_EPI = false, bool SP2 = false, bool F16 = false>
; __device__ __forceinline__ void gemm_phase(PG8_LAS unsigned char* lds, const Gemm g, const Sched& S, const Epi& E, const int wid_in) {
;     ...
;             PG8_WAIT_V(8); PG8_WAIT_L(0); PG8_BAR; PG8_MMA(1, 0, At, B0); PG8_MMA(1, 1, At, B1); PG8_BAR; PG8_SCHED;
;             PG8_LDB(B0, 1, 0); PG8_LDB(B1, 1, 1); PG8_SCHED; PG8_LDA(At, 1, 0); PG8_STAGE(PG8_SA(0, 1), a2 + hstep, voffA);
;             PG8_WAIT_V(8); PG8_WAIT_L(0); PG8_BAR; PG8_MMA(0, 0, At, B0); PG8_MMA(0, 1, At, B1); PG8_BAR; PG8_SCHED;
	v_mfma_f32_16x16x32_f16 v[60:63], v[112:115], v[160:163], v[60:63]
	v_mfma_f32_16x16x32_f16 v[56:59], v[128:131], v[160:163], v[56:59]
	v_mfma_f32_16x16x32_f16 v[44:47], v[112:115], v[168:171], v[44:47]
	v_mfma_f32_16x16x32_f16 v[40:43], v[128:131], v[168:171], v[40:43]
	v_mfma_f32_16x16x32_f16 v[28:31], v[112:115], v[176:179], v[28:31]
	v_mfma_f32_16x16x32_f16 v[24:27], v[128:131], v[176:179], v[24:27]
	v_mfma_f32_16x16x32_f16 v[12:15], v[112:115], v[184:187], v[12:15]
	v_mfma_f32_16x16x32_f16 v[8:11], v[128:131], v[184:187], v[8:11]
	v_mfma_f32_16x16x32_f16 v[60:63], v[116:119], v[164:167], v[60:63]
	v_mfma_f32_16x16x32_f16 v[56:59], v[132:135], v[164:167], v[56:59]
	v_mfma_f32_16x16x32_f16 v[44:47], v[116:119], v[172:175], v[44:47]
	v_mfma_f32_16x16x32_f16 v[40:43], v[132:135], v[172:175], v[40:43]
	v_mfma_f32_16x16x32_f16 v[28:31], v[116:119], v[180:183], v[28:31]
	v_mfma_f32_16x16x32_f16 v[24:27], v[132:135], v[180:183], v[24:27]
	v_mfma_f32_16x16x32_f16 v[12:15], v[116:119], v[188:191], v[12:15]
	v_mfma_f32_16x16x32_f16 v[8:11], v[132:135], v[188:191], v[8:11]
	v_mfma_f32_16x16x32_f16 v[52:55], v[144:147], v[160:163], v[52:55]
	v_mfma_f32_16x16x32_f16 v[48:51], v[152:155], v[160:163], v[48:51]
	v_mfma_f32_16x16x32_f16 v[36:39], v[144:147], v[168:171], v[36:39]
	v_mfma_f32_16x16x32_f16 v[32:35], v[152:155], v[168:171], v[32:35]
	v_mfma_f32_16x16x32_f16 v[20:23], v[144:147], v[176:179], v[20:23]
	v_mfma_f32_16x16x32_f16 v[16:19], v[152:155], v[176:179], v[16:19]
	v_mfma_f32_16x16x32_f16 v[4:7], v[144:147], v[184:187], v[4:7]
	v_mfma_f32_16x16x32_f16 v[0:3], v[152:155], v[184:187], v[0:3]
	v_mfma_f32_16x16x32_f16 v[52:55], v[148:151], v[164:167], v[52:55]
	v_mfma_f32_16x16x32_f16 v[48:51], v[156:159], v[164:167], v[48:51]
	v_mfma_f32_16x16x32_f16 v[36:39], v[148:151], v[172:175], v[36:39]
	v_mfma_f32_16x16x32_f16 v[32:35], v[156:159], v[172:175], v[32:35]
	v_mfma_f32_16x16x32_f16 v[20:23], v[148:151], v[180:183], v[20:23]
	v_mfma_f32_16x16x32_f16 v[16:19], v[156:159], v[180:183], v[16:19]
	v_mfma_f32_16x16x32_f16 v[4:7], v[148:151], v[188:191], v[4:7]
	v_mfma_f32_16x16x32_f16 v[0:3], v[156:159], v[188:191], v[0:3]
	s_barrier
	s_add_i32 s45, 0, 0x18000
	s_add_i32 s51, 0, 0x1c000
	v_add_u32_e32 v132, s45, v234
	v_add_u32_e32 v156, s51, v234
	ds_read_b128 v[112:115], v132
	ds_read_b128 v[116:119], v132 offset:1024
	ds_read_b128 v[128:131], v132 offset:2048
	ds_read_b128 v[132:135], v132 offset:3072
	ds_read_b128 v[144:147], v156
	ds_read_b128 v[148:151], v156 offset:1024
	ds_read_b128 v[152:155], v156 offset:2048
	ds_read_b128 v[156:159], v156 offset:3072
	s_add_u32 s56, s56, 0x40000
	s_addc_u32 s57, s57, 0
	s_mov_b32 m0, s90
	v_lshl_add_u64 v[216:217], s[56:57], 0, v[196:197]
	ds_read_b128 v[160:163], v237 offset:32768
	ds_read_b128 v[164:167], v237 offset:33792
	ds_read_b128 v[168:171], v237 offset:34816
	ds_read_b128 v[172:175], v237 offset:35840
	ds_read_b128 v[176:179], v237 offset:36864
	ds_read_b128 v[180:183], v237 offset:37888
	ds_read_b128 v[184:187], v237 offset:38912
	ds_read_b128 v[188:191], v237 offset:39936
	global_load_lds_dwordx4 v[216:217], off
	v_lshl_add_u64 v[216:217], s[56:57], 0, v[200:201]
	s_mov_b32 m0, s59
	s_nop 0
	global_load_lds_dwordx4 v[216:217], off
	s_waitcnt vmcnt(8)
	s_waitcnt lgkmcnt(0)
	s_barrier
	v_mfma_f32_16x16x32_f16 v[140:143], v[112:115], v[160:163], v[140:143]
	v_mfma_f32_16x16x32_f16 v[136:139], v[128:131], v[160:163], v[136:139]
	v_mfma_f32_16x16x32_f16 v[108:111], v[112:115], v[168:171], v[108:111]
	v_mfma_f32_16x16x32_f16 v[104:107], v[128:131], v[168:171], v[104:107]
	v_mfma_f32_16x16x32_f16 v[92:95], v[112:115], v[176:179], v[92:95]
	v_mfma_f32_16x16x32_f16 v[88:91], v[128:131], v[176:179], v[88:91]
	v_mfma_f32_16x16x32_f16 v[76:79], v[112:115], v[184:187], v[76:79]
	v_mfma_f32_16x16x32_f16 v[72:75], v[128:131], v[184:187], v[72:75]
	v_mfma_f32_16x16x32_f16 v[140:143], v[116:119], v[164:167], v[140:143]
	v_mfma_f32_16x16x32_f16 v[136:139], v[132:135], v[164:167], v[136:139]
	v_mfma_f32_16x16x32_f16 v[108:111], v[116:119], v[172:175], v[108:111]
	v_mfma_f32_16x16x32_f16 v[104:107], v[132:135], v[172:175], v[104:107]
	v_mfma_f32_16x16x32_f16 v[92:95], v[116:119], v[180:183], v[92:95]
	v_mfma_f32_16x16x32_f16 v[88:91], v[132:135], v[180:183], v[88:91]
	v_mfma_f32_16x16x32_f16 v[76:79], v[116:119], v[188:191], v[76:79]
	v_mfma_f32_16x16x32_f16 v[72:75], v[132:135], v[188:191], v[72:75]
	v_mfma_f32_16x16x32_f16 v[124:127], v[144:147], v[160:163], v[124:127]
	v_mfma_f32_16x16x32_f16 v[120:123], v[152:155], v[160:163], v[120:123]
	v_mfma_f32_16x16x32_f16 v[100:103], v[144:147], v[168:171], v[100:103]
	v_mfma_f32_16x16x32_f16 v[96:99], v[152:155], v[168:171], v[96:99]
	v_mfma_f32_16x16x32_f16 v[84:87], v[144:147], v[176:179], v[84:87]
	v_mfma_f32_16x16x32_f16 v[80:83], v[152:155], v[176:179], v[80:83]
	v_mfma_f32_16x16x32_f16 v[68:71], v[144:147], v[184:187], v[68:71]
	v_mfma_f32_16x16x32_f16 v[64:67], v[152:155], v[184:187], v[64:67]
	v_mfma_f32_16x16x32_f16 v[124:127], v[148:151], v[164:167], v[124:127]
	v_mfma_f32_16x16x32_f16 v[120:123], v[156:159], v[164:167], v[120:123]
	v_mfma_f32_16x16x32_f16 v[100:103], v[148:151], v[172:175], v[100:103]
	v_mfma_f32_16x16x32_f16 v[96:99], v[156:159], v[172:175], v[96:99]
	v_mfma_f32_16x16x32_f16 v[84:87], v[148:151], v[180:183], v[84:87]
	v_mfma_f32_16x16x32_f16 v[80:83], v[156:159], v[180:183], v[80:83]
	v_mfma_f32_16x16x32_f16 v[68:71], v[148:151], v[188:191], v[68:71]
	v_mfma_f32_16x16x32_f16 v[64:67], v[156:159], v[188:191], v[64:67]
	s_barrier
; #define PG8_STAGE(bufoff, gbase, voff) do { _Pragma("unroll") for (int _i = 0; _i < 2; ++_i) \
;         __builtin_amdgcn_global_load_lds((const unsigned*)((const char*)(gbase) + (voff)[_i]), (PG8_LAS unsigned*)(lds + (bufoff) + ldsw + _i * 8192), 16, 0, 0); } while (0)
; #define PG8_LDA(dst, b, h) do { _Pragma("unroll") for (int m = 0; m < 4; ++m) _Pragma("unroll") for (int k = 0; k < 2; ++k) dst[m][k] = *(const PG8_LAS bf16x8*)(lds + PG8_SA(b, h) + aoff + m * 2048 + k * 1024); } while (0)
; #define PG8_BAR __builtin_amdgcn_s_barrier()
; template <class Epi, class Sched, bool ALIGN_EPI = false, bool SP2 = false, bool F16 = false>
; __device__ __forceinline__ void gemm_phase(PG8_LAS unsigned char* lds, const Gemm g, const Sched& S, const Epi& E, const int wid_in) {
;     ...
;             PG8_LDA(At, 1, 1); PG8_STAGE(PG8_SB(1, 0), b3, voffB); PG8_STAGE(PG8_SB(1, 1), b3 + hstep, voffB); PG8_STAGE(PG8_SA(1, 0), a3, voffA);
;             PG8_WAIT_V(8); PG8_WAIT_L(0); PG8_BAR; PG8_MMA(1, 0, At, B0); PG8_MMA(1, 1, At, B1); PG8_BAR; PG8_SCHED;
;             } else {
;             PG8_LDB(B0, 0, 0); PG8_SCHED; PG8_LDA(At, 0, 0); PG8_STAGE(PG8_SA(1, 1), a1 + hstep, voffA);
;             PG8_WAIT_L(8); PG8_BAR; PG8_WAIT_L(0); PG8_MMA(0, 0, At, B0); PG8_BAR; PG8_SCHED;
;             PG8_LDB(B1, 0, 1); PG8_STAGE(PG8_SB(0, 0), b2, voffB);
;             PG8_BAR; PG8_WAIT_L(0); PG8_MMA(0, 1, At, B1); PG8_BAR;
;             PG8_LDA(At, 0, 1); PG8_STAGE(PG8_SA(0, 0), a2, voffA);
;             PG8_BAR; PG8_WAIT_L(0); PG8_MMA(1, 0, At, B0); PG8_BAR; PG8_SCHED;
;             PG8_STAGE(PG8_SB(0, 1), b2 + hstep, voffB);
;             PG8_WAIT_V(6); PG8_BAR; PG8_MMA(1, 1, At, B1); PG8_BAR;
;             PG8_LDB(B0, 1, 0); PG8_SCHED; PG8_LDA(At, 1, 0); PG8_STAGE(PG8_SA(0, 1), a2 + hstep, voffA);
;             PG8_WAIT_L(8); PG8_BAR; PG8_WAIT_L(0); PG8_MMA(0, 0, At, B0); PG8_BAR; PG8_SCHED;
;             PG8_LDB(B1, 1, 1); PG8_STAGE(PG8_SB(1, 0), b3, voffB);
;             PG8_BAR; PG8_WAIT_L(0); PG8_MMA(0, 1, At, B1); PG8_BAR;
;             PG8_LDA(At, 1, 1); PG8_STAGE(PG8_SA(1, 0), a3, voffA);
;             PG8_BAR; PG8_WAIT_L(0); PG8_MMA(1, 0, At, B0); PG8_BAR; PG8_SCHED;
;             PG8_STAGE(PG8_SB(1, 1), b3 + hstep, voffB);
;             PG8_WAIT_V(6); PG8_BAR; PG8_MMA(1, 1, At, B1); PG8_BAR;
;             }
;         }
;         if constexpr (ALIGN_EPI) { if (wr == 0) PG8_BAR; }
	s_add_i32 s45, s45, s68
	v_lshl_add_u64 v[192:193], v[192:193], 0, s[34:35]
	s_mov_b32 m0, s45
	ds_read_b128 v[160:163], v237 offset:49152
	ds_read_b128 v[164:167], v237 offset:50176
	ds_read_b128 v[168:171], v237 offset:51200
	ds_read_b128 v[172:175], v237 offset:52224
	ds_read_b128 v[176:179], v237 offset:53248
	ds_read_b128 v[180:183], v237 offset:54272
	ds_read_b128 v[184:187], v237 offset:55296
	ds_read_b128 v[188:191], v237 offset:56320
	global_load_lds_dwordx4 v[192:193], off
	s_add_i32 m0, s45, 0x2000
	s_add_u32 s54, s54, 0x40080
	v_lshl_add_u64 v[192:193], v[194:195], 0, s[34:35]
	s_addc_u32 s55, s55, 0
	s_add_i32 s45, s51, s68
	global_load_lds_dwordx4 v[192:193], off
	v_lshl_add_u64 v[192:193], s[54:55], 0, v[198:199]
	s_mov_b32 m0, s45
	s_nop 0
	global_load_lds_dwordx4 v[192:193], off
	v_lshl_add_u64 v[192:193], s[54:55], 0, v[202:203]
	s_add_i32 m0, s45, 0x2000
	s_nop 0
	global_load_lds_dwordx4 v[192:193], off
	v_lshl_add_u64 v[192:193], v[212:213], 0, s[34:35]
	s_mov_b32 m0, s75
	s_nop 0
	global_load_lds_dwordx4 v[192:193], off
	v_lshl_add_u64 v[192:193], v[214:215], 0, s[34:35]
	s_mov_b32 m0, s67
	s_nop 0
	global_load_lds_dwordx4 v[192:193], off
	s_waitcnt vmcnt(8)
	s_waitcnt lgkmcnt(0)
	s_barrier
	v_mfma_f32_16x16x32_f16 v[60:63], v[112:115], v[160:163], v[60:63]
	v_mfma_f32_16x16x32_f16 v[56:59], v[128:131], v[160:163], v[56:59]
	v_mfma_f32_16x16x32_f16 v[44:47], v[112:115], v[168:171], v[44:47]
	v_mfma_f32_16x16x32_f16 v[40:43], v[128:131], v[168:171], v[40:43]
	v_mfma_f32_16x16x32_f16 v[28:31], v[112:115], v[176:179], v[28:31]
	v_mfma_f32_16x16x32_f16 v[24:27], v[128:131], v[176:179], v[24:27]
	v_mfma_f32_16x16x32_f16 v[12:15], v[112:115], v[184:187], v[12:15]
	v_mfma_f32_16x16x32_f16 v[8:11], v[128:131], v[184:187], v[8:11]
	v_mfma_f32_16x16x32_f16 v[60:63], v[116:119], v[164:167], v[60:63]
	v_mfma_f32_16x16x32_f16 v[56:59], v[132:135], v[164:167], v[56:59]
	v_mfma_f32_16x16x32_f16 v[44:47], v[116:119], v[172:175], v[44:47]
	v_mfma_f32_16x16x32_f16 v[40:43], v[132:135], v[172:175], v[40:43]
	v_mfma_f32_16x16x32_f16 v[28:31], v[116:119], v[180:183], v[28:31]
	v_mfma_f32_16x16x32_f16 v[24:27], v[132:135], v[180:183], v[24:27]
	v_mfma_f32_16x16x32_f16 v[12:15], v[116:119], v[188:191], v[12:15]
	v_mfma_f32_16x16x32_f16 v[8:11], v[132:135], v[188:191], v[8:11]
	v_mfma_f32_16x16x32_f16 v[52:55], v[144:147], v[160:163], v[52:55]
	v_mfma_f32_16x16x32_f16 v[48:51], v[152:155], v[160:163], v[48:51]
	v_mfma_f32_16x16x32_f16 v[36:39], v[144:147], v[168:171], v[36:39]
	v_mfma_f32_16x16x32_f16 v[32:35], v[152:155], v[168:171], v[32:35]
	v_mfma_f32_16x16x32_f16 v[20:23], v[144:147], v[176:179], v[20:23]
	v_mfma_f32_16x16x32_f16 v[16:19], v[152:155], v[176:179], v[16:19]
	v_mfma_f32_16x16x32_f16 v[4:7], v[144:147], v[184:187], v[4:7]
	v_mfma_f32_16x16x32_f16 v[0:3], v[152:155], v[184:187], v[0:3]
	v_mfma_f32_16x16x32_f16 v[52:55], v[148:151], v[164:167], v[52:55]
	v_mfma_f32_16x16x32_f16 v[48:51], v[156:159], v[164:167], v[48:51]
	v_mfma_f32_16x16x32_f16 v[36:39], v[148:151], v[172:175], v[36:39]
	v_mfma_f32_16x16x32_f16 v[32:35], v[156:159], v[172:175], v[32:35]
	v_mfma_f32_16x16x32_f16 v[20:23], v[148:151], v[180:183], v[20:23]
	v_mfma_f32_16x16x32_f16 v[16:19], v[156:159], v[180:183], v[16:19]
	v_mfma_f32_16x16x32_f16 v[4:7], v[148:151], v[188:191], v[4:7]
	v_mfma_f32_16x16x32_f16 v[0:3], v[156:159], v[188:191], v[0:3]
	s_barrier
	s_add_i32 s43, s43, 2
	s_add_u32 s52, s52, 0x100
	s_addc_u32 s53, s53, 0
	s_add_u32 s41, s41, 0x100
	s_addc_u32 s42, s42, 0
	s_cmp_gt_u32 s43, 13
	s_cbranch_scc0 .LBB0_2136
	s_and_b64 vcc, exec, s[16:17]
	s_cbranch_vccz .LBB0_2139
	s_barrier

; #define PG8_STAGE(bufoff, gbase, voff) do { _Pragma("unroll") for (int _i = 0; _i < 2; ++_i) \
;         __builtin_amdgcn_global_load_lds((const unsigned*)((const char*)(gbase) + (voff)[_i]), (PG8_LAS unsigned*)(lds + (bufoff) + ldsw + _i * 8192), 16, 0, 0); } while (0)
; #define PG8_LDA(dst, b, h) do { _Pragma("unroll") for (int m = 0; m < 4; ++m) _Pragma("unroll") for (int k = 0; k < 2; ++k) dst[m][k] = *(const PG8_LAS bf16x8*)(lds + PG8_SA(b, h) + aoff + m * 2048 + k * 1024); } while (0)
; #define PG8_LDB(dst, b, h) do { _Pragma("unroll") for (int n = 0; n < 2; ++n) _Pragma("unroll") for (int k = 0; k < 2; ++k) dst[n][k] = *(const PG8_LAS bf16x8*)(lds + PG8_SB(b, h) + boff + n * 2048 + k * 1024); } while (0)
; #define PG8_MMA(ai, bj, At, Bt) do { __builtin_amdgcn_s_setprio(1); _Pragma("unroll") for (int m = 0; m < 4; ++m) _Pragma("unroll") for (int n = 0; n < 2; ++n) _Pragma("unroll") for (int k = 0; k < 2; ++k) \
;         acc[ai][bj][m][n] = mma16<F16>(Bt[n][k], At[m][k], acc[ai][bj][m][n]); __builtin_amdgcn_s_setprio(0); } while (0)
; #define PG8_WAIT_V(n) asm volatile("s_waitcnt vmcnt(" #n ")" ::: "memory")
; #define PG8_WAIT_L(n) asm volatile("s_waitcnt lgkmcnt(" #n ")" ::: "memory")
; template <class Epi, class Sched, bool ALIGN_EPI = false, bool SP2 = false, bool F16 = false>
; __device__ __forceinline__ void gemm_phase(PG8_LAS unsigned char* lds, const Gemm g, const Sched& S, const Epi& E, const int wid_in) {
;     ...
;             const bool last = (t == nt - 2);
;             const char* a1 = cA + (size_t)(t + 1) * kstep;
;             const char* a2 = last ? nA : cA + (size_t)(t + 2) * kstep; const char* b2 = last ? nB : cB + (size_t)(t + 2) * kstep;
;             const char* a3 = a2 + kstep; const char* b3 = b2 + kstep;
;             if (last && has_next) S.a_ready(nxt);
;             if constexpr (SP2) {
;             PG8_LDB(B0, 0, 0); PG8_LDB(B1, 0, 1); PG8_SCHED; PG8_LDA(At, 0, 0); PG8_STAGE(PG8_SA(1, 1), a1 + hstep, voffA);
;             PG8_WAIT_V(8); PG8_WAIT_L(0); PG8_BAR; PG8_MMA(0, 0, At, B0); PG8_MMA(0, 1, At, B1); PG8_BAR; PG8_SCHED;
;             PG8_LDA(At, 0, 1); PG8_STAGE(PG8_SB(0, 0), b2, voffB); PG8_STAGE(PG8_SB(0, 1), b2 + hstep, voffB); PG8_STAGE(PG8_SA(0, 0), a2, voffA);
;             PG8_WAIT_V(8); PG8_WAIT_L(0); PG8_BAR; PG8_MMA(1, 0, At, B0); PG8_MMA(1, 1, At, B1); PG8_BAR; PG8_SCHED;
.LBB0_2226:
	ds_read_b128 v[128:131], v183
	ds_read_b128 v[132:135], v183 offset:1024
	ds_read_b128 v[136:139], v183 offset:2048
	ds_read_b128 v[140:143], v183 offset:3072
	ds_read_b128 v[144:147], v184
	ds_read_b128 v[148:151], v184 offset:1024
	ds_read_b128 v[152:155], v184 offset:2048
	ds_read_b128 v[174:177], v184 offset:3072
	s_add_u32 s43, s48, 0xfffc0080
	s_addc_u32 s50, s49, -1
	s_cmp_eq_u32 s42, 12
	s_cselect_b32 s53, s13, s50
	s_cselect_b32 s52, s23, s43
	s_cselect_b32 s51, s35, s41
	s_cselect_b32 s50, s37, s40
	s_mov_b32 m0, s91
	v_lshl_add_u64 v[178:179], s[48:49], 0, v[166:167]
	ds_read_b128 v[188:191], v185
	ds_read_b128 v[192:195], v185 offset:1024
	ds_read_b128 v[196:199], v185 offset:2048
	ds_read_b128 v[200:203], v185 offset:3072
	ds_read_b128 v[204:207], v185 offset:4096
	ds_read_b128 v[208:211], v185 offset:5120
	ds_read_b128 v[212:215], v185 offset:6144
	ds_read_b128 v[216:219], v185 offset:7168
	global_load_lds_dwordx4 v[178:179], off
	v_lshl_add_u64 v[178:179], s[48:49], 0, v[168:169]
	s_add_i32 m0, s74, 0xe000
	s_nop 0
	global_load_lds_dwordx4 v[178:179], off
	s_waitcnt vmcnt(8)
	s_waitcnt lgkmcnt(0)
	s_barrier
	v_mfma_f32_16x16x32_f16 v[124:127], v[128:131], v[188:191], v[124:127]
	v_mfma_f32_16x16x32_f16 v[120:123], v[136:139], v[188:191], v[120:123]
	v_mfma_f32_16x16x32_f16 v[108:111], v[128:131], v[196:199], v[108:111]
	v_mfma_f32_16x16x32_f16 v[104:107], v[136:139], v[196:199], v[104:107]
	v_mfma_f32_16x16x32_f16 v[92:95], v[128:131], v[204:207], v[92:95]
	v_mfma_f32_16x16x32_f16 v[88:91], v[136:139], v[204:207], v[88:91]
	v_mfma_f32_16x16x32_f16 v[76:79], v[128:131], v[212:215], v[76:79]
	v_mfma_f32_16x16x32_f16 v[72:75], v[136:139], v[212:215], v[72:75]
	v_mfma_f32_16x16x32_f16 v[124:127], v[132:135], v[192:195], v[124:127]
	v_mfma_f32_16x16x32_f16 v[120:123], v[140:143], v[192:195], v[120:123]
	v_mfma_f32_16x16x32_f16 v[108:111], v[132:135], v[200:203], v[108:111]
	v_mfma_f32_16x16x32_f16 v[104:107], v[140:143], v[200:203], v[104:107]
	v_mfma_f32_16x16x32_f16 v[92:95], v[132:135], v[208:211], v[92:95]
	v_mfma_f32_16x16x32_f16 v[88:91], v[140:143], v[208:211], v[88:91]
	v_mfma_f32_16x16x32_f16 v[76:79], v[132:135], v[216:219], v[76:79]
	v_mfma_f32_16x16x32_f16 v[72:75], v[140:143], v[216:219], v[72:75]
	v_mfma_f32_16x16x32_f16 v[116:119], v[144:147], v[188:191], v[116:119]
	v_mfma_f32_16x16x32_f16 v[112:115], v[152:155], v[188:191], v[112:115]
	v_mfma_f32_16x16x32_f16 v[100:103], v[144:147], v[196:199], v[100:103]
	v_mfma_f32_16x16x32_f16 v[96:99], v[152:155], v[196:199], v[96:99]
	v_mfma_f32_16x16x32_f16 v[84:87], v[144:147], v[204:207], v[84:87]
	v_mfma_f32_16x16x32_f16 v[80:83], v[152:155], v[204:207], v[80:83]
	v_mfma_f32_16x16x32_f16 v[68:71], v[144:147], v[212:215], v[68:71]
	v_mfma_f32_16x16x32_f16 v[64:67], v[152:155], v[212:215], v[64:67]
	v_mfma_f32_16x16x32_f16 v[116:119], v[148:151], v[192:195], v[116:119]
	v_mfma_f32_16x16x32_f16 v[112:115], v[174:177], v[192:195], v[112:115]
	v_mfma_f32_16x16x32_f16 v[100:103], v[148:151], v[200:203], v[100:103]
	v_mfma_f32_16x16x32_f16 v[96:99], v[174:177], v[200:203], v[96:99]
	v_mfma_f32_16x16x32_f16 v[84:87], v[148:151], v[208:211], v[84:87]
	v_mfma_f32_16x16x32_f16 v[80:83], v[174:177], v[208:211], v[80:83]
	v_mfma_f32_16x16x32_f16 v[68:71], v[148:151], v[216:219], v[68:71]
	v_mfma_f32_16x16x32_f16 v[64:67], v[174:177], v[216:219], v[64:67]
	s_barrier
	s_add_i32 s43, s84, s68
	v_lshl_add_u64 v[178:179], s[50:51], 0, v[158:159]
	s_mov_b32 m0, s43
	ds_read_b128 v[188:191], v185 offset:16384
	ds_read_b128 v[192:195], v185 offset:17408
	ds_read_b128 v[196:199], v185 offset:18432
	ds_read_b128 v[200:203], v185 offset:19456
	ds_read_b128 v[204:207], v185 offset:20480
	ds_read_b128 v[208:211], v185 offset:21504
	ds_read_b128 v[212:215], v185 offset:22528
	ds_read_b128 v[216:219], v185 offset:23552
	global_load_lds_dwordx4 v[178:179], off
	s_add_i32 m0, s43, 0x2000
	s_add_u32 s54, s50, 0x40000
	v_lshl_add_u64 v[220:221], s[50:51], 0, v[162:163]
	s_addc_u32 s55, s51, 0
	s_add_i32 s43, s93, s68
	global_load_lds_dwordx4 v[220:221], off
	v_lshl_add_u64 v[222:223], s[54:55], 0, v[158:159]
	s_mov_b32 m0, s43
	v_lshl_add_u64 v[224:225], s[52:53], 0, v[160:161]
	global_load_lds_dwordx4 v[222:223], off
	v_lshl_add_u64 v[222:223], s[54:55], 0, v[162:163]
	s_add_i32 m0, s43, 0x2000
	s_nop 0
	global_load_lds_dwordx4 v[222:223], off
	v_lshl_add_u64 v[222:223], s[52:53], 0, v[156:157]
	s_mov_b32 m0, s74
	s_nop 0
	global_load_lds_dwordx4 v[222:223], off
	s_mov_b32 m0, s66
	s_nop 0
	global_load_lds_dwordx4 v[224:225], off
	s_waitcnt vmcnt(8)
	s_waitcnt lgkmcnt(0)
	s_barrier
; #define PG8_STAGE(bufoff, gbase, voff) do { _Pragma("unroll") for (int _i = 0; _i < 2; ++_i) \
;         __builtin_amdgcn_global_load_lds((const unsigned*)((const char*)(gbase) + (voff)[_i]), (PG8_LAS unsigned*)(lds + (bufoff) + ldsw + _i * 8192), 16, 0, 0); } while (0)
; #define PG8_LDA(dst, b, h) do { _Pragma("unroll") for (int m = 0; m < 4; ++m) _Pragma("unroll") for (int k = 0; k < 2; ++k) dst[m][k] = *(const PG8_LAS bf16x8*)(lds + PG8_SA(b, h) + aoff + m * 2048 + k * 1024); } while (0)
; #define PG8_LDB(dst, b, h) do { _Pragma("unroll") for (int n = 0; n < 2; ++n) _Pragma("unroll") for (int k = 0; k < 2; ++k) dst[n][k] = *(const PG8_LAS bf16x8*)(lds + PG8_SB(b, h) + boff + n * 2048 + k * 1024); } while (0)
; #define PG8_MMA(ai, bj, At, Bt) do { __builtin_amdgcn_s_setprio(1); _Pragma("unroll") for (int m = 0; m < 4; ++m) _Pragma("unroll") for (int n = 0; n < 2; ++n) _Pragma("unroll") for (int k = 0; k < 2; ++k) \
;         acc[ai][bj][m][n] = mma16<F16>(Bt[n][k], At[m][k], acc[ai][bj][m][n]); __builtin_amdgcn_s_setprio(0); } while (0)
; #define PG8_WAIT_V(n) asm volatile("s_waitcnt vmcnt(" #n ")" ::: "memory")
; #define PG8_WAIT_L(n) asm volatile("s_waitcnt lgkmcnt(" #n ")" ::: "memory")
; #define PG8_BAR __builtin_amdgcn_s_barrier()
; #define PG8_SCHED __builtin_amdgcn_sched_barrier(0)
; template <class Epi, class Sched, bool ALIGN_EPI = false, bool SP2 = false, bool F16 = false>
; __device__ __forceinline__ void gemm_phase(PG8_LAS unsigned char* lds, const Gemm g, const Sched& S, const Epi& E, const int wid_in) {
;     ...
;             PG8_WAIT_V(8); PG8_WAIT_L(0); PG8_BAR; PG8_MMA(1, 0, At, B0); PG8_MMA(1, 1, At, B1); PG8_BAR; PG8_SCHED;
;             PG8_LDB(B0, 1, 0); PG8_LDB(B1, 1, 1); PG8_SCHED; PG8_LDA(At, 1, 0); PG8_STAGE(PG8_SA(0, 1), a2 + hstep, voffA);
;             PG8_WAIT_V(8); PG8_WAIT_L(0); PG8_BAR; PG8_MMA(0, 0, At, B0); PG8_MMA(0, 1, At, B1); PG8_BAR; PG8_SCHED;
	v_mfma_f32_16x16x32_f16 v[60:63], v[128:131], v[188:191], v[60:63]
	v_mfma_f32_16x16x32_f16 v[56:59], v[136:139], v[188:191], v[56:59]
	v_mfma_f32_16x16x32_f16 v[44:47], v[128:131], v[196:199], v[44:47]
	v_mfma_f32_16x16x32_f16 v[40:43], v[136:139], v[196:199], v[40:43]
	v_mfma_f32_16x16x32_f16 v[28:31], v[128:131], v[204:207], v[28:31]
	v_mfma_f32_16x16x32_f16 v[24:27], v[136:139], v[204:207], v[24:27]
	v_mfma_f32_16x16x32_f16 v[12:15], v[128:131], v[212:215], v[12:15]
	v_mfma_f32_16x16x32_f16 v[8:11], v[136:139], v[212:215], v[8:11]
	v_mfma_f32_16x16x32_f16 v[60:63], v[132:135], v[192:195], v[60:63]
	v_mfma_f32_16x16x32_f16 v[56:59], v[140:143], v[192:195], v[56:59]
	v_mfma_f32_16x16x32_f16 v[44:47], v[132:135], v[200:203], v[44:47]
	v_mfma_f32_16x16x32_f16 v[40:43], v[140:143], v[200:203], v[40:43]
	v_mfma_f32_16x16x32_f16 v[28:31], v[132:135], v[208:211], v[28:31]
	v_mfma_f32_16x16x32_f16 v[24:27], v[140:143], v[208:211], v[24:27]
	v_mfma_f32_16x16x32_f16 v[12:15], v[132:135], v[216:219], v[12:15]
	v_mfma_f32_16x16x32_f16 v[8:11], v[140:143], v[216:219], v[8:11]
	v_mfma_f32_16x16x32_f16 v[52:55], v[144:147], v[188:191], v[52:55]
	v_mfma_f32_16x16x32_f16 v[48:51], v[152:155], v[188:191], v[48:51]
	v_mfma_f32_16x16x32_f16 v[36:39], v[144:147], v[196:199], v[36:39]
	v_mfma_f32_16x16x32_f16 v[32:35], v[152:155], v[196:199], v[32:35]
	v_mfma_f32_16x16x32_f16 v[20:23], v[144:147], v[204:207], v[20:23]
	v_mfma_f32_16x16x32_f16 v[16:19], v[152:155], v[204:207], v[16:19]
	v_mfma_f32_16x16x32_f16 v[4:7], v[144:147], v[212:215], v[4:7]
	v_mfma_f32_16x16x32_f16 v[0:3], v[152:155], v[212:215], v[0:3]
	v_mfma_f32_16x16x32_f16 v[52:55], v[148:151], v[192:195], v[52:55]
	v_mfma_f32_16x16x32_f16 v[48:51], v[174:177], v[192:195], v[48:51]
	v_mfma_f32_16x16x32_f16 v[36:39], v[148:151], v[200:203], v[36:39]
	v_mfma_f32_16x16x32_f16 v[32:35], v[174:177], v[200:203], v[32:35]
	v_mfma_f32_16x16x32_f16 v[20:23], v[148:151], v[208:211], v[20:23]
	v_mfma_f32_16x16x32_f16 v[16:19], v[174:177], v[208:211], v[16:19]
	v_mfma_f32_16x16x32_f16 v[4:7], v[148:151], v[216:219], v[4:7]
	v_mfma_f32_16x16x32_f16 v[0:3], v[174:177], v[216:219], v[0:3]
	s_barrier
	s_add_i32 s43, 0, 0x18000
	s_add_i32 s54, 0, 0x1c000
	v_add_u32_e32 v140, s43, v182
	v_add_u32_e32 v165, s54, v182
	ds_read_b128 v[128:131], v140
	ds_read_b128 v[132:135], v140 offset:1024
	ds_read_b128 v[136:139], v140 offset:2048
	ds_read_b128 v[140:143], v140 offset:3072
	ds_read_b128 v[144:147], v165
	ds_read_b128 v[148:151], v165 offset:1024
	ds_read_b128 v[152:155], v165 offset:2048
	ds_read_b128 v[174:177], v165 offset:3072
	s_add_u32 s52, s52, 0x40000
	s_addc_u32 s53, s53, 0
	s_mov_b32 m0, s90
	v_lshl_add_u64 v[226:227], s[52:53], 0, v[156:157]
	ds_read_b128 v[188:191], v185 offset:32768
	ds_read_b128 v[192:195], v185 offset:33792
	ds_read_b128 v[196:199], v185 offset:34816
	ds_read_b128 v[200:203], v185 offset:35840
	ds_read_b128 v[204:207], v185 offset:36864
	ds_read_b128 v[208:211], v185 offset:37888
	ds_read_b128 v[212:215], v185 offset:38912
	ds_read_b128 v[216:219], v185 offset:39936
	global_load_lds_dwordx4 v[226:227], off
	v_lshl_add_u64 v[226:227], s[52:53], 0, v[160:161]
	s_mov_b32 m0, s63
	s_nop 0
	global_load_lds_dwordx4 v[226:227], off
	s_waitcnt vmcnt(8)
	s_waitcnt lgkmcnt(0)
	s_barrier
	v_mfma_f32_16x16x32_f16 v[124:127], v[128:131], v[188:191], v[124:127]
	v_mfma_f32_16x16x32_f16 v[120:123], v[136:139], v[188:191], v[120:123]
	v_mfma_f32_16x16x32_f16 v[108:111], v[128:131], v[196:199], v[108:111]
	v_mfma_f32_16x16x32_f16 v[104:107], v[136:139], v[196:199], v[104:107]
	v_mfma_f32_16x16x32_f16 v[92:95], v[128:131], v[204:207], v[92:95]
	v_mfma_f32_16x16x32_f16 v[88:91], v[136:139], v[204:207], v[88:91]
	v_mfma_f32_16x16x32_f16 v[76:79], v[128:131], v[212:215], v[76:79]
	v_mfma_f32_16x16x32_f16 v[72:75], v[136:139], v[212:215], v[72:75]
	v_mfma_f32_16x16x32_f16 v[124:127], v[132:135], v[192:195], v[124:127]
	v_mfma_f32_16x16x32_f16 v[120:123], v[140:143], v[192:195], v[120:123]
	v_mfma_f32_16x16x32_f16 v[108:111], v[132:135], v[200:203], v[108:111]
	v_mfma_f32_16x16x32_f16 v[104:107], v[140:143], v[200:203], v[104:107]
	v_mfma_f32_16x16x32_f16 v[92:95], v[132:135], v[208:211], v[92:95]
	v_mfma_f32_16x16x32_f16 v[88:91], v[140:143], v[208:211], v[88:91]
	v_mfma_f32_16x16x32_f16 v[76:79], v[132:135], v[216:219], v[76:79]
	v_mfma_f32_16x16x32_f16 v[72:75], v[140:143], v[216:219], v[72:75]
	v_mfma_f32_16x16x32_f16 v[116:119], v[144:147], v[188:191], v[116:119]
	v_mfma_f32_16x16x32_f16 v[112:115], v[152:155], v[188:191], v[112:115]
	v_mfma_f32_16x16x32_f16 v[100:103], v[144:147], v[196:199], v[100:103]
	v_mfma_f32_16x16x32_f16 v[96:99], v[152:155], v[196:199], v[96:99]
	v_mfma_f32_16x16x32_f16 v[84:87], v[144:147], v[204:207], v[84:87]
	v_mfma_f32_16x16x32_f16 v[80:83], v[152:155], v[204:207], v[80:83]
	v_mfma_f32_16x16x32_f16 v[68:71], v[144:147], v[212:215], v[68:71]
	v_mfma_f32_16x16x32_f16 v[64:67], v[152:155], v[212:215], v[64:67]
	v_mfma_f32_16x16x32_f16 v[116:119], v[148:151], v[192:195], v[116:119]
	v_mfma_f32_16x16x32_f16 v[112:115], v[174:177], v[192:195], v[112:115]
	v_mfma_f32_16x16x32_f16 v[100:103], v[148:151], v[200:203], v[100:103]
	v_mfma_f32_16x16x32_f16 v[96:99], v[174:177], v[200:203], v[96:99]
	v_mfma_f32_16x16x32_f16 v[84:87], v[148:151], v[208:211], v[84:87]
	v_mfma_f32_16x16x32_f16 v[80:83], v[174:177], v[208:211], v[80:83]
	v_mfma_f32_16x16x32_f16 v[68:71], v[148:151], v[216:219], v[68:71]
	v_mfma_f32_16x16x32_f16 v[64:67], v[174:177], v[216:219], v[64:67]
	s_barrier
; #define PG8_STAGE(bufoff, gbase, voff) do { _Pragma("unroll") for (int _i = 0; _i < 2; ++_i) \
;         __builtin_amdgcn_global_load_lds((const unsigned*)((const char*)(gbase) + (voff)[_i]), (PG8_LAS unsigned*)(lds + (bufoff) + ldsw + _i * 8192), 16, 0, 0); } while (0)
; #define PG8_LDA(dst, b, h) do { _Pragma("unroll") for (int m = 0; m < 4; ++m) _Pragma("unroll") for (int k = 0; k < 2; ++k) dst[m][k] = *(const PG8_LAS bf16x8*)(lds + PG8_SA(b, h) + aoff + m * 2048 + k * 1024); } while (0)
; #define PG8_BAR __builtin_amdgcn_s_barrier()
; template <class Epi, class Sched, bool ALIGN_EPI = false, bool SP2 = false, bool F16 = false>
; __device__ __forceinline__ void gemm_phase(PG8_LAS unsigned char* lds, const Gemm g, const Sched& S, const Epi& E, const int wid_in) {
;     ...
;             PG8_LDA(At, 1, 1); PG8_STAGE(PG8_SB(1, 0), b3, voffB); PG8_STAGE(PG8_SB(1, 1), b3 + hstep, voffB); PG8_STAGE(PG8_SA(1, 0), a3, voffA);
;             PG8_WAIT_V(8); PG8_WAIT_L(0); PG8_BAR; PG8_MMA(1, 0, At, B0); PG8_MMA(1, 1, At, B1); PG8_BAR; PG8_SCHED;
;             } else {
;             PG8_LDB(B0, 0, 0); PG8_SCHED; PG8_LDA(At, 0, 0); PG8_STAGE(PG8_SA(1, 1), a1 + hstep, voffA);
;             PG8_WAIT_L(8); PG8_BAR; PG8_WAIT_L(0); PG8_MMA(0, 0, At, B0); PG8_BAR; PG8_SCHED;
;             PG8_LDB(B1, 0, 1); PG8_STAGE(PG8_SB(0, 0), b2, voffB);
;             PG8_BAR; PG8_WAIT_L(0); PG8_MMA(0, 1, At, B1); PG8_BAR;
;             PG8_LDA(At, 0, 1); PG8_STAGE(PG8_SA(0, 0), a2, voffA);
;             PG8_BAR; PG8_WAIT_L(0); PG8_MMA(1, 0, At, B0); PG8_BAR; PG8_SCHED;
;             PG8_STAGE(PG8_SB(0, 1), b2 + hstep, voffB);
;             PG8_WAIT_V(6); PG8_BAR; PG8_MMA(1, 1, At, B1); PG8_BAR;
;             PG8_LDB(B0, 1, 0); PG8_SCHED; PG8_LDA(At, 1, 0); PG8_STAGE(PG8_SA(0, 1), a2 + hstep, voffA);
;             PG8_WAIT_L(8); PG8_BAR; PG8_WAIT_L(0); PG8_MMA(0, 0, At, B0); PG8_BAR; PG8_SCHED;
;             PG8_LDB(B1, 1, 1); PG8_STAGE(PG8_SB(1, 0), b3, voffB);
;             PG8_BAR; PG8_WAIT_L(0); PG8_MMA(0, 1, At, B1); PG8_BAR;
;             PG8_LDA(At, 1, 1); PG8_STAGE(PG8_SA(1, 0), a3, voffA);
;             PG8_BAR; PG8_WAIT_L(0); PG8_MMA(1, 0, At, B0); PG8_BAR; PG8_SCHED;
;             PG8_STAGE(PG8_SB(1, 1), b3 + hstep, voffB);
;             PG8_WAIT_V(6); PG8_BAR; PG8_MMA(1, 1, At, B1); PG8_BAR;
;             }
;         }
;         if constexpr (ALIGN_EPI) { if (wr == 0) PG8_BAR; }
	s_add_i32 s43, s43, s68
	v_lshl_add_u64 v[178:179], v[178:179], 0, s[26:27]
	s_mov_b32 m0, s43
	ds_read_b128 v[188:191], v185 offset:49152
	ds_read_b128 v[192:195], v185 offset:50176
	ds_read_b128 v[196:199], v185 offset:51200
	ds_read_b128 v[200:203], v185 offset:52224
	ds_read_b128 v[204:207], v185 offset:53248
	ds_read_b128 v[208:211], v185 offset:54272
	ds_read_b128 v[212:215], v185 offset:55296
	ds_read_b128 v[216:219], v185 offset:56320
	global_load_lds_dwordx4 v[178:179], off
	s_add_i32 m0, s43, 0x2000
	s_add_u32 s50, s50, 0x40080
	v_lshl_add_u64 v[178:179], v[220:221], 0, s[26:27]
	s_addc_u32 s51, s51, 0
	s_add_i32 s43, s54, s68
	global_load_lds_dwordx4 v[178:179], off
	v_lshl_add_u64 v[178:179], s[50:51], 0, v[158:159]
	s_mov_b32 m0, s43
	s_nop 0
	global_load_lds_dwordx4 v[178:179], off
	v_lshl_add_u64 v[178:179], s[50:51], 0, v[162:163]
	s_add_i32 m0, s43, 0x2000
	s_nop 0
	global_load_lds_dwordx4 v[178:179], off
	v_lshl_add_u64 v[178:179], v[222:223], 0, s[26:27]
	s_mov_b32 m0, s75
	s_nop 0
	global_load_lds_dwordx4 v[178:179], off
	v_lshl_add_u64 v[178:179], v[224:225], 0, s[26:27]
	s_mov_b32 m0, s67
	s_nop 0
	global_load_lds_dwordx4 v[178:179], off
	s_waitcnt vmcnt(8)
	s_waitcnt lgkmcnt(0)
	s_barrier
	v_mfma_f32_16x16x32_f16 v[60:63], v[128:131], v[188:191], v[60:63]
	v_mfma_f32_16x16x32_f16 v[56:59], v[136:139], v[188:191], v[56:59]
	v_mfma_f32_16x16x32_f16 v[44:47], v[128:131], v[196:199], v[44:47]
	v_mfma_f32_16x16x32_f16 v[40:43], v[136:139], v[196:199], v[40:43]
	v_mfma_f32_16x16x32_f16 v[28:31], v[128:131], v[204:207], v[28:31]
	v_mfma_f32_16x16x32_f16 v[24:27], v[136:139], v[204:207], v[24:27]
	v_mfma_f32_16x16x32_f16 v[12:15], v[128:131], v[212:215], v[12:15]
	v_mfma_f32_16x16x32_f16 v[8:11], v[136:139], v[212:215], v[8:11]
	v_mfma_f32_16x16x32_f16 v[60:63], v[132:135], v[192:195], v[60:63]
	v_mfma_f32_16x16x32_f16 v[56:59], v[140:143], v[192:195], v[56:59]
	v_mfma_f32_16x16x32_f16 v[44:47], v[132:135], v[200:203], v[44:47]
	v_mfma_f32_16x16x32_f16 v[40:43], v[140:143], v[200:203], v[40:43]
	v_mfma_f32_16x16x32_f16 v[28:31], v[132:135], v[208:211], v[28:31]
	v_mfma_f32_16x16x32_f16 v[24:27], v[140:143], v[208:211], v[24:27]
	v_mfma_f32_16x16x32_f16 v[12:15], v[132:135], v[216:219], v[12:15]
	v_mfma_f32_16x16x32_f16 v[8:11], v[140:143], v[216:219], v[8:11]
	v_mfma_f32_16x16x32_f16 v[52:55], v[144:147], v[188:191], v[52:55]
	v_mfma_f32_16x16x32_f16 v[48:51], v[152:155], v[188:191], v[48:51]
	v_mfma_f32_16x16x32_f16 v[36:39], v[144:147], v[196:199], v[36:39]
	v_mfma_f32_16x16x32_f16 v[32:35], v[152:155], v[196:199], v[32:35]
	v_mfma_f32_16x16x32_f16 v[20:23], v[144:147], v[204:207], v[20:23]
	v_mfma_f32_16x16x32_f16 v[16:19], v[152:155], v[204:207], v[16:19]
	v_mfma_f32_16x16x32_f16 v[4:7], v[144:147], v[212:215], v[4:7]
	v_mfma_f32_16x16x32_f16 v[0:3], v[152:155], v[212:215], v[0:3]
	v_mfma_f32_16x16x32_f16 v[52:55], v[148:151], v[192:195], v[52:55]
	v_mfma_f32_16x16x32_f16 v[48:51], v[174:177], v[192:195], v[48:51]
	v_mfma_f32_16x16x32_f16 v[36:39], v[148:151], v[200:203], v[36:39]
	v_mfma_f32_16x16x32_f16 v[32:35], v[174:177], v[200:203], v[32:35]
	v_mfma_f32_16x16x32_f16 v[20:23], v[148:151], v[208:211], v[20:23]
	v_mfma_f32_16x16x32_f16 v[16:19], v[174:177], v[208:211], v[16:19]
	v_mfma_f32_16x16x32_f16 v[4:7], v[148:151], v[216:219], v[4:7]
	v_mfma_f32_16x16x32_f16 v[0:3], v[174:177], v[216:219], v[0:3]
	s_barrier
	s_add_i32 s42, s42, 2
	s_add_u32 s48, s48, 0x100
	s_addc_u32 s49, s49, 0
	s_add_u32 s40, s40, 0x100
	s_addc_u32 s41, s41, 0
	s_cmp_gt_u32 s42, 13
	s_cbranch_scc0 .LBB0_2226
	s_and_b64 vcc, exec, s[16:17]
	s_cbranch_vccz .LBB0_2229
	s_barrier

; #define PG8_STAGE(bufoff, gbase, voff) do { _Pragma("unroll") for (int _i = 0; _i < 2; ++_i) \
;         __builtin_amdgcn_global_load_lds((const unsigned*)((const char*)(gbase) + (voff)[_i]), (PG8_LAS unsigned*)(lds + (bufoff) + ldsw + _i * 8192), 16, 0, 0); } while (0)
; #define PG8_LDA(dst, b, h) do { _Pragma("unroll") for (int m = 0; m < 4; ++m) _Pragma("unroll") for (int k = 0; k < 2; ++k) dst[m][k] = *(const PG8_LAS bf16x8*)(lds + PG8_SA(b, h) + aoff + m * 2048 + k * 1024); } while (0)
; #define PG8_LDB(dst, b, h) do { _Pragma("unroll") for (int n = 0; n < 2; ++n) _Pragma("unroll") for (int k = 0; k < 2; ++k) dst[n][k] = *(const PG8_LAS bf16x8*)(lds + PG8_SB(b, h) + boff + n * 2048 + k * 1024); } while (0)
; #define PG8_MMA(ai, bj, At, Bt) do { __builtin_amdgcn_s_setprio(1); _Pragma("unroll") for (int m = 0; m < 4; ++m) _Pragma("unroll") for (int n = 0; n < 2; ++n) _Pragma("unroll") for (int k = 0; k < 2; ++k) \
;         acc[ai][bj][m][n] = mma16<F16>(Bt[n][k], At[m][k], acc[ai][bj][m][n]); __builtin_amdgcn_s_setprio(0); } while (0)
; #define PG8_WAIT_V(n) asm volatile("s_waitcnt vmcnt(" #n ")" ::: "memory")
; #define PG8_WAIT_L(n) asm volatile("s_waitcnt lgkmcnt(" #n ")" ::: "memory")
; template <class Epi, class Sched, bool ALIGN_EPI = false, bool SP2 = false, bool F16 = false>
; __device__ __forceinline__ void gemm_phase(PG8_LAS unsigned char* lds, const Gemm g, const Sched& S, const Epi& E, const int wid_in) {
;     ...
;             const bool last = (t == nt - 2);
;             const char* a1 = cA + (size_t)(t + 1) * kstep;
;             const char* a2 = last ? nA : cA + (size_t)(t + 2) * kstep; const char* b2 = last ? nB : cB + (size_t)(t + 2) * kstep;
;             const char* a3 = a2 + kstep; const char* b3 = b2 + kstep;
;             if (last && has_next) S.a_ready(nxt);
;             if constexpr (SP2) {
;             PG8_LDB(B0, 0, 0); PG8_LDB(B1, 0, 1); PG8_SCHED; PG8_LDA(At, 0, 0); PG8_STAGE(PG8_SA(1, 1), a1 + hstep, voffA);
;             PG8_WAIT_V(8); PG8_WAIT_L(0); PG8_BAR; PG8_MMA(0, 0, At, B0); PG8_MMA(0, 1, At, B1); PG8_BAR; PG8_SCHED;
;             PG8_LDA(At, 0, 1); PG8_STAGE(PG8_SB(0, 0), b2, voffB); PG8_STAGE(PG8_SB(0, 1), b2 + hstep, voffB); PG8_STAGE(PG8_SA(0, 0), a2, voffA);
;             PG8_WAIT_V(8); PG8_WAIT_L(0); PG8_BAR; PG8_MMA(1, 0, At, B0); PG8_MMA(1, 1, At, B1); PG8_BAR; PG8_SCHED;
.LBB0_2489:
	ds_read_b128 v[128:131], v189
	ds_read_b128 v[132:135], v189 offset:1024
	ds_read_b128 v[136:139], v189 offset:2048
	ds_read_b128 v[140:143], v189 offset:3072
	ds_read_b128 v[144:147], v190
	ds_read_b128 v[148:151], v190 offset:1024
	ds_read_b128 v[168:171], v190 offset:2048
	ds_read_b128 v[172:175], v190 offset:3072
	s_add_u32 s44, s42, 0xfffc0080
	s_addc_u32 s45, s43, -1
	s_cmp_eq_u32 s59, 12
	s_cselect_b32 s47, s29, s45
	s_cselect_b32 s46, s37, s44
	s_cselect_b32 s45, s27, s58
	s_cselect_b32 s44, s56, s57
	s_mov_b32 m0, s91
	v_lshl_add_u64 v[184:185], s[42:43], 0, v[160:161]
	ds_read_b128 v[176:179], v191
	ds_read_b128 v[180:183], v191 offset:1024
	ds_read_b128 v[192:195], v191 offset:2048
	ds_read_b128 v[196:199], v191 offset:3072
	ds_read_b128 v[200:203], v191 offset:4096
	ds_read_b128 v[204:207], v191 offset:5120
	ds_read_b128 v[208:211], v191 offset:6144
	ds_read_b128 v[212:215], v191 offset:7168
	global_load_lds_dwordx4 v[184:185], off
	v_lshl_add_u64 v[184:185], s[42:43], 0, v[162:163]
	s_add_i32 m0, s74, 0xe000
	s_nop 0
	global_load_lds_dwordx4 v[184:185], off
	s_waitcnt vmcnt(8)
	s_waitcnt lgkmcnt(0)
	s_barrier
	v_mfma_f32_16x16x32_bf16 v[124:127], v[128:131], v[176:179], v[124:127]
	v_mfma_f32_16x16x32_bf16 v[120:123], v[136:139], v[176:179], v[120:123]
	v_mfma_f32_16x16x32_bf16 v[108:111], v[128:131], v[192:195], v[108:111]
	v_mfma_f32_16x16x32_bf16 v[104:107], v[136:139], v[192:195], v[104:107]
	v_mfma_f32_16x16x32_bf16 v[92:95], v[128:131], v[200:203], v[92:95]
	v_mfma_f32_16x16x32_bf16 v[88:91], v[136:139], v[200:203], v[88:91]
	v_mfma_f32_16x16x32_bf16 v[76:79], v[128:131], v[208:211], v[76:79]
	v_mfma_f32_16x16x32_bf16 v[72:75], v[136:139], v[208:211], v[72:75]
	v_mfma_f32_16x16x32_bf16 v[124:127], v[132:135], v[180:183], v[124:127]
	v_mfma_f32_16x16x32_bf16 v[120:123], v[140:143], v[180:183], v[120:123]
	v_mfma_f32_16x16x32_bf16 v[108:111], v[132:135], v[196:199], v[108:111]
	v_mfma_f32_16x16x32_bf16 v[104:107], v[140:143], v[196:199], v[104:107]
	v_mfma_f32_16x16x32_bf16 v[92:95], v[132:135], v[204:207], v[92:95]
	v_mfma_f32_16x16x32_bf16 v[88:91], v[140:143], v[204:207], v[88:91]
	v_mfma_f32_16x16x32_bf16 v[76:79], v[132:135], v[212:215], v[76:79]
	v_mfma_f32_16x16x32_bf16 v[72:75], v[140:143], v[212:215], v[72:75]
	v_mfma_f32_16x16x32_bf16 v[116:119], v[144:147], v[176:179], v[116:119]
	v_mfma_f32_16x16x32_bf16 v[112:115], v[168:171], v[176:179], v[112:115]
	v_mfma_f32_16x16x32_bf16 v[100:103], v[144:147], v[192:195], v[100:103]
	v_mfma_f32_16x16x32_bf16 v[96:99], v[168:171], v[192:195], v[96:99]
	v_mfma_f32_16x16x32_bf16 v[84:87], v[144:147], v[200:203], v[84:87]
	v_mfma_f32_16x16x32_bf16 v[80:83], v[168:171], v[200:203], v[80:83]
	v_mfma_f32_16x16x32_bf16 v[68:71], v[144:147], v[208:211], v[68:71]
	v_mfma_f32_16x16x32_bf16 v[64:67], v[168:171], v[208:211], v[64:67]
	v_mfma_f32_16x16x32_bf16 v[116:119], v[148:151], v[180:183], v[116:119]
	v_mfma_f32_16x16x32_bf16 v[112:115], v[172:175], v[180:183], v[112:115]
	v_mfma_f32_16x16x32_bf16 v[100:103], v[148:151], v[196:199], v[100:103]
	v_mfma_f32_16x16x32_bf16 v[96:99], v[172:175], v[196:199], v[96:99]
	v_mfma_f32_16x16x32_bf16 v[84:87], v[148:151], v[204:207], v[84:87]
	v_mfma_f32_16x16x32_bf16 v[80:83], v[172:175], v[204:207], v[80:83]
	v_mfma_f32_16x16x32_bf16 v[68:71], v[148:151], v[212:215], v[68:71]
	v_mfma_f32_16x16x32_bf16 v[64:67], v[172:175], v[212:215], v[64:67]
	s_barrier
	s_add_i32 s60, s53, s68
	v_lshl_add_u64 v[184:185], s[44:45], 0, v[154:155]
	s_mov_b32 m0, s60
	ds_read_b128 v[176:179], v191 offset:16384
	ds_read_b128 v[180:183], v191 offset:17408
	ds_read_b128 v[192:195], v191 offset:18432
	ds_read_b128 v[196:199], v191 offset:19456
	ds_read_b128 v[200:203], v191 offset:20480
	ds_read_b128 v[204:207], v191 offset:21504
	ds_read_b128 v[208:211], v191 offset:22528
	ds_read_b128 v[212:215], v191 offset:23552
	global_load_lds_dwordx4 v[184:185], off
	s_add_i32 m0, s60, 0x2000
	s_add_u32 s60, s44, 0x40000
	v_lshl_add_u64 v[216:217], s[44:45], 0, v[158:159]
	s_addc_u32 s61, s45, 0
	s_add_i32 s62, s54, s68
	global_load_lds_dwordx4 v[216:217], off
	v_lshl_add_u64 v[218:219], s[60:61], 0, v[154:155]
	s_mov_b32 m0, s62
	v_lshl_add_u64 v[220:221], s[46:47], 0, v[156:157]
	global_load_lds_dwordx4 v[218:219], off
	v_lshl_add_u64 v[218:219], s[60:61], 0, v[158:159]
	s_add_i32 m0, s62, 0x2000
	s_nop 0
	global_load_lds_dwordx4 v[218:219], off
	v_lshl_add_u64 v[218:219], s[46:47], 0, v[152:153]
	s_mov_b32 m0, s74
	s_nop 0
	global_load_lds_dwordx4 v[218:219], off
	s_mov_b32 m0, s66
	s_nop 0
	global_load_lds_dwordx4 v[220:221], off
	s_waitcnt vmcnt(8)
	s_waitcnt lgkmcnt(0)
	s_barrier
; #define PG8_STAGE(bufoff, gbase, voff) do { _Pragma("unroll") for (int _i = 0; _i < 2; ++_i) \
;         __builtin_amdgcn_global_load_lds((const unsigned*)((const char*)(gbase) + (voff)[_i]), (PG8_LAS unsigned*)(lds + (bufoff) + ldsw + _i * 8192), 16, 0, 0); } while (0)
; #define PG8_LDA(dst, b, h) do { _Pragma("unroll") for (int m = 0; m < 4; ++m) _Pragma("unroll") for (int k = 0; k < 2; ++k) dst[m][k] = *(const PG8_LAS bf16x8*)(lds + PG8_SA(b, h) + aoff + m * 2048 + k * 1024); } while (0)
; #define PG8_LDB(dst, b, h) do { _Pragma("unroll") for (int n = 0; n < 2; ++n) _Pragma("unroll") for (int k = 0; k < 2; ++k) dst[n][k] = *(const PG8_LAS bf16x8*)(lds + PG8_SB(b, h) + boff + n * 2048 + k * 1024); } while (0)
; #define PG8_MMA(ai, bj, At, Bt) do { __builtin_amdgcn_s_setprio(1); _Pragma("unroll") for (int m = 0; m < 4; ++m) _Pragma("unroll") for (int n = 0; n < 2; ++n) _Pragma("unroll") for (int k = 0; k < 2; ++k) \
;         acc[ai][bj][m][n] = mma16<F16>(Bt[n][k], At[m][k], acc[ai][bj][m][n]); __builtin_amdgcn_s_setprio(0); } while (0)
; #define PG8_WAIT_V(n) asm volatile("s_waitcnt vmcnt(" #n ")" ::: "memory")
; #define PG8_WAIT_L(n) asm volatile("s_waitcnt lgkmcnt(" #n ")" ::: "memory")
; #define PG8_BAR __builtin_amdgcn_s_barrier()
; #define PG8_SCHED __builtin_amdgcn_sched_barrier(0)
; template <class Epi, class Sched, bool ALIGN_EPI = false, bool SP2 = false, bool F16 = false>
; __device__ __forceinline__ void gemm_phase(PG8_LAS unsigned char* lds, const Gemm g, const Sched& S, const Epi& E, const int wid_in) {
;     ...
;             PG8_WAIT_V(8); PG8_WAIT_L(0); PG8_BAR; PG8_MMA(1, 0, At, B0); PG8_MMA(1, 1, At, B1); PG8_BAR; PG8_SCHED;
;             PG8_LDB(B0, 1, 0); PG8_LDB(B1, 1, 1); PG8_SCHED; PG8_LDA(At, 1, 0); PG8_STAGE(PG8_SA(0, 1), a2 + hstep, voffA);
;             PG8_WAIT_V(8); PG8_WAIT_L(0); PG8_BAR; PG8_MMA(0, 0, At, B0); PG8_MMA(0, 1, At, B1); PG8_BAR; PG8_SCHED;
	v_mfma_f32_16x16x32_bf16 v[60:63], v[128:131], v[176:179], v[60:63]
	v_mfma_f32_16x16x32_bf16 v[56:59], v[136:139], v[176:179], v[56:59]
	v_mfma_f32_16x16x32_bf16 v[44:47], v[128:131], v[192:195], v[44:47]
	v_mfma_f32_16x16x32_bf16 v[40:43], v[136:139], v[192:195], v[40:43]
	v_mfma_f32_16x16x32_bf16 v[28:31], v[128:131], v[200:203], v[28:31]
	v_mfma_f32_16x16x32_bf16 v[24:27], v[136:139], v[200:203], v[24:27]
	v_mfma_f32_16x16x32_bf16 v[12:15], v[128:131], v[208:211], v[12:15]
	v_mfma_f32_16x16x32_bf16 v[8:11], v[136:139], v[208:211], v[8:11]
	v_mfma_f32_16x16x32_bf16 v[60:63], v[132:135], v[180:183], v[60:63]
	v_mfma_f32_16x16x32_bf16 v[56:59], v[140:143], v[180:183], v[56:59]
	v_mfma_f32_16x16x32_bf16 v[44:47], v[132:135], v[196:199], v[44:47]
	v_mfma_f32_16x16x32_bf16 v[40:43], v[140:143], v[196:199], v[40:43]
	v_mfma_f32_16x16x32_bf16 v[28:31], v[132:135], v[204:207], v[28:31]
	v_mfma_f32_16x16x32_bf16 v[24:27], v[140:143], v[204:207], v[24:27]
	v_mfma_f32_16x16x32_bf16 v[12:15], v[132:135], v[212:215], v[12:15]
	v_mfma_f32_16x16x32_bf16 v[8:11], v[140:143], v[212:215], v[8:11]
	v_mfma_f32_16x16x32_bf16 v[52:55], v[144:147], v[176:179], v[52:55]
	v_mfma_f32_16x16x32_bf16 v[48:51], v[168:171], v[176:179], v[48:51]
	v_mfma_f32_16x16x32_bf16 v[36:39], v[144:147], v[192:195], v[36:39]
	v_mfma_f32_16x16x32_bf16 v[32:35], v[168:171], v[192:195], v[32:35]
	v_mfma_f32_16x16x32_bf16 v[20:23], v[144:147], v[200:203], v[20:23]
	v_mfma_f32_16x16x32_bf16 v[16:19], v[168:171], v[200:203], v[16:19]
	v_mfma_f32_16x16x32_bf16 v[4:7], v[144:147], v[208:211], v[4:7]
	v_mfma_f32_16x16x32_bf16 v[0:3], v[168:171], v[208:211], v[0:3]
	v_mfma_f32_16x16x32_bf16 v[52:55], v[148:151], v[180:183], v[52:55]
	v_mfma_f32_16x16x32_bf16 v[48:51], v[172:175], v[180:183], v[48:51]
	v_mfma_f32_16x16x32_bf16 v[36:39], v[148:151], v[196:199], v[36:39]
	v_mfma_f32_16x16x32_bf16 v[32:35], v[172:175], v[196:199], v[32:35]
	v_mfma_f32_16x16x32_bf16 v[20:23], v[148:151], v[204:207], v[20:23]
	v_mfma_f32_16x16x32_bf16 v[16:19], v[172:175], v[204:207], v[16:19]
	v_mfma_f32_16x16x32_bf16 v[4:7], v[148:151], v[212:215], v[4:7]
	v_mfma_f32_16x16x32_bf16 v[0:3], v[172:175], v[212:215], v[0:3]
	s_barrier
	s_add_i32 s60, 0, 0x18000
	s_add_i32 s61, 0, 0x1c000
	v_add_u32_e32 v140, s60, v188
	v_add_u32_e32 v172, s61, v188
	ds_read_b128 v[128:131], v140
	ds_read_b128 v[132:135], v140 offset:1024
	ds_read_b128 v[136:139], v140 offset:2048
	ds_read_b128 v[140:143], v140 offset:3072
	ds_read_b128 v[144:147], v172
	ds_read_b128 v[148:151], v172 offset:1024
	ds_read_b128 v[168:171], v172 offset:2048
	ds_read_b128 v[172:175], v172 offset:3072
	s_add_u32 s46, s46, 0x40000
	s_addc_u32 s47, s47, 0
	s_mov_b32 m0, s90
	v_lshl_add_u64 v[222:223], s[46:47], 0, v[152:153]
	ds_read_b128 v[176:179], v191 offset:32768
	ds_read_b128 v[180:183], v191 offset:33792
	ds_read_b128 v[192:195], v191 offset:34816
	ds_read_b128 v[196:199], v191 offset:35840
	ds_read_b128 v[200:203], v191 offset:36864
	ds_read_b128 v[204:207], v191 offset:37888
	ds_read_b128 v[208:211], v191 offset:38912
	ds_read_b128 v[212:215], v191 offset:39936
	global_load_lds_dwordx4 v[222:223], off
	v_lshl_add_u64 v[222:223], s[46:47], 0, v[156:157]
	s_mov_b32 m0, s49
	s_nop 0
	global_load_lds_dwordx4 v[222:223], off
	s_waitcnt vmcnt(8)
	s_waitcnt lgkmcnt(0)
	s_barrier
	v_mfma_f32_16x16x32_bf16 v[124:127], v[128:131], v[176:179], v[124:127]
	v_mfma_f32_16x16x32_bf16 v[120:123], v[136:139], v[176:179], v[120:123]
	v_mfma_f32_16x16x32_bf16 v[108:111], v[128:131], v[192:195], v[108:111]
	v_mfma_f32_16x16x32_bf16 v[104:107], v[136:139], v[192:195], v[104:107]
	v_mfma_f32_16x16x32_bf16 v[92:95], v[128:131], v[200:203], v[92:95]
	v_mfma_f32_16x16x32_bf16 v[88:91], v[136:139], v[200:203], v[88:91]
	v_mfma_f32_16x16x32_bf16 v[76:79], v[128:131], v[208:211], v[76:79]
	v_mfma_f32_16x16x32_bf16 v[72:75], v[136:139], v[208:211], v[72:75]
	v_mfma_f32_16x16x32_bf16 v[124:127], v[132:135], v[180:183], v[124:127]
	v_mfma_f32_16x16x32_bf16 v[120:123], v[140:143], v[180:183], v[120:123]
	v_mfma_f32_16x16x32_bf16 v[108:111], v[132:135], v[196:199], v[108:111]
	v_mfma_f32_16x16x32_bf16 v[104:107], v[140:143], v[196:199], v[104:107]
	v_mfma_f32_16x16x32_bf16 v[92:95], v[132:135], v[204:207], v[92:95]
	v_mfma_f32_16x16x32_bf16 v[88:91], v[140:143], v[204:207], v[88:91]
	v_mfma_f32_16x16x32_bf16 v[76:79], v[132:135], v[212:215], v[76:79]
	v_mfma_f32_16x16x32_bf16 v[72:75], v[140:143], v[212:215], v[72:75]
	v_mfma_f32_16x16x32_bf16 v[116:119], v[144:147], v[176:179], v[116:119]
	v_mfma_f32_16x16x32_bf16 v[112:115], v[168:171], v[176:179], v[112:115]
	v_mfma_f32_16x16x32_bf16 v[100:103], v[144:147], v[192:195], v[100:103]
	v_mfma_f32_16x16x32_bf16 v[96:99], v[168:171], v[192:195], v[96:99]
	v_mfma_f32_16x16x32_bf16 v[84:87], v[144:147], v[200:203], v[84:87]
	v_mfma_f32_16x16x32_bf16 v[80:83], v[168:171], v[200:203], v[80:83]
	v_mfma_f32_16x16x32_bf16 v[68:71], v[144:147], v[208:211], v[68:71]
	v_mfma_f32_16x16x32_bf16 v[64:67], v[168:171], v[208:211], v[64:67]
	v_mfma_f32_16x16x32_bf16 v[116:119], v[148:151], v[180:183], v[116:119]
	v_mfma_f32_16x16x32_bf16 v[112:115], v[172:175], v[180:183], v[112:115]
	v_mfma_f32_16x16x32_bf16 v[100:103], v[148:151], v[196:199], v[100:103]
	v_mfma_f32_16x16x32_bf16 v[96:99], v[172:175], v[196:199], v[96:99]
	v_mfma_f32_16x16x32_bf16 v[84:87], v[148:151], v[204:207], v[84:87]
	v_mfma_f32_16x16x32_bf16 v[80:83], v[172:175], v[204:207], v[80:83]
	v_mfma_f32_16x16x32_bf16 v[68:71], v[148:151], v[212:215], v[68:71]
	v_mfma_f32_16x16x32_bf16 v[64:67], v[172:175], v[212:215], v[64:67]
	s_barrier
; #define PG8_STAGE(bufoff, gbase, voff) do { _Pragma("unroll") for (int _i = 0; _i < 2; ++_i) \
;         __builtin_amdgcn_global_load_lds((const unsigned*)((const char*)(gbase) + (voff)[_i]), (PG8_LAS unsigned*)(lds + (bufoff) + ldsw + _i * 8192), 16, 0, 0); } while (0)
; #define PG8_LDA(dst, b, h) do { _Pragma("unroll") for (int m = 0; m < 4; ++m) _Pragma("unroll") for (int k = 0; k < 2; ++k) dst[m][k] = *(const PG8_LAS bf16x8*)(lds + PG8_SA(b, h) + aoff + m * 2048 + k * 1024); } while (0)
; #define PG8_BAR __builtin_amdgcn_s_barrier()
; template <class Epi, class Sched, bool ALIGN_EPI = false, bool SP2 = false, bool F16 = false>
; __device__ __forceinline__ void gemm_phase(PG8_LAS unsigned char* lds, const Gemm g, const Sched& S, const Epi& E, const int wid_in) {
;     ...
;             PG8_LDA(At, 1, 1); PG8_STAGE(PG8_SB(1, 0), b3, voffB); PG8_STAGE(PG8_SB(1, 1), b3 + hstep, voffB); PG8_STAGE(PG8_SA(1, 0), a3, voffA);
;             PG8_WAIT_V(8); PG8_WAIT_L(0); PG8_BAR; PG8_MMA(1, 0, At, B0); PG8_MMA(1, 1, At, B1); PG8_BAR; PG8_SCHED;
;             } else {
;             PG8_LDB(B0, 0, 0); PG8_SCHED; PG8_LDA(At, 0, 0); PG8_STAGE(PG8_SA(1, 1), a1 + hstep, voffA);
;             PG8_WAIT_L(8); PG8_BAR; PG8_WAIT_L(0); PG8_MMA(0, 0, At, B0); PG8_BAR; PG8_SCHED;
;             PG8_LDB(B1, 0, 1); PG8_STAGE(PG8_SB(0, 0), b2, voffB);
;             PG8_BAR; PG8_WAIT_L(0); PG8_MMA(0, 1, At, B1); PG8_BAR;
;             PG8_LDA(At, 0, 1); PG8_STAGE(PG8_SA(0, 0), a2, voffA);
;             PG8_BAR; PG8_WAIT_L(0); PG8_MMA(1, 0, At, B0); PG8_BAR; PG8_SCHED;
;             PG8_STAGE(PG8_SB(0, 1), b2 + hstep, voffB);
;             PG8_WAIT_V(6); PG8_BAR; PG8_MMA(1, 1, At, B1); PG8_BAR;
;             PG8_LDB(B0, 1, 0); PG8_SCHED; PG8_LDA(At, 1, 0); PG8_STAGE(PG8_SA(0, 1), a2 + hstep, voffA);
;             PG8_WAIT_L(8); PG8_BAR; PG8_WAIT_L(0); PG8_MMA(0, 0, At, B0); PG8_BAR; PG8_SCHED;
;             PG8_LDB(B1, 1, 1); PG8_STAGE(PG8_SB(1, 0), b3, voffB);
;             PG8_BAR; PG8_WAIT_L(0); PG8_MMA(0, 1, At, B1); PG8_BAR;
;             PG8_LDA(At, 1, 1); PG8_STAGE(PG8_SA(1, 0), a3, voffA);
;             PG8_BAR; PG8_WAIT_L(0); PG8_MMA(1, 0, At, B0); PG8_BAR; PG8_SCHED;
;             PG8_STAGE(PG8_SB(1, 1), b3 + hstep, voffB);
;             PG8_WAIT_V(6); PG8_BAR; PG8_MMA(1, 1, At, B1); PG8_BAR;
;             }
;         }
;         if constexpr (ALIGN_EPI) { if (wr == 0) PG8_BAR; }
	s_add_i32 s46, s60, s68
	v_lshl_add_u64 v[184:185], v[184:185], 0, s[24:25]
	s_mov_b32 m0, s46
	ds_read_b128 v[176:179], v191 offset:49152
	ds_read_b128 v[180:183], v191 offset:50176
	ds_read_b128 v[192:195], v191 offset:51200
	ds_read_b128 v[196:199], v191 offset:52224
	ds_read_b128 v[200:203], v191 offset:53248
	ds_read_b128 v[204:207], v191 offset:54272
	ds_read_b128 v[208:211], v191 offset:55296
	ds_read_b128 v[212:215], v191 offset:56320
	global_load_lds_dwordx4 v[184:185], off
	s_add_i32 m0, s46, 0x2000
	s_add_u32 s44, s44, 0x40080
	v_lshl_add_u64 v[184:185], v[216:217], 0, s[24:25]
	s_addc_u32 s45, s45, 0
	s_add_i32 s46, s61, s68
	global_load_lds_dwordx4 v[184:185], off
	v_lshl_add_u64 v[184:185], s[44:45], 0, v[154:155]
	s_mov_b32 m0, s46
	s_nop 0
	global_load_lds_dwordx4 v[184:185], off
	v_lshl_add_u64 v[184:185], s[44:45], 0, v[158:159]
	s_add_i32 m0, s46, 0x2000
	s_nop 0
	global_load_lds_dwordx4 v[184:185], off
	v_lshl_add_u64 v[184:185], v[218:219], 0, s[24:25]
	s_mov_b32 m0, s75
	s_nop 0
	global_load_lds_dwordx4 v[184:185], off
	v_lshl_add_u64 v[184:185], v[220:221], 0, s[24:25]
	s_mov_b32 m0, s67
	s_nop 0
	global_load_lds_dwordx4 v[184:185], off
	s_waitcnt vmcnt(8)
	s_waitcnt lgkmcnt(0)
	s_barrier
	v_mfma_f32_16x16x32_bf16 v[60:63], v[128:131], v[176:179], v[60:63]
	v_mfma_f32_16x16x32_bf16 v[56:59], v[136:139], v[176:179], v[56:59]
	v_mfma_f32_16x16x32_bf16 v[44:47], v[128:131], v[192:195], v[44:47]
	v_mfma_f32_16x16x32_bf16 v[40:43], v[136:139], v[192:195], v[40:43]
	v_mfma_f32_16x16x32_bf16 v[28:31], v[128:131], v[200:203], v[28:31]
	v_mfma_f32_16x16x32_bf16 v[24:27], v[136:139], v[200:203], v[24:27]
	v_mfma_f32_16x16x32_bf16 v[12:15], v[128:131], v[208:211], v[12:15]
	v_mfma_f32_16x16x32_bf16 v[8:11], v[136:139], v[208:211], v[8:11]
	v_mfma_f32_16x16x32_bf16 v[60:63], v[132:135], v[180:183], v[60:63]
	v_mfma_f32_16x16x32_bf16 v[56:59], v[140:143], v[180:183], v[56:59]
	v_mfma_f32_16x16x32_bf16 v[44:47], v[132:135], v[196:199], v[44:47]
	v_mfma_f32_16x16x32_bf16 v[40:43], v[140:143], v[196:199], v[40:43]
	v_mfma_f32_16x16x32_bf16 v[28:31], v[132:135], v[204:207], v[28:31]
	v_mfma_f32_16x16x32_bf16 v[24:27], v[140:143], v[204:207], v[24:27]
	v_mfma_f32_16x16x32_bf16 v[12:15], v[132:135], v[212:215], v[12:15]
	v_mfma_f32_16x16x32_bf16 v[8:11], v[140:143], v[212:215], v[8:11]
	v_mfma_f32_16x16x32_bf16 v[52:55], v[144:147], v[176:179], v[52:55]
	v_mfma_f32_16x16x32_bf16 v[48:51], v[168:171], v[176:179], v[48:51]
	v_mfma_f32_16x16x32_bf16 v[36:39], v[144:147], v[192:195], v[36:39]
	v_mfma_f32_16x16x32_bf16 v[32:35], v[168:171], v[192:195], v[32:35]
	v_mfma_f32_16x16x32_bf16 v[20:23], v[144:147], v[200:203], v[20:23]
	v_mfma_f32_16x16x32_bf16 v[16:19], v[168:171], v[200:203], v[16:19]
	v_mfma_f32_16x16x32_bf16 v[4:7], v[144:147], v[208:211], v[4:7]
	v_mfma_f32_16x16x32_bf16 v[0:3], v[168:171], v[208:211], v[0:3]
	v_mfma_f32_16x16x32_bf16 v[52:55], v[148:151], v[180:183], v[52:55]
	v_mfma_f32_16x16x32_bf16 v[48:51], v[172:175], v[180:183], v[48:51]
	v_mfma_f32_16x16x32_bf16 v[36:39], v[148:151], v[196:199], v[36:39]
	v_mfma_f32_16x16x32_bf16 v[32:35], v[172:175], v[196:199], v[32:35]
	v_mfma_f32_16x16x32_bf16 v[20:23], v[148:151], v[204:207], v[20:23]
	v_mfma_f32_16x16x32_bf16 v[16:19], v[172:175], v[204:207], v[16:19]
	v_mfma_f32_16x16x32_bf16 v[4:7], v[148:151], v[212:215], v[4:7]
	v_mfma_f32_16x16x32_bf16 v[0:3], v[172:175], v[212:215], v[0:3]
	s_barrier
	s_add_i32 s59, s59, 2
	s_add_u32 s42, s42, 0x100
	s_addc_u32 s43, s43, 0
	s_add_u32 s57, s57, 0x100
	s_addc_u32 s58, s58, 0
	s_cmp_gt_u32 s59, 13
	s_cbranch_scc0 .LBB0_2489
	s_and_b64 vcc, exec, s[16:17]
	s_cbranch_vccz .LBB0_2492
	s_barrier

; #define PG8_STAGE(bufoff, gbase, voff) do { _Pragma("unroll") for (int _i = 0; _i < 2; ++_i) \
;         __builtin_amdgcn_global_load_lds((const unsigned*)((const char*)(gbase) + (voff)[_i]), (PG8_LAS unsigned*)(lds + (bufoff) + ldsw + _i * 8192), 16, 0, 0); } while (0)
; #define PG8_LDA(dst, b, h) do { _Pragma("unroll") for (int m = 0; m < 4; ++m) _Pragma("unroll") for (int k = 0; k < 2; ++k) dst[m][k] = *(const PG8_LAS bf16x8*)(lds + PG8_SA(b, h) + aoff + m * 2048 + k * 1024); } while (0)
; #define PG8_LDB(dst, b, h) do { _Pragma("unroll") for (int n = 0; n < 2; ++n) _Pragma("unroll") for (int k = 0; k < 2; ++k) dst[n][k] = *(const PG8_LAS bf16x8*)(lds + PG8_SB(b, h) + boff + n * 2048 + k * 1024); } while (0)
; #define PG8_MMA(ai, bj, At, Bt) do { __builtin_amdgcn_s_setprio(1); _Pragma("unroll") for (int m = 0; m < 4; ++m) _Pragma("unroll") for (int n = 0; n < 2; ++n) _Pragma("unroll") for (int k = 0; k < 2; ++k) \
;         acc[ai][bj][m][n] = mma16<F16>(Bt[n][k], At[m][k], acc[ai][bj][m][n]); __builtin_amdgcn_s_setprio(0); } while (0)
; #define PG8_WAIT_V(n) asm volatile("s_waitcnt vmcnt(" #n ")" ::: "memory")
; #define PG8_WAIT_L(n) asm volatile("s_waitcnt lgkmcnt(" #n ")" ::: "memory")
; template <class Epi, class Sched, bool ALIGN_EPI = false, bool SP2 = false, bool F16 = false>
; __device__ __forceinline__ void gemm_phase(PG8_LAS unsigned char* lds, const Gemm g, const Sched& S, const Epi& E, const int wid_in) {
;     ...
;             const bool last = (t == nt - 2);
;             const char* a1 = cA + (size_t)(t + 1) * kstep;
;             const char* a2 = last ? nA : cA + (size_t)(t + 2) * kstep; const char* b2 = last ? nB : cB + (size_t)(t + 2) * kstep;
;             const char* a3 = a2 + kstep; const char* b3 = b2 + kstep;
;             if (last && has_next) S.a_ready(nxt);
;             if constexpr (SP2) {
;             PG8_LDB(B0, 0, 0); PG8_LDB(B1, 0, 1); PG8_SCHED; PG8_LDA(At, 0, 0); PG8_STAGE(PG8_SA(1, 1), a1 + hstep, voffA);
;             PG8_WAIT_V(8); PG8_WAIT_L(0); PG8_BAR; PG8_MMA(0, 0, At, B0); PG8_MMA(0, 1, At, B1); PG8_BAR; PG8_SCHED;
;             PG8_LDA(At, 0, 1); PG8_STAGE(PG8_SB(0, 0), b2, voffB); PG8_STAGE(PG8_SB(0, 1), b2 + hstep, voffB); PG8_STAGE(PG8_SA(0, 0), a2, voffA);
;             PG8_WAIT_V(8); PG8_WAIT_L(0); PG8_BAR; PG8_MMA(1, 0, At, B0); PG8_MMA(1, 1, At, B1); PG8_BAR; PG8_SCHED;
.LBB0_2566:
	ds_read_b128 v[0:3], v193
	ds_read_b128 v[4:7], v193 offset:1024
	ds_read_b128 v[136:139], v193 offset:2048
	ds_read_b128 v[140:143], v193 offset:3072
	ds_read_b128 v[144:147], v194
	ds_read_b128 v[148:151], v194 offset:1024
	ds_read_b128 v[152:155], v194 offset:2048
	ds_read_b128 v[156:159], v194 offset:3072
	s_add_u32 s42, s36, 0xfffc0080
	s_addc_u32 s43, s37, -1
	s_cmp_eq_u32 s62, 12
	s_cselect_b32 s45, s25, s43
	s_cselect_b32 s44, s35, s42
	s_cselect_b32 s43, s23, s61
	s_cselect_b32 s42, s59, s60
	s_mov_b32 m0, s91
	v_lshl_add_u64 v[188:189], s[36:37], 0, v[168:169]
	ds_read_b128 v[176:179], v195
	ds_read_b128 v[180:183], v195 offset:1024
	ds_read_b128 v[184:187], v195 offset:2048
	ds_read_b128 v[198:201], v195 offset:3072
	ds_read_b128 v[202:205], v195 offset:4096
	ds_read_b128 v[206:209], v195 offset:5120
	ds_read_b128 v[210:213], v195 offset:6144
	ds_read_b128 v[214:217], v195 offset:7168
	global_load_lds_dwordx4 v[188:189], off
	v_lshl_add_u64 v[188:189], s[36:37], 0, v[170:171]
	s_add_i32 m0, s74, 0xe000
	s_nop 0
	global_load_lds_dwordx4 v[188:189], off
	s_waitcnt vmcnt(8)
	s_waitcnt lgkmcnt(0)
	s_barrier
	v_mfma_f32_16x16x32_f16 v[132:135], v[0:3], v[176:179], v[132:135]
	v_mfma_f32_16x16x32_f16 v[128:131], v[136:139], v[176:179], v[128:131]
	v_mfma_f32_16x16x32_f16 v[116:119], v[0:3], v[184:187], v[116:119]
	v_mfma_f32_16x16x32_f16 v[112:115], v[136:139], v[184:187], v[112:115]
	v_mfma_f32_16x16x32_f16 v[100:103], v[0:3], v[202:205], v[100:103]
	v_mfma_f32_16x16x32_f16 v[96:99], v[136:139], v[202:205], v[96:99]
	v_mfma_f32_16x16x32_f16 v[84:87], v[0:3], v[210:213], v[84:87]
	v_mfma_f32_16x16x32_f16 v[80:83], v[136:139], v[210:213], v[80:83]
	v_mfma_f32_16x16x32_f16 v[132:135], v[4:7], v[180:183], v[132:135]
	v_mfma_f32_16x16x32_f16 v[128:131], v[140:143], v[180:183], v[128:131]
	v_mfma_f32_16x16x32_f16 v[116:119], v[4:7], v[198:201], v[116:119]
	v_mfma_f32_16x16x32_f16 v[112:115], v[140:143], v[198:201], v[112:115]
	v_mfma_f32_16x16x32_f16 v[100:103], v[4:7], v[206:209], v[100:103]
	v_mfma_f32_16x16x32_f16 v[96:99], v[140:143], v[206:209], v[96:99]
	v_mfma_f32_16x16x32_f16 v[84:87], v[4:7], v[214:217], v[84:87]
	v_mfma_f32_16x16x32_f16 v[80:83], v[140:143], v[214:217], v[80:83]
	v_mfma_f32_16x16x32_f16 v[124:127], v[144:147], v[176:179], v[124:127]
	v_mfma_f32_16x16x32_f16 v[120:123], v[152:155], v[176:179], v[120:123]
	v_mfma_f32_16x16x32_f16 v[108:111], v[144:147], v[184:187], v[108:111]
	v_mfma_f32_16x16x32_f16 v[104:107], v[152:155], v[184:187], v[104:107]
	v_mfma_f32_16x16x32_f16 v[92:95], v[144:147], v[202:205], v[92:95]
	v_mfma_f32_16x16x32_f16 v[88:91], v[152:155], v[202:205], v[88:91]
	v_mfma_f32_16x16x32_f16 v[76:79], v[144:147], v[210:213], v[76:79]
	v_mfma_f32_16x16x32_f16 v[72:75], v[152:155], v[210:213], v[72:75]
	v_mfma_f32_16x16x32_f16 v[124:127], v[148:151], v[180:183], v[124:127]
	v_mfma_f32_16x16x32_f16 v[120:123], v[156:159], v[180:183], v[120:123]
	v_mfma_f32_16x16x32_f16 v[108:111], v[148:151], v[198:201], v[108:111]
	v_mfma_f32_16x16x32_f16 v[104:107], v[156:159], v[198:201], v[104:107]
	v_mfma_f32_16x16x32_f16 v[92:95], v[148:151], v[206:209], v[92:95]
	v_mfma_f32_16x16x32_f16 v[88:91], v[156:159], v[206:209], v[88:91]
	v_mfma_f32_16x16x32_f16 v[76:79], v[148:151], v[214:217], v[76:79]
	v_mfma_f32_16x16x32_f16 v[72:75], v[156:159], v[214:217], v[72:75]
	s_barrier
	s_add_i32 s63, s56, s68
	v_lshl_add_u64 v[188:189], s[42:43], 0, v[162:163]
	s_mov_b32 m0, s63
	ds_read_b128 v[176:179], v195 offset:16384
	ds_read_b128 v[180:183], v195 offset:17408
	ds_read_b128 v[184:187], v195 offset:18432
	ds_read_b128 v[198:201], v195 offset:19456
	ds_read_b128 v[202:205], v195 offset:20480
	ds_read_b128 v[206:209], v195 offset:21504
	ds_read_b128 v[210:213], v195 offset:22528
	ds_read_b128 v[214:217], v195 offset:23552
	global_load_lds_dwordx4 v[188:189], off
	s_add_i32 m0, s63, 0x2000
	s_add_u32 s64, s42, 0x40000
	v_lshl_add_u64 v[218:219], s[42:43], 0, v[166:167]
	s_addc_u32 s65, s43, 0
	s_add_i32 s63, s57, s68
	global_load_lds_dwordx4 v[218:219], off
	v_lshl_add_u64 v[220:221], s[64:65], 0, v[162:163]
	s_mov_b32 m0, s63
	v_lshl_add_u64 v[222:223], s[44:45], 0, v[164:165]
	global_load_lds_dwordx4 v[220:221], off
	v_lshl_add_u64 v[220:221], s[64:65], 0, v[166:167]
	s_add_i32 m0, s63, 0x2000
	s_nop 0
	global_load_lds_dwordx4 v[220:221], off
	v_lshl_add_u64 v[220:221], s[44:45], 0, v[160:161]
	s_mov_b32 m0, s74
	s_nop 0
	global_load_lds_dwordx4 v[220:221], off
	s_mov_b32 m0, s66
	s_nop 0
	global_load_lds_dwordx4 v[222:223], off
	s_waitcnt vmcnt(8)
	s_waitcnt lgkmcnt(0)
	s_barrier
; #define PG8_STAGE(bufoff, gbase, voff) do { _Pragma("unroll") for (int _i = 0; _i < 2; ++_i) \
;         __builtin_amdgcn_global_load_lds((const unsigned*)((const char*)(gbase) + (voff)[_i]), (PG8_LAS unsigned*)(lds + (bufoff) + ldsw + _i * 8192), 16, 0, 0); } while (0)
; #define PG8_LDA(dst, b, h) do { _Pragma("unroll") for (int m = 0; m < 4; ++m) _Pragma("unroll") for (int k = 0; k < 2; ++k) dst[m][k] = *(const PG8_LAS bf16x8*)(lds + PG8_SA(b, h) + aoff + m * 2048 + k * 1024); } while (0)
; #define PG8_LDB(dst, b, h) do { _Pragma("unroll") for (int n = 0; n < 2; ++n) _Pragma("unroll") for (int k = 0; k < 2; ++k) dst[n][k] = *(const PG8_LAS bf16x8*)(lds + PG8_SB(b, h) + boff + n * 2048 + k * 1024); } while (0)
; #define PG8_MMA(ai, bj, At, Bt) do { __builtin_amdgcn_s_setprio(1); _Pragma("unroll") for (int m = 0; m < 4; ++m) _Pragma("unroll") for (int n = 0; n < 2; ++n) _Pragma("unroll") for (int k = 0; k < 2; ++k) \
;         acc[ai][bj][m][n] = mma16<F16>(Bt[n][k], At[m][k], acc[ai][bj][m][n]); __builtin_amdgcn_s_setprio(0); } while (0)
; #define PG8_WAIT_V(n) asm volatile("s_waitcnt vmcnt(" #n ")" ::: "memory")
; #define PG8_WAIT_L(n) asm volatile("s_waitcnt lgkmcnt(" #n ")" ::: "memory")
; #define PG8_BAR __builtin_amdgcn_s_barrier()
; #define PG8_SCHED __builtin_amdgcn_sched_barrier(0)
; template <class Epi, class Sched, bool ALIGN_EPI = false, bool SP2 = false, bool F16 = false>
; __device__ __forceinline__ void gemm_phase(PG8_LAS unsigned char* lds, const Gemm g, const Sched& S, const Epi& E, const int wid_in) {
;     ...
;             PG8_WAIT_V(8); PG8_WAIT_L(0); PG8_BAR; PG8_MMA(1, 0, At, B0); PG8_MMA(1, 1, At, B1); PG8_BAR; PG8_SCHED;
;             PG8_LDB(B0, 1, 0); PG8_LDB(B1, 1, 1); PG8_SCHED; PG8_LDA(At, 1, 0); PG8_STAGE(PG8_SA(0, 1), a2 + hstep, voffA);
;             PG8_WAIT_V(8); PG8_WAIT_L(0); PG8_BAR; PG8_MMA(0, 0, At, B0); PG8_MMA(0, 1, At, B1); PG8_BAR; PG8_SCHED;
	v_mfma_f32_16x16x32_f16 v[68:71], v[0:3], v[176:179], v[68:71]
	v_mfma_f32_16x16x32_f16 v[64:67], v[136:139], v[176:179], v[64:67]
	v_mfma_f32_16x16x32_f16 v[52:55], v[0:3], v[184:187], v[52:55]
	v_mfma_f32_16x16x32_f16 v[48:51], v[136:139], v[184:187], v[48:51]
	v_mfma_f32_16x16x32_f16 v[36:39], v[0:3], v[202:205], v[36:39]
	v_mfma_f32_16x16x32_f16 v[32:35], v[136:139], v[202:205], v[32:35]
	v_mfma_f32_16x16x32_f16 v[0:3], v[0:3], v[210:213], v[20:23]
	v_mfma_f32_16x16x32_f16 v[68:71], v[4:7], v[180:183], v[68:71]
	v_mfma_f32_16x16x32_f16 v[64:67], v[140:143], v[180:183], v[64:67]
	v_mfma_f32_16x16x32_f16 v[52:55], v[4:7], v[198:201], v[52:55]
	v_mfma_f32_16x16x32_f16 v[48:51], v[140:143], v[198:201], v[48:51]
	v_mfma_f32_16x16x32_f16 v[36:39], v[4:7], v[206:209], v[36:39]
	v_mfma_f32_16x16x32_f16 v[32:35], v[140:143], v[206:209], v[32:35]
	v_mfma_f32_16x16x32_f16 v[0:3], v[4:7], v[214:217], v[0:3]
	v_mfma_f32_16x16x32_f16 v[4:7], v[136:139], v[210:213], v[16:19]
	v_mfma_f32_16x16x32_f16 v[4:7], v[140:143], v[214:217], v[4:7]
	v_mfma_f32_16x16x32_f16 v[16:19], v[144:147], v[176:179], v[60:63]
	v_mfma_f32_16x16x32_f16 v[60:63], v[148:151], v[180:183], v[16:19]
	v_mfma_f32_16x16x32_f16 v[16:19], v[152:155], v[176:179], v[56:59]
	v_mfma_f32_16x16x32_f16 v[56:59], v[156:159], v[180:183], v[16:19]
	v_mfma_f32_16x16x32_f16 v[16:19], v[144:147], v[184:187], v[44:47]
	v_mfma_f32_16x16x32_f16 v[44:47], v[148:151], v[198:201], v[16:19]
	v_mfma_f32_16x16x32_f16 v[16:19], v[152:155], v[184:187], v[40:43]
	v_mfma_f32_16x16x32_f16 v[40:43], v[156:159], v[198:201], v[16:19]
	v_mfma_f32_16x16x32_f16 v[16:19], v[144:147], v[202:205], v[28:31]
	v_mfma_f32_16x16x32_f16 v[28:31], v[148:151], v[206:209], v[16:19]
	v_mfma_f32_16x16x32_f16 v[16:19], v[152:155], v[202:205], v[24:27]
	v_mfma_f32_16x16x32_f16 v[12:15], v[144:147], v[210:213], v[12:15]
	v_mfma_f32_16x16x32_f16 v[8:11], v[152:155], v[210:213], v[8:11]
	v_mfma_f32_16x16x32_f16 v[24:27], v[156:159], v[206:209], v[16:19]
	v_mfma_f32_16x16x32_f16 v[12:15], v[148:151], v[214:217], v[12:15]
	v_mfma_f32_16x16x32_f16 v[8:11], v[156:159], v[214:217], v[8:11]
	s_barrier
	s_add_i32 s63, 0, 0x18000
	s_add_i32 s64, 0, 0x1c000
	v_add_u32_e32 v140, s63, v192
	v_add_u32_e32 v156, s64, v192
	ds_read_b128 v[16:19], v140
	ds_read_b128 v[20:23], v140 offset:1024
	ds_read_b128 v[136:139], v140 offset:2048
	ds_read_b128 v[140:143], v140 offset:3072
	ds_read_b128 v[144:147], v156
	ds_read_b128 v[148:151], v156 offset:1024
	ds_read_b128 v[152:155], v156 offset:2048
	ds_read_b128 v[156:159], v156 offset:3072
	s_add_u32 s44, s44, 0x40000
	s_addc_u32 s45, s45, 0
	s_mov_b32 m0, s90
	v_lshl_add_u64 v[224:225], s[44:45], 0, v[160:161]
	ds_read_b128 v[176:179], v195 offset:32768
	ds_read_b128 v[180:183], v195 offset:33792
	ds_read_b128 v[184:187], v195 offset:34816
	ds_read_b128 v[198:201], v195 offset:35840
	ds_read_b128 v[202:205], v195 offset:36864
	ds_read_b128 v[206:209], v195 offset:37888
	ds_read_b128 v[210:213], v195 offset:38912
	ds_read_b128 v[214:217], v195 offset:39936
	global_load_lds_dwordx4 v[224:225], off
	v_lshl_add_u64 v[224:225], s[44:45], 0, v[164:165]
	s_mov_b32 m0, s31
	s_nop 0
	global_load_lds_dwordx4 v[224:225], off
	s_waitcnt vmcnt(8)
	s_waitcnt lgkmcnt(0)
	s_barrier
	v_mfma_f32_16x16x32_f16 v[132:135], v[16:19], v[176:179], v[132:135]
	v_mfma_f32_16x16x32_f16 v[128:131], v[136:139], v[176:179], v[128:131]
	v_mfma_f32_16x16x32_f16 v[116:119], v[16:19], v[184:187], v[116:119]
	v_mfma_f32_16x16x32_f16 v[112:115], v[136:139], v[184:187], v[112:115]
	v_mfma_f32_16x16x32_f16 v[100:103], v[16:19], v[202:205], v[100:103]
	v_mfma_f32_16x16x32_f16 v[96:99], v[136:139], v[202:205], v[96:99]
	v_mfma_f32_16x16x32_f16 v[84:87], v[16:19], v[210:213], v[84:87]
	v_mfma_f32_16x16x32_f16 v[80:83], v[136:139], v[210:213], v[80:83]
	v_mfma_f32_16x16x32_f16 v[132:135], v[20:23], v[180:183], v[132:135]
	v_mfma_f32_16x16x32_f16 v[128:131], v[140:143], v[180:183], v[128:131]
	v_mfma_f32_16x16x32_f16 v[116:119], v[20:23], v[198:201], v[116:119]
	v_mfma_f32_16x16x32_f16 v[112:115], v[140:143], v[198:201], v[112:115]
	v_mfma_f32_16x16x32_f16 v[100:103], v[20:23], v[206:209], v[100:103]
	v_mfma_f32_16x16x32_f16 v[96:99], v[140:143], v[206:209], v[96:99]
	v_mfma_f32_16x16x32_f16 v[84:87], v[20:23], v[214:217], v[84:87]
	v_mfma_f32_16x16x32_f16 v[80:83], v[140:143], v[214:217], v[80:83]
	v_mfma_f32_16x16x32_f16 v[124:127], v[144:147], v[176:179], v[124:127]
	v_mfma_f32_16x16x32_f16 v[120:123], v[152:155], v[176:179], v[120:123]
	v_mfma_f32_16x16x32_f16 v[108:111], v[144:147], v[184:187], v[108:111]
	v_mfma_f32_16x16x32_f16 v[104:107], v[152:155], v[184:187], v[104:107]
	v_mfma_f32_16x16x32_f16 v[92:95], v[144:147], v[202:205], v[92:95]
	v_mfma_f32_16x16x32_f16 v[88:91], v[152:155], v[202:205], v[88:91]
	v_mfma_f32_16x16x32_f16 v[76:79], v[144:147], v[210:213], v[76:79]
	v_mfma_f32_16x16x32_f16 v[72:75], v[152:155], v[210:213], v[72:75]
	v_mfma_f32_16x16x32_f16 v[124:127], v[148:151], v[180:183], v[124:127]
	v_mfma_f32_16x16x32_f16 v[120:123], v[156:159], v[180:183], v[120:123]
	v_mfma_f32_16x16x32_f16 v[108:111], v[148:151], v[198:201], v[108:111]
	v_mfma_f32_16x16x32_f16 v[104:107], v[156:159], v[198:201], v[104:107]
	v_mfma_f32_16x16x32_f16 v[92:95], v[148:151], v[206:209], v[92:95]
	v_mfma_f32_16x16x32_f16 v[88:91], v[156:159], v[206:209], v[88:91]
	v_mfma_f32_16x16x32_f16 v[76:79], v[148:151], v[214:217], v[76:79]
	v_mfma_f32_16x16x32_f16 v[72:75], v[156:159], v[214:217], v[72:75]
	s_barrier
; #define PG8_STAGE(bufoff, gbase, voff) do { _Pragma("unroll") for (int _i = 0; _i < 2; ++_i) \
;         __builtin_amdgcn_global_load_lds((const unsigned*)((const char*)(gbase) + (voff)[_i]), (PG8_LAS unsigned*)(lds + (bufoff) + ldsw + _i * 8192), 16, 0, 0); } while (0)
; #define PG8_LDA(dst, b, h) do { _Pragma("unroll") for (int m = 0; m < 4; ++m) _Pragma("unroll") for (int k = 0; k < 2; ++k) dst[m][k] = *(const PG8_LAS bf16x8*)(lds + PG8_SA(b, h) + aoff + m * 2048 + k * 1024); } while (0)
; #define PG8_BAR __builtin_amdgcn_s_barrier()
; template <class Epi, class Sched, bool ALIGN_EPI = false, bool SP2 = false, bool F16 = false>
; __device__ __forceinline__ void gemm_phase(PG8_LAS unsigned char* lds, const Gemm g, const Sched& S, const Epi& E, const int wid_in) {
;     ...
;             PG8_LDA(At, 1, 1); PG8_STAGE(PG8_SB(1, 0), b3, voffB); PG8_STAGE(PG8_SB(1, 1), b3 + hstep, voffB); PG8_STAGE(PG8_SA(1, 0), a3, voffA);
;             PG8_WAIT_V(8); PG8_WAIT_L(0); PG8_BAR; PG8_MMA(1, 0, At, B0); PG8_MMA(1, 1, At, B1); PG8_BAR; PG8_SCHED;
;             } else {
;             PG8_LDB(B0, 0, 0); PG8_SCHED; PG8_LDA(At, 0, 0); PG8_STAGE(PG8_SA(1, 1), a1 + hstep, voffA);
;             PG8_WAIT_L(8); PG8_BAR; PG8_WAIT_L(0); PG8_MMA(0, 0, At, B0); PG8_BAR; PG8_SCHED;
;             PG8_LDB(B1, 0, 1); PG8_STAGE(PG8_SB(0, 0), b2, voffB);
;             PG8_BAR; PG8_WAIT_L(0); PG8_MMA(0, 1, At, B1); PG8_BAR;
;             PG8_LDA(At, 0, 1); PG8_STAGE(PG8_SA(0, 0), a2, voffA);
;             PG8_BAR; PG8_WAIT_L(0); PG8_MMA(1, 0, At, B0); PG8_BAR; PG8_SCHED;
;             PG8_STAGE(PG8_SB(0, 1), b2 + hstep, voffB);
;             PG8_WAIT_V(6); PG8_BAR; PG8_MMA(1, 1, At, B1); PG8_BAR;
;             PG8_LDB(B0, 1, 0); PG8_SCHED; PG8_LDA(At, 1, 0); PG8_STAGE(PG8_SA(0, 1), a2 + hstep, voffA);
;             PG8_WAIT_L(8); PG8_BAR; PG8_WAIT_L(0); PG8_MMA(0, 0, At, B0); PG8_BAR; PG8_SCHED;
;             PG8_LDB(B1, 1, 1); PG8_STAGE(PG8_SB(1, 0), b3, voffB);
;             PG8_BAR; PG8_WAIT_L(0); PG8_MMA(0, 1, At, B1); PG8_BAR;
;             PG8_LDA(At, 1, 1); PG8_STAGE(PG8_SA(1, 0), a3, voffA);
;             PG8_BAR; PG8_WAIT_L(0); PG8_MMA(1, 0, At, B0); PG8_BAR; PG8_SCHED;
;             PG8_STAGE(PG8_SB(1, 1), b3 + hstep, voffB);
;             PG8_WAIT_V(6); PG8_BAR; PG8_MMA(1, 1, At, B1); PG8_BAR;
;             }
;         }
;         if constexpr (ALIGN_EPI) { if (wr == 0) PG8_BAR; }
	s_add_i32 s44, s63, s68
	v_lshl_add_u64 v[188:189], v[188:189], 0, s[20:21]
	s_mov_b32 m0, s44
	ds_read_b128 v[176:179], v195 offset:49152
	ds_read_b128 v[180:183], v195 offset:50176
	ds_read_b128 v[184:187], v195 offset:51200
	ds_read_b128 v[198:201], v195 offset:52224
	ds_read_b128 v[202:205], v195 offset:53248
	ds_read_b128 v[206:209], v195 offset:54272
	ds_read_b128 v[210:213], v195 offset:55296
	ds_read_b128 v[214:217], v195 offset:56320
	global_load_lds_dwordx4 v[188:189], off
	s_add_i32 m0, s44, 0x2000
	s_add_u32 s42, s42, 0x40080
	v_lshl_add_u64 v[188:189], v[218:219], 0, s[20:21]
	s_addc_u32 s43, s43, 0
	s_add_i32 s44, s64, s68
	global_load_lds_dwordx4 v[188:189], off
	v_lshl_add_u64 v[188:189], s[42:43], 0, v[162:163]
	s_mov_b32 m0, s44
	s_nop 0
	global_load_lds_dwordx4 v[188:189], off
	v_lshl_add_u64 v[188:189], s[42:43], 0, v[166:167]
	s_add_i32 m0, s44, 0x2000
	s_nop 0
	global_load_lds_dwordx4 v[188:189], off
	v_lshl_add_u64 v[188:189], v[220:221], 0, s[20:21]
	s_mov_b32 m0, s75
	s_nop 0
	global_load_lds_dwordx4 v[188:189], off
	v_lshl_add_u64 v[188:189], v[222:223], 0, s[20:21]
	s_mov_b32 m0, s67
	s_nop 0
	global_load_lds_dwordx4 v[188:189], off
	s_waitcnt vmcnt(8)
	s_waitcnt lgkmcnt(0)
	s_barrier
	v_mfma_f32_16x16x32_f16 v[68:71], v[16:19], v[176:179], v[68:71]
	v_mfma_f32_16x16x32_f16 v[52:55], v[16:19], v[184:187], v[52:55]
	v_mfma_f32_16x16x32_f16 v[36:39], v[16:19], v[202:205], v[36:39]
	v_mfma_f32_16x16x32_f16 v[0:3], v[16:19], v[210:213], v[0:3]
	v_mfma_f32_16x16x32_f16 v[68:71], v[20:23], v[180:183], v[68:71]
	v_mfma_f32_16x16x32_f16 v[64:67], v[136:139], v[176:179], v[64:67]
	v_mfma_f32_16x16x32_f16 v[52:55], v[20:23], v[198:201], v[52:55]
	v_mfma_f32_16x16x32_f16 v[48:51], v[136:139], v[184:187], v[48:51]
	v_mfma_f32_16x16x32_f16 v[36:39], v[20:23], v[206:209], v[36:39]
	v_mfma_f32_16x16x32_f16 v[32:35], v[136:139], v[202:205], v[32:35]
	v_mfma_f32_16x16x32_f16 v[20:23], v[20:23], v[214:217], v[0:3]
	v_mfma_f32_16x16x32_f16 v[0:3], v[136:139], v[210:213], v[4:7]
	v_mfma_f32_16x16x32_f16 v[64:67], v[140:143], v[180:183], v[64:67]
	v_mfma_f32_16x16x32_f16 v[48:51], v[140:143], v[198:201], v[48:51]
	v_mfma_f32_16x16x32_f16 v[32:35], v[140:143], v[206:209], v[32:35]
	v_mfma_f32_16x16x32_f16 v[16:19], v[140:143], v[214:217], v[0:3]
	v_mfma_f32_16x16x32_f16 v[0:3], v[144:147], v[176:179], v[60:63]
	v_mfma_f32_16x16x32_f16 v[60:63], v[148:151], v[180:183], v[0:3]
	v_mfma_f32_16x16x32_f16 v[0:3], v[152:155], v[176:179], v[56:59]
	v_mfma_f32_16x16x32_f16 v[56:59], v[156:159], v[180:183], v[0:3]
	v_mfma_f32_16x16x32_f16 v[0:3], v[144:147], v[184:187], v[44:47]
	v_mfma_f32_16x16x32_f16 v[44:47], v[148:151], v[198:201], v[0:3]
	v_mfma_f32_16x16x32_f16 v[0:3], v[152:155], v[184:187], v[40:43]
	v_mfma_f32_16x16x32_f16 v[40:43], v[156:159], v[198:201], v[0:3]
	v_mfma_f32_16x16x32_f16 v[0:3], v[144:147], v[202:205], v[28:31]
	v_mfma_f32_16x16x32_f16 v[28:31], v[148:151], v[206:209], v[0:3]
	v_mfma_f32_16x16x32_f16 v[0:3], v[152:155], v[202:205], v[24:27]
	v_mfma_f32_16x16x32_f16 v[24:27], v[156:159], v[206:209], v[0:3]
	v_mfma_f32_16x16x32_f16 v[0:3], v[144:147], v[210:213], v[12:15]
	v_mfma_f32_16x16x32_f16 v[12:15], v[148:151], v[214:217], v[0:3]
	v_mfma_f32_16x16x32_f16 v[0:3], v[152:155], v[210:213], v[8:11]
	v_mfma_f32_16x16x32_f16 v[8:11], v[156:159], v[214:217], v[0:3]
	s_barrier
	s_add_i32 s62, s62, 2
	s_add_u32 s36, s36, 0x100
	s_addc_u32 s37, s37, 0
	s_add_u32 s60, s60, 0x100
	s_addc_u32 s61, s61, 0
	s_cmp_gt_u32 s62, 13
	s_cbranch_scc0 .LBB0_2566
	s_and_b64 vcc, exec, s[16:17]
	s_cbranch_vccz .LBB0_2569
	s_barrier

; #define PG8_STAGE(bufoff, gbase, voff) do { _Pragma("unroll") for (int _i = 0; _i < 2; ++_i) \
;         __builtin_amdgcn_global_load_lds((const unsigned*)((const char*)(gbase) + (voff)[_i]), (PG8_LAS unsigned*)(lds + (bufoff) + ldsw + _i * 8192), 16, 0, 0); } while (0)
; #define PG8_LDA(dst, b, h) do { _Pragma("unroll") for (int m = 0; m < 4; ++m) _Pragma("unroll") for (int k = 0; k < 2; ++k) dst[m][k] = *(const PG8_LAS bf16x8*)(lds + PG8_SA(b, h) + aoff + m * 2048 + k * 1024); } while (0)
; #define PG8_LDB(dst, b, h) do { _Pragma("unroll") for (int n = 0; n < 2; ++n) _Pragma("unroll") for (int k = 0; k < 2; ++k) dst[n][k] = *(const PG8_LAS bf16x8*)(lds + PG8_SB(b, h) + boff + n * 2048 + k * 1024); } while (0)
; #define PG8_WAIT_V(n) asm volatile("s_waitcnt vmcnt(" #n ")" ::: "memory")
; #define PG8_WAIT_L(n) asm volatile("s_waitcnt lgkmcnt(" #n ")" ::: "memory")
; #define PG8_BAR __builtin_amdgcn_s_barrier()
; #define PG8_SCHED __builtin_amdgcn_sched_barrier(0)
; template <class Epi, class Sched, bool ALIGN_EPI = false, bool SP2 = false, bool F16 = false>
; __device__ __forceinline__ void gemm_phase(PG8_LAS unsigned char* lds, const Gemm g, const Sched& S, const Epi& E, const int wid_in) {
;     ...
;         const bool has_next = S.next(ui + 1, nxt);
;         const char* nA = has_next ? (const char*)g.A + (size_t)nxt.pm * tstep : cA; const char* nB = has_next ? (const char*)g.Bt + (size_t)nxt.pn * tstep : cB;
;         for (int t = 0; t < nt; t += 2) {
;             const bool last = (t == nt - 2);
;             const char* a1 = cA + (size_t)(t + 1) * kstep;
;             const char* a2 = last ? nA : cA + (size_t)(t + 2) * kstep; const char* b2 = last ? nB : cB + (size_t)(t + 2) * kstep;
;             const char* a3 = a2 + kstep; const char* b3 = b2 + kstep;
;             if (last && has_next) S.a_ready(nxt);
;             if constexpr (SP2) {
;             PG8_LDB(B0, 0, 0); PG8_LDB(B1, 0, 1); PG8_SCHED; PG8_LDA(At, 0, 0); PG8_STAGE(PG8_SA(1, 1), a1 + hstep, voffA);
;             PG8_WAIT_V(8); PG8_WAIT_L(0); PG8_BAR; PG8_MMA(0, 0, At, B0); PG8_MMA(0, 1, At, B1); PG8_BAR; PG8_SCHED;
;             PG8_LDA(At, 0, 1); PG8_STAGE(PG8_SB(0, 0), b2, voffB); PG8_STAGE(PG8_SB(0, 1), b2 + hstep, voffB); PG8_STAGE(PG8_SA(0, 0), a2, voffA);
;             PG8_WAIT_V(8); PG8_WAIT_L(0); PG8_BAR; PG8_MMA(1, 0, At, B0); PG8_MMA(1, 1, At, B1); PG8_BAR; PG8_SCHED;
.LBB0_2601:
	s_mov_b64 s[42:43], s[10:11]
	s_add_i32 s10, s30, s40
	s_mov_b64 s[36:37], s[12:13]
	s_mov_b32 s12, s56
	s_mov_b32 s13, s55
	s_and_b32 s55, s10, 3
	s_ashr_i32 s56, s10, 2
	s_and_b64 s[10:11], s[26:27], exec
	s_cselect_b32 s12, s56, s12
	ds_read_b128 v[0:3], v134
	ds_read_b128 v[4:7], v134 offset:1024
	ds_read_b128 v[8:11], v134 offset:2048
	ds_read_b128 v[12:15], v134 offset:3072
	ds_read_b128 v[16:19], v135
	ds_read_b128 v[20:23], v135 offset:1024
	ds_read_b128 v[24:27], v135 offset:2048
	ds_read_b128 v[28:31], v135 offset:3072
	s_cselect_b32 s10, s55, s13
	s_ashr_i32 s13, s12, 31
	s_lshl_b64 s[12:13], s[12:13], 17
	s_add_u32 s12, s41, s12
	s_addc_u32 s13, s44, s13
	s_and_b64 s[30:31], s[26:27], exec
	s_cselect_b32 s35, s13, s37
	s_cselect_b32 s34, s12, s36
	s_ashr_i32 s11, s10, 31
	s_lshl_b64 s[10:11], s[10:11], 17
	s_add_u32 s10, s45, s10
	s_addc_u32 s11, s46, s11
	s_and_b64 s[30:31], s[26:27], exec
	s_cselect_b32 s31, s11, s43
	s_cselect_b32 s30, s10, s42
	s_add_u32 s58, s36, 0x10080
	s_addc_u32 s59, s37, 0
	s_mov_b32 m0, s91
	v_lshl_add_u64 v[64:65], s[58:59], 0, v[130:131]
	ds_read_b128 v[32:35], v136
	ds_read_b128 v[36:39], v136 offset:1024
	ds_read_b128 v[40:43], v136 offset:2048
	ds_read_b128 v[44:47], v136 offset:3072
	ds_read_b128 v[48:51], v136 offset:4096
	ds_read_b128 v[52:55], v136 offset:5120
	ds_read_b128 v[56:59], v136 offset:6144
	ds_read_b128 v[60:63], v136 offset:7168
	global_load_lds_dwordx4 v[64:65], off
	v_lshl_add_u64 v[64:65], s[58:59], 0, v[128:129]
	s_mov_b32 m0, s14
	s_nop 0
	global_load_lds_dwordx4 v[64:65], off
	s_waitcnt vmcnt(8)
	s_waitcnt lgkmcnt(0)
	s_barrier
	v_mfma_f32_16x16x32_bf16 v[64:67], v[0:3], v[32:35], 0
	v_mfma_f32_16x16x32_bf16 v[68:71], v[8:11], v[32:35], 0
	v_mfma_f32_16x16x32_bf16 v[72:75], v[0:3], v[40:43], 0
	v_mfma_f32_16x16x32_bf16 v[76:79], v[8:11], v[40:43], 0
	v_mfma_f32_16x16x32_bf16 v[80:83], v[0:3], v[48:51], 0
	v_mfma_f32_16x16x32_bf16 v[84:87], v[8:11], v[48:51], 0
	v_mfma_f32_16x16x32_bf16 v[88:91], v[0:3], v[56:59], 0
	v_mfma_f32_16x16x32_bf16 v[92:95], v[8:11], v[56:59], 0
	v_mfma_f32_16x16x32_bf16 v[64:67], v[4:7], v[36:39], v[64:67]
	v_mfma_f32_16x16x32_bf16 v[68:71], v[12:15], v[36:39], v[68:71]
	v_mfma_f32_16x16x32_bf16 v[72:75], v[4:7], v[44:47], v[72:75]
	v_mfma_f32_16x16x32_bf16 v[76:79], v[12:15], v[44:47], v[76:79]
	v_mfma_f32_16x16x32_bf16 v[80:83], v[4:7], v[52:55], v[80:83]
	v_mfma_f32_16x16x32_bf16 v[84:87], v[12:15], v[52:55], v[84:87]
	v_mfma_f32_16x16x32_bf16 v[88:91], v[4:7], v[60:63], v[88:91]
	v_mfma_f32_16x16x32_bf16 v[92:95], v[12:15], v[60:63], v[92:95]
	v_mfma_f32_16x16x32_bf16 v[96:99], v[16:19], v[32:35], 0
	v_mfma_f32_16x16x32_bf16 v[32:35], v[24:27], v[32:35], 0
	v_mfma_f32_16x16x32_bf16 v[96:99], v[20:23], v[36:39], v[96:99]
	v_mfma_f32_16x16x32_bf16 v[32:35], v[28:31], v[36:39], v[32:35]
	v_mfma_f32_16x16x32_bf16 v[36:39], v[16:19], v[40:43], 0
	v_mfma_f32_16x16x32_bf16 v[40:43], v[24:27], v[40:43], 0
	v_mfma_f32_16x16x32_bf16 v[36:39], v[20:23], v[44:47], v[36:39]
	v_mfma_f32_16x16x32_bf16 v[40:43], v[28:31], v[44:47], v[40:43]
	v_mfma_f32_16x16x32_bf16 v[44:47], v[16:19], v[48:51], 0
	v_mfma_f32_16x16x32_bf16 v[48:51], v[24:27], v[48:51], 0
	v_mfma_f32_16x16x32_bf16 v[44:47], v[20:23], v[52:55], v[44:47]
	v_mfma_f32_16x16x32_bf16 v[48:51], v[28:31], v[52:55], v[48:51]
	v_mfma_f32_16x16x32_bf16 v[52:55], v[16:19], v[56:59], 0
	v_mfma_f32_16x16x32_bf16 v[56:59], v[24:27], v[56:59], 0
	v_mfma_f32_16x16x32_bf16 v[52:55], v[20:23], v[60:63], v[52:55]
	v_mfma_f32_16x16x32_bf16 v[56:59], v[28:31], v[60:63], v[56:59]
	s_barrier
	v_lshl_add_u64 v[204:205], s[42:43], 0, v[130:131]
	s_mov_b32 m0, s15
	v_lshl_add_u64 v[140:141], v[204:205], 0, s[22:23]
	v_lshl_add_u64 v[206:207], s[42:43], 0, v[128:129]
	s_add_u32 s58, s42, 0x10100
	ds_read_b128 v[60:63], v136 offset:16384
	ds_read_b128 v[100:103], v136 offset:17408
	ds_read_b128 v[104:107], v136 offset:18432
	ds_read_b128 v[108:111], v136 offset:19456
	ds_read_b128 v[112:115], v136 offset:20480
	ds_read_b128 v[116:119], v136 offset:21504
	ds_read_b128 v[120:123], v136 offset:22528
	ds_read_b128 v[124:127], v136 offset:23552
	global_load_lds_dwordx4 v[140:141], off
	v_lshl_add_u64 v[140:141], v[206:207], 0, s[22:23]
	s_mov_b32 m0, s48
	s_addc_u32 s59, s43, 0
	global_load_lds_dwordx4 v[140:141], off
	v_lshl_add_u64 v[140:141], s[58:59], 0, v[130:131]
	s_mov_b32 m0, s49
	v_lshl_add_u64 v[208:209], s[36:37], 0, v[130:131]
	global_load_lds_dwordx4 v[140:141], off
	v_lshl_add_u64 v[140:141], s[58:59], 0, v[128:129]
	s_mov_b32 m0, s50
	v_lshl_add_u64 v[210:211], s[36:37], 0, v[128:129]
	global_load_lds_dwordx4 v[140:141], off
	v_lshl_add_u64 v[140:141], v[208:209], 0, s[22:23]
	s_mov_b32 m0, s74
	s_nop 0
	global_load_lds_dwordx4 v[140:141], off
	v_lshl_add_u64 v[140:141], v[210:211], 0, s[22:23]
	s_mov_b32 m0, s66
	s_nop 0
	global_load_lds_dwordx4 v[140:141], off
	s_waitcnt vmcnt(8)
	s_waitcnt lgkmcnt(0)
	s_barrier
; #define PG8_STAGE(bufoff, gbase, voff) do { _Pragma("unroll") for (int _i = 0; _i < 2; ++_i) \
;         __builtin_amdgcn_global_load_lds((const unsigned*)((const char*)(gbase) + (voff)[_i]), (PG8_LAS unsigned*)(lds + (bufoff) + ldsw + _i * 8192), 16, 0, 0); } while (0)
; #define PG8_LDA(dst, b, h) do { _Pragma("unroll") for (int m = 0; m < 4; ++m) _Pragma("unroll") for (int k = 0; k < 2; ++k) dst[m][k] = *(const PG8_LAS bf16x8*)(lds + PG8_SA(b, h) + aoff + m * 2048 + k * 1024); } while (0)
; #define PG8_LDB(dst, b, h) do { _Pragma("unroll") for (int n = 0; n < 2; ++n) _Pragma("unroll") for (int k = 0; k < 2; ++k) dst[n][k] = *(const PG8_LAS bf16x8*)(lds + PG8_SB(b, h) + boff + n * 2048 + k * 1024); } while (0)
; #define PG8_MMA(ai, bj, At, Bt) do { __builtin_amdgcn_s_setprio(1); _Pragma("unroll") for (int m = 0; m < 4; ++m) _Pragma("unroll") for (int n = 0; n < 2; ++n) _Pragma("unroll") for (int k = 0; k < 2; ++k) \
;         acc[ai][bj][m][n] = mma16<F16>(Bt[n][k], At[m][k], acc[ai][bj][m][n]); __builtin_amdgcn_s_setprio(0); } while (0)
; #define PG8_WAIT_V(n) asm volatile("s_waitcnt vmcnt(" #n ")" ::: "memory")
; #define PG8_WAIT_L(n) asm volatile("s_waitcnt lgkmcnt(" #n ")" ::: "memory")
; #define PG8_BAR __builtin_amdgcn_s_barrier()
; #define PG8_SCHED __builtin_amdgcn_sched_barrier(0)
; template <class Epi, class Sched, bool ALIGN_EPI = false, bool SP2 = false, bool F16 = false>
; __device__ __forceinline__ void gemm_phase(PG8_LAS unsigned char* lds, const Gemm g, const Sched& S, const Epi& E, const int wid_in) {
;     ...
;             PG8_LDA(At, 0, 1); PG8_STAGE(PG8_SB(0, 0), b2, voffB); PG8_STAGE(PG8_SB(0, 1), b2 + hstep, voffB); PG8_STAGE(PG8_SA(0, 0), a2, voffA);
;             PG8_WAIT_V(8); PG8_WAIT_L(0); PG8_BAR; PG8_MMA(1, 0, At, B0); PG8_MMA(1, 1, At, B1); PG8_BAR; PG8_SCHED;
;             PG8_LDB(B0, 1, 0); PG8_LDB(B1, 1, 1); PG8_SCHED; PG8_LDA(At, 1, 0); PG8_STAGE(PG8_SA(0, 1), a2 + hstep, voffA);
;             PG8_WAIT_V(8); PG8_WAIT_L(0); PG8_BAR; PG8_MMA(0, 0, At, B0); PG8_MMA(0, 1, At, B1); PG8_BAR; PG8_SCHED;
	v_mfma_f32_16x16x32_bf16 v[140:143], v[0:3], v[60:63], 0
	v_mfma_f32_16x16x32_bf16 v[148:151], v[0:3], v[104:107], 0
	v_mfma_f32_16x16x32_bf16 v[156:159], v[0:3], v[112:115], 0
	v_mfma_f32_16x16x32_bf16 v[0:3], v[0:3], v[120:123], 0
	v_mfma_f32_16x16x32_bf16 v[140:143], v[4:7], v[100:103], v[140:143]
	v_mfma_f32_16x16x32_bf16 v[148:151], v[4:7], v[108:111], v[148:151]
	v_mfma_f32_16x16x32_bf16 v[156:159], v[4:7], v[116:119], v[156:159]
	v_mfma_f32_16x16x32_bf16 v[0:3], v[4:7], v[124:127], v[0:3]
	v_mfma_f32_16x16x32_bf16 v[4:7], v[8:11], v[120:123], 0
	v_mfma_f32_16x16x32_bf16 v[144:147], v[8:11], v[60:63], 0
	v_mfma_f32_16x16x32_bf16 v[152:155], v[8:11], v[104:107], 0
	v_mfma_f32_16x16x32_bf16 v[160:163], v[8:11], v[112:115], 0
	v_mfma_f32_16x16x32_bf16 v[4:7], v[12:15], v[124:127], v[4:7]
	v_mfma_f32_16x16x32_bf16 v[144:147], v[12:15], v[100:103], v[144:147]
	v_mfma_f32_16x16x32_bf16 v[152:155], v[12:15], v[108:111], v[152:155]
	v_mfma_f32_16x16x32_bf16 v[160:163], v[12:15], v[116:119], v[160:163]
	v_mfma_f32_16x16x32_bf16 v[8:11], v[16:19], v[60:63], 0
	v_mfma_f32_16x16x32_bf16 v[12:15], v[24:27], v[60:63], 0
	v_mfma_f32_16x16x32_bf16 v[8:11], v[20:23], v[100:103], v[8:11]
	v_mfma_f32_16x16x32_bf16 v[12:15], v[28:31], v[100:103], v[12:15]
	v_mfma_f32_16x16x32_bf16 v[60:63], v[16:19], v[104:107], 0
	v_mfma_f32_16x16x32_bf16 v[100:103], v[24:27], v[104:107], 0
	v_mfma_f32_16x16x32_bf16 v[104:107], v[16:19], v[112:115], 0
	v_mfma_f32_16x16x32_bf16 v[16:19], v[16:19], v[120:123], 0
	v_mfma_f32_16x16x32_bf16 v[60:63], v[20:23], v[108:111], v[60:63]
	v_mfma_f32_16x16x32_bf16 v[100:103], v[28:31], v[108:111], v[100:103]
	v_mfma_f32_16x16x32_bf16 v[104:107], v[20:23], v[116:119], v[104:107]
	v_mfma_f32_16x16x32_bf16 v[108:111], v[24:27], v[112:115], 0
	v_mfma_f32_16x16x32_bf16 v[16:19], v[20:23], v[124:127], v[16:19]
	v_mfma_f32_16x16x32_bf16 v[20:23], v[24:27], v[120:123], 0
	v_mfma_f32_16x16x32_bf16 v[108:111], v[28:31], v[116:119], v[108:111]
	v_mfma_f32_16x16x32_bf16 v[20:23], v[28:31], v[124:127], v[20:23]
	s_barrier
	ds_read_b128 v[24:27], v137
	ds_read_b128 v[28:31], v137 offset:1024
	ds_read_b128 v[112:115], v137 offset:2048
	ds_read_b128 v[116:119], v137 offset:3072
	ds_read_b128 v[120:123], v138
	ds_read_b128 v[124:127], v138 offset:1024
	ds_read_b128 v[164:167], v138 offset:2048
	ds_read_b128 v[168:171], v138 offset:3072
	s_add_u32 s58, s36, 0x10100
	s_addc_u32 s59, s37, 0
	s_mov_b32 m0, s90
	v_lshl_add_u64 v[212:213], s[58:59], 0, v[130:131]
	ds_read_b128 v[172:175], v136 offset:32768
	ds_read_b128 v[176:179], v136 offset:33792
	ds_read_b128 v[180:183], v136 offset:34816
	ds_read_b128 v[184:187], v136 offset:35840
	ds_read_b128 v[188:191], v136 offset:36864
	ds_read_b128 v[192:195], v136 offset:37888
	ds_read_b128 v[196:199], v136 offset:38912
	ds_read_b128 v[200:203], v136 offset:39936
	global_load_lds_dwordx4 v[212:213], off
	v_lshl_add_u64 v[212:213], s[58:59], 0, v[128:129]
	s_mov_b32 m0, s47
	s_nop 0
	global_load_lds_dwordx4 v[212:213], off
	s_waitcnt vmcnt(8)
	s_waitcnt lgkmcnt(0)
	s_barrier
	v_mfma_f32_16x16x32_bf16 v[64:67], v[24:27], v[172:175], v[64:67]
	v_mfma_f32_16x16x32_bf16 v[68:71], v[112:115], v[172:175], v[68:71]
	v_mfma_f32_16x16x32_bf16 v[72:75], v[24:27], v[180:183], v[72:75]
	v_mfma_f32_16x16x32_bf16 v[76:79], v[112:115], v[180:183], v[76:79]
	v_mfma_f32_16x16x32_bf16 v[80:83], v[24:27], v[188:191], v[80:83]
	v_mfma_f32_16x16x32_bf16 v[84:87], v[112:115], v[188:191], v[84:87]
	v_mfma_f32_16x16x32_bf16 v[88:91], v[24:27], v[196:199], v[88:91]
	v_mfma_f32_16x16x32_bf16 v[92:95], v[112:115], v[196:199], v[92:95]
	v_mfma_f32_16x16x32_bf16 v[64:67], v[28:31], v[176:179], v[64:67]
	v_mfma_f32_16x16x32_bf16 v[68:71], v[116:119], v[176:179], v[68:71]
	v_mfma_f32_16x16x32_bf16 v[72:75], v[28:31], v[184:187], v[72:75]
	v_mfma_f32_16x16x32_bf16 v[76:79], v[116:119], v[184:187], v[76:79]
	v_mfma_f32_16x16x32_bf16 v[80:83], v[28:31], v[192:195], v[80:83]
	v_mfma_f32_16x16x32_bf16 v[84:87], v[116:119], v[192:195], v[84:87]
	v_mfma_f32_16x16x32_bf16 v[88:91], v[28:31], v[200:203], v[88:91]
	v_mfma_f32_16x16x32_bf16 v[92:95], v[116:119], v[200:203], v[92:95]
	v_mfma_f32_16x16x32_bf16 v[96:99], v[120:123], v[172:175], v[96:99]
	v_mfma_f32_16x16x32_bf16 v[32:35], v[164:167], v[172:175], v[32:35]
	v_mfma_f32_16x16x32_bf16 v[36:39], v[120:123], v[180:183], v[36:39]
	v_mfma_f32_16x16x32_bf16 v[40:43], v[164:167], v[180:183], v[40:43]
	v_mfma_f32_16x16x32_bf16 v[44:47], v[120:123], v[188:191], v[44:47]
	v_mfma_f32_16x16x32_bf16 v[48:51], v[164:167], v[188:191], v[48:51]
	v_mfma_f32_16x16x32_bf16 v[52:55], v[120:123], v[196:199], v[52:55]
	v_mfma_f32_16x16x32_bf16 v[56:59], v[164:167], v[196:199], v[56:59]
	v_mfma_f32_16x16x32_bf16 v[96:99], v[124:127], v[176:179], v[96:99]
	v_mfma_f32_16x16x32_bf16 v[32:35], v[168:171], v[176:179], v[32:35]
	v_mfma_f32_16x16x32_bf16 v[36:39], v[124:127], v[184:187], v[36:39]
	v_mfma_f32_16x16x32_bf16 v[40:43], v[168:171], v[184:187], v[40:43]
	v_mfma_f32_16x16x32_bf16 v[44:47], v[124:127], v[192:195], v[44:47]
	v_mfma_f32_16x16x32_bf16 v[48:51], v[168:171], v[192:195], v[48:51]
	v_mfma_f32_16x16x32_bf16 v[52:55], v[124:127], v[200:203], v[52:55]
	v_mfma_f32_16x16x32_bf16 v[56:59], v[168:171], v[200:203], v[56:59]
	s_barrier
; #define PG8_STAGE(bufoff, gbase, voff) do { _Pragma("unroll") for (int _i = 0; _i < 2; ++_i) \
;         __builtin_amdgcn_global_load_lds((const unsigned*)((const char*)(gbase) + (voff)[_i]), (PG8_LAS unsigned*)(lds + (bufoff) + ldsw + _i * 8192), 16, 0, 0); } while (0)
; #define PG8_LDA(dst, b, h) do { _Pragma("unroll") for (int m = 0; m < 4; ++m) _Pragma("unroll") for (int k = 0; k < 2; ++k) dst[m][k] = *(const PG8_LAS bf16x8*)(lds + PG8_SA(b, h) + aoff + m * 2048 + k * 1024); } while (0)
; #define PG8_LDB(dst, b, h) do { _Pragma("unroll") for (int n = 0; n < 2; ++n) _Pragma("unroll") for (int k = 0; k < 2; ++k) dst[n][k] = *(const PG8_LAS bf16x8*)(lds + PG8_SB(b, h) + boff + n * 2048 + k * 1024); } while (0)
; #define PG8_MMA(ai, bj, At, Bt) do { __builtin_amdgcn_s_setprio(1); _Pragma("unroll") for (int m = 0; m < 4; ++m) _Pragma("unroll") for (int n = 0; n < 2; ++n) _Pragma("unroll") for (int k = 0; k < 2; ++k) \
;         acc[ai][bj][m][n] = mma16<F16>(Bt[n][k], At[m][k], acc[ai][bj][m][n]); __builtin_amdgcn_s_setprio(0); } while (0)
; #define PG8_WAIT_V(n) asm volatile("s_waitcnt vmcnt(" #n ")" ::: "memory")
; template <class Epi, class Sched, bool ALIGN_EPI = false, bool SP2 = false, bool F16 = false>
; __device__ __forceinline__ void gemm_phase(PG8_LAS unsigned char* lds, const Gemm g, const Sched& S, const Epi& E, const int wid_in) {
;     ...
;             PG8_LDB(B0, 0, 0); PG8_LDB(B1, 0, 1); PG8_SCHED; PG8_LDA(At, 0, 0); PG8_STAGE(PG8_SA(1, 1), a1 + hstep, voffA);
;             PG8_WAIT_V(8); PG8_WAIT_L(0); PG8_BAR; PG8_MMA(0, 0, At, B0); PG8_MMA(0, 1, At, B1); PG8_BAR; PG8_SCHED;
;             PG8_LDA(At, 0, 1); PG8_STAGE(PG8_SB(0, 0), b2, voffB); PG8_STAGE(PG8_SB(0, 1), b2 + hstep, voffB); PG8_STAGE(PG8_SA(0, 0), a2, voffA);
;             PG8_WAIT_V(8); PG8_WAIT_L(0); PG8_BAR; PG8_MMA(1, 0, At, B0); PG8_MMA(1, 1, At, B1); PG8_BAR; PG8_SCHED;
;             PG8_LDB(B0, 1, 0); PG8_LDB(B1, 1, 1); PG8_SCHED; PG8_LDA(At, 1, 0); PG8_STAGE(PG8_SA(0, 1), a2 + hstep, voffA);
;             PG8_WAIT_V(8); PG8_WAIT_L(0); PG8_BAR; PG8_MMA(0, 0, At, B0); PG8_MMA(0, 1, At, B1); PG8_BAR; PG8_SCHED;
;             PG8_LDA(At, 1, 1); PG8_STAGE(PG8_SB(1, 0), b3, voffB); PG8_STAGE(PG8_SB(1, 1), b3 + hstep, voffB); PG8_STAGE(PG8_SA(1, 0), a3, voffA);
;             PG8_WAIT_V(8); PG8_WAIT_L(0); PG8_BAR; PG8_MMA(1, 0, At, B0); PG8_MMA(1, 1, At, B1); PG8_BAR; PG8_SCHED;
	s_mov_b32 m0, s51
	v_lshl_add_u64 v[204:205], v[204:205], 0, s[24:25]
	s_add_u32 s42, s42, 0x10180
	ds_read_b128 v[172:175], v136 offset:49152
	ds_read_b128 v[176:179], v136 offset:50176
	ds_read_b128 v[180:183], v136 offset:51200
	ds_read_b128 v[184:187], v136 offset:52224
	ds_read_b128 v[188:191], v136 offset:53248
	ds_read_b128 v[192:195], v136 offset:54272
	ds_read_b128 v[196:199], v136 offset:55296
	ds_read_b128 v[200:203], v136 offset:56320
	global_load_lds_dwordx4 v[204:205], off
	v_lshl_add_u64 v[204:205], v[206:207], 0, s[24:25]
	s_mov_b32 m0, s52
	s_addc_u32 s43, s43, 0
	global_load_lds_dwordx4 v[204:205], off
	v_lshl_add_u64 v[204:205], s[42:43], 0, v[130:131]
	s_mov_b32 m0, s53
	s_nop 0
	global_load_lds_dwordx4 v[204:205], off
	v_lshl_add_u64 v[204:205], s[42:43], 0, v[128:129]
	s_mov_b32 m0, s54
	s_nop 0
	global_load_lds_dwordx4 v[204:205], off
	v_lshl_add_u64 v[204:205], v[208:209], 0, s[24:25]
	s_mov_b32 m0, s75
	s_nop 0
	global_load_lds_dwordx4 v[204:205], off
	v_lshl_add_u64 v[204:205], v[210:211], 0, s[24:25]
	s_mov_b32 m0, s67
	s_nop 0
	global_load_lds_dwordx4 v[204:205], off
	s_waitcnt vmcnt(8)
	s_waitcnt lgkmcnt(0)
	s_barrier
	v_mfma_f32_16x16x32_bf16 v[0:3], v[24:27], v[196:199], v[0:3]
	v_mfma_f32_16x16x32_bf16 v[4:7], v[112:115], v[196:199], v[4:7]
	v_mfma_f32_16x16x32_bf16 v[140:143], v[24:27], v[172:175], v[140:143]
	v_mfma_f32_16x16x32_bf16 v[144:147], v[112:115], v[172:175], v[144:147]
	v_mfma_f32_16x16x32_bf16 v[148:151], v[24:27], v[180:183], v[148:151]
	v_mfma_f32_16x16x32_bf16 v[152:155], v[112:115], v[180:183], v[152:155]
	v_mfma_f32_16x16x32_bf16 v[156:159], v[24:27], v[188:191], v[156:159]
	v_mfma_f32_16x16x32_bf16 v[160:163], v[112:115], v[188:191], v[160:163]
	v_mfma_f32_16x16x32_bf16 v[0:3], v[28:31], v[200:203], v[0:3]
	v_mfma_f32_16x16x32_bf16 v[4:7], v[116:119], v[200:203], v[4:7]
	v_mfma_f32_16x16x32_bf16 v[140:143], v[28:31], v[176:179], v[140:143]
	v_mfma_f32_16x16x32_bf16 v[144:147], v[116:119], v[176:179], v[144:147]
	v_mfma_f32_16x16x32_bf16 v[148:151], v[28:31], v[184:187], v[148:151]
	v_mfma_f32_16x16x32_bf16 v[152:155], v[116:119], v[184:187], v[152:155]
	v_mfma_f32_16x16x32_bf16 v[156:159], v[28:31], v[192:195], v[156:159]
	v_mfma_f32_16x16x32_bf16 v[160:163], v[116:119], v[192:195], v[160:163]
	v_mfma_f32_16x16x32_bf16 v[8:11], v[120:123], v[172:175], v[8:11]
	v_mfma_f32_16x16x32_bf16 v[12:15], v[164:167], v[172:175], v[12:15]
	v_mfma_f32_16x16x32_bf16 v[24:27], v[120:123], v[180:183], v[60:63]
	v_mfma_f32_16x16x32_bf16 v[28:31], v[164:167], v[180:183], v[100:103]
	v_mfma_f32_16x16x32_bf16 v[60:63], v[120:123], v[188:191], v[104:107]
	v_mfma_f32_16x16x32_bf16 v[100:103], v[164:167], v[188:191], v[108:111]
	v_mfma_f32_16x16x32_bf16 v[16:19], v[120:123], v[196:199], v[16:19]
	v_mfma_f32_16x16x32_bf16 v[20:23], v[164:167], v[196:199], v[20:23]
	v_mfma_f32_16x16x32_bf16 v[8:11], v[124:127], v[176:179], v[8:11]
	v_mfma_f32_16x16x32_bf16 v[12:15], v[168:171], v[176:179], v[12:15]
	v_mfma_f32_16x16x32_bf16 v[24:27], v[124:127], v[184:187], v[24:27]
	v_mfma_f32_16x16x32_bf16 v[28:31], v[168:171], v[184:187], v[28:31]
	v_mfma_f32_16x16x32_bf16 v[60:63], v[124:127], v[192:195], v[60:63]
	v_mfma_f32_16x16x32_bf16 v[100:103], v[168:171], v[192:195], v[100:103]
	v_mfma_f32_16x16x32_bf16 v[16:19], v[124:127], v[200:203], v[16:19]
	v_mfma_f32_16x16x32_bf16 v[20:23], v[168:171], v[200:203], v[20:23]
	s_barrier
	ds_read_b128 v[104:107], v134
	ds_read_b128 v[108:111], v134 offset:1024
	ds_read_b128 v[112:115], v134 offset:2048
	ds_read_b128 v[116:119], v134 offset:3072
	ds_read_b128 v[120:123], v135
	ds_read_b128 v[124:127], v135 offset:1024
	ds_read_b128 v[164:167], v135 offset:2048
	ds_read_b128 v[168:171], v135 offset:3072
	s_add_u32 s36, s36, 0x10180
	s_addc_u32 s37, s37, 0
	s_mov_b32 m0, s91
	v_lshl_add_u64 v[204:205], s[36:37], 0, v[130:131]
	ds_read_b128 v[172:175], v136
	ds_read_b128 v[176:179], v136 offset:1024
	ds_read_b128 v[180:183], v136 offset:2048
	ds_read_b128 v[184:187], v136 offset:3072
	ds_read_b128 v[188:191], v136 offset:4096
	ds_read_b128 v[192:195], v136 offset:5120
	ds_read_b128 v[196:199], v136 offset:6144
	ds_read_b128 v[200:203], v136 offset:7168
	global_load_lds_dwordx4 v[204:205], off
	v_lshl_add_u64 v[204:205], s[36:37], 0, v[128:129]
	s_mov_b32 m0, s14
	s_nop 0
	global_load_lds_dwordx4 v[204:205], off
	s_waitcnt vmcnt(8)
	s_waitcnt lgkmcnt(0)
	s_barrier
	v_mfma_f32_16x16x32_bf16 v[64:67], v[104:107], v[172:175], v[64:67]
	v_mfma_f32_16x16x32_bf16 v[68:71], v[112:115], v[172:175], v[68:71]
	v_mfma_f32_16x16x32_bf16 v[72:75], v[104:107], v[180:183], v[72:75]
	v_mfma_f32_16x16x32_bf16 v[76:79], v[112:115], v[180:183], v[76:79]
	v_mfma_f32_16x16x32_bf16 v[80:83], v[104:107], v[188:191], v[80:83]
	v_mfma_f32_16x16x32_bf16 v[84:87], v[112:115], v[188:191], v[84:87]
	v_mfma_f32_16x16x32_bf16 v[88:91], v[104:107], v[196:199], v[88:91]
	v_mfma_f32_16x16x32_bf16 v[92:95], v[112:115], v[196:199], v[92:95]
	v_mfma_f32_16x16x32_bf16 v[64:67], v[108:111], v[176:179], v[64:67]
	v_mfma_f32_16x16x32_bf16 v[68:71], v[116:119], v[176:179], v[68:71]
	v_mfma_f32_16x16x32_bf16 v[72:75], v[108:111], v[184:187], v[72:75]
	v_mfma_f32_16x16x32_bf16 v[76:79], v[116:119], v[184:187], v[76:79]
	v_mfma_f32_16x16x32_bf16 v[80:83], v[108:111], v[192:195], v[80:83]
	v_mfma_f32_16x16x32_bf16 v[84:87], v[116:119], v[192:195], v[84:87]
	v_mfma_f32_16x16x32_bf16 v[88:91], v[108:111], v[200:203], v[88:91]
	v_mfma_f32_16x16x32_bf16 v[92:95], v[116:119], v[200:203], v[92:95]
	v_mfma_f32_16x16x32_bf16 v[32:35], v[164:167], v[172:175], v[32:35]
	v_mfma_f32_16x16x32_bf16 v[96:99], v[120:123], v[172:175], v[96:99]
	v_mfma_f32_16x16x32_bf16 v[172:175], v[168:171], v[176:179], v[32:35]
	v_mfma_f32_16x16x32_bf16 v[32:35], v[120:123], v[180:183], v[36:39]
	v_mfma_f32_16x16x32_bf16 v[204:207], v[124:127], v[176:179], v[96:99]
	v_mfma_f32_16x16x32_bf16 v[176:179], v[124:127], v[184:187], v[32:35]
	v_mfma_f32_16x16x32_bf16 v[32:35], v[164:167], v[180:183], v[40:43]
	v_mfma_f32_16x16x32_bf16 v[40:43], v[168:171], v[184:187], v[32:35]
	v_mfma_f32_16x16x32_bf16 v[32:35], v[120:123], v[188:191], v[44:47]
	v_mfma_f32_16x16x32_bf16 v[44:47], v[124:127], v[192:195], v[32:35]
	v_mfma_f32_16x16x32_bf16 v[32:35], v[164:167], v[188:191], v[48:51]
	v_mfma_f32_16x16x32_bf16 v[48:51], v[168:171], v[192:195], v[32:35]
	v_mfma_f32_16x16x32_bf16 v[32:35], v[120:123], v[196:199], v[52:55]
	v_mfma_f32_16x16x32_bf16 v[52:55], v[124:127], v[200:203], v[32:35]
	v_mfma_f32_16x16x32_bf16 v[32:35], v[164:167], v[196:199], v[56:59]
	v_mfma_f32_16x16x32_bf16 v[56:59], v[168:171], v[200:203], v[32:35]
	s_barrier
; #define PG8_STAGE(bufoff, gbase, voff) do { _Pragma("unroll") for (int _i = 0; _i < 2; ++_i) \
;         __builtin_amdgcn_global_load_lds((const unsigned*)((const char*)(gbase) + (voff)[_i]), (PG8_LAS unsigned*)(lds + (bufoff) + ldsw + _i * 8192), 16, 0, 0); } while (0)
; #define PG8_LDA(dst, b, h) do { _Pragma("unroll") for (int m = 0; m < 4; ++m) _Pragma("unroll") for (int k = 0; k < 2; ++k) dst[m][k] = *(const PG8_LAS bf16x8*)(lds + PG8_SA(b, h) + aoff + m * 2048 + k * 1024); } while (0)
; #define PG8_LDB(dst, b, h) do { _Pragma("unroll") for (int n = 0; n < 2; ++n) _Pragma("unroll") for (int k = 0; k < 2; ++k) dst[n][k] = *(const PG8_LAS bf16x8*)(lds + PG8_SB(b, h) + boff + n * 2048 + k * 1024); } while (0)
; #define PG8_MMA(ai, bj, At, Bt) do { __builtin_amdgcn_s_setprio(1); _Pragma("unroll") for (int m = 0; m < 4; ++m) _Pragma("unroll") for (int n = 0; n < 2; ++n) _Pragma("unroll") for (int k = 0; k < 2; ++k) \
;         acc[ai][bj][m][n] = mma16<F16>(Bt[n][k], At[m][k], acc[ai][bj][m][n]); __builtin_amdgcn_s_setprio(0); } while (0)
; #define PG8_WAIT_V(n) asm volatile("s_waitcnt vmcnt(" #n ")" ::: "memory")
; template <class Epi, class Sched, bool ALIGN_EPI = false, bool SP2 = false, bool F16 = false>
; __device__ __forceinline__ void gemm_phase(PG8_LAS unsigned char* lds, const Gemm g, const Sched& S, const Epi& E, const int wid_in) {
;     ...
;             PG8_LDB(B0, 0, 0); PG8_LDB(B1, 0, 1); PG8_SCHED; PG8_LDA(At, 0, 0); PG8_STAGE(PG8_SA(1, 1), a1 + hstep, voffA);
;             PG8_WAIT_V(8); PG8_WAIT_L(0); PG8_BAR; PG8_MMA(0, 0, At, B0); PG8_MMA(0, 1, At, B1); PG8_BAR; PG8_SCHED;
;             PG8_LDA(At, 0, 1); PG8_STAGE(PG8_SB(0, 0), b2, voffB); PG8_STAGE(PG8_SB(0, 1), b2 + hstep, voffB); PG8_STAGE(PG8_SA(0, 0), a2, voffA);
;             PG8_WAIT_V(8); PG8_WAIT_L(0); PG8_BAR; PG8_MMA(1, 0, At, B0); PG8_MMA(1, 1, At, B1); PG8_BAR; PG8_SCHED;
;             PG8_LDB(B0, 1, 0); PG8_LDB(B1, 1, 1); PG8_SCHED; PG8_LDA(At, 1, 0); PG8_STAGE(PG8_SA(0, 1), a2 + hstep, voffA);
;             PG8_WAIT_V(8); PG8_WAIT_L(0); PG8_BAR; PG8_MMA(0, 0, At, B0); PG8_MMA(0, 1, At, B1); PG8_BAR; PG8_SCHED;
;             PG8_LDA(At, 1, 1); PG8_STAGE(PG8_SB(1, 0), b3, voffB); PG8_STAGE(PG8_SB(1, 1), b3 + hstep, voffB); PG8_STAGE(PG8_SA(1, 0), a3, voffA);
;             PG8_WAIT_V(8); PG8_WAIT_L(0); PG8_BAR; PG8_MMA(1, 0, At, B0); PG8_MMA(1, 1, At, B1); PG8_BAR; PG8_SCHED;
	s_mov_b32 m0, s15
	v_lshl_add_u64 v[240:241], s[30:31], 0, v[130:131]
	s_add_u32 s36, s30, 0x10000
	s_nop 1
	ds_read_b128 v[32:35], v136 offset:16384
	ds_read_b128 v[36:39], v136 offset:17408
	ds_read_b128 v[96:99], v136 offset:18432
	ds_read_b128 v[180:183], v136 offset:19456
	ds_read_b128 v[184:187], v136 offset:20480
	ds_read_b128 v[188:191], v136 offset:21504
	ds_read_b128 v[192:195], v136 offset:22528
	ds_read_b128 v[196:199], v136 offset:23552
	global_load_lds_dwordx4 v[240:241], off
	v_lshl_add_u64 v[242:243], s[30:31], 0, v[128:129]
	s_mov_b32 m0, s48
	s_addc_u32 s37, s31, 0
	global_load_lds_dwordx4 v[242:243], off
	v_lshl_add_u64 v[200:201], s[36:37], 0, v[130:131]
	s_mov_b32 m0, s49
	v_lshl_add_u64 v[244:245], s[34:35], 0, v[130:131]
	global_load_lds_dwordx4 v[200:201], off
	v_lshl_add_u64 v[200:201], s[36:37], 0, v[128:129]
	s_mov_b32 m0, s50
	v_lshl_add_u64 v[246:247], s[34:35], 0, v[128:129]
	global_load_lds_dwordx4 v[200:201], off
	s_mov_b32 m0, s74
	s_nop 0
	global_load_lds_dwordx4 v[244:245], off
	s_mov_b32 m0, s66
	s_nop 0
	global_load_lds_dwordx4 v[246:247], off
	s_waitcnt vmcnt(8)
	s_waitcnt lgkmcnt(0)
	s_barrier
	v_mfma_f32_16x16x32_bf16 v[0:3], v[104:107], v[192:195], v[0:3]
	v_mfma_f32_16x16x32_bf16 v[140:143], v[104:107], v[32:35], v[140:143]
	v_mfma_f32_16x16x32_bf16 v[144:147], v[112:115], v[32:35], v[144:147]
	v_mfma_f32_16x16x32_bf16 v[148:151], v[104:107], v[96:99], v[148:151]
	v_mfma_f32_16x16x32_bf16 v[152:155], v[112:115], v[96:99], v[152:155]
	v_mfma_f32_16x16x32_bf16 v[156:159], v[104:107], v[184:187], v[156:159]
	v_mfma_f32_16x16x32_bf16 v[160:163], v[112:115], v[184:187], v[160:163]
	v_mfma_f32_16x16x32_bf16 v[0:3], v[108:111], v[196:199], v[0:3]
	v_mfma_f32_16x16x32_bf16 v[4:7], v[112:115], v[192:195], v[4:7]
	v_mfma_f32_16x16x32_bf16 v[140:143], v[108:111], v[36:39], v[140:143]
	v_mfma_f32_16x16x32_bf16 v[144:147], v[116:119], v[36:39], v[144:147]
	v_mfma_f32_16x16x32_bf16 v[148:151], v[108:111], v[180:183], v[148:151]
	v_mfma_f32_16x16x32_bf16 v[152:155], v[116:119], v[180:183], v[152:155]
	v_mfma_f32_16x16x32_bf16 v[156:159], v[108:111], v[188:191], v[156:159]
	v_mfma_f32_16x16x32_bf16 v[160:163], v[116:119], v[188:191], v[160:163]
	v_mfma_f32_16x16x32_bf16 v[200:203], v[116:119], v[196:199], v[4:7]
	v_mfma_f32_16x16x32_bf16 v[4:7], v[120:123], v[32:35], v[8:11]
	v_mfma_f32_16x16x32_bf16 v[8:11], v[124:127], v[36:39], v[4:7]
	v_mfma_f32_16x16x32_bf16 v[4:7], v[164:167], v[32:35], v[12:15]
	v_mfma_f32_16x16x32_bf16 v[12:15], v[168:171], v[36:39], v[4:7]
	v_mfma_f32_16x16x32_bf16 v[4:7], v[120:123], v[96:99], v[24:27]
	v_mfma_f32_16x16x32_bf16 v[24:27], v[124:127], v[180:183], v[4:7]
	v_mfma_f32_16x16x32_bf16 v[4:7], v[164:167], v[96:99], v[28:31]
	v_mfma_f32_16x16x32_bf16 v[28:31], v[168:171], v[180:183], v[4:7]
	v_mfma_f32_16x16x32_bf16 v[4:7], v[120:123], v[184:187], v[60:63]
	v_mfma_f32_16x16x32_bf16 v[180:183], v[124:127], v[188:191], v[4:7]
	v_mfma_f32_16x16x32_bf16 v[4:7], v[164:167], v[184:187], v[100:103]
	v_mfma_f32_16x16x32_bf16 v[184:187], v[168:171], v[188:191], v[4:7]
	v_mfma_f32_16x16x32_bf16 v[4:7], v[120:123], v[192:195], v[16:19]
	v_mfma_f32_16x16x32_bf16 v[188:191], v[124:127], v[196:199], v[4:7]
	v_mfma_f32_16x16x32_bf16 v[4:7], v[164:167], v[192:195], v[20:23]
	v_mfma_f32_16x16x32_bf16 v[164:167], v[168:171], v[196:199], v[4:7]
	s_barrier
	s_nop 4
	ds_read_b128 v[4:7], v137
	ds_read_b128 v[60:63], v137 offset:1024
	ds_read_b128 v[168:171], v137 offset:2048
	ds_read_b128 v[192:195], v137 offset:3072
	ds_read_b128 v[196:199], v138
	ds_read_b128 v[208:211], v138 offset:1024
	ds_read_b128 v[212:215], v138 offset:2048
	ds_read_b128 v[216:219], v138 offset:3072
	s_add_u32 s34, s34, 0x10000
	s_addc_u32 s35, s35, 0
	s_mov_b32 m0, s90
	v_lshl_add_u64 v[32:33], s[34:35], 0, v[130:131]
	ds_read_b128 v[16:19], v136 offset:32768
	ds_read_b128 v[20:23], v136 offset:33792
	ds_read_b128 v[104:107], v136 offset:34816
	ds_read_b128 v[220:223], v136 offset:35840
	ds_read_b128 v[224:227], v136 offset:36864
	ds_read_b128 v[228:231], v136 offset:37888
	ds_read_b128 v[232:235], v136 offset:38912
	ds_read_b128 v[236:239], v136 offset:39936
	global_load_lds_dwordx4 v[32:33], off
	v_lshl_add_u64 v[32:33], s[34:35], 0, v[128:129]
	s_mov_b32 m0, s47
	s_nop 0
	global_load_lds_dwordx4 v[32:33], off
	s_waitcnt vmcnt(8)
	s_waitcnt lgkmcnt(0)
	s_barrier
; #define PG8_STAGE(bufoff, gbase, voff) do { _Pragma("unroll") for (int _i = 0; _i < 2; ++_i) \
;         __builtin_amdgcn_global_load_lds((const unsigned*)((const char*)(gbase) + (voff)[_i]), (PG8_LAS unsigned*)(lds + (bufoff) + ldsw + _i * 8192), 16, 0, 0); } while (0)
; #define PG8_LDA(dst, b, h) do { _Pragma("unroll") for (int m = 0; m < 4; ++m) _Pragma("unroll") for (int k = 0; k < 2; ++k) dst[m][k] = *(const PG8_LAS bf16x8*)(lds + PG8_SA(b, h) + aoff + m * 2048 + k * 1024); } while (0)
; #define PG8_LDB(dst, b, h) do { _Pragma("unroll") for (int n = 0; n < 2; ++n) _Pragma("unroll") for (int k = 0; k < 2; ++k) dst[n][k] = *(const PG8_LAS bf16x8*)(lds + PG8_SB(b, h) + boff + n * 2048 + k * 1024); } while (0)
; #define PG8_WAIT_V(n) asm volatile("s_waitcnt vmcnt(" #n ")" ::: "memory")
; #define PG8_WAIT_L(n) asm volatile("s_waitcnt lgkmcnt(" #n ")" ::: "memory")
; #define PG8_BAR __builtin_amdgcn_s_barrier()
; #define PG8_SCHED __builtin_amdgcn_sched_barrier(0)
; template <class Epi, class Sched, bool ALIGN_EPI = false, bool SP2 = false, bool F16 = false>
; __device__ __forceinline__ void gemm_phase(PG8_LAS unsigned char* lds, const Gemm g, const Sched& S, const Epi& E, const int wid_in) {
;     ...
;             PG8_LDB(B0, 0, 0); PG8_LDB(B1, 0, 1); PG8_SCHED; PG8_LDA(At, 0, 0); PG8_STAGE(PG8_SA(1, 1), a1 + hstep, voffA);
;             PG8_WAIT_V(8); PG8_WAIT_L(0); PG8_BAR; PG8_MMA(0, 0, At, B0); PG8_MMA(0, 1, At, B1); PG8_BAR; PG8_SCHED;
;             PG8_LDA(At, 0, 1); PG8_STAGE(PG8_SB(0, 0), b2, voffB); PG8_STAGE(PG8_SB(0, 1), b2 + hstep, voffB); PG8_STAGE(PG8_SA(0, 0), a2, voffA);
;             PG8_WAIT_V(8); PG8_WAIT_L(0); PG8_BAR; PG8_MMA(1, 0, At, B0); PG8_MMA(1, 1, At, B1); PG8_BAR; PG8_SCHED;
;             PG8_LDB(B0, 1, 0); PG8_LDB(B1, 1, 1); PG8_SCHED; PG8_LDA(At, 1, 0); PG8_STAGE(PG8_SA(0, 1), a2 + hstep, voffA);
;             PG8_WAIT_V(8); PG8_WAIT_L(0); PG8_BAR; PG8_MMA(0, 0, At, B0); PG8_MMA(0, 1, At, B1); PG8_BAR; PG8_SCHED;
;             PG8_LDA(At, 1, 1); PG8_STAGE(PG8_SB(1, 0), b3, voffB); PG8_STAGE(PG8_SB(1, 1), b3 + hstep, voffB); PG8_STAGE(PG8_SA(1, 0), a3, voffA);
;             PG8_WAIT_V(8); PG8_WAIT_L(0); PG8_BAR; PG8_MMA(1, 0, At, B0); PG8_MMA(1, 1, At, B1); PG8_BAR; PG8_SCHED;
;     ...
;         if constexpr (ALIGN_EPI) { if (wr == 0) PG8_BAR; }
;         if constexpr (!Epi::AFTER_DRAIN) { E(acc, cur, wr, wc, fr, fq); S.done(cur); }
	v_mfma_f32_16x16x32_bf16 v[32:35], v[4:7], v[16:19], v[64:67]
	v_mfma_f32_16x16x32_bf16 v[116:119], v[60:63], v[20:23], v[32:35]
	v_mfma_f32_16x16x32_bf16 v[32:35], v[168:171], v[16:19], v[68:71]
	v_mfma_f32_16x16x32_bf16 v[112:115], v[192:195], v[20:23], v[32:35]
	v_mfma_f32_16x16x32_bf16 v[32:35], v[4:7], v[104:107], v[72:75]
	v_mfma_f32_16x16x32_bf16 v[100:103], v[60:63], v[220:223], v[32:35]
	v_mfma_f32_16x16x32_bf16 v[32:35], v[168:171], v[104:107], v[76:79]
	v_mfma_f32_16x16x32_bf16 v[96:99], v[192:195], v[220:223], v[32:35]
	v_mfma_f32_16x16x32_bf16 v[32:35], v[4:7], v[224:227], v[80:83]
	v_mfma_f32_16x16x32_bf16 v[68:71], v[60:63], v[228:231], v[32:35]
	v_mfma_f32_16x16x32_bf16 v[32:35], v[168:171], v[224:227], v[84:87]
	v_mfma_f32_16x16x32_bf16 v[64:67], v[192:195], v[228:231], v[32:35]
	v_mfma_f32_16x16x32_bf16 v[32:35], v[4:7], v[232:235], v[88:91]
	v_mfma_f32_16x16x32_bf16 v[36:39], v[60:63], v[236:239], v[32:35]
	v_mfma_f32_16x16x32_bf16 v[32:35], v[168:171], v[232:235], v[92:95]
	v_mfma_f32_16x16x32_bf16 v[32:35], v[192:195], v[236:239], v[32:35]
	v_mfma_f32_16x16x32_bf16 v[72:75], v[196:199], v[16:19], v[204:207]
	v_mfma_f32_16x16x32_bf16 v[16:19], v[212:215], v[16:19], v[172:175]
	v_mfma_f32_16x16x32_bf16 v[120:123], v[216:219], v[20:23], v[16:19]
	v_mfma_f32_16x16x32_bf16 v[16:19], v[196:199], v[104:107], v[176:179]
	v_mfma_f32_16x16x32_bf16 v[108:111], v[208:211], v[220:223], v[16:19]
	v_mfma_f32_16x16x32_bf16 v[16:19], v[212:215], v[104:107], v[40:43]
	v_mfma_f32_16x16x32_bf16 v[104:107], v[216:219], v[220:223], v[16:19]
	v_mfma_f32_16x16x32_bf16 v[16:19], v[196:199], v[224:227], v[44:47]
	v_mfma_f32_16x16x32_bf16 v[80:83], v[208:211], v[228:231], v[16:19]
	v_mfma_f32_16x16x32_bf16 v[16:19], v[212:215], v[224:227], v[48:51]
	v_mfma_f32_16x16x32_bf16 v[124:127], v[208:211], v[20:23], v[72:75]
	v_mfma_f32_16x16x32_bf16 v[72:75], v[216:219], v[228:231], v[16:19]
	v_mfma_f32_16x16x32_bf16 v[16:19], v[196:199], v[232:235], v[52:55]
	v_mfma_f32_16x16x32_bf16 v[48:51], v[208:211], v[236:239], v[16:19]
	v_mfma_f32_16x16x32_bf16 v[16:19], v[212:215], v[232:235], v[56:59]
	v_mfma_f32_16x16x32_bf16 v[40:43], v[216:219], v[236:239], v[16:19]
	s_barrier
	s_mov_b32 m0, s51
	s_nop 3
	v_lshl_add_u64 v[16:17], v[240:241], 0, s[20:21]
	s_add_u32 s30, s30, 0x10080
	ds_read_b128 v[56:59], v136 offset:49152
	ds_read_b128 v[88:91], v136 offset:50176
	ds_read_b128 v[172:175], v136 offset:51200
	ds_read_b128 v[176:179], v136 offset:52224
	ds_read_b128 v[204:207], v136 offset:53248
	ds_read_b128 v[220:223], v136 offset:54272
	ds_read_b128 v[224:227], v136 offset:55296
	ds_read_b128 v[228:231], v136 offset:56320
	global_load_lds_dwordx4 v[16:17], off
	v_lshl_add_u64 v[16:17], v[242:243], 0, s[20:21]
	s_mov_b32 m0, s52
	s_addc_u32 s31, s31, 0
	global_load_lds_dwordx4 v[16:17], off
	v_lshl_add_u64 v[16:17], s[30:31], 0, v[130:131]
	s_mov_b32 m0, s53
	s_nop 0
	global_load_lds_dwordx4 v[16:17], off
	v_lshl_add_u64 v[16:17], s[30:31], 0, v[128:129]
	s_mov_b32 m0, s54
	s_nop 0
	global_load_lds_dwordx4 v[16:17], off
	v_lshl_add_u64 v[16:17], v[244:245], 0, s[20:21]
	s_mov_b32 m0, s75
	s_nop 0
	global_load_lds_dwordx4 v[16:17], off
	v_lshl_add_u64 v[16:17], v[246:247], 0, s[20:21]
	s_mov_b32 m0, s67
	s_nop 0
	global_load_lds_dwordx4 v[16:17], off
	s_waitcnt vmcnt(8)
	s_waitcnt lgkmcnt(0)
	s_barrier
	v_mfma_f32_16x16x32_bf16 v[16:19], v[4:7], v[56:59], v[140:143]
	v_mfma_f32_16x16x32_bf16 v[84:87], v[60:63], v[88:91], v[16:19]
	v_mfma_f32_16x16x32_bf16 v[16:19], v[168:171], v[56:59], v[144:147]
	v_mfma_f32_16x16x32_bf16 v[76:79], v[192:195], v[88:91], v[16:19]
	v_mfma_f32_16x16x32_bf16 v[16:19], v[4:7], v[172:175], v[148:151]
	v_mfma_f32_16x16x32_bf16 v[52:55], v[60:63], v[176:179], v[16:19]
	v_mfma_f32_16x16x32_bf16 v[16:19], v[168:171], v[172:175], v[152:155]
	v_mfma_f32_16x16x32_bf16 v[44:47], v[192:195], v[176:179], v[16:19]
	v_mfma_f32_16x16x32_bf16 v[16:19], v[4:7], v[204:207], v[156:159]
	v_mfma_f32_16x16x32_bf16 v[0:3], v[4:7], v[224:227], v[0:3]
	v_mfma_f32_16x16x32_bf16 v[20:23], v[60:63], v[220:223], v[16:19]
	v_mfma_f32_16x16x32_bf16 v[16:19], v[168:171], v[204:207], v[160:163]
	v_mfma_f32_16x16x32_bf16 v[4:7], v[60:63], v[228:231], v[0:3]
	v_mfma_f32_16x16x32_bf16 v[0:3], v[168:171], v[224:227], v[200:203]
	v_mfma_f32_16x16x32_bf16 v[16:19], v[192:195], v[220:223], v[16:19]
	v_mfma_f32_16x16x32_bf16 v[0:3], v[192:195], v[228:231], v[0:3]
	v_mfma_f32_16x16x32_bf16 v[8:11], v[196:199], v[56:59], v[8:11]
	v_mfma_f32_16x16x32_bf16 v[92:95], v[208:211], v[88:91], v[8:11]
	v_mfma_f32_16x16x32_bf16 v[8:11], v[212:215], v[56:59], v[12:15]
	v_mfma_f32_16x16x32_bf16 v[88:91], v[216:219], v[88:91], v[8:11]
	v_mfma_f32_16x16x32_bf16 v[8:11], v[196:199], v[172:175], v[24:27]
	v_mfma_f32_16x16x32_bf16 v[60:63], v[208:211], v[176:179], v[8:11]
	v_mfma_f32_16x16x32_bf16 v[8:11], v[212:215], v[172:175], v[28:31]
	v_mfma_f32_16x16x32_bf16 v[56:59], v[216:219], v[176:179], v[8:11]
	v_mfma_f32_16x16x32_bf16 v[8:11], v[196:199], v[204:207], v[180:183]
	v_mfma_f32_16x16x32_bf16 v[28:31], v[208:211], v[220:223], v[8:11]
	v_mfma_f32_16x16x32_bf16 v[8:11], v[212:215], v[204:207], v[184:187]
	v_mfma_f32_16x16x32_bf16 v[24:27], v[216:219], v[220:223], v[8:11]
	v_mfma_f32_16x16x32_bf16 v[8:11], v[196:199], v[224:227], v[188:191]
	v_mfma_f32_16x16x32_bf16 v[12:15], v[208:211], v[228:231], v[8:11]
	v_mfma_f32_16x16x32_bf16 v[8:11], v[212:215], v[224:227], v[164:167]
	v_mfma_f32_16x16x32_bf16 v[8:11], v[216:219], v[228:231], v[8:11]
	s_barrier
	s_and_b64 vcc, exec, s[8:9]
	s_cbranch_vccnz .LBB0_2603
	s_barrier

; #define PG8_STAGE(bufoff, gbase, voff) do { _Pragma("unroll") for (int _i = 0; _i < 2; ++_i) \
;         __builtin_amdgcn_global_load_lds((const unsigned*)((const char*)(gbase) + (voff)[_i]), (PG8_LAS unsigned*)(lds + (bufoff) + ldsw + _i * 8192), 16, 0, 0); } while (0)
; #define PG8_LDA(dst, b, h) do { _Pragma("unroll") for (int m = 0; m < 4; ++m) _Pragma("unroll") for (int k = 0; k < 2; ++k) dst[m][k] = *(const PG8_LAS bf16x8*)(lds + PG8_SA(b, h) + aoff + m * 2048 + k * 1024); } while (0)
; #define PG8_WAIT_V(n) asm volatile("s_waitcnt vmcnt(" #n ")" ::: "memory")
; #define PG8_WAIT_L(n) asm volatile("s_waitcnt lgkmcnt(" #n ")" ::: "memory")
; template <class Epi, class Sched, bool ALIGN_EPI = false, bool SP2 = false, bool F16 = false>
; __device__ __forceinline__ void gemm_phase(PG8_LAS unsigned char* lds, const Gemm g, const Sched& S, const Epi& E, const int wid_in) {
;     ...
;         for (int t = 0; t < nt; t += 2) {
;             const bool last = (t == nt - 2);
;             const char* a1 = cA + (size_t)(t + 1) * kstep;
;             const char* a2 = last ? nA : cA + (size_t)(t + 2) * kstep; const char* b2 = last ? nB : cB + (size_t)(t + 2) * kstep;
;             const char* a3 = a2 + kstep; const char* b3 = b2 + kstep;
;             if (last && has_next) S.a_ready(nxt);
;             if constexpr (SP2) {
;             PG8_LDB(B0, 0, 0); PG8_LDB(B1, 0, 1); PG8_SCHED; PG8_LDA(At, 0, 0); PG8_STAGE(PG8_SA(1, 1), a1 + hstep, voffA);
;             PG8_WAIT_V(8); PG8_WAIT_L(0); PG8_BAR; PG8_MMA(0, 0, At, B0); PG8_MMA(0, 1, At, B1); PG8_BAR; PG8_SCHED;
;             PG8_LDA(At, 0, 1); PG8_STAGE(PG8_SB(0, 0), b2, voffB); PG8_STAGE(PG8_SB(0, 1), b2 + hstep, voffB); PG8_STAGE(PG8_SA(0, 0), a2, voffA);
;             PG8_WAIT_V(8); PG8_WAIT_L(0); PG8_BAR; PG8_MMA(1, 0, At, B0); PG8_MMA(1, 1, At, B1); PG8_BAR; PG8_SCHED;
;             PG8_LDB(B0, 1, 0); PG8_LDB(B1, 1, 1); PG8_SCHED; PG8_LDA(At, 1, 0); PG8_STAGE(PG8_SA(0, 1), a2 + hstep, voffA);
;             PG8_WAIT_V(8); PG8_WAIT_L(0); PG8_BAR; PG8_MMA(0, 0, At, B0); PG8_MMA(0, 1, At, B1); PG8_BAR; PG8_SCHED;
;             PG8_LDA(At, 1, 1); PG8_STAGE(PG8_SB(1, 0), b3, voffB); PG8_STAGE(PG8_SB(1, 1), b3 + hstep, voffB); PG8_STAGE(PG8_SA(1, 0), a3, voffA);
;             PG8_WAIT_V(8); PG8_WAIT_L(0); PG8_BAR; PG8_MMA(1, 0, At, B0); PG8_MMA(1, 1, At, B1); PG8_BAR; PG8_SCHED;
.LBB0_2697:
	ds_read_b128 v[128:131], v189
	ds_read_b128 v[132:135], v189 offset:1024
	ds_read_b128 v[136:139], v189 offset:2048
	ds_read_b128 v[140:143], v189 offset:3072
	ds_read_b128 v[144:147], v190
	ds_read_b128 v[148:151], v190 offset:1024
	ds_read_b128 v[168:171], v190 offset:2048
	ds_read_b128 v[172:175], v190 offset:3072
	s_add_u32 s30, s28, 0x100
	s_addc_u32 s31, s29, 0
	s_cmp_eq_u32 s55, 40
	s_cselect_b32 s37, s11, s31
	s_cselect_b32 s36, s10, s30
	s_cselect_b32 s35, s27, s54
	s_cselect_b32 s34, s26, s53
	s_mov_b32 m0, s91
	v_lshl_add_u64 v[184:185], s[28:29], 0, v[160:161]
	ds_read_b128 v[176:179], v191
	ds_read_b128 v[180:183], v191 offset:1024
	ds_read_b128 v[192:195], v191 offset:2048
	ds_read_b128 v[196:199], v191 offset:3072
	ds_read_b128 v[200:203], v191 offset:4096
	ds_read_b128 v[204:207], v191 offset:5120
	ds_read_b128 v[208:211], v191 offset:6144
	ds_read_b128 v[212:215], v191 offset:7168
	global_load_lds_dwordx4 v[184:185], off
	v_lshl_add_u64 v[184:185], s[28:29], 0, v[162:163]
	s_add_i32 m0, s74, 0xe000
	s_nop 0
	global_load_lds_dwordx4 v[184:185], off
	s_waitcnt vmcnt(8)
	s_waitcnt lgkmcnt(0)
	s_barrier
	v_mfma_f32_16x16x32_bf16 v[124:127], v[128:131], v[176:179], v[124:127]
	v_mfma_f32_16x16x32_bf16 v[120:123], v[136:139], v[176:179], v[120:123]
	v_mfma_f32_16x16x32_bf16 v[108:111], v[128:131], v[192:195], v[108:111]
	v_mfma_f32_16x16x32_bf16 v[104:107], v[136:139], v[192:195], v[104:107]
	v_mfma_f32_16x16x32_bf16 v[92:95], v[128:131], v[200:203], v[92:95]
	v_mfma_f32_16x16x32_bf16 v[88:91], v[136:139], v[200:203], v[88:91]
	v_mfma_f32_16x16x32_bf16 v[76:79], v[128:131], v[208:211], v[76:79]
	v_mfma_f32_16x16x32_bf16 v[72:75], v[136:139], v[208:211], v[72:75]
	v_mfma_f32_16x16x32_bf16 v[124:127], v[132:135], v[180:183], v[124:127]
	v_mfma_f32_16x16x32_bf16 v[120:123], v[140:143], v[180:183], v[120:123]
	v_mfma_f32_16x16x32_bf16 v[108:111], v[132:135], v[196:199], v[108:111]
	v_mfma_f32_16x16x32_bf16 v[104:107], v[140:143], v[196:199], v[104:107]
	v_mfma_f32_16x16x32_bf16 v[92:95], v[132:135], v[204:207], v[92:95]
	v_mfma_f32_16x16x32_bf16 v[88:91], v[140:143], v[204:207], v[88:91]
	v_mfma_f32_16x16x32_bf16 v[76:79], v[132:135], v[212:215], v[76:79]
	v_mfma_f32_16x16x32_bf16 v[72:75], v[140:143], v[212:215], v[72:75]
	v_mfma_f32_16x16x32_bf16 v[116:119], v[144:147], v[176:179], v[116:119]
	v_mfma_f32_16x16x32_bf16 v[112:115], v[168:171], v[176:179], v[112:115]
	v_mfma_f32_16x16x32_bf16 v[100:103], v[144:147], v[192:195], v[100:103]
	v_mfma_f32_16x16x32_bf16 v[96:99], v[168:171], v[192:195], v[96:99]
	v_mfma_f32_16x16x32_bf16 v[84:87], v[144:147], v[200:203], v[84:87]
	v_mfma_f32_16x16x32_bf16 v[80:83], v[168:171], v[200:203], v[80:83]
	v_mfma_f32_16x16x32_bf16 v[68:71], v[144:147], v[208:211], v[68:71]
	v_mfma_f32_16x16x32_bf16 v[64:67], v[168:171], v[208:211], v[64:67]
	v_mfma_f32_16x16x32_bf16 v[116:119], v[148:151], v[180:183], v[116:119]
	v_mfma_f32_16x16x32_bf16 v[112:115], v[172:175], v[180:183], v[112:115]
	v_mfma_f32_16x16x32_bf16 v[100:103], v[148:151], v[196:199], v[100:103]
	v_mfma_f32_16x16x32_bf16 v[96:99], v[172:175], v[196:199], v[96:99]
	v_mfma_f32_16x16x32_bf16 v[84:87], v[148:151], v[204:207], v[84:87]
	v_mfma_f32_16x16x32_bf16 v[80:83], v[172:175], v[204:207], v[80:83]
	v_mfma_f32_16x16x32_bf16 v[68:71], v[148:151], v[212:215], v[68:71]
	v_mfma_f32_16x16x32_bf16 v[64:67], v[172:175], v[212:215], v[64:67]
	s_barrier
	s_add_i32 s28, s47, s68
	v_lshl_add_u64 v[184:185], s[34:35], 0, v[154:155]
	s_mov_b32 m0, s28
	ds_read_b128 v[176:179], v191 offset:16384
	ds_read_b128 v[180:183], v191 offset:17408
	ds_read_b128 v[192:195], v191 offset:18432
	ds_read_b128 v[196:199], v191 offset:19456
	ds_read_b128 v[200:203], v191 offset:20480
	ds_read_b128 v[204:207], v191 offset:21504
	ds_read_b128 v[208:211], v191 offset:22528
	ds_read_b128 v[212:215], v191 offset:23552
	global_load_lds_dwordx4 v[184:185], off
	s_add_i32 m0, s28, 0x2000
	s_add_u32 s28, s34, 0xb0000
	v_lshl_add_u64 v[216:217], s[34:35], 0, v[158:159]
	s_addc_u32 s29, s35, 0
	s_add_i32 s56, s48, s68
	global_load_lds_dwordx4 v[216:217], off
	v_lshl_add_u64 v[218:219], s[28:29], 0, v[154:155]
	s_mov_b32 m0, s56
	v_lshl_add_u64 v[220:221], s[36:37], 0, v[156:157]
	global_load_lds_dwordx4 v[218:219], off
	v_lshl_add_u64 v[218:219], s[28:29], 0, v[158:159]
	s_add_i32 m0, s56, 0x2000
	s_nop 0
	global_load_lds_dwordx4 v[218:219], off
	v_lshl_add_u64 v[218:219], s[36:37], 0, v[152:153]
	s_mov_b32 m0, s74
	s_nop 0
	global_load_lds_dwordx4 v[218:219], off
	s_mov_b32 m0, s66
	s_nop 0
	global_load_lds_dwordx4 v[220:221], off
	s_waitcnt vmcnt(8)
	s_waitcnt lgkmcnt(0)
	s_barrier
; #define PG8_STAGE(bufoff, gbase, voff) do { _Pragma("unroll") for (int _i = 0; _i < 2; ++_i) \
;         __builtin_amdgcn_global_load_lds((const unsigned*)((const char*)(gbase) + (voff)[_i]), (PG8_LAS unsigned*)(lds + (bufoff) + ldsw + _i * 8192), 16, 0, 0); } while (0)
; #define PG8_LDA(dst, b, h) do { _Pragma("unroll") for (int m = 0; m < 4; ++m) _Pragma("unroll") for (int k = 0; k < 2; ++k) dst[m][k] = *(const PG8_LAS bf16x8*)(lds + PG8_SA(b, h) + aoff + m * 2048 + k * 1024); } while (0)
; #define PG8_LDB(dst, b, h) do { _Pragma("unroll") for (int n = 0; n < 2; ++n) _Pragma("unroll") for (int k = 0; k < 2; ++k) dst[n][k] = *(const PG8_LAS bf16x8*)(lds + PG8_SB(b, h) + boff + n * 2048 + k * 1024); } while (0)
; #define PG8_MMA(ai, bj, At, Bt) do { __builtin_amdgcn_s_setprio(1); _Pragma("unroll") for (int m = 0; m < 4; ++m) _Pragma("unroll") for (int n = 0; n < 2; ++n) _Pragma("unroll") for (int k = 0; k < 2; ++k) \
;         acc[ai][bj][m][n] = mma16<F16>(Bt[n][k], At[m][k], acc[ai][bj][m][n]); __builtin_amdgcn_s_setprio(0); } while (0)
; #define PG8_WAIT_V(n) asm volatile("s_waitcnt vmcnt(" #n ")" ::: "memory")
; template <class Epi, class Sched, bool ALIGN_EPI = false, bool SP2 = false, bool F16 = false>
; __device__ __forceinline__ void gemm_phase(PG8_LAS unsigned char* lds, const Gemm g, const Sched& S, const Epi& E, const int wid_in) {
;     ...
;             PG8_LDB(B0, 0, 0); PG8_LDB(B1, 0, 1); PG8_SCHED; PG8_LDA(At, 0, 0); PG8_STAGE(PG8_SA(1, 1), a1 + hstep, voffA);
;             PG8_WAIT_V(8); PG8_WAIT_L(0); PG8_BAR; PG8_MMA(0, 0, At, B0); PG8_MMA(0, 1, At, B1); PG8_BAR; PG8_SCHED;
;             PG8_LDA(At, 0, 1); PG8_STAGE(PG8_SB(0, 0), b2, voffB); PG8_STAGE(PG8_SB(0, 1), b2 + hstep, voffB); PG8_STAGE(PG8_SA(0, 0), a2, voffA);
;             PG8_WAIT_V(8); PG8_WAIT_L(0); PG8_BAR; PG8_MMA(1, 0, At, B0); PG8_MMA(1, 1, At, B1); PG8_BAR; PG8_SCHED;
;             PG8_LDB(B0, 1, 0); PG8_LDB(B1, 1, 1); PG8_SCHED; PG8_LDA(At, 1, 0); PG8_STAGE(PG8_SA(0, 1), a2 + hstep, voffA);
;             PG8_WAIT_V(8); PG8_WAIT_L(0); PG8_BAR; PG8_MMA(0, 0, At, B0); PG8_MMA(0, 1, At, B1); PG8_BAR; PG8_SCHED;
;             PG8_LDA(At, 1, 1); PG8_STAGE(PG8_SB(1, 0), b3, voffB); PG8_STAGE(PG8_SB(1, 1), b3 + hstep, voffB); PG8_STAGE(PG8_SA(1, 0), a3, voffA);
;             PG8_WAIT_V(8); PG8_WAIT_L(0); PG8_BAR; PG8_MMA(1, 0, At, B0); PG8_MMA(1, 1, At, B1); PG8_BAR; PG8_SCHED;
	v_mfma_f32_16x16x32_bf16 v[60:63], v[128:131], v[176:179], v[60:63]
	v_mfma_f32_16x16x32_bf16 v[56:59], v[136:139], v[176:179], v[56:59]
	v_mfma_f32_16x16x32_bf16 v[44:47], v[128:131], v[192:195], v[44:47]
	v_mfma_f32_16x16x32_bf16 v[40:43], v[136:139], v[192:195], v[40:43]
	v_mfma_f32_16x16x32_bf16 v[28:31], v[128:131], v[200:203], v[28:31]
	v_mfma_f32_16x16x32_bf16 v[24:27], v[136:139], v[200:203], v[24:27]
	v_mfma_f32_16x16x32_bf16 v[12:15], v[128:131], v[208:211], v[12:15]
	v_mfma_f32_16x16x32_bf16 v[8:11], v[136:139], v[208:211], v[8:11]
	v_mfma_f32_16x16x32_bf16 v[60:63], v[132:135], v[180:183], v[60:63]
	v_mfma_f32_16x16x32_bf16 v[56:59], v[140:143], v[180:183], v[56:59]
	v_mfma_f32_16x16x32_bf16 v[44:47], v[132:135], v[196:199], v[44:47]
	v_mfma_f32_16x16x32_bf16 v[40:43], v[140:143], v[196:199], v[40:43]
	v_mfma_f32_16x16x32_bf16 v[28:31], v[132:135], v[204:207], v[28:31]
	v_mfma_f32_16x16x32_bf16 v[24:27], v[140:143], v[204:207], v[24:27]
	v_mfma_f32_16x16x32_bf16 v[12:15], v[132:135], v[212:215], v[12:15]
	v_mfma_f32_16x16x32_bf16 v[8:11], v[140:143], v[212:215], v[8:11]
	v_mfma_f32_16x16x32_bf16 v[52:55], v[144:147], v[176:179], v[52:55]
	v_mfma_f32_16x16x32_bf16 v[48:51], v[168:171], v[176:179], v[48:51]
	v_mfma_f32_16x16x32_bf16 v[36:39], v[144:147], v[192:195], v[36:39]
	v_mfma_f32_16x16x32_bf16 v[32:35], v[168:171], v[192:195], v[32:35]
	v_mfma_f32_16x16x32_bf16 v[20:23], v[144:147], v[200:203], v[20:23]
	v_mfma_f32_16x16x32_bf16 v[16:19], v[168:171], v[200:203], v[16:19]
	v_mfma_f32_16x16x32_bf16 v[4:7], v[144:147], v[208:211], v[4:7]
	v_mfma_f32_16x16x32_bf16 v[0:3], v[168:171], v[208:211], v[0:3]
	v_mfma_f32_16x16x32_bf16 v[52:55], v[148:151], v[180:183], v[52:55]
	v_mfma_f32_16x16x32_bf16 v[48:51], v[172:175], v[180:183], v[48:51]
	v_mfma_f32_16x16x32_bf16 v[36:39], v[148:151], v[196:199], v[36:39]
	v_mfma_f32_16x16x32_bf16 v[32:35], v[172:175], v[196:199], v[32:35]
	v_mfma_f32_16x16x32_bf16 v[20:23], v[148:151], v[204:207], v[20:23]
	v_mfma_f32_16x16x32_bf16 v[16:19], v[172:175], v[204:207], v[16:19]
	v_mfma_f32_16x16x32_bf16 v[4:7], v[148:151], v[212:215], v[4:7]
	v_mfma_f32_16x16x32_bf16 v[0:3], v[172:175], v[212:215], v[0:3]
	s_barrier
	s_add_i32 s56, 0, 0x18000
	s_add_i32 s57, 0, 0x1c000
	v_add_u32_e32 v140, s56, v188
	v_add_u32_e32 v172, s57, v188
	ds_read_b128 v[128:131], v140
	ds_read_b128 v[132:135], v140 offset:1024
	ds_read_b128 v[136:139], v140 offset:2048
	ds_read_b128 v[140:143], v140 offset:3072
	ds_read_b128 v[144:147], v172
	ds_read_b128 v[148:151], v172 offset:1024
	ds_read_b128 v[168:171], v172 offset:2048
	ds_read_b128 v[172:175], v172 offset:3072
	s_add_u32 s28, s36, 0xb0000
	s_addc_u32 s29, s37, 0
	s_mov_b32 m0, s90
	v_lshl_add_u64 v[222:223], s[28:29], 0, v[152:153]
	ds_read_b128 v[176:179], v191 offset:32768
	ds_read_b128 v[180:183], v191 offset:33792
	ds_read_b128 v[192:195], v191 offset:34816
	ds_read_b128 v[196:199], v191 offset:35840
	ds_read_b128 v[200:203], v191 offset:36864
	ds_read_b128 v[204:207], v191 offset:37888
	ds_read_b128 v[208:211], v191 offset:38912
	ds_read_b128 v[212:215], v191 offset:39936
	global_load_lds_dwordx4 v[222:223], off
	v_lshl_add_u64 v[222:223], s[28:29], 0, v[156:157]
	s_mov_b32 m0, s43
	s_nop 0
	global_load_lds_dwordx4 v[222:223], off
	s_waitcnt vmcnt(8)
	s_waitcnt lgkmcnt(0)
	s_barrier
	v_mfma_f32_16x16x32_bf16 v[124:127], v[128:131], v[176:179], v[124:127]
	v_mfma_f32_16x16x32_bf16 v[120:123], v[136:139], v[176:179], v[120:123]
	v_mfma_f32_16x16x32_bf16 v[108:111], v[128:131], v[192:195], v[108:111]
	v_mfma_f32_16x16x32_bf16 v[104:107], v[136:139], v[192:195], v[104:107]
	v_mfma_f32_16x16x32_bf16 v[92:95], v[128:131], v[200:203], v[92:95]
	v_mfma_f32_16x16x32_bf16 v[88:91], v[136:139], v[200:203], v[88:91]
	v_mfma_f32_16x16x32_bf16 v[76:79], v[128:131], v[208:211], v[76:79]
	v_mfma_f32_16x16x32_bf16 v[72:75], v[136:139], v[208:211], v[72:75]
	v_mfma_f32_16x16x32_bf16 v[124:127], v[132:135], v[180:183], v[124:127]
	v_mfma_f32_16x16x32_bf16 v[120:123], v[140:143], v[180:183], v[120:123]
	v_mfma_f32_16x16x32_bf16 v[108:111], v[132:135], v[196:199], v[108:111]
	v_mfma_f32_16x16x32_bf16 v[104:107], v[140:143], v[196:199], v[104:107]
	v_mfma_f32_16x16x32_bf16 v[92:95], v[132:135], v[204:207], v[92:95]
	v_mfma_f32_16x16x32_bf16 v[88:91], v[140:143], v[204:207], v[88:91]
	v_mfma_f32_16x16x32_bf16 v[76:79], v[132:135], v[212:215], v[76:79]
	v_mfma_f32_16x16x32_bf16 v[72:75], v[140:143], v[212:215], v[72:75]
	v_mfma_f32_16x16x32_bf16 v[116:119], v[144:147], v[176:179], v[116:119]
	v_mfma_f32_16x16x32_bf16 v[112:115], v[168:171], v[176:179], v[112:115]
	v_mfma_f32_16x16x32_bf16 v[100:103], v[144:147], v[192:195], v[100:103]
	v_mfma_f32_16x16x32_bf16 v[96:99], v[168:171], v[192:195], v[96:99]
	v_mfma_f32_16x16x32_bf16 v[84:87], v[144:147], v[200:203], v[84:87]
	v_mfma_f32_16x16x32_bf16 v[80:83], v[168:171], v[200:203], v[80:83]
	v_mfma_f32_16x16x32_bf16 v[68:71], v[144:147], v[208:211], v[68:71]
	v_mfma_f32_16x16x32_bf16 v[64:67], v[168:171], v[208:211], v[64:67]
	v_mfma_f32_16x16x32_bf16 v[116:119], v[148:151], v[180:183], v[116:119]
	v_mfma_f32_16x16x32_bf16 v[112:115], v[172:175], v[180:183], v[112:115]
	v_mfma_f32_16x16x32_bf16 v[100:103], v[148:151], v[196:199], v[100:103]
	v_mfma_f32_16x16x32_bf16 v[96:99], v[172:175], v[196:199], v[96:99]
	v_mfma_f32_16x16x32_bf16 v[84:87], v[148:151], v[204:207], v[84:87]
	v_mfma_f32_16x16x32_bf16 v[80:83], v[172:175], v[204:207], v[80:83]
	v_mfma_f32_16x16x32_bf16 v[68:71], v[148:151], v[212:215], v[68:71]
	v_mfma_f32_16x16x32_bf16 v[64:67], v[172:175], v[212:215], v[64:67]
	s_barrier
; #define PG8_STAGE(bufoff, gbase, voff) do { _Pragma("unroll") for (int _i = 0; _i < 2; ++_i) \
;         __builtin_amdgcn_global_load_lds((const unsigned*)((const char*)(gbase) + (voff)[_i]), (PG8_LAS unsigned*)(lds + (bufoff) + ldsw + _i * 8192), 16, 0, 0); } while (0)
; #define PG8_LDA(dst, b, h) do { _Pragma("unroll") for (int m = 0; m < 4; ++m) _Pragma("unroll") for (int k = 0; k < 2; ++k) dst[m][k] = *(const PG8_LAS bf16x8*)(lds + PG8_SA(b, h) + aoff + m * 2048 + k * 1024); } while (0)
; #define PG8_LDB(dst, b, h) do { _Pragma("unroll") for (int n = 0; n < 2; ++n) _Pragma("unroll") for (int k = 0; k < 2; ++k) dst[n][k] = *(const PG8_LAS bf16x8*)(lds + PG8_SB(b, h) + boff + n * 2048 + k * 1024); } while (0)
; #define PG8_MMA(ai, bj, At, Bt) do { __builtin_amdgcn_s_setprio(1); _Pragma("unroll") for (int m = 0; m < 4; ++m) _Pragma("unroll") for (int n = 0; n < 2; ++n) _Pragma("unroll") for (int k = 0; k < 2; ++k) \
;         acc[ai][bj][m][n] = mma16<F16>(Bt[n][k], At[m][k], acc[ai][bj][m][n]); __builtin_amdgcn_s_setprio(0); } while (0)
; template <class Epi, class Sched, bool ALIGN_EPI = false, bool SP2 = false, bool F16 = false>
; __device__ __forceinline__ void gemm_phase(PG8_LAS unsigned char* lds, const Gemm g, const Sched& S, const Epi& E, const int wid_in) {
;     ...
;         for (int t = 0; t < nt; t += 2) {
;     ...
;             PG8_LDB(B0, 0, 0); PG8_LDB(B1, 0, 1); PG8_SCHED; PG8_LDA(At, 0, 0); PG8_STAGE(PG8_SA(1, 1), a1 + hstep, voffA);
;             PG8_WAIT_V(8); PG8_WAIT_L(0); PG8_BAR; PG8_MMA(0, 0, At, B0); PG8_MMA(0, 1, At, B1); PG8_BAR; PG8_SCHED;
;             PG8_LDA(At, 0, 1); PG8_STAGE(PG8_SB(0, 0), b2, voffB); PG8_STAGE(PG8_SB(0, 1), b2 + hstep, voffB); PG8_STAGE(PG8_SA(0, 0), a2, voffA);
;             PG8_WAIT_V(8); PG8_WAIT_L(0); PG8_BAR; PG8_MMA(1, 0, At, B0); PG8_MMA(1, 1, At, B1); PG8_BAR; PG8_SCHED;
;             PG8_LDB(B0, 1, 0); PG8_LDB(B1, 1, 1); PG8_SCHED; PG8_LDA(At, 1, 0); PG8_STAGE(PG8_SA(0, 1), a2 + hstep, voffA);
;             PG8_WAIT_V(8); PG8_WAIT_L(0); PG8_BAR; PG8_MMA(0, 0, At, B0); PG8_MMA(0, 1, At, B1); PG8_BAR; PG8_SCHED;
;             PG8_LDA(At, 1, 1); PG8_STAGE(PG8_SB(1, 0), b3, voffB); PG8_STAGE(PG8_SB(1, 1), b3 + hstep, voffB); PG8_STAGE(PG8_SA(1, 0), a3, voffA);
;             PG8_WAIT_V(8); PG8_WAIT_L(0); PG8_BAR; PG8_MMA(1, 0, At, B0); PG8_MMA(1, 1, At, B1); PG8_BAR; PG8_SCHED;
	s_add_i32 s28, s56, s68
	v_lshl_add_u64 v[184:185], v[184:185], 0, s[24:25]
	s_mov_b32 m0, s28
	ds_read_b128 v[176:179], v191 offset:49152
	ds_read_b128 v[180:183], v191 offset:50176
	ds_read_b128 v[192:195], v191 offset:51200
	ds_read_b128 v[196:199], v191 offset:52224
	ds_read_b128 v[200:203], v191 offset:53248
	ds_read_b128 v[204:207], v191 offset:54272
	ds_read_b128 v[208:211], v191 offset:55296
	ds_read_b128 v[212:215], v191 offset:56320
	global_load_lds_dwordx4 v[184:185], off
	s_add_i32 m0, s28, 0x2000
	s_add_u32 s28, s34, 0xb0080
	v_lshl_add_u64 v[184:185], v[216:217], 0, s[24:25]
	s_addc_u32 s29, s35, 0
	s_add_i32 s34, s57, s68
	global_load_lds_dwordx4 v[184:185], off
	v_lshl_add_u64 v[184:185], s[28:29], 0, v[154:155]
	s_mov_b32 m0, s34
	s_nop 0
	global_load_lds_dwordx4 v[184:185], off
	v_lshl_add_u64 v[184:185], s[28:29], 0, v[158:159]
	s_add_i32 m0, s34, 0x2000
	s_nop 0
	global_load_lds_dwordx4 v[184:185], off
	v_lshl_add_u64 v[184:185], v[218:219], 0, s[24:25]
	s_mov_b32 m0, s75
	s_nop 0
	global_load_lds_dwordx4 v[184:185], off
	v_lshl_add_u64 v[184:185], v[220:221], 0, s[24:25]
	s_mov_b32 m0, s67
	s_nop 0
	global_load_lds_dwordx4 v[184:185], off
	s_waitcnt vmcnt(8)
	s_waitcnt lgkmcnt(0)
	s_barrier
	v_mfma_f32_16x16x32_bf16 v[60:63], v[128:131], v[176:179], v[60:63]
	v_mfma_f32_16x16x32_bf16 v[56:59], v[136:139], v[176:179], v[56:59]
	v_mfma_f32_16x16x32_bf16 v[44:47], v[128:131], v[192:195], v[44:47]
	v_mfma_f32_16x16x32_bf16 v[40:43], v[136:139], v[192:195], v[40:43]
	v_mfma_f32_16x16x32_bf16 v[28:31], v[128:131], v[200:203], v[28:31]
	v_mfma_f32_16x16x32_bf16 v[24:27], v[136:139], v[200:203], v[24:27]
	v_mfma_f32_16x16x32_bf16 v[12:15], v[128:131], v[208:211], v[12:15]
	v_mfma_f32_16x16x32_bf16 v[8:11], v[136:139], v[208:211], v[8:11]
	v_mfma_f32_16x16x32_bf16 v[60:63], v[132:135], v[180:183], v[60:63]
	v_mfma_f32_16x16x32_bf16 v[56:59], v[140:143], v[180:183], v[56:59]
	v_mfma_f32_16x16x32_bf16 v[44:47], v[132:135], v[196:199], v[44:47]
	v_mfma_f32_16x16x32_bf16 v[40:43], v[140:143], v[196:199], v[40:43]
	v_mfma_f32_16x16x32_bf16 v[28:31], v[132:135], v[204:207], v[28:31]
	v_mfma_f32_16x16x32_bf16 v[24:27], v[140:143], v[204:207], v[24:27]
	v_mfma_f32_16x16x32_bf16 v[12:15], v[132:135], v[212:215], v[12:15]
	v_mfma_f32_16x16x32_bf16 v[8:11], v[140:143], v[212:215], v[8:11]
	v_mfma_f32_16x16x32_bf16 v[52:55], v[144:147], v[176:179], v[52:55]
	v_mfma_f32_16x16x32_bf16 v[48:51], v[168:171], v[176:179], v[48:51]
	v_mfma_f32_16x16x32_bf16 v[36:39], v[144:147], v[192:195], v[36:39]
	v_mfma_f32_16x16x32_bf16 v[32:35], v[168:171], v[192:195], v[32:35]
	v_mfma_f32_16x16x32_bf16 v[20:23], v[144:147], v[200:203], v[20:23]
	v_mfma_f32_16x16x32_bf16 v[16:19], v[168:171], v[200:203], v[16:19]
	v_mfma_f32_16x16x32_bf16 v[4:7], v[144:147], v[208:211], v[4:7]
	v_mfma_f32_16x16x32_bf16 v[0:3], v[168:171], v[208:211], v[0:3]
	v_mfma_f32_16x16x32_bf16 v[52:55], v[148:151], v[180:183], v[52:55]
	v_mfma_f32_16x16x32_bf16 v[48:51], v[172:175], v[180:183], v[48:51]
	v_mfma_f32_16x16x32_bf16 v[36:39], v[148:151], v[196:199], v[36:39]
	v_mfma_f32_16x16x32_bf16 v[32:35], v[172:175], v[196:199], v[32:35]
	v_mfma_f32_16x16x32_bf16 v[20:23], v[148:151], v[204:207], v[20:23]
	v_mfma_f32_16x16x32_bf16 v[16:19], v[172:175], v[204:207], v[16:19]
	v_mfma_f32_16x16x32_bf16 v[4:7], v[148:151], v[212:215], v[4:7]
	v_mfma_f32_16x16x32_bf16 v[0:3], v[172:175], v[212:215], v[0:3]
	s_barrier
	s_add_i32 s55, s55, 2
	s_add_u32 s53, s53, 0x100
	s_addc_u32 s54, s54, 0
	s_cmp_gt_u32 s55, 41
	s_mov_b64 s[28:29], s[30:31]
	s_cbranch_scc0 .LBB0_2697
	s_and_b64 vcc, exec, s[16:17]
	s_cbranch_vccz .LBB0_2700
	s_barrier

; #define PG8_STAGE(bufoff, gbase, voff) do { _Pragma("unroll") for (int _i = 0; _i < 2; ++_i) \
;         __builtin_amdgcn_global_load_lds((const unsigned*)((const char*)(gbase) + (voff)[_i]), (PG8_LAS unsigned*)(lds + (bufoff) + ldsw + _i * 8192), 16, 0, 0); } while (0)
; #define PG8_LDA(dst, b, h) do { _Pragma("unroll") for (int m = 0; m < 4; ++m) _Pragma("unroll") for (int k = 0; k < 2; ++k) dst[m][k] = *(const PG8_LAS bf16x8*)(lds + PG8_SA(b, h) + aoff + m * 2048 + k * 1024); } while (0)
; #define PG8_WAIT_V(n) asm volatile("s_waitcnt vmcnt(" #n ")" ::: "memory")
; #define PG8_WAIT_L(n) asm volatile("s_waitcnt lgkmcnt(" #n ")" ::: "memory")
; template <class Epi, class Sched, bool ALIGN_EPI = false, bool SP2 = false, bool F16 = false>
; __device__ __forceinline__ void gemm_phase(PG8_LAS unsigned char* lds, const Gemm g, const Sched& S, const Epi& E, const int wid_in) {
;     ...
;         for (int t = 0; t < nt; t += 2) {
;             const bool last = (t == nt - 2);
;             const char* a1 = cA + (size_t)(t + 1) * kstep;
;             const char* a2 = last ? nA : cA + (size_t)(t + 2) * kstep; const char* b2 = last ? nB : cB + (size_t)(t + 2) * kstep;
;             const char* a3 = a2 + kstep; const char* b3 = b2 + kstep;
;             if (last && has_next) S.a_ready(nxt);
;             if constexpr (SP2) {
;             PG8_LDB(B0, 0, 0); PG8_LDB(B1, 0, 1); PG8_SCHED; PG8_LDA(At, 0, 0); PG8_STAGE(PG8_SA(1, 1), a1 + hstep, voffA);
;             PG8_WAIT_V(8); PG8_WAIT_L(0); PG8_BAR; PG8_MMA(0, 0, At, B0); PG8_MMA(0, 1, At, B1); PG8_BAR; PG8_SCHED;
;             PG8_LDA(At, 0, 1); PG8_STAGE(PG8_SB(0, 0), b2, voffB); PG8_STAGE(PG8_SB(0, 1), b2 + hstep, voffB); PG8_STAGE(PG8_SA(0, 0), a2, voffA);
;             PG8_WAIT_V(8); PG8_WAIT_L(0); PG8_BAR; PG8_MMA(1, 0, At, B0); PG8_MMA(1, 1, At, B1); PG8_BAR; PG8_SCHED;
;             PG8_LDB(B0, 1, 0); PG8_LDB(B1, 1, 1); PG8_SCHED; PG8_LDA(At, 1, 0); PG8_STAGE(PG8_SA(0, 1), a2 + hstep, voffA);
;             PG8_WAIT_V(8); PG8_WAIT_L(0); PG8_BAR; PG8_MMA(0, 0, At, B0); PG8_MMA(0, 1, At, B1); PG8_BAR; PG8_SCHED;
;             PG8_LDA(At, 1, 1); PG8_STAGE(PG8_SB(1, 0), b3, voffB); PG8_STAGE(PG8_SB(1, 1), b3 + hstep, voffB); PG8_STAGE(PG8_SA(1, 0), a3, voffA);
;             PG8_WAIT_V(8); PG8_WAIT_L(0); PG8_BAR; PG8_MMA(1, 0, At, B0); PG8_MMA(1, 1, At, B1); PG8_BAR; PG8_SCHED;
.LBB0_2793:
	ds_read_b128 v[112:115], v235
	ds_read_b128 v[116:119], v235 offset:1024
	ds_read_b128 v[128:131], v235 offset:2048
	ds_read_b128 v[132:135], v235 offset:3072
	ds_read_b128 v[144:147], v236
	ds_read_b128 v[148:151], v236 offset:1024
	ds_read_b128 v[152:155], v236 offset:2048
	ds_read_b128 v[156:159], v236 offset:3072
	s_add_u32 s44, s42, 0xfffc0080
	s_addc_u32 s45, s43, -1
	s_cmp_eq_u32 s59, 12
	s_cselect_b32 s47, s14, s45
	s_cselect_b32 s46, s15, s44
	s_cselect_b32 s45, s29, s58
	s_cselect_b32 s44, s31, s41
	s_mov_b32 m0, s91
	v_lshl_add_u64 v[192:193], s[42:43], 0, v[204:205]
	ds_read_b128 v[160:163], v237
	ds_read_b128 v[164:167], v237 offset:1024
	ds_read_b128 v[168:171], v237 offset:2048
	ds_read_b128 v[172:175], v237 offset:3072
	ds_read_b128 v[176:179], v237 offset:4096
	ds_read_b128 v[180:183], v237 offset:5120
	ds_read_b128 v[184:187], v237 offset:6144
	ds_read_b128 v[188:191], v237 offset:7168
	global_load_lds_dwordx4 v[192:193], off
	v_lshl_add_u64 v[192:193], s[42:43], 0, v[206:207]
	s_add_i32 m0, s74, 0xe000
	s_nop 0
	global_load_lds_dwordx4 v[192:193], off
	s_waitcnt vmcnt(8)
	s_waitcnt lgkmcnt(0)
	s_barrier
	v_mfma_f32_16x16x32_f16 v[140:143], v[112:115], v[160:163], v[140:143]
	v_mfma_f32_16x16x32_f16 v[136:139], v[128:131], v[160:163], v[136:139]
	v_mfma_f32_16x16x32_f16 v[108:111], v[112:115], v[168:171], v[108:111]
	v_mfma_f32_16x16x32_f16 v[104:107], v[128:131], v[168:171], v[104:107]
	v_mfma_f32_16x16x32_f16 v[92:95], v[112:115], v[176:179], v[92:95]
	v_mfma_f32_16x16x32_f16 v[88:91], v[128:131], v[176:179], v[88:91]
	v_mfma_f32_16x16x32_f16 v[76:79], v[112:115], v[184:187], v[76:79]
	v_mfma_f32_16x16x32_f16 v[72:75], v[128:131], v[184:187], v[72:75]
	v_mfma_f32_16x16x32_f16 v[140:143], v[116:119], v[164:167], v[140:143]
	v_mfma_f32_16x16x32_f16 v[136:139], v[132:135], v[164:167], v[136:139]
	v_mfma_f32_16x16x32_f16 v[108:111], v[116:119], v[172:175], v[108:111]
	v_mfma_f32_16x16x32_f16 v[104:107], v[132:135], v[172:175], v[104:107]
	v_mfma_f32_16x16x32_f16 v[92:95], v[116:119], v[180:183], v[92:95]
	v_mfma_f32_16x16x32_f16 v[88:91], v[132:135], v[180:183], v[88:91]
	v_mfma_f32_16x16x32_f16 v[76:79], v[116:119], v[188:191], v[76:79]
	v_mfma_f32_16x16x32_f16 v[72:75], v[132:135], v[188:191], v[72:75]
	v_mfma_f32_16x16x32_f16 v[124:127], v[144:147], v[160:163], v[124:127]
	v_mfma_f32_16x16x32_f16 v[120:123], v[152:155], v[160:163], v[120:123]
	v_mfma_f32_16x16x32_f16 v[100:103], v[144:147], v[168:171], v[100:103]
	v_mfma_f32_16x16x32_f16 v[96:99], v[152:155], v[168:171], v[96:99]
	v_mfma_f32_16x16x32_f16 v[84:87], v[144:147], v[176:179], v[84:87]
	v_mfma_f32_16x16x32_f16 v[80:83], v[152:155], v[176:179], v[80:83]
	v_mfma_f32_16x16x32_f16 v[68:71], v[144:147], v[184:187], v[68:71]
	v_mfma_f32_16x16x32_f16 v[64:67], v[152:155], v[184:187], v[64:67]
	v_mfma_f32_16x16x32_f16 v[124:127], v[148:151], v[164:167], v[124:127]
	v_mfma_f32_16x16x32_f16 v[120:123], v[156:159], v[164:167], v[120:123]
	v_mfma_f32_16x16x32_f16 v[100:103], v[148:151], v[172:175], v[100:103]
	v_mfma_f32_16x16x32_f16 v[96:99], v[156:159], v[172:175], v[96:99]
	v_mfma_f32_16x16x32_f16 v[84:87], v[148:151], v[180:183], v[84:87]
	v_mfma_f32_16x16x32_f16 v[80:83], v[156:159], v[180:183], v[80:83]
	v_mfma_f32_16x16x32_f16 v[68:71], v[148:151], v[188:191], v[68:71]
	v_mfma_f32_16x16x32_f16 v[64:67], v[156:159], v[188:191], v[64:67]
	s_barrier
	s_add_i32 s60, s55, s68
	v_lshl_add_u64 v[192:193], s[44:45], 0, v[198:199]
	s_mov_b32 m0, s60
	ds_read_b128 v[160:163], v237 offset:16384
	ds_read_b128 v[164:167], v237 offset:17408
	ds_read_b128 v[168:171], v237 offset:18432
	ds_read_b128 v[172:175], v237 offset:19456
	ds_read_b128 v[176:179], v237 offset:20480
	ds_read_b128 v[180:183], v237 offset:21504
	ds_read_b128 v[184:187], v237 offset:22528
	ds_read_b128 v[188:191], v237 offset:23552
	global_load_lds_dwordx4 v[192:193], off
	s_add_i32 m0, s60, 0x2000
	s_add_u32 s60, s44, 0x40000
	v_lshl_add_u64 v[194:195], s[44:45], 0, v[202:203]
	s_addc_u32 s61, s45, 0
	s_add_i32 s62, s56, s68
	global_load_lds_dwordx4 v[194:195], off
	v_lshl_add_u64 v[212:213], s[60:61], 0, v[198:199]
	s_mov_b32 m0, s62
	v_lshl_add_u64 v[214:215], s[46:47], 0, v[200:201]
	global_load_lds_dwordx4 v[212:213], off
	v_lshl_add_u64 v[212:213], s[60:61], 0, v[202:203]
	s_add_i32 m0, s62, 0x2000
	s_nop 0
	global_load_lds_dwordx4 v[212:213], off
	v_lshl_add_u64 v[212:213], s[46:47], 0, v[196:197]
	s_mov_b32 m0, s74
	s_nop 0
	global_load_lds_dwordx4 v[212:213], off
	s_mov_b32 m0, s66
	s_nop 0
	global_load_lds_dwordx4 v[214:215], off
	s_waitcnt vmcnt(8)
	s_waitcnt lgkmcnt(0)
	s_barrier
; #define PG8_STAGE(bufoff, gbase, voff) do { _Pragma("unroll") for (int _i = 0; _i < 2; ++_i) \
;         __builtin_amdgcn_global_load_lds((const unsigned*)((const char*)(gbase) + (voff)[_i]), (PG8_LAS unsigned*)(lds + (bufoff) + ldsw + _i * 8192), 16, 0, 0); } while (0)
; #define PG8_LDA(dst, b, h) do { _Pragma("unroll") for (int m = 0; m < 4; ++m) _Pragma("unroll") for (int k = 0; k < 2; ++k) dst[m][k] = *(const PG8_LAS bf16x8*)(lds + PG8_SA(b, h) + aoff + m * 2048 + k * 1024); } while (0)
; #define PG8_LDB(dst, b, h) do { _Pragma("unroll") for (int n = 0; n < 2; ++n) _Pragma("unroll") for (int k = 0; k < 2; ++k) dst[n][k] = *(const PG8_LAS bf16x8*)(lds + PG8_SB(b, h) + boff + n * 2048 + k * 1024); } while (0)
; #define PG8_MMA(ai, bj, At, Bt) do { __builtin_amdgcn_s_setprio(1); _Pragma("unroll") for (int m = 0; m < 4; ++m) _Pragma("unroll") for (int n = 0; n < 2; ++n) _Pragma("unroll") for (int k = 0; k < 2; ++k) \
;         acc[ai][bj][m][n] = mma16<F16>(Bt[n][k], At[m][k], acc[ai][bj][m][n]); __builtin_amdgcn_s_setprio(0); } while (0)
; #define PG8_WAIT_V(n) asm volatile("s_waitcnt vmcnt(" #n ")" ::: "memory")
; template <class Epi, class Sched, bool ALIGN_EPI = false, bool SP2 = false, bool F16 = false>
; __device__ __forceinline__ void gemm_phase(PG8_LAS unsigned char* lds, const Gemm g, const Sched& S, const Epi& E, const int wid_in) {
;     ...
;             PG8_LDB(B0, 0, 0); PG8_LDB(B1, 0, 1); PG8_SCHED; PG8_LDA(At, 0, 0); PG8_STAGE(PG8_SA(1, 1), a1 + hstep, voffA);
;             PG8_WAIT_V(8); PG8_WAIT_L(0); PG8_BAR; PG8_MMA(0, 0, At, B0); PG8_MMA(0, 1, At, B1); PG8_BAR; PG8_SCHED;
;             PG8_LDA(At, 0, 1); PG8_STAGE(PG8_SB(0, 0), b2, voffB); PG8_STAGE(PG8_SB(0, 1), b2 + hstep, voffB); PG8_STAGE(PG8_SA(0, 0), a2, voffA);
;             PG8_WAIT_V(8); PG8_WAIT_L(0); PG8_BAR; PG8_MMA(1, 0, At, B0); PG8_MMA(1, 1, At, B1); PG8_BAR; PG8_SCHED;
;             PG8_LDB(B0, 1, 0); PG8_LDB(B1, 1, 1); PG8_SCHED; PG8_LDA(At, 1, 0); PG8_STAGE(PG8_SA(0, 1), a2 + hstep, voffA);
;             PG8_WAIT_V(8); PG8_WAIT_L(0); PG8_BAR; PG8_MMA(0, 0, At, B0); PG8_MMA(0, 1, At, B1); PG8_BAR; PG8_SCHED;
;             PG8_LDA(At, 1, 1); PG8_STAGE(PG8_SB(1, 0), b3, voffB); PG8_STAGE(PG8_SB(1, 1), b3 + hstep, voffB); PG8_STAGE(PG8_SA(1, 0), a3, voffA);
;             PG8_WAIT_V(8); PG8_WAIT_L(0); PG8_BAR; PG8_MMA(1, 0, At, B0); PG8_MMA(1, 1, At, B1); PG8_BAR; PG8_SCHED;
	v_mfma_f32_16x16x32_f16 v[60:63], v[112:115], v[160:163], v[60:63]
	v_mfma_f32_16x16x32_f16 v[56:59], v[128:131], v[160:163], v[56:59]
	v_mfma_f32_16x16x32_f16 v[44:47], v[112:115], v[168:171], v[44:47]
	v_mfma_f32_16x16x32_f16 v[40:43], v[128:131], v[168:171], v[40:43]
	v_mfma_f32_16x16x32_f16 v[28:31], v[112:115], v[176:179], v[28:31]
	v_mfma_f32_16x16x32_f16 v[24:27], v[128:131], v[176:179], v[24:27]
	v_mfma_f32_16x16x32_f16 v[12:15], v[112:115], v[184:187], v[12:15]
	v_mfma_f32_16x16x32_f16 v[8:11], v[128:131], v[184:187], v[8:11]
	v_mfma_f32_16x16x32_f16 v[60:63], v[116:119], v[164:167], v[60:63]
	v_mfma_f32_16x16x32_f16 v[56:59], v[132:135], v[164:167], v[56:59]
	v_mfma_f32_16x16x32_f16 v[44:47], v[116:119], v[172:175], v[44:47]
	v_mfma_f32_16x16x32_f16 v[40:43], v[132:135], v[172:175], v[40:43]
	v_mfma_f32_16x16x32_f16 v[28:31], v[116:119], v[180:183], v[28:31]
	v_mfma_f32_16x16x32_f16 v[24:27], v[132:135], v[180:183], v[24:27]
	v_mfma_f32_16x16x32_f16 v[12:15], v[116:119], v[188:191], v[12:15]
	v_mfma_f32_16x16x32_f16 v[8:11], v[132:135], v[188:191], v[8:11]
	v_mfma_f32_16x16x32_f16 v[52:55], v[144:147], v[160:163], v[52:55]
	v_mfma_f32_16x16x32_f16 v[48:51], v[152:155], v[160:163], v[48:51]
	v_mfma_f32_16x16x32_f16 v[36:39], v[144:147], v[168:171], v[36:39]
	v_mfma_f32_16x16x32_f16 v[32:35], v[152:155], v[168:171], v[32:35]
	v_mfma_f32_16x16x32_f16 v[20:23], v[144:147], v[176:179], v[20:23]
	v_mfma_f32_16x16x32_f16 v[16:19], v[152:155], v[176:179], v[16:19]
	v_mfma_f32_16x16x32_f16 v[4:7], v[144:147], v[184:187], v[4:7]
	v_mfma_f32_16x16x32_f16 v[0:3], v[152:155], v[184:187], v[0:3]
	v_mfma_f32_16x16x32_f16 v[52:55], v[148:151], v[164:167], v[52:55]
	v_mfma_f32_16x16x32_f16 v[48:51], v[156:159], v[164:167], v[48:51]
	v_mfma_f32_16x16x32_f16 v[36:39], v[148:151], v[172:175], v[36:39]
	v_mfma_f32_16x16x32_f16 v[32:35], v[156:159], v[172:175], v[32:35]
	v_mfma_f32_16x16x32_f16 v[20:23], v[148:151], v[180:183], v[20:23]
	v_mfma_f32_16x16x32_f16 v[16:19], v[156:159], v[180:183], v[16:19]
	v_mfma_f32_16x16x32_f16 v[4:7], v[148:151], v[188:191], v[4:7]
	v_mfma_f32_16x16x32_f16 v[0:3], v[156:159], v[188:191], v[0:3]
	s_barrier
	s_add_i32 s60, 0, 0x18000
	s_add_i32 s61, 0, 0x1c000
	v_add_u32_e32 v132, s60, v234
	v_add_u32_e32 v156, s61, v234
	ds_read_b128 v[112:115], v132
	ds_read_b128 v[116:119], v132 offset:1024
	ds_read_b128 v[128:131], v132 offset:2048
	ds_read_b128 v[132:135], v132 offset:3072
	ds_read_b128 v[144:147], v156
	ds_read_b128 v[148:151], v156 offset:1024
	ds_read_b128 v[152:155], v156 offset:2048
	ds_read_b128 v[156:159], v156 offset:3072
	s_add_u32 s46, s46, 0x40000
	s_addc_u32 s47, s47, 0
	s_mov_b32 m0, s90
	v_lshl_add_u64 v[216:217], s[46:47], 0, v[196:197]
	ds_read_b128 v[160:163], v237 offset:32768
	ds_read_b128 v[164:167], v237 offset:33792
	ds_read_b128 v[168:171], v237 offset:34816
	ds_read_b128 v[172:175], v237 offset:35840
	ds_read_b128 v[176:179], v237 offset:36864
	ds_read_b128 v[180:183], v237 offset:37888
	ds_read_b128 v[184:187], v237 offset:38912
	ds_read_b128 v[188:191], v237 offset:39936
	global_load_lds_dwordx4 v[216:217], off
	v_lshl_add_u64 v[216:217], s[46:47], 0, v[200:201]
	s_mov_b32 m0, s51
	s_nop 0
	global_load_lds_dwordx4 v[216:217], off
	s_waitcnt vmcnt(8)
	s_waitcnt lgkmcnt(0)
	s_barrier
	v_mfma_f32_16x16x32_f16 v[140:143], v[112:115], v[160:163], v[140:143]
	v_mfma_f32_16x16x32_f16 v[136:139], v[128:131], v[160:163], v[136:139]
	v_mfma_f32_16x16x32_f16 v[108:111], v[112:115], v[168:171], v[108:111]
	v_mfma_f32_16x16x32_f16 v[104:107], v[128:131], v[168:171], v[104:107]
	v_mfma_f32_16x16x32_f16 v[92:95], v[112:115], v[176:179], v[92:95]
	v_mfma_f32_16x16x32_f16 v[88:91], v[128:131], v[176:179], v[88:91]
	v_mfma_f32_16x16x32_f16 v[76:79], v[112:115], v[184:187], v[76:79]
	v_mfma_f32_16x16x32_f16 v[72:75], v[128:131], v[184:187], v[72:75]
	v_mfma_f32_16x16x32_f16 v[140:143], v[116:119], v[164:167], v[140:143]
	v_mfma_f32_16x16x32_f16 v[136:139], v[132:135], v[164:167], v[136:139]
	v_mfma_f32_16x16x32_f16 v[108:111], v[116:119], v[172:175], v[108:111]
	v_mfma_f32_16x16x32_f16 v[104:107], v[132:135], v[172:175], v[104:107]
	v_mfma_f32_16x16x32_f16 v[92:95], v[116:119], v[180:183], v[92:95]
	v_mfma_f32_16x16x32_f16 v[88:91], v[132:135], v[180:183], v[88:91]
	v_mfma_f32_16x16x32_f16 v[76:79], v[116:119], v[188:191], v[76:79]
	v_mfma_f32_16x16x32_f16 v[72:75], v[132:135], v[188:191], v[72:75]
	v_mfma_f32_16x16x32_f16 v[124:127], v[144:147], v[160:163], v[124:127]
	v_mfma_f32_16x16x32_f16 v[120:123], v[152:155], v[160:163], v[120:123]
	v_mfma_f32_16x16x32_f16 v[100:103], v[144:147], v[168:171], v[100:103]
	v_mfma_f32_16x16x32_f16 v[96:99], v[152:155], v[168:171], v[96:99]
	v_mfma_f32_16x16x32_f16 v[84:87], v[144:147], v[176:179], v[84:87]
	v_mfma_f32_16x16x32_f16 v[80:83], v[152:155], v[176:179], v[80:83]
	v_mfma_f32_16x16x32_f16 v[68:71], v[144:147], v[184:187], v[68:71]
	v_mfma_f32_16x16x32_f16 v[64:67], v[152:155], v[184:187], v[64:67]
	v_mfma_f32_16x16x32_f16 v[124:127], v[148:151], v[164:167], v[124:127]
	v_mfma_f32_16x16x32_f16 v[120:123], v[156:159], v[164:167], v[120:123]
	v_mfma_f32_16x16x32_f16 v[100:103], v[148:151], v[172:175], v[100:103]
	v_mfma_f32_16x16x32_f16 v[96:99], v[156:159], v[172:175], v[96:99]
	v_mfma_f32_16x16x32_f16 v[84:87], v[148:151], v[180:183], v[84:87]
	v_mfma_f32_16x16x32_f16 v[80:83], v[156:159], v[180:183], v[80:83]
	v_mfma_f32_16x16x32_f16 v[68:71], v[148:151], v[188:191], v[68:71]
	v_mfma_f32_16x16x32_f16 v[64:67], v[156:159], v[188:191], v[64:67]
	s_barrier
; #define PG8_STAGE(bufoff, gbase, voff) do { _Pragma("unroll") for (int _i = 0; _i < 2; ++_i) \
;         __builtin_amdgcn_global_load_lds((const unsigned*)((const char*)(gbase) + (voff)[_i]), (PG8_LAS unsigned*)(lds + (bufoff) + ldsw + _i * 8192), 16, 0, 0); } while (0)
; #define PG8_LDA(dst, b, h) do { _Pragma("unroll") for (int m = 0; m < 4; ++m) _Pragma("unroll") for (int k = 0; k < 2; ++k) dst[m][k] = *(const PG8_LAS bf16x8*)(lds + PG8_SA(b, h) + aoff + m * 2048 + k * 1024); } while (0)
; #define PG8_LDB(dst, b, h) do { _Pragma("unroll") for (int n = 0; n < 2; ++n) _Pragma("unroll") for (int k = 0; k < 2; ++k) dst[n][k] = *(const PG8_LAS bf16x8*)(lds + PG8_SB(b, h) + boff + n * 2048 + k * 1024); } while (0)
; #define PG8_MMA(ai, bj, At, Bt) do { __builtin_amdgcn_s_setprio(1); _Pragma("unroll") for (int m = 0; m < 4; ++m) _Pragma("unroll") for (int n = 0; n < 2; ++n) _Pragma("unroll") for (int k = 0; k < 2; ++k) \
;         acc[ai][bj][m][n] = mma16<F16>(Bt[n][k], At[m][k], acc[ai][bj][m][n]); __builtin_amdgcn_s_setprio(0); } while (0)
; template <class Epi, class Sched, bool ALIGN_EPI = false, bool SP2 = false, bool F16 = false>
; __device__ __forceinline__ void gemm_phase(PG8_LAS unsigned char* lds, const Gemm g, const Sched& S, const Epi& E, const int wid_in) {
;     ...
;         for (int t = 0; t < nt; t += 2) {
;     ...
;             PG8_LDB(B0, 0, 0); PG8_LDB(B1, 0, 1); PG8_SCHED; PG8_LDA(At, 0, 0); PG8_STAGE(PG8_SA(1, 1), a1 + hstep, voffA);
;             PG8_WAIT_V(8); PG8_WAIT_L(0); PG8_BAR; PG8_MMA(0, 0, At, B0); PG8_MMA(0, 1, At, B1); PG8_BAR; PG8_SCHED;
;             PG8_LDA(At, 0, 1); PG8_STAGE(PG8_SB(0, 0), b2, voffB); PG8_STAGE(PG8_SB(0, 1), b2 + hstep, voffB); PG8_STAGE(PG8_SA(0, 0), a2, voffA);
;             PG8_WAIT_V(8); PG8_WAIT_L(0); PG8_BAR; PG8_MMA(1, 0, At, B0); PG8_MMA(1, 1, At, B1); PG8_BAR; PG8_SCHED;
;             PG8_LDB(B0, 1, 0); PG8_LDB(B1, 1, 1); PG8_SCHED; PG8_LDA(At, 1, 0); PG8_STAGE(PG8_SA(0, 1), a2 + hstep, voffA);
;             PG8_WAIT_V(8); PG8_WAIT_L(0); PG8_BAR; PG8_MMA(0, 0, At, B0); PG8_MMA(0, 1, At, B1); PG8_BAR; PG8_SCHED;
;             PG8_LDA(At, 1, 1); PG8_STAGE(PG8_SB(1, 0), b3, voffB); PG8_STAGE(PG8_SB(1, 1), b3 + hstep, voffB); PG8_STAGE(PG8_SA(1, 0), a3, voffA);
;             PG8_WAIT_V(8); PG8_WAIT_L(0); PG8_BAR; PG8_MMA(1, 0, At, B0); PG8_MMA(1, 1, At, B1); PG8_BAR; PG8_SCHED;
	s_add_i32 s46, s60, s68
	v_lshl_add_u64 v[192:193], v[192:193], 0, s[26:27]
	s_mov_b32 m0, s46
	ds_read_b128 v[160:163], v237 offset:49152
	ds_read_b128 v[164:167], v237 offset:50176
	ds_read_b128 v[168:171], v237 offset:51200
	ds_read_b128 v[172:175], v237 offset:52224
	ds_read_b128 v[176:179], v237 offset:53248
	ds_read_b128 v[180:183], v237 offset:54272
	ds_read_b128 v[184:187], v237 offset:55296
	ds_read_b128 v[188:191], v237 offset:56320
	global_load_lds_dwordx4 v[192:193], off
	s_add_i32 m0, s46, 0x2000
	s_add_u32 s44, s44, 0x40080
	v_lshl_add_u64 v[192:193], v[194:195], 0, s[26:27]
	s_addc_u32 s45, s45, 0
	s_add_i32 s46, s61, s68
	global_load_lds_dwordx4 v[192:193], off
	v_lshl_add_u64 v[192:193], s[44:45], 0, v[198:199]
	s_mov_b32 m0, s46
	s_nop 0
	global_load_lds_dwordx4 v[192:193], off
	v_lshl_add_u64 v[192:193], s[44:45], 0, v[202:203]
	s_add_i32 m0, s46, 0x2000
	s_nop 0
	global_load_lds_dwordx4 v[192:193], off
	v_lshl_add_u64 v[192:193], v[212:213], 0, s[26:27]
	s_mov_b32 m0, s75
	s_nop 0
	global_load_lds_dwordx4 v[192:193], off
	v_lshl_add_u64 v[192:193], v[214:215], 0, s[26:27]
	s_mov_b32 m0, s67
	s_nop 0
	global_load_lds_dwordx4 v[192:193], off
	s_waitcnt vmcnt(8)
	s_waitcnt lgkmcnt(0)
	s_barrier
	v_mfma_f32_16x16x32_f16 v[60:63], v[112:115], v[160:163], v[60:63]
	v_mfma_f32_16x16x32_f16 v[56:59], v[128:131], v[160:163], v[56:59]
	v_mfma_f32_16x16x32_f16 v[44:47], v[112:115], v[168:171], v[44:47]
	v_mfma_f32_16x16x32_f16 v[40:43], v[128:131], v[168:171], v[40:43]
	v_mfma_f32_16x16x32_f16 v[28:31], v[112:115], v[176:179], v[28:31]
	v_mfma_f32_16x16x32_f16 v[24:27], v[128:131], v[176:179], v[24:27]
	v_mfma_f32_16x16x32_f16 v[12:15], v[112:115], v[184:187], v[12:15]
	v_mfma_f32_16x16x32_f16 v[8:11], v[128:131], v[184:187], v[8:11]
	v_mfma_f32_16x16x32_f16 v[60:63], v[116:119], v[164:167], v[60:63]
	v_mfma_f32_16x16x32_f16 v[56:59], v[132:135], v[164:167], v[56:59]
	v_mfma_f32_16x16x32_f16 v[44:47], v[116:119], v[172:175], v[44:47]
	v_mfma_f32_16x16x32_f16 v[40:43], v[132:135], v[172:175], v[40:43]
	v_mfma_f32_16x16x32_f16 v[28:31], v[116:119], v[180:183], v[28:31]
	v_mfma_f32_16x16x32_f16 v[24:27], v[132:135], v[180:183], v[24:27]
	v_mfma_f32_16x16x32_f16 v[12:15], v[116:119], v[188:191], v[12:15]
	v_mfma_f32_16x16x32_f16 v[8:11], v[132:135], v[188:191], v[8:11]
	v_mfma_f32_16x16x32_f16 v[52:55], v[144:147], v[160:163], v[52:55]
	v_mfma_f32_16x16x32_f16 v[48:51], v[152:155], v[160:163], v[48:51]
	v_mfma_f32_16x16x32_f16 v[36:39], v[144:147], v[168:171], v[36:39]
	v_mfma_f32_16x16x32_f16 v[32:35], v[152:155], v[168:171], v[32:35]
	v_mfma_f32_16x16x32_f16 v[20:23], v[144:147], v[176:179], v[20:23]
	v_mfma_f32_16x16x32_f16 v[16:19], v[152:155], v[176:179], v[16:19]
	v_mfma_f32_16x16x32_f16 v[4:7], v[144:147], v[184:187], v[4:7]
	v_mfma_f32_16x16x32_f16 v[0:3], v[152:155], v[184:187], v[0:3]
	v_mfma_f32_16x16x32_f16 v[52:55], v[148:151], v[164:167], v[52:55]
	v_mfma_f32_16x16x32_f16 v[48:51], v[156:159], v[164:167], v[48:51]
	v_mfma_f32_16x16x32_f16 v[36:39], v[148:151], v[172:175], v[36:39]
	v_mfma_f32_16x16x32_f16 v[32:35], v[156:159], v[172:175], v[32:35]
	v_mfma_f32_16x16x32_f16 v[20:23], v[148:151], v[180:183], v[20:23]
	v_mfma_f32_16x16x32_f16 v[16:19], v[156:159], v[180:183], v[16:19]
	v_mfma_f32_16x16x32_f16 v[4:7], v[148:151], v[188:191], v[4:7]
	v_mfma_f32_16x16x32_f16 v[0:3], v[156:159], v[188:191], v[0:3]
	s_barrier
	s_add_i32 s59, s59, 2
	s_add_u32 s42, s42, 0x100
	s_addc_u32 s43, s43, 0
	s_add_u32 s41, s41, 0x100
	s_addc_u32 s58, s58, 0
	s_cmp_gt_u32 s59, 13
	s_cbranch_scc0 .LBB0_2793
	s_and_b64 vcc, exec, s[16:17]
	s_cbranch_vccz .LBB0_2796
	s_barrier
